# all flat_load/flat_store (804) converted to global_* with saddr=off: memory ops no longer count on lgkmcnt, so LDS waits in epilogues and local phases stop waiting on stores
# speedup vs baseline: 1.0023x; 1.0023x over previous
; __device__ __forceinline__ unsigned xb_ld(unsigned* p)              { return __hip_atomic_load(p, __ATOMIC_RELAXED, __HIP_MEMORY_SCOPE_AGENT); }
; __device__ __forceinline__ void xcd_barrier_complete(unsigned* bar, unsigned x, unsigned& nloc, unsigned& nx) {
;     ...
;     for (;;) {
;         sum = 0u; cnt = 0u; mine = 0u;
; #pragma unroll
;         for (unsigned j = 0; j < 16; ++j) { const unsigned c = xb_ld(&bar[XB_XCNT(j)]); sum += c; cnt += (c > 0u) ? 1u : 0u; mine = (j == x) ? c : mine; }
;         if (sum == G) break;
;         __builtin_amdgcn_s_sleep(1);
;         if ((++sp & 255u) == 0u) { if (xb_ld(&bar[XB_TMO])) break; if (sp > XB_SPIN_CAP) { atomicAdd(&bar[XB_TMO], 1u); break; } }
;     }
.LBB0_30:
	global_load_dword v50, v[4:5], off sc1
	s_waitcnt lgkmcnt(0)
	global_load_dword v0, v[6:7], off sc1
	global_load_dword v36, v[8:9], off sc1
	global_load_dword v37, v[10:11], off sc1
	global_load_dword v38, v[12:13], off sc1
	global_load_dword v39, v[14:15], off sc1
	global_load_dword v40, v[16:17], off sc1
	global_load_dword v41, v[18:19], off sc1
	global_load_dword v42, v[20:21], off sc1
	global_load_dword v43, v[22:23], off sc1
	global_load_dword v44, v[24:25], off sc1
	global_load_dword v45, v[26:27], off sc1
	global_load_dword v46, v[28:29], off sc1
	global_load_dword v47, v[30:31], off sc1
	global_load_dword v48, v[32:33], off sc1
	global_load_dword v49, v[34:35], off sc1
	s_or_b64 s[16:17], s[16:17], exec
	s_or_b64 s[10:11], s[10:11], exec
	s_waitcnt vmcnt(0) lgkmcnt(0)
	v_add_u32_e32 v51, v0, v50
	v_add_u32_e32 v51, v51, v36
	v_add_u32_e32 v51, v51, v37
	v_add_u32_e32 v51, v51, v38
	v_add_u32_e32 v51, v51, v39
	v_add_u32_e32 v51, v51, v40
	v_add_u32_e32 v51, v51, v41
	v_add_u32_e32 v51, v51, v42
	v_add_u32_e32 v51, v51, v43
	v_add_u32_e32 v51, v51, v44
	v_add_u32_e32 v51, v51, v45
	v_add_u32_e32 v51, v51, v46
	v_add_u32_e32 v51, v51, v47
	v_add_u32_e32 v51, v51, v48
	v_add_u32_e32 v51, v51, v49
	v_cmp_ne_u32_e32 vcc, s53, v51
	s_and_saveexec_b64 s[18:19], vcc
	s_cbranch_execz .LBB0_29
	s_and_b32 s4, s24, 0xff
	s_mov_b64 s[20:21], -1
	s_cmp_eq_u32 s4, 0
	s_mov_b64 s[4:5], -1
	s_mov_b64 s[22:23], -1
	s_sleep 1
	s_cbranch_scc1 .LBB0_33
	s_and_saveexec_b64 s[14:15], s[4:5]
	s_cbranch_execz .LBB0_28
	s_branch .LBB0_36
.LBB0_33:
	v_mov_b64_e32 v[52:53], s[0:1]
	global_load_dword v51, v[52:53], off sc1
	s_mov_b64 s[4:5], 0
	s_waitcnt vmcnt(0) lgkmcnt(0)
	v_cmp_eq_u32_e32 vcc, 0, v51
	s_and_saveexec_b64 s[14:15], vcc
	s_cmp_lt_u32 s24, 0x40001
	s_cselect_b64 s[4:5], -1, 0
	s_xor_b64 s[22:23], exec, -1
	s_and_b64 s[4:5], s[4:5], exec
	s_or_b64 exec, exec, s[14:15]
	s_and_saveexec_b64 s[14:15], s[4:5]
	s_cbranch_execz .LBB0_28

; __device__ __forceinline__ unsigned xb_ld(unsigned* p)              { return __hip_atomic_load(p, __ATOMIC_RELAXED, __HIP_MEMORY_SCOPE_AGENT); }
; __device__ __forceinline__ unsigned xb_add(unsigned* p, unsigned v) { return __hip_atomic_fetch_add(p, v, __ATOMIC_RELAXED, __HIP_MEMORY_SCOPE_AGENT); }
; #define XB_SPIN(cond, bar) do { unsigned _sp = 0; while (cond) { __builtin_amdgcn_s_sleep(1); \
;     if ((++_sp & 255u) == 0u) { if (xb_ld(&(bar)[XB_TMO])) break; if (_sp > XB_SPIN_CAP) { atomicAdd(&(bar)[XB_TMO], 1u); break; } } } } while (0)
; __device__ __forceinline__ void xcd_barrier(unsigned* bar, volatile LAS unsigned* st) {
;     ...
;         const unsigned old = xb_add(&bar[XB_XSUB(x)], 1u);
;         const unsigned gen = old / nloc;
;         if (old + 1u == (gen + 1u) * nloc) {
;             __builtin_amdgcn_fence(__ATOMIC_RELEASE, "agent");
;             asm volatile("s_waitcnt vmcnt(0)" ::: "memory");
;             const unsigned og = xb_add(&bar[XB_TOP], 1u);
;             const unsigned tg = og / nx;
;             if (og + 1u == (tg + 1u) * nx) xb_add(&bar[XB_TOPGEN], 1u);
;             else XB_SPIN(xb_ld(&bar[XB_TOPGEN]) == tg, bar);
;             __builtin_amdgcn_fence(__ATOMIC_ACQUIRE, "agent");
;             xb_add(&bar[XB_XGEN(x)], 1u);
;             asm volatile("s_waitcnt vmcnt(0)" ::: "memory");
;         } else {
;             XB_SPIN(xb_ld(&bar[XB_XGEN(x)]) == gen, bar);
.LBB0_40:
	s_lshl_b32 s0, s45, 8
	s_add_u32 s0, s44, s0
	s_addc_u32 s1, s43, 0
	v_mov_b32_e32 v5, s0
	v_add_co_u32_e32 v6, vcc, 0x19701000, v5
	v_mov_b32_e32 v5, s1
	s_nop 0
	v_addc_co_u32_e32 v7, vcc, 0, v5, vcc
	flat_atomic_add v5, v[6:7], v223 offset:1024 sc0
	v_cvt_f32_u32_e32 v6, v4
	v_sub_u32_e32 v7, 0, v4
	s_add_u32 s27, s0, 0x19700000
	s_addc_u32 s26, s1, 0
	v_rcp_iflag_f32_e32 v6, v6
	s_waitcnt vmcnt(0) lgkmcnt(0)
	v_add_u32_e32 v8, 1, v5
	v_mul_f32_e32 v6, 0x4f7ffffe, v6
	v_cvt_u32_f32_e32 v6, v6
	v_mul_lo_u32 v7, v7, v6
	v_mul_hi_u32 v7, v6, v7
	v_add_u32_e32 v6, v6, v7
	v_mul_hi_u32 v6, v5, v6
	v_mul_lo_u32 v7, v6, v4
	v_sub_u32_e32 v5, v5, v7
	v_add_u32_e32 v9, 1, v6
	v_cmp_ge_u32_e32 vcc, v5, v4
	v_sub_u32_e32 v7, v5, v4
	s_nop 0
	v_cndmask_b32_e32 v6, v6, v9, vcc
	v_cndmask_b32_e32 v5, v5, v7, vcc
	v_add_u32_e32 v7, 1, v6
	v_cmp_ge_u32_e32 vcc, v5, v4
	s_nop 1
	v_cndmask_b32_e32 v5, v6, v7, vcc
	v_mad_u64_u32 v[6:7], s[0:1], v4, v5, v[4:5]
	v_cmp_ne_u32_e32 vcc, v8, v6
	s_and_saveexec_b64 s[0:1], vcc
	s_xor_b64 s[0:1], exec, s[0:1]
	s_cbranch_execz .LBB0_53
	v_mov_b32_e32 v0, s27
	v_add_co_u32_e32 v6, vcc, 0x2000, v0
	v_mov_b32_e32 v0, s26
	s_nop 0
	v_addc_co_u32_e32 v7, vcc, 0, v0, vcc
	global_load_dword v0, v[6:7], off offset:1024 sc1
	s_add_u32 s8, s27, 0x2400
	s_addc_u32 s9, s26, 0
	s_waitcnt vmcnt(0) lgkmcnt(0)
	v_cmp_eq_u32_e32 vcc, v0, v5
	s_and_saveexec_b64 s[6:7], vcc
	s_cbranch_execz .LBB0_52
	s_add_u32 s10, s44, 0x19700200
	s_addc_u32 s11, s43, 0
	s_mov_b32 s28, 1
	s_mov_b64 s[16:17], 0
	s_branch .LBB0_44

; __device__ __forceinline__ unsigned xb_ld(unsigned* p)              { return __hip_atomic_load(p, __ATOMIC_RELAXED, __HIP_MEMORY_SCOPE_AGENT); }
; #define XB_SPIN(cond, bar) do { unsigned _sp = 0; while (cond) { __builtin_amdgcn_s_sleep(1); \
;     if ((++_sp & 255u) == 0u) { if (xb_ld(&(bar)[XB_TMO])) break; if (_sp > XB_SPIN_CAP) { atomicAdd(&(bar)[XB_TMO], 1u); break; } } } } while (0)
; __device__ __forceinline__ void xcd_barrier(unsigned* bar, volatile LAS unsigned* st) {
;     ...
;             XB_SPIN(xb_ld(&bar[XB_XGEN(x)]) == gen, bar);
.LBB0_44:
	s_and_b32 s4, s28, 0xff
	s_mov_b64 s[22:23], -1
	s_cmp_lg_u32 s4, 0
	s_mov_b64 s[24:25], -1
	s_sleep 1
	s_cbranch_scc1 .LBB0_48
	v_mov_b64_e32 v[6:7], s[10:11]
	global_load_dword v0, v[6:7], off sc1
	s_mov_b64 s[24:25], 0
	s_mov_b64 s[4:5], -1
	s_waitcnt vmcnt(0) lgkmcnt(0)
	v_cmp_eq_u32_e32 vcc, 0, v0
	s_and_saveexec_b64 s[14:15], vcc
	s_cmp_lt_u32 s28, 0x40001
	s_cselect_b64 s[24:25], -1, 0
	s_xor_b64 s[4:5], exec, -1
	s_and_b64 s[24:25], s[24:25], exec
	s_or_b64 exec, exec, s[14:15]
.LBB0_48:
	s_andn2_b64 s[14:15], s[20:21], exec
	s_and_b64 s[4:5], s[4:5], exec
	s_or_b64 s[20:21], s[14:15], s[4:5]
	s_and_saveexec_b64 s[4:5], s[24:25]
	s_cbranch_execz .LBB0_43
	v_mov_b64_e32 v[6:7], s[8:9]
	global_load_dword v0, v[6:7], off sc1
	s_add_i32 s28, s28, 1
	s_or_b64 s[20:21], s[20:21], exec
	s_waitcnt vmcnt(0) lgkmcnt(0)
	v_cmp_ne_u32_e32 vcc, v0, v5
	s_orn2_b64 s[22:23], vcc, exec
	s_branch .LBB0_43

; __device__ __forceinline__ unsigned xb_ld(unsigned* p)              { return __hip_atomic_load(p, __ATOMIC_RELAXED, __HIP_MEMORY_SCOPE_AGENT); }
; __device__ __forceinline__ unsigned xb_add(unsigned* p, unsigned v) { return __hip_atomic_fetch_add(p, v, __ATOMIC_RELAXED, __HIP_MEMORY_SCOPE_AGENT); }
; #define XB_SPIN(cond, bar) do { unsigned _sp = 0; while (cond) { __builtin_amdgcn_s_sleep(1); \
;     if ((++_sp & 255u) == 0u) { if (xb_ld(&(bar)[XB_TMO])) break; if (_sp > XB_SPIN_CAP) { atomicAdd(&(bar)[XB_TMO], 1u); break; } } } } while (0)
; __device__ __forceinline__ void xcd_barrier(unsigned* bar, volatile LAS unsigned* st) {
;     ...
;         if (old + 1u == (gen + 1u) * nloc) {
;             __builtin_amdgcn_fence(__ATOMIC_RELEASE, "agent");
;             asm volatile("s_waitcnt vmcnt(0)" ::: "memory");
;             const unsigned og = xb_add(&bar[XB_TOP], 1u);
;             const unsigned tg = og / nx;
;             if (og + 1u == (tg + 1u) * nx) xb_add(&bar[XB_TOPGEN], 1u);
;             else XB_SPIN(xb_ld(&bar[XB_TOPGEN]) == tg, bar);
.LBB0_53:
	s_andn2_saveexec_b64 s[0:1], s[0:1]
	s_cbranch_execz .LBB0_69
	v_mov_b32_e32 v4, s44
	v_add_co_u32_e32 v4, vcc, 0x19703000, v4
	v_mov_b32_e32 v5, s43
	buffer_wbl2 sc1
	s_waitcnt vmcnt(0)
	v_addc_co_u32_e32 v5, vcc, 0, v5, vcc
	flat_atomic_add v4, v[4:5], v223 offset:1024 sc0
	v_cvt_f32_u32_e32 v5, v0
	v_sub_u32_e32 v6, 0, v0
	s_add_u32 s0, s44, 0x19703500
	s_addc_u32 s1, s43, 0
	v_rcp_iflag_f32_e32 v5, v5
	s_mov_b64 s[8:9], -1
	v_mul_f32_e32 v5, 0x4f7ffffe, v5
	v_cvt_u32_f32_e32 v5, v5
	v_mul_lo_u32 v6, v6, v5
	v_mul_hi_u32 v6, v5, v6
	v_add_u32_e32 v5, v5, v6
	s_waitcnt vmcnt(0) lgkmcnt(0)
	v_mul_hi_u32 v5, v4, v5
	v_mul_lo_u32 v6, v5, v0
	v_add_u32_e32 v7, 1, v4
	v_sub_u32_e32 v4, v4, v6
	v_add_u32_e32 v8, 1, v5
	v_cmp_ge_u32_e32 vcc, v4, v0
	v_sub_u32_e32 v6, v4, v0
	s_nop 0
	v_cndmask_b32_e32 v5, v5, v8, vcc
	v_cndmask_b32_e32 v4, v4, v6, vcc
	v_add_u32_e32 v6, 1, v5
	v_cmp_ge_u32_e32 vcc, v4, v0
	s_nop 1
	v_cndmask_b32_e32 v6, v5, v6, vcc
	v_mad_u64_u32 v[4:5], s[4:5], v0, v6, v[0:1]
	v_cmp_ne_u32_e32 vcc, v7, v4
	v_mov_b64_e32 v[4:5], s[0:1]
	s_and_saveexec_b64 s[6:7], vcc
	s_cbranch_execz .LBB0_66
	v_mov_b64_e32 v[4:5], s[0:1]
	global_load_dword v0, v[4:5], off sc1
	s_mov_b64 s[4:5], 0
	s_waitcnt vmcnt(0) lgkmcnt(0)
	v_cmp_eq_u32_e32 vcc, v0, v6
	s_and_saveexec_b64 s[10:11], vcc
	s_cbranch_execz .LBB0_65
	s_add_u32 s8, s44, 0x19700200
	s_addc_u32 s9, s43, 0
	s_mov_b32 s28, 1
	s_mov_b64 s[16:17], 0
	s_branch .LBB0_58

; __device__ __forceinline__ unsigned xb_ld(unsigned* p)              { return __hip_atomic_load(p, __ATOMIC_RELAXED, __HIP_MEMORY_SCOPE_AGENT); }
; #define XB_SPIN(cond, bar) do { unsigned _sp = 0; while (cond) { __builtin_amdgcn_s_sleep(1); \
;     if ((++_sp & 255u) == 0u) { if (xb_ld(&(bar)[XB_TMO])) break; if (_sp > XB_SPIN_CAP) { atomicAdd(&(bar)[XB_TMO], 1u); break; } } } } while (0)
; __device__ __forceinline__ void xcd_barrier(unsigned* bar, volatile LAS unsigned* st) {
;     ...
;             else XB_SPIN(xb_ld(&bar[XB_TOPGEN]) == tg, bar);
.LBB0_60:
	v_mov_b64_e32 v[4:5], s[8:9]
	global_load_dword v0, v[4:5], off sc1
	s_mov_b64 s[4:5], 0
	s_mov_b64 s[22:23], -1
	s_waitcnt vmcnt(0) lgkmcnt(0)
	v_cmp_eq_u32_e32 vcc, 0, v0
	s_and_saveexec_b64 s[14:15], vcc
	s_cmp_lt_u32 s28, 0x40001
	s_cselect_b64 s[4:5], -1, 0
	s_xor_b64 s[22:23], exec, -1
	s_and_b64 s[4:5], s[4:5], exec
	s_or_b64 exec, exec, s[14:15]
	s_and_saveexec_b64 s[24:25], s[4:5]
	s_cbranch_execz .LBB0_57
.LBB0_63:
	v_mov_b64_e32 v[4:5], s[0:1]
	global_load_dword v0, v[4:5], off sc1
	s_add_i32 s28, s28, 1
	s_or_b64 s[22:23], s[22:23], exec
	s_waitcnt vmcnt(0) lgkmcnt(0)
	v_cmp_ne_u32_e32 vcc, v0, v6
	s_orn2_b64 s[20:21], vcc, exec
	s_branch .LBB0_57

; __device__ __forceinline__ unsigned xb_ld(unsigned* p)              { return __hip_atomic_load(p, __ATOMIC_RELAXED, __HIP_MEMORY_SCOPE_AGENT); }
; __device__ __forceinline__ unsigned xb_add(unsigned* p, unsigned v) { return __hip_atomic_fetch_add(p, v, __ATOMIC_RELAXED, __HIP_MEMORY_SCOPE_AGENT); }
; #define XB_SPIN(cond, bar) do { unsigned _sp = 0; while (cond) { __builtin_amdgcn_s_sleep(1); \
;     if ((++_sp & 255u) == 0u) { if (xb_ld(&(bar)[XB_TMO])) break; if (_sp > XB_SPIN_CAP) { atomicAdd(&(bar)[XB_TMO], 1u); break; } } } } while (0)
; __device__ __forceinline__ void xcc_barrier(unsigned* bar, unsigned x, unsigned nloc) {
;     asm volatile("s_waitcnt vmcnt(0)" ::: "memory");
;     __syncthreads();
;     if (threadIdx.x == 0) {
;         __builtin_amdgcn_s_waitcnt(0);
;         const unsigned old = xb_add(&bar[XL_SUB(x)], 1u), gen = old / nloc;
;         if (old + 1u == (gen + 1u) * nloc) xb_add(&bar[XL_GEN(x)], 1u); else XB_SPIN(xb_ld(&bar[XL_GEN(x)]) == gen, bar);
;         __builtin_amdgcn_fence(__ATOMIC_ACQUIRE, "agent");
.LBB0_70:
	s_and_b64 vcc, exec, s[0:1]
	s_cbranch_vccz .LBB0_88
	s_waitcnt vmcnt(0)
	s_waitcnt lgkmcnt(0)
	v_readfirstlane_b32 s14, v3
	v_readfirstlane_b32 s15, v2
	s_barrier
	s_and_saveexec_b64 s[0:1], s[60:61]
	s_cbranch_execz .LBB0_87
	v_readlane_b32 s4, v254, 22
	s_lshl_b32 s4, s4, 8
	s_and_b32 s4, s4, 0x700
	s_add_u32 s4, s15, s4
	s_addc_u32 s5, s14, 0
	v_mov_b32_e32 v0, s4
	v_add_co_u32_e32 v2, vcc, 0x19704000, v0
	v_mov_b32_e32 v0, s5
	s_nop 0
	v_addc_co_u32_e32 v3, vcc, 0, v0, vcc
	s_waitcnt vmcnt(0) expcnt(0) lgkmcnt(0)
	buffer_inv sc1
	flat_atomic_add v0, v[2:3], v223 sc0
	s_add_u32 s6, s4, 0x19705000
	s_addc_u32 s7, s5, 0
	s_mov_b64 s[10:11], -1
	s_waitcnt vmcnt(0) lgkmcnt(0)
	v_mul_hi_u32 v2, v0, v222
	v_mul_lo_u32 v4, v2, s65
	v_add_u32_e32 v3, 1, v0
	v_sub_u32_e32 v0, v0, v4
	v_add_u32_e32 v5, 1, v2
	v_cmp_le_u32_e32 vcc, s65, v0
	v_subrev_u32_e32 v4, s65, v0
	s_nop 0
	v_cndmask_b32_e32 v2, v2, v5, vcc
	v_cndmask_b32_e32 v0, v0, v4, vcc
	v_add_u32_e32 v4, 1, v2
	v_cmp_le_u32_e32 vcc, s65, v0
	s_nop 1
	v_cndmask_b32_e32 v0, v2, v4, vcc
	v_mul_lo_u32 v2, s65, v0
	v_add_u32_e32 v2, s65, v2
	v_cmp_ne_u32_e32 vcc, v3, v2
	v_mov_b64_e32 v[2:3], s[6:7]
	s_and_saveexec_b64 s[8:9], vcc
	s_cbranch_execz .LBB0_84
	v_mov_b64_e32 v[2:3], s[6:7]
	global_load_dword v2, v[2:3], off sc1
	s_mov_b64 s[4:5], 0
	s_waitcnt vmcnt(0) lgkmcnt(0)
	v_cmp_eq_u32_e32 vcc, v2, v0
	s_and_saveexec_b64 s[16:17], vcc
	s_cbranch_execz .LBB0_83
	s_add_u32 s10, s15, 0x19700200
	s_addc_u32 s11, s14, 0
	s_mov_b32 s28, 1
	s_mov_b64 s[18:19], 0
	s_branch .LBB0_76

; __device__ __forceinline__ unsigned xb_ld(unsigned* p)              { return __hip_atomic_load(p, __ATOMIC_RELAXED, __HIP_MEMORY_SCOPE_AGENT); }
; __device__ __forceinline__ unsigned xb_add(unsigned* p, unsigned v) { return __hip_atomic_fetch_add(p, v, __ATOMIC_RELAXED, __HIP_MEMORY_SCOPE_AGENT); }
; #define XB_SPIN(cond, bar) do { unsigned _sp = 0; while (cond) { __builtin_amdgcn_s_sleep(1); \
;     if ((++_sp & 255u) == 0u) { if (xb_ld(&(bar)[XB_TMO])) break; if (_sp > XB_SPIN_CAP) { atomicAdd(&(bar)[XB_TMO], 1u); break; } } } } while (0)
; __device__ __forceinline__ void xcc_barrier(unsigned* bar, unsigned x, unsigned nloc) {
;     ...
;         if (old + 1u == (gen + 1u) * nloc) xb_add(&bar[XL_GEN(x)], 1u); else XB_SPIN(xb_ld(&bar[XL_GEN(x)]) == gen, bar);
.LBB0_78:
	v_mov_b64_e32 v[2:3], s[10:11]
	global_load_dword v2, v[2:3], off sc1
	s_mov_b64 s[4:5], 0
	s_mov_b64 s[24:25], -1
	s_waitcnt vmcnt(0) lgkmcnt(0)
	v_cmp_eq_u32_e32 vcc, 0, v2
	s_and_saveexec_b64 s[14:15], vcc
	s_cmp_lt_u32 s28, 0x40001
	s_cselect_b64 s[4:5], -1, 0
	s_xor_b64 s[24:25], exec, -1
	s_and_b64 s[4:5], s[4:5], exec
	s_or_b64 exec, exec, s[14:15]
	s_and_saveexec_b64 s[26:27], s[4:5]
	s_cbranch_execz .LBB0_75
.LBB0_81:
	v_mov_b64_e32 v[2:3], s[6:7]
	global_load_dword v2, v[2:3], off sc1
	s_add_i32 s28, s28, 1
	s_or_b64 s[24:25], s[24:25], exec
	s_waitcnt vmcnt(0) lgkmcnt(0)
	v_cmp_ne_u32_e32 vcc, v2, v0
	s_orn2_b64 s[22:23], vcc, exec
	s_branch .LBB0_75

; __device__ __forceinline__ unsigned xb_ld(unsigned* p)              { return __hip_atomic_load(p, __ATOMIC_RELAXED, __HIP_MEMORY_SCOPE_AGENT); }
; __global__ void __launch_bounds__(NTHR, 2) fwd_megakernel(Args P) {
;     ...
;                 if (threadIdx.x == 0) { unsigned* bar0 = (unsigned*)(WSP + WS_BAR); const unsigned want = gridDim.x >> 3; unsigned okc = (gridDim.x & 7u) == 0u;
; #pragma unroll
;                     for (unsigned j = 0; j < 16; ++j) { const unsigned cj = xb_ld(&bar0[XL_RANK(j)]); okc &= (j < 8 ? cj == want : cj == 0u); }
;                     bst[4] = okc; }
.LBB0_100:
	s_and_saveexec_b64 s[22:23], s[60:61]
	s_cbranch_execz .LBB0_102
	v_mov_b32_e32 v0, s80
	ds_read_b64 v[2:3], v0
	v_readlane_b32 s4, v254, 0
	v_readlane_b32 s5, v254, 1
	s_waitcnt lgkmcnt(0)
	v_readfirstlane_b32 s1, v2
	v_readfirstlane_b32 s0, v3
	s_nop 0
	v_mov_b32_e32 v0, s1
	v_add_co_u32_e32 v2, vcc, 0x19706000, v0
	v_mov_b32_e32 v3, s0
	s_nop 0
	v_addc_co_u32_e32 v3, vcc, 0, v3, vcc
	global_load_dword v0, v[2:3], off sc1
	global_load_dword v4, v[2:3], off offset:256 sc1
	global_load_dword v5, v[2:3], off offset:512 sc1
	global_load_dword v6, v[2:3], off offset:768 sc1
	global_load_dword v7, v[2:3], off offset:1024 sc1
	global_load_dword v8, v[2:3], off offset:1280 sc1
	global_load_dword v9, v[2:3], off offset:1536 sc1
	global_load_dword v10, v[2:3], off offset:1792 sc1
	global_load_dword v11, v[2:3], off offset:2048 sc1
	global_load_dword v12, v[2:3], off offset:2304 sc1
	global_load_dword v13, v[2:3], off offset:2560 sc1
	global_load_dword v14, v[2:3], off offset:2816 sc1
	global_load_dword v15, v[2:3], off offset:3072 sc1
	global_load_dword v16, v[2:3], off offset:3328 sc1
	global_load_dword v17, v[2:3], off offset:3584 sc1
	s_nop 0
	global_load_dword v2, v[2:3], off offset:3840 sc1
	s_waitcnt vmcnt(0) lgkmcnt(0)
	v_cmp_eq_u32_e32 vcc, s65, v0
	s_and_b64 s[4:5], vcc, s[4:5]
	v_cmp_eq_u32_e64 s[6:7], s65, v5
	v_cmp_eq_u32_e64 s[8:9], s65, v6
	v_cmp_eq_u32_e64 s[10:11], s65, v7
	v_cmp_eq_u32_e64 s[16:17], s65, v8
	v_cmp_eq_u32_e64 s[18:19], s65, v9
	v_cmp_eq_u32_e64 s[20:21], s65, v10
	v_cmp_eq_u32_e64 s[0:1], s65, v4
	v_or_b32_e32 v0, v2, v17
	v_or_b32_e32 v0, v0, v16
	v_or_b32_e32 v0, v0, v15
	v_or_b32_e32 v0, v0, v14
	v_or_b32_e32 v0, v0, v13
	v_or_b32_e32 v0, v0, v12
	v_or_b32_e32 v0, v0, v11
	v_cmp_eq_u32_e32 vcc, 0, v0
	s_and_b64 s[14:15], vcc, s[20:21]
	s_and_b64 s[14:15], s[14:15], s[18:19]
	s_and_b64 s[14:15], s[14:15], s[16:17]
	s_and_b64 s[10:11], s[14:15], s[10:11]
	s_and_b64 s[8:9], s[10:11], s[8:9]
	s_and_b64 s[6:7], s[8:9], s[6:7]
	s_and_b64 s[0:1], s[6:7], s[0:1]
	s_and_b64 s[0:1], s[0:1], s[4:5]
	v_cndmask_b32_e64 v0, 0, 1, s[0:1]
	v_readlane_b32 s0, v254, 5
	s_nop 1
	v_mov_b32_e32 v2, s0
	ds_write_b32 v2, v0

; __device__ __forceinline__ unsigned cvt_pk_bf16(float lo, float hi) { unsigned r; asm volatile("v_cvt_pk_bf16_f32 %0, %1, %2" : "=v"(r) : "v"(lo), "v"(hi)); return r; }
;     __device__ __forceinline__ void operator()(const f32x4 (&acc)[2][2][4][2], const Unit& u, int wr, int wc, int fr, int fq) const {
;     ...
;                 for (int bj = 0; bj < 2; ++bj) bb[ai][m][bj] = *(const u32x4*)(xb + (size_t)(row0 + ai * HALF + m * 16) * D + col0 + bj * HALF);
; #pragma unroll
;         for (int ai = 0; ai < 2; ++ai)
; #pragma unroll
;             for (int m = 0; m < 4; ++m) { const size_t off = (size_t)(row0 + ai * HALF + m * 16) * D + col0; float sq = 0.f;
; #pragma unroll
;                 for (int bj = 0; bj < 2; ++bj) { const u32x4 b = bb[ai][m][bj];
;                     const f32x4 v0 = acc[ai][bj][m][0] + (f32x4){bflo(b.x), bfhi(b.x), bflo(b.y), bfhi(b.y)}, v1 = acc[ai][bj][m][1] + (f32x4){bflo(b.z), bfhi(b.z), bflo(b.w), bfhi(b.w)};
;                     u32x4 w; w.x = cvt_pk_bf16(v0[0], v0[1]); w.y = cvt_pk_bf16(v0[2], v0[3]); w.z = cvt_pk_bf16(v1[0], v1[1]); w.w = cvt_pk_bf16(v1[2], v1[3]);
;                     *(u32x4*)(xb + off + bj * HALF) = w;
;                     const float r0 = bflo(w.x), r1 = bfhi(w.x), r2 = bflo(w.y), r3 = bfhi(w.y), r4 = bflo(w.z), r5 = bfhi(w.z), r6 = bflo(w.w), r7 = bfhi(w.w);
;                     sq += ((r0 * r0 + r1 * r1) + (r2 * r2 + r3 * r3)) + ((r4 * r4 + r5 * r5) + (r6 * r6 + r7 * r7)); }
;                 sq += __shfl_xor(sq, 16); sq += __shfl_xor(sq, 32);
;                 if (fq == 0) part[(ai * HALF + wr * 64 + m * 16 + fr) * 4 + wc] = sq; }
.LBB0_154:
	s_lshl_b32 s35, s35, 8
	v_lshl_or_b32 v192, s34, 8, v243
	v_add_u32_e32 v108, s35, v242
	v_ashrrev_i32_e32 v193, 31, v192
	v_lshlrev_b64 v[216:217], 1, v[192:193]
	v_ashrrev_i32_e32 v109, 31, v108
	v_lshl_add_u64 v[110:111], s[18:19], 0, v[216:217]
	v_lshlrev_b64 v[218:219], 11, v[108:109]
	v_lshl_add_u64 v[120:121], v[110:111], 0, v[218:219]
	global_load_dwordx4 v[248:251], v[120:121], off
	global_load_dwordx4 v[188:191], v[120:121], off offset:256
	v_or_b32_e32 v120, 16, v108
	v_ashrrev_i32_e32 v121, 31, v120
	v_lshlrev_b64 v[214:215], 11, v[120:121]
	v_lshl_add_u64 v[120:121], v[110:111], 0, v[214:215]
	global_load_dwordx4 v[184:187], v[120:121], off
	global_load_dwordx4 v[180:183], v[120:121], off offset:256
	v_or_b32_e32 v120, 32, v108
	v_or_b32_e32 v108, 48, v108
	v_ashrrev_i32_e32 v121, 31, v120
	v_ashrrev_i32_e32 v109, 31, v108
	v_lshlrev_b64 v[212:213], 11, v[120:121]
	v_lshlrev_b64 v[210:211], 11, v[108:109]
	s_mov_b64 s[4:5], 0x40000
	v_lshl_add_u64 v[120:121], v[110:111], 0, v[212:213]
	v_lshl_add_u64 v[108:109], v[110:111], 0, v[210:211]
	v_lshl_add_u64 v[208:209], v[218:219], 0, s[4:5]
	s_mov_b64 s[4:5], 0x48000
	global_load_dwordx4 v[176:179], v[120:121], off
	global_load_dwordx4 v[164:167], v[120:121], off offset:256
	global_load_dwordx4 v[160:163], v[108:109], off
	global_load_dwordx4 v[156:159], v[108:109], off offset:256
	v_lshl_add_u64 v[108:109], v[110:111], 0, v[208:209]
	v_lshl_add_u64 v[206:207], v[218:219], 0, s[4:5]
	s_mov_b64 s[4:5], 0x50000
	global_load_dwordx4 v[152:155], v[108:109], off
	global_load_dwordx4 v[148:151], v[108:109], off offset:256
	v_lshl_add_u64 v[108:109], v[110:111], 0, v[206:207]
	v_lshl_add_u64 v[204:205], v[218:219], 0, s[4:5]
	s_mov_b64 s[4:5], 0x58000
	global_load_dwordx4 v[144:147], v[108:109], off
	global_load_dwordx4 v[136:139], v[108:109], off offset:256
	v_lshl_add_u64 v[108:109], v[110:111], 0, v[204:205]
	v_lshl_add_u64 v[202:203], v[218:219], 0, s[4:5]
	global_load_dwordx4 v[132:135], v[108:109], off
	global_load_dwordx4 v[128:131], v[108:109], off offset:256
	v_lshl_add_u64 v[108:109], v[110:111], 0, v[202:203]
	global_load_dwordx4 v[120:123], v[108:109], off
	s_nop 0
	global_load_dwordx4 v[108:111], v[108:109], off offset:256
	s_waitcnt vmcnt(0) lgkmcnt(0)
	v_lshlrev_b32_e32 v252, 16, v248
	v_and_b32_e32 v253, 0xffff0000, v248
	v_lshlrev_b32_e32 v248, 16, v249
	v_and_b32_e32 v249, 0xffff0000, v249
	v_pk_add_f32 v[174:175], v[174:175], v[248:249]
	v_lshlrev_b32_e32 v248, 16, v250
	v_and_b32_e32 v249, 0xffff0000, v250
	v_pk_add_f32 v[172:173], v[172:173], v[252:253]
	v_lshlrev_b32_e32 v250, 16, v251
	v_and_b32_e32 v251, 0xffff0000, v251
	v_pk_add_f32 v[168:169], v[168:169], v[248:249]
	v_pk_add_f32 v[250:251], v[170:171], v[250:251]
	v_cvt_pk_bf16_f32 v170, v172, v173
	v_cvt_pk_bf16_f32 v171, v174, v175
	v_cvt_pk_bf16_f32 v172, v168, v169
	v_lshl_add_u64 v[168:169], s[18:19], 0, v[218:219]
	v_lshl_add_u64 v[168:169], v[168:169], 0, v[216:217]
	v_cvt_pk_bf16_f32 v173, v250, v251
	global_store_dwordx4 v[168:169], v[170:173], off
	v_lshlrev_b32_e32 v174, 16, v170
	v_lshlrev_b32_e32 v175, 16, v171
	v_and_b32_e32 v170, 0xffff0000, v170
	v_and_b32_e32 v171, 0xffff0000, v171
	v_mul_f32_e32 v170, v170, v170
	v_mul_f32_e32 v171, v171, v171
	v_lshlrev_b32_e32 v216, 16, v172
	v_and_b32_e32 v172, 0xffff0000, v172
	v_lshlrev_b32_e32 v217, 16, v173
	v_and_b32_e32 v173, 0xffff0000, v173
	v_fmac_f32_e32 v170, v174, v174
	v_fmac_f32_e32 v171, v175, v175
	v_add_f32_e32 v170, v170, v171
	v_mul_f32_e32 v171, v172, v172
	v_mul_f32_e32 v172, v173, v173
	v_fmac_f32_e32 v171, v216, v216
	v_fmac_f32_e32 v172, v217, v217
	v_add_f32_e32 v171, v171, v172
	v_add_f32_e32 v174, v170, v171
	v_lshlrev_b32_e32 v170, 16, v188
	v_and_b32_e32 v171, 0xffff0000, v188
	v_lshlrev_b32_e32 v172, 16, v189
	v_and_b32_e32 v173, 0xffff0000, v189
	v_pk_add_f32 v[142:143], v[142:143], v[172:173]
	v_pk_add_f32 v[140:141], v[140:141], v[170:171]
	v_lshlrev_b32_e32 v170, 16, v190
	v_and_b32_e32 v171, 0xffff0000, v190
	v_lshlrev_b32_e32 v172, 16, v191
	v_and_b32_e32 v173, 0xffff0000, v191
	v_pk_add_f32 v[172:173], v[126:127], v[172:173]
	v_pk_add_f32 v[126:127], v[124:125], v[170:171]
	v_cvt_pk_bf16_f32 v124, v140, v141
	v_cvt_pk_bf16_f32 v125, v142, v143
	s_nop 0
	v_cvt_pk_bf16_f32 v126, v126, v127
	v_cvt_pk_bf16_f32 v127, v172, v173
	global_store_dwordx4 v[168:169], v[124:127], off offset:256
	v_lshlrev_b32_e32 v140, 16, v124
	v_lshlrev_b32_e32 v141, 16, v125
	v_and_b32_e32 v124, 0xffff0000, v124
	v_and_b32_e32 v125, 0xffff0000, v125
	v_mul_f32_e32 v124, v124, v124
	v_mul_f32_e32 v125, v125, v125
	v_lshlrev_b32_e32 v142, 16, v126
	v_and_b32_e32 v126, 0xffff0000, v126
	v_lshlrev_b32_e32 v143, 16, v127
	v_and_b32_e32 v127, 0xffff0000, v127
	v_fmac_f32_e32 v124, v140, v140
	v_fmac_f32_e32 v125, v141, v141
	v_add_f32_e32 v124, v124, v125
	v_mul_f32_e32 v125, v126, v126
	v_mul_f32_e32 v126, v127, v127
	v_fmac_f32_e32 v125, v142, v142
	v_fmac_f32_e32 v126, v143, v143
	v_add_f32_e32 v125, v125, v126
	v_add_f32_e32 v124, v124, v125
	v_and_b32_e32 v126, 64, v226
	v_add_f32_e32 v125, v174, v124
	v_xor_b32_e32 v124, 16, v226
	v_add_u32_e32 v127, 64, v126
	v_cmp_lt_i32_e32 vcc, v124, v127
	s_nop 1
	v_cndmask_b32_e32 v124, v226, v124, vcc
	v_lshlrev_b32_e32 v124, 2, v124
	ds_bpermute_b32 v126, v124, v125
	s_waitcnt lgkmcnt(0)
	v_add_f32_e32 v126, v125, v126
	v_xor_b32_e32 v125, 32, v226
	v_cmp_lt_i32_e32 vcc, v125, v127
	s_nop 1
	v_cndmask_b32_e32 v125, v226, v125, vcc
	v_lshlrev_b32_e32 v125, 2, v125
	ds_bpermute_b32 v127, v125, v126
	s_and_saveexec_b64 s[4:5], s[6:7]
	s_cbranch_execz .LBB0_156
	s_waitcnt lgkmcnt(0)
	v_add_f32_e32 v126, v126, v127
	ds_write_b32 v246, v126
; __device__ __forceinline__ unsigned cvt_pk_bf16(float lo, float hi) { unsigned r; asm volatile("v_cvt_pk_bf16_f32 %0, %1, %2" : "=v"(r) : "v"(lo), "v"(hi)); return r; }
;     __device__ __forceinline__ void operator()(const f32x4 (&acc)[2][2][4][2], const Unit& u, int wr, int wc, int fr, int fq) const {
;     ...
;             for (int m = 0; m < 4; ++m) { const size_t off = (size_t)(row0 + ai * HALF + m * 16) * D + col0; float sq = 0.f;
; #pragma unroll
;                 for (int bj = 0; bj < 2; ++bj) { const u32x4 b = bb[ai][m][bj];
;                     const f32x4 v0 = acc[ai][bj][m][0] + (f32x4){bflo(b.x), bfhi(b.x), bflo(b.y), bfhi(b.y)}, v1 = acc[ai][bj][m][1] + (f32x4){bflo(b.z), bfhi(b.z), bflo(b.w), bfhi(b.w)};
;                     u32x4 w; w.x = cvt_pk_bf16(v0[0], v0[1]); w.y = cvt_pk_bf16(v0[2], v0[3]); w.z = cvt_pk_bf16(v1[0], v1[1]); w.w = cvt_pk_bf16(v1[2], v1[3]);
;                     *(u32x4*)(xb + off + bj * HALF) = w;
;                     const float r0 = bflo(w.x), r1 = bfhi(w.x), r2 = bflo(w.y), r3 = bfhi(w.y), r4 = bflo(w.z), r5 = bfhi(w.z), r6 = bflo(w.w), r7 = bfhi(w.w);
;                     sq += ((r0 * r0 + r1 * r1) + (r2 * r2 + r3 * r3)) + ((r4 * r4 + r5 * r5) + (r6 * r6 + r7 * r7)); }
;                 sq += __shfl_xor(sq, 16); sq += __shfl_xor(sq, 32);
;                 if (fq == 0) part[(ai * HALF + wr * 64 + m * 16 + fr) * 4 + wc] = sq; }
.LBB0_156:
	s_or_b64 exec, exec, s[4:5]
	v_lshlrev_b32_e32 v126, 16, v184
	s_waitcnt lgkmcnt(0)
	v_and_b32_e32 v127, 0xffff0000, v184
	v_lshlrev_b32_e32 v140, 16, v185
	v_and_b32_e32 v141, 0xffff0000, v185
	v_pk_add_f32 v[118:119], v[118:119], v[140:141]
	v_pk_add_f32 v[116:117], v[116:117], v[126:127]
	v_lshlrev_b32_e32 v126, 16, v186
	v_and_b32_e32 v127, 0xffff0000, v186
	v_lshlrev_b32_e32 v140, 16, v187
	v_and_b32_e32 v141, 0xffff0000, v187
	v_pk_add_f32 v[140:141], v[114:115], v[140:141]
	v_pk_add_f32 v[114:115], v[112:113], v[126:127]
	v_cvt_pk_bf16_f32 v112, v116, v117
	v_lshl_add_u64 v[116:117], s[18:19], 0, v[214:215]
	v_cvt_pk_bf16_f32 v113, v118, v119
	v_lshl_add_u64 v[116:117], v[192:193], 1, v[116:117]
	v_cvt_pk_bf16_f32 v114, v114, v115
	v_cvt_pk_bf16_f32 v115, v140, v141
	global_store_dwordx4 v[116:117], v[112:115], off
	v_lshlrev_b32_e32 v118, 16, v112
	v_lshlrev_b32_e32 v119, 16, v113
	v_and_b32_e32 v112, 0xffff0000, v112
	v_and_b32_e32 v113, 0xffff0000, v113
	v_mul_f32_e32 v112, v112, v112
	v_mul_f32_e32 v113, v113, v113
	v_lshlrev_b32_e32 v126, 16, v114
	v_and_b32_e32 v114, 0xffff0000, v114
	v_lshlrev_b32_e32 v127, 16, v115
	v_and_b32_e32 v115, 0xffff0000, v115
	v_fmac_f32_e32 v112, v118, v118
	v_fmac_f32_e32 v113, v119, v119
	v_add_f32_e32 v112, v112, v113
	v_mul_f32_e32 v113, v114, v114
	v_mul_f32_e32 v114, v115, v115
	v_fmac_f32_e32 v113, v126, v126
	v_fmac_f32_e32 v114, v127, v127
	v_add_f32_e32 v113, v113, v114
	v_add_f32_e32 v118, v112, v113
	v_lshlrev_b32_e32 v112, 16, v180
	v_and_b32_e32 v113, 0xffff0000, v180
	v_lshlrev_b32_e32 v114, 16, v181
	v_and_b32_e32 v115, 0xffff0000, v181
	v_pk_add_f32 v[104:105], v[104:105], v[112:113]
	v_lshlrev_b32_e32 v112, 16, v182
	v_and_b32_e32 v113, 0xffff0000, v182
	v_pk_add_f32 v[106:107], v[106:107], v[114:115]
	v_lshlrev_b32_e32 v114, 16, v183
	v_and_b32_e32 v115, 0xffff0000, v183
	v_pk_add_f32 v[100:101], v[100:101], v[112:113]
	v_pk_add_f32 v[114:115], v[102:103], v[114:115]
	v_cvt_pk_bf16_f32 v102, v104, v105
	v_cvt_pk_bf16_f32 v103, v106, v107
	v_cvt_pk_bf16_f32 v104, v100, v101
	s_nop 0
	v_and_b32_e32 v101, 0xffff0000, v102
	v_lshlrev_b32_e32 v100, 16, v102
	v_and_b32_e32 v107, 0xffff0000, v103
	v_mul_f32_e32 v101, v101, v101
	v_lshlrev_b32_e32 v106, 16, v103
	v_fmac_f32_e32 v101, v100, v100
	v_mul_f32_e32 v100, v107, v107
	v_cvt_pk_bf16_f32 v105, v114, v115
	v_and_b32_e32 v113, 0xffff0000, v104
	v_and_b32_e32 v115, 0xffff0000, v105
	v_fmac_f32_e32 v100, v106, v106
	v_lshlrev_b32_e32 v112, 16, v104
	v_lshlrev_b32_e32 v114, 16, v105
	v_add_f32_e32 v100, v101, v100
	v_mul_f32_e32 v101, v113, v113
	v_mul_f32_e32 v106, v115, v115
	v_fmac_f32_e32 v101, v112, v112
	v_fmac_f32_e32 v106, v114, v114
	v_add_f32_e32 v101, v101, v106
	v_add_f32_e32 v100, v100, v101
	v_add_f32_e32 v100, v118, v100
	ds_bpermute_b32 v101, v124, v100
	global_store_dwordx4 v[116:117], v[102:105], off offset:256
	s_waitcnt lgkmcnt(0)
	v_add_f32_e32 v100, v100, v101
	ds_bpermute_b32 v101, v125, v100
	s_and_saveexec_b64 s[4:5], s[6:7]
	s_cbranch_execz .LBB0_158
	s_waitcnt lgkmcnt(0)
	v_add_f32_e32 v100, v100, v101
	ds_write_b32 v246, v100 offset:256
.LBB0_158:
	s_or_b64 exec, exec, s[4:5]
	v_lshlrev_b32_e32 v100, 16, v176
	s_waitcnt lgkmcnt(0)
	v_and_b32_e32 v101, 0xffff0000, v176
	v_lshlrev_b32_e32 v102, 16, v177
	v_and_b32_e32 v103, 0xffff0000, v177
	v_pk_add_f32 v[98:99], v[98:99], v[102:103]
	v_pk_add_f32 v[96:97], v[96:97], v[100:101]
	v_lshlrev_b32_e32 v100, 16, v178
	v_and_b32_e32 v101, 0xffff0000, v178
	v_lshlrev_b32_e32 v102, 16, v179
	v_and_b32_e32 v103, 0xffff0000, v179
	v_pk_add_f32 v[102:103], v[94:95], v[102:103]
	v_pk_add_f32 v[94:95], v[92:93], v[100:101]
	v_cvt_pk_bf16_f32 v92, v96, v97
	v_lshl_add_u64 v[96:97], s[18:19], 0, v[212:213]
	v_cvt_pk_bf16_f32 v93, v98, v99
	v_lshl_add_u64 v[96:97], v[192:193], 1, v[96:97]
	v_cvt_pk_bf16_f32 v94, v94, v95
	v_cvt_pk_bf16_f32 v95, v102, v103
	global_store_dwordx4 v[96:97], v[92:95], off
	v_lshlrev_b32_e32 v98, 16, v92
	v_lshlrev_b32_e32 v99, 16, v93
	v_and_b32_e32 v92, 0xffff0000, v92
	v_and_b32_e32 v93, 0xffff0000, v93
	v_mul_f32_e32 v92, v92, v92
	v_mul_f32_e32 v93, v93, v93
	v_lshlrev_b32_e32 v100, 16, v94
	v_and_b32_e32 v94, 0xffff0000, v94
	v_lshlrev_b32_e32 v101, 16, v95
	v_and_b32_e32 v95, 0xffff0000, v95
	v_fmac_f32_e32 v92, v98, v98
	v_fmac_f32_e32 v93, v99, v99
	v_add_f32_e32 v92, v92, v93
	v_mul_f32_e32 v93, v94, v94
	v_mul_f32_e32 v94, v95, v95
	v_fmac_f32_e32 v93, v100, v100
	v_fmac_f32_e32 v94, v101, v101
	v_add_f32_e32 v93, v93, v94
	v_add_f32_e32 v98, v92, v93
	v_lshlrev_b32_e32 v92, 16, v164
	v_and_b32_e32 v93, 0xffff0000, v164
	v_lshlrev_b32_e32 v94, 16, v165
	v_and_b32_e32 v95, 0xffff0000, v165
	v_pk_add_f32 v[88:89], v[88:89], v[92:93]
	v_lshlrev_b32_e32 v92, 16, v166
	v_and_b32_e32 v93, 0xffff0000, v166
	v_pk_add_f32 v[90:91], v[90:91], v[94:95]
	v_lshlrev_b32_e32 v94, 16, v167
	v_and_b32_e32 v95, 0xffff0000, v167
	v_pk_add_f32 v[84:85], v[84:85], v[92:93]
	v_pk_add_f32 v[94:95], v[86:87], v[94:95]
	v_cvt_pk_bf16_f32 v86, v88, v89
	v_cvt_pk_bf16_f32 v87, v90, v91
	v_cvt_pk_bf16_f32 v88, v84, v85
	s_nop 0
	v_and_b32_e32 v85, 0xffff0000, v86
	v_lshlrev_b32_e32 v84, 16, v86
	v_and_b32_e32 v91, 0xffff0000, v87
	v_mul_f32_e32 v85, v85, v85
	v_lshlrev_b32_e32 v90, 16, v87
	v_fmac_f32_e32 v85, v84, v84
	v_mul_f32_e32 v84, v91, v91
	v_cvt_pk_bf16_f32 v89, v94, v95
	v_and_b32_e32 v93, 0xffff0000, v88
	v_and_b32_e32 v95, 0xffff0000, v89
	v_fmac_f32_e32 v84, v90, v90
	v_lshlrev_b32_e32 v92, 16, v88
	v_lshlrev_b32_e32 v94, 16, v89
	v_add_f32_e32 v84, v85, v84
	v_mul_f32_e32 v85, v93, v93
	v_mul_f32_e32 v90, v95, v95
	v_fmac_f32_e32 v85, v92, v92
	v_fmac_f32_e32 v90, v94, v94
	v_add_f32_e32 v85, v85, v90
	v_add_f32_e32 v84, v84, v85
	v_add_f32_e32 v84, v98, v84
	ds_bpermute_b32 v85, v124, v84
	global_store_dwordx4 v[96:97], v[86:89], off offset:256
	s_waitcnt lgkmcnt(0)
	v_add_f32_e32 v84, v84, v85
	ds_bpermute_b32 v85, v125, v84
	s_and_saveexec_b64 s[4:5], s[6:7]
	s_cbranch_execz .LBB0_160
	s_waitcnt lgkmcnt(0)
	v_add_f32_e32 v84, v84, v85
	ds_write_b32 v246, v84 offset:512
; __device__ __forceinline__ unsigned cvt_pk_bf16(float lo, float hi) { unsigned r; asm volatile("v_cvt_pk_bf16_f32 %0, %1, %2" : "=v"(r) : "v"(lo), "v"(hi)); return r; }
;     __device__ __forceinline__ void operator()(const f32x4 (&acc)[2][2][4][2], const Unit& u, int wr, int wc, int fr, int fq) const {
;     ...
;             for (int m = 0; m < 4; ++m) { const size_t off = (size_t)(row0 + ai * HALF + m * 16) * D + col0; float sq = 0.f;
; #pragma unroll
;                 for (int bj = 0; bj < 2; ++bj) { const u32x4 b = bb[ai][m][bj];
;                     const f32x4 v0 = acc[ai][bj][m][0] + (f32x4){bflo(b.x), bfhi(b.x), bflo(b.y), bfhi(b.y)}, v1 = acc[ai][bj][m][1] + (f32x4){bflo(b.z), bfhi(b.z), bflo(b.w), bfhi(b.w)};
;                     u32x4 w; w.x = cvt_pk_bf16(v0[0], v0[1]); w.y = cvt_pk_bf16(v0[2], v0[3]); w.z = cvt_pk_bf16(v1[0], v1[1]); w.w = cvt_pk_bf16(v1[2], v1[3]);
;                     *(u32x4*)(xb + off + bj * HALF) = w;
;                     const float r0 = bflo(w.x), r1 = bfhi(w.x), r2 = bflo(w.y), r3 = bfhi(w.y), r4 = bflo(w.z), r5 = bfhi(w.z), r6 = bflo(w.w), r7 = bfhi(w.w);
;                     sq += ((r0 * r0 + r1 * r1) + (r2 * r2 + r3 * r3)) + ((r4 * r4 + r5 * r5) + (r6 * r6 + r7 * r7)); }
;                 sq += __shfl_xor(sq, 16); sq += __shfl_xor(sq, 32);
;                 if (fq == 0) part[(ai * HALF + wr * 64 + m * 16 + fr) * 4 + wc] = sq; }
.LBB0_160:
	s_or_b64 exec, exec, s[4:5]
	v_lshlrev_b32_e32 v84, 16, v160
	s_waitcnt lgkmcnt(0)
	v_and_b32_e32 v85, 0xffff0000, v160
	v_lshlrev_b32_e32 v86, 16, v161
	v_and_b32_e32 v87, 0xffff0000, v161
	v_pk_add_f32 v[82:83], v[82:83], v[86:87]
	v_pk_add_f32 v[80:81], v[80:81], v[84:85]
	v_lshlrev_b32_e32 v84, 16, v162
	v_and_b32_e32 v85, 0xffff0000, v162
	v_lshlrev_b32_e32 v86, 16, v163
	v_and_b32_e32 v87, 0xffff0000, v163
	v_pk_add_f32 v[86:87], v[78:79], v[86:87]
	v_pk_add_f32 v[78:79], v[76:77], v[84:85]
	v_cvt_pk_bf16_f32 v76, v80, v81
	v_lshl_add_u64 v[80:81], s[18:19], 0, v[210:211]
	v_cvt_pk_bf16_f32 v77, v82, v83
	v_lshl_add_u64 v[80:81], v[192:193], 1, v[80:81]
	v_cvt_pk_bf16_f32 v78, v78, v79
	v_cvt_pk_bf16_f32 v79, v86, v87
	global_store_dwordx4 v[80:81], v[76:79], off
	v_lshlrev_b32_e32 v82, 16, v76
	v_lshlrev_b32_e32 v83, 16, v77
	v_and_b32_e32 v76, 0xffff0000, v76
	v_and_b32_e32 v77, 0xffff0000, v77
	v_mul_f32_e32 v76, v76, v76
	v_mul_f32_e32 v77, v77, v77
	v_lshlrev_b32_e32 v84, 16, v78
	v_and_b32_e32 v78, 0xffff0000, v78
	v_lshlrev_b32_e32 v85, 16, v79
	v_and_b32_e32 v79, 0xffff0000, v79
	v_fmac_f32_e32 v76, v82, v82
	v_fmac_f32_e32 v77, v83, v83
	v_add_f32_e32 v76, v76, v77
	v_mul_f32_e32 v77, v78, v78
	v_mul_f32_e32 v78, v79, v79
	v_fmac_f32_e32 v77, v84, v84
	v_fmac_f32_e32 v78, v85, v85
	v_add_f32_e32 v77, v77, v78
	v_add_f32_e32 v82, v76, v77
	v_lshlrev_b32_e32 v76, 16, v156
	v_and_b32_e32 v77, 0xffff0000, v156
	v_lshlrev_b32_e32 v78, 16, v157
	v_and_b32_e32 v79, 0xffff0000, v157
	v_pk_add_f32 v[72:73], v[72:73], v[76:77]
	v_lshlrev_b32_e32 v76, 16, v158
	v_and_b32_e32 v77, 0xffff0000, v158
	v_pk_add_f32 v[74:75], v[74:75], v[78:79]
	v_lshlrev_b32_e32 v78, 16, v159
	v_and_b32_e32 v79, 0xffff0000, v159
	v_pk_add_f32 v[68:69], v[68:69], v[76:77]
	v_pk_add_f32 v[78:79], v[70:71], v[78:79]
	v_cvt_pk_bf16_f32 v70, v72, v73
	v_cvt_pk_bf16_f32 v71, v74, v75
	v_cvt_pk_bf16_f32 v72, v68, v69
	s_nop 0
	v_and_b32_e32 v69, 0xffff0000, v70
	v_lshlrev_b32_e32 v68, 16, v70
	v_and_b32_e32 v75, 0xffff0000, v71
	v_mul_f32_e32 v69, v69, v69
	v_lshlrev_b32_e32 v74, 16, v71
	v_fmac_f32_e32 v69, v68, v68
	v_mul_f32_e32 v68, v75, v75
	v_cvt_pk_bf16_f32 v73, v78, v79
	v_and_b32_e32 v77, 0xffff0000, v72
	v_and_b32_e32 v79, 0xffff0000, v73
	v_fmac_f32_e32 v68, v74, v74
	v_lshlrev_b32_e32 v76, 16, v72
	v_lshlrev_b32_e32 v78, 16, v73
	v_add_f32_e32 v68, v69, v68
	v_mul_f32_e32 v69, v77, v77
	v_mul_f32_e32 v74, v79, v79
	v_fmac_f32_e32 v69, v76, v76
	v_fmac_f32_e32 v74, v78, v78
	v_add_f32_e32 v69, v69, v74
	v_add_f32_e32 v68, v68, v69
	v_add_f32_e32 v68, v82, v68
	ds_bpermute_b32 v69, v124, v68
	global_store_dwordx4 v[80:81], v[70:73], off offset:256
	s_waitcnt lgkmcnt(0)
	v_add_f32_e32 v68, v68, v69
	ds_bpermute_b32 v69, v125, v68
	s_and_saveexec_b64 s[4:5], s[6:7]
	s_cbranch_execz .LBB0_162
	s_waitcnt lgkmcnt(0)
	v_add_f32_e32 v68, v68, v69
	ds_write_b32 v246, v68 offset:768
.LBB0_162:
	s_or_b64 exec, exec, s[4:5]
	v_lshlrev_b32_e32 v68, 16, v152
	s_waitcnt lgkmcnt(0)
	v_and_b32_e32 v69, 0xffff0000, v152
	v_lshlrev_b32_e32 v70, 16, v153
	v_and_b32_e32 v71, 0xffff0000, v153
	v_pk_add_f32 v[66:67], v[66:67], v[70:71]
	v_pk_add_f32 v[64:65], v[64:65], v[68:69]
	v_lshlrev_b32_e32 v68, 16, v154
	v_and_b32_e32 v69, 0xffff0000, v154
	v_lshlrev_b32_e32 v70, 16, v155
	v_and_b32_e32 v71, 0xffff0000, v155
	v_pk_add_f32 v[70:71], v[62:63], v[70:71]
	v_pk_add_f32 v[62:63], v[60:61], v[68:69]
	v_cvt_pk_bf16_f32 v60, v64, v65
	v_lshl_add_u64 v[64:65], s[18:19], 0, v[208:209]
	v_cvt_pk_bf16_f32 v61, v66, v67
	v_lshl_add_u64 v[64:65], v[192:193], 1, v[64:65]
	v_cvt_pk_bf16_f32 v62, v62, v63
	v_cvt_pk_bf16_f32 v63, v70, v71
	global_store_dwordx4 v[64:65], v[60:63], off
	v_lshlrev_b32_e32 v66, 16, v60
	v_lshlrev_b32_e32 v67, 16, v61
	v_and_b32_e32 v60, 0xffff0000, v60
	v_and_b32_e32 v61, 0xffff0000, v61
	v_mul_f32_e32 v60, v60, v60
	v_mul_f32_e32 v61, v61, v61
	v_lshlrev_b32_e32 v68, 16, v62
	v_and_b32_e32 v62, 0xffff0000, v62
	v_lshlrev_b32_e32 v69, 16, v63
	v_and_b32_e32 v63, 0xffff0000, v63
	v_fmac_f32_e32 v60, v66, v66
	v_fmac_f32_e32 v61, v67, v67
	v_add_f32_e32 v60, v60, v61
	v_mul_f32_e32 v61, v62, v62
	v_mul_f32_e32 v62, v63, v63
	v_fmac_f32_e32 v61, v68, v68
	v_fmac_f32_e32 v62, v69, v69
	v_add_f32_e32 v61, v61, v62
	v_add_f32_e32 v66, v60, v61
	v_lshlrev_b32_e32 v60, 16, v148
	v_and_b32_e32 v61, 0xffff0000, v148
	v_lshlrev_b32_e32 v62, 16, v149
	v_and_b32_e32 v63, 0xffff0000, v149
	v_pk_add_f32 v[56:57], v[56:57], v[60:61]
	v_lshlrev_b32_e32 v60, 16, v150
	v_and_b32_e32 v61, 0xffff0000, v150
	v_pk_add_f32 v[58:59], v[58:59], v[62:63]
	v_lshlrev_b32_e32 v62, 16, v151
	v_and_b32_e32 v63, 0xffff0000, v151
	v_pk_add_f32 v[52:53], v[52:53], v[60:61]
	v_pk_add_f32 v[62:63], v[54:55], v[62:63]
	v_cvt_pk_bf16_f32 v54, v56, v57
	v_cvt_pk_bf16_f32 v55, v58, v59
	v_cvt_pk_bf16_f32 v56, v52, v53
	s_nop 0
	v_and_b32_e32 v53, 0xffff0000, v54
	v_lshlrev_b32_e32 v52, 16, v54
	v_and_b32_e32 v59, 0xffff0000, v55
	v_mul_f32_e32 v53, v53, v53
	v_lshlrev_b32_e32 v58, 16, v55
	v_fmac_f32_e32 v53, v52, v52
	v_mul_f32_e32 v52, v59, v59
	v_cvt_pk_bf16_f32 v57, v62, v63
	v_and_b32_e32 v61, 0xffff0000, v56
	v_and_b32_e32 v63, 0xffff0000, v57
	v_fmac_f32_e32 v52, v58, v58
	v_lshlrev_b32_e32 v60, 16, v56
	v_lshlrev_b32_e32 v62, 16, v57
	v_add_f32_e32 v52, v53, v52
	v_mul_f32_e32 v53, v61, v61
	v_mul_f32_e32 v58, v63, v63
	v_fmac_f32_e32 v53, v60, v60
	v_fmac_f32_e32 v58, v62, v62
	v_add_f32_e32 v53, v53, v58
	v_add_f32_e32 v52, v52, v53
	v_add_f32_e32 v52, v66, v52
	ds_bpermute_b32 v53, v124, v52
	global_store_dwordx4 v[64:65], v[54:57], off offset:256
	s_waitcnt lgkmcnt(0)
	v_add_f32_e32 v52, v52, v53
	ds_bpermute_b32 v53, v125, v52
	s_and_saveexec_b64 s[4:5], s[6:7]
	s_cbranch_execz .LBB0_164
	s_waitcnt lgkmcnt(0)
	v_add_f32_e32 v52, v52, v53
	ds_write_b32 v246, v52 offset:2048
; __device__ __forceinline__ unsigned cvt_pk_bf16(float lo, float hi) { unsigned r; asm volatile("v_cvt_pk_bf16_f32 %0, %1, %2" : "=v"(r) : "v"(lo), "v"(hi)); return r; }
;     __device__ __forceinline__ void operator()(const f32x4 (&acc)[2][2][4][2], const Unit& u, int wr, int wc, int fr, int fq) const {
;     ...
;             for (int m = 0; m < 4; ++m) { const size_t off = (size_t)(row0 + ai * HALF + m * 16) * D + col0; float sq = 0.f;
; #pragma unroll
;                 for (int bj = 0; bj < 2; ++bj) { const u32x4 b = bb[ai][m][bj];
;                     const f32x4 v0 = acc[ai][bj][m][0] + (f32x4){bflo(b.x), bfhi(b.x), bflo(b.y), bfhi(b.y)}, v1 = acc[ai][bj][m][1] + (f32x4){bflo(b.z), bfhi(b.z), bflo(b.w), bfhi(b.w)};
;                     u32x4 w; w.x = cvt_pk_bf16(v0[0], v0[1]); w.y = cvt_pk_bf16(v0[2], v0[3]); w.z = cvt_pk_bf16(v1[0], v1[1]); w.w = cvt_pk_bf16(v1[2], v1[3]);
;                     *(u32x4*)(xb + off + bj * HALF) = w;
;                     const float r0 = bflo(w.x), r1 = bfhi(w.x), r2 = bflo(w.y), r3 = bfhi(w.y), r4 = bflo(w.z), r5 = bfhi(w.z), r6 = bflo(w.w), r7 = bfhi(w.w);
;                     sq += ((r0 * r0 + r1 * r1) + (r2 * r2 + r3 * r3)) + ((r4 * r4 + r5 * r5) + (r6 * r6 + r7 * r7)); }
;                 sq += __shfl_xor(sq, 16); sq += __shfl_xor(sq, 32);
;                 if (fq == 0) part[(ai * HALF + wr * 64 + m * 16 + fr) * 4 + wc] = sq; }
.LBB0_164:
	s_or_b64 exec, exec, s[4:5]
	v_lshlrev_b32_e32 v52, 16, v144
	s_waitcnt lgkmcnt(0)
	v_and_b32_e32 v53, 0xffff0000, v144
	v_lshlrev_b32_e32 v54, 16, v145
	v_and_b32_e32 v55, 0xffff0000, v145
	v_pk_add_f32 v[50:51], v[50:51], v[54:55]
	v_pk_add_f32 v[48:49], v[48:49], v[52:53]
	v_lshlrev_b32_e32 v52, 16, v146
	v_and_b32_e32 v53, 0xffff0000, v146
	v_lshlrev_b32_e32 v54, 16, v147
	v_and_b32_e32 v55, 0xffff0000, v147
	v_pk_add_f32 v[54:55], v[46:47], v[54:55]
	v_pk_add_f32 v[46:47], v[44:45], v[52:53]
	v_cvt_pk_bf16_f32 v44, v48, v49
	v_lshl_add_u64 v[48:49], s[18:19], 0, v[206:207]
	v_cvt_pk_bf16_f32 v45, v50, v51
	v_lshl_add_u64 v[48:49], v[192:193], 1, v[48:49]
	v_cvt_pk_bf16_f32 v46, v46, v47
	v_cvt_pk_bf16_f32 v47, v54, v55
	global_store_dwordx4 v[48:49], v[44:47], off
	v_lshlrev_b32_e32 v50, 16, v44
	v_lshlrev_b32_e32 v51, 16, v45
	v_and_b32_e32 v44, 0xffff0000, v44
	v_and_b32_e32 v45, 0xffff0000, v45
	v_mul_f32_e32 v44, v44, v44
	v_mul_f32_e32 v45, v45, v45
	v_lshlrev_b32_e32 v52, 16, v46
	v_and_b32_e32 v46, 0xffff0000, v46
	v_lshlrev_b32_e32 v53, 16, v47
	v_and_b32_e32 v47, 0xffff0000, v47
	v_fmac_f32_e32 v44, v50, v50
	v_fmac_f32_e32 v45, v51, v51
	v_add_f32_e32 v44, v44, v45
	v_mul_f32_e32 v45, v46, v46
	v_mul_f32_e32 v46, v47, v47
	v_fmac_f32_e32 v45, v52, v52
	v_fmac_f32_e32 v46, v53, v53
	v_add_f32_e32 v45, v45, v46
	v_add_f32_e32 v50, v44, v45
	v_lshlrev_b32_e32 v44, 16, v136
	v_and_b32_e32 v45, 0xffff0000, v136
	v_lshlrev_b32_e32 v46, 16, v137
	v_and_b32_e32 v47, 0xffff0000, v137
	v_pk_add_f32 v[40:41], v[40:41], v[44:45]
	v_lshlrev_b32_e32 v44, 16, v138
	v_and_b32_e32 v45, 0xffff0000, v138
	v_pk_add_f32 v[42:43], v[42:43], v[46:47]
	v_lshlrev_b32_e32 v46, 16, v139
	v_and_b32_e32 v47, 0xffff0000, v139
	v_pk_add_f32 v[36:37], v[36:37], v[44:45]
	v_pk_add_f32 v[46:47], v[38:39], v[46:47]
	v_cvt_pk_bf16_f32 v38, v40, v41
	v_cvt_pk_bf16_f32 v39, v42, v43
	v_cvt_pk_bf16_f32 v40, v36, v37
	s_nop 0
	v_and_b32_e32 v37, 0xffff0000, v38
	v_lshlrev_b32_e32 v36, 16, v38
	v_and_b32_e32 v43, 0xffff0000, v39
	v_mul_f32_e32 v37, v37, v37
	v_lshlrev_b32_e32 v42, 16, v39
	v_fmac_f32_e32 v37, v36, v36
	v_mul_f32_e32 v36, v43, v43
	v_cvt_pk_bf16_f32 v41, v46, v47
	v_and_b32_e32 v45, 0xffff0000, v40
	v_and_b32_e32 v47, 0xffff0000, v41
	v_fmac_f32_e32 v36, v42, v42
	v_lshlrev_b32_e32 v44, 16, v40
	v_lshlrev_b32_e32 v46, 16, v41
	v_add_f32_e32 v36, v37, v36
	v_mul_f32_e32 v37, v45, v45
	v_mul_f32_e32 v42, v47, v47
	v_fmac_f32_e32 v37, v44, v44
	v_fmac_f32_e32 v42, v46, v46
	v_add_f32_e32 v37, v37, v42
	v_add_f32_e32 v36, v36, v37
	v_add_f32_e32 v36, v50, v36
	ds_bpermute_b32 v37, v124, v36
	global_store_dwordx4 v[48:49], v[38:41], off offset:256
	s_waitcnt lgkmcnt(0)
	v_add_f32_e32 v36, v36, v37
	ds_bpermute_b32 v37, v125, v36
	s_and_saveexec_b64 s[4:5], s[6:7]
	s_cbranch_execz .LBB0_166
	s_waitcnt lgkmcnt(0)
	v_add_f32_e32 v36, v36, v37
	ds_write_b32 v246, v36 offset:2304
.LBB0_166:
	s_or_b64 exec, exec, s[4:5]
	v_lshlrev_b32_e32 v36, 16, v132
	s_waitcnt lgkmcnt(0)
	v_and_b32_e32 v37, 0xffff0000, v132
	v_lshlrev_b32_e32 v38, 16, v133
	v_and_b32_e32 v39, 0xffff0000, v133
	v_pk_add_f32 v[34:35], v[34:35], v[38:39]
	v_pk_add_f32 v[32:33], v[32:33], v[36:37]
	v_lshlrev_b32_e32 v36, 16, v134
	v_and_b32_e32 v37, 0xffff0000, v134
	v_lshlrev_b32_e32 v38, 16, v135
	v_and_b32_e32 v39, 0xffff0000, v135
	v_pk_add_f32 v[38:39], v[30:31], v[38:39]
	v_pk_add_f32 v[30:31], v[28:29], v[36:37]
	v_cvt_pk_bf16_f32 v28, v32, v33
	v_lshl_add_u64 v[32:33], s[18:19], 0, v[204:205]
	v_cvt_pk_bf16_f32 v29, v34, v35
	v_lshl_add_u64 v[32:33], v[192:193], 1, v[32:33]
	v_cvt_pk_bf16_f32 v30, v30, v31
	v_cvt_pk_bf16_f32 v31, v38, v39
	global_store_dwordx4 v[32:33], v[28:31], off
	v_lshlrev_b32_e32 v34, 16, v28
	v_lshlrev_b32_e32 v35, 16, v29
	v_and_b32_e32 v28, 0xffff0000, v28
	v_and_b32_e32 v29, 0xffff0000, v29
	v_mul_f32_e32 v28, v28, v28
	v_mul_f32_e32 v29, v29, v29
	v_lshlrev_b32_e32 v36, 16, v30
	v_and_b32_e32 v30, 0xffff0000, v30
	v_lshlrev_b32_e32 v37, 16, v31
	v_and_b32_e32 v31, 0xffff0000, v31
	v_fmac_f32_e32 v28, v34, v34
	v_fmac_f32_e32 v29, v35, v35
	v_add_f32_e32 v28, v28, v29
	v_mul_f32_e32 v29, v30, v30
	v_mul_f32_e32 v30, v31, v31
	v_fmac_f32_e32 v29, v36, v36
	v_fmac_f32_e32 v30, v37, v37
	v_add_f32_e32 v29, v29, v30
	v_add_f32_e32 v34, v28, v29
	v_lshlrev_b32_e32 v28, 16, v128
	v_and_b32_e32 v29, 0xffff0000, v128
	v_lshlrev_b32_e32 v30, 16, v129
	v_and_b32_e32 v31, 0xffff0000, v129
	v_pk_add_f32 v[24:25], v[24:25], v[28:29]
	v_lshlrev_b32_e32 v28, 16, v130
	v_and_b32_e32 v29, 0xffff0000, v130
	v_pk_add_f32 v[26:27], v[26:27], v[30:31]
	v_lshlrev_b32_e32 v30, 16, v131
	v_and_b32_e32 v31, 0xffff0000, v131
	v_pk_add_f32 v[20:21], v[20:21], v[28:29]
	v_pk_add_f32 v[30:31], v[22:23], v[30:31]
	v_cvt_pk_bf16_f32 v22, v24, v25
	v_cvt_pk_bf16_f32 v23, v26, v27
	v_cvt_pk_bf16_f32 v24, v20, v21
	s_nop 0
	v_and_b32_e32 v21, 0xffff0000, v22
	v_lshlrev_b32_e32 v20, 16, v22
	v_and_b32_e32 v27, 0xffff0000, v23
	v_mul_f32_e32 v21, v21, v21
	v_lshlrev_b32_e32 v26, 16, v23
	v_fmac_f32_e32 v21, v20, v20
	v_mul_f32_e32 v20, v27, v27
	v_cvt_pk_bf16_f32 v25, v30, v31
	v_and_b32_e32 v29, 0xffff0000, v24
	v_and_b32_e32 v31, 0xffff0000, v25
	v_fmac_f32_e32 v20, v26, v26
	v_lshlrev_b32_e32 v28, 16, v24
	v_lshlrev_b32_e32 v30, 16, v25
	v_add_f32_e32 v20, v21, v20
	v_mul_f32_e32 v21, v29, v29
	v_mul_f32_e32 v26, v31, v31
	v_fmac_f32_e32 v21, v28, v28
	v_fmac_f32_e32 v26, v30, v30
	v_add_f32_e32 v21, v21, v26
	v_add_f32_e32 v20, v20, v21
	v_add_f32_e32 v20, v34, v20
	ds_bpermute_b32 v21, v124, v20
	global_store_dwordx4 v[32:33], v[22:25], off offset:256
	s_waitcnt lgkmcnt(0)
	v_add_f32_e32 v20, v20, v21
	ds_bpermute_b32 v21, v125, v20
	s_and_saveexec_b64 s[4:5], s[6:7]
	s_cbranch_execz .LBB0_168
	s_waitcnt lgkmcnt(0)
	v_add_f32_e32 v20, v20, v21
	ds_write_b32 v246, v20 offset:2560
; #define LAS __attribute__((address_space(3)))
; __device__ __forceinline__ unsigned cvt_pk_bf16(float lo, float hi) { unsigned r; asm volatile("v_cvt_pk_bf16_f32 %0, %1, %2" : "=v"(r) : "v"(lo), "v"(hi)); return r; }
;     __device__ __forceinline__ void operator()(const f32x4 (&acc)[2][2][4][2], const Unit& u, int wr, int wc, int fr, int fq) const {
;     ...
;             for (int m = 0; m < 4; ++m) { const size_t off = (size_t)(row0 + ai * HALF + m * 16) * D + col0; float sq = 0.f;
; #pragma unroll
;                 for (int bj = 0; bj < 2; ++bj) { const u32x4 b = bb[ai][m][bj];
;                     const f32x4 v0 = acc[ai][bj][m][0] + (f32x4){bflo(b.x), bfhi(b.x), bflo(b.y), bfhi(b.y)}, v1 = acc[ai][bj][m][1] + (f32x4){bflo(b.z), bfhi(b.z), bflo(b.w), bfhi(b.w)};
;                     u32x4 w; w.x = cvt_pk_bf16(v0[0], v0[1]); w.y = cvt_pk_bf16(v0[2], v0[3]); w.z = cvt_pk_bf16(v1[0], v1[1]); w.w = cvt_pk_bf16(v1[2], v1[3]);
;                     *(u32x4*)(xb + off + bj * HALF) = w;
;                     const float r0 = bflo(w.x), r1 = bfhi(w.x), r2 = bflo(w.y), r3 = bfhi(w.y), r4 = bflo(w.z), r5 = bfhi(w.z), r6 = bflo(w.w), r7 = bfhi(w.w);
;                     sq += ((r0 * r0 + r1 * r1) + (r2 * r2 + r3 * r3)) + ((r4 * r4 + r5 * r5) + (r6 * r6 + r7 * r7)); }
;                 sq += __shfl_xor(sq, 16); sq += __shfl_xor(sq, 32);
;                 if (fq == 0) part[(ai * HALF + wr * 64 + m * 16 + fr) * 4 + wc] = sq; }
;         asm volatile("s_waitcnt lgkmcnt(0)" ::: "memory"); __builtin_amdgcn_s_barrier(); asm volatile("" ::: "memory");
;         const int t = threadIdx.x;
;         if (t < 256) { const f32x4 p = *(const LAS f32x4*)(part + t * 4); ssn[(size_t)(u.pm * BM + t) * 4 + u.pn] = (p.x + p.y) + (p.z + p.w); }
.LBB0_168:
	s_or_b64 exec, exec, s[4:5]
	v_lshlrev_b32_e32 v20, 16, v120
	s_waitcnt lgkmcnt(0)
	v_and_b32_e32 v21, 0xffff0000, v120
	v_lshlrev_b32_e32 v22, 16, v121
	v_and_b32_e32 v23, 0xffff0000, v121
	v_pk_add_f32 v[18:19], v[18:19], v[22:23]
	v_pk_add_f32 v[16:17], v[16:17], v[20:21]
	v_lshlrev_b32_e32 v20, 16, v122
	v_and_b32_e32 v21, 0xffff0000, v122
	v_lshlrev_b32_e32 v22, 16, v123
	v_and_b32_e32 v23, 0xffff0000, v123
	v_pk_add_f32 v[22:23], v[14:15], v[22:23]
	v_pk_add_f32 v[14:15], v[12:13], v[20:21]
	v_cvt_pk_bf16_f32 v12, v16, v17
	v_lshl_add_u64 v[16:17], s[18:19], 0, v[202:203]
	v_cvt_pk_bf16_f32 v13, v18, v19
	v_lshl_add_u64 v[16:17], v[192:193], 1, v[16:17]
	v_cvt_pk_bf16_f32 v14, v14, v15
	v_cvt_pk_bf16_f32 v15, v22, v23
	global_store_dwordx4 v[16:17], v[12:15], off
	v_lshlrev_b32_e32 v18, 16, v12
	v_lshlrev_b32_e32 v19, 16, v13
	v_and_b32_e32 v12, 0xffff0000, v12
	v_and_b32_e32 v13, 0xffff0000, v13
	v_mul_f32_e32 v12, v12, v12
	v_mul_f32_e32 v13, v13, v13
	v_lshlrev_b32_e32 v20, 16, v14
	v_and_b32_e32 v14, 0xffff0000, v14
	v_lshlrev_b32_e32 v21, 16, v15
	v_and_b32_e32 v15, 0xffff0000, v15
	v_fmac_f32_e32 v12, v18, v18
	v_fmac_f32_e32 v13, v19, v19
	v_add_f32_e32 v12, v12, v13
	v_mul_f32_e32 v13, v14, v14
	v_mul_f32_e32 v14, v15, v15
	v_fmac_f32_e32 v13, v20, v20
	v_fmac_f32_e32 v14, v21, v21
	v_add_f32_e32 v13, v13, v14
	v_add_f32_e32 v18, v12, v13
	v_lshlrev_b32_e32 v12, 16, v108
	v_and_b32_e32 v13, 0xffff0000, v108
	v_lshlrev_b32_e32 v14, 16, v109
	v_and_b32_e32 v15, 0xffff0000, v109
	v_pk_add_f32 v[8:9], v[8:9], v[12:13]
	v_lshlrev_b32_e32 v12, 16, v110
	v_and_b32_e32 v13, 0xffff0000, v110
	v_pk_add_f32 v[10:11], v[10:11], v[14:15]
	v_lshlrev_b32_e32 v14, 16, v111
	v_and_b32_e32 v15, 0xffff0000, v111
	v_pk_add_f32 v[4:5], v[4:5], v[12:13]
	v_pk_add_f32 v[14:15], v[6:7], v[14:15]
	v_cvt_pk_bf16_f32 v6, v8, v9
	v_cvt_pk_bf16_f32 v7, v10, v11
	v_cvt_pk_bf16_f32 v8, v4, v5
	s_nop 0
	v_and_b32_e32 v5, 0xffff0000, v6
	v_lshlrev_b32_e32 v4, 16, v6
	v_and_b32_e32 v11, 0xffff0000, v7
	v_mul_f32_e32 v5, v5, v5
	v_lshlrev_b32_e32 v10, 16, v7
	v_fmac_f32_e32 v5, v4, v4
	v_mul_f32_e32 v4, v11, v11
	v_cvt_pk_bf16_f32 v9, v14, v15
	v_and_b32_e32 v13, 0xffff0000, v8
	v_and_b32_e32 v15, 0xffff0000, v9
	v_fmac_f32_e32 v4, v10, v10
	v_lshlrev_b32_e32 v12, 16, v8
	v_lshlrev_b32_e32 v14, 16, v9
	v_add_f32_e32 v4, v5, v4
	v_mul_f32_e32 v5, v13, v13
	v_mul_f32_e32 v10, v15, v15
	v_fmac_f32_e32 v5, v12, v12
	v_fmac_f32_e32 v10, v14, v14
	v_add_f32_e32 v5, v5, v10
	v_add_f32_e32 v4, v4, v5
	v_add_f32_e32 v4, v18, v4
	ds_bpermute_b32 v5, v124, v4
	global_store_dwordx4 v[16:17], v[6:9], off offset:256
	s_waitcnt lgkmcnt(0)
	v_add_f32_e32 v4, v4, v5
	ds_bpermute_b32 v5, v125, v4
	s_and_saveexec_b64 s[4:5], s[6:7]
	s_cbranch_execz .LBB0_170
	s_waitcnt lgkmcnt(0)
	v_add_f32_e32 v4, v4, v5
	ds_write_b32 v246, v4 offset:2816
.LBB0_170:
	s_or_b64 exec, exec, s[4:5]
	s_waitcnt lgkmcnt(0)
	s_barrier
	s_mov_b64 s[44:45], exec
	v_readlane_b32 s4, v254, 2
	v_readlane_b32 s5, v254, 3
	s_and_b64 s[4:5], s[44:45], s[4:5]
	s_mov_b64 exec, s[4:5]
	s_cbranch_execz .LBB0_172
	v_add_u32_e32 v4, 0, v221
	v_add_u32_e32 v4, 0x20800, v4
	s_waitcnt lgkmcnt(0)
	ds_read_b128 v[4:7], v4
	s_waitcnt lgkmcnt(0)
	v_mov_b32_e32 v8, v5
	v_mov_b32_e32 v9, v6
	v_mov_b32_e32 v5, v7
	v_pk_add_f32 v[4:5], v[8:9], v[4:5]
	s_nop 0
	v_add_f32_e32 v6, v4, v5
	v_or_b32_e32 v4, s35, v220
	v_ashrrev_i32_e32 v5, 31, v4
	s_ashr_i32 s35, s34, 31
	v_lshl_add_u64 v[4:5], v[4:5], 4, s[38:39]
	v_lshl_add_u64 v[4:5], s[34:35], 2, v[4:5]
	global_store_dword v[4:5], v6, off

;     __device__ __forceinline__ void operator()(f32x4 (&acc)[2][2][4][2], const Unit& u, int wr, int wc, int fr, int fq) const {
;     ...
;         u32x4 bb[2][4][2];
; #pragma unroll
;         for (int ai = 0; ai < 2; ++ai)
; #pragma unroll
;             for (int m = 0; m < 4; ++m)
; #pragma unroll
;                 for (int bj = 0; bj < 2; ++bj) bb[ai][m][bj] = *(const u32x4*)(xb + (size_t)(row0 + ai * HALF + m * 16) * D + col0 + bj * HALF);
; #pragma unroll
;         for (int ai = 0; ai < 2; ++ai)
; #pragma unroll
;             for (int m = 0; m < 4; ++m) { float sq = 0.f;
; #pragma unroll
;                 for (int bj = 0; bj < 2; ++bj) { const u32x4 b = bb[ai][m][bj];
;                     const f32x4 v0 = acc[ai][bj][m][0] + (f32x4){bflo(b.x), bfhi(b.x), bflo(b.y), bfhi(b.y)}, v1 = acc[ai][bj][m][1] + (f32x4){bflo(b.z), bfhi(b.z), bflo(b.w), bfhi(b.w)};
;                     acc[ai][bj][m][0] = v0; acc[ai][bj][m][1] = v1;
;                     sq += ((v0[0] * v0[0] + v0[1] * v0[1]) + (v0[2] * v0[2] + v0[3] * v0[3])) + ((v1[0] * v1[0] + v1[1] * v1[1]) + (v1[2] * v1[2] + v1[3] * v1[3])); }
;                 sq += __shfl_xor(sq, 16); sq += __shfl_xor(sq, 32);
;                 if (fq == 0) part[(ai * HALF + wr * 64 + m * 16 + fr) * 4 + wc] = sq; }
.LBB0_204:
	s_lshl_b32 s51, s14, 8
	v_add_u32_e32 v202, s51, v208
	v_lshl_or_b32 v204, s96, 8, v209
	v_ashrrev_i32_e32 v205, 31, v204
	v_ashrrev_i32_e32 v203, 31, v202
	v_lshl_add_u64 v[130:131], v[204:205], 1, s[18:19]
	v_lshlrev_b64 v[132:133], 11, v[202:203]
	v_lshl_add_u64 v[138:139], v[130:131], 0, v[132:133]
	global_load_dwordx4 v[190:193], v[138:139], off
	global_load_dwordx4 v[186:189], v[138:139], off offset:256
	v_or_b32_e32 v132, 16, v202
	v_ashrrev_i32_e32 v133, 31, v132
	v_lshlrev_b64 v[132:133], 11, v[132:133]
	v_lshl_add_u64 v[132:133], v[130:131], 0, v[132:133]
	global_load_dwordx4 v[182:185], v[132:133], off
	global_load_dwordx4 v[178:181], v[132:133], off offset:256
	v_or_b32_e32 v132, 32, v202
	v_ashrrev_i32_e32 v133, 31, v132
	v_lshlrev_b64 v[132:133], 11, v[132:133]
	v_lshl_add_u64 v[132:133], v[130:131], 0, v[132:133]
	global_load_dwordx4 v[174:177], v[132:133], off
	global_load_dwordx4 v[170:173], v[132:133], off offset:256
	v_or_b32_e32 v132, 48, v202
	v_ashrrev_i32_e32 v133, 31, v132
	v_lshlrev_b64 v[132:133], 11, v[132:133]
	v_lshl_add_u64 v[130:131], v[130:131], 0, v[132:133]
	s_mov_b64 s[4:5], 0x40000
	global_load_dwordx4 v[166:169], v[130:131], off
	global_load_dwordx4 v[162:165], v[130:131], off offset:256
	v_lshl_add_u64 v[130:131], v[138:139], 0, s[4:5]
	s_mov_b32 s4, 0x40000
	v_add_co_u32_e32 v132, vcc, s4, v138
	s_mov_b64 s[4:5], 0x48000
	s_nop 0
	v_addc_co_u32_e32 v133, vcc, 0, v139, vcc
	global_load_dwordx4 v[158:161], v[132:133], off
	global_load_dwordx4 v[154:157], v[130:131], off offset:256
	v_lshl_add_u64 v[130:131], v[138:139], 0, s[4:5]
	s_mov_b32 s4, 0x48000
	v_add_co_u32_e32 v132, vcc, s4, v138
	s_mov_b64 s[4:5], 0x50000
	s_nop 0
	v_addc_co_u32_e32 v133, vcc, 0, v139, vcc
	v_lshl_add_u64 v[134:135], v[138:139], 0, s[4:5]
	s_mov_b32 s4, 0x50000
	v_add_co_u32_e32 v136, vcc, s4, v138
	s_mov_b64 s[4:5], 0x58000
	s_nop 0
	v_addc_co_u32_e32 v137, vcc, 0, v139, vcc
	v_lshl_add_u64 v[140:141], v[138:139], 0, s[4:5]
	s_mov_b32 s4, 0x58000
	v_add_co_u32_e32 v138, vcc, s4, v138
	global_load_dwordx4 v[142:145], v[132:133], off
	s_nop 0
	global_load_dwordx4 v[130:133], v[130:131], off offset:256
	v_addc_co_u32_e32 v139, vcc, 0, v139, vcc
	global_load_dwordx4 v[150:153], v[136:137], off
	s_nop 0
	global_load_dwordx4 v[134:137], v[134:135], off offset:256
	s_nop 0
	global_load_dwordx4 v[146:149], v[138:139], off
	s_nop 0
	global_load_dwordx4 v[138:141], v[140:141], off offset:256
	v_and_b32_e32 v249, 64, v226
	v_xor_b32_e32 v248, 16, v226
	v_add_u32_e32 v249, 64, v249
	v_cmp_lt_i32_e32 vcc, v248, v249
	v_xor_b32_e32 v250, 32, v226
	s_waitcnt vmcnt(0) lgkmcnt(0)
	v_and_b32_e32 v251, 0xffff0000, v190
	v_cndmask_b32_e32 v248, v226, v248, vcc
	v_cmp_lt_i32_e32 vcc, v250, v249
	v_lshlrev_b32_e32 v248, 2, v248
	s_nop 0
	v_cndmask_b32_e32 v249, v226, v250, vcc
	v_lshlrev_b32_e32 v250, 16, v190
	v_lshlrev_b32_e32 v190, 16, v191
	v_and_b32_e32 v191, 0xffff0000, v191
	v_pk_add_f32 v[128:129], v[128:129], v[190:191]
	v_pk_add_f32 v[126:127], v[126:127], v[250:251]
	v_lshlrev_b32_e32 v190, 16, v192
	v_and_b32_e32 v191, 0xffff0000, v192
	v_lshlrev_b32_e32 v192, 16, v193
	v_and_b32_e32 v193, 0xffff0000, v193
	v_pk_add_f32 v[122:123], v[122:123], v[190:191]
	v_mul_f32_e32 v190, v127, v127
	v_mul_f32_e32 v191, v129, v129
	v_pk_add_f32 v[124:125], v[124:125], v[192:193]
	v_fmac_f32_e32 v190, v126, v126
	v_fmac_f32_e32 v191, v128, v128
	v_add_f32_e32 v190, v190, v191
	v_mul_f32_e32 v191, v123, v123
	v_mul_f32_e32 v192, v125, v125
	v_fmac_f32_e32 v191, v122, v122
	v_fmac_f32_e32 v192, v124, v124
	v_add_f32_e32 v191, v191, v192
	v_add_f32_e32 v192, v190, v191
	v_lshlrev_b32_e32 v190, 16, v186
	v_and_b32_e32 v191, 0xffff0000, v186
	v_lshlrev_b32_e32 v186, 16, v187
	v_and_b32_e32 v187, 0xffff0000, v187
	v_pk_add_f32 v[120:121], v[120:121], v[186:187]
	v_pk_add_f32 v[118:119], v[118:119], v[190:191]
	v_lshlrev_b32_e32 v186, 16, v188
	v_and_b32_e32 v187, 0xffff0000, v188
	v_lshlrev_b32_e32 v188, 16, v189
	v_and_b32_e32 v189, 0xffff0000, v189
	v_pk_add_f32 v[114:115], v[114:115], v[186:187]
	v_mul_f32_e32 v186, v119, v119
	v_mul_f32_e32 v187, v121, v121
	v_pk_add_f32 v[116:117], v[116:117], v[188:189]
	v_fmac_f32_e32 v186, v118, v118
	v_fmac_f32_e32 v187, v120, v120
	v_add_f32_e32 v186, v186, v187
	v_mul_f32_e32 v187, v115, v115
	v_mul_f32_e32 v188, v117, v117
	v_fmac_f32_e32 v187, v114, v114
	v_fmac_f32_e32 v188, v116, v116
	v_add_f32_e32 v187, v187, v188
	v_add_f32_e32 v186, v186, v187
	v_add_f32_e32 v186, v192, v186
	ds_bpermute_b32 v187, v248, v186
	v_lshlrev_b32_e32 v249, 2, v249
	s_waitcnt lgkmcnt(0)
	v_add_f32_e32 v186, v186, v187
	ds_bpermute_b32 v187, v249, v186
	s_and_saveexec_b64 s[4:5], s[6:7]
	s_cbranch_execz .LBB0_206
	s_waitcnt lgkmcnt(0)
	v_add_f32_e32 v186, v186, v187
	ds_write_b32 v247, v186

; #define LAS __attribute__((address_space(3)))
;     __device__ __forceinline__ void operator()(f32x4 (&acc)[2][2][4][2], const Unit& u, int wr, int wc, int fr, int fq) const {
;     ...
;         asm volatile("s_waitcnt lgkmcnt(0)" ::: "memory"); __builtin_amdgcn_s_barrier(); asm volatile("" ::: "memory");
;         const int t = threadIdx.x;
;         if (t < 256) { const f32x4 p = *(const LAS f32x4*)(part + t * 4); __hip_atomic_store(ssn + (size_t)(u.pm * BM + t) * 4 + u.pn, (p.x + p.y) + (p.z + p.w), __ATOMIC_RELAXED, __HIP_MEMORY_SCOPE_AGENT); }
.LBB0_220:
	s_or_b64 exec, exec, s[4:5]
	s_waitcnt lgkmcnt(0)
	s_barrier
	v_or_b32_e32 v2, s51, v220
	s_waitcnt lgkmcnt(0)
	v_ashrrev_i32_e32 v3, 31, v2
	s_mov_b64 s[4:5], exec
	v_readlane_b32 s42, v254, 2
	v_readlane_b32 s43, v254, 3
	s_and_b64 s[42:43], s[4:5], s[42:43]
	s_mov_b64 exec, s[42:43]
	s_cbranch_execz .LBB0_222
	v_add_u32_e32 v4, 0, v221
	v_add_u32_e32 v4, 0x20800, v4
	ds_read_b128 v[4:7], v4
	v_readlane_b32 s42, v254, 62
	v_readlane_b32 s43, v254, 63
	s_ashr_i32 s97, s96, 31
	s_waitcnt lgkmcnt(0)
	v_mov_b32_e32 v10, v5
	v_mov_b32_e32 v11, v6
	v_mov_b32_e32 v5, v7
	v_lshl_add_u64 v[8:9], v[2:3], 4, s[42:43]
	v_pk_add_f32 v[4:5], v[10:11], v[4:5]
	v_lshl_add_u64 v[8:9], s[96:97], 2, v[8:9]
	v_pk_add_f32 v[4:5], v[4:5], v[4:5] op_sel:[0,1] op_sel_hi:[1,0]
	global_store_dword v[8:9], v4, off sc1

;     __device__ __forceinline__ void operator()(f32x4 (&acc)[2][2][4][2], const Unit& u, int wr, int wc, int fr, int fq) const {
;     ...
;         if (t == 0) { unsigned* c = pcnt + 8 * u.pm; (void)__hip_atomic_fetch_add(c, 1u, __ATOMIC_RELAXED, __HIP_MEMORY_SCOPE_AGENT);
;             unsigned sp = 0; while (__hip_atomic_load(c, __ATOMIC_RELAXED, __HIP_MEMORY_SCOPE_AGENT) < 4u) { __builtin_amdgcn_s_sleep(1); if (++sp > (1u << 22)) break; }
;             __builtin_amdgcn_fence(__ATOMIC_ACQUIRE, "agent"); asm volatile("s_waitcnt vmcnt(0)" ::: "memory"); }
.LBB0_229:
	v_mov_b64_e32 v[4:5], s[44:45]
	global_load_dword v4, v[4:5], off sc1
	s_or_b64 s[56:57], s[56:57], exec
	s_waitcnt vmcnt(0) lgkmcnt(0)
	v_cmp_gt_u32_e32 vcc, 4, v4
	s_and_saveexec_b64 s[58:59], vcc
	s_cbranch_execz .LBB0_228
	v_mov_b64_e32 v[4:5], s[44:45]
	s_sleep 1
	global_load_dword v4, v[4:5], off sc1
	s_mov_b64 s[4:5], -1
	s_waitcnt vmcnt(0) lgkmcnt(0)
	v_cmp_gt_u32_e32 vcc, 4, v4
	s_and_saveexec_b64 s[60:61], vcc
	s_cbranch_execz .LBB0_227
	v_mov_b64_e32 v[4:5], s[44:45]
	s_sleep 1
	global_load_dword v4, v[4:5], off sc1
	s_waitcnt vmcnt(0) lgkmcnt(0)
	v_cmp_gt_u32_e32 vcc, 4, v4
	s_and_saveexec_b64 s[96:97], vcc
	s_cbranch_execz .LBB0_226
	v_mov_b64_e32 v[4:5], s[44:45]
	s_sleep 1
	global_load_dword v4, v[4:5], off sc1
	s_mov_b64 s[14:15], -1
	s_waitcnt vmcnt(0) lgkmcnt(0)
	v_cmp_gt_u32_e32 vcc, 4, v4
	s_and_saveexec_b64 s[4:5], vcc
	s_cbranch_execz .LBB0_225
	v_mov_b64_e32 v[4:5], s[44:45]
	s_sleep 1
	global_load_dword v4, v[4:5], off sc1
	s_waitcnt vmcnt(0) lgkmcnt(0)
	v_cmp_gt_u32_e32 vcc, 4, v4
	s_and_saveexec_b64 s[42:43], vcc
	s_cbranch_execz .LBB0_224
	s_add_i32 s75, s75, -5
	s_cmp_eq_u32 s75, 0
	s_cselect_b64 s[14:15], -1, 0
	s_orn2_b64 s[14:15], s[14:15], exec
	s_sleep 1
	s_branch .LBB0_224

;     __device__ __forceinline__ void operator()(f32x4 (&acc)[2][2][4][2], const Unit& u, int wr, int wc, int fr, int fq) const {
;     ...
;         asm volatile("" ::: "memory"); __builtin_amdgcn_s_barrier(); asm volatile("" ::: "memory");
;         if (t < 256) { const float* pp = ssn + (size_t)(u.pm * BM + t) * 4;
;             const float p0 = __hip_atomic_load(pp, __ATOMIC_RELAXED, __HIP_MEMORY_SCOPE_AGENT), p1 = __hip_atomic_load(pp + 1, __ATOMIC_RELAXED, __HIP_MEMORY_SCOPE_AGENT),
;                         p2 = __hip_atomic_load(pp + 2, __ATOMIC_RELAXED, __HIP_MEMORY_SCOPE_AGENT), p3 = __hip_atomic_load(pp + 3, __ATOMIC_RELAXED, __HIP_MEMORY_SCOPE_AGENT);
;             rstab[t] = __builtin_amdgcn_rsqf(((p0 + p1) + (p2 + p3)) * (1.0f / D) + EPS); }
;         asm volatile("s_waitcnt lgkmcnt(0)" ::: "memory"); __builtin_amdgcn_s_barrier(); asm volatile("" ::: "memory");
;         f32x4 gg[2][2];
; #pragma unroll
;         for (int bj = 0; bj < 2; ++bj) { gg[bj][0] = *(const f32x4*)(gfin + col0 + bj * HALF); gg[bj][1] = *(const f32x4*)(gfin + col0 + bj * HALF + 4); }
; #pragma unroll
;         for (int ai = 0; ai < 2; ++ai)
; #pragma unroll
;             for (int m = 0; m < 4; ++m) { const int rl = ai * HALF + wr * 64 + m * 16 + fr; const float rs = rstab[rl]; float* orow = out + (size_t)(u.pm * BM + rl) * D + col0;
; #pragma unroll
;                 for (int bj = 0; bj < 2; ++bj) { *(f32x4*)(orow + bj * HALF) = acc[ai][bj][m][0] * gg[bj][0] * rs; *(f32x4*)(orow + bj * HALF + 4) = acc[ai][bj][m][1] * gg[bj][1] * rs; } }
.LBB0_236:
	s_or_b64 exec, exec, s[48:49]
	s_barrier
	s_mov_b64 s[4:5], exec
	v_readlane_b32 s14, v254, 2
	v_readlane_b32 s15, v254, 3
	s_and_b64 s[14:15], s[4:5], s[14:15]
	s_mov_b64 exec, s[14:15]
	s_cbranch_execz .LBB0_238
	v_readlane_b32 s14, v254, 62
	v_readlane_b32 s15, v254, 63
	s_nop 1
	v_lshl_add_u64 v[2:3], v[2:3], 4, s[14:15]
	global_load_dword v4, v[2:3], off sc1
	global_load_dword v6, v[2:3], off offset:4 sc1
	global_load_dword v5, v[2:3], off offset:8 sc1
	global_load_dword v7, v[2:3], off offset:12 sc1
	v_readlane_b32 s14, v254, 41
	s_waitcnt vmcnt(0) lgkmcnt(0)
	v_pk_add_f32 v[2:3], v[4:5], v[6:7]
	s_nop 0
	v_add_f32_e32 v2, v2, v3
	v_fmamk_f32 v2, v2, 0x3a800000, v224
	v_rsq_f32_e32 v2, v2
	v_lshl_add_u32 v3, v220, 2, s14
	ds_write_b32 v3, v2
.LBB0_238:
	s_or_b64 exec, exec, s[4:5]
	v_readlane_b32 s4, v255, 0
	v_lshlrev_b64 v[146:147], 2, v[204:205]
	v_readlane_b32 s5, v255, 1
	s_waitcnt lgkmcnt(0)
	s_barrier
	v_lshlrev_b64 v[148:149], 12, v[202:203]
	v_lshl_add_u64 v[2:3], s[4:5], 0, v[146:147]
	global_load_dwordx4 v[14:17], v[2:3], off
	global_load_dwordx4 v[10:13], v[2:3], off offset:16
	global_load_dwordx4 v[6:9], v[2:3], off offset:512
	s_nop 0
	global_load_dwordx4 v[2:5], v[2:3], off offset:528
	ds_read_b32 v156, v217
	v_lshl_add_u64 v[148:149], s[34:35], 0, v[148:149]
	v_lshl_add_u64 v[148:149], v[148:149], 0, v[146:147]
	v_add_u32_e32 v150, s51, v210
	v_ashrrev_i32_e32 v151, 31, v150
	v_lshlrev_b64 v[150:151], 12, v[150:151]
	v_lshl_add_u64 v[150:151], s[34:35], 0, v[150:151]
	v_lshl_add_u64 v[150:151], v[150:151], 0, v[146:147]
	v_add_u32_e32 v152, s51, v211
	v_ashrrev_i32_e32 v153, 31, v152
	v_lshlrev_b64 v[152:153], 12, v[152:153]
	v_lshl_add_u64 v[152:153], s[34:35], 0, v[152:153]
	v_lshl_add_u64 v[152:153], v[152:153], 0, v[146:147]
	v_add_u32_e32 v154, s51, v212
	v_ashrrev_i32_e32 v155, 31, v154
	v_lshlrev_b64 v[154:155], 12, v[154:155]
	v_lshl_add_u64 v[154:155], s[34:35], 0, v[154:155]
	v_lshl_add_u64 v[154:155], v[154:155], 0, v[146:147]
	s_and_b64 vcc, exec, s[8:9]
	s_mov_b64 s[4:5], -1
	s_waitcnt vmcnt(0) lgkmcnt(0)
	v_pk_mul_f32 v[128:129], v[128:129], v[16:17]
	v_pk_mul_f32 v[126:127], v[126:127], v[14:15]
	v_pk_mul_f32 v[124:125], v[124:125], v[12:13]
	v_pk_mul_f32 v[122:123], v[122:123], v[10:11]
	v_pk_mul_f32 v[120:121], v[120:121], v[8:9]
	v_pk_mul_f32 v[118:119], v[118:119], v[6:7]
	v_pk_mul_f32 v[116:117], v[116:117], v[4:5]
	v_pk_mul_f32 v[114:115], v[114:115], v[2:3]
	v_pk_mul_f32 v[170:171], v[96:97], v[16:17]
	v_pk_mul_f32 v[172:173], v[94:95], v[14:15]
	v_pk_mul_f32 v[94:95], v[126:127], v[156:157] op_sel_hi:[1,0]
	v_pk_mul_f32 v[96:97], v[128:129], v[156:157] op_sel_hi:[1,0]
	v_pk_mul_f32 v[158:159], v[108:109], v[12:13]
	v_pk_mul_f32 v[160:161], v[106:107], v[10:11]
	v_pk_mul_f32 v[162:163], v[104:105], v[8:9]
	v_pk_mul_f32 v[164:165], v[102:103], v[6:7]
	v_pk_mul_f32 v[166:167], v[100:101], v[4:5]
	v_pk_mul_f32 v[168:169], v[98:99], v[2:3]
	v_pk_mul_f32 v[98:99], v[122:123], v[156:157] op_sel_hi:[1,0]
	v_pk_mul_f32 v[100:101], v[124:125], v[156:157] op_sel_hi:[1,0]
	v_pk_mul_f32 v[102:103], v[118:119], v[156:157] op_sel_hi:[1,0]
	v_pk_mul_f32 v[104:105], v[120:121], v[156:157] op_sel_hi:[1,0]
	v_pk_mul_f32 v[106:107], v[114:115], v[156:157] op_sel_hi:[1,0]
	v_pk_mul_f32 v[108:109], v[116:117], v[156:157] op_sel_hi:[1,0]
	global_store_dwordx4 v[148:149], v[94:97], off
	global_store_dwordx4 v[148:149], v[98:101], off offset:16
	global_store_dwordx4 v[148:149], v[102:105], off offset:512
	global_store_dwordx4 v[148:149], v[106:109], off offset:528
	ds_read_b32 v98, v218
	v_pk_mul_f32 v[112:113], v[112:113], v[16:17]
	v_pk_mul_f32 v[110:111], v[110:111], v[14:15]
	v_pk_mul_f32 v[106:107], v[88:89], v[8:9]
	v_pk_mul_f32 v[108:109], v[86:87], v[6:7]
	s_waitcnt lgkmcnt(0)
	v_pk_mul_f32 v[88:89], v[112:113], v[98:99] op_sel_hi:[1,0]
	v_pk_mul_f32 v[86:87], v[110:111], v[98:99] op_sel_hi:[1,0]
	v_pk_mul_f32 v[102:103], v[92:93], v[12:13]
	v_pk_mul_f32 v[104:105], v[90:91], v[10:11]
	v_pk_mul_f32 v[92:93], v[158:159], v[98:99] op_sel_hi:[1,0]
	v_pk_mul_f32 v[90:91], v[160:161], v[98:99] op_sel_hi:[1,0]
	v_pk_mul_f32 v[96:97], v[162:163], v[98:99] op_sel_hi:[1,0]
	v_pk_mul_f32 v[94:95], v[164:165], v[98:99] op_sel_hi:[1,0]
	v_pk_mul_f32 v[100:101], v[166:167], v[98:99] op_sel_hi:[1,0]
	v_pk_mul_f32 v[98:99], v[168:169], v[98:99] op_sel_hi:[1,0]
	global_store_dwordx4 v[150:151], v[86:89], off
	global_store_dwordx4 v[150:151], v[90:93], off offset:16
	global_store_dwordx4 v[150:151], v[94:97], off offset:512
	global_store_dwordx4 v[150:151], v[98:101], off offset:528
	ds_read_b32 v90, v219
	v_pk_mul_f32 v[92:93], v[84:85], v[4:5]
	v_pk_mul_f32 v[94:95], v[82:83], v[2:3]
	v_pk_mul_f32 v[96:97], v[80:81], v[16:17]
	v_pk_mul_f32 v[98:99], v[78:79], v[14:15]
	s_waitcnt lgkmcnt(0)
	v_pk_mul_f32 v[80:81], v[170:171], v[90:91] op_sel_hi:[1,0]
	v_pk_mul_f32 v[78:79], v[172:173], v[90:91] op_sel_hi:[1,0]
	v_pk_mul_f32 v[84:85], v[102:103], v[90:91] op_sel_hi:[1,0]
	v_pk_mul_f32 v[82:83], v[104:105], v[90:91] op_sel_hi:[1,0]
	v_pk_mul_f32 v[88:89], v[106:107], v[90:91] op_sel_hi:[1,0]
	v_pk_mul_f32 v[86:87], v[108:109], v[90:91] op_sel_hi:[1,0]
	v_pk_mul_f32 v[92:93], v[92:93], v[90:91] op_sel_hi:[1,0]
	v_pk_mul_f32 v[90:91], v[94:95], v[90:91] op_sel_hi:[1,0]
	global_store_dwordx4 v[152:153], v[78:81], off
	global_store_dwordx4 v[152:153], v[82:85], off offset:16
	global_store_dwordx4 v[152:153], v[86:89], off offset:512
	global_store_dwordx4 v[152:153], v[90:93], off offset:528
	ds_read_b32 v82, v240
	v_pk_mul_f32 v[68:69], v[68:69], v[4:5]
	v_pk_mul_f32 v[66:67], v[66:67], v[2:3]
	v_pk_mul_f32 v[76:77], v[76:77], v[12:13]
	v_pk_mul_f32 v[74:75], v[74:75], v[10:11]
	v_pk_mul_f32 v[78:79], v[72:73], v[8:9]
	v_pk_mul_f32 v[84:85], v[70:71], v[6:7]
	s_waitcnt lgkmcnt(0)
;     __device__ __forceinline__ void operator()(f32x4 (&acc)[2][2][4][2], const Unit& u, int wr, int wc, int fr, int fq) const {
;     ...
; #pragma unroll
;         for (int ai = 0; ai < 2; ++ai)
; #pragma unroll
;             for (int m = 0; m < 4; ++m) { const int rl = ai * HALF + wr * 64 + m * 16 + fr; const float rs = rstab[rl]; float* orow = out + (size_t)(u.pm * BM + rl) * D + col0;
; #pragma unroll
;                 for (int bj = 0; bj < 2; ++bj) { *(f32x4*)(orow + bj * HALF) = acc[ai][bj][m][0] * gg[bj][0] * rs; *(f32x4*)(orow + bj * HALF + 4) = acc[ai][bj][m][1] * gg[bj][1] * rs; } }
	v_pk_mul_f32 v[72:73], v[96:97], v[82:83] op_sel_hi:[1,0]
	v_pk_mul_f32 v[70:71], v[98:99], v[82:83] op_sel_hi:[1,0]
	v_pk_mul_f32 v[68:69], v[68:69], v[82:83] op_sel_hi:[1,0]
	v_pk_mul_f32 v[66:67], v[66:67], v[82:83] op_sel_hi:[1,0]
	v_pk_mul_f32 v[76:77], v[76:77], v[82:83] op_sel_hi:[1,0]
	v_pk_mul_f32 v[74:75], v[74:75], v[82:83] op_sel_hi:[1,0]
	v_pk_mul_f32 v[80:81], v[78:79], v[82:83] op_sel_hi:[1,0]
	v_pk_mul_f32 v[78:79], v[84:85], v[82:83] op_sel_hi:[1,0]
	global_store_dwordx4 v[154:155], v[70:73], off
	global_store_dwordx4 v[154:155], v[74:77], off offset:16
	global_store_dwordx4 v[154:155], v[78:81], off offset:512
	global_store_dwordx4 v[154:155], v[66:69], off offset:528
	ds_read_b32 v66, v241
	v_pk_mul_f32 v[64:65], v[64:65], v[16:17]
	v_add_u32_e32 v68, s51, v213
	v_ashrrev_i32_e32 v69, 31, v68
	v_lshlrev_b64 v[68:69], 12, v[68:69]
	v_lshl_add_u64 v[68:69], s[34:35], 0, v[68:69]
	v_pk_mul_f32 v[62:63], v[62:63], v[14:15]
	v_pk_mul_f32 v[60:61], v[60:61], v[12:13]
	v_pk_mul_f32 v[58:59], v[58:59], v[10:11]
	v_pk_mul_f32 v[56:57], v[56:57], v[8:9]
	v_pk_mul_f32 v[54:55], v[54:55], v[6:7]
	v_pk_mul_f32 v[52:53], v[52:53], v[4:5]
	v_pk_mul_f32 v[50:51], v[50:51], v[2:3]
	v_lshl_add_u64 v[68:69], v[68:69], 0, v[146:147]
	s_waitcnt lgkmcnt(0)
	v_pk_mul_f32 v[64:65], v[64:65], v[66:67] op_sel_hi:[1,0]
	v_pk_mul_f32 v[62:63], v[62:63], v[66:67] op_sel_hi:[1,0]
	v_pk_mul_f32 v[60:61], v[60:61], v[66:67] op_sel_hi:[1,0]
	v_pk_mul_f32 v[58:59], v[58:59], v[66:67] op_sel_hi:[1,0]
	v_pk_mul_f32 v[56:57], v[56:57], v[66:67] op_sel_hi:[1,0]
	v_pk_mul_f32 v[54:55], v[54:55], v[66:67] op_sel_hi:[1,0]
	v_pk_mul_f32 v[52:53], v[52:53], v[66:67] op_sel_hi:[1,0]
	v_pk_mul_f32 v[50:51], v[50:51], v[66:67] op_sel_hi:[1,0]
	global_store_dwordx4 v[68:69], v[62:65], off
	global_store_dwordx4 v[68:69], v[58:61], off offset:16
	global_store_dwordx4 v[68:69], v[54:57], off offset:512
	global_store_dwordx4 v[68:69], v[50:53], off offset:528
	ds_read_b32 v50, v242
	v_pk_mul_f32 v[48:49], v[48:49], v[16:17]
	v_add_u32_e32 v52, s51, v214
	v_ashrrev_i32_e32 v53, 31, v52
	v_lshlrev_b64 v[52:53], 12, v[52:53]
	v_lshl_add_u64 v[52:53], s[34:35], 0, v[52:53]
	v_pk_mul_f32 v[46:47], v[46:47], v[14:15]
	v_pk_mul_f32 v[44:45], v[44:45], v[12:13]
	v_pk_mul_f32 v[42:43], v[42:43], v[10:11]
	v_pk_mul_f32 v[40:41], v[40:41], v[8:9]
	v_pk_mul_f32 v[38:39], v[38:39], v[6:7]
	v_pk_mul_f32 v[36:37], v[36:37], v[4:5]
	v_pk_mul_f32 v[34:35], v[34:35], v[2:3]
	v_lshl_add_u64 v[52:53], v[52:53], 0, v[146:147]
	s_waitcnt lgkmcnt(0)
	v_pk_mul_f32 v[48:49], v[48:49], v[50:51] op_sel_hi:[1,0]
	v_pk_mul_f32 v[46:47], v[46:47], v[50:51] op_sel_hi:[1,0]
	v_pk_mul_f32 v[44:45], v[44:45], v[50:51] op_sel_hi:[1,0]
	v_pk_mul_f32 v[42:43], v[42:43], v[50:51] op_sel_hi:[1,0]
	v_pk_mul_f32 v[40:41], v[40:41], v[50:51] op_sel_hi:[1,0]
	v_pk_mul_f32 v[38:39], v[38:39], v[50:51] op_sel_hi:[1,0]
	v_pk_mul_f32 v[36:37], v[36:37], v[50:51] op_sel_hi:[1,0]
	v_pk_mul_f32 v[34:35], v[34:35], v[50:51] op_sel_hi:[1,0]
	global_store_dwordx4 v[52:53], v[46:49], off
	global_store_dwordx4 v[52:53], v[42:45], off offset:16
	global_store_dwordx4 v[52:53], v[38:41], off offset:512
	global_store_dwordx4 v[52:53], v[34:37], off offset:528
	ds_read_b32 v34, v243
	v_pk_mul_f32 v[32:33], v[32:33], v[16:17]
	v_add_u32_e32 v36, s51, v215
	v_ashrrev_i32_e32 v37, 31, v36
	v_lshlrev_b64 v[36:37], 12, v[36:37]
	v_lshl_add_u64 v[36:37], s[34:35], 0, v[36:37]
	v_pk_mul_f32 v[30:31], v[30:31], v[14:15]
	v_pk_mul_f32 v[28:29], v[28:29], v[12:13]
	v_pk_mul_f32 v[26:27], v[26:27], v[10:11]
	v_pk_mul_f32 v[24:25], v[24:25], v[8:9]
	v_pk_mul_f32 v[22:23], v[22:23], v[6:7]
	v_pk_mul_f32 v[20:21], v[20:21], v[4:5]
	v_pk_mul_f32 v[18:19], v[18:19], v[2:3]
	v_lshl_add_u64 v[36:37], v[36:37], 0, v[146:147]
	s_waitcnt lgkmcnt(0)
	v_pk_mul_f32 v[32:33], v[32:33], v[34:35] op_sel_hi:[1,0]
	v_pk_mul_f32 v[30:31], v[30:31], v[34:35] op_sel_hi:[1,0]
	v_pk_mul_f32 v[28:29], v[28:29], v[34:35] op_sel_hi:[1,0]
	v_pk_mul_f32 v[26:27], v[26:27], v[34:35] op_sel_hi:[1,0]
	v_pk_mul_f32 v[24:25], v[24:25], v[34:35] op_sel_hi:[1,0]
	v_pk_mul_f32 v[22:23], v[22:23], v[34:35] op_sel_hi:[1,0]
	v_pk_mul_f32 v[20:21], v[20:21], v[34:35] op_sel_hi:[1,0]
	v_pk_mul_f32 v[18:19], v[18:19], v[34:35] op_sel_hi:[1,0]
	global_store_dwordx4 v[36:37], v[30:33], off
	global_store_dwordx4 v[36:37], v[26:29], off offset:16
	global_store_dwordx4 v[36:37], v[22:25], off offset:512
	global_store_dwordx4 v[36:37], v[18:21], off offset:528
	ds_read_b32 v18, v244
	v_pk_mul_f32 v[16:17], v[132:133], v[16:17]
	v_add_u32_e32 v20, s51, v216
	v_ashrrev_i32_e32 v21, 31, v20
	v_lshlrev_b64 v[20:21], 12, v[20:21]
	v_lshl_add_u64 v[20:21], s[34:35], 0, v[20:21]
	v_pk_mul_f32 v[14:15], v[136:137], v[14:15]
	v_pk_mul_f32 v[12:13], v[130:131], v[12:13]
	v_pk_mul_f32 v[10:11], v[134:135], v[10:11]
	v_pk_mul_f32 v[8:9], v[138:139], v[8:9]
	v_pk_mul_f32 v[6:7], v[142:143], v[6:7]
	v_pk_mul_f32 v[4:5], v[140:141], v[4:5]
	v_pk_mul_f32 v[2:3], v[144:145], v[2:3]
	v_lshl_add_u64 v[20:21], v[20:21], 0, v[146:147]
	s_waitcnt lgkmcnt(0)
	v_pk_mul_f32 v[16:17], v[16:17], v[18:19] op_sel_hi:[1,0]
	v_pk_mul_f32 v[14:15], v[14:15], v[18:19] op_sel_hi:[1,0]
	v_pk_mul_f32 v[12:13], v[12:13], v[18:19] op_sel_hi:[1,0]
	v_pk_mul_f32 v[10:11], v[10:11], v[18:19] op_sel_hi:[1,0]
	v_pk_mul_f32 v[8:9], v[8:9], v[18:19] op_sel_hi:[1,0]
	v_pk_mul_f32 v[6:7], v[6:7], v[18:19] op_sel_hi:[1,0]
	v_pk_mul_f32 v[4:5], v[4:5], v[18:19] op_sel_hi:[1,0]
	v_pk_mul_f32 v[2:3], v[2:3], v[18:19] op_sel_hi:[1,0]
	global_store_dwordx4 v[20:21], v[14:17], off
	global_store_dwordx4 v[20:21], v[10:13], off offset:16
	global_store_dwordx4 v[20:21], v[6:9], off offset:512
	global_store_dwordx4 v[20:21], v[2:5], off offset:528
	s_cbranch_vccnz .LBB0_189
	v_readlane_b32 s4, v255, 2
	v_readlane_b32 s5, v255, 3
	s_andn2_b64 vcc, exec, s[4:5]
	s_cbranch_vccnz .LBB0_188
	s_barrier
	s_branch .LBB0_188

; __device__ __forceinline__ float rstd_of(const float* ss, int row) { const f32x4 p = *(const f32x4*)(ss + 4 * (size_t)row); return __builtin_amdgcn_rsqf(((p.x + p.y) + (p.z + p.w)) * (1.0f / D) + EPS); }
; __device__ __forceinline__ float silu_f(float g) { return g * __builtin_amdgcn_rcpf(1.0f + __builtin_amdgcn_exp2f(g * -1.4426950408889634f)); }
; __device__ __forceinline__ void rstd8(const float* ss, int row0, float (&rs)[2][4]) {
;     f32x4 p[2][4];
; #pragma unroll
;     for (int ai = 0; ai < 2; ++ai)
; #pragma unroll
;         for (int m = 0; m < 4; ++m) p[ai][m] = *(const f32x4*)(ss + 4 * (size_t)(row0 + ai * HALF + m * 16));
; #pragma unroll
;     for (int ai = 0; ai < 2; ++ai)
; #pragma unroll
;         for (int m = 0; m < 4; ++m) rs[ai][m] = __builtin_amdgcn_rsqf(((p[ai][m].x + p[ai][m].y) + (p[ai][m].z + p[ai][m].w)) * (1.0f / D) + EPS);
;     __device__ __forceinline__ void operator()(const f32x4 (&acc)[2][2][4][2], const Unit& u, int wr, int wc, int fr, int fq) const {
;         const int row0 = u.pm * BM + wr * 64 + fr, col0 = u.pn * BM + wc * 32 + 8 * fq;
;         f32x4 cv[2][2];
; #pragma unroll
;         for (int bj = 0; bj < 2; ++bj)
; #pragma unroll
;             for (int n = 0; n < 2; ++n) cv[bj][n] = cscale ? *(const f32x4*)(cscale + col0 + bj * HALF + 4 * n) : (f32x4){1.f, 1.f, 1.f, 1.f};
;         float rsv[2][4];
;         if (ss) rstd8(ss, row0, rsv); else {
; #pragma unroll
;             for (int i = 0; i < 8; ++i) rsv[i >> 2][i & 3] = 1.0f; }
.LBB0_274:
	v_lshl_or_b32 v160, s51, 8, v178
	v_ashrrev_i32_e32 v161, 31, v160
	v_lshl_add_u64 v[146:147], v[160:161], 2, s[8:9]
	v_mov_b32_e32 v130, 1.0
	s_and_b64 vcc, exec, s[90:91]
	v_mov_b32_e32 v134, 1.0
	v_mov_b32_e32 v135, 1.0
	v_mov_b32_e32 v136, 1.0
	v_mov_b32_e32 v137, 1.0
	s_cbranch_vccz .LBB0_276
	global_load_dwordx4 v[134:137], v[146:147], off
.LBB0_276:
	v_cndmask_b32_e64 v0, 0, 1, s[90:91]
	v_cmp_ne_u32_e64 s[0:1], 1, v0
	s_andn2_b64 vcc, exec, s[90:91]
	v_mov_b32_e32 v131, 1.0
	v_mov_b32_e32 v132, 1.0
	v_mov_b32_e32 v133, 1.0
	s_cbranch_vccnz .LBB0_278
	global_load_dwordx4 v[130:133], v[146:147], off offset:16
.LBB0_278:
	v_mov_b32_e32 v138, 1.0
	s_and_b64 vcc, exec, s[0:1]
	v_mov_b32_e32 v142, 1.0
	v_mov_b32_e32 v143, 1.0
	v_mov_b32_e32 v144, 1.0
	v_mov_b32_e32 v145, 1.0
	s_cbranch_vccnz .LBB0_280
	global_load_dwordx4 v[142:145], v[146:147], off offset:512
.LBB0_280:
	s_and_b64 vcc, exec, s[0:1]
	v_mov_b32_e32 v139, 1.0
	v_mov_b32_e32 v140, 1.0
	v_mov_b32_e32 v141, 1.0
	s_cbranch_vccnz .LBB0_282
	global_load_dwordx4 v[138:141], v[146:147], off offset:528
.LBB0_282:
	s_lshl_b32 s4, s94, 8
	v_readlane_b32 s0, v254, 46
	s_add_i32 s4, s4, s0
	v_or_b32_e32 v168, s4, v177
	v_ashrrev_i32_e32 v169, 31, v168
	s_andn2_b64 vcc, exec, s[92:93]
	v_or_b32_e32 v162, 16, v168
	v_or_b32_e32 v158, 32, v168
	v_or_b32_e32 v156, 48, v168
	v_add_u32_e32 v172, 0x80, v168
	s_cbranch_vccnz .LBB0_288
	v_lshl_add_u64 v[146:147], v[168:169], 4, s[34:35]
	global_load_dwordx4 v[182:185], v[146:147], off
	v_ashrrev_i32_e32 v163, 31, v162
	v_lshl_add_u64 v[148:149], v[162:163], 4, s[34:35]
	global_load_dwordx4 v[186:189], v[148:149], off
	v_ashrrev_i32_e32 v159, 31, v158
	v_lshl_add_u64 v[148:149], v[158:159], 4, s[34:35]
	global_load_dwordx4 v[190:193], v[148:149], off
	v_ashrrev_i32_e32 v157, 31, v156
	v_lshl_add_u64 v[148:149], v[156:157], 4, s[34:35]
	global_load_dwordx4 v[202:205], v[148:149], off
	v_add_u32_e32 v154, 0x80, v168
	v_ashrrev_i32_e32 v155, 31, v154
	v_lshl_add_u64 v[148:149], v[154:155], 4, s[34:35]
	global_load_dwordx4 v[206:209], v[148:149], off
	global_load_dwordx4 v[210:213], v[146:147], off offset:2304
	global_load_dwordx4 v[150:153], v[146:147], off offset:2560
	s_nop 0
	global_load_dwordx4 v[146:149], v[146:147], off offset:2816
	s_waitcnt vmcnt(0) lgkmcnt(0)
	v_mov_b32_e32 v214, v183
	v_mov_b32_e32 v215, v184
	v_mov_b32_e32 v183, v185
	v_pk_add_f32 v[182:183], v[214:215], v[182:183]
	s_nop 0
	v_add_f32_e32 v0, v182, v183
	v_mov_b32_e32 v182, v187
	v_mov_b32_e32 v183, v188
	v_mov_b32_e32 v187, v189
	v_fmamk_f32 v0, v0, 0x3a800000, v224
	v_pk_add_f32 v[182:183], v[182:183], v[186:187]
	v_rsq_f32_e32 v176, v0
	v_add_f32_e32 v0, v182, v183
	v_mov_b32_e32 v182, v191
	v_mov_b32_e32 v183, v192
	v_mov_b32_e32 v191, v193
	v_fmamk_f32 v0, v0, 0x3a800000, v224
	v_pk_add_f32 v[182:183], v[182:183], v[190:191]
	v_rsq_f32_e32 v174, v0
	v_add_f32_e32 v0, v182, v183
	v_mov_b32_e32 v182, v203
	v_mov_b32_e32 v183, v204
	v_mov_b32_e32 v203, v205
	v_fmamk_f32 v0, v0, 0x3a800000, v224
	v_pk_add_f32 v[182:183], v[182:183], v[202:203]
	v_rsq_f32_e32 v170, v0
	v_add_f32_e32 v0, v182, v183
	v_mov_b32_e32 v182, v207
	v_mov_b32_e32 v183, v208
	v_mov_b32_e32 v207, v209
	v_fmamk_f32 v0, v0, 0x3a800000, v224
	v_pk_add_f32 v[182:183], v[182:183], v[206:207]
	v_rsq_f32_e32 v164, v0
	v_add_f32_e32 v0, v182, v183
	v_mov_b32_e32 v182, v211
	v_mov_b32_e32 v183, v212
	v_mov_b32_e32 v211, v213
	v_pk_add_f32 v[182:183], v[182:183], v[210:211]
	v_fmamk_f32 v0, v0, 0x3a800000, v224
	v_add_f32_e32 v166, v182, v183
	v_mov_b32_e32 v182, v151
	v_mov_b32_e32 v183, v152
	v_mov_b32_e32 v151, v153
	v_mov_b32_e32 v152, v147
	v_mov_b32_e32 v153, v148
	v_mov_b32_e32 v147, v149
	v_pk_add_f32 v[150:151], v[182:183], v[150:151]
	v_pk_add_f32 v[146:147], v[152:153], v[146:147]
	v_add_f32_e32 v150, v150, v151
	v_add_f32_e32 v146, v146, v147
	v_fmamk_f32 v166, v166, 0x3a800000, v224
	v_fmamk_f32 v150, v150, 0x3a800000, v224
	v_fmamk_f32 v146, v146, 0x3a800000, v224
	v_rsq_f32_e32 v0, v0
	v_rsq_f32_e32 v166, v166
	v_rsq_f32_e32 v150, v150
	v_rsq_f32_e32 v146, v146
	v_mov_b64_e32 v[148:149], v[154:155]
	s_cbranch_execnz .LBB0_285

; __device__ __forceinline__ unsigned cvt_pk_bf16(float lo, float hi) { unsigned r; asm volatile("v_cvt_pk_bf16_f32 %0, %1, %2" : "=v"(r) : "v"(lo), "v"(hi)); return r; }
;     __device__ __forceinline__ void operator()(const f32x4 (&acc)[2][2][4][2], const Unit& u, int wr, int wc, int fr, int fq) const {
;     ...
;         for (int ai = 0; ai < 2; ++ai)
; #pragma unroll
;             for (int m = 0; m < 4; ++m) { const int row = row0 + ai * HALF + m * 16; const float rs = rsv[ai][m]; bf16_t* rowp = O + (size_t)row * ldc + col0 + (size_t)(row >> 12) * adj;
; #pragma unroll
;                 for (int bj = 0; bj < 2; ++bj) { const f32x4 v0 = acc[ai][bj][m][0] * cv[bj][0] * rs, v1 = acc[ai][bj][m][1] * cv[bj][1] * rs;
;                     u32x4 w; w.x = cvt_pk_bf16(v0[0], v0[1]); w.y = cvt_pk_bf16(v0[2], v0[3]); w.z = cvt_pk_bf16(v1[0], v1[1]); w.w = cvt_pk_bf16(v1[2], v1[3]);
;                     *(u32x4*)(rowp + bj * HALF) = w; } }
.LBB0_285:
	s_ashr_i32 s0, s4, 12
	v_lshlrev_b64 v[152:153], 11, v[168:169]
	s_ashr_i32 s1, s0, 31
	v_lshl_add_u64 v[168:169], s[28:29], 0, v[152:153]
	v_lshlrev_b64 v[152:153], 1, v[160:161]
	v_lshl_add_u64 v[160:161], v[168:169], 0, v[152:153]
	s_lshl_b64 s[0:1], s[0:1], 23
	s_waitcnt vmcnt(0) lgkmcnt(0)
	v_pk_mul_f32 v[128:129], v[128:129], v[136:137]
	v_pk_mul_f32 v[126:127], v[126:127], v[134:135]
	v_pk_mul_f32 v[124:125], v[124:125], v[132:133]
	v_pk_mul_f32 v[122:123], v[122:123], v[130:131]
	v_lshl_add_u64 v[160:161], v[160:161], 0, s[0:1]
	v_pk_mul_f32 v[128:129], v[128:129], v[176:177] op_sel_hi:[1,0]
	v_pk_mul_f32 v[126:127], v[126:127], v[176:177] op_sel_hi:[1,0]
	v_pk_mul_f32 v[168:169], v[124:125], v[176:177] op_sel_hi:[1,0]
	v_pk_mul_f32 v[124:125], v[122:123], v[176:177] op_sel_hi:[1,0]
	v_cvt_pk_bf16_f32 v122, v126, v127
	v_cvt_pk_bf16_f32 v123, v128, v129
	v_pk_mul_f32 v[120:121], v[120:121], v[144:145]
	v_pk_mul_f32 v[118:119], v[118:119], v[142:143]
	v_pk_mul_f32 v[112:113], v[112:113], v[140:141]
	v_pk_mul_f32 v[110:111], v[110:111], v[138:139]
	v_cvt_pk_bf16_f32 v124, v124, v125
	v_cvt_pk_bf16_f32 v125, v168, v169
	global_store_dwordx4 v[160:161], v[122:125], off
	v_pk_mul_f32 v[120:121], v[120:121], v[176:177] op_sel_hi:[1,0]
	v_pk_mul_f32 v[118:119], v[118:119], v[176:177] op_sel_hi:[1,0]
	v_pk_mul_f32 v[122:123], v[112:113], v[176:177] op_sel_hi:[1,0]
	v_pk_mul_f32 v[112:113], v[110:111], v[176:177] op_sel_hi:[1,0]
	v_cvt_pk_bf16_f32 v110, v118, v119
	v_cvt_pk_bf16_f32 v111, v120, v121
	v_pk_mul_f32 v[114:115], v[114:115], v[134:135]
	v_cvt_pk_bf16_f32 v112, v112, v113
	v_cvt_pk_bf16_f32 v113, v122, v123
	global_store_dwordx4 v[160:161], v[110:113], off offset:256
	v_pk_mul_f32 v[108:109], v[108:109], v[132:133]
	v_pk_mul_f32 v[106:107], v[106:107], v[130:131]
	v_lshlrev_b64 v[110:111], 11, v[162:163]
	v_lshl_add_u64 v[110:111], s[28:29], 0, v[110:111]
	v_lshl_add_u64 v[110:111], v[110:111], 0, v[152:153]
	v_pk_mul_f32 v[112:113], v[116:117], v[136:137]
	v_lshl_add_u64 v[110:111], v[110:111], 0, s[0:1]
	v_pk_mul_f32 v[112:113], v[112:113], v[174:175] op_sel_hi:[1,0]
	v_pk_mul_f32 v[114:115], v[114:115], v[174:175] op_sel_hi:[1,0]
	v_pk_mul_f32 v[116:117], v[108:109], v[174:175] op_sel_hi:[1,0]
	v_pk_mul_f32 v[108:109], v[106:107], v[174:175] op_sel_hi:[1,0]
	v_cvt_pk_bf16_f32 v106, v114, v115
	v_cvt_pk_bf16_f32 v107, v112, v113
	v_pk_mul_f32 v[104:105], v[104:105], v[144:145]
	v_pk_mul_f32 v[102:103], v[102:103], v[142:143]
	v_pk_mul_f32 v[96:97], v[96:97], v[140:141]
	v_pk_mul_f32 v[94:95], v[94:95], v[138:139]
	v_cvt_pk_bf16_f32 v108, v108, v109
	v_cvt_pk_bf16_f32 v109, v116, v117
	global_store_dwordx4 v[110:111], v[106:109], off
	v_pk_mul_f32 v[104:105], v[104:105], v[174:175] op_sel_hi:[1,0]
	v_pk_mul_f32 v[102:103], v[102:103], v[174:175] op_sel_hi:[1,0]
	v_pk_mul_f32 v[106:107], v[96:97], v[174:175] op_sel_hi:[1,0]
	v_pk_mul_f32 v[96:97], v[94:95], v[174:175] op_sel_hi:[1,0]
	v_cvt_pk_bf16_f32 v94, v102, v103
	v_cvt_pk_bf16_f32 v95, v104, v105
	v_pk_mul_f32 v[98:99], v[98:99], v[134:135]
	v_cvt_pk_bf16_f32 v96, v96, v97
	v_cvt_pk_bf16_f32 v97, v106, v107
	global_store_dwordx4 v[110:111], v[94:97], off offset:256
	v_pk_mul_f32 v[92:93], v[92:93], v[132:133]
	v_pk_mul_f32 v[90:91], v[90:91], v[130:131]
	v_lshlrev_b64 v[94:95], 11, v[158:159]
	v_lshl_add_u64 v[94:95], s[28:29], 0, v[94:95]
	v_lshl_add_u64 v[94:95], v[94:95], 0, v[152:153]
	v_pk_mul_f32 v[96:97], v[100:101], v[136:137]
	v_lshl_add_u64 v[94:95], v[94:95], 0, s[0:1]
	v_pk_mul_f32 v[96:97], v[96:97], v[170:171] op_sel_hi:[1,0]
	v_pk_mul_f32 v[98:99], v[98:99], v[170:171] op_sel_hi:[1,0]
	v_pk_mul_f32 v[100:101], v[92:93], v[170:171] op_sel_hi:[1,0]
	v_pk_mul_f32 v[92:93], v[90:91], v[170:171] op_sel_hi:[1,0]
	v_cvt_pk_bf16_f32 v90, v98, v99
	v_cvt_pk_bf16_f32 v91, v96, v97
	v_pk_mul_f32 v[88:89], v[88:89], v[144:145]
	v_pk_mul_f32 v[86:87], v[86:87], v[142:143]
	v_pk_mul_f32 v[80:81], v[80:81], v[140:141]
	v_pk_mul_f32 v[78:79], v[78:79], v[138:139]
	v_cvt_pk_bf16_f32 v92, v92, v93
	v_cvt_pk_bf16_f32 v93, v100, v101
	global_store_dwordx4 v[94:95], v[90:93], off
	v_pk_mul_f32 v[88:89], v[88:89], v[170:171] op_sel_hi:[1,0]
	v_pk_mul_f32 v[86:87], v[86:87], v[170:171] op_sel_hi:[1,0]
	v_pk_mul_f32 v[90:91], v[80:81], v[170:171] op_sel_hi:[1,0]
	v_pk_mul_f32 v[80:81], v[78:79], v[170:171] op_sel_hi:[1,0]
	v_cvt_pk_bf16_f32 v78, v86, v87
	v_cvt_pk_bf16_f32 v79, v88, v89
	v_pk_mul_f32 v[82:83], v[82:83], v[134:135]
	v_cvt_pk_bf16_f32 v80, v80, v81
	v_cvt_pk_bf16_f32 v81, v90, v91
	global_store_dwordx4 v[94:95], v[78:81], off offset:256
	v_pk_mul_f32 v[76:77], v[76:77], v[132:133]
	v_pk_mul_f32 v[74:75], v[74:75], v[130:131]
	v_lshlrev_b64 v[78:79], 11, v[156:157]
	v_lshl_add_u64 v[78:79], s[28:29], 0, v[78:79]
	v_lshl_add_u64 v[78:79], v[78:79], 0, v[152:153]
	v_pk_mul_f32 v[80:81], v[84:85], v[136:137]
	v_lshl_add_u64 v[78:79], v[78:79], 0, s[0:1]
	v_pk_mul_f32 v[80:81], v[80:81], v[164:165] op_sel_hi:[1,0]
	v_pk_mul_f32 v[82:83], v[82:83], v[164:165] op_sel_hi:[1,0]
	v_pk_mul_f32 v[84:85], v[76:77], v[164:165] op_sel_hi:[1,0]
	v_pk_mul_f32 v[76:77], v[74:75], v[164:165] op_sel_hi:[1,0]
	v_cvt_pk_bf16_f32 v74, v82, v83
	v_cvt_pk_bf16_f32 v75, v80, v81
	v_pk_mul_f32 v[68:69], v[68:69], v[140:141]
	v_pk_mul_f32 v[66:67], v[66:67], v[138:139]
	v_cvt_pk_bf16_f32 v76, v76, v77
	v_cvt_pk_bf16_f32 v77, v84, v85
	global_store_dwordx4 v[78:79], v[74:77], off
	v_pk_mul_f32 v[72:73], v[72:73], v[144:145]
	v_pk_mul_f32 v[70:71], v[70:71], v[142:143]
	v_pk_mul_f32 v[74:75], v[68:69], v[164:165] op_sel_hi:[1,0]
	v_pk_mul_f32 v[68:69], v[66:67], v[164:165] op_sel_hi:[1,0]
; __device__ __forceinline__ unsigned cvt_pk_bf16(float lo, float hi) { unsigned r; asm volatile("v_cvt_pk_bf16_f32 %0, %1, %2" : "=v"(r) : "v"(lo), "v"(hi)); return r; }
;     __device__ __forceinline__ void operator()(const f32x4 (&acc)[2][2][4][2], const Unit& u, int wr, int wc, int fr, int fq) const {
;     ...
;         for (int ai = 0; ai < 2; ++ai)
; #pragma unroll
;             for (int m = 0; m < 4; ++m) { const int row = row0 + ai * HALF + m * 16; const float rs = rsv[ai][m]; bf16_t* rowp = O + (size_t)row * ldc + col0 + (size_t)(row >> 12) * adj;
; #pragma unroll
;                 for (int bj = 0; bj < 2; ++bj) { const f32x4 v0 = acc[ai][bj][m][0] * cv[bj][0] * rs, v1 = acc[ai][bj][m][1] * cv[bj][1] * rs;
;                     u32x4 w; w.x = cvt_pk_bf16(v0[0], v0[1]); w.y = cvt_pk_bf16(v0[2], v0[3]); w.z = cvt_pk_bf16(v1[0], v1[1]); w.w = cvt_pk_bf16(v1[2], v1[3]);
;                     *(u32x4*)(rowp + bj * HALF) = w; } }
	v_pk_mul_f32 v[72:73], v[72:73], v[164:165] op_sel_hi:[1,0]
	v_pk_mul_f32 v[70:71], v[70:71], v[164:165] op_sel_hi:[1,0]
	v_pk_mul_f32 v[64:65], v[64:65], v[136:137]
	v_cvt_pk_bf16_f32 v66, v70, v71
	v_cvt_pk_bf16_f32 v67, v72, v73
	v_cvt_pk_bf16_f32 v68, v68, v69
	v_cvt_pk_bf16_f32 v69, v74, v75
	global_store_dwordx4 v[78:79], v[66:69], off offset:256
	v_pk_mul_f32 v[62:63], v[62:63], v[134:135]
	v_pk_mul_f32 v[60:61], v[60:61], v[132:133]
	v_ashrrev_i32_e32 v66, 12, v154
	v_lshlrev_b64 v[68:69], 11, v[148:149]
	v_ashrrev_i32_e32 v67, 31, v66
	v_lshl_add_u64 v[68:69], s[28:29], 0, v[68:69]
	v_lshl_add_u64 v[68:69], v[68:69], 0, v[152:153]
	v_lshlrev_b64 v[66:67], 23, v[66:67]
	v_pk_mul_f32 v[58:59], v[58:59], v[130:131]
	v_lshl_add_u64 v[68:69], v[68:69], 0, v[66:67]
	v_pk_mul_f32 v[64:65], v[64:65], v[0:1] op_sel_hi:[1,0]
	v_pk_mul_f32 v[62:63], v[62:63], v[0:1] op_sel_hi:[1,0]
	v_pk_mul_f32 v[70:71], v[60:61], v[0:1] op_sel_hi:[1,0]
	v_pk_mul_f32 v[60:61], v[58:59], v[0:1] op_sel_hi:[1,0]
	v_cvt_pk_bf16_f32 v58, v62, v63
	v_cvt_pk_bf16_f32 v59, v64, v65
	v_pk_mul_f32 v[56:57], v[56:57], v[144:145]
	v_pk_mul_f32 v[54:55], v[54:55], v[142:143]
	v_pk_mul_f32 v[52:53], v[52:53], v[140:141]
	v_pk_mul_f32 v[50:51], v[50:51], v[138:139]
	v_cvt_pk_bf16_f32 v60, v60, v61
	v_cvt_pk_bf16_f32 v61, v70, v71
	global_store_dwordx4 v[68:69], v[58:61], off
	v_pk_mul_f32 v[56:57], v[56:57], v[0:1] op_sel_hi:[1,0]
	v_pk_mul_f32 v[54:55], v[54:55], v[0:1] op_sel_hi:[1,0]
	v_pk_mul_f32 v[58:59], v[52:53], v[0:1] op_sel_hi:[1,0]
	v_pk_mul_f32 v[52:53], v[50:51], v[0:1] op_sel_hi:[1,0]
	v_cvt_pk_bf16_f32 v50, v54, v55
	v_cvt_pk_bf16_f32 v51, v56, v57
	v_ashrrev_i32_e32 v155, 31, v154
	v_cvt_pk_bf16_f32 v52, v52, v53
	v_cvt_pk_bf16_f32 v53, v58, v59
	global_store_dwordx4 v[68:69], v[50:53], off offset:256
	v_pk_mul_f32 v[46:47], v[46:47], v[134:135]
	v_pk_mul_f32 v[44:45], v[44:45], v[132:133]
	v_lshlrev_b64 v[50:51], 11, v[154:155]
	v_lshl_add_u64 v[50:51], s[28:29], 0, v[50:51]
	v_lshl_add_u64 v[50:51], v[50:51], 0, v[152:153]
	v_lshl_add_u64 v[50:51], v[50:51], 0, v[66:67]
	v_pk_mul_f32 v[46:47], v[46:47], v[166:167] op_sel_hi:[1,0]
	v_pk_mul_f32 v[42:43], v[42:43], v[130:131]
	v_pk_mul_f32 v[48:49], v[48:49], v[136:137]
	v_pk_mul_f32 v[54:55], v[44:45], v[166:167] op_sel_hi:[1,0]
	v_pk_mul_f32 v[44:45], v[42:43], v[166:167] op_sel_hi:[1,0]
	v_cvt_pk_bf16_f32 v42, v46, v47
	v_add_co_u32_e32 v46, vcc, s77, v50
	v_pk_mul_f32 v[48:49], v[48:49], v[166:167] op_sel_hi:[1,0]
	s_nop 0
	v_addc_co_u32_e32 v47, vcc, 0, v51, vcc
	v_cvt_pk_bf16_f32 v43, v48, v49
	v_pk_mul_f32 v[32:33], v[32:33], v[140:141]
	v_pk_mul_f32 v[30:31], v[30:31], v[138:139]
	s_mov_b64 s[0:1], 0x8000
	v_cvt_pk_bf16_f32 v44, v44, v45
	v_cvt_pk_bf16_f32 v45, v54, v55
	global_store_dwordx4 v[46:47], v[42:45], off
	v_pk_mul_f32 v[40:41], v[40:41], v[144:145]
	v_pk_mul_f32 v[38:39], v[38:39], v[142:143]
	v_pk_mul_f32 v[42:43], v[32:33], v[166:167] op_sel_hi:[1,0]
	v_pk_mul_f32 v[32:33], v[30:31], v[166:167] op_sel_hi:[1,0]
	v_lshl_add_u64 v[52:53], v[50:51], 0, s[0:1]
	v_pk_mul_f32 v[40:41], v[40:41], v[166:167] op_sel_hi:[1,0]
	v_pk_mul_f32 v[38:39], v[38:39], v[166:167] op_sel_hi:[1,0]
	s_mov_b64 s[0:1], 0x10000
	v_cvt_pk_bf16_f32 v30, v38, v39
	v_cvt_pk_bf16_f32 v31, v40, v41
	v_cvt_pk_bf16_f32 v32, v32, v33
	v_cvt_pk_bf16_f32 v33, v42, v43
	global_store_dwordx4 v[52:53], v[30:33], off offset:256
	v_pk_mul_f32 v[34:35], v[34:35], v[134:135]
	v_pk_mul_f32 v[28:29], v[28:29], v[132:133]
	v_pk_mul_f32 v[32:33], v[36:37], v[136:137]
	v_lshl_add_u64 v[30:31], v[50:51], 0, s[0:1]
	v_pk_mul_f32 v[32:33], v[32:33], v[150:151] op_sel_hi:[1,0]
	v_pk_mul_f32 v[26:27], v[26:27], v[130:131]
	s_mov_b32 s0, 0x10000
	v_pk_mul_f32 v[34:35], v[34:35], v[150:151] op_sel_hi:[1,0]
	v_pk_mul_f32 v[36:37], v[28:29], v[150:151] op_sel_hi:[1,0]
	v_pk_mul_f32 v[28:29], v[26:27], v[150:151] op_sel_hi:[1,0]
	v_cvt_pk_bf16_f32 v26, v34, v35
	v_cvt_pk_bf16_f32 v27, v32, v33
	v_add_co_u32_e32 v32, vcc, s0, v50
	v_pk_mul_f32 v[16:17], v[16:17], v[140:141]
	s_nop 0
	v_addc_co_u32_e32 v33, vcc, 0, v51, vcc
	v_pk_mul_f32 v[14:15], v[14:15], v[138:139]
	v_cvt_pk_bf16_f32 v28, v28, v29
	v_cvt_pk_bf16_f32 v29, v36, v37
	global_store_dwordx4 v[32:33], v[26:29], off
	v_pk_mul_f32 v[24:25], v[24:25], v[144:145]
	v_pk_mul_f32 v[22:23], v[22:23], v[142:143]
	v_pk_mul_f32 v[26:27], v[16:17], v[150:151] op_sel_hi:[1,0]
	v_pk_mul_f32 v[16:17], v[14:15], v[150:151] op_sel_hi:[1,0]
	v_pk_mul_f32 v[24:25], v[24:25], v[150:151] op_sel_hi:[1,0]
	v_pk_mul_f32 v[22:23], v[22:23], v[150:151] op_sel_hi:[1,0]
	v_pk_mul_f32 v[18:19], v[18:19], v[134:135]
	v_cvt_pk_bf16_f32 v14, v22, v23
	v_cvt_pk_bf16_f32 v15, v24, v25
	v_cvt_pk_bf16_f32 v16, v16, v17
	v_cvt_pk_bf16_f32 v17, v26, v27
	global_store_dwordx4 v[30:31], v[14:17], off offset:256
	v_pk_mul_f32 v[12:13], v[12:13], v[132:133]
	v_pk_mul_f32 v[10:11], v[10:11], v[130:131]
	v_pk_mul_f32 v[16:17], v[20:21], v[136:137]
	v_pk_mul_f32 v[18:19], v[18:19], v[146:147] op_sel_hi:[1,0]
	v_pk_mul_f32 v[16:17], v[16:17], v[146:147] op_sel_hi:[1,0]
	v_pk_mul_f32 v[20:21], v[12:13], v[146:147] op_sel_hi:[1,0]
	v_pk_mul_f32 v[12:13], v[10:11], v[146:147] op_sel_hi:[1,0]
	v_cvt_pk_bf16_f32 v10, v18, v19
	v_cvt_pk_bf16_f32 v11, v16, v17
	v_add_co_u32_e32 v16, vcc, s71, v50
	s_mov_b64 s[0:1], 0x18000
	s_nop 0
	v_addc_co_u32_e32 v17, vcc, 0, v51, vcc
	v_pk_mul_f32 v[4:5], v[4:5], v[140:141]
	v_pk_mul_f32 v[2:3], v[2:3], v[138:139]
	v_lshl_add_u64 v[14:15], v[50:51], 0, s[0:1]
	v_cvt_pk_bf16_f32 v12, v12, v13
	v_cvt_pk_bf16_f32 v13, v20, v21
	global_store_dwordx4 v[16:17], v[10:13], off
	v_pk_mul_f32 v[8:9], v[8:9], v[144:145]
	v_pk_mul_f32 v[6:7], v[6:7], v[142:143]
	v_pk_mul_f32 v[10:11], v[4:5], v[146:147] op_sel_hi:[1,0]
	v_pk_mul_f32 v[4:5], v[2:3], v[146:147] op_sel_hi:[1,0]
	s_and_b64 vcc, exec, s[6:7]
	s_mov_b64 s[0:1], -1
	v_pk_mul_f32 v[8:9], v[8:9], v[146:147] op_sel_hi:[1,0]
	v_pk_mul_f32 v[6:7], v[6:7], v[146:147] op_sel_hi:[1,0]
	s_nop 0
	v_cvt_pk_bf16_f32 v2, v6, v7
	v_cvt_pk_bf16_f32 v3, v8, v9
	v_cvt_pk_bf16_f32 v4, v4, v5
	v_cvt_pk_bf16_f32 v5, v10, v11
	global_store_dwordx4 v[14:15], v[2:5], off offset:256
	s_cbranch_vccnz .LBB0_259
	v_readlane_b32 s0, v254, 60
	v_readlane_b32 s1, v254, 61
	s_andn2_b64 vcc, exec, s[0:1]
	s_cbranch_vccnz .LBB0_258
	s_barrier
	s_branch .LBB0_258

; __device__ __forceinline__ unsigned cvt_pk_bf16(float lo, float hi) { unsigned r; asm volatile("v_cvt_pk_bf16_f32 %0, %1, %2" : "=v"(r) : "v"(lo), "v"(hi)); return r; }
; __device__ __forceinline__ float rstd_of(const float* ss, int row) { const f32x4 p = *(const f32x4*)(ss + 4 * (size_t)row); return __builtin_amdgcn_rsqf(((p.x + p.y) + (p.z + p.w)) * (1.0f / D) + EPS); }
; __device__ __forceinline__ float silu_f(float g) { return g * __builtin_amdgcn_rcpf(1.0f + __builtin_amdgcn_exp2f(g * -1.4426950408889634f)); }
; __device__ __forceinline__ void rstd8(const float* ss, int row0, float (&rs)[2][4]) {
;     f32x4 p[2][4];
; #pragma unroll
;     for (int ai = 0; ai < 2; ++ai)
; #pragma unroll
;         for (int m = 0; m < 4; ++m) p[ai][m] = *(const f32x4*)(ss + 4 * (size_t)(row0 + ai * HALF + m * 16));
; #pragma unroll
;     for (int ai = 0; ai < 2; ++ai)
; #pragma unroll
;         for (int m = 0; m < 4; ++m) rs[ai][m] = __builtin_amdgcn_rsqf(((p[ai][m].x + p[ai][m].y) + (p[ai][m].z + p[ai][m].w)) * (1.0f / D) + EPS);
;     __device__ __forceinline__ void operator()(const f32x4 (&acc)[2][2][4][2], const Unit& u, int wr, int wc, int fr, int fq) const {
;         const int row0 = u.pm * BM + wr * 64 + fr, col0 = u.pn * HALF + wc * 32 + 8 * fq;
;         float rsv[2][4]; rstd8(ss, row0, rsv);
; #pragma unroll
;         for (int ai = 0; ai < 2; ++ai)
; #pragma unroll
;             for (int m = 0; m < 4; ++m) { const int row = row0 + ai * HALF + m * 16; const float rs = rsv[ai][m];
;                 f32x4 g0 = acc[ai][0][m][0] * rs, g1 = acc[ai][0][m][1] * rs; const f32x4 t0 = acc[ai][1][m][0] * rs, t1 = acc[ai][1][m][1] * rs;
;                 if (silu) {
; #pragma unroll
;                     for (int j = 0; j < 4; ++j) { g0[j] = silu_f(g0[j]); g1[j] = silu_f(g1[j]); } }
;                 g0 = g0 * t0; g1 = g1 * t1;
;                 u32x4 w; w.x = cvt_pk_bf16(g0[0], g0[1]); w.y = cvt_pk_bf16(g0[2], g0[3]); w.z = cvt_pk_bf16(g1[0], g1[1]); w.w = cvt_pk_bf16(g1[2], g1[3]);
;                 *(u32x4*)(O + (size_t)row * ldc + col0 + (size_t)(row >> 12) * adj) = w; }
.LBB0_309:
	s_and_b64 vcc, exec, s[6:7]
	s_cbranch_vccz .Lep_fast
	s_lshl_b32 s4, s54, 8
	s_add_i32 s4, s4, s89
	v_or_b32_e32 v172, s4, v183
	v_ashrrev_i32_e32 v173, 31, v172
	v_or_b32_e32 v170, 16, v172
	v_lshl_add_u64 v[74:75], v[172:173], 4, s[24:25]
	v_ashrrev_i32_e32 v171, 31, v170
	v_lshl_add_u64 v[76:77], v[170:171], 4, s[24:25]
	global_load_dwordx4 v[174:177], v[74:75], off
	global_load_dwordx4 v[154:157], v[76:77], off
	v_or_b32_e32 v168, 32, v172
	v_or_b32_e32 v166, 48, v172
	v_ashrrev_i32_e32 v169, 31, v168
	v_ashrrev_i32_e32 v167, 31, v166
	v_add_u32_e32 v164, 0x80, v172
	v_add_u32_e32 v162, 0x90, v172
	v_lshl_add_u64 v[74:75], v[168:169], 4, s[24:25]
	v_lshl_add_u64 v[76:77], v[166:167], 4, s[24:25]
	v_ashrrev_i32_e32 v165, 31, v164
	v_ashrrev_i32_e32 v163, 31, v162
	v_add_u32_e32 v160, 0xa0, v172
	v_add_u32_e32 v158, 0xb0, v172
	global_load_dwordx4 v[150:153], v[74:75], off
	global_load_dwordx4 v[146:149], v[76:77], off
	v_lshl_add_u64 v[74:75], v[164:165], 4, s[24:25]
	v_lshl_add_u64 v[76:77], v[162:163], 4, s[24:25]
	v_ashrrev_i32_e32 v161, 31, v160
	v_ashrrev_i32_e32 v159, 31, v158
	global_load_dwordx4 v[134:137], v[74:75], off
	global_load_dwordx4 v[114:117], v[76:77], off
	v_lshl_add_u64 v[74:75], v[160:161], 4, s[24:25]
	v_lshl_add_u64 v[76:77], v[158:159], 4, s[24:25]
	global_load_dwordx4 v[94:97], v[74:75], off
	s_nop 0
	global_load_dwordx4 v[74:77], v[76:77], off
	s_and_b64 vcc, exec, s[6:7]
	s_waitcnt vmcnt(0) lgkmcnt(0)
	v_mov_b32_e32 v178, v175
	v_mov_b32_e32 v179, v176
	v_mov_b32_e32 v175, v177
	v_pk_add_f32 v[174:175], v[178:179], v[174:175]
	s_nop 0
	v_add_f32_e32 v159, v174, v175
	v_fmamk_f32 v159, v159, 0x3a800000, v224
	v_rsq_f32_e32 v174, v159
	s_nop 0
	v_pk_mul_f32 v[176:177], v[144:145], v[174:175] op_sel_hi:[1,0]
	v_pk_mul_f32 v[178:179], v[142:143], v[174:175] op_sel_hi:[1,0]
	v_pk_mul_f32 v[142:143], v[140:141], v[174:175] op_sel_hi:[1,0]
	v_pk_mul_f32 v[144:145], v[138:139], v[174:175] op_sel_hi:[1,0]
	s_cbranch_vccnz .LBB0_311
	v_mul_f32_e32 v139, 0xbfb8aa3b, v144
	v_exp_f32_e32 v139, v139
	v_mul_f32_e32 v159, 0xbfb8aa3b, v176
	v_exp_f32_e32 v159, v159
	v_mul_f32_e32 v138, 0xbfb8aa3b, v178
	v_add_f32_e32 v139, 1.0, v139
	v_rcp_f32_e32 v140, v139
	v_mul_f32_e32 v139, 0xbfb8aa3b, v179
	v_exp_f32_e32 v138, v138
	v_exp_f32_e32 v139, v139
	v_add_f32_e32 v159, 1.0, v159
	v_rcp_f32_e32 v188, v159
	v_mul_f32_e32 v159, 0xbfb8aa3b, v142
	v_add_f32_e32 v138, 1.0, v138
	v_add_f32_e32 v139, 1.0, v139
	v_exp_f32_e32 v159, v159
	v_rcp_f32_e32 v138, v138
	v_rcp_f32_e32 v139, v139
	v_mul_f32_e32 v141, 0xbfb8aa3b, v145
	v_add_f32_e32 v159, 1.0, v159
	v_rcp_f32_e32 v190, v159
	v_mul_f32_e32 v159, 0xbfb8aa3b, v177
	v_pk_mul_f32 v[178:179], v[178:179], v[138:139]
	v_mul_f32_e32 v138, 0xbfb8aa3b, v143
	v_exp_f32_e32 v141, v141
	v_exp_f32_e32 v159, v159
	v_exp_f32_e32 v138, v138
	v_add_f32_e32 v141, 1.0, v141
	v_add_f32_e32 v159, 1.0, v159
	v_add_f32_e32 v138, 1.0, v138
	v_rcp_f32_e32 v141, v141
	v_rcp_f32_e32 v189, v159
	v_rcp_f32_e32 v191, v138
	v_pk_mul_f32 v[144:145], v[144:145], v[140:141]
	v_pk_mul_f32 v[176:177], v[176:177], v[188:189]
	v_pk_mul_f32 v[142:143], v[142:143], v[190:191]
.LBB0_311:
	v_add_f32_e32 v139, v154, v155
	v_add_f32_e32 v140, v156, v157
	v_mov_b32_e32 v175, v174
	v_add_f32_e32 v139, v139, v140
	v_fmamk_f32 v139, v139, 0x3a800000, v224
	v_mov_b32_e32 v154, v174
	v_mov_b32_e32 v155, v174
	v_pk_mul_f32 v[130:131], v[130:131], v[174:175]
	v_rsq_f32_e32 v140, v139
	v_pk_mul_f32 v[128:129], v[128:129], v[154:155]
	v_pk_mul_f32 v[126:127], v[126:127], v[174:175]
	v_pk_mul_f32 v[130:131], v[130:131], v[178:179]
	v_lshl_or_b32 v138, s48, 7, v184
	s_ashr_i32 s30, s4, 12
	v_pk_mul_f32 v[142:143], v[128:129], v[142:143]
	v_pk_mul_f32 v[128:129], v[126:127], v[144:145]
	v_cvt_pk_bf16_f32 v126, v130, v131
	v_mad_i64_i32 v[130:131], s[4:5], s0, v172, 0
	v_ashrrev_i32_e32 v139, 31, v138
	v_lshl_add_u64 v[130:131], v[130:131], 1, s[10:11]
	v_lshl_add_u64 v[130:131], v[138:139], 1, v[130:131]
	s_mul_hi_i32 s49, s28, s30
	s_mul_i32 s48, s28, s30
	v_pk_mul_f32 v[132:133], v[132:133], v[154:155]
	v_lshl_add_u64 v[130:131], s[48:49], 1, v[130:131]
	v_pk_mul_f32 v[124:125], v[124:125], v[140:141] op_sel_hi:[1,0]
	v_pk_mul_f32 v[122:123], v[122:123], v[140:141] op_sel_hi:[1,0]
	v_pk_mul_f32 v[120:121], v[120:121], v[140:141] op_sel_hi:[1,0]
	s_and_b64 vcc, exec, s[6:7]
	v_pk_mul_f32 v[118:119], v[118:119], v[140:141] op_sel_hi:[1,0]
	v_pk_mul_f32 v[132:133], v[132:133], v[176:177]
	s_nop 0
	v_cvt_pk_bf16_f32 v127, v132, v133
	v_cvt_pk_bf16_f32 v128, v128, v129
	v_cvt_pk_bf16_f32 v129, v142, v143
	global_store_dwordx4 v[130:131], v[126:129], off
	s_cbranch_vccnz .LBB0_313
	s_nop 0
	v_mul_f32_e32 v127, 0xbfb8aa3b, v118
	v_exp_f32_e32 v127, v127
	v_mul_f32_e32 v126, 0xbfb8aa3b, v122
	v_exp_f32_e32 v126, v126
	v_mul_f32_e32 v131, 0xbfb8aa3b, v120
	v_add_f32_e32 v127, 1.0, v127
	v_rcp_f32_e32 v128, v127
	v_mul_f32_e32 v127, 0xbfb8aa3b, v123
	v_exp_f32_e32 v127, v127
	v_add_f32_e32 v126, 1.0, v126
	v_exp_f32_e32 v131, v131
	v_rcp_f32_e32 v126, v126
	v_add_f32_e32 v127, 1.0, v127
	v_rcp_f32_e32 v127, v127
	v_add_f32_e32 v131, 1.0, v131
	v_mul_f32_e32 v129, 0xbfb8aa3b, v119
	v_mul_f32_e32 v130, 0xbfb8aa3b, v124
	v_rcp_f32_e32 v132, v131
	v_mul_f32_e32 v131, 0xbfb8aa3b, v125
	v_pk_mul_f32 v[122:123], v[122:123], v[126:127]
	v_mul_f32_e32 v126, 0xbfb8aa3b, v121
	v_exp_f32_e32 v129, v129
	v_exp_f32_e32 v130, v130
	v_exp_f32_e32 v131, v131
	v_exp_f32_e32 v126, v126
	v_add_f32_e32 v129, 1.0, v129
	v_add_f32_e32 v130, 1.0, v130
	v_add_f32_e32 v131, 1.0, v131
	v_add_f32_e32 v126, 1.0, v126
	v_rcp_f32_e32 v129, v129
	v_rcp_f32_e32 v130, v130
	v_rcp_f32_e32 v131, v131
	v_rcp_f32_e32 v133, v126
	v_pk_mul_f32 v[118:119], v[118:119], v[128:129]
	v_pk_mul_f32 v[124:125], v[124:125], v[130:131]
	v_pk_mul_f32 v[120:121], v[120:121], v[132:133]
; __device__ __forceinline__ unsigned cvt_pk_bf16(float lo, float hi) { unsigned r; asm volatile("v_cvt_pk_bf16_f32 %0, %1, %2" : "=v"(r) : "v"(lo), "v"(hi)); return r; }
; __device__ __forceinline__ float silu_f(float g) { return g * __builtin_amdgcn_rcpf(1.0f + __builtin_amdgcn_exp2f(g * -1.4426950408889634f)); }
;     __device__ __forceinline__ void operator()(const f32x4 (&acc)[2][2][4][2], const Unit& u, int wr, int wc, int fr, int fq) const {
;     ...
;             for (int m = 0; m < 4; ++m) { const int row = row0 + ai * HALF + m * 16; const float rs = rsv[ai][m];
;                 f32x4 g0 = acc[ai][0][m][0] * rs, g1 = acc[ai][0][m][1] * rs; const f32x4 t0 = acc[ai][1][m][0] * rs, t1 = acc[ai][1][m][1] * rs;
;                 if (silu) {
; #pragma unroll
;                     for (int j = 0; j < 4; ++j) { g0[j] = silu_f(g0[j]); g1[j] = silu_f(g1[j]); } }
;                 g0 = g0 * t0; g1 = g1 * t1;
;                 u32x4 w; w.x = cvt_pk_bf16(g0[0], g0[1]); w.y = cvt_pk_bf16(g0[2], g0[3]); w.z = cvt_pk_bf16(g1[0], g1[1]); w.w = cvt_pk_bf16(g1[2], g1[3]);
;                 *(u32x4*)(O + (size_t)row * ldc + col0 + (size_t)(row >> 12) * adj) = w; }
.LBB0_313:
	v_mov_b32_e32 v141, v140
	v_mov_b32_e32 v126, v140
	v_mov_b32_e32 v127, v140
	v_pk_mul_f32 v[112:113], v[112:113], v[126:127]
	v_pk_mul_f32 v[108:109], v[108:109], v[126:127]
	v_pk_mul_f32 v[126:127], v[106:107], v[140:141]
	v_add_f32_e32 v106, v150, v151
	v_add_f32_e32 v107, v152, v153
	v_add_f32_e32 v106, v106, v107
	v_fmamk_f32 v106, v106, 0x3a800000, v224
	v_pk_mul_f32 v[110:111], v[110:111], v[140:141]
	v_rsq_f32_e32 v106, v106
	v_pk_mul_f32 v[112:113], v[112:113], v[124:125]
	v_pk_mul_f32 v[110:111], v[110:111], v[122:123]
	v_pk_mul_f32 v[120:121], v[108:109], v[120:121]
	v_cvt_pk_bf16_f32 v108, v110, v111
	v_cvt_pk_bf16_f32 v109, v112, v113
	v_mad_i64_i32 v[112:113], s[4:5], s0, v170, 0
	v_lshl_add_u64 v[112:113], v[112:113], 1, s[10:11]
	v_lshl_add_u64 v[112:113], v[138:139], 1, v[112:113]
	v_lshl_add_u64 v[112:113], s[48:49], 1, v[112:113]
	v_pk_mul_f32 v[104:105], v[104:105], v[106:107] op_sel_hi:[1,0]
	v_pk_mul_f32 v[102:103], v[102:103], v[106:107] op_sel_hi:[1,0]
	v_pk_mul_f32 v[100:101], v[100:101], v[106:107] op_sel_hi:[1,0]
	s_and_b64 vcc, exec, s[6:7]
	v_pk_mul_f32 v[98:99], v[98:99], v[106:107] op_sel_hi:[1,0]
	v_pk_mul_f32 v[118:119], v[126:127], v[118:119]
	s_nop 0
	v_cvt_pk_bf16_f32 v110, v118, v119
	v_cvt_pk_bf16_f32 v111, v120, v121
	global_store_dwordx4 v[112:113], v[108:111], off
	s_cbranch_vccnz .LBB0_315
	v_mul_f32_e32 v107, 0xbfb8aa3b, v102
	v_exp_f32_e32 v107, v107
	s_nop 0
	v_add_f32_e32 v107, 1.0, v107
	v_rcp_f32_e32 v108, v107
	v_mul_f32_e32 v107, 0xbfb8aa3b, v98
	v_exp_f32_e32 v107, v107
	s_nop 0
	v_add_f32_e32 v107, 1.0, v107
	v_rcp_f32_e32 v110, v107
	v_mul_f32_e32 v107, 0xbfb8aa3b, v103
	v_exp_f32_e32 v107, v107
	s_nop 0
	v_add_f32_e32 v107, 1.0, v107
	v_rcp_f32_e32 v109, v107
	v_mul_f32_e32 v107, 0xbfb8aa3b, v99
	v_exp_f32_e32 v107, v107
	v_pk_mul_f32 v[102:103], v[102:103], v[108:109]
	v_add_f32_e32 v107, 1.0, v107
	v_rcp_f32_e32 v111, v107
	v_mul_f32_e32 v107, 0xbfb8aa3b, v104
	v_exp_f32_e32 v107, v107
	v_pk_mul_f32 v[98:99], v[98:99], v[110:111]
	v_add_f32_e32 v107, 1.0, v107
	v_rcp_f32_e32 v112, v107
	v_mul_f32_e32 v107, 0xbfb8aa3b, v100
	v_exp_f32_e32 v107, v107
	s_nop 0
	v_add_f32_e32 v107, 1.0, v107
	v_rcp_f32_e32 v118, v107
	v_mul_f32_e32 v107, 0xbfb8aa3b, v105
	v_exp_f32_e32 v107, v107
	s_nop 0
	v_add_f32_e32 v107, 1.0, v107
	v_rcp_f32_e32 v113, v107
	v_mul_f32_e32 v107, 0xbfb8aa3b, v101
	v_exp_f32_e32 v107, v107
	v_pk_mul_f32 v[104:105], v[104:105], v[112:113]
	v_add_f32_e32 v107, 1.0, v107
	v_rcp_f32_e32 v119, v107
	s_nop 0
	v_pk_mul_f32 v[100:101], v[100:101], v[118:119]
.LBB0_315:
	v_mov_b32_e32 v107, v106
	v_mov_b32_e32 v108, v106
	v_mov_b32_e32 v109, v106
	v_pk_mul_f32 v[90:91], v[90:91], v[106:107]
	v_pk_mul_f32 v[106:107], v[86:87], v[106:107]
	v_add_f32_e32 v86, v146, v147
	v_add_f32_e32 v87, v148, v149
	v_add_f32_e32 v86, v86, v87
	v_pk_mul_f32 v[92:93], v[92:93], v[108:109]
	v_fmamk_f32 v86, v86, 0x3a800000, v224
	v_pk_mul_f32 v[88:89], v[88:89], v[108:109]
	v_rsq_f32_e32 v86, v86
	v_pk_mul_f32 v[92:93], v[92:93], v[104:105]
	v_pk_mul_f32 v[90:91], v[90:91], v[102:103]
	v_pk_mul_f32 v[100:101], v[88:89], v[100:101]
	v_cvt_pk_bf16_f32 v88, v90, v91
	v_cvt_pk_bf16_f32 v89, v92, v93
	v_mad_i64_i32 v[92:93], s[4:5], s0, v168, 0
	v_lshl_add_u64 v[92:93], v[92:93], 1, s[10:11]
	v_lshl_add_u64 v[92:93], v[138:139], 1, v[92:93]
	v_lshl_add_u64 v[92:93], s[48:49], 1, v[92:93]
	v_pk_mul_f32 v[84:85], v[84:85], v[86:87] op_sel_hi:[1,0]
	v_pk_mul_f32 v[82:83], v[82:83], v[86:87] op_sel_hi:[1,0]
	v_pk_mul_f32 v[80:81], v[80:81], v[86:87] op_sel_hi:[1,0]
	s_and_b64 vcc, exec, s[6:7]
	v_pk_mul_f32 v[78:79], v[78:79], v[86:87] op_sel_hi:[1,0]
	v_pk_mul_f32 v[98:99], v[106:107], v[98:99]
	s_nop 0
	v_cvt_pk_bf16_f32 v90, v98, v99
	v_cvt_pk_bf16_f32 v91, v100, v101
	global_store_dwordx4 v[92:93], v[88:91], off
	s_cbranch_vccnz .LBB0_317
	v_mul_f32_e32 v87, 0xbfb8aa3b, v82
	v_exp_f32_e32 v87, v87
	s_nop 0
	v_add_f32_e32 v87, 1.0, v87
	v_rcp_f32_e32 v88, v87
	v_mul_f32_e32 v87, 0xbfb8aa3b, v78
	v_exp_f32_e32 v87, v87
	s_nop 0
	v_add_f32_e32 v87, 1.0, v87
	v_rcp_f32_e32 v90, v87
	v_mul_f32_e32 v87, 0xbfb8aa3b, v83
	v_exp_f32_e32 v87, v87
	s_nop 0
	v_add_f32_e32 v87, 1.0, v87
	v_rcp_f32_e32 v89, v87
	v_mul_f32_e32 v87, 0xbfb8aa3b, v79
	v_exp_f32_e32 v87, v87
	v_pk_mul_f32 v[82:83], v[82:83], v[88:89]
	v_add_f32_e32 v87, 1.0, v87
	v_rcp_f32_e32 v91, v87
	v_mul_f32_e32 v87, 0xbfb8aa3b, v84
	v_exp_f32_e32 v87, v87
	v_pk_mul_f32 v[78:79], v[78:79], v[90:91]
	v_add_f32_e32 v87, 1.0, v87
	v_rcp_f32_e32 v92, v87
	v_mul_f32_e32 v87, 0xbfb8aa3b, v80
	v_exp_f32_e32 v87, v87
	s_nop 0
	v_add_f32_e32 v87, 1.0, v87
	v_rcp_f32_e32 v98, v87
	v_mul_f32_e32 v87, 0xbfb8aa3b, v85
	v_exp_f32_e32 v87, v87
	s_nop 0
	v_add_f32_e32 v87, 1.0, v87
	v_rcp_f32_e32 v93, v87
	v_mul_f32_e32 v87, 0xbfb8aa3b, v81
	v_exp_f32_e32 v87, v87
	v_pk_mul_f32 v[84:85], v[84:85], v[92:93]
	v_add_f32_e32 v87, 1.0, v87
	v_rcp_f32_e32 v99, v87
	s_nop 0
	v_pk_mul_f32 v[80:81], v[80:81], v[98:99]
; __device__ __forceinline__ unsigned cvt_pk_bf16(float lo, float hi) { unsigned r; asm volatile("v_cvt_pk_bf16_f32 %0, %1, %2" : "=v"(r) : "v"(lo), "v"(hi)); return r; }
; __device__ __forceinline__ float silu_f(float g) { return g * __builtin_amdgcn_rcpf(1.0f + __builtin_amdgcn_exp2f(g * -1.4426950408889634f)); }
;     __device__ __forceinline__ void operator()(const f32x4 (&acc)[2][2][4][2], const Unit& u, int wr, int wc, int fr, int fq) const {
;     ...
;             for (int m = 0; m < 4; ++m) { const int row = row0 + ai * HALF + m * 16; const float rs = rsv[ai][m];
;                 f32x4 g0 = acc[ai][0][m][0] * rs, g1 = acc[ai][0][m][1] * rs; const f32x4 t0 = acc[ai][1][m][0] * rs, t1 = acc[ai][1][m][1] * rs;
;                 if (silu) {
; #pragma unroll
;                     for (int j = 0; j < 4; ++j) { g0[j] = silu_f(g0[j]); g1[j] = silu_f(g1[j]); } }
;                 g0 = g0 * t0; g1 = g1 * t1;
;                 u32x4 w; w.x = cvt_pk_bf16(g0[0], g0[1]); w.y = cvt_pk_bf16(g0[2], g0[3]); w.z = cvt_pk_bf16(g1[0], g1[1]); w.w = cvt_pk_bf16(g1[2], g1[3]);
;                 *(u32x4*)(O + (size_t)row * ldc + col0 + (size_t)(row >> 12) * adj) = w; }
.LBB0_317:
	v_mov_b32_e32 v87, v86
	v_mov_b32_e32 v88, v86
	v_mov_b32_e32 v89, v86
	v_pk_mul_f32 v[70:71], v[70:71], v[86:87]
	v_pk_mul_f32 v[86:87], v[66:67], v[86:87]
	v_add_f32_e32 v66, v134, v135
	v_add_f32_e32 v67, v136, v137
	v_add_f32_e32 v66, v66, v67
	v_pk_mul_f32 v[72:73], v[72:73], v[88:89]
	v_fmamk_f32 v66, v66, 0x3a800000, v224
	v_pk_mul_f32 v[68:69], v[68:69], v[88:89]
	v_rsq_f32_e32 v66, v66
	v_pk_mul_f32 v[72:73], v[72:73], v[84:85]
	v_pk_mul_f32 v[70:71], v[70:71], v[82:83]
	v_pk_mul_f32 v[80:81], v[68:69], v[80:81]
	v_cvt_pk_bf16_f32 v68, v70, v71
	v_cvt_pk_bf16_f32 v69, v72, v73
	v_mad_i64_i32 v[72:73], s[4:5], s0, v166, 0
	v_lshl_add_u64 v[72:73], v[72:73], 1, s[10:11]
	v_lshl_add_u64 v[72:73], v[138:139], 1, v[72:73]
	v_lshl_add_u64 v[72:73], s[48:49], 1, v[72:73]
	v_pk_mul_f32 v[64:65], v[64:65], v[66:67] op_sel_hi:[1,0]
	v_pk_mul_f32 v[62:63], v[62:63], v[66:67] op_sel_hi:[1,0]
	v_pk_mul_f32 v[60:61], v[60:61], v[66:67] op_sel_hi:[1,0]
	s_and_b64 vcc, exec, s[6:7]
	v_pk_mul_f32 v[58:59], v[58:59], v[66:67] op_sel_hi:[1,0]
	v_pk_mul_f32 v[78:79], v[86:87], v[78:79]
	s_nop 0
	v_cvt_pk_bf16_f32 v70, v78, v79
	v_cvt_pk_bf16_f32 v71, v80, v81
	global_store_dwordx4 v[72:73], v[68:71], off
	s_cbranch_vccnz .LBB0_319
	v_mul_f32_e32 v67, 0xbfb8aa3b, v62
	v_exp_f32_e32 v67, v67
	s_nop 0
	v_add_f32_e32 v67, 1.0, v67
	v_rcp_f32_e32 v68, v67
	v_mul_f32_e32 v67, 0xbfb8aa3b, v58
	v_exp_f32_e32 v67, v67
	s_nop 0
	v_add_f32_e32 v67, 1.0, v67
	v_rcp_f32_e32 v70, v67
	v_mul_f32_e32 v67, 0xbfb8aa3b, v63
	v_exp_f32_e32 v67, v67
	s_nop 0
	v_add_f32_e32 v67, 1.0, v67
	v_rcp_f32_e32 v69, v67
	v_mul_f32_e32 v67, 0xbfb8aa3b, v59
	v_exp_f32_e32 v67, v67
	v_pk_mul_f32 v[62:63], v[62:63], v[68:69]
	v_add_f32_e32 v67, 1.0, v67
	v_rcp_f32_e32 v71, v67
	v_mul_f32_e32 v67, 0xbfb8aa3b, v64
	v_exp_f32_e32 v67, v67
	v_pk_mul_f32 v[58:59], v[58:59], v[70:71]
	v_add_f32_e32 v67, 1.0, v67
	v_rcp_f32_e32 v72, v67
	v_mul_f32_e32 v67, 0xbfb8aa3b, v60
	v_exp_f32_e32 v67, v67
	s_nop 0
	v_add_f32_e32 v67, 1.0, v67
	v_rcp_f32_e32 v78, v67
	v_mul_f32_e32 v67, 0xbfb8aa3b, v65
	v_exp_f32_e32 v67, v67
	s_nop 0
	v_add_f32_e32 v67, 1.0, v67
	v_rcp_f32_e32 v73, v67
	v_mul_f32_e32 v67, 0xbfb8aa3b, v61
	v_exp_f32_e32 v67, v67
	v_pk_mul_f32 v[64:65], v[64:65], v[72:73]
	v_add_f32_e32 v67, 1.0, v67
	v_rcp_f32_e32 v79, v67
	s_nop 0
	v_pk_mul_f32 v[60:61], v[60:61], v[78:79]
.LBB0_319:
	s_nop 0
	v_mov_b32_e32 v68, v66
	v_mov_b32_e32 v69, v66
	v_pk_mul_f32 v[56:57], v[56:57], v[68:69]
	v_pk_mul_f32 v[68:69], v[52:53], v[68:69]
	v_add_f32_e32 v52, v114, v115
	v_add_f32_e32 v53, v116, v117
	v_mov_b32_e32 v67, v66
	v_add_f32_e32 v52, v52, v53
	v_pk_mul_f32 v[54:55], v[54:55], v[66:67]
	v_pk_mul_f32 v[50:51], v[50:51], v[66:67]
	v_fmamk_f32 v52, v52, 0x3a800000, v224
	v_rsq_f32_e32 v52, v52
	v_pk_mul_f32 v[56:57], v[56:57], v[64:65]
	v_pk_mul_f32 v[54:55], v[54:55], v[62:63]
	v_pk_mul_f32 v[50:51], v[50:51], v[58:59]
	v_cvt_pk_bf16_f32 v54, v54, v55
	v_cvt_pk_bf16_f32 v55, v56, v57
	v_ashrrev_i32_e32 v70, 12, v164
	v_cvt_pk_bf16_f32 v56, v50, v51
	v_mad_i64_i32 v[50:51], s[4:5], s0, v164, 0
	v_lshl_add_u64 v[50:51], v[50:51], 1, s[10:11]
	v_lshl_add_u64 v[58:59], v[138:139], 1, v[50:51]
	v_mul_hi_i32_i24_e32 v51, s28, v70
	v_mul_i32_i24_e32 v50, s28, v70
	v_lshl_add_u64 v[58:59], v[50:51], 1, v[58:59]
	v_pk_mul_f32 v[48:49], v[48:49], v[52:53] op_sel_hi:[1,0]
	v_pk_mul_f32 v[46:47], v[46:47], v[52:53] op_sel_hi:[1,0]
	v_pk_mul_f32 v[44:45], v[44:45], v[52:53] op_sel_hi:[1,0]
	s_and_b64 vcc, exec, s[6:7]
	v_pk_mul_f32 v[42:43], v[42:43], v[52:53] op_sel_hi:[1,0]
	v_pk_mul_f32 v[60:61], v[68:69], v[60:61]
	s_nop 0
	v_cvt_pk_bf16_f32 v57, v60, v61
	global_store_dwordx4 v[58:59], v[54:57], off
	s_cbranch_vccnz .LBB0_321
	v_mul_f32_e32 v53, 0xbfb8aa3b, v46
	v_exp_f32_e32 v53, v53
	s_nop 0
	v_add_f32_e32 v53, 1.0, v53
	v_rcp_f32_e32 v54, v53
	v_mul_f32_e32 v53, 0xbfb8aa3b, v42
	v_exp_f32_e32 v53, v53
	s_nop 0
	v_add_f32_e32 v53, 1.0, v53
	v_rcp_f32_e32 v56, v53
	v_mul_f32_e32 v53, 0xbfb8aa3b, v47
	v_exp_f32_e32 v53, v53
	s_nop 0
	v_add_f32_e32 v53, 1.0, v53
	v_rcp_f32_e32 v55, v53
	v_mul_f32_e32 v53, 0xbfb8aa3b, v43
	v_exp_f32_e32 v53, v53
	v_pk_mul_f32 v[46:47], v[46:47], v[54:55]
	v_add_f32_e32 v53, 1.0, v53
	v_rcp_f32_e32 v57, v53
	v_mul_f32_e32 v53, 0xbfb8aa3b, v48
	v_exp_f32_e32 v53, v53
	v_pk_mul_f32 v[42:43], v[42:43], v[56:57]
	v_add_f32_e32 v53, 1.0, v53
	v_rcp_f32_e32 v58, v53
	v_mul_f32_e32 v53, 0xbfb8aa3b, v44
	v_exp_f32_e32 v53, v53
	s_nop 0
	v_add_f32_e32 v53, 1.0, v53
	v_rcp_f32_e32 v60, v53
	v_mul_f32_e32 v53, 0xbfb8aa3b, v49
	v_exp_f32_e32 v53, v53
	s_nop 0
	v_add_f32_e32 v53, 1.0, v53
	v_rcp_f32_e32 v59, v53
	v_mul_f32_e32 v53, 0xbfb8aa3b, v45
	v_exp_f32_e32 v53, v53
	v_pk_mul_f32 v[48:49], v[48:49], v[58:59]
	v_add_f32_e32 v53, 1.0, v53
	v_rcp_f32_e32 v61, v53
	s_nop 0
	v_pk_mul_f32 v[44:45], v[44:45], v[60:61]
; __device__ __forceinline__ unsigned cvt_pk_bf16(float lo, float hi) { unsigned r; asm volatile("v_cvt_pk_bf16_f32 %0, %1, %2" : "=v"(r) : "v"(lo), "v"(hi)); return r; }
; __device__ __forceinline__ float silu_f(float g) { return g * __builtin_amdgcn_rcpf(1.0f + __builtin_amdgcn_exp2f(g * -1.4426950408889634f)); }
;     __device__ __forceinline__ void operator()(const f32x4 (&acc)[2][2][4][2], const Unit& u, int wr, int wc, int fr, int fq) const {
;     ...
;             for (int m = 0; m < 4; ++m) { const int row = row0 + ai * HALF + m * 16; const float rs = rsv[ai][m];
;                 f32x4 g0 = acc[ai][0][m][0] * rs, g1 = acc[ai][0][m][1] * rs; const f32x4 t0 = acc[ai][1][m][0] * rs, t1 = acc[ai][1][m][1] * rs;
;                 if (silu) {
; #pragma unroll
;                     for (int j = 0; j < 4; ++j) { g0[j] = silu_f(g0[j]); g1[j] = silu_f(g1[j]); } }
;                 g0 = g0 * t0; g1 = g1 * t1;
;                 u32x4 w; w.x = cvt_pk_bf16(g0[0], g0[1]); w.y = cvt_pk_bf16(g0[2], g0[3]); w.z = cvt_pk_bf16(g1[0], g1[1]); w.w = cvt_pk_bf16(g1[2], g1[3]);
;                 *(u32x4*)(O + (size_t)row * ldc + col0 + (size_t)(row >> 12) * adj) = w; }
.LBB0_321:
	v_mov_b32_e32 v53, v52
	v_mov_b32_e32 v54, v52
	v_mov_b32_e32 v55, v52
	v_pk_mul_f32 v[38:39], v[38:39], v[52:53]
	v_pk_mul_f32 v[52:53], v[34:35], v[52:53]
	v_add_f32_e32 v34, v94, v95
	v_add_f32_e32 v35, v96, v97
	v_add_f32_e32 v34, v34, v35
	v_pk_mul_f32 v[40:41], v[40:41], v[54:55]
	v_fmamk_f32 v34, v34, 0x3a800000, v224
	v_pk_mul_f32 v[36:37], v[36:37], v[54:55]
	v_rsq_f32_e32 v34, v34
	v_pk_mul_f32 v[40:41], v[40:41], v[48:49]
	v_pk_mul_f32 v[38:39], v[38:39], v[46:47]
	v_pk_mul_f32 v[44:45], v[36:37], v[44:45]
	v_cvt_pk_bf16_f32 v36, v38, v39
	v_cvt_pk_bf16_f32 v37, v40, v41
	v_mad_i64_i32 v[40:41], s[4:5], s0, v162, 0
	v_lshl_add_u64 v[40:41], v[40:41], 1, s[10:11]
	v_lshl_add_u64 v[40:41], v[138:139], 1, v[40:41]
	v_lshl_add_u64 v[40:41], v[50:51], 1, v[40:41]
	v_pk_mul_f32 v[32:33], v[32:33], v[34:35] op_sel_hi:[1,0]
	v_pk_mul_f32 v[30:31], v[30:31], v[34:35] op_sel_hi:[1,0]
	v_pk_mul_f32 v[28:29], v[28:29], v[34:35] op_sel_hi:[1,0]
	s_and_b64 vcc, exec, s[6:7]
	v_pk_mul_f32 v[26:27], v[26:27], v[34:35] op_sel_hi:[1,0]
	v_pk_mul_f32 v[42:43], v[52:53], v[42:43]
	s_nop 0
	v_cvt_pk_bf16_f32 v38, v42, v43
	v_cvt_pk_bf16_f32 v39, v44, v45
	global_store_dwordx4 v[40:41], v[36:39], off
	s_cbranch_vccnz .LBB0_323
	v_mul_f32_e32 v35, 0xbfb8aa3b, v30
	v_exp_f32_e32 v35, v35
	s_nop 0
	v_add_f32_e32 v35, 1.0, v35
	v_rcp_f32_e32 v36, v35
	v_mul_f32_e32 v35, 0xbfb8aa3b, v26
	v_exp_f32_e32 v35, v35
	s_nop 0
	v_add_f32_e32 v35, 1.0, v35
	v_rcp_f32_e32 v38, v35
	v_mul_f32_e32 v35, 0xbfb8aa3b, v31
	v_exp_f32_e32 v35, v35
	s_nop 0
	v_add_f32_e32 v35, 1.0, v35
	v_rcp_f32_e32 v37, v35
	v_mul_f32_e32 v35, 0xbfb8aa3b, v27
	v_exp_f32_e32 v35, v35
	v_pk_mul_f32 v[30:31], v[30:31], v[36:37]
	v_add_f32_e32 v35, 1.0, v35
	v_rcp_f32_e32 v39, v35
	v_mul_f32_e32 v35, 0xbfb8aa3b, v32
	v_exp_f32_e32 v35, v35
	v_pk_mul_f32 v[26:27], v[26:27], v[38:39]
	v_add_f32_e32 v35, 1.0, v35
	v_rcp_f32_e32 v40, v35
	v_mul_f32_e32 v35, 0xbfb8aa3b, v28
	v_exp_f32_e32 v35, v35
	s_nop 0
	v_add_f32_e32 v35, 1.0, v35
	v_rcp_f32_e32 v42, v35
	v_mul_f32_e32 v35, 0xbfb8aa3b, v33
	v_exp_f32_e32 v35, v35
	s_nop 0
	v_add_f32_e32 v35, 1.0, v35
	v_rcp_f32_e32 v41, v35
	v_mul_f32_e32 v35, 0xbfb8aa3b, v29
	v_exp_f32_e32 v35, v35
	v_pk_mul_f32 v[32:33], v[32:33], v[40:41]
	v_add_f32_e32 v35, 1.0, v35
	v_rcp_f32_e32 v43, v35
	s_nop 0
	v_pk_mul_f32 v[28:29], v[28:29], v[42:43]
.LBB0_323:
	v_mov_b32_e32 v35, v34
	v_mov_b32_e32 v36, v34
	v_mov_b32_e32 v37, v34
	v_pk_mul_f32 v[22:23], v[22:23], v[34:35]
	v_pk_mul_f32 v[34:35], v[18:19], v[34:35]
	v_add_f32_e32 v18, v74, v75
	v_add_f32_e32 v19, v76, v77
	v_add_f32_e32 v18, v18, v19
	v_pk_mul_f32 v[24:25], v[24:25], v[36:37]
	v_fmamk_f32 v18, v18, 0x3a800000, v224
	v_pk_mul_f32 v[20:21], v[20:21], v[36:37]
	v_rsq_f32_e32 v18, v18
	v_pk_mul_f32 v[24:25], v[24:25], v[32:33]
	v_pk_mul_f32 v[22:23], v[22:23], v[30:31]
	v_pk_mul_f32 v[28:29], v[20:21], v[28:29]
	v_cvt_pk_bf16_f32 v20, v22, v23
	v_cvt_pk_bf16_f32 v21, v24, v25
	v_mad_i64_i32 v[24:25], s[4:5], s0, v160, 0
	v_lshl_add_u64 v[24:25], v[24:25], 1, s[10:11]
	v_lshl_add_u64 v[24:25], v[138:139], 1, v[24:25]
	v_lshl_add_u64 v[24:25], v[50:51], 1, v[24:25]
	v_pk_mul_f32 v[16:17], v[16:17], v[18:19] op_sel_hi:[1,0]
	v_pk_mul_f32 v[14:15], v[14:15], v[18:19] op_sel_hi:[1,0]
	v_pk_mul_f32 v[12:13], v[12:13], v[18:19] op_sel_hi:[1,0]
	s_and_b64 vcc, exec, s[6:7]
	v_pk_mul_f32 v[10:11], v[10:11], v[18:19] op_sel_hi:[1,0]
	v_pk_mul_f32 v[26:27], v[34:35], v[26:27]
	s_nop 0
	v_cvt_pk_bf16_f32 v22, v26, v27
	v_cvt_pk_bf16_f32 v23, v28, v29
	global_store_dwordx4 v[24:25], v[20:23], off
	s_cbranch_vccnz .LBB0_325
	v_mul_f32_e32 v19, 0xbfb8aa3b, v14
	v_exp_f32_e32 v19, v19
	s_nop 0
	v_add_f32_e32 v19, 1.0, v19
	v_rcp_f32_e32 v20, v19
	v_mul_f32_e32 v19, 0xbfb8aa3b, v10
	v_exp_f32_e32 v19, v19
	s_nop 0
	v_add_f32_e32 v19, 1.0, v19
	v_rcp_f32_e32 v22, v19
	v_mul_f32_e32 v19, 0xbfb8aa3b, v15
	v_exp_f32_e32 v19, v19
	s_nop 0
	v_add_f32_e32 v19, 1.0, v19
	v_rcp_f32_e32 v21, v19
	v_mul_f32_e32 v19, 0xbfb8aa3b, v11
	v_exp_f32_e32 v19, v19
	v_pk_mul_f32 v[14:15], v[14:15], v[20:21]
	v_add_f32_e32 v19, 1.0, v19
	v_rcp_f32_e32 v23, v19
	v_mul_f32_e32 v19, 0xbfb8aa3b, v16
	v_exp_f32_e32 v19, v19
	v_pk_mul_f32 v[10:11], v[10:11], v[22:23]
	v_add_f32_e32 v19, 1.0, v19
	v_rcp_f32_e32 v24, v19
	v_mul_f32_e32 v19, 0xbfb8aa3b, v12
	v_exp_f32_e32 v19, v19
	s_nop 0
	v_add_f32_e32 v19, 1.0, v19
	v_rcp_f32_e32 v26, v19
	v_mul_f32_e32 v19, 0xbfb8aa3b, v17
	v_exp_f32_e32 v19, v19
	s_nop 0
	v_add_f32_e32 v19, 1.0, v19
	v_rcp_f32_e32 v25, v19
	v_mul_f32_e32 v19, 0xbfb8aa3b, v13
	v_exp_f32_e32 v19, v19
	v_pk_mul_f32 v[16:17], v[16:17], v[24:25]
	v_add_f32_e32 v19, 1.0, v19
	v_rcp_f32_e32 v27, v19
	s_nop 0
	v_pk_mul_f32 v[12:13], v[12:13], v[26:27]
.LBB0_325:
	v_mov_b32_e32 v19, v18
	v_mov_b32_e32 v20, v18
	v_mov_b32_e32 v21, v18
	v_pk_mul_f32 v[6:7], v[6:7], v[18:19]
	v_pk_mul_f32 v[4:5], v[4:5], v[20:21]
	v_pk_mul_f32 v[2:3], v[2:3], v[18:19]
	v_pk_mul_f32 v[6:7], v[6:7], v[14:15]
	v_pk_mul_f32 v[12:13], v[4:5], v[12:13]
	v_pk_mul_f32 v[4:5], v[2:3], v[10:11]
	v_cvt_pk_bf16_f32 v2, v6, v7
	v_mad_i64_i32 v[6:7], s[4:5], s0, v158, 0
	v_lshl_add_u64 v[6:7], v[6:7], 1, s[10:11]
	v_lshl_add_u64 v[6:7], v[138:139], 1, v[6:7]
	v_pk_mul_f32 v[8:9], v[8:9], v[20:21]
	v_lshl_add_u64 v[6:7], v[50:51], 1, v[6:7]
	s_andn2_b64 vcc, exec, s[8:9]
	s_mov_b64 s[4:5], -1
	v_pk_mul_f32 v[8:9], v[8:9], v[16:17]
	s_nop 0
	v_cvt_pk_bf16_f32 v3, v8, v9
	v_cvt_pk_bf16_f32 v4, v4, v5
	v_cvt_pk_bf16_f32 v5, v12, v13
	global_store_dwordx4 v[6:7], v[2:5], off

; __device__ __forceinline__ f32x2 gelu_pk(f32x2 v) {
;     const f32x2 av = __builtin_elementwise_abs(v), d = av * 0.2316418882f + 1.0f;
;     f32x2 t; t.x = __builtin_amdgcn_rcpf(d.x); t.y = __builtin_amdgcn_rcpf(d.y);
;     f32x2 q = t * 0.5307027145f + (-0.7265760135f); q = q * t + 0.7107068705f; q = q * t + (-0.142248368f); q = q * t + 0.127414796f; q = q * t;
;     const f32x2 s = (v * v) * (-0.72134752044f);
;     f32x2 e; e.x = __builtin_amdgcn_exp2f(s.x); e.y = __builtin_amdgcn_exp2f(s.y);
;     const f32x2 m = v * (q * e), r = v - m;
;     f32x2 o; o.x = v.x < 0.f ? m.x : r.x; o.y = v.y < 0.f ? m.y : r.y; return o;
; }
;     __device__ __forceinline__ void operator()(const f32x4 (&acc)[2][2][4][2], const Unit& u, int wr, int wc, int fr, int fq) const {
;     ...
;         float rsv[2][4]; rstd8(ss, row0, rsv);
; #pragma unroll
;         for (int ai = 0; ai < 2; ++ai)
; #pragma unroll
;             for (int m = 0; m < 4; ++m) { const int row = row0 + ai * HALF + m * 16; const float rs = rsv[ai][m]; bf16_t* rowp = O + (size_t)row * ldc + col0; float s1 = 0.f, s2 = 0.f;
; #pragma unroll
;                 for (int bj = 0; bj < 2; ++bj) { f32x4 v0 = acc[ai][bj][m][0] * rs, v1 = acc[ai][bj][m][1] * rs;
;                     const f32x2 a = gelu_pk((f32x2){v0[0], v0[1]}), b = gelu_pk((f32x2){v0[2], v0[3]}), c = gelu_pk((f32x2){v1[0], v1[1]}), d = gelu_pk((f32x2){v1[2], v1[3]});
.LBB0_352:
	s_lshl_b32 s27, s10, 8
	v_add_u32_e32 v190, s27, v184
	v_ashrrev_i32_e32 v191, 31, v190
	v_lshl_add_u64 v[34:35], v[190:191], 4, s[22:23]
	global_load_dwordx4 v[176:179], v[34:35], off
	v_or_b32_e32 v174, 16, v190
	v_or_b32_e32 v172, 32, v190
	v_or_b32_e32 v170, 48, v190
	v_add_u32_e32 v168, 0x80, v190
	v_add_u32_e32 v166, 0x90, v190
	v_add_u32_e32 v164, 0xa0, v190
	v_add_u32_e32 v162, 0xb0, v190
	s_mov_b32 s4, 0xbf3a00e3
	v_ashrrev_i32_e32 v175, 31, v174
	v_lshl_add_u64 v[34:35], v[174:175], 4, s[22:23]
	v_ashrrev_i32_e32 v173, 31, v172
	global_load_dwordx4 v[146:149], v[34:35], off
	v_lshl_add_u64 v[34:35], v[172:173], 4, s[22:23]
	v_ashrrev_i32_e32 v171, 31, v170
	global_load_dwordx4 v[126:129], v[34:35], off
	v_lshl_add_u64 v[34:35], v[170:171], 4, s[22:23]
	v_ashrrev_i32_e32 v169, 31, v168
	global_load_dwordx4 v[110:113], v[34:35], off
	v_lshl_add_u64 v[34:35], v[168:169], 4, s[22:23]
	v_ashrrev_i32_e32 v167, 31, v166
	global_load_dwordx4 v[94:97], v[34:35], off
	v_lshl_add_u64 v[34:35], v[166:167], 4, s[22:23]
	v_ashrrev_i32_e32 v165, 31, v164
	global_load_dwordx4 v[74:77], v[34:35], off
	v_lshl_add_u64 v[34:35], v[164:165], 4, s[22:23]
	v_ashrrev_i32_e32 v163, 31, v162
	global_load_dwordx4 v[54:57], v[34:35], off
	v_lshl_add_u64 v[34:35], v[162:163], 4, s[22:23]
	global_load_dwordx4 v[34:37], v[34:35], off
	v_lshl_or_b32 v160, s46, 8, v185
	v_ashrrev_i32_e32 v161, 31, v160
	s_cmp_gt_i32 s46, 3
	s_cselect_b64 s[36:37], -1, 0
	s_cmp_lt_i32 s46, 4
	s_waitcnt vmcnt(0) lgkmcnt(0)
	v_mov_b32_e32 v192, v177
	v_mov_b32_e32 v193, v178
	v_mov_b32_e32 v177, v179
	v_pk_add_f32 v[176:177], v[192:193], v[176:177]
	s_nop 0
	v_add_f32_e32 v0, v176, v177
	v_fmamk_f32 v0, v0, 0x3a800000, v224
	v_rsq_f32_e32 v0, v0
	v_lshlrev_b64 v[176:177], 12, v[190:191]
	v_lshl_add_u64 v[176:177], s[20:21], 0, v[176:177]
	v_lshl_add_u64 v[176:177], v[160:161], 1, v[176:177]
	v_pk_mul_f32 v[178:179], v[154:155], v[0:1] op_sel_hi:[1,0]
	v_pk_mul_f32 v[154:155], v[150:151], v[0:1] op_sel_hi:[1,0]
	v_and_b32_e32 v151, 0x7fffffff, v179
	v_and_b32_e32 v150, 0x7fffffff, v178
	v_pk_fma_f32 v[150:151], v[150:151], s[64:65], 1.0 op_sel_hi:[1,0,0]
	v_pk_mul_f32 v[202:203], v[178:179], v[178:179]
	v_rcp_f32_e32 v190, v150
	v_rcp_f32_e32 v191, v151
	v_mov_b64_e32 v[150:151], s[4:5]
	v_pk_mul_f32 v[202:203], v[202:203], s[76:77] op_sel_hi:[1,0]
	v_cmp_gt_f32_e32 vcc, 0, v178
	v_pk_fma_f32 v[192:193], v[190:191], s[66:67], v[150:151] op_sel_hi:[1,0,0]
	v_exp_f32_e32 v202, v202
	v_pk_fma_f32 v[192:193], v[190:191], v[192:193], s[70:71] op_sel_hi:[1,1,0]
	v_exp_f32_e32 v203, v203
	v_pk_fma_f32 v[192:193], v[190:191], v[192:193], s[72:73] op_sel_hi:[1,1,0]
	v_pk_mul_f32 v[156:157], v[156:157], v[0:1] op_sel_hi:[1,0]
	v_pk_fma_f32 v[192:193], v[190:191], v[192:193], s[74:75] op_sel_hi:[1,1,0]
	v_pk_mul_f32 v[152:153], v[152:153], v[0:1] op_sel_hi:[1,0]
	v_pk_mul_f32 v[190:191], v[190:191], v[192:193]
	v_pk_mul_f32 v[192:193], v[156:157], v[156:157]
	v_pk_mul_f32 v[190:191], v[202:203], v[190:191]
	v_pk_mul_f32 v[192:193], v[192:193], s[76:77] op_sel_hi:[1,0]
	v_pk_mul_f32 v[202:203], v[178:179], v[190:191]
	v_pk_fma_f32 v[190:191], v[178:179], v[190:191], v[178:179] neg_lo:[1,0,0] neg_hi:[1,0,0]
	v_exp_f32_e32 v192, v192
	v_cndmask_b32_e32 v178, v190, v202, vcc
	v_cmp_gt_f32_e32 vcc, 0, v179
	v_and_b32_e32 v190, 0x7fffffff, v156
	v_exp_f32_e32 v193, v193
	v_cndmask_b32_e32 v179, v191, v203, vcc
	v_and_b32_e32 v191, 0x7fffffff, v157
	v_pk_fma_f32 v[190:191], v[190:191], s[64:65], 1.0 op_sel_hi:[1,0,0]
	v_cmp_gt_f32_e32 vcc, 0, v156
	v_rcp_f32_e32 v190, v190
	v_rcp_f32_e32 v191, v191
	v_pk_mul_f32 v[142:143], v[142:143], v[0:1] op_sel_hi:[1,0]
	v_pk_mul_f32 v[144:145], v[144:145], v[0:1] op_sel_hi:[1,0]
	v_pk_mul_f32 v[140:141], v[140:141], v[0:1] op_sel_hi:[1,0]
	v_pk_fma_f32 v[202:203], v[190:191], s[66:67], v[150:151] op_sel_hi:[1,0,0]
	s_nop 0
	v_pk_fma_f32 v[202:203], v[190:191], v[202:203], s[70:71] op_sel_hi:[1,1,0]
	s_nop 0
	v_pk_fma_f32 v[202:203], v[190:191], v[202:203], s[72:73] op_sel_hi:[1,1,0]
	s_nop 0
	v_pk_fma_f32 v[202:203], v[190:191], v[202:203], s[74:75] op_sel_hi:[1,1,0]
	s_nop 0
	v_pk_mul_f32 v[190:191], v[190:191], v[202:203]
	v_pk_mul_f32 v[202:203], v[154:155], v[154:155]
	v_pk_mul_f32 v[190:191], v[192:193], v[190:191]
	v_pk_mul_f32 v[202:203], v[202:203], s[76:77] op_sel_hi:[1,0]
	v_pk_mul_f32 v[192:193], v[156:157], v[190:191]
	v_pk_fma_f32 v[190:191], v[156:157], v[190:191], v[156:157] neg_lo:[1,0,0] neg_hi:[1,0,0]
	v_and_b32_e32 v156, 0x7fffffff, v154
	v_cndmask_b32_e32 v189, v190, v192, vcc
	v_cmp_gt_f32_e32 vcc, 0, v157
	v_and_b32_e32 v157, 0x7fffffff, v155
	v_pk_fma_f32 v[156:157], v[156:157], s[64:65], 1.0 op_sel_hi:[1,0,0]
	v_cndmask_b32_e32 v190, v191, v193, vcc
	v_rcp_f32_e32 v156, v156
	v_rcp_f32_e32 v157, v157
	v_exp_f32_e32 v202, v202
	v_exp_f32_e32 v203, v203
	v_cmp_gt_f32_e32 vcc, 0, v154
	v_pk_fma_f32 v[192:193], v[156:157], s[66:67], v[150:151] op_sel_hi:[1,0,0]
	s_nop 0
	v_pk_fma_f32 v[192:193], v[156:157], v[192:193], s[70:71] op_sel_hi:[1,1,0]
	s_nop 0
	v_pk_fma_f32 v[192:193], v[156:157], v[192:193], s[72:73] op_sel_hi:[1,1,0]
	s_nop 0
	v_pk_fma_f32 v[192:193], v[156:157], v[192:193], s[74:75] op_sel_hi:[1,1,0]
	s_nop 0
	v_pk_mul_f32 v[192:193], v[156:157], v[192:193]
	v_pk_mul_f32 v[156:157], v[152:153], v[152:153]
	v_pk_mul_f32 v[192:193], v[202:203], v[192:193]
	v_pk_mul_f32 v[156:157], v[156:157], s[76:77] op_sel_hi:[1,0]
	v_pk_mul_f32 v[202:203], v[154:155], v[192:193]
	v_pk_fma_f32 v[192:193], v[154:155], v[192:193], v[154:155] neg_lo:[1,0,0] neg_hi:[1,0,0]
	v_exp_f32_e32 v156, v156
	v_cndmask_b32_e32 v154, v192, v202, vcc
; __device__ __forceinline__ unsigned cvt_pk_bf16(float lo, float hi) { unsigned r; asm volatile("v_cvt_pk_bf16_f32 %0, %1, %2" : "=v"(r) : "v"(lo), "v"(hi)); return r; }
; __device__ __forceinline__ f32x2 gelu_pk(f32x2 v) {
;     const f32x2 av = __builtin_elementwise_abs(v), d = av * 0.2316418882f + 1.0f;
;     f32x2 t; t.x = __builtin_amdgcn_rcpf(d.x); t.y = __builtin_amdgcn_rcpf(d.y);
;     f32x2 q = t * 0.5307027145f + (-0.7265760135f); q = q * t + 0.7107068705f; q = q * t + (-0.142248368f); q = q * t + 0.127414796f; q = q * t;
;     const f32x2 s = (v * v) * (-0.72134752044f);
;     f32x2 e; e.x = __builtin_amdgcn_exp2f(s.x); e.y = __builtin_amdgcn_exp2f(s.y);
;     const f32x2 m = v * (q * e), r = v - m;
;     f32x2 o; o.x = v.x < 0.f ? m.x : r.x; o.y = v.y < 0.f ? m.y : r.y; return o;
; }
;     __device__ __forceinline__ void operator()(const f32x4 (&acc)[2][2][4][2], const Unit& u, int wr, int wc, int fr, int fq) const {
;     ...
;                 for (int bj = 0; bj < 2; ++bj) { f32x4 v0 = acc[ai][bj][m][0] * rs, v1 = acc[ai][bj][m][1] * rs;
;                     const f32x2 a = gelu_pk((f32x2){v0[0], v0[1]}), b = gelu_pk((f32x2){v0[2], v0[3]}), c = gelu_pk((f32x2){v1[0], v1[1]}), d = gelu_pk((f32x2){v1[2], v1[3]});
;                     s1 += ((a.x + a.y) + (b.x + b.y)) + ((c.x + c.y) + (d.x + d.y));
;                     s2 += ((a.x * a.x + a.y * a.y) + (b.x * b.x + b.y * b.y)) + ((c.x * c.x + c.y * c.y) + (d.x * d.x + d.y * d.y));
;                     u32x4 w; w.x = cvt_pk_bf16(a.x, a.y); w.y = cvt_pk_bf16(b.x, b.y); w.z = cvt_pk_bf16(c.x, c.y); w.w = cvt_pk_bf16(d.x, d.y);
;                     *(u32x4*)(rowp + bj * HALF) = w; }
	v_cmp_gt_f32_e32 vcc, 0, v155
	v_and_b32_e32 v192, 0x7fffffff, v152
	v_exp_f32_e32 v157, v157
	v_cndmask_b32_e32 v155, v193, v203, vcc
	v_and_b32_e32 v193, 0x7fffffff, v153
	v_pk_fma_f32 v[192:193], v[192:193], s[64:65], 1.0 op_sel_hi:[1,0,0]
	v_cmp_gt_f32_e32 vcc, 0, v152
	v_rcp_f32_e32 v192, v192
	v_rcp_f32_e32 v193, v193
	s_nop 0
	v_pk_fma_f32 v[202:203], v[192:193], s[66:67], v[150:151] op_sel_hi:[1,0,0]
	s_nop 0
	v_pk_fma_f32 v[202:203], v[192:193], v[202:203], s[70:71] op_sel_hi:[1,1,0]
	s_nop 0
	v_pk_fma_f32 v[202:203], v[192:193], v[202:203], s[72:73] op_sel_hi:[1,1,0]
	s_nop 0
	v_pk_fma_f32 v[202:203], v[192:193], v[202:203], s[74:75] op_sel_hi:[1,1,0]
	s_nop 0
	v_pk_mul_f32 v[192:193], v[192:193], v[202:203]
	v_cvt_pk_bf16_f32 v202, v178, v179
	v_cvt_pk_bf16_f32 v203, v189, v190
	v_cvt_pk_bf16_f32 v204, v154, v155
	s_nop 0
	v_pk_mul_f32 v[156:157], v[156:157], v[192:193]
	s_nop 0
	v_pk_mul_f32 v[192:193], v[152:153], v[156:157]
	v_pk_fma_f32 v[156:157], v[152:153], v[156:157], v[152:153] neg_lo:[1,0,0] neg_hi:[1,0,0]
	s_nop 0
	v_cndmask_b32_e32 v152, v156, v192, vcc
	v_cmp_gt_f32_e32 vcc, 0, v153
	s_nop 1
	v_cndmask_b32_e32 v153, v157, v193, vcc
	v_pk_mul_f32 v[156:157], v[138:139], v[0:1] op_sel_hi:[1,0]
	v_and_b32_e32 v139, 0x7fffffff, v143
	v_and_b32_e32 v138, 0x7fffffff, v142
	v_pk_fma_f32 v[138:139], v[138:139], s[64:65], 1.0 op_sel_hi:[1,0,0]
	v_cvt_pk_bf16_f32 v205, v152, v153
	global_store_dwordx4 v[176:177], v[202:205], off
	v_rcp_f32_e32 v138, v138
	v_rcp_f32_e32 v139, v139
	v_pk_mul_f32 v[202:203], v[142:143], v[142:143]
	v_cmp_gt_f32_e32 vcc, 0, v142
	v_pk_mul_f32 v[202:203], v[202:203], s[76:77] op_sel_hi:[1,0]
	v_pk_fma_f32 v[192:193], v[138:139], s[66:67], v[150:151] op_sel_hi:[1,0,0]
	v_exp_f32_e32 v202, v202
	v_pk_fma_f32 v[192:193], v[138:139], v[192:193], s[70:71] op_sel_hi:[1,1,0]
	v_exp_f32_e32 v203, v203
	v_pk_fma_f32 v[192:193], v[138:139], v[192:193], s[72:73] op_sel_hi:[1,1,0]
	s_nop 0
	v_pk_fma_f32 v[192:193], v[138:139], v[192:193], s[74:75] op_sel_hi:[1,1,0]
	s_nop 0
	v_pk_mul_f32 v[138:139], v[138:139], v[192:193]
	v_pk_mul_f32 v[192:193], v[144:145], v[144:145]
	v_pk_mul_f32 v[138:139], v[202:203], v[138:139]
	v_pk_mul_f32 v[192:193], v[192:193], s[76:77] op_sel_hi:[1,0]
	v_pk_mul_f32 v[202:203], v[142:143], v[138:139]
	v_pk_fma_f32 v[138:139], v[142:143], v[138:139], v[142:143] neg_lo:[1,0,0] neg_hi:[1,0,0]
	v_and_b32_e32 v142, 0x7fffffff, v144
	v_cndmask_b32_e32 v0, v138, v202, vcc
	v_cmp_gt_f32_e32 vcc, 0, v143
	v_and_b32_e32 v143, 0x7fffffff, v145
	v_pk_fma_f32 v[142:143], v[142:143], s[64:65], 1.0 op_sel_hi:[1,0,0]
	v_cndmask_b32_e32 v138, v139, v203, vcc
	v_rcp_f32_e32 v142, v142
	v_rcp_f32_e32 v143, v143
	v_exp_f32_e32 v192, v192
	v_exp_f32_e32 v193, v193
	v_cmp_gt_f32_e32 vcc, 0, v144
	v_pk_fma_f32 v[202:203], v[142:143], s[66:67], v[150:151] op_sel_hi:[1,0,0]
	s_nop 0
	v_pk_fma_f32 v[202:203], v[142:143], v[202:203], s[70:71] op_sel_hi:[1,1,0]
	s_nop 0
	v_pk_fma_f32 v[202:203], v[142:143], v[202:203], s[72:73] op_sel_hi:[1,1,0]
	s_nop 0
	v_pk_fma_f32 v[202:203], v[142:143], v[202:203], s[74:75] op_sel_hi:[1,1,0]
	s_nop 0
	v_pk_mul_f32 v[142:143], v[142:143], v[202:203]
	v_pk_mul_f32 v[202:203], v[156:157], v[156:157]
	v_pk_mul_f32 v[142:143], v[192:193], v[142:143]
	v_pk_mul_f32 v[202:203], v[202:203], s[76:77] op_sel_hi:[1,0]
	v_pk_mul_f32 v[192:193], v[144:145], v[142:143]
	v_pk_fma_f32 v[142:143], v[144:145], v[142:143], v[144:145] neg_lo:[1,0,0] neg_hi:[1,0,0]
	v_and_b32_e32 v144, 0x7fffffff, v156
	v_cndmask_b32_e32 v139, v142, v192, vcc
	v_cmp_gt_f32_e32 vcc, 0, v145
	v_and_b32_e32 v145, 0x7fffffff, v157
	v_pk_fma_f32 v[144:145], v[144:145], s[64:65], 1.0 op_sel_hi:[1,0,0]
	v_cndmask_b32_e32 v142, v143, v193, vcc
	v_rcp_f32_e32 v144, v144
	v_rcp_f32_e32 v145, v145
	v_exp_f32_e32 v202, v202
	v_exp_f32_e32 v203, v203
	v_cmp_gt_f32_e32 vcc, 0, v156
	v_pk_fma_f32 v[192:193], v[144:145], s[66:67], v[150:151] op_sel_hi:[1,0,0]
	s_nop 0
	v_pk_fma_f32 v[192:193], v[144:145], v[192:193], s[70:71] op_sel_hi:[1,1,0]
	s_nop 0
	v_pk_fma_f32 v[192:193], v[144:145], v[192:193], s[72:73] op_sel_hi:[1,1,0]
	s_nop 0
	v_pk_fma_f32 v[192:193], v[144:145], v[192:193], s[74:75] op_sel_hi:[1,1,0]
	s_nop 0
	v_pk_mul_f32 v[144:145], v[144:145], v[192:193]
	v_pk_mul_f32 v[192:193], v[140:141], v[140:141]
	v_pk_mul_f32 v[144:145], v[202:203], v[144:145]
	s_nop 0
	v_pk_mul_f32 v[202:203], v[156:157], v[144:145]
	v_pk_fma_f32 v[144:145], v[156:157], v[144:145], v[156:157] neg_lo:[1,0,0] neg_hi:[1,0,0]
	v_and_b32_e32 v156, 0x7fffffff, v140
	v_cndmask_b32_e32 v143, v144, v202, vcc
	v_cmp_gt_f32_e32 vcc, 0, v157
	v_and_b32_e32 v157, 0x7fffffff, v141
	v_pk_fma_f32 v[156:157], v[156:157], s[64:65], 1.0 op_sel_hi:[1,0,0]
	v_cndmask_b32_e32 v144, v145, v203, vcc
	v_rcp_f32_e32 v156, v156
	v_rcp_f32_e32 v157, v157
	v_cmp_gt_f32_e32 vcc, 0, v140
	v_cvt_pk_bf16_f32 v202, v0, v138
	v_cvt_pk_bf16_f32 v203, v139, v142
	v_pk_fma_f32 v[150:151], v[156:157], s[66:67], v[150:151] op_sel_hi:[1,0,0]
	v_cvt_pk_bf16_f32 v204, v143, v144
	s_nop 0
	v_pk_fma_f32 v[150:151], v[156:157], v[150:151], s[70:71] op_sel_hi:[1,1,0]
	s_nop 0
	v_pk_fma_f32 v[150:151], v[156:157], v[150:151], s[72:73] op_sel_hi:[1,1,0]
	s_nop 0
	v_pk_fma_f32 v[150:151], v[156:157], v[150:151], s[74:75] op_sel_hi:[1,1,0]
	s_nop 0
	v_pk_mul_f32 v[150:151], v[156:157], v[150:151]
	v_pk_mul_f32 v[156:157], v[192:193], s[76:77] op_sel_hi:[1,0]
	s_nop 0
	v_exp_f32_e32 v156, v156
	v_exp_f32_e32 v157, v157
	s_nop 0
	v_pk_mul_f32 v[150:151], v[156:157], v[150:151]
	s_nop 0
	v_pk_mul_f32 v[156:157], v[140:141], v[150:151]
	v_pk_fma_f32 v[150:151], v[140:141], v[150:151], v[140:141] neg_lo:[1,0,0] neg_hi:[1,0,0]
	s_nop 0
	v_cndmask_b32_e32 v140, v150, v156, vcc
	v_cmp_gt_f32_e32 vcc, 0, v141
	s_nop 1
	v_cndmask_b32_e32 v141, v151, v157, vcc
	v_cvt_pk_bf16_f32 v205, v140, v141
	global_store_dwordx4 v[176:177], v[202:205], off offset:256
	s_cbranch_scc1 .LBB0_356
; __device__ __forceinline__ unsigned cvt_pk_bf16(float lo, float hi) { unsigned r; asm volatile("v_cvt_pk_bf16_f32 %0, %1, %2" : "=v"(r) : "v"(lo), "v"(hi)); return r; }
;     __device__ __forceinline__ void operator()(const f32x4 (&acc)[2][2][4][2], const Unit& u, int wr, int wc, int fr, int fq) const {
;     ...
;                     s1 += ((a.x + a.y) + (b.x + b.y)) + ((c.x + c.y) + (d.x + d.y));
;                     s2 += ((a.x * a.x + a.y * a.y) + (b.x * b.x + b.y * b.y)) + ((c.x * c.x + c.y * c.y) + (d.x * d.x + d.y * d.y));
;                     u32x4 w; w.x = cvt_pk_bf16(a.x, a.y); w.y = cvt_pk_bf16(b.x, b.y); w.z = cvt_pk_bf16(c.x, c.y); w.w = cvt_pk_bf16(d.x, d.y);
;                     *(u32x4*)(rowp + bj * HALF) = w; }
;                 if (isv) { s1 += __shfl_xor(s1, 16); s1 += __shfl_xor(s1, 32); s2 += __shfl_xor(s2, 16); s2 += __shfl_xor(s2, 32);
;                     if (fq == 0) { const int rl = ai * HALF + wr * 64 + m * 16 + fr; part[rl * 4 + wc] = s1; part[1024 + rl * 4 + wc] = s2; } } }
	v_mul_f32_e32 v145, v179, v179
	v_mul_f32_e32 v150, v190, v190
	v_fmac_f32_e32 v145, v178, v178
	v_fmac_f32_e32 v150, v189, v189
	v_add_f32_e32 v145, v145, v150
	v_mul_f32_e32 v150, v155, v155
	v_mul_f32_e32 v151, v153, v153
	v_fmac_f32_e32 v150, v154, v154
	v_fmac_f32_e32 v151, v152, v152
	v_add_f32_e32 v150, v150, v151
	v_add_f32_e32 v145, v145, v150
	v_mul_f32_e32 v150, v138, v138
	v_fmac_f32_e32 v150, v0, v0
	v_mul_f32_e32 v151, v142, v142
	v_add_f32_e32 v0, v0, v138
	v_add_f32_e32 v138, v139, v142
	v_fmac_f32_e32 v151, v139, v139
	v_add_f32_e32 v0, v0, v138
	v_add_f32_e32 v138, v143, v144
	v_add_f32_e32 v139, v140, v141
	v_add_f32_e32 v157, v178, v179
	v_add_f32_e32 v176, v189, v190
	v_add_f32_e32 v154, v154, v155
	v_add_f32_e32 v152, v152, v153
	v_add_f32_e32 v138, v138, v139
	v_and_b32_e32 v139, 64, v226
	v_add_f32_e32 v157, v157, v176
	v_add_f32_e32 v152, v154, v152
	v_add_f32_e32 v0, v0, v138
	v_xor_b32_e32 v138, 16, v226
	v_add_u32_e32 v139, 64, v139
	v_add_f32_e32 v152, v157, v152
	v_cmp_lt_i32_e32 vcc, v138, v139
	v_add_f32_e32 v150, v150, v151
	v_mul_f32_e32 v151, v144, v144
	v_mul_f32_e32 v156, v141, v141
	v_add_f32_e32 v152, 0, v152
	v_cndmask_b32_e32 v138, v226, v138, vcc
	v_fmac_f32_e32 v151, v143, v143
	v_add_f32_e32 v0, v0, v152
	v_lshlrev_b32_e32 v138, 2, v138
	v_fmac_f32_e32 v156, v140, v140
	ds_bpermute_b32 v141, v138, v0
	v_add_f32_e32 v140, v151, v156
	v_add_f32_e32 v140, v150, v140
	v_add_f32_e32 v140, v145, v140
	ds_bpermute_b32 v142, v138, v140
	s_waitcnt lgkmcnt(0)
	v_add_f32_e32 v0, v0, v141
	v_xor_b32_e32 v141, 32, v226
	v_cmp_lt_i32_e32 vcc, v141, v139
	v_add_f32_e32 v139, v140, v142
	s_nop 0
	v_cndmask_b32_e32 v138, v226, v141, vcc
	v_lshlrev_b32_e32 v141, 2, v138
	ds_bpermute_b32 v138, v141, v0
	ds_bpermute_b32 v140, v141, v139
	s_and_saveexec_b64 s[4:5], s[6:7]
	s_cbranch_execz .LBB0_355
	s_waitcnt lgkmcnt(0)
	v_add_f32_e32 v139, v139, v140
	v_add_f32_e32 v0, v0, v138
	ds_write2st64_b32 v186, v0, v139 offset1:16

; __device__ __forceinline__ unsigned cvt_pk_bf16(float lo, float hi) { unsigned r; asm volatile("v_cvt_pk_bf16_f32 %0, %1, %2" : "=v"(r) : "v"(lo), "v"(hi)); return r; }
; __device__ __forceinline__ f32x2 gelu_pk(f32x2 v) {
;     const f32x2 av = __builtin_elementwise_abs(v), d = av * 0.2316418882f + 1.0f;
;     f32x2 t; t.x = __builtin_amdgcn_rcpf(d.x); t.y = __builtin_amdgcn_rcpf(d.y);
;     f32x2 q = t * 0.5307027145f + (-0.7265760135f); q = q * t + 0.7107068705f; q = q * t + (-0.142248368f); q = q * t + 0.127414796f; q = q * t;
;     const f32x2 s = (v * v) * (-0.72134752044f);
;     f32x2 e; e.x = __builtin_amdgcn_exp2f(s.x); e.y = __builtin_amdgcn_exp2f(s.y);
;     const f32x2 m = v * (q * e), r = v - m;
;     f32x2 o; o.x = v.x < 0.f ? m.x : r.x; o.y = v.y < 0.f ? m.y : r.y; return o;
; }
;     __device__ __forceinline__ void operator()(const f32x4 (&acc)[2][2][4][2], const Unit& u, int wr, int wc, int fr, int fq) const {
;     ...
;             for (int m = 0; m < 4; ++m) { const int row = row0 + ai * HALF + m * 16; const float rs = rsv[ai][m]; bf16_t* rowp = O + (size_t)row * ldc + col0; float s1 = 0.f, s2 = 0.f;
; #pragma unroll
;                 for (int bj = 0; bj < 2; ++bj) { f32x4 v0 = acc[ai][bj][m][0] * rs, v1 = acc[ai][bj][m][1] * rs;
;                     const f32x2 a = gelu_pk((f32x2){v0[0], v0[1]}), b = gelu_pk((f32x2){v0[2], v0[3]}), c = gelu_pk((f32x2){v1[0], v1[1]}), d = gelu_pk((f32x2){v1[2], v1[3]});
;                     s1 += ((a.x + a.y) + (b.x + b.y)) + ((c.x + c.y) + (d.x + d.y));
;                     s2 += ((a.x * a.x + a.y * a.y) + (b.x * b.x + b.y * b.y)) + ((c.x * c.x + c.y * c.y) + (d.x * d.x + d.y * d.y));
;                     u32x4 w; w.x = cvt_pk_bf16(a.x, a.y); w.y = cvt_pk_bf16(b.x, b.y); w.z = cvt_pk_bf16(c.x, c.y); w.w = cvt_pk_bf16(d.x, d.y);
;                     *(u32x4*)(rowp + bj * HALF) = w; }
;                 if (isv) { s1 += __shfl_xor(s1, 16); s1 += __shfl_xor(s1, 32); s2 += __shfl_xor(s2, 16); s2 += __shfl_xor(s2, 32);
;                     if (fq == 0) { const int rl = ai * HALF + wr * 64 + m * 16 + fr; part[rl * 4 + wc] = s1; part[1024 + rl * 4 + wc] = s2; } } }
.LBB0_356:
	v_add_f32_e32 v0, v146, v147
	s_waitcnt lgkmcnt(0)
	v_add_f32_e32 v138, v148, v149
	v_add_f32_e32 v0, v0, v138
	v_fmamk_f32 v0, v0, 0x3a800000, v224
	v_rsq_f32_e32 v0, v0
	s_mov_b32 s4, 0xbf3a00e3
	v_lshlrev_b64 v[138:139], 12, v[174:175]
	v_lshl_add_u64 v[138:139], s[20:21], 0, v[138:139]
	v_pk_mul_f32 v[134:135], v[134:135], v[0:1] op_sel_hi:[1,0]
	v_pk_mul_f32 v[140:141], v[130:131], v[0:1] op_sel_hi:[1,0]
	v_and_b32_e32 v131, 0x7fffffff, v135
	v_and_b32_e32 v130, 0x7fffffff, v134
	v_pk_fma_f32 v[130:131], v[130:131], s[64:65], 1.0 op_sel_hi:[1,0,0]
	v_pk_mul_f32 v[146:147], v[134:135], v[134:135]
	v_rcp_f32_e32 v142, v130
	v_rcp_f32_e32 v143, v131
	v_mov_b64_e32 v[130:131], s[4:5]
	v_pk_mul_f32 v[146:147], v[146:147], s[76:77] op_sel_hi:[1,0]
	v_cmp_gt_f32_e32 vcc, 0, v134
	v_pk_fma_f32 v[144:145], v[142:143], s[66:67], v[130:131] op_sel_hi:[1,0,0]
	v_exp_f32_e32 v146, v146
	v_pk_fma_f32 v[144:145], v[142:143], v[144:145], s[70:71] op_sel_hi:[1,1,0]
	v_exp_f32_e32 v147, v147
	v_pk_fma_f32 v[144:145], v[142:143], v[144:145], s[72:73] op_sel_hi:[1,1,0]
	v_pk_mul_f32 v[136:137], v[136:137], v[0:1] op_sel_hi:[1,0]
	v_pk_fma_f32 v[144:145], v[142:143], v[144:145], s[74:75] op_sel_hi:[1,1,0]
	v_pk_mul_f32 v[132:133], v[132:133], v[0:1] op_sel_hi:[1,0]
	v_pk_mul_f32 v[142:143], v[142:143], v[144:145]
	v_pk_mul_f32 v[144:145], v[136:137], v[136:137]
	v_pk_mul_f32 v[142:143], v[146:147], v[142:143]
	v_pk_mul_f32 v[144:145], v[144:145], s[76:77] op_sel_hi:[1,0]
	v_pk_mul_f32 v[146:147], v[134:135], v[142:143]
	v_pk_fma_f32 v[142:143], v[134:135], v[142:143], v[134:135] neg_lo:[1,0,0] neg_hi:[1,0,0]
	v_exp_f32_e32 v144, v144
	v_cndmask_b32_e32 v134, v142, v146, vcc
	v_cmp_gt_f32_e32 vcc, 0, v135
	v_and_b32_e32 v142, 0x7fffffff, v136
	v_exp_f32_e32 v145, v145
	v_cndmask_b32_e32 v135, v143, v147, vcc
	v_and_b32_e32 v143, 0x7fffffff, v137
	v_pk_fma_f32 v[142:143], v[142:143], s[64:65], 1.0 op_sel_hi:[1,0,0]
	v_cmp_gt_f32_e32 vcc, 0, v136
	v_rcp_f32_e32 v142, v142
	v_rcp_f32_e32 v143, v143
	v_lshl_add_u64 v[138:139], v[160:161], 1, v[138:139]
	v_pk_mul_f32 v[122:123], v[122:123], v[0:1] op_sel_hi:[1,0]
	v_pk_mul_f32 v[124:125], v[124:125], v[0:1] op_sel_hi:[1,0]
	v_pk_fma_f32 v[146:147], v[142:143], s[66:67], v[130:131] op_sel_hi:[1,0,0]
	v_pk_mul_f32 v[120:121], v[120:121], v[0:1] op_sel_hi:[1,0]
	v_pk_fma_f32 v[146:147], v[142:143], v[146:147], s[70:71] op_sel_hi:[1,1,0]
	s_nop 0
	v_pk_fma_f32 v[146:147], v[142:143], v[146:147], s[72:73] op_sel_hi:[1,1,0]
	s_nop 0
	v_pk_fma_f32 v[146:147], v[142:143], v[146:147], s[74:75] op_sel_hi:[1,1,0]
	s_nop 0
	v_pk_mul_f32 v[142:143], v[142:143], v[146:147]
	v_pk_mul_f32 v[146:147], v[140:141], v[140:141]
	v_pk_mul_f32 v[142:143], v[144:145], v[142:143]
	v_pk_mul_f32 v[146:147], v[146:147], s[76:77] op_sel_hi:[1,0]
	v_pk_mul_f32 v[144:145], v[136:137], v[142:143]
	v_pk_fma_f32 v[142:143], v[136:137], v[142:143], v[136:137] neg_lo:[1,0,0] neg_hi:[1,0,0]
	v_exp_f32_e32 v146, v146
	v_cndmask_b32_e32 v136, v142, v144, vcc
	v_cmp_gt_f32_e32 vcc, 0, v137
	v_and_b32_e32 v142, 0x7fffffff, v140
	v_exp_f32_e32 v147, v147
	v_cndmask_b32_e32 v137, v143, v145, vcc
	v_and_b32_e32 v143, 0x7fffffff, v141
	v_pk_fma_f32 v[142:143], v[142:143], s[64:65], 1.0 op_sel_hi:[1,0,0]
	v_cmp_gt_f32_e32 vcc, 0, v140
	v_rcp_f32_e32 v142, v142
	v_rcp_f32_e32 v143, v143
	s_nop 0
	v_pk_fma_f32 v[144:145], v[142:143], s[66:67], v[130:131] op_sel_hi:[1,0,0]
	s_nop 0
	v_pk_fma_f32 v[144:145], v[142:143], v[144:145], s[70:71] op_sel_hi:[1,1,0]
	s_nop 0
	v_pk_fma_f32 v[144:145], v[142:143], v[144:145], s[72:73] op_sel_hi:[1,1,0]
	s_nop 0
	v_pk_fma_f32 v[144:145], v[142:143], v[144:145], s[74:75] op_sel_hi:[1,1,0]
	s_nop 0
	v_pk_mul_f32 v[142:143], v[142:143], v[144:145]
	v_pk_mul_f32 v[144:145], v[132:133], v[132:133]
	v_pk_mul_f32 v[142:143], v[146:147], v[142:143]
	v_pk_mul_f32 v[144:145], v[144:145], s[76:77] op_sel_hi:[1,0]
	v_pk_mul_f32 v[146:147], v[140:141], v[142:143]
	v_pk_fma_f32 v[142:143], v[140:141], v[142:143], v[140:141] neg_lo:[1,0,0] neg_hi:[1,0,0]
	v_exp_f32_e32 v144, v144
	v_cndmask_b32_e32 v140, v142, v146, vcc
	v_cmp_gt_f32_e32 vcc, 0, v141
	v_and_b32_e32 v142, 0x7fffffff, v132
	v_exp_f32_e32 v145, v145
	v_cndmask_b32_e32 v141, v143, v147, vcc
	v_and_b32_e32 v143, 0x7fffffff, v133
	v_pk_fma_f32 v[142:143], v[142:143], s[64:65], 1.0 op_sel_hi:[1,0,0]
	v_cmp_gt_f32_e32 vcc, 0, v132
	v_rcp_f32_e32 v142, v142
	v_rcp_f32_e32 v143, v143
	s_nop 0
	v_pk_fma_f32 v[146:147], v[142:143], s[66:67], v[130:131] op_sel_hi:[1,0,0]
	s_nop 0
	v_pk_fma_f32 v[146:147], v[142:143], v[146:147], s[70:71] op_sel_hi:[1,1,0]
	s_nop 0
	v_pk_fma_f32 v[146:147], v[142:143], v[146:147], s[72:73] op_sel_hi:[1,1,0]
	s_nop 0
	v_pk_fma_f32 v[146:147], v[142:143], v[146:147], s[74:75] op_sel_hi:[1,1,0]
	s_nop 0
	v_pk_mul_f32 v[142:143], v[142:143], v[146:147]
	v_pk_mul_f32 v[146:147], v[122:123], v[122:123]
	v_pk_mul_f32 v[142:143], v[144:145], v[142:143]
	v_pk_mul_f32 v[146:147], v[146:147], s[76:77] op_sel_hi:[1,0]
	v_pk_mul_f32 v[144:145], v[132:133], v[142:143]
	v_pk_fma_f32 v[142:143], v[132:133], v[142:143], v[132:133] neg_lo:[1,0,0] neg_hi:[1,0,0]
	v_exp_f32_e32 v146, v146
	v_cndmask_b32_e32 v132, v142, v144, vcc
	v_cmp_gt_f32_e32 vcc, 0, v133
	v_cvt_pk_bf16_f32 v142, v134, v135
	v_exp_f32_e32 v147, v147
	s_nop 0
	v_cndmask_b32_e32 v133, v143, v145, vcc
	v_cvt_pk_bf16_f32 v143, v136, v137
	v_cvt_pk_bf16_f32 v144, v140, v141
	v_cvt_pk_bf16_f32 v145, v132, v133
	global_store_dwordx4 v[138:139], v[142:145], off
	v_cmp_gt_f32_e32 vcc, 0, v122
	s_nop 0
	v_pk_mul_f32 v[142:143], v[118:119], v[0:1] op_sel_hi:[1,0]
	v_and_b32_e32 v119, 0x7fffffff, v123
; __device__ __forceinline__ unsigned cvt_pk_bf16(float lo, float hi) { unsigned r; asm volatile("v_cvt_pk_bf16_f32 %0, %1, %2" : "=v"(r) : "v"(lo), "v"(hi)); return r; }
; __device__ __forceinline__ f32x2 gelu_pk(f32x2 v) {
;     const f32x2 av = __builtin_elementwise_abs(v), d = av * 0.2316418882f + 1.0f;
;     f32x2 t; t.x = __builtin_amdgcn_rcpf(d.x); t.y = __builtin_amdgcn_rcpf(d.y);
;     f32x2 q = t * 0.5307027145f + (-0.7265760135f); q = q * t + 0.7107068705f; q = q * t + (-0.142248368f); q = q * t + 0.127414796f; q = q * t;
;     const f32x2 s = (v * v) * (-0.72134752044f);
;     f32x2 e; e.x = __builtin_amdgcn_exp2f(s.x); e.y = __builtin_amdgcn_exp2f(s.y);
;     const f32x2 m = v * (q * e), r = v - m;
;     f32x2 o; o.x = v.x < 0.f ? m.x : r.x; o.y = v.y < 0.f ? m.y : r.y; return o;
; }
;     __device__ __forceinline__ void operator()(const f32x4 (&acc)[2][2][4][2], const Unit& u, int wr, int wc, int fr, int fq) const {
;     ...
;             for (int m = 0; m < 4; ++m) { const int row = row0 + ai * HALF + m * 16; const float rs = rsv[ai][m]; bf16_t* rowp = O + (size_t)row * ldc + col0; float s1 = 0.f, s2 = 0.f;
; #pragma unroll
;                 for (int bj = 0; bj < 2; ++bj) { f32x4 v0 = acc[ai][bj][m][0] * rs, v1 = acc[ai][bj][m][1] * rs;
;                     const f32x2 a = gelu_pk((f32x2){v0[0], v0[1]}), b = gelu_pk((f32x2){v0[2], v0[3]}), c = gelu_pk((f32x2){v1[0], v1[1]}), d = gelu_pk((f32x2){v1[2], v1[3]});
;                     s1 += ((a.x + a.y) + (b.x + b.y)) + ((c.x + c.y) + (d.x + d.y));
;                     s2 += ((a.x * a.x + a.y * a.y) + (b.x * b.x + b.y * b.y)) + ((c.x * c.x + c.y * c.y) + (d.x * d.x + d.y * d.y));
;                     u32x4 w; w.x = cvt_pk_bf16(a.x, a.y); w.y = cvt_pk_bf16(b.x, b.y); w.z = cvt_pk_bf16(c.x, c.y); w.w = cvt_pk_bf16(d.x, d.y);
;                     *(u32x4*)(rowp + bj * HALF) = w; }
;                 if (isv) { s1 += __shfl_xor(s1, 16); s1 += __shfl_xor(s1, 32); s2 += __shfl_xor(s2, 16); s2 += __shfl_xor(s2, 32);
;                     if (fq == 0) { const int rl = ai * HALF + wr * 64 + m * 16 + fr; part[rl * 4 + wc] = s1; part[1024 + rl * 4 + wc] = s2; } } }
	v_and_b32_e32 v118, 0x7fffffff, v122
	v_pk_fma_f32 v[118:119], v[118:119], s[64:65], 1.0 op_sel_hi:[1,0,0]
	s_nop 0
	v_rcp_f32_e32 v118, v118
	v_rcp_f32_e32 v119, v119
	s_nop 0
	v_pk_fma_f32 v[144:145], v[118:119], s[66:67], v[130:131] op_sel_hi:[1,0,0]
	s_nop 0
	v_pk_fma_f32 v[144:145], v[118:119], v[144:145], s[70:71] op_sel_hi:[1,1,0]
	s_nop 0
	v_pk_fma_f32 v[144:145], v[118:119], v[144:145], s[72:73] op_sel_hi:[1,1,0]
	s_nop 0
	v_pk_fma_f32 v[144:145], v[118:119], v[144:145], s[74:75] op_sel_hi:[1,1,0]
	s_nop 0
	v_pk_mul_f32 v[118:119], v[118:119], v[144:145]
	v_pk_mul_f32 v[144:145], v[124:125], v[124:125]
	v_pk_mul_f32 v[118:119], v[146:147], v[118:119]
	v_pk_mul_f32 v[144:145], v[144:145], s[76:77] op_sel_hi:[1,0]
	v_pk_mul_f32 v[146:147], v[122:123], v[118:119]
	v_pk_fma_f32 v[118:119], v[122:123], v[118:119], v[122:123] neg_lo:[1,0,0] neg_hi:[1,0,0]
	v_and_b32_e32 v122, 0x7fffffff, v124
	v_cndmask_b32_e32 v0, v118, v146, vcc
	v_cmp_gt_f32_e32 vcc, 0, v123
	v_and_b32_e32 v123, 0x7fffffff, v125
	v_pk_fma_f32 v[122:123], v[122:123], s[64:65], 1.0 op_sel_hi:[1,0,0]
	v_cndmask_b32_e32 v118, v119, v147, vcc
	v_rcp_f32_e32 v122, v122
	v_rcp_f32_e32 v123, v123
	v_exp_f32_e32 v144, v144
	v_exp_f32_e32 v145, v145
	v_cmp_gt_f32_e32 vcc, 0, v124
	v_pk_fma_f32 v[146:147], v[122:123], s[66:67], v[130:131] op_sel_hi:[1,0,0]
	s_nop 0
	v_pk_fma_f32 v[146:147], v[122:123], v[146:147], s[70:71] op_sel_hi:[1,1,0]
	s_nop 0
	v_pk_fma_f32 v[146:147], v[122:123], v[146:147], s[72:73] op_sel_hi:[1,1,0]
	s_nop 0
	v_pk_fma_f32 v[146:147], v[122:123], v[146:147], s[74:75] op_sel_hi:[1,1,0]
	s_nop 0
	v_pk_mul_f32 v[122:123], v[122:123], v[146:147]
	v_pk_mul_f32 v[146:147], v[142:143], v[142:143]
	v_pk_mul_f32 v[122:123], v[144:145], v[122:123]
	v_pk_mul_f32 v[146:147], v[146:147], s[76:77] op_sel_hi:[1,0]
	v_pk_mul_f32 v[144:145], v[124:125], v[122:123]
	v_pk_fma_f32 v[122:123], v[124:125], v[122:123], v[124:125] neg_lo:[1,0,0] neg_hi:[1,0,0]
	v_and_b32_e32 v124, 0x7fffffff, v142
	v_cndmask_b32_e32 v119, v122, v144, vcc
	v_cmp_gt_f32_e32 vcc, 0, v125
	v_and_b32_e32 v125, 0x7fffffff, v143
	v_pk_fma_f32 v[124:125], v[124:125], s[64:65], 1.0 op_sel_hi:[1,0,0]
	v_cndmask_b32_e32 v122, v123, v145, vcc
	v_rcp_f32_e32 v124, v124
	v_rcp_f32_e32 v125, v125
	v_exp_f32_e32 v146, v146
	v_exp_f32_e32 v147, v147
	v_cmp_gt_f32_e32 vcc, 0, v142
	v_pk_fma_f32 v[144:145], v[124:125], s[66:67], v[130:131] op_sel_hi:[1,0,0]
	s_nop 0
	v_pk_fma_f32 v[144:145], v[124:125], v[144:145], s[70:71] op_sel_hi:[1,1,0]
	s_nop 0
	v_pk_fma_f32 v[144:145], v[124:125], v[144:145], s[72:73] op_sel_hi:[1,1,0]
	s_nop 0
	v_pk_fma_f32 v[144:145], v[124:125], v[144:145], s[74:75] op_sel_hi:[1,1,0]
	s_nop 0
	v_pk_mul_f32 v[124:125], v[124:125], v[144:145]
	v_pk_mul_f32 v[144:145], v[120:121], v[120:121]
	v_pk_mul_f32 v[124:125], v[146:147], v[124:125]
	s_nop 0
	v_pk_mul_f32 v[146:147], v[142:143], v[124:125]
	v_pk_fma_f32 v[124:125], v[142:143], v[124:125], v[142:143] neg_lo:[1,0,0] neg_hi:[1,0,0]
	v_and_b32_e32 v142, 0x7fffffff, v120
	v_cndmask_b32_e32 v123, v124, v146, vcc
	v_cmp_gt_f32_e32 vcc, 0, v143
	v_and_b32_e32 v143, 0x7fffffff, v121
	v_pk_fma_f32 v[142:143], v[142:143], s[64:65], 1.0 op_sel_hi:[1,0,0]
	v_cndmask_b32_e32 v124, v125, v147, vcc
	v_rcp_f32_e32 v142, v142
	v_rcp_f32_e32 v143, v143
	v_cmp_gt_f32_e32 vcc, 0, v120
	v_cndmask_b32_e64 v125, 0, 1, s[36:37]
	v_cmp_ne_u32_e64 s[10:11], 1, v125
	v_pk_fma_f32 v[130:131], v[142:143], s[66:67], v[130:131] op_sel_hi:[1,0,0]
	s_nop 0
	v_pk_fma_f32 v[130:131], v[142:143], v[130:131], s[70:71] op_sel_hi:[1,1,0]
	s_nop 0
	v_pk_fma_f32 v[130:131], v[142:143], v[130:131], s[72:73] op_sel_hi:[1,1,0]
	s_nop 0
	v_pk_fma_f32 v[130:131], v[142:143], v[130:131], s[74:75] op_sel_hi:[1,1,0]
	s_nop 0
	v_pk_mul_f32 v[130:131], v[142:143], v[130:131]
	v_pk_mul_f32 v[142:143], v[144:145], s[76:77] op_sel_hi:[1,0]
	s_nop 0
	v_exp_f32_e32 v142, v142
	v_exp_f32_e32 v143, v143
	s_nop 0
	v_pk_mul_f32 v[130:131], v[142:143], v[130:131]
	s_nop 0
	v_pk_mul_f32 v[142:143], v[120:121], v[130:131]
	v_pk_fma_f32 v[130:131], v[120:121], v[130:131], v[120:121] neg_lo:[1,0,0] neg_hi:[1,0,0]
	s_nop 0
	v_cndmask_b32_e32 v120, v130, v142, vcc
	v_cmp_gt_f32_e32 vcc, 0, v121
	v_cvt_pk_bf16_f32 v142, v0, v118
	s_nop 1
	v_cndmask_b32_e32 v121, v131, v143, vcc
	s_andn2_b64 vcc, exec, s[36:37]
	v_cvt_pk_bf16_f32 v143, v119, v122
	v_cvt_pk_bf16_f32 v144, v123, v124
	v_cvt_pk_bf16_f32 v145, v120, v121
	global_store_dwordx4 v[138:139], v[142:145], off offset:256
	s_cbranch_vccnz .LBB0_360
	v_mul_f32_e32 v125, v135, v135
	v_mul_f32_e32 v130, v137, v137
	v_fmac_f32_e32 v125, v134, v134
	v_fmac_f32_e32 v130, v136, v136
	v_add_f32_e32 v125, v125, v130
	v_mul_f32_e32 v130, v141, v141
	v_mul_f32_e32 v131, v133, v133
	v_fmac_f32_e32 v130, v140, v140
	v_fmac_f32_e32 v131, v132, v132
	v_add_f32_e32 v130, v130, v131
	v_add_f32_e32 v125, v125, v130
	v_mul_f32_e32 v130, v118, v118
	v_fmac_f32_e32 v130, v0, v0
	v_mul_f32_e32 v131, v122, v122
	v_add_f32_e32 v0, v0, v118
	v_add_f32_e32 v118, v119, v122
	v_fmac_f32_e32 v131, v119, v119
	v_add_f32_e32 v134, v134, v135
	v_add_f32_e32 v135, v136, v137
	v_add_f32_e32 v0, v0, v118
	v_add_f32_e32 v118, v123, v124
	v_add_f32_e32 v119, v120, v121
	v_add_f32_e32 v134, v134, v135
	v_add_f32_e32 v135, v140, v141
	v_add_f32_e32 v132, v132, v133
	v_add_f32_e32 v118, v118, v119
	v_and_b32_e32 v119, 64, v226
	v_add_f32_e32 v132, v135, v132
	v_add_f32_e32 v0, v0, v118
	v_xor_b32_e32 v118, 16, v226
	v_add_u32_e32 v119, 64, v119
	v_add_f32_e32 v132, v134, v132
	v_cmp_lt_i32_e32 vcc, v118, v119
	v_add_f32_e32 v130, v130, v131
	v_mul_f32_e32 v131, v124, v124
	v_mul_f32_e32 v138, v121, v121
	v_add_f32_e32 v132, 0, v132
	v_cndmask_b32_e32 v118, v226, v118, vcc
	v_fmac_f32_e32 v131, v123, v123
	v_add_f32_e32 v0, v0, v132
	v_lshlrev_b32_e32 v118, 2, v118
	v_fmac_f32_e32 v138, v120, v120
	ds_bpermute_b32 v121, v118, v0
	v_add_f32_e32 v120, v131, v138
	v_add_f32_e32 v120, v130, v120
	v_add_f32_e32 v120, v125, v120
	ds_bpermute_b32 v122, v118, v120
	s_waitcnt lgkmcnt(0)
	v_add_f32_e32 v0, v0, v121
	v_xor_b32_e32 v121, 32, v226
	v_cmp_lt_i32_e32 vcc, v121, v119
	v_add_f32_e32 v119, v120, v122
	s_nop 0
	v_cndmask_b32_e32 v118, v226, v121, vcc
	v_lshlrev_b32_e32 v121, 2, v118
	ds_bpermute_b32 v118, v121, v0
	ds_bpermute_b32 v120, v121, v119
	s_and_saveexec_b64 s[4:5], s[6:7]
	s_cbranch_execz .LBB0_359
	s_waitcnt lgkmcnt(0)
	v_add_f32_e32 v119, v119, v120
	v_add_f32_e32 v0, v0, v118
	ds_write2st64_b32 v186, v0, v119 offset0:1 offset1:17

; __device__ __forceinline__ unsigned cvt_pk_bf16(float lo, float hi) { unsigned r; asm volatile("v_cvt_pk_bf16_f32 %0, %1, %2" : "=v"(r) : "v"(lo), "v"(hi)); return r; }
; __device__ __forceinline__ f32x2 gelu_pk(f32x2 v) {
;     const f32x2 av = __builtin_elementwise_abs(v), d = av * 0.2316418882f + 1.0f;
;     f32x2 t; t.x = __builtin_amdgcn_rcpf(d.x); t.y = __builtin_amdgcn_rcpf(d.y);
;     f32x2 q = t * 0.5307027145f + (-0.7265760135f); q = q * t + 0.7107068705f; q = q * t + (-0.142248368f); q = q * t + 0.127414796f; q = q * t;
;     const f32x2 s = (v * v) * (-0.72134752044f);
;     f32x2 e; e.x = __builtin_amdgcn_exp2f(s.x); e.y = __builtin_amdgcn_exp2f(s.y);
;     const f32x2 m = v * (q * e), r = v - m;
;     f32x2 o; o.x = v.x < 0.f ? m.x : r.x; o.y = v.y < 0.f ? m.y : r.y; return o;
; }
;     __device__ __forceinline__ void operator()(const f32x4 (&acc)[2][2][4][2], const Unit& u, int wr, int wc, int fr, int fq) const {
;     ...
;             for (int m = 0; m < 4; ++m) { const int row = row0 + ai * HALF + m * 16; const float rs = rsv[ai][m]; bf16_t* rowp = O + (size_t)row * ldc + col0; float s1 = 0.f, s2 = 0.f;
; #pragma unroll
;                 for (int bj = 0; bj < 2; ++bj) { f32x4 v0 = acc[ai][bj][m][0] * rs, v1 = acc[ai][bj][m][1] * rs;
;                     const f32x2 a = gelu_pk((f32x2){v0[0], v0[1]}), b = gelu_pk((f32x2){v0[2], v0[3]}), c = gelu_pk((f32x2){v1[0], v1[1]}), d = gelu_pk((f32x2){v1[2], v1[3]});
;                     s1 += ((a.x + a.y) + (b.x + b.y)) + ((c.x + c.y) + (d.x + d.y));
;                     s2 += ((a.x * a.x + a.y * a.y) + (b.x * b.x + b.y * b.y)) + ((c.x * c.x + c.y * c.y) + (d.x * d.x + d.y * d.y));
;                     u32x4 w; w.x = cvt_pk_bf16(a.x, a.y); w.y = cvt_pk_bf16(b.x, b.y); w.z = cvt_pk_bf16(c.x, c.y); w.w = cvt_pk_bf16(d.x, d.y);
;                     *(u32x4*)(rowp + bj * HALF) = w; }
;                 if (isv) { s1 += __shfl_xor(s1, 16); s1 += __shfl_xor(s1, 32); s2 += __shfl_xor(s2, 16); s2 += __shfl_xor(s2, 32);
;                     if (fq == 0) { const int rl = ai * HALF + wr * 64 + m * 16 + fr; part[rl * 4 + wc] = s1; part[1024 + rl * 4 + wc] = s2; } } }
.LBB0_360:
	v_add_f32_e32 v0, v126, v127
	s_waitcnt lgkmcnt(0)
	v_add_f32_e32 v118, v128, v129
	v_add_f32_e32 v0, v0, v118
	v_fmamk_f32 v0, v0, 0x3a800000, v224
	v_rsq_f32_e32 v0, v0
	s_mov_b32 s4, 0xbf3a00e3
	v_lshlrev_b64 v[118:119], 12, v[172:173]
	v_lshl_add_u64 v[118:119], s[20:21], 0, v[118:119]
	v_pk_mul_f32 v[114:115], v[114:115], v[0:1] op_sel_hi:[1,0]
	v_pk_mul_f32 v[120:121], v[106:107], v[0:1] op_sel_hi:[1,0]
	v_and_b32_e32 v107, 0x7fffffff, v115
	v_and_b32_e32 v106, 0x7fffffff, v114
	v_pk_fma_f32 v[106:107], v[106:107], s[64:65], 1.0 op_sel_hi:[1,0,0]
	v_pk_mul_f32 v[126:127], v[114:115], v[114:115]
	v_rcp_f32_e32 v122, v106
	v_rcp_f32_e32 v123, v107
	v_mov_b64_e32 v[106:107], s[4:5]
	v_pk_mul_f32 v[126:127], v[126:127], s[76:77] op_sel_hi:[1,0]
	v_cmp_gt_f32_e32 vcc, 0, v114
	v_pk_fma_f32 v[124:125], v[122:123], s[66:67], v[106:107] op_sel_hi:[1,0,0]
	v_exp_f32_e32 v126, v126
	v_pk_fma_f32 v[124:125], v[122:123], v[124:125], s[70:71] op_sel_hi:[1,1,0]
	v_exp_f32_e32 v127, v127
	v_pk_fma_f32 v[124:125], v[122:123], v[124:125], s[72:73] op_sel_hi:[1,1,0]
	v_pk_mul_f32 v[116:117], v[116:117], v[0:1] op_sel_hi:[1,0]
	v_pk_fma_f32 v[124:125], v[122:123], v[124:125], s[74:75] op_sel_hi:[1,1,0]
	v_pk_mul_f32 v[108:109], v[108:109], v[0:1] op_sel_hi:[1,0]
	v_pk_mul_f32 v[122:123], v[122:123], v[124:125]
	v_pk_mul_f32 v[124:125], v[116:117], v[116:117]
	v_pk_mul_f32 v[122:123], v[126:127], v[122:123]
	v_pk_mul_f32 v[124:125], v[124:125], s[76:77] op_sel_hi:[1,0]
	v_pk_mul_f32 v[126:127], v[114:115], v[122:123]
	v_pk_fma_f32 v[122:123], v[114:115], v[122:123], v[114:115] neg_lo:[1,0,0] neg_hi:[1,0,0]
	v_exp_f32_e32 v124, v124
	v_cndmask_b32_e32 v114, v122, v126, vcc
	v_cmp_gt_f32_e32 vcc, 0, v115
	v_and_b32_e32 v122, 0x7fffffff, v116
	v_exp_f32_e32 v125, v125
	v_cndmask_b32_e32 v115, v123, v127, vcc
	v_and_b32_e32 v123, 0x7fffffff, v117
	v_pk_fma_f32 v[122:123], v[122:123], s[64:65], 1.0 op_sel_hi:[1,0,0]
	v_cmp_gt_f32_e32 vcc, 0, v116
	v_rcp_f32_e32 v122, v122
	v_rcp_f32_e32 v123, v123
	v_lshl_add_u64 v[118:119], v[160:161], 1, v[118:119]
	v_pk_mul_f32 v[102:103], v[102:103], v[0:1] op_sel_hi:[1,0]
	v_pk_mul_f32 v[104:105], v[104:105], v[0:1] op_sel_hi:[1,0]
	v_pk_fma_f32 v[126:127], v[122:123], s[66:67], v[106:107] op_sel_hi:[1,0,0]
	v_pk_mul_f32 v[100:101], v[100:101], v[0:1] op_sel_hi:[1,0]
	v_pk_fma_f32 v[126:127], v[122:123], v[126:127], s[70:71] op_sel_hi:[1,1,0]
	s_nop 0
	v_pk_fma_f32 v[126:127], v[122:123], v[126:127], s[72:73] op_sel_hi:[1,1,0]
	s_nop 0
	v_pk_fma_f32 v[126:127], v[122:123], v[126:127], s[74:75] op_sel_hi:[1,1,0]
	s_nop 0
	v_pk_mul_f32 v[122:123], v[122:123], v[126:127]
	v_pk_mul_f32 v[126:127], v[120:121], v[120:121]
	v_pk_mul_f32 v[122:123], v[124:125], v[122:123]
	v_pk_mul_f32 v[126:127], v[126:127], s[76:77] op_sel_hi:[1,0]
	v_pk_mul_f32 v[124:125], v[116:117], v[122:123]
	v_pk_fma_f32 v[122:123], v[116:117], v[122:123], v[116:117] neg_lo:[1,0,0] neg_hi:[1,0,0]
	v_exp_f32_e32 v126, v126
	v_cndmask_b32_e32 v116, v122, v124, vcc
	v_cmp_gt_f32_e32 vcc, 0, v117
	v_and_b32_e32 v122, 0x7fffffff, v120
	v_exp_f32_e32 v127, v127
	v_cndmask_b32_e32 v117, v123, v125, vcc
	v_and_b32_e32 v123, 0x7fffffff, v121
	v_pk_fma_f32 v[122:123], v[122:123], s[64:65], 1.0 op_sel_hi:[1,0,0]
	v_cmp_gt_f32_e32 vcc, 0, v120
	v_rcp_f32_e32 v122, v122
	v_rcp_f32_e32 v123, v123
	s_nop 0
	v_pk_fma_f32 v[124:125], v[122:123], s[66:67], v[106:107] op_sel_hi:[1,0,0]
	s_nop 0
	v_pk_fma_f32 v[124:125], v[122:123], v[124:125], s[70:71] op_sel_hi:[1,1,0]
	s_nop 0
	v_pk_fma_f32 v[124:125], v[122:123], v[124:125], s[72:73] op_sel_hi:[1,1,0]
	s_nop 0
	v_pk_fma_f32 v[124:125], v[122:123], v[124:125], s[74:75] op_sel_hi:[1,1,0]
	s_nop 0
	v_pk_mul_f32 v[122:123], v[122:123], v[124:125]
	v_pk_mul_f32 v[124:125], v[108:109], v[108:109]
	v_pk_mul_f32 v[122:123], v[126:127], v[122:123]
	v_pk_mul_f32 v[124:125], v[124:125], s[76:77] op_sel_hi:[1,0]
	v_pk_mul_f32 v[126:127], v[120:121], v[122:123]
	v_pk_fma_f32 v[122:123], v[120:121], v[122:123], v[120:121] neg_lo:[1,0,0] neg_hi:[1,0,0]
	v_exp_f32_e32 v124, v124
	v_cndmask_b32_e32 v120, v122, v126, vcc
	v_cmp_gt_f32_e32 vcc, 0, v121
	v_and_b32_e32 v122, 0x7fffffff, v108
	v_exp_f32_e32 v125, v125
	v_cndmask_b32_e32 v121, v123, v127, vcc
	v_and_b32_e32 v123, 0x7fffffff, v109
	v_pk_fma_f32 v[122:123], v[122:123], s[64:65], 1.0 op_sel_hi:[1,0,0]
	v_cmp_gt_f32_e32 vcc, 0, v108
	v_rcp_f32_e32 v122, v122
	v_rcp_f32_e32 v123, v123
	s_nop 0
	v_pk_fma_f32 v[126:127], v[122:123], s[66:67], v[106:107] op_sel_hi:[1,0,0]
	s_nop 0
	v_pk_fma_f32 v[126:127], v[122:123], v[126:127], s[70:71] op_sel_hi:[1,1,0]
	s_nop 0
	v_pk_fma_f32 v[126:127], v[122:123], v[126:127], s[72:73] op_sel_hi:[1,1,0]
	s_nop 0
	v_pk_fma_f32 v[126:127], v[122:123], v[126:127], s[74:75] op_sel_hi:[1,1,0]
	s_nop 0
	v_pk_mul_f32 v[122:123], v[122:123], v[126:127]
	v_pk_mul_f32 v[126:127], v[102:103], v[102:103]
	v_pk_mul_f32 v[122:123], v[124:125], v[122:123]
	v_pk_mul_f32 v[126:127], v[126:127], s[76:77] op_sel_hi:[1,0]
	v_pk_mul_f32 v[124:125], v[108:109], v[122:123]
	v_pk_fma_f32 v[122:123], v[108:109], v[122:123], v[108:109] neg_lo:[1,0,0] neg_hi:[1,0,0]
	v_exp_f32_e32 v126, v126
	v_cndmask_b32_e32 v108, v122, v124, vcc
	v_cmp_gt_f32_e32 vcc, 0, v109
	v_cvt_pk_bf16_f32 v122, v114, v115
	v_exp_f32_e32 v127, v127
	s_nop 0
	v_cndmask_b32_e32 v109, v123, v125, vcc
	v_cvt_pk_bf16_f32 v123, v116, v117
	v_cvt_pk_bf16_f32 v124, v120, v121
	v_cvt_pk_bf16_f32 v125, v108, v109
	global_store_dwordx4 v[118:119], v[122:125], off
	v_cmp_gt_f32_e32 vcc, 0, v102
	s_nop 0
	v_pk_mul_f32 v[122:123], v[98:99], v[0:1] op_sel_hi:[1,0]
	v_and_b32_e32 v99, 0x7fffffff, v103
; __device__ __forceinline__ unsigned cvt_pk_bf16(float lo, float hi) { unsigned r; asm volatile("v_cvt_pk_bf16_f32 %0, %1, %2" : "=v"(r) : "v"(lo), "v"(hi)); return r; }
; __device__ __forceinline__ f32x2 gelu_pk(f32x2 v) {
;     const f32x2 av = __builtin_elementwise_abs(v), d = av * 0.2316418882f + 1.0f;
;     f32x2 t; t.x = __builtin_amdgcn_rcpf(d.x); t.y = __builtin_amdgcn_rcpf(d.y);
;     f32x2 q = t * 0.5307027145f + (-0.7265760135f); q = q * t + 0.7107068705f; q = q * t + (-0.142248368f); q = q * t + 0.127414796f; q = q * t;
;     const f32x2 s = (v * v) * (-0.72134752044f);
;     f32x2 e; e.x = __builtin_amdgcn_exp2f(s.x); e.y = __builtin_amdgcn_exp2f(s.y);
;     const f32x2 m = v * (q * e), r = v - m;
;     f32x2 o; o.x = v.x < 0.f ? m.x : r.x; o.y = v.y < 0.f ? m.y : r.y; return o;
; }
;     __device__ __forceinline__ void operator()(const f32x4 (&acc)[2][2][4][2], const Unit& u, int wr, int wc, int fr, int fq) const {
;     ...
;             for (int m = 0; m < 4; ++m) { const int row = row0 + ai * HALF + m * 16; const float rs = rsv[ai][m]; bf16_t* rowp = O + (size_t)row * ldc + col0; float s1 = 0.f, s2 = 0.f;
; #pragma unroll
;                 for (int bj = 0; bj < 2; ++bj) { f32x4 v0 = acc[ai][bj][m][0] * rs, v1 = acc[ai][bj][m][1] * rs;
;                     const f32x2 a = gelu_pk((f32x2){v0[0], v0[1]}), b = gelu_pk((f32x2){v0[2], v0[3]}), c = gelu_pk((f32x2){v1[0], v1[1]}), d = gelu_pk((f32x2){v1[2], v1[3]});
;                     s1 += ((a.x + a.y) + (b.x + b.y)) + ((c.x + c.y) + (d.x + d.y));
;                     s2 += ((a.x * a.x + a.y * a.y) + (b.x * b.x + b.y * b.y)) + ((c.x * c.x + c.y * c.y) + (d.x * d.x + d.y * d.y));
;                     u32x4 w; w.x = cvt_pk_bf16(a.x, a.y); w.y = cvt_pk_bf16(b.x, b.y); w.z = cvt_pk_bf16(c.x, c.y); w.w = cvt_pk_bf16(d.x, d.y);
;                     *(u32x4*)(rowp + bj * HALF) = w; }
;                 if (isv) { s1 += __shfl_xor(s1, 16); s1 += __shfl_xor(s1, 32); s2 += __shfl_xor(s2, 16); s2 += __shfl_xor(s2, 32);
;                     if (fq == 0) { const int rl = ai * HALF + wr * 64 + m * 16 + fr; part[rl * 4 + wc] = s1; part[1024 + rl * 4 + wc] = s2; } } }
	v_and_b32_e32 v98, 0x7fffffff, v102
	v_pk_fma_f32 v[98:99], v[98:99], s[64:65], 1.0 op_sel_hi:[1,0,0]
	s_nop 0
	v_rcp_f32_e32 v98, v98
	v_rcp_f32_e32 v99, v99
	s_nop 0
	v_pk_fma_f32 v[124:125], v[98:99], s[66:67], v[106:107] op_sel_hi:[1,0,0]
	s_nop 0
	v_pk_fma_f32 v[124:125], v[98:99], v[124:125], s[70:71] op_sel_hi:[1,1,0]
	s_nop 0
	v_pk_fma_f32 v[124:125], v[98:99], v[124:125], s[72:73] op_sel_hi:[1,1,0]
	s_nop 0
	v_pk_fma_f32 v[124:125], v[98:99], v[124:125], s[74:75] op_sel_hi:[1,1,0]
	s_nop 0
	v_pk_mul_f32 v[98:99], v[98:99], v[124:125]
	v_pk_mul_f32 v[124:125], v[104:105], v[104:105]
	v_pk_mul_f32 v[98:99], v[126:127], v[98:99]
	v_pk_mul_f32 v[124:125], v[124:125], s[76:77] op_sel_hi:[1,0]
	v_pk_mul_f32 v[126:127], v[102:103], v[98:99]
	v_pk_fma_f32 v[98:99], v[102:103], v[98:99], v[102:103] neg_lo:[1,0,0] neg_hi:[1,0,0]
	v_and_b32_e32 v102, 0x7fffffff, v104
	v_cndmask_b32_e32 v0, v98, v126, vcc
	v_cmp_gt_f32_e32 vcc, 0, v103
	v_and_b32_e32 v103, 0x7fffffff, v105
	v_pk_fma_f32 v[102:103], v[102:103], s[64:65], 1.0 op_sel_hi:[1,0,0]
	v_cndmask_b32_e32 v98, v99, v127, vcc
	v_rcp_f32_e32 v102, v102
	v_rcp_f32_e32 v103, v103
	v_exp_f32_e32 v124, v124
	v_exp_f32_e32 v125, v125
	v_cmp_gt_f32_e32 vcc, 0, v104
	v_pk_fma_f32 v[126:127], v[102:103], s[66:67], v[106:107] op_sel_hi:[1,0,0]
	s_nop 0
	v_pk_fma_f32 v[126:127], v[102:103], v[126:127], s[70:71] op_sel_hi:[1,1,0]
	s_nop 0
	v_pk_fma_f32 v[126:127], v[102:103], v[126:127], s[72:73] op_sel_hi:[1,1,0]
	s_nop 0
	v_pk_fma_f32 v[126:127], v[102:103], v[126:127], s[74:75] op_sel_hi:[1,1,0]
	s_nop 0
	v_pk_mul_f32 v[102:103], v[102:103], v[126:127]
	v_pk_mul_f32 v[126:127], v[122:123], v[122:123]
	v_pk_mul_f32 v[102:103], v[124:125], v[102:103]
	v_pk_mul_f32 v[126:127], v[126:127], s[76:77] op_sel_hi:[1,0]
	v_pk_mul_f32 v[124:125], v[104:105], v[102:103]
	v_pk_fma_f32 v[102:103], v[104:105], v[102:103], v[104:105] neg_lo:[1,0,0] neg_hi:[1,0,0]
	v_and_b32_e32 v104, 0x7fffffff, v122
	v_cndmask_b32_e32 v99, v102, v124, vcc
	v_cmp_gt_f32_e32 vcc, 0, v105
	v_and_b32_e32 v105, 0x7fffffff, v123
	v_pk_fma_f32 v[104:105], v[104:105], s[64:65], 1.0 op_sel_hi:[1,0,0]
	v_cndmask_b32_e32 v102, v103, v125, vcc
	v_rcp_f32_e32 v104, v104
	v_rcp_f32_e32 v105, v105
	v_exp_f32_e32 v126, v126
	v_exp_f32_e32 v127, v127
	v_cmp_gt_f32_e32 vcc, 0, v122
	v_pk_fma_f32 v[124:125], v[104:105], s[66:67], v[106:107] op_sel_hi:[1,0,0]
	s_nop 0
	v_pk_fma_f32 v[124:125], v[104:105], v[124:125], s[70:71] op_sel_hi:[1,1,0]
	s_nop 0
	v_pk_fma_f32 v[124:125], v[104:105], v[124:125], s[72:73] op_sel_hi:[1,1,0]
	s_nop 0
	v_pk_fma_f32 v[124:125], v[104:105], v[124:125], s[74:75] op_sel_hi:[1,1,0]
	s_nop 0
	v_pk_mul_f32 v[104:105], v[104:105], v[124:125]
	v_pk_mul_f32 v[124:125], v[100:101], v[100:101]
	v_pk_mul_f32 v[104:105], v[126:127], v[104:105]
	s_nop 0
	v_pk_mul_f32 v[126:127], v[122:123], v[104:105]
	v_pk_fma_f32 v[104:105], v[122:123], v[104:105], v[122:123] neg_lo:[1,0,0] neg_hi:[1,0,0]
	v_and_b32_e32 v122, 0x7fffffff, v100
	v_cndmask_b32_e32 v103, v104, v126, vcc
	v_cmp_gt_f32_e32 vcc, 0, v123
	v_and_b32_e32 v123, 0x7fffffff, v101
	v_pk_fma_f32 v[122:123], v[122:123], s[64:65], 1.0 op_sel_hi:[1,0,0]
	v_cndmask_b32_e32 v104, v105, v127, vcc
	v_rcp_f32_e32 v122, v122
	v_rcp_f32_e32 v123, v123
	v_cmp_gt_f32_e32 vcc, 0, v100
	v_pk_fma_f32 v[106:107], v[122:123], s[66:67], v[106:107] op_sel_hi:[1,0,0]
	s_nop 0
	v_pk_fma_f32 v[106:107], v[122:123], v[106:107], s[70:71] op_sel_hi:[1,1,0]
	s_nop 0
	v_pk_fma_f32 v[106:107], v[122:123], v[106:107], s[72:73] op_sel_hi:[1,1,0]
	s_nop 0
	v_pk_fma_f32 v[106:107], v[122:123], v[106:107], s[74:75] op_sel_hi:[1,1,0]
	s_nop 0
	v_pk_mul_f32 v[106:107], v[122:123], v[106:107]
	v_pk_mul_f32 v[122:123], v[124:125], s[76:77] op_sel_hi:[1,0]
	s_nop 0
	v_exp_f32_e32 v122, v122
	v_exp_f32_e32 v123, v123
	s_nop 0
	v_pk_mul_f32 v[106:107], v[122:123], v[106:107]
	s_nop 0
	v_pk_mul_f32 v[122:123], v[100:101], v[106:107]
	v_pk_fma_f32 v[106:107], v[100:101], v[106:107], v[100:101] neg_lo:[1,0,0] neg_hi:[1,0,0]
	s_nop 0
	v_cndmask_b32_e32 v100, v106, v122, vcc
	v_cmp_gt_f32_e32 vcc, 0, v101
	v_cvt_pk_bf16_f32 v122, v0, v98
	s_nop 1
	v_cndmask_b32_e32 v101, v107, v123, vcc
	s_and_b64 vcc, exec, s[10:11]
	v_cvt_pk_bf16_f32 v123, v99, v102
	v_cvt_pk_bf16_f32 v124, v103, v104
	v_cvt_pk_bf16_f32 v125, v100, v101
	global_store_dwordx4 v[118:119], v[122:125], off offset:256
	s_cbranch_vccnz .LBB0_364
	v_mul_f32_e32 v105, v115, v115
	v_mul_f32_e32 v106, v117, v117
	v_fmac_f32_e32 v105, v114, v114
	v_fmac_f32_e32 v106, v116, v116
	v_add_f32_e32 v105, v105, v106
	v_mul_f32_e32 v106, v121, v121
	v_mul_f32_e32 v107, v109, v109
	v_fmac_f32_e32 v106, v120, v120
	v_fmac_f32_e32 v107, v108, v108
	v_add_f32_e32 v106, v106, v107
	v_add_f32_e32 v105, v105, v106
	v_mul_f32_e32 v106, v98, v98
	v_fmac_f32_e32 v106, v0, v0
	v_mul_f32_e32 v107, v102, v102
	v_add_f32_e32 v0, v0, v98
	v_add_f32_e32 v98, v99, v102
	v_fmac_f32_e32 v107, v99, v99
	v_add_f32_e32 v114, v114, v115
	v_add_f32_e32 v115, v116, v117
	v_add_f32_e32 v0, v0, v98
	v_add_f32_e32 v98, v103, v104
	v_add_f32_e32 v99, v100, v101
	v_add_f32_e32 v114, v114, v115
	v_add_f32_e32 v115, v120, v121
	v_add_f32_e32 v108, v108, v109
	v_add_f32_e32 v98, v98, v99
	v_and_b32_e32 v99, 64, v226
	v_add_f32_e32 v108, v115, v108
	v_add_f32_e32 v0, v0, v98
	v_xor_b32_e32 v98, 16, v226
	v_add_u32_e32 v99, 64, v99
	v_add_f32_e32 v108, v114, v108
	v_cmp_lt_i32_e32 vcc, v98, v99
	v_add_f32_e32 v106, v106, v107
	v_mul_f32_e32 v107, v104, v104
	v_mul_f32_e32 v118, v101, v101
	v_add_f32_e32 v108, 0, v108
	v_cndmask_b32_e32 v98, v226, v98, vcc
	v_fmac_f32_e32 v107, v103, v103
	v_add_f32_e32 v0, v0, v108
	v_lshlrev_b32_e32 v98, 2, v98
	v_fmac_f32_e32 v118, v100, v100
	ds_bpermute_b32 v101, v98, v0
	v_add_f32_e32 v100, v107, v118
	v_add_f32_e32 v100, v106, v100
	v_add_f32_e32 v100, v105, v100
	ds_bpermute_b32 v102, v98, v100
	s_waitcnt lgkmcnt(0)
	v_add_f32_e32 v0, v0, v101
	v_xor_b32_e32 v101, 32, v226
	v_cmp_lt_i32_e32 vcc, v101, v99
	v_add_f32_e32 v99, v100, v102
	s_nop 0
	v_cndmask_b32_e32 v98, v226, v101, vcc
	v_lshlrev_b32_e32 v101, 2, v98
	ds_bpermute_b32 v98, v101, v0
	ds_bpermute_b32 v100, v101, v99
	s_and_saveexec_b64 s[4:5], s[6:7]
	s_cbranch_execz .LBB0_363
	s_waitcnt lgkmcnt(0)
	v_add_f32_e32 v99, v99, v100
	v_add_f32_e32 v0, v0, v98
	ds_write2st64_b32 v186, v0, v99 offset0:2 offset1:18

; __device__ __forceinline__ unsigned cvt_pk_bf16(float lo, float hi) { unsigned r; asm volatile("v_cvt_pk_bf16_f32 %0, %1, %2" : "=v"(r) : "v"(lo), "v"(hi)); return r; }
; __device__ __forceinline__ f32x2 gelu_pk(f32x2 v) {
;     const f32x2 av = __builtin_elementwise_abs(v), d = av * 0.2316418882f + 1.0f;
;     f32x2 t; t.x = __builtin_amdgcn_rcpf(d.x); t.y = __builtin_amdgcn_rcpf(d.y);
;     f32x2 q = t * 0.5307027145f + (-0.7265760135f); q = q * t + 0.7107068705f; q = q * t + (-0.142248368f); q = q * t + 0.127414796f; q = q * t;
;     const f32x2 s = (v * v) * (-0.72134752044f);
;     f32x2 e; e.x = __builtin_amdgcn_exp2f(s.x); e.y = __builtin_amdgcn_exp2f(s.y);
;     const f32x2 m = v * (q * e), r = v - m;
;     f32x2 o; o.x = v.x < 0.f ? m.x : r.x; o.y = v.y < 0.f ? m.y : r.y; return o;
; }
;     __device__ __forceinline__ void operator()(const f32x4 (&acc)[2][2][4][2], const Unit& u, int wr, int wc, int fr, int fq) const {
;     ...
;             for (int m = 0; m < 4; ++m) { const int row = row0 + ai * HALF + m * 16; const float rs = rsv[ai][m]; bf16_t* rowp = O + (size_t)row * ldc + col0; float s1 = 0.f, s2 = 0.f;
; #pragma unroll
;                 for (int bj = 0; bj < 2; ++bj) { f32x4 v0 = acc[ai][bj][m][0] * rs, v1 = acc[ai][bj][m][1] * rs;
;                     const f32x2 a = gelu_pk((f32x2){v0[0], v0[1]}), b = gelu_pk((f32x2){v0[2], v0[3]}), c = gelu_pk((f32x2){v1[0], v1[1]}), d = gelu_pk((f32x2){v1[2], v1[3]});
;                     s1 += ((a.x + a.y) + (b.x + b.y)) + ((c.x + c.y) + (d.x + d.y));
;                     s2 += ((a.x * a.x + a.y * a.y) + (b.x * b.x + b.y * b.y)) + ((c.x * c.x + c.y * c.y) + (d.x * d.x + d.y * d.y));
;                     u32x4 w; w.x = cvt_pk_bf16(a.x, a.y); w.y = cvt_pk_bf16(b.x, b.y); w.z = cvt_pk_bf16(c.x, c.y); w.w = cvt_pk_bf16(d.x, d.y);
;                     *(u32x4*)(rowp + bj * HALF) = w; }
;                 if (isv) { s1 += __shfl_xor(s1, 16); s1 += __shfl_xor(s1, 32); s2 += __shfl_xor(s2, 16); s2 += __shfl_xor(s2, 32);
;                     if (fq == 0) { const int rl = ai * HALF + wr * 64 + m * 16 + fr; part[rl * 4 + wc] = s1; part[1024 + rl * 4 + wc] = s2; } } }
.LBB0_364:
	v_add_f32_e32 v0, v110, v111
	s_waitcnt lgkmcnt(0)
	v_add_f32_e32 v98, v112, v113
	v_add_f32_e32 v0, v0, v98
	v_fmamk_f32 v0, v0, 0x3a800000, v224
	v_rsq_f32_e32 v0, v0
	s_mov_b32 s4, 0xbf3a00e3
	v_lshlrev_b64 v[98:99], 12, v[170:171]
	v_lshl_add_u64 v[98:99], s[20:21], 0, v[98:99]
	v_pk_mul_f32 v[90:91], v[90:91], v[0:1] op_sel_hi:[1,0]
	v_pk_mul_f32 v[100:101], v[86:87], v[0:1] op_sel_hi:[1,0]
	v_and_b32_e32 v87, 0x7fffffff, v91
	v_and_b32_e32 v86, 0x7fffffff, v90
	v_pk_fma_f32 v[86:87], v[86:87], s[64:65], 1.0 op_sel_hi:[1,0,0]
	v_pk_mul_f32 v[106:107], v[90:91], v[90:91]
	v_rcp_f32_e32 v102, v86
	v_rcp_f32_e32 v103, v87
	v_mov_b64_e32 v[86:87], s[4:5]
	v_pk_mul_f32 v[106:107], v[106:107], s[76:77] op_sel_hi:[1,0]
	v_cmp_gt_f32_e32 vcc, 0, v90
	v_pk_fma_f32 v[104:105], v[102:103], s[66:67], v[86:87] op_sel_hi:[1,0,0]
	v_exp_f32_e32 v106, v106
	v_pk_fma_f32 v[104:105], v[102:103], v[104:105], s[70:71] op_sel_hi:[1,1,0]
	v_exp_f32_e32 v107, v107
	v_pk_fma_f32 v[104:105], v[102:103], v[104:105], s[72:73] op_sel_hi:[1,1,0]
	v_pk_mul_f32 v[92:93], v[92:93], v[0:1] op_sel_hi:[1,0]
	v_pk_fma_f32 v[104:105], v[102:103], v[104:105], s[74:75] op_sel_hi:[1,1,0]
	v_pk_mul_f32 v[88:89], v[88:89], v[0:1] op_sel_hi:[1,0]
	v_pk_mul_f32 v[102:103], v[102:103], v[104:105]
	v_pk_mul_f32 v[104:105], v[92:93], v[92:93]
	v_pk_mul_f32 v[102:103], v[106:107], v[102:103]
	v_pk_mul_f32 v[104:105], v[104:105], s[76:77] op_sel_hi:[1,0]
	v_pk_mul_f32 v[106:107], v[90:91], v[102:103]
	v_pk_fma_f32 v[102:103], v[90:91], v[102:103], v[90:91] neg_lo:[1,0,0] neg_hi:[1,0,0]
	v_exp_f32_e32 v104, v104
	v_cndmask_b32_e32 v90, v102, v106, vcc
	v_cmp_gt_f32_e32 vcc, 0, v91
	v_and_b32_e32 v102, 0x7fffffff, v92
	v_exp_f32_e32 v105, v105
	v_cndmask_b32_e32 v91, v103, v107, vcc
	v_and_b32_e32 v103, 0x7fffffff, v93
	v_pk_fma_f32 v[102:103], v[102:103], s[64:65], 1.0 op_sel_hi:[1,0,0]
	v_cmp_gt_f32_e32 vcc, 0, v92
	v_rcp_f32_e32 v102, v102
	v_rcp_f32_e32 v103, v103
	v_lshl_add_u64 v[98:99], v[160:161], 1, v[98:99]
	v_pk_mul_f32 v[82:83], v[82:83], v[0:1] op_sel_hi:[1,0]
	v_pk_mul_f32 v[84:85], v[84:85], v[0:1] op_sel_hi:[1,0]
	v_pk_fma_f32 v[106:107], v[102:103], s[66:67], v[86:87] op_sel_hi:[1,0,0]
	v_pk_mul_f32 v[80:81], v[80:81], v[0:1] op_sel_hi:[1,0]
	v_pk_fma_f32 v[106:107], v[102:103], v[106:107], s[70:71] op_sel_hi:[1,1,0]
	s_nop 0
	v_pk_fma_f32 v[106:107], v[102:103], v[106:107], s[72:73] op_sel_hi:[1,1,0]
	s_nop 0
	v_pk_fma_f32 v[106:107], v[102:103], v[106:107], s[74:75] op_sel_hi:[1,1,0]
	s_nop 0
	v_pk_mul_f32 v[102:103], v[102:103], v[106:107]
	v_pk_mul_f32 v[106:107], v[100:101], v[100:101]
	v_pk_mul_f32 v[102:103], v[104:105], v[102:103]
	v_pk_mul_f32 v[106:107], v[106:107], s[76:77] op_sel_hi:[1,0]
	v_pk_mul_f32 v[104:105], v[92:93], v[102:103]
	v_pk_fma_f32 v[102:103], v[92:93], v[102:103], v[92:93] neg_lo:[1,0,0] neg_hi:[1,0,0]
	v_exp_f32_e32 v106, v106
	v_cndmask_b32_e32 v92, v102, v104, vcc
	v_cmp_gt_f32_e32 vcc, 0, v93
	v_and_b32_e32 v102, 0x7fffffff, v100
	v_exp_f32_e32 v107, v107
	v_cndmask_b32_e32 v93, v103, v105, vcc
	v_and_b32_e32 v103, 0x7fffffff, v101
	v_pk_fma_f32 v[102:103], v[102:103], s[64:65], 1.0 op_sel_hi:[1,0,0]
	v_cmp_gt_f32_e32 vcc, 0, v100
	v_rcp_f32_e32 v102, v102
	v_rcp_f32_e32 v103, v103
	s_nop 0
	v_pk_fma_f32 v[104:105], v[102:103], s[66:67], v[86:87] op_sel_hi:[1,0,0]
	s_nop 0
	v_pk_fma_f32 v[104:105], v[102:103], v[104:105], s[70:71] op_sel_hi:[1,1,0]
	s_nop 0
	v_pk_fma_f32 v[104:105], v[102:103], v[104:105], s[72:73] op_sel_hi:[1,1,0]
	s_nop 0
	v_pk_fma_f32 v[104:105], v[102:103], v[104:105], s[74:75] op_sel_hi:[1,1,0]
	s_nop 0
	v_pk_mul_f32 v[102:103], v[102:103], v[104:105]
	v_pk_mul_f32 v[104:105], v[88:89], v[88:89]
	v_pk_mul_f32 v[102:103], v[106:107], v[102:103]
	v_pk_mul_f32 v[104:105], v[104:105], s[76:77] op_sel_hi:[1,0]
	v_pk_mul_f32 v[106:107], v[100:101], v[102:103]
	v_pk_fma_f32 v[102:103], v[100:101], v[102:103], v[100:101] neg_lo:[1,0,0] neg_hi:[1,0,0]
	v_exp_f32_e32 v104, v104
	v_cndmask_b32_e32 v100, v102, v106, vcc
	v_cmp_gt_f32_e32 vcc, 0, v101
	v_and_b32_e32 v102, 0x7fffffff, v88
	v_exp_f32_e32 v105, v105
	v_cndmask_b32_e32 v101, v103, v107, vcc
	v_and_b32_e32 v103, 0x7fffffff, v89
	v_pk_fma_f32 v[102:103], v[102:103], s[64:65], 1.0 op_sel_hi:[1,0,0]
	v_cmp_gt_f32_e32 vcc, 0, v88
	v_rcp_f32_e32 v102, v102
	v_rcp_f32_e32 v103, v103
	s_nop 0
	v_pk_fma_f32 v[106:107], v[102:103], s[66:67], v[86:87] op_sel_hi:[1,0,0]
	s_nop 0
	v_pk_fma_f32 v[106:107], v[102:103], v[106:107], s[70:71] op_sel_hi:[1,1,0]
	s_nop 0
	v_pk_fma_f32 v[106:107], v[102:103], v[106:107], s[72:73] op_sel_hi:[1,1,0]
	s_nop 0
	v_pk_fma_f32 v[106:107], v[102:103], v[106:107], s[74:75] op_sel_hi:[1,1,0]
	s_nop 0
	v_pk_mul_f32 v[102:103], v[102:103], v[106:107]
	v_pk_mul_f32 v[106:107], v[82:83], v[82:83]
	v_pk_mul_f32 v[102:103], v[104:105], v[102:103]
	v_pk_mul_f32 v[106:107], v[106:107], s[76:77] op_sel_hi:[1,0]
	v_pk_mul_f32 v[104:105], v[88:89], v[102:103]
	v_pk_fma_f32 v[102:103], v[88:89], v[102:103], v[88:89] neg_lo:[1,0,0] neg_hi:[1,0,0]
	v_exp_f32_e32 v106, v106
	v_cndmask_b32_e32 v88, v102, v104, vcc
	v_cmp_gt_f32_e32 vcc, 0, v89
	v_cvt_pk_bf16_f32 v102, v90, v91
	v_exp_f32_e32 v107, v107
	s_nop 0
	v_cndmask_b32_e32 v89, v103, v105, vcc
	v_cvt_pk_bf16_f32 v103, v92, v93
	v_cvt_pk_bf16_f32 v104, v100, v101
	v_cvt_pk_bf16_f32 v105, v88, v89
	global_store_dwordx4 v[98:99], v[102:105], off
	v_cmp_gt_f32_e32 vcc, 0, v82
	s_nop 0
	v_pk_mul_f32 v[102:103], v[78:79], v[0:1] op_sel_hi:[1,0]
	v_and_b32_e32 v79, 0x7fffffff, v83
	v_and_b32_e32 v78, 0x7fffffff, v82
	v_pk_fma_f32 v[78:79], v[78:79], s[64:65], 1.0 op_sel_hi:[1,0,0]
	s_nop 0
; __device__ __forceinline__ unsigned cvt_pk_bf16(float lo, float hi) { unsigned r; asm volatile("v_cvt_pk_bf16_f32 %0, %1, %2" : "=v"(r) : "v"(lo), "v"(hi)); return r; }
; __device__ __forceinline__ f32x2 gelu_pk(f32x2 v) {
;     const f32x2 av = __builtin_elementwise_abs(v), d = av * 0.2316418882f + 1.0f;
;     f32x2 t; t.x = __builtin_amdgcn_rcpf(d.x); t.y = __builtin_amdgcn_rcpf(d.y);
;     f32x2 q = t * 0.5307027145f + (-0.7265760135f); q = q * t + 0.7107068705f; q = q * t + (-0.142248368f); q = q * t + 0.127414796f; q = q * t;
;     const f32x2 s = (v * v) * (-0.72134752044f);
;     f32x2 e; e.x = __builtin_amdgcn_exp2f(s.x); e.y = __builtin_amdgcn_exp2f(s.y);
;     const f32x2 m = v * (q * e), r = v - m;
;     f32x2 o; o.x = v.x < 0.f ? m.x : r.x; o.y = v.y < 0.f ? m.y : r.y; return o;
; }
;     __device__ __forceinline__ void operator()(const f32x4 (&acc)[2][2][4][2], const Unit& u, int wr, int wc, int fr, int fq) const {
;     ...
;             for (int m = 0; m < 4; ++m) { const int row = row0 + ai * HALF + m * 16; const float rs = rsv[ai][m]; bf16_t* rowp = O + (size_t)row * ldc + col0; float s1 = 0.f, s2 = 0.f;
; #pragma unroll
;                 for (int bj = 0; bj < 2; ++bj) { f32x4 v0 = acc[ai][bj][m][0] * rs, v1 = acc[ai][bj][m][1] * rs;
;                     const f32x2 a = gelu_pk((f32x2){v0[0], v0[1]}), b = gelu_pk((f32x2){v0[2], v0[3]}), c = gelu_pk((f32x2){v1[0], v1[1]}), d = gelu_pk((f32x2){v1[2], v1[3]});
;                     s1 += ((a.x + a.y) + (b.x + b.y)) + ((c.x + c.y) + (d.x + d.y));
;                     s2 += ((a.x * a.x + a.y * a.y) + (b.x * b.x + b.y * b.y)) + ((c.x * c.x + c.y * c.y) + (d.x * d.x + d.y * d.y));
;                     u32x4 w; w.x = cvt_pk_bf16(a.x, a.y); w.y = cvt_pk_bf16(b.x, b.y); w.z = cvt_pk_bf16(c.x, c.y); w.w = cvt_pk_bf16(d.x, d.y);
;                     *(u32x4*)(rowp + bj * HALF) = w; }
;                 if (isv) { s1 += __shfl_xor(s1, 16); s1 += __shfl_xor(s1, 32); s2 += __shfl_xor(s2, 16); s2 += __shfl_xor(s2, 32);
;                     if (fq == 0) { const int rl = ai * HALF + wr * 64 + m * 16 + fr; part[rl * 4 + wc] = s1; part[1024 + rl * 4 + wc] = s2; } } }
	v_rcp_f32_e32 v78, v78
	v_rcp_f32_e32 v79, v79
	s_nop 0
	v_pk_fma_f32 v[104:105], v[78:79], s[66:67], v[86:87] op_sel_hi:[1,0,0]
	s_nop 0
	v_pk_fma_f32 v[104:105], v[78:79], v[104:105], s[70:71] op_sel_hi:[1,1,0]
	s_nop 0
	v_pk_fma_f32 v[104:105], v[78:79], v[104:105], s[72:73] op_sel_hi:[1,1,0]
	s_nop 0
	v_pk_fma_f32 v[104:105], v[78:79], v[104:105], s[74:75] op_sel_hi:[1,1,0]
	s_nop 0
	v_pk_mul_f32 v[78:79], v[78:79], v[104:105]
	v_pk_mul_f32 v[104:105], v[84:85], v[84:85]
	v_pk_mul_f32 v[78:79], v[106:107], v[78:79]
	v_pk_mul_f32 v[104:105], v[104:105], s[76:77] op_sel_hi:[1,0]
	v_pk_mul_f32 v[106:107], v[82:83], v[78:79]
	v_pk_fma_f32 v[78:79], v[82:83], v[78:79], v[82:83] neg_lo:[1,0,0] neg_hi:[1,0,0]
	v_and_b32_e32 v82, 0x7fffffff, v84
	v_cndmask_b32_e32 v0, v78, v106, vcc
	v_cmp_gt_f32_e32 vcc, 0, v83
	v_and_b32_e32 v83, 0x7fffffff, v85
	v_pk_fma_f32 v[82:83], v[82:83], s[64:65], 1.0 op_sel_hi:[1,0,0]
	v_cndmask_b32_e32 v78, v79, v107, vcc
	v_rcp_f32_e32 v82, v82
	v_rcp_f32_e32 v83, v83
	v_exp_f32_e32 v104, v104
	v_exp_f32_e32 v105, v105
	v_cmp_gt_f32_e32 vcc, 0, v84
	v_pk_fma_f32 v[106:107], v[82:83], s[66:67], v[86:87] op_sel_hi:[1,0,0]
	s_nop 0
	v_pk_fma_f32 v[106:107], v[82:83], v[106:107], s[70:71] op_sel_hi:[1,1,0]
	s_nop 0
	v_pk_fma_f32 v[106:107], v[82:83], v[106:107], s[72:73] op_sel_hi:[1,1,0]
	s_nop 0
	v_pk_fma_f32 v[106:107], v[82:83], v[106:107], s[74:75] op_sel_hi:[1,1,0]
	s_nop 0
	v_pk_mul_f32 v[82:83], v[82:83], v[106:107]
	v_pk_mul_f32 v[106:107], v[102:103], v[102:103]
	v_pk_mul_f32 v[82:83], v[104:105], v[82:83]
	v_pk_mul_f32 v[106:107], v[106:107], s[76:77] op_sel_hi:[1,0]
	v_pk_mul_f32 v[104:105], v[84:85], v[82:83]
	v_pk_fma_f32 v[82:83], v[84:85], v[82:83], v[84:85] neg_lo:[1,0,0] neg_hi:[1,0,0]
	v_and_b32_e32 v84, 0x7fffffff, v102
	v_cndmask_b32_e32 v79, v82, v104, vcc
	v_cmp_gt_f32_e32 vcc, 0, v85
	v_and_b32_e32 v85, 0x7fffffff, v103
	v_pk_fma_f32 v[84:85], v[84:85], s[64:65], 1.0 op_sel_hi:[1,0,0]
	v_cndmask_b32_e32 v82, v83, v105, vcc
	v_rcp_f32_e32 v84, v84
	v_rcp_f32_e32 v85, v85
	v_exp_f32_e32 v106, v106
	v_exp_f32_e32 v107, v107
	v_cmp_gt_f32_e32 vcc, 0, v102
	v_pk_fma_f32 v[104:105], v[84:85], s[66:67], v[86:87] op_sel_hi:[1,0,0]
	s_nop 0
	v_pk_fma_f32 v[104:105], v[84:85], v[104:105], s[70:71] op_sel_hi:[1,1,0]
	s_nop 0
	v_pk_fma_f32 v[104:105], v[84:85], v[104:105], s[72:73] op_sel_hi:[1,1,0]
	s_nop 0
	v_pk_fma_f32 v[104:105], v[84:85], v[104:105], s[74:75] op_sel_hi:[1,1,0]
	s_nop 0
	v_pk_mul_f32 v[84:85], v[84:85], v[104:105]
	v_pk_mul_f32 v[104:105], v[80:81], v[80:81]
	v_pk_mul_f32 v[84:85], v[106:107], v[84:85]
	s_nop 0
	v_pk_mul_f32 v[106:107], v[102:103], v[84:85]
	v_pk_fma_f32 v[84:85], v[102:103], v[84:85], v[102:103] neg_lo:[1,0,0] neg_hi:[1,0,0]
	v_and_b32_e32 v102, 0x7fffffff, v80
	v_cndmask_b32_e32 v83, v84, v106, vcc
	v_cmp_gt_f32_e32 vcc, 0, v103
	v_and_b32_e32 v103, 0x7fffffff, v81
	v_pk_fma_f32 v[102:103], v[102:103], s[64:65], 1.0 op_sel_hi:[1,0,0]
	v_cndmask_b32_e32 v84, v85, v107, vcc
	v_rcp_f32_e32 v102, v102
	v_rcp_f32_e32 v103, v103
	v_cmp_gt_f32_e32 vcc, 0, v80
	v_pk_fma_f32 v[86:87], v[102:103], s[66:67], v[86:87] op_sel_hi:[1,0,0]
	s_nop 0
	v_pk_fma_f32 v[86:87], v[102:103], v[86:87], s[70:71] op_sel_hi:[1,1,0]
	s_nop 0
	v_pk_fma_f32 v[86:87], v[102:103], v[86:87], s[72:73] op_sel_hi:[1,1,0]
	s_nop 0
	v_pk_fma_f32 v[86:87], v[102:103], v[86:87], s[74:75] op_sel_hi:[1,1,0]
	s_nop 0
	v_pk_mul_f32 v[86:87], v[102:103], v[86:87]
	v_pk_mul_f32 v[102:103], v[104:105], s[76:77] op_sel_hi:[1,0]
	s_nop 0
	v_exp_f32_e32 v102, v102
	v_exp_f32_e32 v103, v103
	s_nop 0
	v_pk_mul_f32 v[86:87], v[102:103], v[86:87]
	s_nop 0
	v_pk_mul_f32 v[102:103], v[80:81], v[86:87]
	v_pk_fma_f32 v[86:87], v[80:81], v[86:87], v[80:81] neg_lo:[1,0,0] neg_hi:[1,0,0]
	s_nop 0
	v_cndmask_b32_e32 v80, v86, v102, vcc
	v_cmp_gt_f32_e32 vcc, 0, v81
	v_cvt_pk_bf16_f32 v102, v0, v78
	s_nop 1
	v_cndmask_b32_e32 v81, v87, v103, vcc
	s_and_b64 vcc, exec, s[10:11]
	v_cvt_pk_bf16_f32 v103, v79, v82
	v_cvt_pk_bf16_f32 v104, v83, v84
	v_cvt_pk_bf16_f32 v105, v80, v81
	global_store_dwordx4 v[98:99], v[102:105], off offset:256
	s_cbranch_vccnz .LBB0_368
	v_mul_f32_e32 v85, v91, v91
	v_mul_f32_e32 v86, v93, v93
	v_fmac_f32_e32 v85, v90, v90
	v_fmac_f32_e32 v86, v92, v92
	v_add_f32_e32 v85, v85, v86
	v_mul_f32_e32 v86, v101, v101
	v_mul_f32_e32 v87, v89, v89
	v_fmac_f32_e32 v86, v100, v100
	v_fmac_f32_e32 v87, v88, v88
	v_add_f32_e32 v86, v86, v87
	v_add_f32_e32 v85, v85, v86
	v_mul_f32_e32 v86, v78, v78
	v_fmac_f32_e32 v86, v0, v0
	v_mul_f32_e32 v87, v82, v82
	v_add_f32_e32 v0, v0, v78
	v_add_f32_e32 v78, v79, v82
	v_fmac_f32_e32 v87, v79, v79
	v_add_f32_e32 v90, v90, v91
	v_add_f32_e32 v91, v92, v93
	v_add_f32_e32 v0, v0, v78
	v_add_f32_e32 v78, v83, v84
	v_add_f32_e32 v79, v80, v81
	v_add_f32_e32 v90, v90, v91
	v_add_f32_e32 v91, v100, v101
	v_add_f32_e32 v88, v88, v89
	v_add_f32_e32 v78, v78, v79
	v_and_b32_e32 v79, 64, v226
	v_add_f32_e32 v88, v91, v88
	v_add_f32_e32 v0, v0, v78
	v_xor_b32_e32 v78, 16, v226
	v_add_u32_e32 v79, 64, v79
	v_add_f32_e32 v88, v90, v88
	v_cmp_lt_i32_e32 vcc, v78, v79
	v_add_f32_e32 v86, v86, v87
	v_mul_f32_e32 v87, v84, v84
	v_mul_f32_e32 v98, v81, v81
	v_add_f32_e32 v88, 0, v88
	v_cndmask_b32_e32 v78, v226, v78, vcc
	v_fmac_f32_e32 v87, v83, v83
	v_add_f32_e32 v0, v0, v88
	v_lshlrev_b32_e32 v78, 2, v78
	v_fmac_f32_e32 v98, v80, v80
	ds_bpermute_b32 v81, v78, v0
	v_add_f32_e32 v80, v87, v98
	v_add_f32_e32 v80, v86, v80
	v_add_f32_e32 v80, v85, v80
	ds_bpermute_b32 v82, v78, v80
	s_waitcnt lgkmcnt(0)
	v_add_f32_e32 v0, v0, v81
	v_xor_b32_e32 v81, 32, v226
	v_cmp_lt_i32_e32 vcc, v81, v79
	v_add_f32_e32 v79, v80, v82
	s_nop 0
	v_cndmask_b32_e32 v78, v226, v81, vcc
	v_lshlrev_b32_e32 v81, 2, v78
	ds_bpermute_b32 v78, v81, v0
	ds_bpermute_b32 v80, v81, v79
	s_and_saveexec_b64 s[4:5], s[6:7]
	s_cbranch_execz .LBB0_367
	s_waitcnt lgkmcnt(0)
	v_add_f32_e32 v79, v79, v80
	v_add_f32_e32 v0, v0, v78
	ds_write2st64_b32 v186, v0, v79 offset0:3 offset1:19

; __device__ __forceinline__ unsigned cvt_pk_bf16(float lo, float hi) { unsigned r; asm volatile("v_cvt_pk_bf16_f32 %0, %1, %2" : "=v"(r) : "v"(lo), "v"(hi)); return r; }
; __device__ __forceinline__ f32x2 gelu_pk(f32x2 v) {
;     const f32x2 av = __builtin_elementwise_abs(v), d = av * 0.2316418882f + 1.0f;
;     f32x2 t; t.x = __builtin_amdgcn_rcpf(d.x); t.y = __builtin_amdgcn_rcpf(d.y);
;     f32x2 q = t * 0.5307027145f + (-0.7265760135f); q = q * t + 0.7107068705f; q = q * t + (-0.142248368f); q = q * t + 0.127414796f; q = q * t;
;     const f32x2 s = (v * v) * (-0.72134752044f);
;     f32x2 e; e.x = __builtin_amdgcn_exp2f(s.x); e.y = __builtin_amdgcn_exp2f(s.y);
;     const f32x2 m = v * (q * e), r = v - m;
;     f32x2 o; o.x = v.x < 0.f ? m.x : r.x; o.y = v.y < 0.f ? m.y : r.y; return o;
; }
;     __device__ __forceinline__ void operator()(const f32x4 (&acc)[2][2][4][2], const Unit& u, int wr, int wc, int fr, int fq) const {
;     ...
;             for (int m = 0; m < 4; ++m) { const int row = row0 + ai * HALF + m * 16; const float rs = rsv[ai][m]; bf16_t* rowp = O + (size_t)row * ldc + col0; float s1 = 0.f, s2 = 0.f;
; #pragma unroll
;                 for (int bj = 0; bj < 2; ++bj) { f32x4 v0 = acc[ai][bj][m][0] * rs, v1 = acc[ai][bj][m][1] * rs;
;                     const f32x2 a = gelu_pk((f32x2){v0[0], v0[1]}), b = gelu_pk((f32x2){v0[2], v0[3]}), c = gelu_pk((f32x2){v1[0], v1[1]}), d = gelu_pk((f32x2){v1[2], v1[3]});
;                     s1 += ((a.x + a.y) + (b.x + b.y)) + ((c.x + c.y) + (d.x + d.y));
;                     s2 += ((a.x * a.x + a.y * a.y) + (b.x * b.x + b.y * b.y)) + ((c.x * c.x + c.y * c.y) + (d.x * d.x + d.y * d.y));
;                     u32x4 w; w.x = cvt_pk_bf16(a.x, a.y); w.y = cvt_pk_bf16(b.x, b.y); w.z = cvt_pk_bf16(c.x, c.y); w.w = cvt_pk_bf16(d.x, d.y);
;                     *(u32x4*)(rowp + bj * HALF) = w; }
;                 if (isv) { s1 += __shfl_xor(s1, 16); s1 += __shfl_xor(s1, 32); s2 += __shfl_xor(s2, 16); s2 += __shfl_xor(s2, 32);
;                     if (fq == 0) { const int rl = ai * HALF + wr * 64 + m * 16 + fr; part[rl * 4 + wc] = s1; part[1024 + rl * 4 + wc] = s2; } } }
.LBB0_368:
	v_add_f32_e32 v0, v94, v95
	s_waitcnt lgkmcnt(0)
	v_add_f32_e32 v78, v96, v97
	v_add_f32_e32 v0, v0, v78
	v_fmamk_f32 v0, v0, 0x3a800000, v224
	v_rsq_f32_e32 v0, v0
	s_mov_b32 s4, 0xbf3a00e3
	v_lshlrev_b64 v[78:79], 12, v[168:169]
	v_lshl_add_u64 v[78:79], s[20:21], 0, v[78:79]
	v_pk_mul_f32 v[70:71], v[70:71], v[0:1] op_sel_hi:[1,0]
	v_pk_mul_f32 v[80:81], v[66:67], v[0:1] op_sel_hi:[1,0]
	v_and_b32_e32 v67, 0x7fffffff, v71
	v_and_b32_e32 v66, 0x7fffffff, v70
	v_pk_fma_f32 v[66:67], v[66:67], s[64:65], 1.0 op_sel_hi:[1,0,0]
	v_pk_mul_f32 v[86:87], v[70:71], v[70:71]
	v_rcp_f32_e32 v82, v66
	v_rcp_f32_e32 v83, v67
	v_mov_b64_e32 v[66:67], s[4:5]
	v_pk_mul_f32 v[86:87], v[86:87], s[76:77] op_sel_hi:[1,0]
	v_cmp_gt_f32_e32 vcc, 0, v70
	v_pk_fma_f32 v[84:85], v[82:83], s[66:67], v[66:67] op_sel_hi:[1,0,0]
	v_exp_f32_e32 v86, v86
	v_pk_fma_f32 v[84:85], v[82:83], v[84:85], s[70:71] op_sel_hi:[1,1,0]
	v_exp_f32_e32 v87, v87
	v_pk_fma_f32 v[84:85], v[82:83], v[84:85], s[72:73] op_sel_hi:[1,1,0]
	v_pk_mul_f32 v[72:73], v[72:73], v[0:1] op_sel_hi:[1,0]
	v_pk_fma_f32 v[84:85], v[82:83], v[84:85], s[74:75] op_sel_hi:[1,1,0]
	v_pk_mul_f32 v[68:69], v[68:69], v[0:1] op_sel_hi:[1,0]
	v_pk_mul_f32 v[82:83], v[82:83], v[84:85]
	v_pk_mul_f32 v[84:85], v[72:73], v[72:73]
	v_pk_mul_f32 v[82:83], v[86:87], v[82:83]
	v_pk_mul_f32 v[84:85], v[84:85], s[76:77] op_sel_hi:[1,0]
	v_pk_mul_f32 v[86:87], v[70:71], v[82:83]
	v_pk_fma_f32 v[82:83], v[70:71], v[82:83], v[70:71] neg_lo:[1,0,0] neg_hi:[1,0,0]
	v_exp_f32_e32 v84, v84
	v_cndmask_b32_e32 v70, v82, v86, vcc
	v_cmp_gt_f32_e32 vcc, 0, v71
	v_and_b32_e32 v82, 0x7fffffff, v72
	v_exp_f32_e32 v85, v85
	v_cndmask_b32_e32 v71, v83, v87, vcc
	v_and_b32_e32 v83, 0x7fffffff, v73
	v_pk_fma_f32 v[82:83], v[82:83], s[64:65], 1.0 op_sel_hi:[1,0,0]
	v_cmp_gt_f32_e32 vcc, 0, v72
	v_rcp_f32_e32 v82, v82
	v_rcp_f32_e32 v83, v83
	v_lshl_add_u64 v[78:79], v[160:161], 1, v[78:79]
	v_pk_mul_f32 v[62:63], v[62:63], v[0:1] op_sel_hi:[1,0]
	v_pk_mul_f32 v[64:65], v[64:65], v[0:1] op_sel_hi:[1,0]
	v_pk_fma_f32 v[86:87], v[82:83], s[66:67], v[66:67] op_sel_hi:[1,0,0]
	v_pk_mul_f32 v[60:61], v[60:61], v[0:1] op_sel_hi:[1,0]
	v_pk_fma_f32 v[86:87], v[82:83], v[86:87], s[70:71] op_sel_hi:[1,1,0]
	s_nop 0
	v_pk_fma_f32 v[86:87], v[82:83], v[86:87], s[72:73] op_sel_hi:[1,1,0]
	s_nop 0
	v_pk_fma_f32 v[86:87], v[82:83], v[86:87], s[74:75] op_sel_hi:[1,1,0]
	s_nop 0
	v_pk_mul_f32 v[82:83], v[82:83], v[86:87]
	v_pk_mul_f32 v[86:87], v[80:81], v[80:81]
	v_pk_mul_f32 v[82:83], v[84:85], v[82:83]
	v_pk_mul_f32 v[86:87], v[86:87], s[76:77] op_sel_hi:[1,0]
	v_pk_mul_f32 v[84:85], v[72:73], v[82:83]
	v_pk_fma_f32 v[82:83], v[72:73], v[82:83], v[72:73] neg_lo:[1,0,0] neg_hi:[1,0,0]
	v_exp_f32_e32 v86, v86
	v_cndmask_b32_e32 v72, v82, v84, vcc
	v_cmp_gt_f32_e32 vcc, 0, v73
	v_and_b32_e32 v82, 0x7fffffff, v80
	v_exp_f32_e32 v87, v87
	v_cndmask_b32_e32 v73, v83, v85, vcc
	v_and_b32_e32 v83, 0x7fffffff, v81
	v_pk_fma_f32 v[82:83], v[82:83], s[64:65], 1.0 op_sel_hi:[1,0,0]
	v_cmp_gt_f32_e32 vcc, 0, v80
	v_rcp_f32_e32 v82, v82
	v_rcp_f32_e32 v83, v83
	s_nop 0
	v_pk_fma_f32 v[84:85], v[82:83], s[66:67], v[66:67] op_sel_hi:[1,0,0]
	s_nop 0
	v_pk_fma_f32 v[84:85], v[82:83], v[84:85], s[70:71] op_sel_hi:[1,1,0]
	s_nop 0
	v_pk_fma_f32 v[84:85], v[82:83], v[84:85], s[72:73] op_sel_hi:[1,1,0]
	s_nop 0
	v_pk_fma_f32 v[84:85], v[82:83], v[84:85], s[74:75] op_sel_hi:[1,1,0]
	s_nop 0
	v_pk_mul_f32 v[82:83], v[82:83], v[84:85]
	v_pk_mul_f32 v[84:85], v[68:69], v[68:69]
	v_pk_mul_f32 v[82:83], v[86:87], v[82:83]
	v_pk_mul_f32 v[84:85], v[84:85], s[76:77] op_sel_hi:[1,0]
	v_pk_mul_f32 v[86:87], v[80:81], v[82:83]
	v_pk_fma_f32 v[82:83], v[80:81], v[82:83], v[80:81] neg_lo:[1,0,0] neg_hi:[1,0,0]
	v_exp_f32_e32 v84, v84
	v_cndmask_b32_e32 v80, v82, v86, vcc
	v_cmp_gt_f32_e32 vcc, 0, v81
	v_and_b32_e32 v82, 0x7fffffff, v68
	v_exp_f32_e32 v85, v85
	v_cndmask_b32_e32 v81, v83, v87, vcc
	v_and_b32_e32 v83, 0x7fffffff, v69
	v_pk_fma_f32 v[82:83], v[82:83], s[64:65], 1.0 op_sel_hi:[1,0,0]
	v_cmp_gt_f32_e32 vcc, 0, v68
	v_rcp_f32_e32 v82, v82
	v_rcp_f32_e32 v83, v83
	s_nop 0
	v_pk_fma_f32 v[86:87], v[82:83], s[66:67], v[66:67] op_sel_hi:[1,0,0]
	s_nop 0
	v_pk_fma_f32 v[86:87], v[82:83], v[86:87], s[70:71] op_sel_hi:[1,1,0]
	s_nop 0
	v_pk_fma_f32 v[86:87], v[82:83], v[86:87], s[72:73] op_sel_hi:[1,1,0]
	s_nop 0
	v_pk_fma_f32 v[86:87], v[82:83], v[86:87], s[74:75] op_sel_hi:[1,1,0]
	s_nop 0
	v_pk_mul_f32 v[82:83], v[82:83], v[86:87]
	v_pk_mul_f32 v[86:87], v[62:63], v[62:63]
	v_pk_mul_f32 v[82:83], v[84:85], v[82:83]
	v_pk_mul_f32 v[86:87], v[86:87], s[76:77] op_sel_hi:[1,0]
	v_pk_mul_f32 v[84:85], v[68:69], v[82:83]
	v_pk_fma_f32 v[82:83], v[68:69], v[82:83], v[68:69] neg_lo:[1,0,0] neg_hi:[1,0,0]
	v_exp_f32_e32 v86, v86
	v_cndmask_b32_e32 v68, v82, v84, vcc
	v_cmp_gt_f32_e32 vcc, 0, v69
	v_cvt_pk_bf16_f32 v82, v70, v71
	v_exp_f32_e32 v87, v87
	s_nop 0
	v_cndmask_b32_e32 v69, v83, v85, vcc
	v_cvt_pk_bf16_f32 v83, v72, v73
	v_cvt_pk_bf16_f32 v84, v80, v81
	v_cvt_pk_bf16_f32 v85, v68, v69
	global_store_dwordx4 v[78:79], v[82:85], off
	v_cmp_gt_f32_e32 vcc, 0, v62
	s_nop 0
	v_pk_mul_f32 v[82:83], v[58:59], v[0:1] op_sel_hi:[1,0]
	v_and_b32_e32 v59, 0x7fffffff, v63
	v_and_b32_e32 v58, 0x7fffffff, v62
	v_pk_fma_f32 v[58:59], v[58:59], s[64:65], 1.0 op_sel_hi:[1,0,0]
	s_nop 0
	v_rcp_f32_e32 v58, v58
	v_rcp_f32_e32 v59, v59
	s_nop 0
	v_pk_fma_f32 v[84:85], v[58:59], s[66:67], v[66:67] op_sel_hi:[1,0,0]
	s_nop 0
	v_pk_fma_f32 v[84:85], v[58:59], v[84:85], s[70:71] op_sel_hi:[1,1,0]
	s_nop 0
	v_pk_fma_f32 v[84:85], v[58:59], v[84:85], s[72:73] op_sel_hi:[1,1,0]
; __device__ __forceinline__ unsigned cvt_pk_bf16(float lo, float hi) { unsigned r; asm volatile("v_cvt_pk_bf16_f32 %0, %1, %2" : "=v"(r) : "v"(lo), "v"(hi)); return r; }
; __device__ __forceinline__ f32x2 gelu_pk(f32x2 v) {
;     const f32x2 av = __builtin_elementwise_abs(v), d = av * 0.2316418882f + 1.0f;
;     f32x2 t; t.x = __builtin_amdgcn_rcpf(d.x); t.y = __builtin_amdgcn_rcpf(d.y);
;     f32x2 q = t * 0.5307027145f + (-0.7265760135f); q = q * t + 0.7107068705f; q = q * t + (-0.142248368f); q = q * t + 0.127414796f; q = q * t;
;     const f32x2 s = (v * v) * (-0.72134752044f);
;     f32x2 e; e.x = __builtin_amdgcn_exp2f(s.x); e.y = __builtin_amdgcn_exp2f(s.y);
;     const f32x2 m = v * (q * e), r = v - m;
;     f32x2 o; o.x = v.x < 0.f ? m.x : r.x; o.y = v.y < 0.f ? m.y : r.y; return o;
; }
;     __device__ __forceinline__ void operator()(const f32x4 (&acc)[2][2][4][2], const Unit& u, int wr, int wc, int fr, int fq) const {
;     ...
;             for (int m = 0; m < 4; ++m) { const int row = row0 + ai * HALF + m * 16; const float rs = rsv[ai][m]; bf16_t* rowp = O + (size_t)row * ldc + col0; float s1 = 0.f, s2 = 0.f;
; #pragma unroll
;                 for (int bj = 0; bj < 2; ++bj) { f32x4 v0 = acc[ai][bj][m][0] * rs, v1 = acc[ai][bj][m][1] * rs;
;                     const f32x2 a = gelu_pk((f32x2){v0[0], v0[1]}), b = gelu_pk((f32x2){v0[2], v0[3]}), c = gelu_pk((f32x2){v1[0], v1[1]}), d = gelu_pk((f32x2){v1[2], v1[3]});
;                     s1 += ((a.x + a.y) + (b.x + b.y)) + ((c.x + c.y) + (d.x + d.y));
;                     s2 += ((a.x * a.x + a.y * a.y) + (b.x * b.x + b.y * b.y)) + ((c.x * c.x + c.y * c.y) + (d.x * d.x + d.y * d.y));
;                     u32x4 w; w.x = cvt_pk_bf16(a.x, a.y); w.y = cvt_pk_bf16(b.x, b.y); w.z = cvt_pk_bf16(c.x, c.y); w.w = cvt_pk_bf16(d.x, d.y);
;                     *(u32x4*)(rowp + bj * HALF) = w; }
;                 if (isv) { s1 += __shfl_xor(s1, 16); s1 += __shfl_xor(s1, 32); s2 += __shfl_xor(s2, 16); s2 += __shfl_xor(s2, 32);
;                     if (fq == 0) { const int rl = ai * HALF + wr * 64 + m * 16 + fr; part[rl * 4 + wc] = s1; part[1024 + rl * 4 + wc] = s2; } } }
	s_nop 0
	v_pk_fma_f32 v[84:85], v[58:59], v[84:85], s[74:75] op_sel_hi:[1,1,0]
	s_nop 0
	v_pk_mul_f32 v[58:59], v[58:59], v[84:85]
	v_pk_mul_f32 v[84:85], v[64:65], v[64:65]
	v_pk_mul_f32 v[58:59], v[86:87], v[58:59]
	v_pk_mul_f32 v[84:85], v[84:85], s[76:77] op_sel_hi:[1,0]
	v_pk_mul_f32 v[86:87], v[62:63], v[58:59]
	v_pk_fma_f32 v[58:59], v[62:63], v[58:59], v[62:63] neg_lo:[1,0,0] neg_hi:[1,0,0]
	v_and_b32_e32 v62, 0x7fffffff, v64
	v_cndmask_b32_e32 v0, v58, v86, vcc
	v_cmp_gt_f32_e32 vcc, 0, v63
	v_and_b32_e32 v63, 0x7fffffff, v65
	v_pk_fma_f32 v[62:63], v[62:63], s[64:65], 1.0 op_sel_hi:[1,0,0]
	v_cndmask_b32_e32 v58, v59, v87, vcc
	v_rcp_f32_e32 v62, v62
	v_rcp_f32_e32 v63, v63
	v_exp_f32_e32 v84, v84
	v_exp_f32_e32 v85, v85
	v_cmp_gt_f32_e32 vcc, 0, v64
	v_pk_fma_f32 v[86:87], v[62:63], s[66:67], v[66:67] op_sel_hi:[1,0,0]
	s_nop 0
	v_pk_fma_f32 v[86:87], v[62:63], v[86:87], s[70:71] op_sel_hi:[1,1,0]
	s_nop 0
	v_pk_fma_f32 v[86:87], v[62:63], v[86:87], s[72:73] op_sel_hi:[1,1,0]
	s_nop 0
	v_pk_fma_f32 v[86:87], v[62:63], v[86:87], s[74:75] op_sel_hi:[1,1,0]
	s_nop 0
	v_pk_mul_f32 v[62:63], v[62:63], v[86:87]
	v_pk_mul_f32 v[86:87], v[82:83], v[82:83]
	v_pk_mul_f32 v[62:63], v[84:85], v[62:63]
	v_pk_mul_f32 v[86:87], v[86:87], s[76:77] op_sel_hi:[1,0]
	v_pk_mul_f32 v[84:85], v[64:65], v[62:63]
	v_pk_fma_f32 v[62:63], v[64:65], v[62:63], v[64:65] neg_lo:[1,0,0] neg_hi:[1,0,0]
	v_and_b32_e32 v64, 0x7fffffff, v82
	v_cndmask_b32_e32 v59, v62, v84, vcc
	v_cmp_gt_f32_e32 vcc, 0, v65
	v_and_b32_e32 v65, 0x7fffffff, v83
	v_pk_fma_f32 v[64:65], v[64:65], s[64:65], 1.0 op_sel_hi:[1,0,0]
	v_cndmask_b32_e32 v62, v63, v85, vcc
	v_rcp_f32_e32 v64, v64
	v_rcp_f32_e32 v65, v65
	v_exp_f32_e32 v86, v86
	v_exp_f32_e32 v87, v87
	v_cmp_gt_f32_e32 vcc, 0, v82
	v_pk_fma_f32 v[84:85], v[64:65], s[66:67], v[66:67] op_sel_hi:[1,0,0]
	s_nop 0
	v_pk_fma_f32 v[84:85], v[64:65], v[84:85], s[70:71] op_sel_hi:[1,1,0]
	s_nop 0
	v_pk_fma_f32 v[84:85], v[64:65], v[84:85], s[72:73] op_sel_hi:[1,1,0]
	s_nop 0
	v_pk_fma_f32 v[84:85], v[64:65], v[84:85], s[74:75] op_sel_hi:[1,1,0]
	s_nop 0
	v_pk_mul_f32 v[64:65], v[64:65], v[84:85]
	v_pk_mul_f32 v[84:85], v[60:61], v[60:61]
	v_pk_mul_f32 v[64:65], v[86:87], v[64:65]
	s_nop 0
	v_pk_mul_f32 v[86:87], v[82:83], v[64:65]
	v_pk_fma_f32 v[64:65], v[82:83], v[64:65], v[82:83] neg_lo:[1,0,0] neg_hi:[1,0,0]
	v_and_b32_e32 v82, 0x7fffffff, v60
	v_cndmask_b32_e32 v63, v64, v86, vcc
	v_cmp_gt_f32_e32 vcc, 0, v83
	v_and_b32_e32 v83, 0x7fffffff, v61
	v_pk_fma_f32 v[82:83], v[82:83], s[64:65], 1.0 op_sel_hi:[1,0,0]
	v_cndmask_b32_e32 v64, v65, v87, vcc
	v_rcp_f32_e32 v82, v82
	v_rcp_f32_e32 v83, v83
	v_cmp_gt_f32_e32 vcc, 0, v60
	v_pk_fma_f32 v[66:67], v[82:83], s[66:67], v[66:67] op_sel_hi:[1,0,0]
	s_nop 0
	v_pk_fma_f32 v[66:67], v[82:83], v[66:67], s[70:71] op_sel_hi:[1,1,0]
	s_nop 0
	v_pk_fma_f32 v[66:67], v[82:83], v[66:67], s[72:73] op_sel_hi:[1,1,0]
	s_nop 0
	v_pk_fma_f32 v[66:67], v[82:83], v[66:67], s[74:75] op_sel_hi:[1,1,0]
	s_nop 0
	v_pk_mul_f32 v[66:67], v[82:83], v[66:67]
	v_pk_mul_f32 v[82:83], v[84:85], s[76:77] op_sel_hi:[1,0]
	s_nop 0
	v_exp_f32_e32 v82, v82
	v_exp_f32_e32 v83, v83
	s_nop 0
	v_pk_mul_f32 v[66:67], v[82:83], v[66:67]
	s_nop 0
	v_pk_mul_f32 v[82:83], v[60:61], v[66:67]
	v_pk_fma_f32 v[66:67], v[60:61], v[66:67], v[60:61] neg_lo:[1,0,0] neg_hi:[1,0,0]
	s_nop 0
	v_cndmask_b32_e32 v60, v66, v82, vcc
	v_cmp_gt_f32_e32 vcc, 0, v61
	v_cvt_pk_bf16_f32 v82, v0, v58
	s_nop 1
	v_cndmask_b32_e32 v61, v67, v83, vcc
	s_and_b64 vcc, exec, s[10:11]
	v_cvt_pk_bf16_f32 v83, v59, v62
	v_cvt_pk_bf16_f32 v84, v63, v64
	v_cvt_pk_bf16_f32 v85, v60, v61
	global_store_dwordx4 v[78:79], v[82:85], off offset:256
	s_cbranch_vccnz .LBB0_372
	v_mul_f32_e32 v65, v71, v71
	v_mul_f32_e32 v66, v73, v73
	v_fmac_f32_e32 v65, v70, v70
	v_fmac_f32_e32 v66, v72, v72
	v_add_f32_e32 v65, v65, v66
	v_mul_f32_e32 v66, v81, v81
	v_mul_f32_e32 v67, v69, v69
	v_fmac_f32_e32 v66, v80, v80
	v_fmac_f32_e32 v67, v68, v68
	v_add_f32_e32 v66, v66, v67
	v_add_f32_e32 v65, v65, v66
	v_mul_f32_e32 v66, v58, v58
	v_fmac_f32_e32 v66, v0, v0
	v_mul_f32_e32 v67, v62, v62
	v_add_f32_e32 v0, v0, v58
	v_add_f32_e32 v58, v59, v62
	v_fmac_f32_e32 v67, v59, v59
	v_add_f32_e32 v70, v70, v71
	v_add_f32_e32 v71, v72, v73
	v_add_f32_e32 v0, v0, v58
	v_add_f32_e32 v58, v63, v64
	v_add_f32_e32 v59, v60, v61
	v_add_f32_e32 v70, v70, v71
	v_add_f32_e32 v71, v80, v81
	v_add_f32_e32 v68, v68, v69
	v_add_f32_e32 v58, v58, v59
	v_and_b32_e32 v59, 64, v226
	v_add_f32_e32 v68, v71, v68
	v_add_f32_e32 v0, v0, v58
	v_xor_b32_e32 v58, 16, v226
	v_add_u32_e32 v59, 64, v59
	v_add_f32_e32 v68, v70, v68
	v_cmp_lt_i32_e32 vcc, v58, v59
	v_add_f32_e32 v66, v66, v67
	v_mul_f32_e32 v67, v64, v64
	v_mul_f32_e32 v78, v61, v61
	v_add_f32_e32 v68, 0, v68
	v_cndmask_b32_e32 v58, v226, v58, vcc
	v_fmac_f32_e32 v67, v63, v63
	v_add_f32_e32 v0, v0, v68
	v_lshlrev_b32_e32 v58, 2, v58
	v_fmac_f32_e32 v78, v60, v60
	ds_bpermute_b32 v61, v58, v0
	v_add_f32_e32 v60, v67, v78
	v_add_f32_e32 v60, v66, v60
	v_add_f32_e32 v60, v65, v60
	ds_bpermute_b32 v62, v58, v60
	s_waitcnt lgkmcnt(0)
	v_add_f32_e32 v0, v0, v61
	v_xor_b32_e32 v61, 32, v226
	v_cmp_lt_i32_e32 vcc, v61, v59
	v_add_f32_e32 v59, v60, v62
	s_nop 0
	v_cndmask_b32_e32 v58, v226, v61, vcc
	v_lshlrev_b32_e32 v61, 2, v58
	ds_bpermute_b32 v58, v61, v0
	ds_bpermute_b32 v60, v61, v59
	s_and_saveexec_b64 s[4:5], s[6:7]
	s_cbranch_execz .LBB0_371
	s_waitcnt lgkmcnt(0)
	v_add_f32_e32 v59, v59, v60
	v_add_f32_e32 v0, v0, v58
	ds_write2st64_b32 v186, v0, v59 offset0:8 offset1:24

; __device__ __forceinline__ unsigned cvt_pk_bf16(float lo, float hi) { unsigned r; asm volatile("v_cvt_pk_bf16_f32 %0, %1, %2" : "=v"(r) : "v"(lo), "v"(hi)); return r; }
; __device__ __forceinline__ f32x2 gelu_pk(f32x2 v) {
;     const f32x2 av = __builtin_elementwise_abs(v), d = av * 0.2316418882f + 1.0f;
;     f32x2 t; t.x = __builtin_amdgcn_rcpf(d.x); t.y = __builtin_amdgcn_rcpf(d.y);
;     f32x2 q = t * 0.5307027145f + (-0.7265760135f); q = q * t + 0.7107068705f; q = q * t + (-0.142248368f); q = q * t + 0.127414796f; q = q * t;
;     const f32x2 s = (v * v) * (-0.72134752044f);
;     f32x2 e; e.x = __builtin_amdgcn_exp2f(s.x); e.y = __builtin_amdgcn_exp2f(s.y);
;     const f32x2 m = v * (q * e), r = v - m;
;     f32x2 o; o.x = v.x < 0.f ? m.x : r.x; o.y = v.y < 0.f ? m.y : r.y; return o;
; }
;     __device__ __forceinline__ void operator()(const f32x4 (&acc)[2][2][4][2], const Unit& u, int wr, int wc, int fr, int fq) const {
;     ...
;             for (int m = 0; m < 4; ++m) { const int row = row0 + ai * HALF + m * 16; const float rs = rsv[ai][m]; bf16_t* rowp = O + (size_t)row * ldc + col0; float s1 = 0.f, s2 = 0.f;
; #pragma unroll
;                 for (int bj = 0; bj < 2; ++bj) { f32x4 v0 = acc[ai][bj][m][0] * rs, v1 = acc[ai][bj][m][1] * rs;
;                     const f32x2 a = gelu_pk((f32x2){v0[0], v0[1]}), b = gelu_pk((f32x2){v0[2], v0[3]}), c = gelu_pk((f32x2){v1[0], v1[1]}), d = gelu_pk((f32x2){v1[2], v1[3]});
;                     s1 += ((a.x + a.y) + (b.x + b.y)) + ((c.x + c.y) + (d.x + d.y));
;                     s2 += ((a.x * a.x + a.y * a.y) + (b.x * b.x + b.y * b.y)) + ((c.x * c.x + c.y * c.y) + (d.x * d.x + d.y * d.y));
;                     u32x4 w; w.x = cvt_pk_bf16(a.x, a.y); w.y = cvt_pk_bf16(b.x, b.y); w.z = cvt_pk_bf16(c.x, c.y); w.w = cvt_pk_bf16(d.x, d.y);
;                     *(u32x4*)(rowp + bj * HALF) = w; }
;                 if (isv) { s1 += __shfl_xor(s1, 16); s1 += __shfl_xor(s1, 32); s2 += __shfl_xor(s2, 16); s2 += __shfl_xor(s2, 32);
;                     if (fq == 0) { const int rl = ai * HALF + wr * 64 + m * 16 + fr; part[rl * 4 + wc] = s1; part[1024 + rl * 4 + wc] = s2; } } }
.LBB0_372:
	v_add_f32_e32 v0, v74, v75
	s_waitcnt lgkmcnt(0)
	v_add_f32_e32 v58, v76, v77
	v_add_f32_e32 v0, v0, v58
	v_fmamk_f32 v0, v0, 0x3a800000, v224
	v_rsq_f32_e32 v0, v0
	s_mov_b32 s4, 0xbf3a00e3
	v_lshlrev_b64 v[58:59], 12, v[166:167]
	v_lshl_add_u64 v[58:59], s[20:21], 0, v[58:59]
	v_pk_mul_f32 v[50:51], v[50:51], v[0:1] op_sel_hi:[1,0]
	v_pk_mul_f32 v[60:61], v[46:47], v[0:1] op_sel_hi:[1,0]
	v_and_b32_e32 v47, 0x7fffffff, v51
	v_and_b32_e32 v46, 0x7fffffff, v50
	v_pk_fma_f32 v[46:47], v[46:47], s[64:65], 1.0 op_sel_hi:[1,0,0]
	v_pk_mul_f32 v[66:67], v[50:51], v[50:51]
	v_rcp_f32_e32 v62, v46
	v_rcp_f32_e32 v63, v47
	v_mov_b64_e32 v[46:47], s[4:5]
	v_pk_mul_f32 v[66:67], v[66:67], s[76:77] op_sel_hi:[1,0]
	v_cmp_gt_f32_e32 vcc, 0, v50
	v_pk_fma_f32 v[64:65], v[62:63], s[66:67], v[46:47] op_sel_hi:[1,0,0]
	v_exp_f32_e32 v66, v66
	v_pk_fma_f32 v[64:65], v[62:63], v[64:65], s[70:71] op_sel_hi:[1,1,0]
	v_exp_f32_e32 v67, v67
	v_pk_fma_f32 v[64:65], v[62:63], v[64:65], s[72:73] op_sel_hi:[1,1,0]
	v_pk_mul_f32 v[52:53], v[52:53], v[0:1] op_sel_hi:[1,0]
	v_pk_fma_f32 v[64:65], v[62:63], v[64:65], s[74:75] op_sel_hi:[1,1,0]
	v_pk_mul_f32 v[48:49], v[48:49], v[0:1] op_sel_hi:[1,0]
	v_pk_mul_f32 v[62:63], v[62:63], v[64:65]
	v_pk_mul_f32 v[64:65], v[52:53], v[52:53]
	v_pk_mul_f32 v[62:63], v[66:67], v[62:63]
	v_pk_mul_f32 v[64:65], v[64:65], s[76:77] op_sel_hi:[1,0]
	v_pk_mul_f32 v[66:67], v[50:51], v[62:63]
	v_pk_fma_f32 v[62:63], v[50:51], v[62:63], v[50:51] neg_lo:[1,0,0] neg_hi:[1,0,0]
	v_exp_f32_e32 v64, v64
	v_cndmask_b32_e32 v50, v62, v66, vcc
	v_cmp_gt_f32_e32 vcc, 0, v51
	v_and_b32_e32 v62, 0x7fffffff, v52
	v_exp_f32_e32 v65, v65
	v_cndmask_b32_e32 v51, v63, v67, vcc
	v_and_b32_e32 v63, 0x7fffffff, v53
	v_pk_fma_f32 v[62:63], v[62:63], s[64:65], 1.0 op_sel_hi:[1,0,0]
	v_cmp_gt_f32_e32 vcc, 0, v52
	v_rcp_f32_e32 v62, v62
	v_rcp_f32_e32 v63, v63
	v_lshl_add_u64 v[58:59], v[160:161], 1, v[58:59]
	v_pk_mul_f32 v[42:43], v[42:43], v[0:1] op_sel_hi:[1,0]
	v_pk_mul_f32 v[44:45], v[44:45], v[0:1] op_sel_hi:[1,0]
	v_pk_fma_f32 v[66:67], v[62:63], s[66:67], v[46:47] op_sel_hi:[1,0,0]
	v_pk_mul_f32 v[40:41], v[40:41], v[0:1] op_sel_hi:[1,0]
	v_pk_fma_f32 v[66:67], v[62:63], v[66:67], s[70:71] op_sel_hi:[1,1,0]
	s_nop 0
	v_pk_fma_f32 v[66:67], v[62:63], v[66:67], s[72:73] op_sel_hi:[1,1,0]
	s_nop 0
	v_pk_fma_f32 v[66:67], v[62:63], v[66:67], s[74:75] op_sel_hi:[1,1,0]
	s_nop 0
	v_pk_mul_f32 v[62:63], v[62:63], v[66:67]
	v_pk_mul_f32 v[66:67], v[60:61], v[60:61]
	v_pk_mul_f32 v[62:63], v[64:65], v[62:63]
	v_pk_mul_f32 v[66:67], v[66:67], s[76:77] op_sel_hi:[1,0]
	v_pk_mul_f32 v[64:65], v[52:53], v[62:63]
	v_pk_fma_f32 v[62:63], v[52:53], v[62:63], v[52:53] neg_lo:[1,0,0] neg_hi:[1,0,0]
	v_exp_f32_e32 v66, v66
	v_cndmask_b32_e32 v52, v62, v64, vcc
	v_cmp_gt_f32_e32 vcc, 0, v53
	v_and_b32_e32 v62, 0x7fffffff, v60
	v_exp_f32_e32 v67, v67
	v_cndmask_b32_e32 v53, v63, v65, vcc
	v_and_b32_e32 v63, 0x7fffffff, v61
	v_pk_fma_f32 v[62:63], v[62:63], s[64:65], 1.0 op_sel_hi:[1,0,0]
	v_cmp_gt_f32_e32 vcc, 0, v60
	v_rcp_f32_e32 v62, v62
	v_rcp_f32_e32 v63, v63
	s_nop 0
	v_pk_fma_f32 v[64:65], v[62:63], s[66:67], v[46:47] op_sel_hi:[1,0,0]
	s_nop 0
	v_pk_fma_f32 v[64:65], v[62:63], v[64:65], s[70:71] op_sel_hi:[1,1,0]
	s_nop 0
	v_pk_fma_f32 v[64:65], v[62:63], v[64:65], s[72:73] op_sel_hi:[1,1,0]
	s_nop 0
	v_pk_fma_f32 v[64:65], v[62:63], v[64:65], s[74:75] op_sel_hi:[1,1,0]
	s_nop 0
	v_pk_mul_f32 v[62:63], v[62:63], v[64:65]
	v_pk_mul_f32 v[64:65], v[48:49], v[48:49]
	v_pk_mul_f32 v[62:63], v[66:67], v[62:63]
	v_pk_mul_f32 v[64:65], v[64:65], s[76:77] op_sel_hi:[1,0]
	v_pk_mul_f32 v[66:67], v[60:61], v[62:63]
	v_pk_fma_f32 v[62:63], v[60:61], v[62:63], v[60:61] neg_lo:[1,0,0] neg_hi:[1,0,0]
	v_exp_f32_e32 v64, v64
	v_cndmask_b32_e32 v60, v62, v66, vcc
	v_cmp_gt_f32_e32 vcc, 0, v61
	v_and_b32_e32 v62, 0x7fffffff, v48
	v_exp_f32_e32 v65, v65
	v_cndmask_b32_e32 v61, v63, v67, vcc
	v_and_b32_e32 v63, 0x7fffffff, v49
	v_pk_fma_f32 v[62:63], v[62:63], s[64:65], 1.0 op_sel_hi:[1,0,0]
	v_cmp_gt_f32_e32 vcc, 0, v48
	v_rcp_f32_e32 v62, v62
	v_rcp_f32_e32 v63, v63
	s_nop 0
	v_pk_fma_f32 v[66:67], v[62:63], s[66:67], v[46:47] op_sel_hi:[1,0,0]
	s_nop 0
	v_pk_fma_f32 v[66:67], v[62:63], v[66:67], s[70:71] op_sel_hi:[1,1,0]
	s_nop 0
	v_pk_fma_f32 v[66:67], v[62:63], v[66:67], s[72:73] op_sel_hi:[1,1,0]
	s_nop 0
	v_pk_fma_f32 v[66:67], v[62:63], v[66:67], s[74:75] op_sel_hi:[1,1,0]
	s_nop 0
	v_pk_mul_f32 v[62:63], v[62:63], v[66:67]
	v_pk_mul_f32 v[66:67], v[42:43], v[42:43]
	v_pk_mul_f32 v[62:63], v[64:65], v[62:63]
	v_pk_mul_f32 v[66:67], v[66:67], s[76:77] op_sel_hi:[1,0]
	v_pk_mul_f32 v[64:65], v[48:49], v[62:63]
	v_pk_fma_f32 v[62:63], v[48:49], v[62:63], v[48:49] neg_lo:[1,0,0] neg_hi:[1,0,0]
	v_exp_f32_e32 v66, v66
	v_cndmask_b32_e32 v48, v62, v64, vcc
	v_cmp_gt_f32_e32 vcc, 0, v49
	v_cvt_pk_bf16_f32 v62, v50, v51
	v_exp_f32_e32 v67, v67
	s_nop 0
	v_cndmask_b32_e32 v49, v63, v65, vcc
	v_cvt_pk_bf16_f32 v63, v52, v53
	v_cvt_pk_bf16_f32 v64, v60, v61
	v_cvt_pk_bf16_f32 v65, v48, v49
	global_store_dwordx4 v[58:59], v[62:65], off
	v_cmp_gt_f32_e32 vcc, 0, v42
	s_nop 0
	v_pk_mul_f32 v[62:63], v[38:39], v[0:1] op_sel_hi:[1,0]
	v_and_b32_e32 v39, 0x7fffffff, v43
	v_and_b32_e32 v38, 0x7fffffff, v42
	v_pk_fma_f32 v[38:39], v[38:39], s[64:65], 1.0 op_sel_hi:[1,0,0]
	s_nop 0
	v_rcp_f32_e32 v38, v38
	v_rcp_f32_e32 v39, v39
	s_nop 0
	v_pk_fma_f32 v[64:65], v[38:39], s[66:67], v[46:47] op_sel_hi:[1,0,0]
	s_nop 0
	v_pk_fma_f32 v[64:65], v[38:39], v[64:65], s[70:71] op_sel_hi:[1,1,0]
	s_nop 0
	v_pk_fma_f32 v[64:65], v[38:39], v[64:65], s[72:73] op_sel_hi:[1,1,0]
; __device__ __forceinline__ unsigned cvt_pk_bf16(float lo, float hi) { unsigned r; asm volatile("v_cvt_pk_bf16_f32 %0, %1, %2" : "=v"(r) : "v"(lo), "v"(hi)); return r; }
; __device__ __forceinline__ f32x2 gelu_pk(f32x2 v) {
;     const f32x2 av = __builtin_elementwise_abs(v), d = av * 0.2316418882f + 1.0f;
;     f32x2 t; t.x = __builtin_amdgcn_rcpf(d.x); t.y = __builtin_amdgcn_rcpf(d.y);
;     f32x2 q = t * 0.5307027145f + (-0.7265760135f); q = q * t + 0.7107068705f; q = q * t + (-0.142248368f); q = q * t + 0.127414796f; q = q * t;
;     const f32x2 s = (v * v) * (-0.72134752044f);
;     f32x2 e; e.x = __builtin_amdgcn_exp2f(s.x); e.y = __builtin_amdgcn_exp2f(s.y);
;     const f32x2 m = v * (q * e), r = v - m;
;     f32x2 o; o.x = v.x < 0.f ? m.x : r.x; o.y = v.y < 0.f ? m.y : r.y; return o;
; }
;     __device__ __forceinline__ void operator()(const f32x4 (&acc)[2][2][4][2], const Unit& u, int wr, int wc, int fr, int fq) const {
;     ...
;             for (int m = 0; m < 4; ++m) { const int row = row0 + ai * HALF + m * 16; const float rs = rsv[ai][m]; bf16_t* rowp = O + (size_t)row * ldc + col0; float s1 = 0.f, s2 = 0.f;
; #pragma unroll
;                 for (int bj = 0; bj < 2; ++bj) { f32x4 v0 = acc[ai][bj][m][0] * rs, v1 = acc[ai][bj][m][1] * rs;
;                     const f32x2 a = gelu_pk((f32x2){v0[0], v0[1]}), b = gelu_pk((f32x2){v0[2], v0[3]}), c = gelu_pk((f32x2){v1[0], v1[1]}), d = gelu_pk((f32x2){v1[2], v1[3]});
;                     s1 += ((a.x + a.y) + (b.x + b.y)) + ((c.x + c.y) + (d.x + d.y));
;                     s2 += ((a.x * a.x + a.y * a.y) + (b.x * b.x + b.y * b.y)) + ((c.x * c.x + c.y * c.y) + (d.x * d.x + d.y * d.y));
;                     u32x4 w; w.x = cvt_pk_bf16(a.x, a.y); w.y = cvt_pk_bf16(b.x, b.y); w.z = cvt_pk_bf16(c.x, c.y); w.w = cvt_pk_bf16(d.x, d.y);
;                     *(u32x4*)(rowp + bj * HALF) = w; }
;                 if (isv) { s1 += __shfl_xor(s1, 16); s1 += __shfl_xor(s1, 32); s2 += __shfl_xor(s2, 16); s2 += __shfl_xor(s2, 32);
;                     if (fq == 0) { const int rl = ai * HALF + wr * 64 + m * 16 + fr; part[rl * 4 + wc] = s1; part[1024 + rl * 4 + wc] = s2; } } }
	s_nop 0
	v_pk_fma_f32 v[64:65], v[38:39], v[64:65], s[74:75] op_sel_hi:[1,1,0]
	s_nop 0
	v_pk_mul_f32 v[38:39], v[38:39], v[64:65]
	v_pk_mul_f32 v[64:65], v[44:45], v[44:45]
	v_pk_mul_f32 v[38:39], v[66:67], v[38:39]
	v_pk_mul_f32 v[64:65], v[64:65], s[76:77] op_sel_hi:[1,0]
	v_pk_mul_f32 v[66:67], v[42:43], v[38:39]
	v_pk_fma_f32 v[38:39], v[42:43], v[38:39], v[42:43] neg_lo:[1,0,0] neg_hi:[1,0,0]
	v_and_b32_e32 v42, 0x7fffffff, v44
	v_cndmask_b32_e32 v0, v38, v66, vcc
	v_cmp_gt_f32_e32 vcc, 0, v43
	v_and_b32_e32 v43, 0x7fffffff, v45
	v_pk_fma_f32 v[42:43], v[42:43], s[64:65], 1.0 op_sel_hi:[1,0,0]
	v_cndmask_b32_e32 v38, v39, v67, vcc
	v_rcp_f32_e32 v42, v42
	v_rcp_f32_e32 v43, v43
	v_exp_f32_e32 v64, v64
	v_exp_f32_e32 v65, v65
	v_cmp_gt_f32_e32 vcc, 0, v44
	v_pk_fma_f32 v[66:67], v[42:43], s[66:67], v[46:47] op_sel_hi:[1,0,0]
	s_nop 0
	v_pk_fma_f32 v[66:67], v[42:43], v[66:67], s[70:71] op_sel_hi:[1,1,0]
	s_nop 0
	v_pk_fma_f32 v[66:67], v[42:43], v[66:67], s[72:73] op_sel_hi:[1,1,0]
	s_nop 0
	v_pk_fma_f32 v[66:67], v[42:43], v[66:67], s[74:75] op_sel_hi:[1,1,0]
	s_nop 0
	v_pk_mul_f32 v[42:43], v[42:43], v[66:67]
	v_pk_mul_f32 v[66:67], v[62:63], v[62:63]
	v_pk_mul_f32 v[42:43], v[64:65], v[42:43]
	v_pk_mul_f32 v[66:67], v[66:67], s[76:77] op_sel_hi:[1,0]
	v_pk_mul_f32 v[64:65], v[44:45], v[42:43]
	v_pk_fma_f32 v[42:43], v[44:45], v[42:43], v[44:45] neg_lo:[1,0,0] neg_hi:[1,0,0]
	v_and_b32_e32 v44, 0x7fffffff, v62
	v_cndmask_b32_e32 v39, v42, v64, vcc
	v_cmp_gt_f32_e32 vcc, 0, v45
	v_and_b32_e32 v45, 0x7fffffff, v63
	v_pk_fma_f32 v[44:45], v[44:45], s[64:65], 1.0 op_sel_hi:[1,0,0]
	v_cndmask_b32_e32 v42, v43, v65, vcc
	v_rcp_f32_e32 v44, v44
	v_rcp_f32_e32 v45, v45
	v_exp_f32_e32 v66, v66
	v_exp_f32_e32 v67, v67
	v_cmp_gt_f32_e32 vcc, 0, v62
	v_pk_fma_f32 v[64:65], v[44:45], s[66:67], v[46:47] op_sel_hi:[1,0,0]
	s_nop 0
	v_pk_fma_f32 v[64:65], v[44:45], v[64:65], s[70:71] op_sel_hi:[1,1,0]
	s_nop 0
	v_pk_fma_f32 v[64:65], v[44:45], v[64:65], s[72:73] op_sel_hi:[1,1,0]
	s_nop 0
	v_pk_fma_f32 v[64:65], v[44:45], v[64:65], s[74:75] op_sel_hi:[1,1,0]
	s_nop 0
	v_pk_mul_f32 v[44:45], v[44:45], v[64:65]
	v_pk_mul_f32 v[64:65], v[40:41], v[40:41]
	v_pk_mul_f32 v[44:45], v[66:67], v[44:45]
	s_nop 0
	v_pk_mul_f32 v[66:67], v[62:63], v[44:45]
	v_pk_fma_f32 v[44:45], v[62:63], v[44:45], v[62:63] neg_lo:[1,0,0] neg_hi:[1,0,0]
	v_and_b32_e32 v62, 0x7fffffff, v40
	v_cndmask_b32_e32 v43, v44, v66, vcc
	v_cmp_gt_f32_e32 vcc, 0, v63
	v_and_b32_e32 v63, 0x7fffffff, v41
	v_pk_fma_f32 v[62:63], v[62:63], s[64:65], 1.0 op_sel_hi:[1,0,0]
	v_cndmask_b32_e32 v44, v45, v67, vcc
	v_rcp_f32_e32 v62, v62
	v_rcp_f32_e32 v63, v63
	v_cmp_gt_f32_e32 vcc, 0, v40
	v_pk_fma_f32 v[46:47], v[62:63], s[66:67], v[46:47] op_sel_hi:[1,0,0]
	s_nop 0
	v_pk_fma_f32 v[46:47], v[62:63], v[46:47], s[70:71] op_sel_hi:[1,1,0]
	s_nop 0
	v_pk_fma_f32 v[46:47], v[62:63], v[46:47], s[72:73] op_sel_hi:[1,1,0]
	s_nop 0
	v_pk_fma_f32 v[46:47], v[62:63], v[46:47], s[74:75] op_sel_hi:[1,1,0]
	s_nop 0
	v_pk_mul_f32 v[46:47], v[62:63], v[46:47]
	v_pk_mul_f32 v[62:63], v[64:65], s[76:77] op_sel_hi:[1,0]
	s_nop 0
	v_exp_f32_e32 v62, v62
	v_exp_f32_e32 v63, v63
	s_nop 0
	v_pk_mul_f32 v[46:47], v[62:63], v[46:47]
	s_nop 0
	v_pk_mul_f32 v[62:63], v[40:41], v[46:47]
	v_pk_fma_f32 v[46:47], v[40:41], v[46:47], v[40:41] neg_lo:[1,0,0] neg_hi:[1,0,0]
	s_nop 0
	v_cndmask_b32_e32 v40, v46, v62, vcc
	v_cmp_gt_f32_e32 vcc, 0, v41
	v_cvt_pk_bf16_f32 v62, v0, v38
	s_nop 1
	v_cndmask_b32_e32 v41, v47, v63, vcc
	s_and_b64 vcc, exec, s[10:11]
	v_cvt_pk_bf16_f32 v63, v39, v42
	v_cvt_pk_bf16_f32 v64, v43, v44
	v_cvt_pk_bf16_f32 v65, v40, v41
	global_store_dwordx4 v[58:59], v[62:65], off offset:256
	s_cbranch_vccnz .LBB0_376
	v_mul_f32_e32 v45, v51, v51
	v_mul_f32_e32 v46, v53, v53
	v_fmac_f32_e32 v45, v50, v50
	v_fmac_f32_e32 v46, v52, v52
	v_add_f32_e32 v45, v45, v46
	v_mul_f32_e32 v46, v61, v61
	v_mul_f32_e32 v47, v49, v49
	v_fmac_f32_e32 v46, v60, v60
	v_fmac_f32_e32 v47, v48, v48
	v_add_f32_e32 v46, v46, v47
	v_add_f32_e32 v45, v45, v46
	v_mul_f32_e32 v46, v38, v38
	v_fmac_f32_e32 v46, v0, v0
	v_mul_f32_e32 v47, v42, v42
	v_add_f32_e32 v0, v0, v38
	v_add_f32_e32 v38, v39, v42
	v_fmac_f32_e32 v47, v39, v39
	v_add_f32_e32 v50, v50, v51
	v_add_f32_e32 v51, v52, v53
	v_add_f32_e32 v0, v0, v38
	v_add_f32_e32 v38, v43, v44
	v_add_f32_e32 v39, v40, v41
	v_add_f32_e32 v50, v50, v51
	v_add_f32_e32 v51, v60, v61
	v_add_f32_e32 v48, v48, v49
	v_add_f32_e32 v38, v38, v39
	v_and_b32_e32 v39, 64, v226
	v_add_f32_e32 v48, v51, v48
	v_add_f32_e32 v0, v0, v38
	v_xor_b32_e32 v38, 16, v226
	v_add_u32_e32 v39, 64, v39
	v_add_f32_e32 v48, v50, v48
	v_cmp_lt_i32_e32 vcc, v38, v39
	v_add_f32_e32 v46, v46, v47
	v_mul_f32_e32 v47, v44, v44
	v_mul_f32_e32 v58, v41, v41
	v_add_f32_e32 v48, 0, v48
	v_cndmask_b32_e32 v38, v226, v38, vcc
	v_fmac_f32_e32 v47, v43, v43
	v_add_f32_e32 v0, v0, v48
	v_lshlrev_b32_e32 v38, 2, v38
	v_fmac_f32_e32 v58, v40, v40
	ds_bpermute_b32 v41, v38, v0
	v_add_f32_e32 v40, v47, v58
	v_add_f32_e32 v40, v46, v40
	v_add_f32_e32 v40, v45, v40
	ds_bpermute_b32 v42, v38, v40
	s_waitcnt lgkmcnt(0)
	v_add_f32_e32 v0, v0, v41
	v_xor_b32_e32 v41, 32, v226
	v_cmp_lt_i32_e32 vcc, v41, v39
	v_add_f32_e32 v39, v40, v42
	s_nop 0
	v_cndmask_b32_e32 v38, v226, v41, vcc
	v_lshlrev_b32_e32 v41, 2, v38
	ds_bpermute_b32 v38, v41, v0
	ds_bpermute_b32 v40, v41, v39
	s_and_saveexec_b64 s[4:5], s[6:7]
	s_cbranch_execz .LBB0_375
	s_waitcnt lgkmcnt(0)
	v_add_f32_e32 v39, v39, v40
	v_add_f32_e32 v0, v0, v38
	ds_write2st64_b32 v186, v0, v39 offset0:9 offset1:25

; __device__ __forceinline__ unsigned cvt_pk_bf16(float lo, float hi) { unsigned r; asm volatile("v_cvt_pk_bf16_f32 %0, %1, %2" : "=v"(r) : "v"(lo), "v"(hi)); return r; }
; __device__ __forceinline__ f32x2 gelu_pk(f32x2 v) {
;     const f32x2 av = __builtin_elementwise_abs(v), d = av * 0.2316418882f + 1.0f;
;     f32x2 t; t.x = __builtin_amdgcn_rcpf(d.x); t.y = __builtin_amdgcn_rcpf(d.y);
;     f32x2 q = t * 0.5307027145f + (-0.7265760135f); q = q * t + 0.7107068705f; q = q * t + (-0.142248368f); q = q * t + 0.127414796f; q = q * t;
;     const f32x2 s = (v * v) * (-0.72134752044f);
;     f32x2 e; e.x = __builtin_amdgcn_exp2f(s.x); e.y = __builtin_amdgcn_exp2f(s.y);
;     const f32x2 m = v * (q * e), r = v - m;
;     f32x2 o; o.x = v.x < 0.f ? m.x : r.x; o.y = v.y < 0.f ? m.y : r.y; return o;
; }
;     __device__ __forceinline__ void operator()(const f32x4 (&acc)[2][2][4][2], const Unit& u, int wr, int wc, int fr, int fq) const {
;     ...
;             for (int m = 0; m < 4; ++m) { const int row = row0 + ai * HALF + m * 16; const float rs = rsv[ai][m]; bf16_t* rowp = O + (size_t)row * ldc + col0; float s1 = 0.f, s2 = 0.f;
; #pragma unroll
;                 for (int bj = 0; bj < 2; ++bj) { f32x4 v0 = acc[ai][bj][m][0] * rs, v1 = acc[ai][bj][m][1] * rs;
;                     const f32x2 a = gelu_pk((f32x2){v0[0], v0[1]}), b = gelu_pk((f32x2){v0[2], v0[3]}), c = gelu_pk((f32x2){v1[0], v1[1]}), d = gelu_pk((f32x2){v1[2], v1[3]});
;                     s1 += ((a.x + a.y) + (b.x + b.y)) + ((c.x + c.y) + (d.x + d.y));
;                     s2 += ((a.x * a.x + a.y * a.y) + (b.x * b.x + b.y * b.y)) + ((c.x * c.x + c.y * c.y) + (d.x * d.x + d.y * d.y));
;                     u32x4 w; w.x = cvt_pk_bf16(a.x, a.y); w.y = cvt_pk_bf16(b.x, b.y); w.z = cvt_pk_bf16(c.x, c.y); w.w = cvt_pk_bf16(d.x, d.y);
;                     *(u32x4*)(rowp + bj * HALF) = w; }
;                 if (isv) { s1 += __shfl_xor(s1, 16); s1 += __shfl_xor(s1, 32); s2 += __shfl_xor(s2, 16); s2 += __shfl_xor(s2, 32);
;                     if (fq == 0) { const int rl = ai * HALF + wr * 64 + m * 16 + fr; part[rl * 4 + wc] = s1; part[1024 + rl * 4 + wc] = s2; } } }
.LBB0_376:
	v_add_f32_e32 v0, v54, v55
	s_waitcnt lgkmcnt(0)
	v_add_f32_e32 v38, v56, v57
	v_add_f32_e32 v0, v0, v38
	v_fmamk_f32 v0, v0, 0x3a800000, v224
	v_rsq_f32_e32 v0, v0
	s_mov_b32 s4, 0xbf3a00e3
	v_lshlrev_b64 v[38:39], 12, v[164:165]
	v_lshl_add_u64 v[38:39], s[20:21], 0, v[38:39]
	v_pk_mul_f32 v[30:31], v[30:31], v[0:1] op_sel_hi:[1,0]
	v_pk_mul_f32 v[40:41], v[26:27], v[0:1] op_sel_hi:[1,0]
	v_and_b32_e32 v27, 0x7fffffff, v31
	v_and_b32_e32 v26, 0x7fffffff, v30
	v_pk_fma_f32 v[26:27], v[26:27], s[64:65], 1.0 op_sel_hi:[1,0,0]
	v_pk_mul_f32 v[46:47], v[30:31], v[30:31]
	v_rcp_f32_e32 v42, v26
	v_rcp_f32_e32 v43, v27
	v_mov_b64_e32 v[26:27], s[4:5]
	v_pk_mul_f32 v[46:47], v[46:47], s[76:77] op_sel_hi:[1,0]
	v_cmp_gt_f32_e32 vcc, 0, v30
	v_pk_fma_f32 v[44:45], v[42:43], s[66:67], v[26:27] op_sel_hi:[1,0,0]
	v_exp_f32_e32 v46, v46
	v_pk_fma_f32 v[44:45], v[42:43], v[44:45], s[70:71] op_sel_hi:[1,1,0]
	v_exp_f32_e32 v47, v47
	v_pk_fma_f32 v[44:45], v[42:43], v[44:45], s[72:73] op_sel_hi:[1,1,0]
	v_pk_mul_f32 v[32:33], v[32:33], v[0:1] op_sel_hi:[1,0]
	v_pk_fma_f32 v[44:45], v[42:43], v[44:45], s[74:75] op_sel_hi:[1,1,0]
	v_pk_mul_f32 v[28:29], v[28:29], v[0:1] op_sel_hi:[1,0]
	v_pk_mul_f32 v[42:43], v[42:43], v[44:45]
	v_pk_mul_f32 v[44:45], v[32:33], v[32:33]
	v_pk_mul_f32 v[42:43], v[46:47], v[42:43]
	v_pk_mul_f32 v[44:45], v[44:45], s[76:77] op_sel_hi:[1,0]
	v_pk_mul_f32 v[46:47], v[30:31], v[42:43]
	v_pk_fma_f32 v[42:43], v[30:31], v[42:43], v[30:31] neg_lo:[1,0,0] neg_hi:[1,0,0]
	v_exp_f32_e32 v44, v44
	v_cndmask_b32_e32 v30, v42, v46, vcc
	v_cmp_gt_f32_e32 vcc, 0, v31
	v_and_b32_e32 v42, 0x7fffffff, v32
	v_exp_f32_e32 v45, v45
	v_cndmask_b32_e32 v31, v43, v47, vcc
	v_and_b32_e32 v43, 0x7fffffff, v33
	v_pk_fma_f32 v[42:43], v[42:43], s[64:65], 1.0 op_sel_hi:[1,0,0]
	v_cmp_gt_f32_e32 vcc, 0, v32
	v_rcp_f32_e32 v42, v42
	v_rcp_f32_e32 v43, v43
	v_lshl_add_u64 v[38:39], v[160:161], 1, v[38:39]
	v_pk_mul_f32 v[22:23], v[22:23], v[0:1] op_sel_hi:[1,0]
	v_pk_mul_f32 v[24:25], v[24:25], v[0:1] op_sel_hi:[1,0]
	v_pk_fma_f32 v[46:47], v[42:43], s[66:67], v[26:27] op_sel_hi:[1,0,0]
	v_pk_mul_f32 v[20:21], v[20:21], v[0:1] op_sel_hi:[1,0]
	v_pk_fma_f32 v[46:47], v[42:43], v[46:47], s[70:71] op_sel_hi:[1,1,0]
	s_nop 0
	v_pk_fma_f32 v[46:47], v[42:43], v[46:47], s[72:73] op_sel_hi:[1,1,0]
	s_nop 0
	v_pk_fma_f32 v[46:47], v[42:43], v[46:47], s[74:75] op_sel_hi:[1,1,0]
	s_nop 0
	v_pk_mul_f32 v[42:43], v[42:43], v[46:47]
	v_pk_mul_f32 v[46:47], v[40:41], v[40:41]
	v_pk_mul_f32 v[42:43], v[44:45], v[42:43]
	v_pk_mul_f32 v[46:47], v[46:47], s[76:77] op_sel_hi:[1,0]
	v_pk_mul_f32 v[44:45], v[32:33], v[42:43]
	v_pk_fma_f32 v[42:43], v[32:33], v[42:43], v[32:33] neg_lo:[1,0,0] neg_hi:[1,0,0]
	v_exp_f32_e32 v46, v46
	v_cndmask_b32_e32 v32, v42, v44, vcc
	v_cmp_gt_f32_e32 vcc, 0, v33
	v_and_b32_e32 v42, 0x7fffffff, v40
	v_exp_f32_e32 v47, v47
	v_cndmask_b32_e32 v33, v43, v45, vcc
	v_and_b32_e32 v43, 0x7fffffff, v41
	v_pk_fma_f32 v[42:43], v[42:43], s[64:65], 1.0 op_sel_hi:[1,0,0]
	v_cmp_gt_f32_e32 vcc, 0, v40
	v_rcp_f32_e32 v42, v42
	v_rcp_f32_e32 v43, v43
	s_nop 0
	v_pk_fma_f32 v[44:45], v[42:43], s[66:67], v[26:27] op_sel_hi:[1,0,0]
	s_nop 0
	v_pk_fma_f32 v[44:45], v[42:43], v[44:45], s[70:71] op_sel_hi:[1,1,0]
	s_nop 0
	v_pk_fma_f32 v[44:45], v[42:43], v[44:45], s[72:73] op_sel_hi:[1,1,0]
	s_nop 0
	v_pk_fma_f32 v[44:45], v[42:43], v[44:45], s[74:75] op_sel_hi:[1,1,0]
	s_nop 0
	v_pk_mul_f32 v[42:43], v[42:43], v[44:45]
	v_pk_mul_f32 v[44:45], v[28:29], v[28:29]
	v_pk_mul_f32 v[42:43], v[46:47], v[42:43]
	v_pk_mul_f32 v[44:45], v[44:45], s[76:77] op_sel_hi:[1,0]
	v_pk_mul_f32 v[46:47], v[40:41], v[42:43]
	v_pk_fma_f32 v[42:43], v[40:41], v[42:43], v[40:41] neg_lo:[1,0,0] neg_hi:[1,0,0]
	v_exp_f32_e32 v44, v44
	v_cndmask_b32_e32 v40, v42, v46, vcc
	v_cmp_gt_f32_e32 vcc, 0, v41
	v_and_b32_e32 v42, 0x7fffffff, v28
	v_exp_f32_e32 v45, v45
	v_cndmask_b32_e32 v41, v43, v47, vcc
	v_and_b32_e32 v43, 0x7fffffff, v29
	v_pk_fma_f32 v[42:43], v[42:43], s[64:65], 1.0 op_sel_hi:[1,0,0]
	v_cmp_gt_f32_e32 vcc, 0, v28
	v_rcp_f32_e32 v42, v42
	v_rcp_f32_e32 v43, v43
	s_nop 0
	v_pk_fma_f32 v[46:47], v[42:43], s[66:67], v[26:27] op_sel_hi:[1,0,0]
	s_nop 0
	v_pk_fma_f32 v[46:47], v[42:43], v[46:47], s[70:71] op_sel_hi:[1,1,0]
	s_nop 0
	v_pk_fma_f32 v[46:47], v[42:43], v[46:47], s[72:73] op_sel_hi:[1,1,0]
	s_nop 0
	v_pk_fma_f32 v[46:47], v[42:43], v[46:47], s[74:75] op_sel_hi:[1,1,0]
	s_nop 0
	v_pk_mul_f32 v[42:43], v[42:43], v[46:47]
	v_pk_mul_f32 v[46:47], v[22:23], v[22:23]
	v_pk_mul_f32 v[42:43], v[44:45], v[42:43]
	v_pk_mul_f32 v[46:47], v[46:47], s[76:77] op_sel_hi:[1,0]
	v_pk_mul_f32 v[44:45], v[28:29], v[42:43]
	v_pk_fma_f32 v[42:43], v[28:29], v[42:43], v[28:29] neg_lo:[1,0,0] neg_hi:[1,0,0]
	v_exp_f32_e32 v46, v46
	v_cndmask_b32_e32 v28, v42, v44, vcc
	v_cmp_gt_f32_e32 vcc, 0, v29
	v_cvt_pk_bf16_f32 v42, v30, v31
	v_exp_f32_e32 v47, v47
	s_nop 0
	v_cndmask_b32_e32 v29, v43, v45, vcc
	v_cvt_pk_bf16_f32 v43, v32, v33
	v_cvt_pk_bf16_f32 v44, v40, v41
	v_cvt_pk_bf16_f32 v45, v28, v29
	global_store_dwordx4 v[38:39], v[42:45], off
	v_cmp_gt_f32_e32 vcc, 0, v22
	s_nop 0
	v_pk_mul_f32 v[42:43], v[18:19], v[0:1] op_sel_hi:[1,0]
	v_and_b32_e32 v19, 0x7fffffff, v23
	v_and_b32_e32 v18, 0x7fffffff, v22
	v_pk_fma_f32 v[18:19], v[18:19], s[64:65], 1.0 op_sel_hi:[1,0,0]
	s_nop 0
	v_rcp_f32_e32 v18, v18
	v_rcp_f32_e32 v19, v19
	s_nop 0
	v_pk_fma_f32 v[44:45], v[18:19], s[66:67], v[26:27] op_sel_hi:[1,0,0]
	s_nop 0
	v_pk_fma_f32 v[44:45], v[18:19], v[44:45], s[70:71] op_sel_hi:[1,1,0]
	s_nop 0
	v_pk_fma_f32 v[44:45], v[18:19], v[44:45], s[72:73] op_sel_hi:[1,1,0]
; __device__ __forceinline__ unsigned cvt_pk_bf16(float lo, float hi) { unsigned r; asm volatile("v_cvt_pk_bf16_f32 %0, %1, %2" : "=v"(r) : "v"(lo), "v"(hi)); return r; }
; __device__ __forceinline__ f32x2 gelu_pk(f32x2 v) {
;     const f32x2 av = __builtin_elementwise_abs(v), d = av * 0.2316418882f + 1.0f;
;     f32x2 t; t.x = __builtin_amdgcn_rcpf(d.x); t.y = __builtin_amdgcn_rcpf(d.y);
;     f32x2 q = t * 0.5307027145f + (-0.7265760135f); q = q * t + 0.7107068705f; q = q * t + (-0.142248368f); q = q * t + 0.127414796f; q = q * t;
;     const f32x2 s = (v * v) * (-0.72134752044f);
;     f32x2 e; e.x = __builtin_amdgcn_exp2f(s.x); e.y = __builtin_amdgcn_exp2f(s.y);
;     const f32x2 m = v * (q * e), r = v - m;
;     f32x2 o; o.x = v.x < 0.f ? m.x : r.x; o.y = v.y < 0.f ? m.y : r.y; return o;
; }
;     __device__ __forceinline__ void operator()(const f32x4 (&acc)[2][2][4][2], const Unit& u, int wr, int wc, int fr, int fq) const {
;     ...
;             for (int m = 0; m < 4; ++m) { const int row = row0 + ai * HALF + m * 16; const float rs = rsv[ai][m]; bf16_t* rowp = O + (size_t)row * ldc + col0; float s1 = 0.f, s2 = 0.f;
; #pragma unroll
;                 for (int bj = 0; bj < 2; ++bj) { f32x4 v0 = acc[ai][bj][m][0] * rs, v1 = acc[ai][bj][m][1] * rs;
;                     const f32x2 a = gelu_pk((f32x2){v0[0], v0[1]}), b = gelu_pk((f32x2){v0[2], v0[3]}), c = gelu_pk((f32x2){v1[0], v1[1]}), d = gelu_pk((f32x2){v1[2], v1[3]});
;                     s1 += ((a.x + a.y) + (b.x + b.y)) + ((c.x + c.y) + (d.x + d.y));
;                     s2 += ((a.x * a.x + a.y * a.y) + (b.x * b.x + b.y * b.y)) + ((c.x * c.x + c.y * c.y) + (d.x * d.x + d.y * d.y));
;                     u32x4 w; w.x = cvt_pk_bf16(a.x, a.y); w.y = cvt_pk_bf16(b.x, b.y); w.z = cvt_pk_bf16(c.x, c.y); w.w = cvt_pk_bf16(d.x, d.y);
;                     *(u32x4*)(rowp + bj * HALF) = w; }
;                 if (isv) { s1 += __shfl_xor(s1, 16); s1 += __shfl_xor(s1, 32); s2 += __shfl_xor(s2, 16); s2 += __shfl_xor(s2, 32);
;                     if (fq == 0) { const int rl = ai * HALF + wr * 64 + m * 16 + fr; part[rl * 4 + wc] = s1; part[1024 + rl * 4 + wc] = s2; } } }
	s_nop 0
	v_pk_fma_f32 v[44:45], v[18:19], v[44:45], s[74:75] op_sel_hi:[1,1,0]
	s_nop 0
	v_pk_mul_f32 v[18:19], v[18:19], v[44:45]
	v_pk_mul_f32 v[44:45], v[24:25], v[24:25]
	v_pk_mul_f32 v[18:19], v[46:47], v[18:19]
	v_pk_mul_f32 v[44:45], v[44:45], s[76:77] op_sel_hi:[1,0]
	v_pk_mul_f32 v[46:47], v[22:23], v[18:19]
	v_pk_fma_f32 v[18:19], v[22:23], v[18:19], v[22:23] neg_lo:[1,0,0] neg_hi:[1,0,0]
	v_and_b32_e32 v22, 0x7fffffff, v24
	v_cndmask_b32_e32 v0, v18, v46, vcc
	v_cmp_gt_f32_e32 vcc, 0, v23
	v_and_b32_e32 v23, 0x7fffffff, v25
	v_pk_fma_f32 v[22:23], v[22:23], s[64:65], 1.0 op_sel_hi:[1,0,0]
	v_cndmask_b32_e32 v18, v19, v47, vcc
	v_rcp_f32_e32 v22, v22
	v_rcp_f32_e32 v23, v23
	v_exp_f32_e32 v44, v44
	v_exp_f32_e32 v45, v45
	v_cmp_gt_f32_e32 vcc, 0, v24
	v_pk_fma_f32 v[46:47], v[22:23], s[66:67], v[26:27] op_sel_hi:[1,0,0]
	s_nop 0
	v_pk_fma_f32 v[46:47], v[22:23], v[46:47], s[70:71] op_sel_hi:[1,1,0]
	s_nop 0
	v_pk_fma_f32 v[46:47], v[22:23], v[46:47], s[72:73] op_sel_hi:[1,1,0]
	s_nop 0
	v_pk_fma_f32 v[46:47], v[22:23], v[46:47], s[74:75] op_sel_hi:[1,1,0]
	s_nop 0
	v_pk_mul_f32 v[22:23], v[22:23], v[46:47]
	v_pk_mul_f32 v[46:47], v[42:43], v[42:43]
	v_pk_mul_f32 v[22:23], v[44:45], v[22:23]
	v_pk_mul_f32 v[46:47], v[46:47], s[76:77] op_sel_hi:[1,0]
	v_pk_mul_f32 v[44:45], v[24:25], v[22:23]
	v_pk_fma_f32 v[22:23], v[24:25], v[22:23], v[24:25] neg_lo:[1,0,0] neg_hi:[1,0,0]
	v_and_b32_e32 v24, 0x7fffffff, v42
	v_cndmask_b32_e32 v19, v22, v44, vcc
	v_cmp_gt_f32_e32 vcc, 0, v25
	v_and_b32_e32 v25, 0x7fffffff, v43
	v_pk_fma_f32 v[24:25], v[24:25], s[64:65], 1.0 op_sel_hi:[1,0,0]
	v_cndmask_b32_e32 v22, v23, v45, vcc
	v_rcp_f32_e32 v24, v24
	v_rcp_f32_e32 v25, v25
	v_exp_f32_e32 v46, v46
	v_exp_f32_e32 v47, v47
	v_cmp_gt_f32_e32 vcc, 0, v42
	v_pk_fma_f32 v[44:45], v[24:25], s[66:67], v[26:27] op_sel_hi:[1,0,0]
	s_nop 0
	v_pk_fma_f32 v[44:45], v[24:25], v[44:45], s[70:71] op_sel_hi:[1,1,0]
	s_nop 0
	v_pk_fma_f32 v[44:45], v[24:25], v[44:45], s[72:73] op_sel_hi:[1,1,0]
	s_nop 0
	v_pk_fma_f32 v[44:45], v[24:25], v[44:45], s[74:75] op_sel_hi:[1,1,0]
	s_nop 0
	v_pk_mul_f32 v[24:25], v[24:25], v[44:45]
	v_pk_mul_f32 v[44:45], v[20:21], v[20:21]
	v_pk_mul_f32 v[24:25], v[46:47], v[24:25]
	s_nop 0
	v_pk_mul_f32 v[46:47], v[42:43], v[24:25]
	v_pk_fma_f32 v[24:25], v[42:43], v[24:25], v[42:43] neg_lo:[1,0,0] neg_hi:[1,0,0]
	v_and_b32_e32 v42, 0x7fffffff, v20
	v_cndmask_b32_e32 v23, v24, v46, vcc
	v_cmp_gt_f32_e32 vcc, 0, v43
	v_and_b32_e32 v43, 0x7fffffff, v21
	v_pk_fma_f32 v[42:43], v[42:43], s[64:65], 1.0 op_sel_hi:[1,0,0]
	v_cndmask_b32_e32 v24, v25, v47, vcc
	v_rcp_f32_e32 v42, v42
	v_rcp_f32_e32 v43, v43
	v_cmp_gt_f32_e32 vcc, 0, v20
	v_pk_fma_f32 v[26:27], v[42:43], s[66:67], v[26:27] op_sel_hi:[1,0,0]
	s_nop 0
	v_pk_fma_f32 v[26:27], v[42:43], v[26:27], s[70:71] op_sel_hi:[1,1,0]
	s_nop 0
	v_pk_fma_f32 v[26:27], v[42:43], v[26:27], s[72:73] op_sel_hi:[1,1,0]
	s_nop 0
	v_pk_fma_f32 v[26:27], v[42:43], v[26:27], s[74:75] op_sel_hi:[1,1,0]
	s_nop 0
	v_pk_mul_f32 v[26:27], v[42:43], v[26:27]
	v_pk_mul_f32 v[42:43], v[44:45], s[76:77] op_sel_hi:[1,0]
	s_nop 0
	v_exp_f32_e32 v42, v42
	v_exp_f32_e32 v43, v43
	s_nop 0
	v_pk_mul_f32 v[26:27], v[42:43], v[26:27]
	s_nop 0
	v_pk_mul_f32 v[42:43], v[20:21], v[26:27]
	v_pk_fma_f32 v[26:27], v[20:21], v[26:27], v[20:21] neg_lo:[1,0,0] neg_hi:[1,0,0]
	s_nop 0
	v_cndmask_b32_e32 v20, v26, v42, vcc
	v_cmp_gt_f32_e32 vcc, 0, v21
	v_cvt_pk_bf16_f32 v42, v0, v18
	s_nop 1
	v_cndmask_b32_e32 v21, v27, v43, vcc
	s_and_b64 vcc, exec, s[10:11]
	v_cvt_pk_bf16_f32 v43, v19, v22
	v_cvt_pk_bf16_f32 v44, v23, v24
	v_cvt_pk_bf16_f32 v45, v20, v21
	global_store_dwordx4 v[38:39], v[42:45], off offset:256
	s_cbranch_vccnz .LBB0_380
	v_mul_f32_e32 v25, v31, v31
	v_mul_f32_e32 v26, v33, v33
	v_fmac_f32_e32 v25, v30, v30
	v_fmac_f32_e32 v26, v32, v32
	v_add_f32_e32 v25, v25, v26
	v_mul_f32_e32 v26, v41, v41
	v_mul_f32_e32 v27, v29, v29
	v_fmac_f32_e32 v26, v40, v40
	v_fmac_f32_e32 v27, v28, v28
	v_add_f32_e32 v26, v26, v27
	v_add_f32_e32 v25, v25, v26
	v_mul_f32_e32 v26, v18, v18
	v_fmac_f32_e32 v26, v0, v0
	v_mul_f32_e32 v27, v22, v22
	v_add_f32_e32 v0, v0, v18
	v_add_f32_e32 v18, v19, v22
	v_fmac_f32_e32 v27, v19, v19
	v_add_f32_e32 v30, v30, v31
	v_add_f32_e32 v31, v32, v33
	v_add_f32_e32 v0, v0, v18
	v_add_f32_e32 v18, v23, v24
	v_add_f32_e32 v19, v20, v21
	v_add_f32_e32 v30, v30, v31
	v_add_f32_e32 v31, v40, v41
	v_add_f32_e32 v28, v28, v29
	v_add_f32_e32 v18, v18, v19
	v_and_b32_e32 v19, 64, v226
	v_add_f32_e32 v28, v31, v28
	v_add_f32_e32 v0, v0, v18
	v_xor_b32_e32 v18, 16, v226
	v_add_u32_e32 v19, 64, v19
	v_add_f32_e32 v28, v30, v28
	v_cmp_lt_i32_e32 vcc, v18, v19
	v_add_f32_e32 v26, v26, v27
	v_mul_f32_e32 v27, v24, v24
	v_mul_f32_e32 v38, v21, v21
	v_add_f32_e32 v28, 0, v28
	v_cndmask_b32_e32 v18, v226, v18, vcc
	v_fmac_f32_e32 v27, v23, v23
	v_add_f32_e32 v0, v0, v28
	v_lshlrev_b32_e32 v18, 2, v18
	v_fmac_f32_e32 v38, v20, v20
	ds_bpermute_b32 v21, v18, v0
	v_add_f32_e32 v20, v27, v38
	v_add_f32_e32 v20, v26, v20
	v_add_f32_e32 v20, v25, v20
	ds_bpermute_b32 v22, v18, v20
	s_waitcnt lgkmcnt(0)
	v_add_f32_e32 v0, v0, v21
	v_xor_b32_e32 v21, 32, v226
	v_cmp_lt_i32_e32 vcc, v21, v19
	v_add_f32_e32 v19, v20, v22
	s_nop 0
	v_cndmask_b32_e32 v18, v226, v21, vcc
	v_lshlrev_b32_e32 v21, 2, v18
	ds_bpermute_b32 v18, v21, v0
	ds_bpermute_b32 v20, v21, v19
	s_and_saveexec_b64 s[4:5], s[6:7]
	s_cbranch_execz .LBB0_379
	s_waitcnt lgkmcnt(0)
	v_add_f32_e32 v19, v19, v20
	v_add_f32_e32 v0, v0, v18
	ds_write2st64_b32 v186, v0, v19 offset0:10 offset1:26

; __device__ __forceinline__ unsigned cvt_pk_bf16(float lo, float hi) { unsigned r; asm volatile("v_cvt_pk_bf16_f32 %0, %1, %2" : "=v"(r) : "v"(lo), "v"(hi)); return r; }
; __device__ __forceinline__ f32x2 gelu_pk(f32x2 v) {
;     const f32x2 av = __builtin_elementwise_abs(v), d = av * 0.2316418882f + 1.0f;
;     f32x2 t; t.x = __builtin_amdgcn_rcpf(d.x); t.y = __builtin_amdgcn_rcpf(d.y);
;     f32x2 q = t * 0.5307027145f + (-0.7265760135f); q = q * t + 0.7107068705f; q = q * t + (-0.142248368f); q = q * t + 0.127414796f; q = q * t;
;     const f32x2 s = (v * v) * (-0.72134752044f);
;     f32x2 e; e.x = __builtin_amdgcn_exp2f(s.x); e.y = __builtin_amdgcn_exp2f(s.y);
;     const f32x2 m = v * (q * e), r = v - m;
;     f32x2 o; o.x = v.x < 0.f ? m.x : r.x; o.y = v.y < 0.f ? m.y : r.y; return o;
; }
;     __device__ __forceinline__ void operator()(const f32x4 (&acc)[2][2][4][2], const Unit& u, int wr, int wc, int fr, int fq) const {
;     ...
;             for (int m = 0; m < 4; ++m) { const int row = row0 + ai * HALF + m * 16; const float rs = rsv[ai][m]; bf16_t* rowp = O + (size_t)row * ldc + col0; float s1 = 0.f, s2 = 0.f;
; #pragma unroll
;                 for (int bj = 0; bj < 2; ++bj) { f32x4 v0 = acc[ai][bj][m][0] * rs, v1 = acc[ai][bj][m][1] * rs;
;                     const f32x2 a = gelu_pk((f32x2){v0[0], v0[1]}), b = gelu_pk((f32x2){v0[2], v0[3]}), c = gelu_pk((f32x2){v1[0], v1[1]}), d = gelu_pk((f32x2){v1[2], v1[3]});
;                     s1 += ((a.x + a.y) + (b.x + b.y)) + ((c.x + c.y) + (d.x + d.y));
;                     s2 += ((a.x * a.x + a.y * a.y) + (b.x * b.x + b.y * b.y)) + ((c.x * c.x + c.y * c.y) + (d.x * d.x + d.y * d.y));
;                     u32x4 w; w.x = cvt_pk_bf16(a.x, a.y); w.y = cvt_pk_bf16(b.x, b.y); w.z = cvt_pk_bf16(c.x, c.y); w.w = cvt_pk_bf16(d.x, d.y);
;                     *(u32x4*)(rowp + bj * HALF) = w; }
;                 if (isv) { s1 += __shfl_xor(s1, 16); s1 += __shfl_xor(s1, 32); s2 += __shfl_xor(s2, 16); s2 += __shfl_xor(s2, 32);
;                     if (fq == 0) { const int rl = ai * HALF + wr * 64 + m * 16 + fr; part[rl * 4 + wc] = s1; part[1024 + rl * 4 + wc] = s2; } } }
.LBB0_380:
	v_add_f32_e32 v0, v34, v35
	s_waitcnt lgkmcnt(0)
	v_add_f32_e32 v18, v36, v37
	v_add_f32_e32 v0, v0, v18
	v_fmamk_f32 v0, v0, 0x3a800000, v224
	v_rsq_f32_e32 v0, v0
	s_mov_b32 s4, 0xbf3a00e3
	v_lshlrev_b64 v[18:19], 12, v[162:163]
	v_lshl_add_u64 v[18:19], s[20:21], 0, v[18:19]
	v_pk_mul_f32 v[14:15], v[14:15], v[0:1] op_sel_hi:[1,0]
	v_pk_mul_f32 v[20:21], v[10:11], v[0:1] op_sel_hi:[1,0]
	v_and_b32_e32 v11, 0x7fffffff, v15
	v_and_b32_e32 v10, 0x7fffffff, v14
	v_pk_fma_f32 v[10:11], v[10:11], s[64:65], 1.0 op_sel_hi:[1,0,0]
	v_pk_mul_f32 v[26:27], v[14:15], v[14:15]
	v_rcp_f32_e32 v22, v10
	v_rcp_f32_e32 v23, v11
	v_mov_b64_e32 v[10:11], s[4:5]
	v_pk_mul_f32 v[26:27], v[26:27], s[76:77] op_sel_hi:[1,0]
	v_cmp_gt_f32_e32 vcc, 0, v14
	v_pk_fma_f32 v[24:25], v[22:23], s[66:67], v[10:11] op_sel_hi:[1,0,0]
	v_exp_f32_e32 v26, v26
	v_pk_fma_f32 v[24:25], v[22:23], v[24:25], s[70:71] op_sel_hi:[1,1,0]
	v_exp_f32_e32 v27, v27
	v_pk_fma_f32 v[24:25], v[22:23], v[24:25], s[72:73] op_sel_hi:[1,1,0]
	v_pk_mul_f32 v[16:17], v[16:17], v[0:1] op_sel_hi:[1,0]
	v_pk_fma_f32 v[24:25], v[22:23], v[24:25], s[74:75] op_sel_hi:[1,1,0]
	v_pk_mul_f32 v[12:13], v[12:13], v[0:1] op_sel_hi:[1,0]
	v_pk_mul_f32 v[22:23], v[22:23], v[24:25]
	v_pk_mul_f32 v[24:25], v[16:17], v[16:17]
	v_pk_mul_f32 v[22:23], v[26:27], v[22:23]
	v_pk_mul_f32 v[24:25], v[24:25], s[76:77] op_sel_hi:[1,0]
	v_pk_mul_f32 v[26:27], v[14:15], v[22:23]
	v_pk_fma_f32 v[22:23], v[14:15], v[22:23], v[14:15] neg_lo:[1,0,0] neg_hi:[1,0,0]
	v_exp_f32_e32 v24, v24
	v_cndmask_b32_e32 v14, v22, v26, vcc
	v_cmp_gt_f32_e32 vcc, 0, v15
	v_and_b32_e32 v22, 0x7fffffff, v16
	v_exp_f32_e32 v25, v25
	v_cndmask_b32_e32 v15, v23, v27, vcc
	v_and_b32_e32 v23, 0x7fffffff, v17
	v_pk_fma_f32 v[22:23], v[22:23], s[64:65], 1.0 op_sel_hi:[1,0,0]
	v_cmp_gt_f32_e32 vcc, 0, v16
	v_rcp_f32_e32 v22, v22
	v_rcp_f32_e32 v23, v23
	v_lshl_add_u64 v[18:19], v[160:161], 1, v[18:19]
	v_pk_mul_f32 v[6:7], v[6:7], v[0:1] op_sel_hi:[1,0]
	v_pk_mul_f32 v[8:9], v[8:9], v[0:1] op_sel_hi:[1,0]
	v_pk_fma_f32 v[26:27], v[22:23], s[66:67], v[10:11] op_sel_hi:[1,0,0]
	v_pk_mul_f32 v[4:5], v[4:5], v[0:1] op_sel_hi:[1,0]
	v_pk_fma_f32 v[26:27], v[22:23], v[26:27], s[70:71] op_sel_hi:[1,1,0]
	s_nop 0
	v_pk_fma_f32 v[26:27], v[22:23], v[26:27], s[72:73] op_sel_hi:[1,1,0]
	s_nop 0
	v_pk_fma_f32 v[26:27], v[22:23], v[26:27], s[74:75] op_sel_hi:[1,1,0]
	s_nop 0
	v_pk_mul_f32 v[22:23], v[22:23], v[26:27]
	v_pk_mul_f32 v[26:27], v[20:21], v[20:21]
	v_pk_mul_f32 v[22:23], v[24:25], v[22:23]
	v_pk_mul_f32 v[26:27], v[26:27], s[76:77] op_sel_hi:[1,0]
	v_pk_mul_f32 v[24:25], v[16:17], v[22:23]
	v_pk_fma_f32 v[22:23], v[16:17], v[22:23], v[16:17] neg_lo:[1,0,0] neg_hi:[1,0,0]
	v_exp_f32_e32 v26, v26
	v_cndmask_b32_e32 v16, v22, v24, vcc
	v_cmp_gt_f32_e32 vcc, 0, v17
	v_and_b32_e32 v22, 0x7fffffff, v20
	v_exp_f32_e32 v27, v27
	v_cndmask_b32_e32 v17, v23, v25, vcc
	v_and_b32_e32 v23, 0x7fffffff, v21
	v_pk_fma_f32 v[22:23], v[22:23], s[64:65], 1.0 op_sel_hi:[1,0,0]
	v_cmp_gt_f32_e32 vcc, 0, v20
	v_rcp_f32_e32 v22, v22
	v_rcp_f32_e32 v23, v23
	s_nop 0
	v_pk_fma_f32 v[24:25], v[22:23], s[66:67], v[10:11] op_sel_hi:[1,0,0]
	s_nop 0
	v_pk_fma_f32 v[24:25], v[22:23], v[24:25], s[70:71] op_sel_hi:[1,1,0]
	s_nop 0
	v_pk_fma_f32 v[24:25], v[22:23], v[24:25], s[72:73] op_sel_hi:[1,1,0]
	s_nop 0
	v_pk_fma_f32 v[24:25], v[22:23], v[24:25], s[74:75] op_sel_hi:[1,1,0]
	s_nop 0
	v_pk_mul_f32 v[22:23], v[22:23], v[24:25]
	v_pk_mul_f32 v[24:25], v[12:13], v[12:13]
	v_pk_mul_f32 v[22:23], v[26:27], v[22:23]
	v_pk_mul_f32 v[24:25], v[24:25], s[76:77] op_sel_hi:[1,0]
	v_pk_mul_f32 v[26:27], v[20:21], v[22:23]
	v_pk_fma_f32 v[22:23], v[20:21], v[22:23], v[20:21] neg_lo:[1,0,0] neg_hi:[1,0,0]
	v_exp_f32_e32 v24, v24
	v_cndmask_b32_e32 v20, v22, v26, vcc
	v_cmp_gt_f32_e32 vcc, 0, v21
	v_and_b32_e32 v22, 0x7fffffff, v12
	v_exp_f32_e32 v25, v25
	v_cndmask_b32_e32 v21, v23, v27, vcc
	v_and_b32_e32 v23, 0x7fffffff, v13
	v_pk_fma_f32 v[22:23], v[22:23], s[64:65], 1.0 op_sel_hi:[1,0,0]
	v_cmp_gt_f32_e32 vcc, 0, v12
	v_rcp_f32_e32 v22, v22
	v_rcp_f32_e32 v23, v23
	s_nop 0
	v_pk_fma_f32 v[26:27], v[22:23], s[66:67], v[10:11] op_sel_hi:[1,0,0]
	s_nop 0
	v_pk_fma_f32 v[26:27], v[22:23], v[26:27], s[70:71] op_sel_hi:[1,1,0]
	s_nop 0
	v_pk_fma_f32 v[26:27], v[22:23], v[26:27], s[72:73] op_sel_hi:[1,1,0]
	s_nop 0
	v_pk_fma_f32 v[26:27], v[22:23], v[26:27], s[74:75] op_sel_hi:[1,1,0]
	s_nop 0
	v_pk_mul_f32 v[22:23], v[22:23], v[26:27]
	v_pk_mul_f32 v[26:27], v[6:7], v[6:7]
	v_pk_mul_f32 v[22:23], v[24:25], v[22:23]
	v_pk_mul_f32 v[26:27], v[26:27], s[76:77] op_sel_hi:[1,0]
	v_pk_mul_f32 v[24:25], v[12:13], v[22:23]
	v_pk_fma_f32 v[22:23], v[12:13], v[22:23], v[12:13] neg_lo:[1,0,0] neg_hi:[1,0,0]
	v_exp_f32_e32 v26, v26
	v_cndmask_b32_e32 v12, v22, v24, vcc
	v_cmp_gt_f32_e32 vcc, 0, v13
	v_cvt_pk_bf16_f32 v22, v14, v15
	v_exp_f32_e32 v27, v27
	s_nop 0
	v_cndmask_b32_e32 v13, v23, v25, vcc
	v_cvt_pk_bf16_f32 v23, v16, v17
	v_cvt_pk_bf16_f32 v24, v20, v21
	v_cvt_pk_bf16_f32 v25, v12, v13
	global_store_dwordx4 v[18:19], v[22:25], off
	v_cmp_gt_f32_e32 vcc, 0, v6
	s_nop 0
	v_pk_mul_f32 v[22:23], v[2:3], v[0:1] op_sel_hi:[1,0]
	v_and_b32_e32 v3, 0x7fffffff, v7
	v_and_b32_e32 v2, 0x7fffffff, v6
	v_pk_fma_f32 v[2:3], v[2:3], s[64:65], 1.0 op_sel_hi:[1,0,0]
	s_nop 0
	v_rcp_f32_e32 v2, v2
	v_rcp_f32_e32 v3, v3
	s_nop 0
	v_pk_fma_f32 v[24:25], v[2:3], s[66:67], v[10:11] op_sel_hi:[1,0,0]
	s_nop 0
	v_pk_fma_f32 v[24:25], v[2:3], v[24:25], s[70:71] op_sel_hi:[1,1,0]
	s_nop 0
	v_pk_fma_f32 v[24:25], v[2:3], v[24:25], s[72:73] op_sel_hi:[1,1,0]
	s_nop 0
	v_pk_fma_f32 v[24:25], v[2:3], v[24:25], s[74:75] op_sel_hi:[1,1,0]
; #define LAS __attribute__((address_space(3)))
; __device__ __forceinline__ f32x2 gelu_pk(f32x2 v) {
;     const f32x2 av = __builtin_elementwise_abs(v), d = av * 0.2316418882f + 1.0f;
;     f32x2 t; t.x = __builtin_amdgcn_rcpf(d.x); t.y = __builtin_amdgcn_rcpf(d.y);
;     f32x2 q = t * 0.5307027145f + (-0.7265760135f); q = q * t + 0.7107068705f; q = q * t + (-0.142248368f); q = q * t + 0.127414796f; q = q * t;
;     const f32x2 s = (v * v) * (-0.72134752044f);
;     f32x2 e; e.x = __builtin_amdgcn_exp2f(s.x); e.y = __builtin_amdgcn_exp2f(s.y);
;     const f32x2 m = v * (q * e), r = v - m;
;     f32x2 o; o.x = v.x < 0.f ? m.x : r.x; o.y = v.y < 0.f ? m.y : r.y; return o;
; }
;     __device__ __forceinline__ void operator()(const f32x4 (&acc)[2][2][4][2], const Unit& u, int wr, int wc, int fr, int fq) const {
;     ...
;                 for (int bj = 0; bj < 2; ++bj) { f32x4 v0 = acc[ai][bj][m][0] * rs, v1 = acc[ai][bj][m][1] * rs;
;                     const f32x2 a = gelu_pk((f32x2){v0[0], v0[1]}), b = gelu_pk((f32x2){v0[2], v0[3]}), c = gelu_pk((f32x2){v1[0], v1[1]}), d = gelu_pk((f32x2){v1[2], v1[3]});
;                     s1 += ((a.x + a.y) + (b.x + b.y)) + ((c.x + c.y) + (d.x + d.y));
;                     s2 += ((a.x * a.x + a.y * a.y) + (b.x * b.x + b.y * b.y)) + ((c.x * c.x + c.y * c.y) + (d.x * d.x + d.y * d.y));
;                     u32x4 w; w.x = cvt_pk_bf16(a.x, a.y); w.y = cvt_pk_bf16(b.x, b.y); w.z = cvt_pk_bf16(c.x, c.y); w.w = cvt_pk_bf16(d.x, d.y);
;                     *(u32x4*)(rowp + bj * HALF) = w; }
;                 if (isv) { s1 += __shfl_xor(s1, 16); s1 += __shfl_xor(s1, 32); s2 += __shfl_xor(s2, 16); s2 += __shfl_xor(s2, 32);
;                     if (fq == 0) { const int rl = ai * HALF + wr * 64 + m * 16 + fr; part[rl * 4 + wc] = s1; part[1024 + rl * 4 + wc] = s2; } } }
;         if (isv) {
;             asm volatile("s_waitcnt lgkmcnt(0)" ::: "memory"); __builtin_amdgcn_s_barrier(); asm volatile("" ::: "memory");
;             const int t = threadIdx.x;
;             { const int rl = t & 255, which = t >> 8; const f32x4 p = *(const LAS f32x4*)(part + which * 1024 + rl * 4);
;               vstat[(size_t)(u.pm * BM + rl) * 8 + which * 4 + (u.pn - 4)] = (p.x + p.y) + (p.z + p.w); }
	s_nop 0
	v_pk_mul_f32 v[2:3], v[2:3], v[24:25]
	v_pk_mul_f32 v[24:25], v[8:9], v[8:9]
	v_pk_mul_f32 v[2:3], v[26:27], v[2:3]
	v_pk_mul_f32 v[24:25], v[24:25], s[76:77] op_sel_hi:[1,0]
	v_pk_mul_f32 v[26:27], v[6:7], v[2:3]
	v_pk_fma_f32 v[2:3], v[6:7], v[2:3], v[6:7] neg_lo:[1,0,0] neg_hi:[1,0,0]
	v_and_b32_e32 v6, 0x7fffffff, v8
	v_cndmask_b32_e32 v0, v2, v26, vcc
	v_cmp_gt_f32_e32 vcc, 0, v7
	v_and_b32_e32 v7, 0x7fffffff, v9
	v_pk_fma_f32 v[6:7], v[6:7], s[64:65], 1.0 op_sel_hi:[1,0,0]
	v_cndmask_b32_e32 v2, v3, v27, vcc
	v_rcp_f32_e32 v6, v6
	v_rcp_f32_e32 v7, v7
	v_exp_f32_e32 v24, v24
	v_exp_f32_e32 v25, v25
	v_cmp_gt_f32_e32 vcc, 0, v8
	v_pk_fma_f32 v[26:27], v[6:7], s[66:67], v[10:11] op_sel_hi:[1,0,0]
	s_nop 0
	v_pk_fma_f32 v[26:27], v[6:7], v[26:27], s[70:71] op_sel_hi:[1,1,0]
	s_nop 0
	v_pk_fma_f32 v[26:27], v[6:7], v[26:27], s[72:73] op_sel_hi:[1,1,0]
	s_nop 0
	v_pk_fma_f32 v[26:27], v[6:7], v[26:27], s[74:75] op_sel_hi:[1,1,0]
	s_nop 0
	v_pk_mul_f32 v[6:7], v[6:7], v[26:27]
	v_pk_mul_f32 v[26:27], v[22:23], v[22:23]
	v_pk_mul_f32 v[6:7], v[24:25], v[6:7]
	v_pk_mul_f32 v[26:27], v[26:27], s[76:77] op_sel_hi:[1,0]
	v_pk_mul_f32 v[24:25], v[8:9], v[6:7]
	v_pk_fma_f32 v[6:7], v[8:9], v[6:7], v[8:9] neg_lo:[1,0,0] neg_hi:[1,0,0]
	v_and_b32_e32 v8, 0x7fffffff, v22
	v_cndmask_b32_e32 v3, v6, v24, vcc
	v_cmp_gt_f32_e32 vcc, 0, v9
	v_and_b32_e32 v9, 0x7fffffff, v23
	v_pk_fma_f32 v[8:9], v[8:9], s[64:65], 1.0 op_sel_hi:[1,0,0]
	v_cndmask_b32_e32 v6, v7, v25, vcc
	v_rcp_f32_e32 v8, v8
	v_rcp_f32_e32 v9, v9
	v_exp_f32_e32 v26, v26
	v_exp_f32_e32 v27, v27
	v_cmp_gt_f32_e32 vcc, 0, v22
	v_pk_fma_f32 v[24:25], v[8:9], s[66:67], v[10:11] op_sel_hi:[1,0,0]
	s_nop 0
	v_pk_fma_f32 v[24:25], v[8:9], v[24:25], s[70:71] op_sel_hi:[1,1,0]
	s_nop 0
	v_pk_fma_f32 v[24:25], v[8:9], v[24:25], s[72:73] op_sel_hi:[1,1,0]
	s_nop 0
	v_pk_fma_f32 v[24:25], v[8:9], v[24:25], s[74:75] op_sel_hi:[1,1,0]
	s_nop 0
	v_pk_mul_f32 v[8:9], v[8:9], v[24:25]
	v_pk_mul_f32 v[24:25], v[4:5], v[4:5]
	v_pk_mul_f32 v[8:9], v[26:27], v[8:9]
	s_nop 0
	v_pk_mul_f32 v[26:27], v[22:23], v[8:9]
	v_pk_fma_f32 v[8:9], v[22:23], v[8:9], v[22:23] neg_lo:[1,0,0] neg_hi:[1,0,0]
	v_and_b32_e32 v22, 0x7fffffff, v4
	v_cndmask_b32_e32 v7, v8, v26, vcc
	v_cmp_gt_f32_e32 vcc, 0, v23
	v_and_b32_e32 v23, 0x7fffffff, v5
	v_pk_fma_f32 v[22:23], v[22:23], s[64:65], 1.0 op_sel_hi:[1,0,0]
	v_cndmask_b32_e32 v8, v9, v27, vcc
	v_rcp_f32_e32 v22, v22
	v_rcp_f32_e32 v23, v23
	v_cmp_gt_f32_e32 vcc, 0, v4
	v_pk_fma_f32 v[10:11], v[22:23], s[66:67], v[10:11] op_sel_hi:[1,0,0]
	s_nop 0
	v_pk_fma_f32 v[10:11], v[22:23], v[10:11], s[70:71] op_sel_hi:[1,1,0]
	s_nop 0
	v_pk_fma_f32 v[10:11], v[22:23], v[10:11], s[72:73] op_sel_hi:[1,1,0]
	s_nop 0
	v_pk_fma_f32 v[10:11], v[22:23], v[10:11], s[74:75] op_sel_hi:[1,1,0]
	s_nop 0
	v_pk_mul_f32 v[10:11], v[22:23], v[10:11]
	v_pk_mul_f32 v[22:23], v[24:25], s[76:77] op_sel_hi:[1,0]
	s_nop 0
	v_exp_f32_e32 v22, v22
	v_exp_f32_e32 v23, v23
	s_nop 0
	v_pk_mul_f32 v[10:11], v[22:23], v[10:11]
	s_nop 0
	v_pk_mul_f32 v[22:23], v[4:5], v[10:11]
	v_pk_fma_f32 v[10:11], v[4:5], v[10:11], v[4:5] neg_lo:[1,0,0] neg_hi:[1,0,0]
	s_nop 0
	v_cndmask_b32_e32 v4, v10, v22, vcc
	v_cmp_gt_f32_e32 vcc, 0, v5
	v_cvt_pk_bf16_f32 v22, v0, v2
	s_nop 1
	v_cndmask_b32_e32 v5, v11, v23, vcc
	s_and_b64 vcc, exec, s[10:11]
	v_cvt_pk_bf16_f32 v23, v3, v6
	v_cvt_pk_bf16_f32 v24, v7, v8
	v_cvt_pk_bf16_f32 v25, v4, v5
	global_store_dwordx4 v[18:19], v[22:25], off offset:256
	s_cbranch_vccnz .LBB0_384
	v_mul_f32_e32 v9, v15, v15
	v_mul_f32_e32 v10, v17, v17
	v_fmac_f32_e32 v9, v14, v14
	v_fmac_f32_e32 v10, v16, v16
	v_add_f32_e32 v9, v9, v10
	v_mul_f32_e32 v10, v21, v21
	v_mul_f32_e32 v11, v13, v13
	v_fmac_f32_e32 v10, v20, v20
	v_fmac_f32_e32 v11, v12, v12
	v_add_f32_e32 v10, v10, v11
	v_add_f32_e32 v9, v9, v10
	v_mul_f32_e32 v10, v2, v2
	v_fmac_f32_e32 v10, v0, v0
	v_mul_f32_e32 v11, v6, v6
	v_add_f32_e32 v0, v0, v2
	v_add_f32_e32 v2, v3, v6
	v_fmac_f32_e32 v11, v3, v3
	v_add_f32_e32 v14, v14, v15
	v_add_f32_e32 v15, v16, v17
	v_add_f32_e32 v0, v0, v2
	v_add_f32_e32 v2, v7, v8
	v_add_f32_e32 v3, v4, v5
	v_add_f32_e32 v14, v14, v15
	v_add_f32_e32 v15, v20, v21
	v_add_f32_e32 v12, v12, v13
	v_add_f32_e32 v2, v2, v3
	v_and_b32_e32 v3, 64, v226
	v_add_f32_e32 v12, v15, v12
	v_add_f32_e32 v0, v0, v2
	v_xor_b32_e32 v2, 16, v226
	v_add_u32_e32 v3, 64, v3
	v_add_f32_e32 v12, v14, v12
	v_cmp_lt_i32_e32 vcc, v2, v3
	v_add_f32_e32 v10, v10, v11
	v_mul_f32_e32 v11, v8, v8
	v_mul_f32_e32 v18, v5, v5
	v_add_f32_e32 v12, 0, v12
	v_cndmask_b32_e32 v2, v226, v2, vcc
	v_fmac_f32_e32 v11, v7, v7
	v_add_f32_e32 v0, v0, v12
	v_lshlrev_b32_e32 v2, 2, v2
	v_fmac_f32_e32 v18, v4, v4
	ds_bpermute_b32 v5, v2, v0
	v_add_f32_e32 v4, v11, v18
	v_add_f32_e32 v4, v10, v4
	v_add_f32_e32 v4, v9, v4
	ds_bpermute_b32 v6, v2, v4
	s_waitcnt lgkmcnt(0)
	v_add_f32_e32 v0, v0, v5
	v_xor_b32_e32 v5, 32, v226
	v_cmp_lt_i32_e32 vcc, v5, v3
	v_add_f32_e32 v3, v4, v6
	s_nop 0
	v_cndmask_b32_e32 v2, v226, v5, vcc
	v_lshlrev_b32_e32 v5, 2, v2
	ds_bpermute_b32 v2, v5, v0
	ds_bpermute_b32 v4, v5, v3
	s_and_saveexec_b64 s[4:5], s[6:7]
	s_cbranch_execz .LBB0_383
	s_waitcnt lgkmcnt(0)
	v_add_f32_e32 v3, v3, v4
	v_add_f32_e32 v0, v0, v2
	ds_write2st64_b32 v186, v0, v3 offset0:11 offset1:27
.LBB0_383:
	s_or_b64 exec, exec, s[4:5]
	s_waitcnt lgkmcnt(0)
	s_barrier
	s_waitcnt lgkmcnt(0)
	ds_read_b128 v[2:5], v225
	s_waitcnt lgkmcnt(0)
	v_mov_b32_e32 v6, v3
	v_mov_b32_e32 v7, v4
	v_mov_b32_e32 v3, v5
	v_pk_add_f32 v[2:3], v[6:7], v[2:3]
	s_nop 0
	v_add_f32_e32 v0, v2, v3
	v_or_b32_sdwa v2, s27, v220 dst_sel:DWORD dst_unused:UNUSED_PAD src0_sel:DWORD src1_sel:BYTE_0
	v_ashrrev_i32_e32 v3, 31, v2
	v_lshlrev_b64 v[2:3], 5, v[2:3]
	v_lshl_add_u64 v[2:3], v[158:159], 0, v[2:3]
	v_lshl_add_u64 v[2:3], s[46:47], 2, v[2:3]
	v_add_co_u32_e32 v2, vcc, 0x194ff000, v2
	s_nop 1
	v_addc_co_u32_e32 v3, vcc, 0, v3, vcc
	global_store_dword v[2:3], v0, off offset:4080

; __device__ __forceinline__ float rstd_of(const float* ss, int row) { const f32x4 p = *(const f32x4*)(ss + 4 * (size_t)row); return __builtin_amdgcn_rsqf(((p.x + p.y) + (p.z + p.w)) * (1.0f / D) + EPS); }
; __device__ __forceinline__ int tid_opaque() { int t = threadIdx.x; asm volatile("" : "+v"(t)); return t; }
; __device__ __forceinline__ int sgpr_opaque(int x) { asm volatile("" : "+s"(x)); return x; }
; #define INP(i) ((const float*)ldp(T, (i)))
; __device__ __forceinline__ void final_phase(const PT& T, int vc) {
;     const int tid = tid_opaque(), lane = tid & 63, wave = tid >> 6, R8 = sgpr_opaque(gridDim.x) >> 3, vx = sgpr_opaque(vc) & 7, vr = sgpr_opaque(vc) >> 3;
;     const float* ss = (const float*)(WSP + WS_CTL) + (size_t)8 * M * 4; const f32x4* gp = (const f32x4*)INP(3) + lane;
;     f32x4 gg[4];
; #pragma unroll
;     for (int j = 0; j < 4; ++j) gg[j] = gp[64 * j];
;     const bf16_t* XB = (const bf16_t*)(WSP + WS_XB); float* outp = OUTP;
;     for (int mi = vr * NWAVES + wave; mi < 4096; mi += R8 * NWAVES) { const int m = 4096 * vx + mi; const float rs = pg8::rstd_of(ss, m); const u32x2* xr = (const u32x2*)(XB + (size_t)m * D) + lane; f32x4* orow = (f32x4*)(outp + (size_t)m * D) + lane;
; #pragma unroll
;         for (int j = 0; j < 4; ++j) { const u32x2 b = xr[64 * j]; orow[64 * j] = (f32x4){bflo(b.x), bfhi(b.x), bflo(b.y), bfhi(b.y)} * gg[j] * rs; } }
; }
.LBB0_396:
	v_readlane_b32 s0, v254, 8
	v_readlane_b32 s6, v254, 22
	v_mov_b32_e32 v0, v220
	v_mov_b32_e32 v2, s0
	v_readlane_b32 s0, v254, 9
	s_mov_b32 s8, s68
	s_mov_b32 s9, s6
	v_mov_b32_e32 v6, s0
	s_waitcnt lgkmcnt(0)
	ds_read2_b64 v[2:5], v2 offset1:1
	ds_read_b64 v[6:7], v6
	v_ashrrev_i32_e32 v18, 6, v0
	s_and_b32 s10, s6, -8
	v_add_u32_e32 v24, s10, v18
	s_movk_i32 s6, 0x1000
	s_waitcnt lgkmcnt(0)
	v_readfirstlane_b32 s1, v5
	v_readfirstlane_b32 s0, v4
	v_readfirstlane_b32 s5, v7
	v_readfirstlane_b32 s4, v6
	v_readfirstlane_b32 s19, v3
	v_readfirstlane_b32 s18, v2
	v_cmp_gt_i32_e32 vcc, s6, v24
	s_and_saveexec_b64 s[6:7], vcc
	s_cbranch_execz .LBB0_399
	v_and_b32_e32 v25, 63, v0
	v_lshlrev_b32_e32 v0, 4, v25
	v_lshl_add_u64 v[14:15], s[4:5], 0, v[0:1]
	global_load_dwordx4 v[2:5], v[14:15], off
	global_load_dwordx4 v[6:9], v[14:15], off offset:1024
	global_load_dwordx4 v[10:13], v[14:15], off offset:2048
	s_nop 0
	global_load_dwordx4 v[14:17], v[14:15], off offset:3072
	s_lshl_b32 s4, s9, 12
	s_and_b32 s4, s4, 0x7000
	s_add_i32 s10, s10, s4
	v_add_u32_e32 v22, s10, v18
	v_ashrrev_i32_e32 v23, 31, v22
	s_and_b32 s8, s8, -8
	v_lshl_add_u64 v[18:19], v[22:23], 4, v[200:201]
	v_lshlrev_b64 v[20:21], 11, v[22:23]
	v_lshlrev_b64 v[22:23], 12, v[22:23]
	s_ashr_i32 s9, s8, 31
	v_or_b32_e32 v22, v22, v0
	s_lshl_b64 s[10:11], s[8:9], 4
	v_lshl_or_b32 v20, v25, 3, v20
	s_lshl_b64 s[16:17], s[8:9], 11
	v_lshl_add_u64 v[22:23], s[18:19], 0, v[22:23]
	s_lshl_b64 s[18:19], s[8:9], 12
	s_mov_b64 s[20:21], 0
.LBB0_398:
	v_lshl_add_u64 v[26:27], s[0:1], 0, v[18:19]
	global_load_dwordx4 v[26:29], v[26:27], off
	v_lshl_add_u64 v[30:31], s[0:1], 0, v[20:21]
	v_add_co_u32_e32 v30, vcc, s2, v30
	v_add_u32_e32 v24, s8, v24
	s_nop 0
	v_addc_co_u32_e32 v31, vcc, 0, v31, vcc
	global_load_dwordx2 v[32:33], v[30:31], off
	s_movk_i32 s4, 0xfff
	v_cmp_lt_i32_e32 vcc, s4, v24
	v_lshl_add_u64 v[18:19], v[18:19], 0, s[10:11]
	v_lshl_add_u64 v[20:21], v[20:21], 0, s[16:17]
	s_or_b64 s[20:21], vcc, s[20:21]
	s_waitcnt vmcnt(0) lgkmcnt(0)
	v_mov_b32_e32 v34, v27
	v_mov_b32_e32 v35, v28
	v_mov_b32_e32 v27, v29
	v_pk_add_f32 v[26:27], v[34:35], v[26:27]
	v_lshlrev_b32_e32 v28, 16, v33
	v_add_f32_e32 v0, v26, v27
	v_fmamk_f32 v0, v0, 0x3a800000, v224
	v_rsq_f32_e32 v0, v0
	v_lshlrev_b32_e32 v26, 16, v32
	v_and_b32_e32 v27, 0xffff0000, v32
	v_and_b32_e32 v29, 0xffff0000, v33
	v_pk_mul_f32 v[26:27], v[2:3], v[26:27]
	v_pk_mul_f32 v[28:29], v[4:5], v[28:29]
	v_pk_mul_f32 v[26:27], v[0:1], v[26:27] op_sel_hi:[0,1]
	v_pk_mul_f32 v[28:29], v[0:1], v[28:29] op_sel_hi:[0,1]
	global_store_dwordx4 v[22:23], v[26:29], off
	global_load_dwordx2 v[26:27], v[30:31], off offset:512
	s_waitcnt vmcnt(0) lgkmcnt(0)
	v_lshlrev_b32_e32 v28, 16, v26
	v_and_b32_e32 v29, 0xffff0000, v26
	v_lshlrev_b32_e32 v26, 16, v27
	v_and_b32_e32 v27, 0xffff0000, v27
	v_pk_mul_f32 v[32:33], v[6:7], v[28:29]
	v_pk_mul_f32 v[26:27], v[8:9], v[26:27]
	s_nop 0
	v_pk_mul_f32 v[28:29], v[0:1], v[26:27] op_sel_hi:[0,1]
	v_pk_mul_f32 v[26:27], v[0:1], v[32:33] op_sel_hi:[0,1]
	global_store_dwordx4 v[22:23], v[26:29], off offset:1024
	global_load_dwordx2 v[26:27], v[30:31], off offset:1024
	s_waitcnt vmcnt(0) lgkmcnt(0)
	v_lshlrev_b32_e32 v28, 16, v26
	v_and_b32_e32 v29, 0xffff0000, v26
	v_lshlrev_b32_e32 v26, 16, v27
	v_and_b32_e32 v27, 0xffff0000, v27
	v_pk_mul_f32 v[32:33], v[10:11], v[28:29]
	v_pk_mul_f32 v[26:27], v[12:13], v[26:27]
	s_nop 0
	v_pk_mul_f32 v[28:29], v[0:1], v[26:27] op_sel_hi:[0,1]
	v_pk_mul_f32 v[26:27], v[0:1], v[32:33] op_sel_hi:[0,1]
	global_store_dwordx4 v[22:23], v[26:29], off offset:2048
	global_load_dwordx2 v[26:27], v[30:31], off offset:1536
	s_waitcnt vmcnt(0) lgkmcnt(0)
	v_lshlrev_b32_e32 v28, 16, v26
	v_and_b32_e32 v29, 0xffff0000, v26
	v_lshlrev_b32_e32 v26, 16, v27
	v_and_b32_e32 v27, 0xffff0000, v27
	v_pk_mul_f32 v[30:31], v[14:15], v[28:29]
	v_pk_mul_f32 v[26:27], v[16:17], v[26:27]
	s_nop 0
	v_pk_mul_f32 v[28:29], v[0:1], v[26:27] op_sel_hi:[0,1]
	v_pk_mul_f32 v[26:27], v[0:1], v[30:31] op_sel_hi:[0,1]
	global_store_dwordx4 v[22:23], v[26:29], off offset:3072
	v_lshl_add_u64 v[22:23], v[22:23], 0, s[18:19]
	s_andn2_b64 exec, exec, s[20:21]
	s_cbranch_execnz .LBB0_398

; #define LAS __attribute__((address_space(3)))
; #define INP(i) ((const float*)ldp(T, (i)))
; #define TRJ(cnt, W, ldn, N, WT, ldk, gain, rbase, rstride) if (r >= 0) { if (r < (cnt)) { tr_item((W), (ldn), (N), (WT), (ldk), (gain), (rbase), (rstride), scr, r, lane); r = -1; } else r -= (cnt); }
; __device__ __forceinline__ void tr_item(const float* W, int ldn, int N, bf16_t* WT, int ldk, const float* gain, int rbase, int rstride, LAS float* scr, int item, int lane) {
;     const int nblk = N / 32, kb = item / nblk, nb = item % nblk, k0 = 64 * kb, n0 = 32 * nb;
;     f32x4 v[8]; float gk[8];
; #pragma unroll
;     for (int i = 0; i < 8; ++i) { const int kk = 8 * i + (lane >> 3); v[i] = *(const f32x4*)(W + (size_t)(k0 + kk) * ldn + n0 + 4 * (lane & 7)); gk[i] = gain ? gain[k0 + kk] : 1.0f; }
; __device__ __forceinline__ void prep_phase(const PT& T, LAS unsigned char* lds) {
;     ...
;         TRJ(I_1Kx2K, INP(4), 2048, 2048, Wb + WO_A_IN0, D, INP(1) + 0 * D, 0, 128)
.LBB0_408:
	s_andn2_b64 vcc, exec, s[0:1]
	s_cbranch_vccnz .LBB0_426
	v_readlane_b32 s0, v254, 15
	s_and_b32 s19, s16, 0x7e0
	s_and_b32 s20, s18, 0x3c0
	v_mov_b32_e32 v0, s0
	ds_read_b64 v[2:3], v0
	s_lshl_b32 s4, s19, 2
	v_or_b32_e32 v32, s20, v81
	v_lshlrev_b32_e32 v0, 2, v34
	v_mov_b32_e32 v78, 1.0
	s_waitcnt lgkmcnt(0)
	v_readfirstlane_b32 s0, v2
	v_readfirstlane_b32 s1, v3
	s_add_u32 s0, s0, s4
	s_addc_u32 s1, s1, 0
	v_lshl_add_u64 v[30:31], s[0:1], 0, v[0:1]
	v_lshlrev_b32_e32 v0, 13, v32
	v_lshl_add_u64 v[2:3], v[30:31], 0, v[0:1]
	global_load_dwordx4 v[2:5], v[2:3], off
	v_mov_b32_e32 v0, s79
	ds_read_b64 v[6:7], v0
	v_lshlrev_b32_e32 v82, 2, v32
	v_mov_b32_e32 v80, 1.0
	s_waitcnt lgkmcnt(0)
	v_readfirstlane_b32 s9, v7
	v_readfirstlane_b32 s8, v6
	s_cmp_lg_u64 s[8:9], 0
	s_cselect_b64 s[4:5], -1, 0
	s_cmp_eq_u64 s[8:9], 0
	s_cbranch_scc1 .LBB0_411
	v_mov_b32_e32 v83, v1
	v_lshl_add_u64 v[6:7], s[8:9], 0, v[82:83]
	global_load_dword v80, v[6:7], off
.LBB0_411:
	v_lshl_or_b32 v0, v32, 13, v228
	v_lshl_add_u64 v[6:7], v[30:31], 0, v[0:1]
	global_load_dwordx4 v[6:9], v[6:7], off
	v_cndmask_b32_e64 v0, 0, 1, s[4:5]
	v_cmp_ne_u32_e64 s[0:1], 1, v0
	s_andn2_b64 vcc, exec, s[4:5]
	s_cbranch_vccnz .LBB0_413
	v_mov_b32_e32 v83, v1
	v_lshl_add_u64 v[10:11], s[8:9], 0, v[82:83]
	global_load_dword v78, v[10:11], off offset:32
.LBB0_413:
	v_lshl_or_b32 v0, v32, 13, v229
	v_lshl_add_u64 v[10:11], v[30:31], 0, v[0:1]
	global_load_dwordx4 v[10:13], v[10:11], off
	v_mov_b32_e32 v84, 1.0
	s_and_b64 vcc, exec, s[0:1]
	v_mov_b32_e32 v86, 1.0
	s_cbranch_vccnz .LBB0_415
	v_mov_b32_e32 v83, v1
	v_lshl_add_u64 v[14:15], s[8:9], 0, v[82:83]
	global_load_dword v86, v[14:15], off offset:64
.LBB0_415:
	v_lshl_or_b32 v0, v32, 13, v230
	v_lshl_add_u64 v[14:15], v[30:31], 0, v[0:1]
	global_load_dwordx4 v[14:17], v[14:15], off
	s_and_b64 vcc, exec, s[0:1]
	s_cbranch_vccnz .LBB0_417
	v_mov_b32_e32 v83, v1
	v_lshl_add_u64 v[18:19], s[8:9], 0, v[82:83]
	global_load_dword v84, v[18:19], off offset:96
.LBB0_417:
	v_lshl_or_b32 v0, v32, 13, v231
	v_lshl_add_u64 v[18:19], v[30:31], 0, v[0:1]
	global_load_dwordx4 v[18:21], v[18:19], off
	v_mov_b32_e32 v88, 1.0
	s_and_b64 vcc, exec, s[0:1]
	v_mov_b32_e32 v90, 1.0
	s_cbranch_vccnz .LBB0_419
	v_mov_b32_e32 v83, v1
	v_lshl_add_u64 v[22:23], s[8:9], 0, v[82:83]
	global_load_dword v90, v[22:23], off offset:128
.LBB0_419:
	v_lshl_or_b32 v0, v32, 13, v232
	v_lshl_add_u64 v[22:23], v[30:31], 0, v[0:1]
	global_load_dwordx4 v[22:25], v[22:23], off
	s_and_b64 vcc, exec, s[0:1]
	s_cbranch_vccnz .LBB0_421
	v_mov_b32_e32 v83, v1
	v_lshl_add_u64 v[26:27], s[8:9], 0, v[82:83]
	global_load_dword v88, v[26:27], off offset:160
.LBB0_421:
	v_lshl_or_b32 v0, v32, 13, v233
	v_lshl_add_u64 v[26:27], v[30:31], 0, v[0:1]
	global_load_dwordx4 v[26:29], v[26:27], off
	v_mov_b32_e32 v92, 1.0
	s_and_b64 vcc, exec, s[0:1]
	v_mov_b32_e32 v94, 1.0
	s_cbranch_vccnz .LBB0_423
	v_mov_b32_e32 v83, v1
	v_lshl_add_u64 v[98:99], s[8:9], 0, v[82:83]
	global_load_dword v94, v[98:99], off offset:192
.LBB0_423:
	v_lshl_or_b32 v0, v32, 13, v234
	v_lshl_add_u64 v[30:31], v[30:31], 0, v[0:1]
	global_load_dwordx4 v[30:33], v[30:31], off
	s_and_b64 vcc, exec, s[0:1]
	s_cbranch_vccnz .LBB0_425
	v_mov_b32_e32 v83, v1
	v_lshl_add_u64 v[82:83], s[8:9], 0, v[82:83]
	global_load_dword v92, v[82:83], off offset:224
; #define LAS __attribute__((address_space(3)))
; #define LDS_WAIT() asm volatile("s_waitcnt lgkmcnt(0)" ::: "memory")
; __device__ __forceinline__ unsigned pk2(float lo, float hi) { return pg8::cvt_pk_bf16(lo, hi); }
; __device__ __forceinline__ void tr_item(const float* W, int ldn, int N, bf16_t* WT, int ldk, const float* gain, int rbase, int rstride, LAS float* scr, int item, int lane) {
;     ...
;     for (int i = 0; i < 8; ++i) { LAS float* d = scr + (8 * i + (lane >> 3)) * 33 + 4 * (lane & 7); d[0] = v[i].x * gk[i]; d[1] = v[i].y * gk[i]; d[2] = v[i].z * gk[i]; d[3] = v[i].w * gk[i]; }
;     LDS_WAIT(); asm volatile("" ::: "memory");
;     const int c = lane & 7;
; #pragma unroll
;     for (int j = 0; j < 4; ++j) { const int n = (lane >> 3) + 8 * j; const LAS float* s = scr + (8 * c) * 33 + n;
;         u32x4 o; o.x = pk2(s[0 * 33], s[1 * 33]); o.y = pk2(s[2 * 33], s[3 * 33]); o.z = pk2(s[4 * 33], s[5 * 33]); o.w = pk2(s[6 * 33], s[7 * 33]);
;         const int nn = n0 + n, dest = rbase + (nn >> 7) * rstride + (nn & 127);
;         *(u32x4*)(WT + (size_t)dest * ldk + k0 + 8 * c) = o; }
;     LDS_WAIT(); asm volatile("" ::: "memory");
.LBB0_425:
	s_waitcnt vmcnt(0) lgkmcnt(0)
	v_pk_mul_f32 v[2:3], v[2:3], v[80:81] op_sel_hi:[1,0]
	ds_write2_b32 v87, v2, v3 offset1:1
	v_pk_mul_f32 v[2:3], v[4:5], v[80:81] op_sel_hi:[1,0]
	ds_write2_b32 v87, v2, v3 offset0:2 offset1:3
	v_pk_mul_f32 v[2:3], v[6:7], v[78:79] op_sel_hi:[1,0]
	v_add_u32_e32 v0, v85, v91
	ds_write2_b32 v0, v2, v3 offset1:1
	v_pk_mul_f32 v[2:3], v[8:9], v[78:79] op_sel_hi:[1,0]
	ds_write2_b32 v0, v2, v3 offset0:2 offset1:3
	v_pk_mul_f32 v[2:3], v[10:11], v[86:87] op_sel_hi:[1,0]
	v_add_u32_e32 v4, 0x420, v0
	ds_write2_b32 v4, v2, v3 offset1:1
	v_pk_mul_f32 v[2:3], v[12:13], v[86:87] op_sel_hi:[1,0]
	v_add_u32_e32 v4, 0x428, v0
	ds_write2_b32 v4, v2, v3 offset1:1
	v_pk_mul_f32 v[2:3], v[14:15], v[84:85] op_sel_hi:[1,0]
	v_add_u32_e32 v4, 0x840, v0
	ds_write2_b32 v4, v2, v3 offset1:1
	v_pk_mul_f32 v[2:3], v[16:17], v[84:85] op_sel_hi:[1,0]
	v_add_u32_e32 v0, 0x848, v0
	ds_write2_b32 v0, v2, v3 offset1:1
	v_pk_mul_f32 v[2:3], v[18:19], v[90:91] op_sel_hi:[1,0]
	v_add_u32_e32 v0, 0x1080, v87
	ds_write2_b32 v0, v2, v3 offset1:1
	v_pk_mul_f32 v[2:3], v[20:21], v[90:91] op_sel_hi:[1,0]
	v_add_u32_e32 v0, 0x1088, v87
	ds_write2_b32 v0, v2, v3 offset1:1
	v_pk_mul_f32 v[2:3], v[22:23], v[88:89] op_sel_hi:[1,0]
	v_add_u32_e32 v0, 0x14a0, v87
	ds_write2_b32 v0, v2, v3 offset1:1
	v_pk_mul_f32 v[2:3], v[24:25], v[88:89] op_sel_hi:[1,0]
	v_add_u32_e32 v0, 0x14a8, v87
	ds_write2_b32 v0, v2, v3 offset1:1
	v_pk_mul_f32 v[2:3], v[26:27], v[94:95] op_sel_hi:[1,0]
	v_add_u32_e32 v0, 0x18c0, v87
	ds_write2_b32 v0, v2, v3 offset1:1
	v_pk_mul_f32 v[2:3], v[28:29], v[94:95] op_sel_hi:[1,0]
	v_add_u32_e32 v0, 0x18c8, v87
	ds_write2_b32 v0, v2, v3 offset1:1
	v_pk_mul_f32 v[2:3], v[30:31], v[92:93] op_sel_hi:[1,0]
	v_add_u32_e32 v0, 0x1ce0, v87
	ds_write2_b32 v0, v2, v3 offset1:1
	v_pk_mul_f32 v[2:3], v[32:33], v[92:93] op_sel_hi:[1,0]
	v_add_u32_e32 v0, 0x1ce8, v87
	ds_write2_b32 v0, v2, v3 offset1:1
	s_waitcnt lgkmcnt(0)
	ds_read2_b32 v[2:3], v96 offset1:33
	s_waitcnt lgkmcnt(0)
	v_cvt_pk_bf16_f32 v2, v2, v3
	ds_read2_b32 v[4:5], v96 offset0:66 offset1:99
	s_waitcnt lgkmcnt(0)
	v_cvt_pk_bf16_f32 v3, v4, v5
	ds_read2_b32 v[4:5], v96 offset0:132 offset1:165
	s_lshl_b32 s46, s20, 1
	v_or_b32_e32 v0, s19, v81
	s_waitcnt lgkmcnt(0)
	v_cvt_pk_bf16_f32 v4, v4, v5
	ds_read2_b32 v[6:7], v96 offset0:198 offset1:231
	v_lshl_add_u64 v[8:9], v[36:37], 0, s[46:47]
	v_lshlrev_b32_e32 v0, 11, v0
	s_waitcnt lgkmcnt(0)
	v_cvt_pk_bf16_f32 v5, v6, v7
	v_lshl_add_u64 v[6:7], v[8:9], 0, v[0:1]
	global_store_dwordx4 v[6:7], v[2:5], off
	ds_read2_b32 v[2:3], v96 offset0:8 offset1:41
	v_or_b32_e32 v0, s19, v89
	s_waitcnt lgkmcnt(0)
	v_cvt_pk_bf16_f32 v2, v2, v3
	ds_read2_b32 v[4:5], v96 offset0:74 offset1:107
	s_waitcnt lgkmcnt(0)
	v_cvt_pk_bf16_f32 v3, v4, v5
	ds_read2_b32 v[4:5], v96 offset0:140 offset1:173
	s_waitcnt lgkmcnt(0)
	v_cvt_pk_bf16_f32 v4, v4, v5
	ds_read2_b32 v[6:7], v96 offset0:206 offset1:239
	v_lshlrev_b32_e32 v0, 11, v0
	s_waitcnt lgkmcnt(0)
	v_cvt_pk_bf16_f32 v5, v6, v7
	v_lshl_add_u64 v[6:7], v[8:9], 0, v[0:1]
	global_store_dwordx4 v[6:7], v[2:5], off
	ds_read2_b32 v[2:3], v96 offset0:16 offset1:49
	v_or_b32_e32 v0, s19, v93
	s_waitcnt lgkmcnt(0)
	v_cvt_pk_bf16_f32 v2, v2, v3
	ds_read2_b32 v[4:5], v96 offset0:82 offset1:115
	s_waitcnt lgkmcnt(0)
	v_cvt_pk_bf16_f32 v3, v4, v5
	ds_read2_b32 v[4:5], v96 offset0:148 offset1:181
	s_waitcnt lgkmcnt(0)
	v_cvt_pk_bf16_f32 v4, v4, v5
	ds_read2_b32 v[6:7], v96 offset0:214 offset1:247
	v_lshlrev_b32_e32 v0, 11, v0
	s_waitcnt lgkmcnt(0)
	v_cvt_pk_bf16_f32 v5, v6, v7
	v_lshl_add_u64 v[6:7], v[8:9], 0, v[0:1]
	global_store_dwordx4 v[6:7], v[2:5], off
	ds_read2_b32 v[2:3], v96 offset0:24 offset1:57
	v_or_b32_e32 v0, s19, v95
	s_waitcnt lgkmcnt(0)
	v_cvt_pk_bf16_f32 v2, v2, v3
	ds_read2_b32 v[4:5], v96 offset0:90 offset1:123
	s_waitcnt lgkmcnt(0)
	v_cvt_pk_bf16_f32 v3, v4, v5
	ds_read2_b32 v[4:5], v96 offset0:156 offset1:189
	s_waitcnt lgkmcnt(0)
	v_cvt_pk_bf16_f32 v4, v4, v5
	ds_read2_b32 v[6:7], v96 offset0:222 offset1:255
	v_lshlrev_b32_e32 v0, 11, v0
	s_waitcnt lgkmcnt(0)
	v_cvt_pk_bf16_f32 v5, v6, v7
	v_lshl_add_u64 v[6:7], v[8:9], 0, v[0:1]
	global_store_dwordx4 v[6:7], v[2:5], off
	s_waitcnt lgkmcnt(0)
	s_mov_b32 s4, -1

; #define LAS __attribute__((address_space(3)))
; #define LDS_WAIT() asm volatile("s_waitcnt lgkmcnt(0)" ::: "memory")
; __device__ __forceinline__ unsigned pk2(float lo, float hi) { return pg8::cvt_pk_bf16(lo, hi); }
; __device__ __forceinline__ void tr_item(const float* W, int ldn, int N, bf16_t* WT, int ldk, const float* gain, int rbase, int rstride, LAS float* scr, int item, int lane) {
;     const int nblk = N / 32, kb = item / nblk, nb = item % nblk, k0 = 64 * kb, n0 = 32 * nb;
;     f32x4 v[8]; float gk[8];
; #pragma unroll
;     for (int i = 0; i < 8; ++i) { const int kk = 8 * i + (lane >> 3); v[i] = *(const f32x4*)(W + (size_t)(k0 + kk) * ldn + n0 + 4 * (lane & 7)); gk[i] = gain ? gain[k0 + kk] : 1.0f; }
; #pragma unroll
;     for (int i = 0; i < 8; ++i) { LAS float* d = scr + (8 * i + (lane >> 3)) * 33 + 4 * (lane & 7); d[0] = v[i].x * gk[i]; d[1] = v[i].y * gk[i]; d[2] = v[i].z * gk[i]; d[3] = v[i].w * gk[i]; }
;     LDS_WAIT(); asm volatile("" ::: "memory");
;     const int c = lane & 7;
; #pragma unroll
;     for (int j = 0; j < 4; ++j) { const int n = (lane >> 3) + 8 * j; const LAS float* s = scr + (8 * c) * 33 + n;
;         u32x4 o; o.x = pk2(s[0 * 33], s[1 * 33]); o.y = pk2(s[2 * 33], s[3 * 33]); o.z = pk2(s[4 * 33], s[5 * 33]); o.w = pk2(s[6 * 33], s[7 * 33]);
;         const int nn = n0 + n, dest = rbase + (nn >> 7) * rstride + (nn & 127);
;         *(u32x4*)(WT + (size_t)dest * ldk + k0 + 8 * c) = o; }
;     LDS_WAIT(); asm volatile("" ::: "memory");
.LBB0_429:
	s_andn2_b64 vcc, exec, s[0:1]
	s_cbranch_vccnz .LBB0_431
	v_readlane_b32 s0, v254, 16
	s_lshl_b32 s1, s4, 5
	v_add_u32_e32 v78, 0x1080, v87
	v_mov_b32_e32 v0, s0
	ds_read_b64 v[2:3], v0
	s_lshl_b32 s0, s4, 1
	s_and_b32 s8, s0, 0x3c0
	s_and_b32 s0, s1, 0x3e0
	s_lshl_b32 s1, s0, 2
	s_waitcnt lgkmcnt(0)
	v_readfirstlane_b32 s4, v2
	v_readfirstlane_b32 s5, v3
	s_add_u32 s4, s4, s1
	v_or_b32_e32 v4, s8, v81
	s_addc_u32 s5, s5, 0
	v_lshlrev_b32_e32 v0, 2, v34
	v_lshl_add_u64 v[2:3], s[4:5], 0, v[0:1]
	v_lshlrev_b32_e32 v0, 12, v4
	v_lshl_add_u64 v[30:31], v[2:3], 0, v[0:1]
	v_add_co_u32_e32 v6, vcc, s77, v30
	v_add_u32_e32 v0, v85, v91
	s_nop 0
	v_addc_co_u32_e32 v7, vcc, 0, v31, vcc
	v_add_co_u32_e32 v10, vcc, s24, v30
	global_load_dwordx4 v[2:5], v[30:31], off
	s_nop 0
	global_load_dwordx4 v[6:9], v[6:7], off
	v_addc_co_u32_e32 v11, vcc, 0, v31, vcc
	v_add_co_u32_e32 v14, vcc, s71, v30
	v_add_u32_e32 v80, 0x1088, v87
	s_nop 0
	v_addc_co_u32_e32 v15, vcc, 0, v31, vcc
	v_add_co_u32_e32 v18, vcc, s27, v30
	global_load_dwordx4 v[10:13], v[10:11], off
	s_nop 0
	global_load_dwordx4 v[14:17], v[14:15], off
	v_addc_co_u32_e32 v19, vcc, 0, v31, vcc
	v_add_co_u32_e32 v22, vcc, s28, v30
	v_add_u32_e32 v82, 0x14a0, v87
	s_nop 0
	v_addc_co_u32_e32 v23, vcc, 0, v31, vcc
	global_load_dwordx4 v[18:21], v[18:19], off
	s_nop 0
	global_load_dwordx4 v[22:25], v[22:23], off
	v_add_co_u32_e32 v26, vcc, s81, v30
	v_add_u32_e32 v83, 0x14a8, v87
	s_nop 0
	v_addc_co_u32_e32 v27, vcc, 0, v31, vcc
	global_load_dwordx4 v[26:29], v[26:27], off
	v_add_co_u32_e32 v30, vcc, s29, v30
	v_add_u32_e32 v84, 0x18c0, v87
	s_nop 0
	v_addc_co_u32_e32 v31, vcc, 0, v31, vcc
	global_load_dwordx4 v[30:33], v[30:31], off
	v_add_u32_e32 v86, 0x18c8, v87
	v_add_u32_e32 v88, 0x1ce0, v87
	v_add_u32_e32 v90, 0x1ce8, v87
	v_add_u32_e32 v92, 0x420, v0
	v_add_u32_e32 v94, 0x428, v0
	v_add_u32_e32 v97, 0x840, v0
	v_add_u32_e32 v98, 0x848, v0
	s_lshl_b32 s46, s8, 1
	s_mov_b32 s5, -1
	s_waitcnt vmcnt(0) lgkmcnt(0)
	ds_write2_b32 v87, v2, v3 offset1:1
	ds_write2_b32 v87, v4, v5 offset0:2 offset1:3
	ds_write2_b32 v0, v6, v7 offset1:1
	ds_write2_b32 v0, v8, v9 offset0:2 offset1:3
	ds_write2_b32 v92, v10, v11 offset1:1
	ds_write2_b32 v94, v12, v13 offset1:1
	ds_write2_b32 v97, v14, v15 offset1:1
	ds_write2_b32 v98, v16, v17 offset1:1
	ds_write2_b32 v78, v18, v19 offset1:1
	ds_write2_b32 v80, v20, v21 offset1:1
	ds_write2_b32 v82, v22, v23 offset1:1
	ds_write2_b32 v83, v24, v25 offset1:1
	ds_write2_b32 v84, v26, v27 offset1:1
	ds_write2_b32 v86, v28, v29 offset1:1
	ds_write2_b32 v88, v30, v31 offset1:1
	ds_write2_b32 v90, v32, v33 offset1:1
	s_waitcnt lgkmcnt(0)
	ds_read2_b32 v[2:3], v96 offset1:33
	v_or_b32_e32 v0, s0, v81
	s_waitcnt lgkmcnt(0)
	v_cvt_pk_bf16_f32 v2, v2, v3
	ds_read2_b32 v[4:5], v96 offset0:66 offset1:99
	v_lshl_add_u64 v[8:9], v[38:39], 0, s[46:47]
	v_lshlrev_b32_e32 v0, 11, v0
	s_waitcnt lgkmcnt(0)
	v_cvt_pk_bf16_f32 v3, v4, v5
	ds_read2_b32 v[4:5], v96 offset0:132 offset1:165
	v_lshl_add_u64 v[10:11], v[8:9], 0, v[0:1]
	s_waitcnt lgkmcnt(0)
	v_cvt_pk_bf16_f32 v4, v4, v5
	ds_read2_b32 v[6:7], v96 offset0:198 offset1:231
	s_waitcnt lgkmcnt(0)
	v_cvt_pk_bf16_f32 v5, v6, v7
	global_store_dwordx4 v[10:11], v[2:5], off
	ds_read2_b32 v[2:3], v96 offset0:8 offset1:41
	v_or_b32_e32 v0, s0, v89
	s_waitcnt lgkmcnt(0)
	v_cvt_pk_bf16_f32 v2, v2, v3
	ds_read2_b32 v[4:5], v96 offset0:74 offset1:107
	v_lshlrev_b32_e32 v0, 11, v0
	s_waitcnt lgkmcnt(0)
	v_cvt_pk_bf16_f32 v3, v4, v5
	ds_read2_b32 v[4:5], v96 offset0:140 offset1:173
	v_lshl_add_u64 v[10:11], v[8:9], 0, v[0:1]
	s_waitcnt lgkmcnt(0)
	v_cvt_pk_bf16_f32 v4, v4, v5
	ds_read2_b32 v[6:7], v96 offset0:206 offset1:239
	s_waitcnt lgkmcnt(0)
	v_cvt_pk_bf16_f32 v5, v6, v7
	global_store_dwordx4 v[10:11], v[2:5], off
	ds_read2_b32 v[2:3], v96 offset0:16 offset1:49
	v_or_b32_e32 v0, s0, v93
	s_waitcnt lgkmcnt(0)
	v_cvt_pk_bf16_f32 v2, v2, v3
	ds_read2_b32 v[4:5], v96 offset0:82 offset1:115
	v_lshlrev_b32_e32 v0, 11, v0
	s_waitcnt lgkmcnt(0)
	v_cvt_pk_bf16_f32 v3, v4, v5
	ds_read2_b32 v[4:5], v96 offset0:148 offset1:181
	v_lshl_add_u64 v[10:11], v[8:9], 0, v[0:1]
	s_waitcnt lgkmcnt(0)
	v_cvt_pk_bf16_f32 v4, v4, v5
	ds_read2_b32 v[6:7], v96 offset0:214 offset1:247
	s_waitcnt lgkmcnt(0)
	v_cvt_pk_bf16_f32 v5, v6, v7
	global_store_dwordx4 v[10:11], v[2:5], off
	ds_read2_b32 v[2:3], v96 offset0:24 offset1:57
	v_or_b32_e32 v0, s0, v95
	s_waitcnt lgkmcnt(0)
	v_cvt_pk_bf16_f32 v2, v2, v3
	ds_read2_b32 v[4:5], v96 offset0:90 offset1:123
	s_waitcnt lgkmcnt(0)
	v_cvt_pk_bf16_f32 v3, v4, v5
	ds_read2_b32 v[4:5], v96 offset0:156 offset1:189
	s_waitcnt lgkmcnt(0)
	v_cvt_pk_bf16_f32 v4, v4, v5
	ds_read2_b32 v[6:7], v96 offset0:222 offset1:255
	v_lshlrev_b32_e32 v0, 11, v0
	s_waitcnt lgkmcnt(0)
	v_cvt_pk_bf16_f32 v5, v6, v7
	v_lshl_add_u64 v[6:7], v[8:9], 0, v[0:1]
	global_store_dwordx4 v[6:7], v[2:5], off
	s_waitcnt lgkmcnt(0)

; #define LAS __attribute__((address_space(3)))
; #define LDS_WAIT() asm volatile("s_waitcnt lgkmcnt(0)" ::: "memory")
; __device__ __forceinline__ unsigned pk2(float lo, float hi) { return pg8::cvt_pk_bf16(lo, hi); }
; #define INP(i) ((const float*)ldp(T, (i)))
; #define TRJ(cnt, W, ldn, N, WT, ldk, gain, rbase, rstride) if (r >= 0) { if (r < (cnt)) { tr_item((W), (ldn), (N), (WT), (ldk), (gain), (rbase), (rstride), scr, r, lane); r = -1; } else r -= (cnt); }
; __device__ __forceinline__ void tr_item(const float* W, int ldn, int N, bf16_t* WT, int ldk, const float* gain, int rbase, int rstride, LAS float* scr, int item, int lane) {
;     const int nblk = N / 32, kb = item / nblk, nb = item % nblk, k0 = 64 * kb, n0 = 32 * nb;
;     f32x4 v[8]; float gk[8];
; #pragma unroll
;     for (int i = 0; i < 8; ++i) { const int kk = 8 * i + (lane >> 3); v[i] = *(const f32x4*)(W + (size_t)(k0 + kk) * ldn + n0 + 4 * (lane & 7)); gk[i] = gain ? gain[k0 + kk] : 1.0f; }
; #pragma unroll
;     for (int i = 0; i < 8; ++i) { LAS float* d = scr + (8 * i + (lane >> 3)) * 33 + 4 * (lane & 7); d[0] = v[i].x * gk[i]; d[1] = v[i].y * gk[i]; d[2] = v[i].z * gk[i]; d[3] = v[i].w * gk[i]; }
;     LDS_WAIT(); asm volatile("" ::: "memory");
;     const int c = lane & 7;
; #pragma unroll
;     for (int j = 0; j < 4; ++j) { const int n = (lane >> 3) + 8 * j; const LAS float* s = scr + (8 * c) * 33 + n;
;         u32x4 o; o.x = pk2(s[0 * 33], s[1 * 33]); o.y = pk2(s[2 * 33], s[3 * 33]); o.z = pk2(s[4 * 33], s[5 * 33]); o.w = pk2(s[6 * 33], s[7 * 33]);
;         const int nn = n0 + n, dest = rbase + (nn >> 7) * rstride + (nn & 127);
;         *(u32x4*)(WT + (size_t)dest * ldk + k0 + 8 * c) = o; }
;     LDS_WAIT(); asm volatile("" ::: "memory");
; __device__ __forceinline__ void prep_phase(const PT& T, LAS unsigned char* lds) {
;     ...
;         TRJ(I_1Kx2K, INP(4) + (size_t)D * 2048, 2048, 2048, Wb + WO_A_STRIDE + WO_A_IN0, D, INP(1) + 3 * D, 0, 128)
.LBB0_435:
	s_andn2_b64 vcc, exec, s[0:1]
	s_cbranch_vccnz .LBB0_437
	v_readlane_b32 s0, v254, 15
	v_add_u32_e32 v92, 0x1080, v87
	v_add_u32_e32 v94, 0x1088, v87
	v_mov_b32_e32 v0, s0
	ds_read_b64 v[2:3], v0
	v_mov_b32_e32 v0, s79
	ds_read_b64 v[4:5], v0
	v_lshlrev_b32_e32 v0, 2, v34
	v_add_u32_e32 v97, 0x14a0, v87
	s_waitcnt lgkmcnt(0)
	v_readfirstlane_b32 s8, v2
	v_readfirstlane_b32 s9, v3
	v_readfirstlane_b32 s0, v4
	v_readfirstlane_b32 s1, v5
	s_add_u32 s0, s0, 0x3000
	s_addc_u32 s1, s1, 0
	s_and_b32 s5, s4, 0x3c0
	s_lshl_b32 s4, s4, 5
	s_and_b32 s4, s4, 0x7e0
	s_lshl_b32 s19, s4, 2
	s_add_u32 s8, s8, s19
	s_addc_u32 s9, s9, 0
	v_or_b32_e32 v83, s5, v81
	v_lshl_add_u64 v[2:3], s[8:9], 0, v[0:1]
	s_mov_b64 s[8:9], 0x800000
	v_lshl_add_u64 v[30:31], v[2:3], 0, s[8:9]
	v_lshlrev_b32_e32 v0, 13, v83
	v_lshl_add_u64 v[2:3], v[30:31], 0, v[0:1]
	v_lshlrev_b32_e32 v0, 2, v83
	v_or_b32_e32 v10, 8, v83
	v_lshl_add_u64 v[6:7], s[0:1], 0, v[0:1]
	v_lshlrev_b32_e32 v0, 13, v10
	global_load_dword v78, v[6:7], off
	v_lshl_add_u64 v[6:7], v[30:31], 0, v[0:1]
	v_lshlrev_b32_e32 v0, 2, v10
	v_or_b32_e32 v14, 16, v83
	v_lshl_add_u64 v[10:11], s[0:1], 0, v[0:1]
	v_lshlrev_b32_e32 v0, 13, v14
	global_load_dword v80, v[10:11], off
	v_lshl_add_u64 v[10:11], v[30:31], 0, v[0:1]
	v_lshlrev_b32_e32 v0, 2, v14
	v_or_b32_e32 v18, 24, v83
	v_lshl_add_u64 v[14:15], s[0:1], 0, v[0:1]
	v_lshlrev_b32_e32 v0, 13, v18
	global_load_dword v82, v[14:15], off
	v_lshl_add_u64 v[14:15], v[30:31], 0, v[0:1]
	v_lshlrev_b32_e32 v0, 2, v18
	v_or_b32_e32 v22, 32, v83
	v_lshl_add_u64 v[18:19], s[0:1], 0, v[0:1]
	v_lshlrev_b32_e32 v0, 13, v22
	global_load_dwordx4 v[2:5], v[2:3], off
	v_or_b32_e32 v26, 40, v83
	global_load_dword v84, v[18:19], off
	v_lshl_add_u64 v[18:19], v[30:31], 0, v[0:1]
	v_lshlrev_b32_e32 v0, 2, v22
	global_load_dwordx4 v[6:9], v[6:7], off
	v_lshl_add_u64 v[22:23], s[0:1], 0, v[0:1]
	v_lshlrev_b32_e32 v0, 13, v26
	global_load_dwordx4 v[10:13], v[10:11], off
	v_or_b32_e32 v32, 48, v83
	global_load_dword v86, v[22:23], off
	v_lshl_add_u64 v[22:23], v[30:31], 0, v[0:1]
	v_lshlrev_b32_e32 v0, 2, v26
	global_load_dwordx4 v[14:17], v[14:15], off
	v_lshl_add_u64 v[26:27], s[0:1], 0, v[0:1]
	v_lshlrev_b32_e32 v0, 13, v32
	global_load_dwordx4 v[18:21], v[18:19], off
	v_or_b32_e32 v83, 56, v83
	global_load_dword v88, v[26:27], off
	v_lshl_add_u64 v[26:27], v[30:31], 0, v[0:1]
	v_lshlrev_b32_e32 v0, 2, v32
	global_load_dwordx4 v[22:25], v[22:23], off
	v_lshl_add_u64 v[32:33], s[0:1], 0, v[0:1]
	v_lshlrev_b32_e32 v0, 13, v83
	global_load_dwordx4 v[26:29], v[26:27], off
	v_lshl_add_u64 v[30:31], v[30:31], 0, v[0:1]
	global_load_dword v90, v[32:33], off
	v_lshlrev_b32_e32 v0, 2, v83
	v_lshl_add_u64 v[98:99], s[0:1], 0, v[0:1]
	global_load_dword v0, v[98:99], off
	v_add_u32_e32 v83, v85, v91
	global_load_dwordx4 v[30:33], v[30:31], off
	v_add_u32_e32 v100, 0x420, v83
	v_add_u32_e32 v101, 0x428, v83
	v_add_u32_e32 v102, 0x840, v83
	v_add_u32_e32 v103, 0x848, v83
	v_add_u32_e32 v98, 0x14a8, v87
	v_add_u32_e32 v99, 0x18c0, v87
	s_lshl_b32 s46, s5, 1
	s_mov_b32 s5, -1
	s_waitcnt vmcnt(0) lgkmcnt(0)
	v_pk_mul_f32 v[2:3], v[2:3], v[78:79] op_sel_hi:[1,0]
	v_pk_mul_f32 v[4:5], v[4:5], v[78:79] op_sel_hi:[1,0]
	ds_write2_b32 v87, v2, v3 offset1:1
	ds_write2_b32 v87, v4, v5 offset0:2 offset1:3
	v_pk_mul_f32 v[2:3], v[6:7], v[80:81] op_sel_hi:[1,0]
	v_pk_mul_f32 v[4:5], v[8:9], v[80:81] op_sel_hi:[1,0]
	ds_write2_b32 v83, v2, v3 offset1:1
	ds_write2_b32 v83, v4, v5 offset0:2 offset1:3
	v_pk_mul_f32 v[2:3], v[10:11], v[82:83] op_sel_hi:[1,0]
	v_pk_mul_f32 v[4:5], v[12:13], v[82:83] op_sel_hi:[1,0]
	ds_write2_b32 v100, v2, v3 offset1:1
	ds_write2_b32 v101, v4, v5 offset1:1
	v_lshl_add_u64 v[8:9], v[40:41], 0, s[46:47]
	v_pk_mul_f32 v[2:3], v[14:15], v[84:85] op_sel_hi:[1,0]
	v_pk_mul_f32 v[4:5], v[16:17], v[84:85] op_sel_hi:[1,0]
	ds_write2_b32 v102, v2, v3 offset1:1
	ds_write2_b32 v103, v4, v5 offset1:1
	v_pk_mul_f32 v[2:3], v[18:19], v[86:87] op_sel_hi:[1,0]
	v_pk_mul_f32 v[4:5], v[20:21], v[86:87] op_sel_hi:[1,0]
	ds_write2_b32 v92, v2, v3 offset1:1
	ds_write2_b32 v94, v4, v5 offset1:1
	v_pk_mul_f32 v[2:3], v[22:23], v[88:89] op_sel_hi:[1,0]
	v_pk_mul_f32 v[4:5], v[24:25], v[88:89] op_sel_hi:[1,0]
	ds_write2_b32 v97, v2, v3 offset1:1
	ds_write2_b32 v98, v4, v5 offset1:1
	v_add_u32_e32 v4, 0x18c8, v87
	v_pk_mul_f32 v[2:3], v[26:27], v[90:91] op_sel_hi:[1,0]
	ds_write2_b32 v99, v2, v3 offset1:1
	v_pk_mul_f32 v[2:3], v[28:29], v[90:91] op_sel_hi:[1,0]
	ds_write2_b32 v4, v2, v3 offset1:1
	v_add_u32_e32 v4, 0x1ce0, v87
	v_pk_mul_f32 v[2:3], v[30:31], v[0:1] op_sel_hi:[1,0]
	ds_write2_b32 v4, v2, v3 offset1:1
	v_pk_mul_f32 v[2:3], v[32:33], v[0:1] op_sel_hi:[1,0]
	v_add_u32_e32 v0, 0x1ce8, v87
	ds_write2_b32 v0, v2, v3 offset1:1
	s_waitcnt lgkmcnt(0)
	ds_read2_b32 v[2:3], v96 offset1:33
	v_or_b32_e32 v0, s4, v81
	s_waitcnt lgkmcnt(0)
	v_cvt_pk_bf16_f32 v2, v2, v3
	ds_read2_b32 v[4:5], v96 offset0:66 offset1:99
	v_lshlrev_b32_e32 v0, 11, v0
	s_waitcnt lgkmcnt(0)
	v_cvt_pk_bf16_f32 v3, v4, v5
	ds_read2_b32 v[4:5], v96 offset0:132 offset1:165
	v_lshl_add_u64 v[10:11], v[8:9], 0, v[0:1]
	s_waitcnt lgkmcnt(0)
	v_cvt_pk_bf16_f32 v4, v4, v5
	ds_read2_b32 v[6:7], v96 offset0:198 offset1:231
	s_waitcnt lgkmcnt(0)
	v_cvt_pk_bf16_f32 v5, v6, v7
	global_store_dwordx4 v[10:11], v[2:5], off
	ds_read2_b32 v[2:3], v96 offset0:8 offset1:41
	v_or_b32_e32 v0, s4, v89
	s_waitcnt lgkmcnt(0)
	v_cvt_pk_bf16_f32 v2, v2, v3
	ds_read2_b32 v[4:5], v96 offset0:74 offset1:107
	v_lshlrev_b32_e32 v0, 11, v0
	s_waitcnt lgkmcnt(0)
	v_cvt_pk_bf16_f32 v3, v4, v5
	ds_read2_b32 v[4:5], v96 offset0:140 offset1:173
	v_lshl_add_u64 v[10:11], v[8:9], 0, v[0:1]
	s_waitcnt lgkmcnt(0)
	v_cvt_pk_bf16_f32 v4, v4, v5
	ds_read2_b32 v[6:7], v96 offset0:206 offset1:239
	s_waitcnt lgkmcnt(0)
	v_cvt_pk_bf16_f32 v5, v6, v7
	global_store_dwordx4 v[10:11], v[2:5], off
	ds_read2_b32 v[2:3], v96 offset0:16 offset1:49
	v_or_b32_e32 v0, s4, v93
	s_waitcnt lgkmcnt(0)
	v_cvt_pk_bf16_f32 v2, v2, v3
	ds_read2_b32 v[4:5], v96 offset0:82 offset1:115
	v_lshlrev_b32_e32 v0, 11, v0
	s_waitcnt lgkmcnt(0)
	v_cvt_pk_bf16_f32 v3, v4, v5
	ds_read2_b32 v[4:5], v96 offset0:148 offset1:181
	v_lshl_add_u64 v[10:11], v[8:9], 0, v[0:1]
	s_waitcnt lgkmcnt(0)
	v_cvt_pk_bf16_f32 v4, v4, v5
	ds_read2_b32 v[6:7], v96 offset0:214 offset1:247
	s_waitcnt lgkmcnt(0)
	v_cvt_pk_bf16_f32 v5, v6, v7
	global_store_dwordx4 v[10:11], v[2:5], off
	ds_read2_b32 v[2:3], v96 offset0:24 offset1:57
	v_or_b32_e32 v0, s4, v95
	s_waitcnt lgkmcnt(0)
	v_cvt_pk_bf16_f32 v2, v2, v3
	ds_read2_b32 v[4:5], v96 offset0:90 offset1:123
	s_waitcnt lgkmcnt(0)
	v_cvt_pk_bf16_f32 v3, v4, v5
	ds_read2_b32 v[4:5], v96 offset0:156 offset1:189
	s_waitcnt lgkmcnt(0)
	v_cvt_pk_bf16_f32 v4, v4, v5
	ds_read2_b32 v[6:7], v96 offset0:222 offset1:255
	v_lshlrev_b32_e32 v0, 11, v0
	s_waitcnt lgkmcnt(0)
	v_cvt_pk_bf16_f32 v5, v6, v7
	v_lshl_add_u64 v[6:7], v[8:9], 0, v[0:1]
	global_store_dwordx4 v[6:7], v[2:5], off
	s_waitcnt lgkmcnt(0)

; #define LAS __attribute__((address_space(3)))
; #define LDS_WAIT() asm volatile("s_waitcnt lgkmcnt(0)" ::: "memory")
; __device__ __forceinline__ unsigned pk2(float lo, float hi) { return pg8::cvt_pk_bf16(lo, hi); }
; #define INP(i) ((const float*)ldp(T, (i)))
; #define TRJ(cnt, W, ldn, N, WT, ldk, gain, rbase, rstride) if (r >= 0) { if (r < (cnt)) { tr_item((W), (ldn), (N), (WT), (ldk), (gain), (rbase), (rstride), scr, r, lane); r = -1; } else r -= (cnt); }
; __device__ __forceinline__ void tr_item(const float* W, int ldn, int N, bf16_t* WT, int ldk, const float* gain, int rbase, int rstride, LAS float* scr, int item, int lane) {
;     const int nblk = N / 32, kb = item / nblk, nb = item % nblk, k0 = 64 * kb, n0 = 32 * nb;
;     f32x4 v[8]; float gk[8];
; #pragma unroll
;     for (int i = 0; i < 8; ++i) { const int kk = 8 * i + (lane >> 3); v[i] = *(const f32x4*)(W + (size_t)(k0 + kk) * ldn + n0 + 4 * (lane & 7)); gk[i] = gain ? gain[k0 + kk] : 1.0f; }
; #pragma unroll
;     for (int i = 0; i < 8; ++i) { LAS float* d = scr + (8 * i + (lane >> 3)) * 33 + 4 * (lane & 7); d[0] = v[i].x * gk[i]; d[1] = v[i].y * gk[i]; d[2] = v[i].z * gk[i]; d[3] = v[i].w * gk[i]; }
;     LDS_WAIT(); asm volatile("" ::: "memory");
;     const int c = lane & 7;
; #pragma unroll
;     for (int j = 0; j < 4; ++j) { const int n = (lane >> 3) + 8 * j; const LAS float* s = scr + (8 * c) * 33 + n;
;         u32x4 o; o.x = pk2(s[0 * 33], s[1 * 33]); o.y = pk2(s[2 * 33], s[3 * 33]); o.z = pk2(s[4 * 33], s[5 * 33]); o.w = pk2(s[6 * 33], s[7 * 33]);
;         const int nn = n0 + n, dest = rbase + (nn >> 7) * rstride + (nn & 127);
;         *(u32x4*)(WT + (size_t)dest * ldk + k0 + 8 * c) = o; }
;     LDS_WAIT(); asm volatile("" ::: "memory");
; __device__ __forceinline__ void prep_phase(const PT& T, LAS unsigned char* lds) {
;     ...
;         TRJ(I_1Kx1K, INP(8) + (size_t)D * D, D, D, Wb + WO_A_STRIDE + WO_A_OUT0, D, nullptr, 0, 128)
.LBB0_441:
	s_andn2_b64 vcc, exec, s[0:1]
	s_cbranch_vccnz .LBB0_443
	v_readlane_b32 s0, v254, 16
	s_lshl_b32 s1, s4, 5
	v_add_u32_e32 v78, 0x1080, v87
	v_mov_b32_e32 v0, s0
	ds_read_b64 v[2:3], v0
	s_lshl_b32 s0, s4, 1
	s_and_b32 s8, s0, 0x3c0
	s_and_b32 s0, s1, 0x3e0
	s_lshl_b32 s1, s0, 2
	s_waitcnt lgkmcnt(0)
	v_readfirstlane_b32 s4, v2
	v_readfirstlane_b32 s5, v3
	s_add_u32 s4, s4, s1
	v_or_b32_e32 v4, s8, v81
	s_addc_u32 s5, s5, 0
	v_lshlrev_b32_e32 v0, 2, v34
	v_lshl_add_u64 v[2:3], s[4:5], 0, v[0:1]
	v_lshlrev_b32_e32 v0, 12, v4
	v_lshl_add_u64 v[30:31], v[2:3], 0, v[0:1]
	s_mov_b32 s1, 0x400000
	v_add_co_u32_e32 v2, vcc, s1, v30
	s_mov_b32 s1, 0x408000
	s_nop 0
	v_addc_co_u32_e32 v3, vcc, 0, v31, vcc
	v_add_co_u32_e32 v6, vcc, s1, v30
	s_mov_b32 s1, 0x410000
	s_nop 0
	v_addc_co_u32_e32 v7, vcc, 0, v31, vcc
	v_add_co_u32_e32 v10, vcc, s1, v30
	s_mov_b32 s1, 0x418000
	s_nop 0
	v_addc_co_u32_e32 v11, vcc, 0, v31, vcc
	v_add_co_u32_e32 v14, vcc, s1, v30
	s_mov_b32 s1, 0x420000
	s_nop 0
	v_addc_co_u32_e32 v15, vcc, 0, v31, vcc
	v_add_co_u32_e32 v18, vcc, s1, v30
	s_mov_b32 s1, 0x428000
	s_nop 0
	v_addc_co_u32_e32 v19, vcc, 0, v31, vcc
	v_add_co_u32_e32 v22, vcc, s1, v30
	global_load_dwordx4 v[2:5], v[2:3], off
	s_nop 0
	global_load_dwordx4 v[6:9], v[6:7], off
	v_addc_co_u32_e32 v23, vcc, 0, v31, vcc
	global_load_dwordx4 v[10:13], v[10:11], off
	s_nop 0
	global_load_dwordx4 v[14:17], v[14:15], off
	s_nop 0
	global_load_dwordx4 v[18:21], v[18:19], off
	s_nop 0
	global_load_dwordx4 v[22:25], v[22:23], off
	s_mov_b32 s1, 0x430000
	v_add_co_u32_e32 v26, vcc, s1, v30
	s_mov_b32 s1, 0x438000
	s_nop 0
	v_addc_co_u32_e32 v27, vcc, 0, v31, vcc
	global_load_dwordx4 v[26:29], v[26:27], off
	v_add_co_u32_e32 v30, vcc, s1, v30
	v_add_u32_e32 v0, v85, v91
	s_nop 0
	v_addc_co_u32_e32 v31, vcc, 0, v31, vcc
	global_load_dwordx4 v[30:33], v[30:31], off
	v_add_u32_e32 v80, 0x1088, v87
	v_add_u32_e32 v82, 0x14a0, v87
	v_add_u32_e32 v83, 0x14a8, v87
	v_add_u32_e32 v84, 0x18c0, v87
	v_add_u32_e32 v86, 0x18c8, v87
	v_add_u32_e32 v88, 0x1ce0, v87
	v_add_u32_e32 v90, 0x1ce8, v87
	v_add_u32_e32 v92, 0x420, v0
	v_add_u32_e32 v94, 0x428, v0
	v_add_u32_e32 v97, 0x840, v0
	v_add_u32_e32 v98, 0x848, v0
	s_lshl_b32 s46, s8, 1
	s_mov_b32 s5, -1
	s_waitcnt vmcnt(0) lgkmcnt(0)
	ds_write2_b32 v87, v2, v3 offset1:1
	ds_write2_b32 v87, v4, v5 offset0:2 offset1:3
	ds_write2_b32 v0, v6, v7 offset1:1
	ds_write2_b32 v0, v8, v9 offset0:2 offset1:3
	ds_write2_b32 v92, v10, v11 offset1:1
	ds_write2_b32 v94, v12, v13 offset1:1
	ds_write2_b32 v97, v14, v15 offset1:1
	ds_write2_b32 v98, v16, v17 offset1:1
	ds_write2_b32 v78, v18, v19 offset1:1
	ds_write2_b32 v80, v20, v21 offset1:1
	ds_write2_b32 v82, v22, v23 offset1:1
	ds_write2_b32 v83, v24, v25 offset1:1
	ds_write2_b32 v84, v26, v27 offset1:1
	ds_write2_b32 v86, v28, v29 offset1:1
	ds_write2_b32 v88, v30, v31 offset1:1
	ds_write2_b32 v90, v32, v33 offset1:1
	s_waitcnt lgkmcnt(0)
	ds_read2_b32 v[2:3], v96 offset1:33
	v_or_b32_e32 v0, s0, v81
	s_waitcnt lgkmcnt(0)
	v_cvt_pk_bf16_f32 v2, v2, v3
	ds_read2_b32 v[4:5], v96 offset0:66 offset1:99
	v_lshl_add_u64 v[8:9], v[42:43], 0, s[46:47]
	v_lshlrev_b32_e32 v0, 11, v0
	s_waitcnt lgkmcnt(0)
	v_cvt_pk_bf16_f32 v3, v4, v5
	ds_read2_b32 v[4:5], v96 offset0:132 offset1:165
	v_lshl_add_u64 v[10:11], v[8:9], 0, v[0:1]
	s_waitcnt lgkmcnt(0)
	v_cvt_pk_bf16_f32 v4, v4, v5
	ds_read2_b32 v[6:7], v96 offset0:198 offset1:231
	s_waitcnt lgkmcnt(0)
	v_cvt_pk_bf16_f32 v5, v6, v7
	global_store_dwordx4 v[10:11], v[2:5], off
	ds_read2_b32 v[2:3], v96 offset0:8 offset1:41
	v_or_b32_e32 v0, s0, v89
	s_waitcnt lgkmcnt(0)
	v_cvt_pk_bf16_f32 v2, v2, v3
	ds_read2_b32 v[4:5], v96 offset0:74 offset1:107
	v_lshlrev_b32_e32 v0, 11, v0
	s_waitcnt lgkmcnt(0)
	v_cvt_pk_bf16_f32 v3, v4, v5
	ds_read2_b32 v[4:5], v96 offset0:140 offset1:173
	v_lshl_add_u64 v[10:11], v[8:9], 0, v[0:1]
	s_waitcnt lgkmcnt(0)
	v_cvt_pk_bf16_f32 v4, v4, v5
	ds_read2_b32 v[6:7], v96 offset0:206 offset1:239
	s_waitcnt lgkmcnt(0)
	v_cvt_pk_bf16_f32 v5, v6, v7
	global_store_dwordx4 v[10:11], v[2:5], off
	ds_read2_b32 v[2:3], v96 offset0:16 offset1:49
	v_or_b32_e32 v0, s0, v93
	s_waitcnt lgkmcnt(0)
	v_cvt_pk_bf16_f32 v2, v2, v3
	ds_read2_b32 v[4:5], v96 offset0:82 offset1:115
	v_lshlrev_b32_e32 v0, 11, v0
	s_waitcnt lgkmcnt(0)
	v_cvt_pk_bf16_f32 v3, v4, v5
	ds_read2_b32 v[4:5], v96 offset0:148 offset1:181
	v_lshl_add_u64 v[10:11], v[8:9], 0, v[0:1]
	s_waitcnt lgkmcnt(0)
	v_cvt_pk_bf16_f32 v4, v4, v5
	ds_read2_b32 v[6:7], v96 offset0:214 offset1:247
	s_waitcnt lgkmcnt(0)
	v_cvt_pk_bf16_f32 v5, v6, v7
	global_store_dwordx4 v[10:11], v[2:5], off
	ds_read2_b32 v[2:3], v96 offset0:24 offset1:57
	v_or_b32_e32 v0, s0, v95
	s_waitcnt lgkmcnt(0)
	v_cvt_pk_bf16_f32 v2, v2, v3
	ds_read2_b32 v[4:5], v96 offset0:90 offset1:123
	s_waitcnt lgkmcnt(0)
	v_cvt_pk_bf16_f32 v3, v4, v5
	ds_read2_b32 v[4:5], v96 offset0:156 offset1:189
	s_waitcnt lgkmcnt(0)
	v_cvt_pk_bf16_f32 v4, v4, v5
	ds_read2_b32 v[6:7], v96 offset0:222 offset1:255
	v_lshlrev_b32_e32 v0, 11, v0
	s_waitcnt lgkmcnt(0)
	v_cvt_pk_bf16_f32 v5, v6, v7
	v_lshl_add_u64 v[6:7], v[8:9], 0, v[0:1]
	global_store_dwordx4 v[6:7], v[2:5], off
	s_waitcnt lgkmcnt(0)

; #define LAS __attribute__((address_space(3)))
; #define LDS_WAIT() asm volatile("s_waitcnt lgkmcnt(0)" ::: "memory")
; __device__ __forceinline__ unsigned pk2(float lo, float hi) { return pg8::cvt_pk_bf16(lo, hi); }
; #define INP(i) ((const float*)ldp(T, (i)))
; #define TRJ(cnt, W, ldn, N, WT, ldk, gain, rbase, rstride) if (r >= 0) { if (r < (cnt)) { tr_item((W), (ldn), (N), (WT), (ldk), (gain), (rbase), (rstride), scr, r, lane); r = -1; } else r -= (cnt); }
; __device__ __forceinline__ void tr_item(const float* W, int ldn, int N, bf16_t* WT, int ldk, const float* gain, int rbase, int rstride, LAS float* scr, int item, int lane) {
;     const int nblk = N / 32, kb = item / nblk, nb = item % nblk, k0 = 64 * kb, n0 = 32 * nb;
;     f32x4 v[8]; float gk[8];
; #pragma unroll
;     for (int i = 0; i < 8; ++i) { const int kk = 8 * i + (lane >> 3); v[i] = *(const f32x4*)(W + (size_t)(k0 + kk) * ldn + n0 + 4 * (lane & 7)); gk[i] = gain ? gain[k0 + kk] : 1.0f; }
; #pragma unroll
;     for (int i = 0; i < 8; ++i) { LAS float* d = scr + (8 * i + (lane >> 3)) * 33 + 4 * (lane & 7); d[0] = v[i].x * gk[i]; d[1] = v[i].y * gk[i]; d[2] = v[i].z * gk[i]; d[3] = v[i].w * gk[i]; }
;     LDS_WAIT(); asm volatile("" ::: "memory");
;     const int c = lane & 7;
; #pragma unroll
;     for (int j = 0; j < 4; ++j) { const int n = (lane >> 3) + 8 * j; const LAS float* s = scr + (8 * c) * 33 + n;
;         u32x4 o; o.x = pk2(s[0 * 33], s[1 * 33]); o.y = pk2(s[2 * 33], s[3 * 33]); o.z = pk2(s[4 * 33], s[5 * 33]); o.w = pk2(s[6 * 33], s[7 * 33]);
;         const int nn = n0 + n, dest = rbase + (nn >> 7) * rstride + (nn & 127);
;         *(u32x4*)(WT + (size_t)dest * ldk + k0 + 8 * c) = o; }
;     LDS_WAIT(); asm volatile("" ::: "memory");
; __device__ __forceinline__ void prep_phase(const PT& T, LAS unsigned char* lds) {
;     ...
;         TRJ(I_1Kx1K, INP(9), 3 * D, D, Wb + WO_B_B, D, INP(1) + 1 * D, 0, 128)
.LBB0_447:
	s_andn2_b64 vcc, exec, s[0:1]
	s_cbranch_vccnz .LBB0_449
	v_mov_b32_e32 v0, s52
	ds_read_b64 v[2:3], v0
	v_mov_b32_e32 v0, s79
	ds_read_b64 v[4:5], v0
	v_lshlrev_b32_e32 v0, 2, v34
	v_mov_b32_e32 v83, v1
	s_waitcnt lgkmcnt(0)
	v_readfirstlane_b32 s5, v2
	v_readfirstlane_b32 s1, v3
	v_readfirstlane_b32 s8, v4
	v_readfirstlane_b32 s0, v5
	s_add_u32 s8, s8, 0x1000
	s_addc_u32 s9, s0, 0
	s_lshl_b32 s0, s4, 1
	s_and_b32 s19, s0, 0x3c0
	s_lshl_b32 s0, s4, 5
	s_and_b32 s0, s0, 0x3e0
	s_lshl_b32 s4, s0, 2
	s_add_u32 s4, s5, s4
	v_or_b32_e32 v6, s19, v81
	s_addc_u32 s5, s1, 0
	v_lshl_add_u64 v[30:31], s[4:5], 0, v[0:1]
	v_mul_u32_u24_e32 v0, 0xc00, v6
	v_lshlrev_b32_e32 v0, 2, v0
	v_lshlrev_b32_e32 v82, 2, v6
	v_lshl_add_u64 v[10:11], v[30:31], 0, v[0:1]
	v_lshl_add_u64 v[6:7], s[8:9], 0, v[82:83]
	global_load_dword v78, v[6:7], off
	v_add_co_u32_e32 v6, vcc, s71, v10
	v_or_b32_e32 v12, 32, v82
	v_mov_b32_e32 v13, v1
	v_or_b32_e32 v14, 64, v82
	v_mov_b32_e32 v15, v1
	v_or_b32_e32 v18, 0x60, v82
	v_mov_b32_e32 v19, v1
	v_or_b32_e32 v22, 0x80, v82
	v_mov_b32_e32 v23, v1
	v_or_b32_e32 v26, 0xa0, v82
	v_mov_b32_e32 v27, v1
	v_or_b32_e32 v32, 0xc0, v82
	v_mov_b32_e32 v33, v1
	v_addc_co_u32_e32 v7, vcc, 0, v11, vcc
	v_lshl_add_u64 v[12:13], s[8:9], 0, v[12:13]
	v_lshl_add_u64 v[14:15], s[8:9], 0, v[14:15]
	v_lshl_add_u64 v[18:19], s[8:9], 0, v[18:19]
	v_lshl_add_u64 v[22:23], s[8:9], 0, v[22:23]
	v_lshl_add_u64 v[26:27], s[8:9], 0, v[26:27]
	v_lshl_add_u64 v[32:33], s[8:9], 0, v[32:33]
	global_load_dwordx4 v[2:5], v[10:11], off
	global_load_dword v80, v[12:13], off
	global_load_dword v84, v[14:15], off
	global_load_dword v86, v[18:19], off
	global_load_dword v88, v[22:23], off
	global_load_dword v90, v[26:27], off
	global_load_dword v92, v[32:33], off
	v_add_u32_e32 v14, 0x48000, v0
	global_load_dwordx4 v[6:9], v[6:7], off
	v_add_co_u32_e32 v10, vcc, s81, v10
	v_mov_b32_e32 v15, v1
	s_nop 0
	v_addc_co_u32_e32 v11, vcc, 0, v11, vcc
	v_lshl_add_u64 v[14:15], v[30:31], 0, v[14:15]
	global_load_dwordx4 v[10:13], v[10:11], off
	v_add_u32_e32 v18, 0x60000, v0
	global_load_dwordx4 v[14:17], v[14:15], off
	v_mov_b32_e32 v19, v1
	v_lshl_add_u64 v[18:19], v[30:31], 0, v[18:19]
	global_load_dwordx4 v[18:21], v[18:19], off
	v_add_u32_e32 v22, 0x78000, v0
	v_mov_b32_e32 v23, v1
	v_lshl_add_u64 v[22:23], v[30:31], 0, v[22:23]
	global_load_dwordx4 v[22:25], v[22:23], off
	v_add_u32_e32 v26, 0x90000, v0
	v_mov_b32_e32 v27, v1
	v_lshl_add_u64 v[26:27], v[30:31], 0, v[26:27]
	v_add_u32_e32 v0, 0xa8000, v0
	global_load_dwordx4 v[26:29], v[26:27], off
	v_lshl_add_u64 v[30:31], v[30:31], 0, v[0:1]
	v_or_b32_e32 v0, 0xe0, v82
	v_lshl_add_u64 v[82:83], s[8:9], 0, v[0:1]
	global_load_dwordx4 v[30:33], v[30:31], off
	s_lshl_b32 s46, s19, 1
	global_load_dword v0, v[82:83], off
	v_add_u32_e32 v82, v85, v91
	v_add_u32_e32 v83, 0x420, v82
	v_add_u32_e32 v94, 0x428, v82
	s_mov_b32 s5, -1
	s_waitcnt vmcnt(0) lgkmcnt(0)
	v_pk_mul_f32 v[2:3], v[2:3], v[78:79] op_sel_hi:[1,0]
	v_pk_mul_f32 v[4:5], v[4:5], v[78:79] op_sel_hi:[1,0]
	ds_write2_b32 v87, v2, v3 offset1:1
	ds_write2_b32 v87, v4, v5 offset0:2 offset1:3
	v_pk_mul_f32 v[2:3], v[6:7], v[80:81] op_sel_hi:[1,0]
	v_pk_mul_f32 v[4:5], v[8:9], v[80:81] op_sel_hi:[1,0]
	v_pk_mul_f32 v[6:7], v[10:11], v[84:85] op_sel_hi:[1,0]
	v_pk_mul_f32 v[8:9], v[12:13], v[84:85] op_sel_hi:[1,0]
	ds_write2_b32 v82, v2, v3 offset1:1
	ds_write2_b32 v82, v4, v5 offset0:2 offset1:3
	ds_write2_b32 v83, v6, v7 offset1:1
	ds_write2_b32 v94, v8, v9 offset1:1
	v_pk_mul_f32 v[2:3], v[14:15], v[86:87] op_sel_hi:[1,0]
	v_add_u32_e32 v4, 0x840, v82
	ds_write2_b32 v4, v2, v3 offset1:1
	v_pk_mul_f32 v[2:3], v[16:17], v[86:87] op_sel_hi:[1,0]
	v_add_u32_e32 v4, 0x848, v82
	ds_write2_b32 v4, v2, v3 offset1:1
	v_pk_mul_f32 v[2:3], v[18:19], v[88:89] op_sel_hi:[1,0]
	v_add_u32_e32 v4, 0x1080, v87
	ds_write2_b32 v4, v2, v3 offset1:1
	v_pk_mul_f32 v[2:3], v[20:21], v[88:89] op_sel_hi:[1,0]
	v_add_u32_e32 v4, 0x1088, v87
	ds_write2_b32 v4, v2, v3 offset1:1
	v_pk_mul_f32 v[2:3], v[22:23], v[90:91] op_sel_hi:[1,0]
	v_add_u32_e32 v4, 0x14a0, v87
	ds_write2_b32 v4, v2, v3 offset1:1
	v_pk_mul_f32 v[2:3], v[24:25], v[90:91] op_sel_hi:[1,0]
	v_add_u32_e32 v4, 0x14a8, v87
	ds_write2_b32 v4, v2, v3 offset1:1
	v_pk_mul_f32 v[2:3], v[26:27], v[92:93] op_sel_hi:[1,0]
	v_add_u32_e32 v4, 0x18c0, v87
	ds_write2_b32 v4, v2, v3 offset1:1
	v_pk_mul_f32 v[2:3], v[28:29], v[92:93] op_sel_hi:[1,0]
	v_add_u32_e32 v4, 0x18c8, v87
	ds_write2_b32 v4, v2, v3 offset1:1
	v_pk_mul_f32 v[2:3], v[30:31], v[0:1] op_sel_hi:[1,0]
	v_add_u32_e32 v4, 0x1ce0, v87
	ds_write2_b32 v4, v2, v3 offset1:1
	v_pk_mul_f32 v[2:3], v[32:33], v[0:1] op_sel_hi:[1,0]
	v_add_u32_e32 v0, 0x1ce8, v87
	ds_write2_b32 v0, v2, v3 offset1:1
	s_waitcnt lgkmcnt(0)
	ds_read2_b32 v[2:3], v96 offset1:33
	s_waitcnt lgkmcnt(0)
	v_cvt_pk_bf16_f32 v2, v2, v3
	ds_read2_b32 v[4:5], v96 offset0:66 offset1:99
	s_waitcnt lgkmcnt(0)
	v_cvt_pk_bf16_f32 v3, v4, v5
	ds_read2_b32 v[4:5], v96 offset0:132 offset1:165
	v_or_b32_e32 v0, s0, v81
	s_waitcnt lgkmcnt(0)
	v_cvt_pk_bf16_f32 v4, v4, v5
	ds_read2_b32 v[6:7], v96 offset0:198 offset1:231
	v_lshl_add_u64 v[8:9], v[44:45], 0, s[46:47]
	v_lshlrev_b32_e32 v0, 11, v0
	s_waitcnt lgkmcnt(0)
	v_cvt_pk_bf16_f32 v5, v6, v7
	v_lshl_add_u64 v[6:7], v[8:9], 0, v[0:1]
	global_store_dwordx4 v[6:7], v[2:5], off
	ds_read2_b32 v[2:3], v96 offset0:8 offset1:41
	v_or_b32_e32 v0, s0, v89
	s_waitcnt lgkmcnt(0)
	v_cvt_pk_bf16_f32 v2, v2, v3
	ds_read2_b32 v[4:5], v96 offset0:74 offset1:107
	s_waitcnt lgkmcnt(0)
	v_cvt_pk_bf16_f32 v3, v4, v5
	ds_read2_b32 v[4:5], v96 offset0:140 offset1:173
	s_waitcnt lgkmcnt(0)
	v_cvt_pk_bf16_f32 v4, v4, v5
	ds_read2_b32 v[6:7], v96 offset0:206 offset1:239
	v_lshlrev_b32_e32 v0, 11, v0
	s_waitcnt lgkmcnt(0)
	v_cvt_pk_bf16_f32 v5, v6, v7
	v_lshl_add_u64 v[6:7], v[8:9], 0, v[0:1]
	global_store_dwordx4 v[6:7], v[2:5], off
	ds_read2_b32 v[2:3], v96 offset0:16 offset1:49
	v_or_b32_e32 v0, s0, v93
	s_waitcnt lgkmcnt(0)
	v_cvt_pk_bf16_f32 v2, v2, v3
	ds_read2_b32 v[4:5], v96 offset0:82 offset1:115
	s_waitcnt lgkmcnt(0)
	v_cvt_pk_bf16_f32 v3, v4, v5
	ds_read2_b32 v[4:5], v96 offset0:148 offset1:181
	s_waitcnt lgkmcnt(0)
	v_cvt_pk_bf16_f32 v4, v4, v5
	ds_read2_b32 v[6:7], v96 offset0:214 offset1:247
	v_lshlrev_b32_e32 v0, 11, v0
	s_waitcnt lgkmcnt(0)
	v_cvt_pk_bf16_f32 v5, v6, v7
	v_lshl_add_u64 v[6:7], v[8:9], 0, v[0:1]
	global_store_dwordx4 v[6:7], v[2:5], off
	ds_read2_b32 v[2:3], v96 offset0:24 offset1:57
	v_or_b32_e32 v0, s0, v95
	s_waitcnt lgkmcnt(0)
	v_cvt_pk_bf16_f32 v2, v2, v3
	ds_read2_b32 v[4:5], v96 offset0:90 offset1:123
	s_waitcnt lgkmcnt(0)
	v_cvt_pk_bf16_f32 v3, v4, v5
	ds_read2_b32 v[4:5], v96 offset0:156 offset1:189
	s_waitcnt lgkmcnt(0)
	v_cvt_pk_bf16_f32 v4, v4, v5
	ds_read2_b32 v[6:7], v96 offset0:222 offset1:255
	v_lshlrev_b32_e32 v0, 11, v0
	s_waitcnt lgkmcnt(0)
	v_cvt_pk_bf16_f32 v5, v6, v7
	v_lshl_add_u64 v[6:7], v[8:9], 0, v[0:1]
	global_store_dwordx4 v[6:7], v[2:5], off
	s_waitcnt lgkmcnt(0)

; #define LAS __attribute__((address_space(3)))
; #define INP(i) ((const float*)ldp(T, (i)))
; #define TRJ(cnt, W, ldn, N, WT, ldk, gain, rbase, rstride) if (r >= 0) { if (r < (cnt)) { tr_item((W), (ldn), (N), (WT), (ldk), (gain), (rbase), (rstride), scr, r, lane); r = -1; } else r -= (cnt); }
; __device__ __forceinline__ void tr_item(const float* W, int ldn, int N, bf16_t* WT, int ldk, const float* gain, int rbase, int rstride, LAS float* scr, int item, int lane) {
;     const int nblk = N / 32, kb = item / nblk, nb = item % nblk, k0 = 64 * kb, n0 = 32 * nb;
;     f32x4 v[8]; float gk[8];
; #pragma unroll
;     for (int i = 0; i < 8; ++i) { const int kk = 8 * i + (lane >> 3); v[i] = *(const f32x4*)(W + (size_t)(k0 + kk) * ldn + n0 + 4 * (lane & 7)); gk[i] = gain ? gain[k0 + kk] : 1.0f; }
; #pragma unroll
;     for (int i = 0; i < 8; ++i) { LAS float* d = scr + (8 * i + (lane >> 3)) * 33 + 4 * (lane & 7); d[0] = v[i].x * gk[i]; d[1] = v[i].y * gk[i]; d[2] = v[i].z * gk[i]; d[3] = v[i].w * gk[i]; }
; __device__ __forceinline__ void prep_phase(const PT& T, LAS unsigned char* lds) {
;     ...
;         TRJ(I_1Kx1K, INP(9) + D, 3 * D, D, Wb + WO_B_CX, D, INP(1) + 1 * D, 0, 256)
.LBB0_453:
	s_andn2_b64 vcc, exec, s[0:1]
	s_cbranch_vccnz .LBB0_455
	v_mov_b32_e32 v0, s52
	ds_read_b64 v[2:3], v0
	v_mov_b32_e32 v0, s79
	ds_read_b64 v[4:5], v0
	v_lshlrev_b32_e32 v0, 2, v34
	v_mov_b32_e32 v83, v1
	s_waitcnt lgkmcnt(0)
	v_readfirstlane_b32 s19, v2
	v_readfirstlane_b32 s5, v3
	v_readfirstlane_b32 s1, v4
	v_readfirstlane_b32 s0, v5
	s_add_u32 s8, s1, 0x1000
	s_addc_u32 s9, s0, 0
	s_lshl_b32 s0, s4, 1
	s_lshl_b32 s20, s4, 7
	s_and_b32 s0, s0, 0x3c0
	s_lshl_b32 s1, s4, 5
	s_and_b32 s20, s20, 0xf80
	s_add_u32 s20, s19, s20
	v_or_b32_e32 v6, s0, v81
	s_addc_u32 s21, s5, 0
	v_lshl_add_u64 v[2:3], s[20:21], 0, v[0:1]
	s_mov_b64 s[20:21], 0x1000
	v_mul_u32_u24_e32 v0, 0xc00, v6
	v_lshl_add_u64 v[30:31], v[2:3], 0, s[20:21]
	v_lshlrev_b32_e32 v0, 2, v0
	v_lshlrev_b32_e32 v82, 2, v6
	v_lshl_add_u64 v[10:11], v[30:31], 0, v[0:1]
	v_lshl_add_u64 v[6:7], s[8:9], 0, v[82:83]
	global_load_dword v78, v[6:7], off
	v_add_co_u32_e32 v6, vcc, s71, v10
	v_or_b32_e32 v12, 32, v82
	s_nop 0
	v_addc_co_u32_e32 v7, vcc, 0, v11, vcc
	v_mov_b32_e32 v13, v1
	v_or_b32_e32 v14, 64, v82
	v_mov_b32_e32 v15, v1
	v_or_b32_e32 v18, 0x60, v82
	v_mov_b32_e32 v19, v1
	v_or_b32_e32 v22, 0x80, v82
	v_mov_b32_e32 v23, v1
	v_or_b32_e32 v26, 0xa0, v82
	v_mov_b32_e32 v27, v1
	v_or_b32_e32 v32, 0xc0, v82
	v_mov_b32_e32 v33, v1
	global_load_dwordx4 v[2:5], v[10:11], off
	v_lshl_add_u64 v[12:13], s[8:9], 0, v[12:13]
	global_load_dwordx4 v[6:9], v[6:7], off
	v_add_co_u32_e32 v10, vcc, s81, v10
	v_lshl_add_u64 v[14:15], s[8:9], 0, v[14:15]
	v_lshl_add_u64 v[18:19], s[8:9], 0, v[18:19]
	v_lshl_add_u64 v[22:23], s[8:9], 0, v[22:23]
	v_lshl_add_u64 v[26:27], s[8:9], 0, v[26:27]
	v_lshl_add_u64 v[32:33], s[8:9], 0, v[32:33]
	global_load_dword v80, v[12:13], off
	global_load_dword v84, v[14:15], off
	global_load_dword v86, v[18:19], off
	global_load_dword v88, v[22:23], off
	global_load_dword v90, v[26:27], off
	global_load_dword v92, v[32:33], off
	v_addc_co_u32_e32 v11, vcc, 0, v11, vcc
	v_add_u32_e32 v14, 0x48000, v0
	v_mov_b32_e32 v15, v1
	global_load_dwordx4 v[10:13], v[10:11], off
	v_lshl_add_u64 v[14:15], v[30:31], 0, v[14:15]
	global_load_dwordx4 v[14:17], v[14:15], off
	v_add_u32_e32 v18, 0x60000, v0
	v_mov_b32_e32 v19, v1
	v_lshl_add_u64 v[18:19], v[30:31], 0, v[18:19]
	global_load_dwordx4 v[18:21], v[18:19], off
	v_add_u32_e32 v22, 0x78000, v0
	v_mov_b32_e32 v23, v1
	v_lshl_add_u64 v[22:23], v[30:31], 0, v[22:23]
	global_load_dwordx4 v[22:25], v[22:23], off
	v_add_u32_e32 v26, 0x90000, v0
	v_mov_b32_e32 v27, v1
	v_lshl_add_u64 v[26:27], v[30:31], 0, v[26:27]
	v_add_u32_e32 v0, 0xa8000, v0
	global_load_dwordx4 v[26:29], v[26:27], off
	v_lshl_add_u64 v[30:31], v[30:31], 0, v[0:1]
	v_or_b32_e32 v0, 0xe0, v82
	v_lshl_add_u64 v[82:83], s[8:9], 0, v[0:1]
	global_load_dwordx4 v[30:33], v[30:31], off
	s_lshl_b32 s4, s4, 6
	global_load_dword v0, v[82:83], off
	v_add_u32_e32 v82, v85, v91
	v_add_u32_e32 v83, 0x420, v82
	s_and_b32 s4, s4, 0x700
	s_and_b32 s1, s1, 0x60
	s_or_b32 s1, s4, s1
	s_lshl_b32 s46, s0, 1
	s_mov_b32 s5, -1
	s_waitcnt vmcnt(0) lgkmcnt(0)
; #define LAS __attribute__((address_space(3)))
; #define LDS_WAIT() asm volatile("s_waitcnt lgkmcnt(0)" ::: "memory")
; __device__ __forceinline__ unsigned pk2(float lo, float hi) { return pg8::cvt_pk_bf16(lo, hi); }
; __device__ __forceinline__ void tr_item(const float* W, int ldn, int N, bf16_t* WT, int ldk, const float* gain, int rbase, int rstride, LAS float* scr, int item, int lane) {
;     ...
;     for (int i = 0; i < 8; ++i) { LAS float* d = scr + (8 * i + (lane >> 3)) * 33 + 4 * (lane & 7); d[0] = v[i].x * gk[i]; d[1] = v[i].y * gk[i]; d[2] = v[i].z * gk[i]; d[3] = v[i].w * gk[i]; }
;     LDS_WAIT(); asm volatile("" ::: "memory");
;     const int c = lane & 7;
; #pragma unroll
;     for (int j = 0; j < 4; ++j) { const int n = (lane >> 3) + 8 * j; const LAS float* s = scr + (8 * c) * 33 + n;
;         u32x4 o; o.x = pk2(s[0 * 33], s[1 * 33]); o.y = pk2(s[2 * 33], s[3 * 33]); o.z = pk2(s[4 * 33], s[5 * 33]); o.w = pk2(s[6 * 33], s[7 * 33]);
;         const int nn = n0 + n, dest = rbase + (nn >> 7) * rstride + (nn & 127);
;         *(u32x4*)(WT + (size_t)dest * ldk + k0 + 8 * c) = o; }
;     LDS_WAIT(); asm volatile("" ::: "memory");
	v_pk_mul_f32 v[2:3], v[2:3], v[78:79] op_sel_hi:[1,0]
	v_pk_mul_f32 v[4:5], v[4:5], v[78:79] op_sel_hi:[1,0]
	ds_write2_b32 v87, v2, v3 offset1:1
	ds_write2_b32 v87, v4, v5 offset0:2 offset1:3
	v_pk_mul_f32 v[2:3], v[6:7], v[80:81] op_sel_hi:[1,0]
	v_pk_mul_f32 v[4:5], v[8:9], v[80:81] op_sel_hi:[1,0]
	v_pk_mul_f32 v[6:7], v[10:11], v[84:85] op_sel_hi:[1,0]
	v_pk_mul_f32 v[8:9], v[12:13], v[84:85] op_sel_hi:[1,0]
	ds_write2_b32 v82, v2, v3 offset1:1
	ds_write2_b32 v82, v4, v5 offset0:2 offset1:3
	ds_write2_b32 v83, v6, v7 offset1:1
	v_add_u32_e32 v2, 0x428, v82
	ds_write2_b32 v2, v8, v9 offset1:1
	v_pk_mul_f32 v[2:3], v[14:15], v[86:87] op_sel_hi:[1,0]
	v_add_u32_e32 v4, 0x840, v82
	ds_write2_b32 v4, v2, v3 offset1:1
	v_pk_mul_f32 v[2:3], v[16:17], v[86:87] op_sel_hi:[1,0]
	v_add_u32_e32 v4, 0x848, v82
	ds_write2_b32 v4, v2, v3 offset1:1
	v_pk_mul_f32 v[2:3], v[18:19], v[88:89] op_sel_hi:[1,0]
	v_add_u32_e32 v4, 0x1080, v87
	ds_write2_b32 v4, v2, v3 offset1:1
	v_pk_mul_f32 v[2:3], v[20:21], v[88:89] op_sel_hi:[1,0]
	v_add_u32_e32 v4, 0x1088, v87
	ds_write2_b32 v4, v2, v3 offset1:1
	v_pk_mul_f32 v[2:3], v[22:23], v[90:91] op_sel_hi:[1,0]
	v_add_u32_e32 v4, 0x14a0, v87
	ds_write2_b32 v4, v2, v3 offset1:1
	v_pk_mul_f32 v[2:3], v[24:25], v[90:91] op_sel_hi:[1,0]
	v_add_u32_e32 v4, 0x14a8, v87
	ds_write2_b32 v4, v2, v3 offset1:1
	v_pk_mul_f32 v[2:3], v[26:27], v[92:93] op_sel_hi:[1,0]
	v_add_u32_e32 v4, 0x18c0, v87
	ds_write2_b32 v4, v2, v3 offset1:1
	v_pk_mul_f32 v[2:3], v[28:29], v[92:93] op_sel_hi:[1,0]
	v_add_u32_e32 v4, 0x18c8, v87
	ds_write2_b32 v4, v2, v3 offset1:1
	v_pk_mul_f32 v[2:3], v[30:31], v[0:1] op_sel_hi:[1,0]
	v_add_u32_e32 v4, 0x1ce0, v87
	ds_write2_b32 v4, v2, v3 offset1:1
	v_pk_mul_f32 v[2:3], v[32:33], v[0:1] op_sel_hi:[1,0]
	v_add_u32_e32 v0, 0x1ce8, v87
	ds_write2_b32 v0, v2, v3 offset1:1
	s_waitcnt lgkmcnt(0)
	ds_read2_b32 v[2:3], v96 offset1:33
	s_waitcnt lgkmcnt(0)
	v_cvt_pk_bf16_f32 v2, v2, v3
	ds_read2_b32 v[4:5], v96 offset0:66 offset1:99
	s_waitcnt lgkmcnt(0)
	v_cvt_pk_bf16_f32 v3, v4, v5
	ds_read2_b32 v[4:5], v96 offset0:132 offset1:165
	v_or_b32_e32 v0, s1, v81
	s_waitcnt lgkmcnt(0)
	v_cvt_pk_bf16_f32 v4, v4, v5
	ds_read2_b32 v[6:7], v96 offset0:198 offset1:231
	v_lshl_add_u64 v[8:9], v[46:47], 0, s[46:47]
	v_lshlrev_b32_e32 v0, 11, v0
	s_waitcnt lgkmcnt(0)
	v_cvt_pk_bf16_f32 v5, v6, v7
	v_lshl_add_u64 v[6:7], v[8:9], 0, v[0:1]
	global_store_dwordx4 v[6:7], v[2:5], off
	ds_read2_b32 v[2:3], v96 offset0:8 offset1:41
	v_or_b32_e32 v0, s1, v89
	s_waitcnt lgkmcnt(0)
	v_cvt_pk_bf16_f32 v2, v2, v3
	ds_read2_b32 v[4:5], v96 offset0:74 offset1:107
	s_waitcnt lgkmcnt(0)
	v_cvt_pk_bf16_f32 v3, v4, v5
	ds_read2_b32 v[4:5], v96 offset0:140 offset1:173
	s_waitcnt lgkmcnt(0)
	v_cvt_pk_bf16_f32 v4, v4, v5
	ds_read2_b32 v[6:7], v96 offset0:206 offset1:239
	v_lshlrev_b32_e32 v0, 11, v0
	s_waitcnt lgkmcnt(0)
	v_cvt_pk_bf16_f32 v5, v6, v7
	v_lshl_add_u64 v[6:7], v[8:9], 0, v[0:1]
	global_store_dwordx4 v[6:7], v[2:5], off
	ds_read2_b32 v[2:3], v96 offset0:16 offset1:49
	v_or_b32_e32 v0, s1, v93
	s_waitcnt lgkmcnt(0)
	v_cvt_pk_bf16_f32 v2, v2, v3
	ds_read2_b32 v[4:5], v96 offset0:82 offset1:115
	s_waitcnt lgkmcnt(0)
	v_cvt_pk_bf16_f32 v3, v4, v5
	ds_read2_b32 v[4:5], v96 offset0:148 offset1:181
	s_waitcnt lgkmcnt(0)
	v_cvt_pk_bf16_f32 v4, v4, v5
	ds_read2_b32 v[6:7], v96 offset0:214 offset1:247
	v_lshlrev_b32_e32 v0, 11, v0
	s_waitcnt lgkmcnt(0)
	v_cvt_pk_bf16_f32 v5, v6, v7
	v_lshl_add_u64 v[6:7], v[8:9], 0, v[0:1]
	global_store_dwordx4 v[6:7], v[2:5], off
	ds_read2_b32 v[2:3], v96 offset0:24 offset1:57
	v_or_b32_e32 v0, s1, v95
	s_waitcnt lgkmcnt(0)
	v_cvt_pk_bf16_f32 v2, v2, v3
	ds_read2_b32 v[4:5], v96 offset0:90 offset1:123
	s_waitcnt lgkmcnt(0)
	v_cvt_pk_bf16_f32 v3, v4, v5
	ds_read2_b32 v[4:5], v96 offset0:156 offset1:189
	s_waitcnt lgkmcnt(0)
	v_cvt_pk_bf16_f32 v4, v4, v5
	ds_read2_b32 v[6:7], v96 offset0:222 offset1:255
	v_lshlrev_b32_e32 v0, 11, v0
	s_waitcnt lgkmcnt(0)
	v_cvt_pk_bf16_f32 v5, v6, v7
	v_lshl_add_u64 v[6:7], v[8:9], 0, v[0:1]
	global_store_dwordx4 v[6:7], v[2:5], off
	s_waitcnt lgkmcnt(0)

; #define LAS __attribute__((address_space(3)))
; #define INP(i) ((const float*)ldp(T, (i)))
; #define TRJ(cnt, W, ldn, N, WT, ldk, gain, rbase, rstride) if (r >= 0) { if (r < (cnt)) { tr_item((W), (ldn), (N), (WT), (ldk), (gain), (rbase), (rstride), scr, r, lane); r = -1; } else r -= (cnt); }
; __device__ __forceinline__ void tr_item(const float* W, int ldn, int N, bf16_t* WT, int ldk, const float* gain, int rbase, int rstride, LAS float* scr, int item, int lane) {
;     const int nblk = N / 32, kb = item / nblk, nb = item % nblk, k0 = 64 * kb, n0 = 32 * nb;
;     f32x4 v[8]; float gk[8];
; #pragma unroll
;     for (int i = 0; i < 8; ++i) { const int kk = 8 * i + (lane >> 3); v[i] = *(const f32x4*)(W + (size_t)(k0 + kk) * ldn + n0 + 4 * (lane & 7)); gk[i] = gain ? gain[k0 + kk] : 1.0f; }
; #pragma unroll
;     for (int i = 0; i < 8; ++i) { LAS float* d = scr + (8 * i + (lane >> 3)) * 33 + 4 * (lane & 7); d[0] = v[i].x * gk[i]; d[1] = v[i].y * gk[i]; d[2] = v[i].z * gk[i]; d[3] = v[i].w * gk[i]; }
; __device__ __forceinline__ void prep_phase(const PT& T, LAS unsigned char* lds) {
;     ...
;         TRJ(I_1Kx1K, INP(9) + 2 * D, 3 * D, D, Wb + WO_B_CX, D, INP(1) + 1 * D, 128, 256)
.LBB0_459:
	s_andn2_b64 vcc, exec, s[0:1]
	s_cbranch_vccnz .LBB0_461
	v_mov_b32_e32 v0, s52
	ds_read_b64 v[2:3], v0
	v_mov_b32_e32 v0, s79
	ds_read_b64 v[4:5], v0
	v_lshlrev_b32_e32 v0, 2, v34
	v_mov_b32_e32 v83, v1
	s_waitcnt lgkmcnt(0)
	v_readfirstlane_b32 s19, v2
	v_readfirstlane_b32 s5, v3
	v_readfirstlane_b32 s1, v4
	v_readfirstlane_b32 s0, v5
	s_add_u32 s8, s1, 0x1000
	s_addc_u32 s9, s0, 0
	s_lshl_b32 s0, s4, 1
	s_lshl_b32 s20, s4, 7
	s_and_b32 s0, s0, 0x3c0
	s_lshl_b32 s1, s4, 5
	s_and_b32 s20, s20, 0xf80
	s_add_u32 s20, s19, s20
	v_or_b32_e32 v6, s0, v81
	s_addc_u32 s21, s5, 0
	v_lshl_add_u64 v[2:3], s[20:21], 0, v[0:1]
	s_mov_b64 s[20:21], 0x2000
	v_mul_u32_u24_e32 v0, 0xc00, v6
	v_lshl_add_u64 v[30:31], v[2:3], 0, s[20:21]
	v_lshlrev_b32_e32 v0, 2, v0
	v_lshlrev_b32_e32 v82, 2, v6
	v_lshl_add_u64 v[10:11], v[30:31], 0, v[0:1]
	v_lshl_add_u64 v[6:7], s[8:9], 0, v[82:83]
	global_load_dword v78, v[6:7], off
	v_add_co_u32_e32 v6, vcc, s71, v10
	v_or_b32_e32 v12, 32, v82
	s_nop 0
	v_addc_co_u32_e32 v7, vcc, 0, v11, vcc
	v_mov_b32_e32 v13, v1
	v_or_b32_e32 v14, 64, v82
	v_mov_b32_e32 v15, v1
	v_or_b32_e32 v18, 0x60, v82
	v_mov_b32_e32 v19, v1
	v_or_b32_e32 v22, 0x80, v82
	v_mov_b32_e32 v23, v1
	v_or_b32_e32 v26, 0xa0, v82
	v_mov_b32_e32 v27, v1
	v_or_b32_e32 v32, 0xc0, v82
	v_mov_b32_e32 v33, v1
	global_load_dwordx4 v[2:5], v[10:11], off
	v_lshl_add_u64 v[12:13], s[8:9], 0, v[12:13]
	global_load_dwordx4 v[6:9], v[6:7], off
	v_add_co_u32_e32 v10, vcc, s81, v10
	v_lshl_add_u64 v[14:15], s[8:9], 0, v[14:15]
	v_lshl_add_u64 v[18:19], s[8:9], 0, v[18:19]
	v_lshl_add_u64 v[22:23], s[8:9], 0, v[22:23]
	v_lshl_add_u64 v[26:27], s[8:9], 0, v[26:27]
	v_lshl_add_u64 v[32:33], s[8:9], 0, v[32:33]
	global_load_dword v80, v[12:13], off
	global_load_dword v84, v[14:15], off
	global_load_dword v86, v[18:19], off
	global_load_dword v88, v[22:23], off
	global_load_dword v90, v[26:27], off
	global_load_dword v92, v[32:33], off
	v_addc_co_u32_e32 v11, vcc, 0, v11, vcc
	v_add_u32_e32 v14, 0x48000, v0
	v_mov_b32_e32 v15, v1
	global_load_dwordx4 v[10:13], v[10:11], off
	v_lshl_add_u64 v[14:15], v[30:31], 0, v[14:15]
	global_load_dwordx4 v[14:17], v[14:15], off
	v_add_u32_e32 v18, 0x60000, v0
	v_mov_b32_e32 v19, v1
	v_lshl_add_u64 v[18:19], v[30:31], 0, v[18:19]
	global_load_dwordx4 v[18:21], v[18:19], off
	v_add_u32_e32 v22, 0x78000, v0
	v_mov_b32_e32 v23, v1
	v_lshl_add_u64 v[22:23], v[30:31], 0, v[22:23]
	global_load_dwordx4 v[22:25], v[22:23], off
	v_add_u32_e32 v26, 0x90000, v0
	v_mov_b32_e32 v27, v1
	v_lshl_add_u64 v[26:27], v[30:31], 0, v[26:27]
	v_add_u32_e32 v0, 0xa8000, v0
	global_load_dwordx4 v[26:29], v[26:27], off
	v_lshl_add_u64 v[30:31], v[30:31], 0, v[0:1]
	v_or_b32_e32 v0, 0xe0, v82
	v_lshl_add_u64 v[82:83], s[8:9], 0, v[0:1]
	global_load_dwordx4 v[30:33], v[30:31], off
	s_lshl_b32 s4, s4, 6
	global_load_dword v0, v[82:83], off
	v_add_u32_e32 v82, v85, v91
	v_add_u32_e32 v83, 0x420, v82
	s_and_b32 s4, s4, 0x700
	s_and_b32 s1, s1, 0x60
	s_or_b32 s1, s4, s1
	s_bitset1_b32 s1, 7
	s_lshl_b32 s46, s0, 1
	s_mov_b32 s5, -1
	s_waitcnt vmcnt(0) lgkmcnt(0)
; #define LAS __attribute__((address_space(3)))
; #define LDS_WAIT() asm volatile("s_waitcnt lgkmcnt(0)" ::: "memory")
; __device__ __forceinline__ unsigned pk2(float lo, float hi) { return pg8::cvt_pk_bf16(lo, hi); }
; __device__ __forceinline__ void tr_item(const float* W, int ldn, int N, bf16_t* WT, int ldk, const float* gain, int rbase, int rstride, LAS float* scr, int item, int lane) {
;     ...
;     for (int i = 0; i < 8; ++i) { LAS float* d = scr + (8 * i + (lane >> 3)) * 33 + 4 * (lane & 7); d[0] = v[i].x * gk[i]; d[1] = v[i].y * gk[i]; d[2] = v[i].z * gk[i]; d[3] = v[i].w * gk[i]; }
;     LDS_WAIT(); asm volatile("" ::: "memory");
;     const int c = lane & 7;
; #pragma unroll
;     for (int j = 0; j < 4; ++j) { const int n = (lane >> 3) + 8 * j; const LAS float* s = scr + (8 * c) * 33 + n;
;         u32x4 o; o.x = pk2(s[0 * 33], s[1 * 33]); o.y = pk2(s[2 * 33], s[3 * 33]); o.z = pk2(s[4 * 33], s[5 * 33]); o.w = pk2(s[6 * 33], s[7 * 33]);
;         const int nn = n0 + n, dest = rbase + (nn >> 7) * rstride + (nn & 127);
;         *(u32x4*)(WT + (size_t)dest * ldk + k0 + 8 * c) = o; }
;     LDS_WAIT(); asm volatile("" ::: "memory");
	v_pk_mul_f32 v[2:3], v[2:3], v[78:79] op_sel_hi:[1,0]
	v_pk_mul_f32 v[4:5], v[4:5], v[78:79] op_sel_hi:[1,0]
	ds_write2_b32 v87, v2, v3 offset1:1
	ds_write2_b32 v87, v4, v5 offset0:2 offset1:3
	v_pk_mul_f32 v[2:3], v[6:7], v[80:81] op_sel_hi:[1,0]
	v_pk_mul_f32 v[4:5], v[8:9], v[80:81] op_sel_hi:[1,0]
	v_pk_mul_f32 v[6:7], v[10:11], v[84:85] op_sel_hi:[1,0]
	v_pk_mul_f32 v[8:9], v[12:13], v[84:85] op_sel_hi:[1,0]
	ds_write2_b32 v82, v2, v3 offset1:1
	ds_write2_b32 v82, v4, v5 offset0:2 offset1:3
	ds_write2_b32 v83, v6, v7 offset1:1
	v_add_u32_e32 v2, 0x428, v82
	ds_write2_b32 v2, v8, v9 offset1:1
	v_pk_mul_f32 v[2:3], v[14:15], v[86:87] op_sel_hi:[1,0]
	v_add_u32_e32 v4, 0x840, v82
	ds_write2_b32 v4, v2, v3 offset1:1
	v_pk_mul_f32 v[2:3], v[16:17], v[86:87] op_sel_hi:[1,0]
	v_add_u32_e32 v4, 0x848, v82
	ds_write2_b32 v4, v2, v3 offset1:1
	v_pk_mul_f32 v[2:3], v[18:19], v[88:89] op_sel_hi:[1,0]
	v_add_u32_e32 v4, 0x1080, v87
	ds_write2_b32 v4, v2, v3 offset1:1
	v_pk_mul_f32 v[2:3], v[20:21], v[88:89] op_sel_hi:[1,0]
	v_add_u32_e32 v4, 0x1088, v87
	ds_write2_b32 v4, v2, v3 offset1:1
	v_pk_mul_f32 v[2:3], v[22:23], v[90:91] op_sel_hi:[1,0]
	v_add_u32_e32 v4, 0x14a0, v87
	ds_write2_b32 v4, v2, v3 offset1:1
	v_pk_mul_f32 v[2:3], v[24:25], v[90:91] op_sel_hi:[1,0]
	v_add_u32_e32 v4, 0x14a8, v87
	ds_write2_b32 v4, v2, v3 offset1:1
	v_pk_mul_f32 v[2:3], v[26:27], v[92:93] op_sel_hi:[1,0]
	v_add_u32_e32 v4, 0x18c0, v87
	ds_write2_b32 v4, v2, v3 offset1:1
	v_pk_mul_f32 v[2:3], v[28:29], v[92:93] op_sel_hi:[1,0]
	v_add_u32_e32 v4, 0x18c8, v87
	ds_write2_b32 v4, v2, v3 offset1:1
	v_pk_mul_f32 v[2:3], v[30:31], v[0:1] op_sel_hi:[1,0]
	v_add_u32_e32 v4, 0x1ce0, v87
	ds_write2_b32 v4, v2, v3 offset1:1
	v_pk_mul_f32 v[2:3], v[32:33], v[0:1] op_sel_hi:[1,0]
	v_add_u32_e32 v0, 0x1ce8, v87
	ds_write2_b32 v0, v2, v3 offset1:1
	s_waitcnt lgkmcnt(0)
	ds_read2_b32 v[2:3], v96 offset1:33
	s_waitcnt lgkmcnt(0)
	v_cvt_pk_bf16_f32 v2, v2, v3
	ds_read2_b32 v[4:5], v96 offset0:66 offset1:99
	s_waitcnt lgkmcnt(0)
	v_cvt_pk_bf16_f32 v3, v4, v5
	ds_read2_b32 v[4:5], v96 offset0:132 offset1:165
	v_or_b32_e32 v0, s1, v81
	s_waitcnt lgkmcnt(0)
	v_cvt_pk_bf16_f32 v4, v4, v5
	ds_read2_b32 v[6:7], v96 offset0:198 offset1:231
	v_lshl_add_u64 v[8:9], v[46:47], 0, s[46:47]
	v_lshlrev_b32_e32 v0, 11, v0
	s_waitcnt lgkmcnt(0)
	v_cvt_pk_bf16_f32 v5, v6, v7
	v_lshl_add_u64 v[6:7], v[8:9], 0, v[0:1]
	global_store_dwordx4 v[6:7], v[2:5], off
	ds_read2_b32 v[2:3], v96 offset0:8 offset1:41
	v_or_b32_e32 v0, s1, v89
	s_waitcnt lgkmcnt(0)
	v_cvt_pk_bf16_f32 v2, v2, v3
	ds_read2_b32 v[4:5], v96 offset0:74 offset1:107
	s_waitcnt lgkmcnt(0)
	v_cvt_pk_bf16_f32 v3, v4, v5
	ds_read2_b32 v[4:5], v96 offset0:140 offset1:173
	s_waitcnt lgkmcnt(0)
	v_cvt_pk_bf16_f32 v4, v4, v5
	ds_read2_b32 v[6:7], v96 offset0:206 offset1:239
	v_lshlrev_b32_e32 v0, 11, v0
	s_waitcnt lgkmcnt(0)
	v_cvt_pk_bf16_f32 v5, v6, v7
	v_lshl_add_u64 v[6:7], v[8:9], 0, v[0:1]
	global_store_dwordx4 v[6:7], v[2:5], off
	ds_read2_b32 v[2:3], v96 offset0:16 offset1:49
	v_or_b32_e32 v0, s1, v93
	s_waitcnt lgkmcnt(0)
	v_cvt_pk_bf16_f32 v2, v2, v3
	ds_read2_b32 v[4:5], v96 offset0:82 offset1:115
	s_waitcnt lgkmcnt(0)
	v_cvt_pk_bf16_f32 v3, v4, v5
	ds_read2_b32 v[4:5], v96 offset0:148 offset1:181
	s_waitcnt lgkmcnt(0)
	v_cvt_pk_bf16_f32 v4, v4, v5
	ds_read2_b32 v[6:7], v96 offset0:214 offset1:247
	v_lshlrev_b32_e32 v0, 11, v0
	s_waitcnt lgkmcnt(0)
	v_cvt_pk_bf16_f32 v5, v6, v7
	v_lshl_add_u64 v[6:7], v[8:9], 0, v[0:1]
	global_store_dwordx4 v[6:7], v[2:5], off
	ds_read2_b32 v[2:3], v96 offset0:24 offset1:57
	v_or_b32_e32 v0, s1, v95
	s_waitcnt lgkmcnt(0)
	v_cvt_pk_bf16_f32 v2, v2, v3
	ds_read2_b32 v[4:5], v96 offset0:90 offset1:123
	s_waitcnt lgkmcnt(0)
	v_cvt_pk_bf16_f32 v3, v4, v5
	ds_read2_b32 v[4:5], v96 offset0:156 offset1:189
	s_waitcnt lgkmcnt(0)
	v_cvt_pk_bf16_f32 v4, v4, v5
	ds_read2_b32 v[6:7], v96 offset0:222 offset1:255
	v_lshlrev_b32_e32 v0, 11, v0
	s_waitcnt lgkmcnt(0)
	v_cvt_pk_bf16_f32 v5, v6, v7
	v_lshl_add_u64 v[6:7], v[8:9], 0, v[0:1]
	global_store_dwordx4 v[6:7], v[2:5], off
	s_waitcnt lgkmcnt(0)

; #define LAS __attribute__((address_space(3)))
; #define LDS_WAIT() asm volatile("s_waitcnt lgkmcnt(0)" ::: "memory")
; __device__ __forceinline__ unsigned pk2(float lo, float hi) { return pg8::cvt_pk_bf16(lo, hi); }
; #define INP(i) ((const float*)ldp(T, (i)))
; #define TRJ(cnt, W, ldn, N, WT, ldk, gain, rbase, rstride) if (r >= 0) { if (r < (cnt)) { tr_item((W), (ldn), (N), (WT), (ldk), (gain), (rbase), (rstride), scr, r, lane); r = -1; } else r -= (cnt); }
; __device__ __forceinline__ void tr_item(const float* W, int ldn, int N, bf16_t* WT, int ldk, const float* gain, int rbase, int rstride, LAS float* scr, int item, int lane) {
;     const int nblk = N / 32, kb = item / nblk, nb = item % nblk, k0 = 64 * kb, n0 = 32 * nb;
;     f32x4 v[8]; float gk[8];
; #pragma unroll
;     for (int i = 0; i < 8; ++i) { const int kk = 8 * i + (lane >> 3); v[i] = *(const f32x4*)(W + (size_t)(k0 + kk) * ldn + n0 + 4 * (lane & 7)); gk[i] = gain ? gain[k0 + kk] : 1.0f; }
; #pragma unroll
;     for (int i = 0; i < 8; ++i) { LAS float* d = scr + (8 * i + (lane >> 3)) * 33 + 4 * (lane & 7); d[0] = v[i].x * gk[i]; d[1] = v[i].y * gk[i]; d[2] = v[i].z * gk[i]; d[3] = v[i].w * gk[i]; }
;     LDS_WAIT(); asm volatile("" ::: "memory");
;     const int c = lane & 7;
; #pragma unroll
;     for (int j = 0; j < 4; ++j) { const int n = (lane >> 3) + 8 * j; const LAS float* s = scr + (8 * c) * 33 + n;
;         u32x4 o; o.x = pk2(s[0 * 33], s[1 * 33]); o.y = pk2(s[2 * 33], s[3 * 33]); o.z = pk2(s[4 * 33], s[5 * 33]); o.w = pk2(s[6 * 33], s[7 * 33]);
;         const int nn = n0 + n, dest = rbase + (nn >> 7) * rstride + (nn & 127);
;         *(u32x4*)(WT + (size_t)dest * ldk + k0 + 8 * c) = o; }
;     LDS_WAIT(); asm volatile("" ::: "memory");
; __device__ __forceinline__ void prep_phase(const PT& T, LAS unsigned char* lds) {
;     ...
;         TRJ(I_1Kx1K, INP(11), D, D, Wb + WO_B_OUT, D, nullptr, 0, 128)
.LBB0_465:
	s_andn2_b64 vcc, exec, s[0:1]
	s_cbranch_vccnz .LBB0_467
	v_mov_b32_e32 v0, s30
	ds_read_b64 v[2:3], v0
	s_lshl_b32 s0, s4, 1
	s_lshl_b32 s1, s4, 5
	s_and_b32 s8, s0, 0x3c0
	s_and_b32 s0, s1, 0x3e0
	s_waitcnt lgkmcnt(0)
	v_readfirstlane_b32 s4, v2
	s_lshl_b32 s1, s0, 2
	v_readfirstlane_b32 s5, v3
	s_add_u32 s4, s4, s1
	v_or_b32_e32 v4, s8, v81
	s_addc_u32 s5, s5, 0
	v_lshlrev_b32_e32 v0, 2, v34
	v_lshl_add_u64 v[2:3], s[4:5], 0, v[0:1]
	v_lshlrev_b32_e32 v0, 12, v4
	v_lshl_add_u64 v[30:31], v[2:3], 0, v[0:1]
	v_add_co_u32_e32 v6, vcc, s77, v30
	v_add_u32_e32 v0, v85, v91
	s_nop 0
	v_addc_co_u32_e32 v7, vcc, 0, v31, vcc
	v_add_co_u32_e32 v10, vcc, s24, v30
	global_load_dwordx4 v[2:5], v[30:31], off
	s_nop 0
	global_load_dwordx4 v[6:9], v[6:7], off
	v_addc_co_u32_e32 v11, vcc, 0, v31, vcc
	v_add_co_u32_e32 v14, vcc, s71, v30
	v_add_u32_e32 v78, 0x1080, v87
	s_nop 0
	v_addc_co_u32_e32 v15, vcc, 0, v31, vcc
	v_add_co_u32_e32 v18, vcc, s27, v30
	global_load_dwordx4 v[10:13], v[10:11], off
	s_nop 0
	global_load_dwordx4 v[14:17], v[14:15], off
	v_addc_co_u32_e32 v19, vcc, 0, v31, vcc
	v_add_co_u32_e32 v22, vcc, s28, v30
	v_add_u32_e32 v80, 0x1088, v87
	s_nop 0
	v_addc_co_u32_e32 v23, vcc, 0, v31, vcc
	global_load_dwordx4 v[18:21], v[18:19], off
	s_nop 0
	global_load_dwordx4 v[22:25], v[22:23], off
	v_add_co_u32_e32 v26, vcc, s81, v30
	v_add_u32_e32 v82, 0x14a0, v87
	s_nop 0
	v_addc_co_u32_e32 v27, vcc, 0, v31, vcc
	global_load_dwordx4 v[26:29], v[26:27], off
	v_add_co_u32_e32 v30, vcc, s29, v30
	v_add_u32_e32 v83, 0x14a8, v87
	s_nop 0
	v_addc_co_u32_e32 v31, vcc, 0, v31, vcc
	global_load_dwordx4 v[30:33], v[30:31], off
	v_add_u32_e32 v84, 0x18c0, v87
	v_add_u32_e32 v86, 0x18c8, v87
	v_add_u32_e32 v88, 0x1ce0, v87
	v_add_u32_e32 v90, 0x1ce8, v87
	v_add_u32_e32 v92, 0x420, v0
	v_add_u32_e32 v94, 0x428, v0
	v_add_u32_e32 v97, 0x840, v0
	v_add_u32_e32 v98, 0x848, v0
	s_lshl_b32 s46, s8, 1
	s_mov_b32 s5, -1
	s_waitcnt vmcnt(0) lgkmcnt(0)
	ds_write2_b32 v87, v2, v3 offset1:1
	ds_write2_b32 v87, v4, v5 offset0:2 offset1:3
	ds_write2_b32 v0, v6, v7 offset1:1
	ds_write2_b32 v0, v8, v9 offset0:2 offset1:3
	ds_write2_b32 v92, v10, v11 offset1:1
	ds_write2_b32 v94, v12, v13 offset1:1
	ds_write2_b32 v97, v14, v15 offset1:1
	ds_write2_b32 v98, v16, v17 offset1:1
	ds_write2_b32 v78, v18, v19 offset1:1
	ds_write2_b32 v80, v20, v21 offset1:1
	ds_write2_b32 v82, v22, v23 offset1:1
	ds_write2_b32 v83, v24, v25 offset1:1
	ds_write2_b32 v84, v26, v27 offset1:1
	ds_write2_b32 v86, v28, v29 offset1:1
	ds_write2_b32 v88, v30, v31 offset1:1
	ds_write2_b32 v90, v32, v33 offset1:1
	s_waitcnt lgkmcnt(0)
	ds_read2_b32 v[2:3], v96 offset1:33
	v_or_b32_e32 v0, s0, v81
	s_waitcnt lgkmcnt(0)
	v_cvt_pk_bf16_f32 v2, v2, v3
	ds_read2_b32 v[4:5], v96 offset0:66 offset1:99
	v_lshl_add_u64 v[8:9], v[48:49], 0, s[46:47]
	v_lshlrev_b32_e32 v0, 11, v0
	s_waitcnt lgkmcnt(0)
	v_cvt_pk_bf16_f32 v3, v4, v5
	ds_read2_b32 v[4:5], v96 offset0:132 offset1:165
	v_lshl_add_u64 v[10:11], v[8:9], 0, v[0:1]
	s_waitcnt lgkmcnt(0)
	v_cvt_pk_bf16_f32 v4, v4, v5
	ds_read2_b32 v[6:7], v96 offset0:198 offset1:231
	s_waitcnt lgkmcnt(0)
	v_cvt_pk_bf16_f32 v5, v6, v7
	global_store_dwordx4 v[10:11], v[2:5], off
	ds_read2_b32 v[2:3], v96 offset0:8 offset1:41
	v_or_b32_e32 v0, s0, v89
	s_waitcnt lgkmcnt(0)
	v_cvt_pk_bf16_f32 v2, v2, v3
	ds_read2_b32 v[4:5], v96 offset0:74 offset1:107
	v_lshlrev_b32_e32 v0, 11, v0
	s_waitcnt lgkmcnt(0)
	v_cvt_pk_bf16_f32 v3, v4, v5
	ds_read2_b32 v[4:5], v96 offset0:140 offset1:173
	v_lshl_add_u64 v[10:11], v[8:9], 0, v[0:1]
	s_waitcnt lgkmcnt(0)
	v_cvt_pk_bf16_f32 v4, v4, v5
	ds_read2_b32 v[6:7], v96 offset0:206 offset1:239
	s_waitcnt lgkmcnt(0)
	v_cvt_pk_bf16_f32 v5, v6, v7
	global_store_dwordx4 v[10:11], v[2:5], off
	ds_read2_b32 v[2:3], v96 offset0:16 offset1:49
	v_or_b32_e32 v0, s0, v93
	s_waitcnt lgkmcnt(0)
	v_cvt_pk_bf16_f32 v2, v2, v3
	ds_read2_b32 v[4:5], v96 offset0:82 offset1:115
	v_lshlrev_b32_e32 v0, 11, v0
	s_waitcnt lgkmcnt(0)
	v_cvt_pk_bf16_f32 v3, v4, v5
	ds_read2_b32 v[4:5], v96 offset0:148 offset1:181
	v_lshl_add_u64 v[10:11], v[8:9], 0, v[0:1]
	s_waitcnt lgkmcnt(0)
	v_cvt_pk_bf16_f32 v4, v4, v5
	ds_read2_b32 v[6:7], v96 offset0:214 offset1:247
	s_waitcnt lgkmcnt(0)
	v_cvt_pk_bf16_f32 v5, v6, v7
	global_store_dwordx4 v[10:11], v[2:5], off
	ds_read2_b32 v[2:3], v96 offset0:24 offset1:57
	v_or_b32_e32 v0, s0, v95
	s_waitcnt lgkmcnt(0)
	v_cvt_pk_bf16_f32 v2, v2, v3
	ds_read2_b32 v[4:5], v96 offset0:90 offset1:123
	s_waitcnt lgkmcnt(0)
	v_cvt_pk_bf16_f32 v3, v4, v5
	ds_read2_b32 v[4:5], v96 offset0:156 offset1:189
	s_waitcnt lgkmcnt(0)
	v_cvt_pk_bf16_f32 v4, v4, v5
	ds_read2_b32 v[6:7], v96 offset0:222 offset1:255
	v_lshlrev_b32_e32 v0, 11, v0
	s_waitcnt lgkmcnt(0)
	v_cvt_pk_bf16_f32 v5, v6, v7
	v_lshl_add_u64 v[6:7], v[8:9], 0, v[0:1]
	global_store_dwordx4 v[6:7], v[2:5], off
	s_waitcnt lgkmcnt(0)

; #define LAS __attribute__((address_space(3)))
; #define LDS_WAIT() asm volatile("s_waitcnt lgkmcnt(0)" ::: "memory")
; __device__ __forceinline__ unsigned pk2(float lo, float hi) { return pg8::cvt_pk_bf16(lo, hi); }
; #define INP(i) ((const float*)ldp(T, (i)))
; #define TRJ(cnt, W, ldn, N, WT, ldk, gain, rbase, rstride) if (r >= 0) { if (r < (cnt)) { tr_item((W), (ldn), (N), (WT), (ldk), (gain), (rbase), (rstride), scr, r, lane); r = -1; } else r -= (cnt); }
; __device__ __forceinline__ void tr_item(const float* W, int ldn, int N, bf16_t* WT, int ldk, const float* gain, int rbase, int rstride, LAS float* scr, int item, int lane) {
;     const int nblk = N / 32, kb = item / nblk, nb = item % nblk, k0 = 64 * kb, n0 = 32 * nb;
;     f32x4 v[8]; float gk[8];
; #pragma unroll
;     for (int i = 0; i < 8; ++i) { const int kk = 8 * i + (lane >> 3); v[i] = *(const f32x4*)(W + (size_t)(k0 + kk) * ldn + n0 + 4 * (lane & 7)); gk[i] = gain ? gain[k0 + kk] : 1.0f; }
; #pragma unroll
;     for (int i = 0; i < 8; ++i) { LAS float* d = scr + (8 * i + (lane >> 3)) * 33 + 4 * (lane & 7); d[0] = v[i].x * gk[i]; d[1] = v[i].y * gk[i]; d[2] = v[i].z * gk[i]; d[3] = v[i].w * gk[i]; }
;     LDS_WAIT(); asm volatile("" ::: "memory");
;     const int c = lane & 7;
; #pragma unroll
;     for (int j = 0; j < 4; ++j) { const int n = (lane >> 3) + 8 * j; const LAS float* s = scr + (8 * c) * 33 + n;
;         u32x4 o; o.x = pk2(s[0 * 33], s[1 * 33]); o.y = pk2(s[2 * 33], s[3 * 33]); o.z = pk2(s[4 * 33], s[5 * 33]); o.w = pk2(s[6 * 33], s[7 * 33]);
;         const int nn = n0 + n, dest = rbase + (nn >> 7) * rstride + (nn & 127);
;         *(u32x4*)(WT + (size_t)dest * ldk + k0 + 8 * c) = o; }
;     LDS_WAIT(); asm volatile("" ::: "memory");
; __device__ __forceinline__ void prep_phase(const PT& T, LAS unsigned char* lds) {
;     ...
;         TRJ(I_1Kx1K, INP(12), D, D, Wb + WO_C_IN, D, INP(1) + 2 * D, 0, 128)
.LBB0_471:
	s_andn2_b64 vcc, exec, s[0:1]
	s_cbranch_vccnz .LBB0_473
	v_readlane_b32 s0, v254, 17
	v_add_u32_e32 v92, 0x1080, v87
	v_add_u32_e32 v94, 0x1088, v87
	v_mov_b32_e32 v0, s0
	ds_read_b64 v[2:3], v0
	v_mov_b32_e32 v0, s79
	ds_read_b64 v[4:5], v0
	v_lshlrev_b32_e32 v0, 2, v34
	v_add_u32_e32 v97, 0x14a0, v87
	s_waitcnt lgkmcnt(0)
	v_readfirstlane_b32 s8, v2
	v_readfirstlane_b32 s9, v3
	v_readfirstlane_b32 s0, v4
	v_readfirstlane_b32 s1, v5
	s_add_u32 s0, s0, 0x2000
	s_addc_u32 s1, s1, 0
	s_lshl_b32 s5, s4, 1
	s_lshl_b32 s4, s4, 5
	s_and_b32 s4, s4, 0x3e0
	s_and_b32 s5, s5, 0x3c0
	s_lshl_b32 s19, s4, 2
	s_add_u32 s8, s8, s19
	v_or_b32_e32 v83, s5, v81
	s_addc_u32 s9, s9, 0
	v_lshl_add_u64 v[30:31], s[8:9], 0, v[0:1]
	v_lshlrev_b32_e32 v0, 12, v83
	v_lshl_add_u64 v[2:3], v[30:31], 0, v[0:1]
	v_lshlrev_b32_e32 v0, 2, v83
	v_or_b32_e32 v10, 8, v83
	v_lshl_add_u64 v[6:7], s[0:1], 0, v[0:1]
	v_lshlrev_b32_e32 v0, 12, v10
	global_load_dword v78, v[6:7], off
	v_lshl_add_u64 v[6:7], v[30:31], 0, v[0:1]
	v_lshlrev_b32_e32 v0, 2, v10
	v_or_b32_e32 v14, 16, v83
	v_lshl_add_u64 v[10:11], s[0:1], 0, v[0:1]
	v_lshlrev_b32_e32 v0, 12, v14
	global_load_dword v80, v[10:11], off
	v_lshl_add_u64 v[10:11], v[30:31], 0, v[0:1]
	v_lshlrev_b32_e32 v0, 2, v14
	v_or_b32_e32 v18, 24, v83
	v_lshl_add_u64 v[14:15], s[0:1], 0, v[0:1]
	v_lshlrev_b32_e32 v0, 12, v18
	global_load_dword v82, v[14:15], off
	v_lshl_add_u64 v[14:15], v[30:31], 0, v[0:1]
	v_lshlrev_b32_e32 v0, 2, v18
	v_or_b32_e32 v22, 32, v83
	v_lshl_add_u64 v[18:19], s[0:1], 0, v[0:1]
	v_lshlrev_b32_e32 v0, 12, v22
	global_load_dwordx4 v[2:5], v[2:3], off
	v_or_b32_e32 v26, 40, v83
	global_load_dword v84, v[18:19], off
	v_lshl_add_u64 v[18:19], v[30:31], 0, v[0:1]
	v_lshlrev_b32_e32 v0, 2, v22
	global_load_dwordx4 v[6:9], v[6:7], off
	v_lshl_add_u64 v[22:23], s[0:1], 0, v[0:1]
	v_lshlrev_b32_e32 v0, 12, v26
	global_load_dwordx4 v[10:13], v[10:11], off
	v_or_b32_e32 v32, 48, v83
	global_load_dword v86, v[22:23], off
	v_lshl_add_u64 v[22:23], v[30:31], 0, v[0:1]
	v_lshlrev_b32_e32 v0, 2, v26
	global_load_dwordx4 v[14:17], v[14:15], off
	v_lshl_add_u64 v[26:27], s[0:1], 0, v[0:1]
	v_lshlrev_b32_e32 v0, 12, v32
	global_load_dwordx4 v[18:21], v[18:19], off
	v_or_b32_e32 v83, 56, v83
	global_load_dword v88, v[26:27], off
	v_lshl_add_u64 v[26:27], v[30:31], 0, v[0:1]
	v_lshlrev_b32_e32 v0, 2, v32
	global_load_dwordx4 v[22:25], v[22:23], off
	v_lshl_add_u64 v[32:33], s[0:1], 0, v[0:1]
	v_lshlrev_b32_e32 v0, 12, v83
	global_load_dwordx4 v[26:29], v[26:27], off
	v_lshl_add_u64 v[30:31], v[30:31], 0, v[0:1]
	global_load_dword v90, v[32:33], off
	v_lshlrev_b32_e32 v0, 2, v83
	v_lshl_add_u64 v[98:99], s[0:1], 0, v[0:1]
	global_load_dword v0, v[98:99], off
	v_add_u32_e32 v83, v85, v91
	global_load_dwordx4 v[30:33], v[30:31], off
	v_add_u32_e32 v99, 0x420, v83
	v_add_u32_e32 v100, 0x428, v83
	v_add_u32_e32 v101, 0x840, v83
	v_add_u32_e32 v102, 0x848, v83
	v_add_u32_e32 v98, 0x14a8, v87
	s_lshl_b32 s46, s5, 1
	s_mov_b32 s5, -1
	s_waitcnt vmcnt(0) lgkmcnt(0)
	v_pk_mul_f32 v[2:3], v[2:3], v[78:79] op_sel_hi:[1,0]
	v_pk_mul_f32 v[4:5], v[4:5], v[78:79] op_sel_hi:[1,0]
	ds_write2_b32 v87, v2, v3 offset1:1
	ds_write2_b32 v87, v4, v5 offset0:2 offset1:3
	v_pk_mul_f32 v[2:3], v[6:7], v[80:81] op_sel_hi:[1,0]
	v_pk_mul_f32 v[4:5], v[8:9], v[80:81] op_sel_hi:[1,0]
	ds_write2_b32 v83, v2, v3 offset1:1
	ds_write2_b32 v83, v4, v5 offset0:2 offset1:3
	v_pk_mul_f32 v[2:3], v[10:11], v[82:83] op_sel_hi:[1,0]
	v_pk_mul_f32 v[4:5], v[12:13], v[82:83] op_sel_hi:[1,0]
	ds_write2_b32 v99, v2, v3 offset1:1
	ds_write2_b32 v100, v4, v5 offset1:1
	v_lshl_add_u64 v[8:9], v[50:51], 0, s[46:47]
	v_pk_mul_f32 v[2:3], v[14:15], v[84:85] op_sel_hi:[1,0]
	v_pk_mul_f32 v[4:5], v[16:17], v[84:85] op_sel_hi:[1,0]
	ds_write2_b32 v101, v2, v3 offset1:1
	ds_write2_b32 v102, v4, v5 offset1:1
	v_pk_mul_f32 v[2:3], v[18:19], v[86:87] op_sel_hi:[1,0]
	v_pk_mul_f32 v[4:5], v[20:21], v[86:87] op_sel_hi:[1,0]
	ds_write2_b32 v92, v2, v3 offset1:1
	ds_write2_b32 v94, v4, v5 offset1:1
	v_pk_mul_f32 v[2:3], v[22:23], v[88:89] op_sel_hi:[1,0]
	v_pk_mul_f32 v[4:5], v[24:25], v[88:89] op_sel_hi:[1,0]
	ds_write2_b32 v97, v2, v3 offset1:1
	ds_write2_b32 v98, v4, v5 offset1:1
	v_add_u32_e32 v4, 0x18c0, v87
	v_pk_mul_f32 v[2:3], v[26:27], v[90:91] op_sel_hi:[1,0]
	ds_write2_b32 v4, v2, v3 offset1:1
	v_pk_mul_f32 v[2:3], v[28:29], v[90:91] op_sel_hi:[1,0]
	v_add_u32_e32 v4, 0x18c8, v87
	ds_write2_b32 v4, v2, v3 offset1:1
	v_pk_mul_f32 v[2:3], v[30:31], v[0:1] op_sel_hi:[1,0]
	v_add_u32_e32 v4, 0x1ce0, v87
	ds_write2_b32 v4, v2, v3 offset1:1
	v_pk_mul_f32 v[2:3], v[32:33], v[0:1] op_sel_hi:[1,0]
	v_add_u32_e32 v0, 0x1ce8, v87
	ds_write2_b32 v0, v2, v3 offset1:1
	s_waitcnt lgkmcnt(0)
	ds_read2_b32 v[2:3], v96 offset1:33
	v_or_b32_e32 v0, s4, v81
	s_waitcnt lgkmcnt(0)
	v_cvt_pk_bf16_f32 v2, v2, v3
	ds_read2_b32 v[4:5], v96 offset0:66 offset1:99
	v_lshlrev_b32_e32 v0, 11, v0
	s_waitcnt lgkmcnt(0)
	v_cvt_pk_bf16_f32 v3, v4, v5
	ds_read2_b32 v[4:5], v96 offset0:132 offset1:165
	v_lshl_add_u64 v[10:11], v[8:9], 0, v[0:1]
	s_waitcnt lgkmcnt(0)
	v_cvt_pk_bf16_f32 v4, v4, v5
	ds_read2_b32 v[6:7], v96 offset0:198 offset1:231
	s_waitcnt lgkmcnt(0)
	v_cvt_pk_bf16_f32 v5, v6, v7
	global_store_dwordx4 v[10:11], v[2:5], off
	ds_read2_b32 v[2:3], v96 offset0:8 offset1:41
	v_or_b32_e32 v0, s4, v89
	s_waitcnt lgkmcnt(0)
	v_cvt_pk_bf16_f32 v2, v2, v3
	ds_read2_b32 v[4:5], v96 offset0:74 offset1:107
	v_lshlrev_b32_e32 v0, 11, v0
	s_waitcnt lgkmcnt(0)
	v_cvt_pk_bf16_f32 v3, v4, v5
	ds_read2_b32 v[4:5], v96 offset0:140 offset1:173
	v_lshl_add_u64 v[10:11], v[8:9], 0, v[0:1]
	s_waitcnt lgkmcnt(0)
	v_cvt_pk_bf16_f32 v4, v4, v5
	ds_read2_b32 v[6:7], v96 offset0:206 offset1:239
	s_waitcnt lgkmcnt(0)
	v_cvt_pk_bf16_f32 v5, v6, v7
	global_store_dwordx4 v[10:11], v[2:5], off
	ds_read2_b32 v[2:3], v96 offset0:16 offset1:49
	v_or_b32_e32 v0, s4, v93
	s_waitcnt lgkmcnt(0)
	v_cvt_pk_bf16_f32 v2, v2, v3
	ds_read2_b32 v[4:5], v96 offset0:82 offset1:115
	v_lshlrev_b32_e32 v0, 11, v0
	s_waitcnt lgkmcnt(0)
	v_cvt_pk_bf16_f32 v3, v4, v5
	ds_read2_b32 v[4:5], v96 offset0:148 offset1:181
	v_lshl_add_u64 v[10:11], v[8:9], 0, v[0:1]
	s_waitcnt lgkmcnt(0)
	v_cvt_pk_bf16_f32 v4, v4, v5
	ds_read2_b32 v[6:7], v96 offset0:214 offset1:247
	s_waitcnt lgkmcnt(0)
	v_cvt_pk_bf16_f32 v5, v6, v7
	global_store_dwordx4 v[10:11], v[2:5], off
	ds_read2_b32 v[2:3], v96 offset0:24 offset1:57
	v_or_b32_e32 v0, s4, v95
	s_waitcnt lgkmcnt(0)
	v_cvt_pk_bf16_f32 v2, v2, v3
	ds_read2_b32 v[4:5], v96 offset0:90 offset1:123
	s_waitcnt lgkmcnt(0)
	v_cvt_pk_bf16_f32 v3, v4, v5
	ds_read2_b32 v[4:5], v96 offset0:156 offset1:189
	s_waitcnt lgkmcnt(0)
	v_cvt_pk_bf16_f32 v4, v4, v5
	ds_read2_b32 v[6:7], v96 offset0:222 offset1:255
	v_lshlrev_b32_e32 v0, 11, v0
	s_waitcnt lgkmcnt(0)
	v_cvt_pk_bf16_f32 v5, v6, v7
	v_lshl_add_u64 v[6:7], v[8:9], 0, v[0:1]
	global_store_dwordx4 v[6:7], v[2:5], off
	s_waitcnt lgkmcnt(0)

; #define LAS __attribute__((address_space(3)))
; #define LDS_WAIT() asm volatile("s_waitcnt lgkmcnt(0)" ::: "memory")
; __device__ __forceinline__ unsigned pk2(float lo, float hi) { return pg8::cvt_pk_bf16(lo, hi); }
; #define INP(i) ((const float*)ldp(T, (i)))
; #define TRJ(cnt, W, ldn, N, WT, ldk, gain, rbase, rstride) if (r >= 0) { if (r < (cnt)) { tr_item((W), (ldn), (N), (WT), (ldk), (gain), (rbase), (rstride), scr, r, lane); r = -1; } else r -= (cnt); }
; __device__ __forceinline__ void tr_item(const float* W, int ldn, int N, bf16_t* WT, int ldk, const float* gain, int rbase, int rstride, LAS float* scr, int item, int lane) {
;     const int nblk = N / 32, kb = item / nblk, nb = item % nblk, k0 = 64 * kb, n0 = 32 * nb;
;     f32x4 v[8]; float gk[8];
; #pragma unroll
;     for (int i = 0; i < 8; ++i) { const int kk = 8 * i + (lane >> 3); v[i] = *(const f32x4*)(W + (size_t)(k0 + kk) * ldn + n0 + 4 * (lane & 7)); gk[i] = gain ? gain[k0 + kk] : 1.0f; }
; #pragma unroll
;     for (int i = 0; i < 8; ++i) { LAS float* d = scr + (8 * i + (lane >> 3)) * 33 + 4 * (lane & 7); d[0] = v[i].x * gk[i]; d[1] = v[i].y * gk[i]; d[2] = v[i].z * gk[i]; d[3] = v[i].w * gk[i]; }
;     LDS_WAIT(); asm volatile("" ::: "memory");
;     const int c = lane & 7;
; #pragma unroll
;     for (int j = 0; j < 4; ++j) { const int n = (lane >> 3) + 8 * j; const LAS float* s = scr + (8 * c) * 33 + n;
;         u32x4 o; o.x = pk2(s[0 * 33], s[1 * 33]); o.y = pk2(s[2 * 33], s[3 * 33]); o.z = pk2(s[4 * 33], s[5 * 33]); o.w = pk2(s[6 * 33], s[7 * 33]);
;         const int nn = n0 + n, dest = rbase + (nn >> 7) * rstride + (nn & 127);
;         *(u32x4*)(WT + (size_t)dest * ldk + k0 + 8 * c) = o; }
;     LDS_WAIT(); asm volatile("" ::: "memory");
; __device__ __forceinline__ void prep_phase(const PT& T, LAS unsigned char* lds) {
;     ...
;         TRJ(I_1Kx1K, INP(15), D, D, Wb + WO_C_OUT, D, nullptr, 0, 128)
.LBB0_477:
	s_andn2_b64 vcc, exec, s[0:1]
	s_cbranch_vccnz .LBB0_479
	v_readlane_b32 s0, v254, 18
	s_lshl_b32 s1, s4, 5
	v_add_u32_e32 v78, 0x1080, v87
	v_mov_b32_e32 v0, s0
	ds_read_b64 v[2:3], v0
	s_lshl_b32 s0, s4, 1
	s_and_b32 s8, s0, 0x3c0
	s_and_b32 s0, s1, 0x3e0
	s_lshl_b32 s1, s0, 2
	s_waitcnt lgkmcnt(0)
	v_readfirstlane_b32 s4, v2
	v_readfirstlane_b32 s5, v3
	s_add_u32 s4, s4, s1
	v_or_b32_e32 v4, s8, v81
	s_addc_u32 s5, s5, 0
	v_lshlrev_b32_e32 v0, 2, v34
	v_lshl_add_u64 v[2:3], s[4:5], 0, v[0:1]
	v_lshlrev_b32_e32 v0, 12, v4
	v_lshl_add_u64 v[30:31], v[2:3], 0, v[0:1]
	v_add_co_u32_e32 v6, vcc, s77, v30
	v_add_u32_e32 v0, v85, v91
	s_nop 0
	v_addc_co_u32_e32 v7, vcc, 0, v31, vcc
	v_add_co_u32_e32 v10, vcc, s24, v30
	global_load_dwordx4 v[2:5], v[30:31], off
	s_nop 0
	global_load_dwordx4 v[6:9], v[6:7], off
	v_addc_co_u32_e32 v11, vcc, 0, v31, vcc
	v_add_co_u32_e32 v14, vcc, s71, v30
	v_add_u32_e32 v80, 0x1088, v87
	s_nop 0
	v_addc_co_u32_e32 v15, vcc, 0, v31, vcc
	v_add_co_u32_e32 v18, vcc, s27, v30
	global_load_dwordx4 v[10:13], v[10:11], off
	s_nop 0
	global_load_dwordx4 v[14:17], v[14:15], off
	v_addc_co_u32_e32 v19, vcc, 0, v31, vcc
	v_add_co_u32_e32 v22, vcc, s28, v30
	v_add_u32_e32 v82, 0x14a0, v87
	s_nop 0
	v_addc_co_u32_e32 v23, vcc, 0, v31, vcc
	global_load_dwordx4 v[18:21], v[18:19], off
	s_nop 0
	global_load_dwordx4 v[22:25], v[22:23], off
	v_add_co_u32_e32 v26, vcc, s81, v30
	v_add_u32_e32 v83, 0x14a8, v87
	s_nop 0
	v_addc_co_u32_e32 v27, vcc, 0, v31, vcc
	global_load_dwordx4 v[26:29], v[26:27], off
	v_add_co_u32_e32 v30, vcc, s29, v30
	v_add_u32_e32 v84, 0x18c0, v87
	s_nop 0
	v_addc_co_u32_e32 v31, vcc, 0, v31, vcc
	global_load_dwordx4 v[30:33], v[30:31], off
	v_add_u32_e32 v86, 0x18c8, v87
	v_add_u32_e32 v88, 0x1ce0, v87
	v_add_u32_e32 v90, 0x1ce8, v87
	v_add_u32_e32 v92, 0x420, v0
	v_add_u32_e32 v94, 0x428, v0
	v_add_u32_e32 v97, 0x840, v0
	v_add_u32_e32 v98, 0x848, v0
	s_lshl_b32 s46, s8, 1
	s_mov_b32 s5, -1
	s_waitcnt vmcnt(0) lgkmcnt(0)
	ds_write2_b32 v87, v2, v3 offset1:1
	ds_write2_b32 v87, v4, v5 offset0:2 offset1:3
	ds_write2_b32 v0, v6, v7 offset1:1
	ds_write2_b32 v0, v8, v9 offset0:2 offset1:3
	ds_write2_b32 v92, v10, v11 offset1:1
	ds_write2_b32 v94, v12, v13 offset1:1
	ds_write2_b32 v97, v14, v15 offset1:1
	ds_write2_b32 v98, v16, v17 offset1:1
	ds_write2_b32 v78, v18, v19 offset1:1
	ds_write2_b32 v80, v20, v21 offset1:1
	ds_write2_b32 v82, v22, v23 offset1:1
	ds_write2_b32 v83, v24, v25 offset1:1
	ds_write2_b32 v84, v26, v27 offset1:1
	ds_write2_b32 v86, v28, v29 offset1:1
	ds_write2_b32 v88, v30, v31 offset1:1
	ds_write2_b32 v90, v32, v33 offset1:1
	s_waitcnt lgkmcnt(0)
	ds_read2_b32 v[2:3], v96 offset1:33
	v_or_b32_e32 v0, s0, v81
	s_waitcnt lgkmcnt(0)
	v_cvt_pk_bf16_f32 v2, v2, v3
	ds_read2_b32 v[4:5], v96 offset0:66 offset1:99
	v_lshl_add_u64 v[8:9], v[52:53], 0, s[46:47]
	v_lshlrev_b32_e32 v0, 11, v0
	s_waitcnt lgkmcnt(0)
	v_cvt_pk_bf16_f32 v3, v4, v5
	ds_read2_b32 v[4:5], v96 offset0:132 offset1:165
	v_lshl_add_u64 v[10:11], v[8:9], 0, v[0:1]
	s_waitcnt lgkmcnt(0)
	v_cvt_pk_bf16_f32 v4, v4, v5
	ds_read2_b32 v[6:7], v96 offset0:198 offset1:231
	s_waitcnt lgkmcnt(0)
	v_cvt_pk_bf16_f32 v5, v6, v7
	global_store_dwordx4 v[10:11], v[2:5], off
	ds_read2_b32 v[2:3], v96 offset0:8 offset1:41
	v_or_b32_e32 v0, s0, v89
	s_waitcnt lgkmcnt(0)
	v_cvt_pk_bf16_f32 v2, v2, v3
	ds_read2_b32 v[4:5], v96 offset0:74 offset1:107
	v_lshlrev_b32_e32 v0, 11, v0
	s_waitcnt lgkmcnt(0)
	v_cvt_pk_bf16_f32 v3, v4, v5
	ds_read2_b32 v[4:5], v96 offset0:140 offset1:173
	v_lshl_add_u64 v[10:11], v[8:9], 0, v[0:1]
	s_waitcnt lgkmcnt(0)
	v_cvt_pk_bf16_f32 v4, v4, v5
	ds_read2_b32 v[6:7], v96 offset0:206 offset1:239
	s_waitcnt lgkmcnt(0)
	v_cvt_pk_bf16_f32 v5, v6, v7
	global_store_dwordx4 v[10:11], v[2:5], off
	ds_read2_b32 v[2:3], v96 offset0:16 offset1:49
	v_or_b32_e32 v0, s0, v93
	s_waitcnt lgkmcnt(0)
	v_cvt_pk_bf16_f32 v2, v2, v3
	ds_read2_b32 v[4:5], v96 offset0:82 offset1:115
	v_lshlrev_b32_e32 v0, 11, v0
	s_waitcnt lgkmcnt(0)
	v_cvt_pk_bf16_f32 v3, v4, v5
	ds_read2_b32 v[4:5], v96 offset0:148 offset1:181
	v_lshl_add_u64 v[10:11], v[8:9], 0, v[0:1]
	s_waitcnt lgkmcnt(0)
	v_cvt_pk_bf16_f32 v4, v4, v5
	ds_read2_b32 v[6:7], v96 offset0:214 offset1:247
	s_waitcnt lgkmcnt(0)
	v_cvt_pk_bf16_f32 v5, v6, v7
	global_store_dwordx4 v[10:11], v[2:5], off
	ds_read2_b32 v[2:3], v96 offset0:24 offset1:57
	v_or_b32_e32 v0, s0, v95
	s_waitcnt lgkmcnt(0)
	v_cvt_pk_bf16_f32 v2, v2, v3
	ds_read2_b32 v[4:5], v96 offset0:90 offset1:123
	s_waitcnt lgkmcnt(0)
	v_cvt_pk_bf16_f32 v3, v4, v5
	ds_read2_b32 v[4:5], v96 offset0:156 offset1:189
	s_waitcnt lgkmcnt(0)
	v_cvt_pk_bf16_f32 v4, v4, v5
	ds_read2_b32 v[6:7], v96 offset0:222 offset1:255
	v_lshlrev_b32_e32 v0, 11, v0
	s_waitcnt lgkmcnt(0)
	v_cvt_pk_bf16_f32 v5, v6, v7
	v_lshl_add_u64 v[6:7], v[8:9], 0, v[0:1]
	global_store_dwordx4 v[6:7], v[2:5], off
	s_waitcnt lgkmcnt(0)

; #define LAS __attribute__((address_space(3)))
; #define LDS_WAIT() asm volatile("s_waitcnt lgkmcnt(0)" ::: "memory")
; __device__ __forceinline__ unsigned pk2(float lo, float hi) { return pg8::cvt_pk_bf16(lo, hi); }
; #define INP(i) ((const float*)ldp(T, (i)))
; #define TRJ(cnt, W, ldn, N, WT, ldk, gain, rbase, rstride) if (r >= 0) { if (r < (cnt)) { tr_item((W), (ldn), (N), (WT), (ldk), (gain), (rbase), (rstride), scr, r, lane); r = -1; } else r -= (cnt); }
; __device__ __forceinline__ void tr_item(const float* W, int ldn, int N, bf16_t* WT, int ldk, const float* gain, int rbase, int rstride, LAS float* scr, int item, int lane) {
;     const int nblk = N / 32, kb = item / nblk, nb = item % nblk, k0 = 64 * kb, n0 = 32 * nb;
;     f32x4 v[8]; float gk[8];
; #pragma unroll
;     for (int i = 0; i < 8; ++i) { const int kk = 8 * i + (lane >> 3); v[i] = *(const f32x4*)(W + (size_t)(k0 + kk) * ldn + n0 + 4 * (lane & 7)); gk[i] = gain ? gain[k0 + kk] : 1.0f; }
; #pragma unroll
;     for (int i = 0; i < 8; ++i) { LAS float* d = scr + (8 * i + (lane >> 3)) * 33 + 4 * (lane & 7); d[0] = v[i].x * gk[i]; d[1] = v[i].y * gk[i]; d[2] = v[i].z * gk[i]; d[3] = v[i].w * gk[i]; }
;     LDS_WAIT(); asm volatile("" ::: "memory");
;     const int c = lane & 7;
; #pragma unroll
;     for (int j = 0; j < 4; ++j) { const int n = (lane >> 3) + 8 * j; const LAS float* s = scr + (8 * c) * 33 + n;
;         u32x4 o; o.x = pk2(s[0 * 33], s[1 * 33]); o.y = pk2(s[2 * 33], s[3 * 33]); o.z = pk2(s[4 * 33], s[5 * 33]); o.w = pk2(s[6 * 33], s[7 * 33]);
;         const int nn = n0 + n, dest = rbase + (nn >> 7) * rstride + (nn & 127);
;         *(u32x4*)(WT + (size_t)dest * ldk + k0 + 8 * c) = o; }
;     LDS_WAIT(); asm volatile("" ::: "memory");
; __device__ __forceinline__ void prep_phase(const PT& T, LAS unsigned char* lds) {
;     ...
;         TRJ(I_GRP, INP(13) + 0 * 65536, 256, 256, Wb + WO_C_GRP + 0 * 65536, 256, nullptr, 0, 128)
.LBB0_483:
	s_andn2_b64 vcc, exec, s[0:1]
	s_cbranch_vccnz .LBB0_485
	v_mov_b32_e32 v0, s63
	ds_read_b64 v[2:3], v0
	s_lshl_b32 s0, s4, 3
	s_lshl_b32 s1, s4, 5
	s_and_b32 s8, s0, 0xc0
	s_and_b32 s0, s1, 0xe0
	s_waitcnt lgkmcnt(0)
	v_readfirstlane_b32 s4, v2
	s_lshl_b32 s1, s0, 2
	v_readfirstlane_b32 s5, v3
	s_add_u32 s4, s4, s1
	v_or_b32_e32 v4, s8, v81
	s_addc_u32 s5, s5, 0
	v_lshlrev_b32_e32 v0, 2, v34
	v_lshl_add_u64 v[2:3], s[4:5], 0, v[0:1]
	v_lshlrev_b32_e32 v0, 10, v4
	v_lshl_add_u64 v[30:31], v[2:3], 0, v[0:1]
	v_add_co_u32_e32 v6, vcc, s23, v30
	s_movk_i32 s1, 0x4000
	s_nop 0
	v_addc_co_u32_e32 v7, vcc, 0, v31, vcc
	v_add_co_u32_e32 v10, vcc, s1, v30
	s_movk_i32 s1, 0x6000
	s_nop 0
	v_addc_co_u32_e32 v11, vcc, 0, v31, vcc
	v_add_co_u32_e32 v14, vcc, s1, v30
	s_mov_b32 s1, 0xa000
	s_nop 0
	v_addc_co_u32_e32 v15, vcc, 0, v31, vcc
	v_add_co_u32_e32 v18, vcc, s77, v30
	global_load_dwordx4 v[2:5], v[30:31], off
	s_nop 0
	global_load_dwordx4 v[6:9], v[6:7], off
	v_addc_co_u32_e32 v19, vcc, 0, v31, vcc
	v_add_co_u32_e32 v22, vcc, s1, v30
	global_load_dwordx4 v[10:13], v[10:11], off
	s_nop 0
	global_load_dwordx4 v[14:17], v[14:15], off
	v_addc_co_u32_e32 v23, vcc, 0, v31, vcc
	global_load_dwordx4 v[18:21], v[18:19], off
	s_nop 0
	global_load_dwordx4 v[22:25], v[22:23], off
	s_mov_b32 s1, 0xc000
	v_add_co_u32_e32 v26, vcc, s1, v30
	s_mov_b32 s1, 0xe000
	s_nop 0
	v_addc_co_u32_e32 v27, vcc, 0, v31, vcc
	global_load_dwordx4 v[26:29], v[26:27], off
	v_add_co_u32_e32 v30, vcc, s1, v30
	v_add_u32_e32 v0, v85, v91
	s_nop 0
	v_addc_co_u32_e32 v31, vcc, 0, v31, vcc
	global_load_dwordx4 v[30:33], v[30:31], off
	v_add_u32_e32 v78, 0x1080, v87
	v_add_u32_e32 v80, 0x1088, v87
	v_add_u32_e32 v82, 0x14a0, v87
	v_add_u32_e32 v83, 0x14a8, v87
	v_add_u32_e32 v84, 0x18c0, v87
	v_add_u32_e32 v86, 0x18c8, v87
	v_add_u32_e32 v88, 0x1ce0, v87
	v_add_u32_e32 v90, 0x1ce8, v87
	v_add_u32_e32 v92, 0x420, v0
	v_add_u32_e32 v94, 0x428, v0
	v_add_u32_e32 v97, 0x840, v0
	v_add_u32_e32 v98, 0x848, v0
	s_lshl_b32 s46, s8, 1
	s_mov_b32 s5, -1
	s_waitcnt vmcnt(0) lgkmcnt(0)
	ds_write2_b32 v87, v2, v3 offset1:1
	ds_write2_b32 v87, v4, v5 offset0:2 offset1:3
	ds_write2_b32 v0, v6, v7 offset1:1
	ds_write2_b32 v0, v8, v9 offset0:2 offset1:3
	ds_write2_b32 v92, v10, v11 offset1:1
	ds_write2_b32 v94, v12, v13 offset1:1
	ds_write2_b32 v97, v14, v15 offset1:1
	ds_write2_b32 v98, v16, v17 offset1:1
	ds_write2_b32 v78, v18, v19 offset1:1
	ds_write2_b32 v80, v20, v21 offset1:1
	ds_write2_b32 v82, v22, v23 offset1:1
	ds_write2_b32 v83, v24, v25 offset1:1
	ds_write2_b32 v84, v26, v27 offset1:1
	ds_write2_b32 v86, v28, v29 offset1:1
	ds_write2_b32 v88, v30, v31 offset1:1
	ds_write2_b32 v90, v32, v33 offset1:1
	s_waitcnt lgkmcnt(0)
	ds_read2_b32 v[2:3], v96 offset1:33
	v_or_b32_e32 v0, s0, v81
	s_waitcnt lgkmcnt(0)
	v_cvt_pk_bf16_f32 v2, v2, v3
	ds_read2_b32 v[4:5], v96 offset0:66 offset1:99
	v_lshl_add_u64 v[8:9], v[54:55], 0, s[46:47]
	v_lshlrev_b32_e32 v0, 9, v0
	s_waitcnt lgkmcnt(0)
	v_cvt_pk_bf16_f32 v3, v4, v5
	ds_read2_b32 v[4:5], v96 offset0:132 offset1:165
	v_lshl_add_u64 v[10:11], v[8:9], 0, v[0:1]
	s_waitcnt lgkmcnt(0)
	v_cvt_pk_bf16_f32 v4, v4, v5
	ds_read2_b32 v[6:7], v96 offset0:198 offset1:231
	s_waitcnt lgkmcnt(0)
	v_cvt_pk_bf16_f32 v5, v6, v7
	global_store_dwordx4 v[10:11], v[2:5], off
	ds_read2_b32 v[2:3], v96 offset0:8 offset1:41
	v_or_b32_e32 v0, s0, v89
	s_waitcnt lgkmcnt(0)
	v_cvt_pk_bf16_f32 v2, v2, v3
	ds_read2_b32 v[4:5], v96 offset0:74 offset1:107
	v_lshlrev_b32_e32 v0, 9, v0
	s_waitcnt lgkmcnt(0)
	v_cvt_pk_bf16_f32 v3, v4, v5
	ds_read2_b32 v[4:5], v96 offset0:140 offset1:173
	v_lshl_add_u64 v[10:11], v[8:9], 0, v[0:1]
	s_waitcnt lgkmcnt(0)
	v_cvt_pk_bf16_f32 v4, v4, v5
	ds_read2_b32 v[6:7], v96 offset0:206 offset1:239
	s_waitcnt lgkmcnt(0)
	v_cvt_pk_bf16_f32 v5, v6, v7
	global_store_dwordx4 v[10:11], v[2:5], off
	ds_read2_b32 v[2:3], v96 offset0:16 offset1:49
	v_or_b32_e32 v0, s0, v93
	s_waitcnt lgkmcnt(0)
	v_cvt_pk_bf16_f32 v2, v2, v3
	ds_read2_b32 v[4:5], v96 offset0:82 offset1:115
	v_lshlrev_b32_e32 v0, 9, v0
	s_waitcnt lgkmcnt(0)
	v_cvt_pk_bf16_f32 v3, v4, v5
	ds_read2_b32 v[4:5], v96 offset0:148 offset1:181
	v_lshl_add_u64 v[10:11], v[8:9], 0, v[0:1]
	s_waitcnt lgkmcnt(0)
	v_cvt_pk_bf16_f32 v4, v4, v5
	ds_read2_b32 v[6:7], v96 offset0:214 offset1:247
	s_waitcnt lgkmcnt(0)
	v_cvt_pk_bf16_f32 v5, v6, v7
	global_store_dwordx4 v[10:11], v[2:5], off
	ds_read2_b32 v[2:3], v96 offset0:24 offset1:57
	v_or_b32_e32 v0, s0, v95
	s_waitcnt lgkmcnt(0)
	v_cvt_pk_bf16_f32 v2, v2, v3
	ds_read2_b32 v[4:5], v96 offset0:90 offset1:123
	s_waitcnt lgkmcnt(0)
	v_cvt_pk_bf16_f32 v3, v4, v5
	ds_read2_b32 v[4:5], v96 offset0:156 offset1:189
	s_waitcnt lgkmcnt(0)
	v_cvt_pk_bf16_f32 v4, v4, v5
	ds_read2_b32 v[6:7], v96 offset0:222 offset1:255
	v_lshlrev_b32_e32 v0, 9, v0
	s_waitcnt lgkmcnt(0)
	v_cvt_pk_bf16_f32 v5, v6, v7
	v_lshl_add_u64 v[6:7], v[8:9], 0, v[0:1]
	global_store_dwordx4 v[6:7], v[2:5], off
	s_waitcnt lgkmcnt(0)

; #define LAS __attribute__((address_space(3)))
; #define LDS_WAIT() asm volatile("s_waitcnt lgkmcnt(0)" ::: "memory")
; __device__ __forceinline__ unsigned pk2(float lo, float hi) { return pg8::cvt_pk_bf16(lo, hi); }
; #define INP(i) ((const float*)ldp(T, (i)))
; #define TRJ(cnt, W, ldn, N, WT, ldk, gain, rbase, rstride) if (r >= 0) { if (r < (cnt)) { tr_item((W), (ldn), (N), (WT), (ldk), (gain), (rbase), (rstride), scr, r, lane); r = -1; } else r -= (cnt); }
; __device__ __forceinline__ void tr_item(const float* W, int ldn, int N, bf16_t* WT, int ldk, const float* gain, int rbase, int rstride, LAS float* scr, int item, int lane) {
;     const int nblk = N / 32, kb = item / nblk, nb = item % nblk, k0 = 64 * kb, n0 = 32 * nb;
;     f32x4 v[8]; float gk[8];
; #pragma unroll
;     for (int i = 0; i < 8; ++i) { const int kk = 8 * i + (lane >> 3); v[i] = *(const f32x4*)(W + (size_t)(k0 + kk) * ldn + n0 + 4 * (lane & 7)); gk[i] = gain ? gain[k0 + kk] : 1.0f; }
; #pragma unroll
;     for (int i = 0; i < 8; ++i) { LAS float* d = scr + (8 * i + (lane >> 3)) * 33 + 4 * (lane & 7); d[0] = v[i].x * gk[i]; d[1] = v[i].y * gk[i]; d[2] = v[i].z * gk[i]; d[3] = v[i].w * gk[i]; }
;     LDS_WAIT(); asm volatile("" ::: "memory");
;     const int c = lane & 7;
; #pragma unroll
;     for (int j = 0; j < 4; ++j) { const int n = (lane >> 3) + 8 * j; const LAS float* s = scr + (8 * c) * 33 + n;
;         u32x4 o; o.x = pk2(s[0 * 33], s[1 * 33]); o.y = pk2(s[2 * 33], s[3 * 33]); o.z = pk2(s[4 * 33], s[5 * 33]); o.w = pk2(s[6 * 33], s[7 * 33]);
;         const int nn = n0 + n, dest = rbase + (nn >> 7) * rstride + (nn & 127);
;         *(u32x4*)(WT + (size_t)dest * ldk + k0 + 8 * c) = o; }
;     LDS_WAIT(); asm volatile("" ::: "memory");
; __device__ __forceinline__ void prep_phase(const PT& T, LAS unsigned char* lds) {
;     ...
;         TRJ(I_GRP, INP(13) + 1 * 65536, 256, 256, Wb + WO_C_GRP + 1 * 65536, 256, nullptr, 0, 128)
.LBB0_489:
	s_andn2_b64 vcc, exec, s[0:1]
	s_cbranch_vccnz .LBB0_491
	v_mov_b32_e32 v0, s63
	ds_read_b64 v[2:3], v0
	s_lshl_b32 s0, s4, 3
	s_lshl_b32 s1, s4, 5
	s_and_b32 s8, s0, 0xc0
	s_and_b32 s0, s1, 0xe0
	s_waitcnt lgkmcnt(0)
	v_readfirstlane_b32 s4, v2
	s_lshl_b32 s1, s0, 2
	v_readfirstlane_b32 s5, v3
	s_add_u32 s4, s4, s1
	v_or_b32_e32 v4, s8, v81
	s_addc_u32 s5, s5, 0
	v_lshlrev_b32_e32 v0, 2, v34
	v_lshl_add_u64 v[2:3], s[4:5], 0, v[0:1]
	v_lshlrev_b32_e32 v0, 10, v4
	v_lshl_add_u64 v[30:31], v[2:3], 0, v[0:1]
	v_add_co_u32_e32 v2, vcc, s25, v30
	s_mov_b32 s1, 0x42000
	s_nop 0
	v_addc_co_u32_e32 v3, vcc, 0, v31, vcc
	v_add_co_u32_e32 v6, vcc, s1, v30
	s_mov_b32 s1, 0x44000
	s_nop 0
	v_addc_co_u32_e32 v7, vcc, 0, v31, vcc
	v_add_co_u32_e32 v10, vcc, s1, v30
	s_mov_b32 s1, 0x46000
	s_nop 0
	v_addc_co_u32_e32 v11, vcc, 0, v31, vcc
	v_add_co_u32_e32 v14, vcc, s1, v30
	s_mov_b32 s1, 0x4a000
	s_nop 0
	v_addc_co_u32_e32 v15, vcc, 0, v31, vcc
	v_add_co_u32_e32 v18, vcc, s26, v30
	global_load_dwordx4 v[2:5], v[2:3], off
	s_nop 0
	global_load_dwordx4 v[6:9], v[6:7], off
	v_addc_co_u32_e32 v19, vcc, 0, v31, vcc
	v_add_co_u32_e32 v22, vcc, s1, v30
	global_load_dwordx4 v[10:13], v[10:11], off
	s_nop 0
	global_load_dwordx4 v[14:17], v[14:15], off
	v_addc_co_u32_e32 v23, vcc, 0, v31, vcc
	global_load_dwordx4 v[18:21], v[18:19], off
	s_nop 0
	global_load_dwordx4 v[22:25], v[22:23], off
	s_mov_b32 s1, 0x4c000
	v_add_co_u32_e32 v26, vcc, s1, v30
	s_mov_b32 s1, 0x4e000
	s_nop 0
	v_addc_co_u32_e32 v27, vcc, 0, v31, vcc
	global_load_dwordx4 v[26:29], v[26:27], off
	v_add_co_u32_e32 v30, vcc, s1, v30
	v_add_u32_e32 v0, v85, v91
	s_nop 0
	v_addc_co_u32_e32 v31, vcc, 0, v31, vcc
	global_load_dwordx4 v[30:33], v[30:31], off
	v_add_u32_e32 v78, 0x1080, v87
	v_add_u32_e32 v80, 0x1088, v87
	v_add_u32_e32 v82, 0x14a0, v87
	v_add_u32_e32 v83, 0x14a8, v87
	v_add_u32_e32 v84, 0x18c0, v87
	v_add_u32_e32 v86, 0x18c8, v87
	v_add_u32_e32 v88, 0x1ce0, v87
	v_add_u32_e32 v90, 0x1ce8, v87
	v_add_u32_e32 v92, 0x420, v0
	v_add_u32_e32 v94, 0x428, v0
	v_add_u32_e32 v97, 0x840, v0
	v_add_u32_e32 v98, 0x848, v0
	s_lshl_b32 s46, s8, 1
	s_mov_b32 s5, -1
	s_waitcnt vmcnt(0) lgkmcnt(0)
	ds_write2_b32 v87, v2, v3 offset1:1
	ds_write2_b32 v87, v4, v5 offset0:2 offset1:3
	ds_write2_b32 v0, v6, v7 offset1:1
	ds_write2_b32 v0, v8, v9 offset0:2 offset1:3
	ds_write2_b32 v92, v10, v11 offset1:1
	ds_write2_b32 v94, v12, v13 offset1:1
	ds_write2_b32 v97, v14, v15 offset1:1
	ds_write2_b32 v98, v16, v17 offset1:1
	ds_write2_b32 v78, v18, v19 offset1:1
	ds_write2_b32 v80, v20, v21 offset1:1
	ds_write2_b32 v82, v22, v23 offset1:1
	ds_write2_b32 v83, v24, v25 offset1:1
	ds_write2_b32 v84, v26, v27 offset1:1
	ds_write2_b32 v86, v28, v29 offset1:1
	ds_write2_b32 v88, v30, v31 offset1:1
	ds_write2_b32 v90, v32, v33 offset1:1
	s_waitcnt lgkmcnt(0)
	ds_read2_b32 v[2:3], v96 offset1:33
	v_or_b32_e32 v0, s0, v81
	s_waitcnt lgkmcnt(0)
	v_cvt_pk_bf16_f32 v2, v2, v3
	ds_read2_b32 v[4:5], v96 offset0:66 offset1:99
	v_lshl_add_u64 v[8:9], v[56:57], 0, s[46:47]
	v_lshlrev_b32_e32 v0, 9, v0
	s_waitcnt lgkmcnt(0)
	v_cvt_pk_bf16_f32 v3, v4, v5
	ds_read2_b32 v[4:5], v96 offset0:132 offset1:165
	v_lshl_add_u64 v[10:11], v[8:9], 0, v[0:1]
	s_waitcnt lgkmcnt(0)
	v_cvt_pk_bf16_f32 v4, v4, v5
	ds_read2_b32 v[6:7], v96 offset0:198 offset1:231
	s_waitcnt lgkmcnt(0)
	v_cvt_pk_bf16_f32 v5, v6, v7
	global_store_dwordx4 v[10:11], v[2:5], off
	ds_read2_b32 v[2:3], v96 offset0:8 offset1:41
	v_or_b32_e32 v0, s0, v89
	s_waitcnt lgkmcnt(0)
	v_cvt_pk_bf16_f32 v2, v2, v3
	ds_read2_b32 v[4:5], v96 offset0:74 offset1:107
	v_lshlrev_b32_e32 v0, 9, v0
	s_waitcnt lgkmcnt(0)
	v_cvt_pk_bf16_f32 v3, v4, v5
	ds_read2_b32 v[4:5], v96 offset0:140 offset1:173
	v_lshl_add_u64 v[10:11], v[8:9], 0, v[0:1]
	s_waitcnt lgkmcnt(0)
	v_cvt_pk_bf16_f32 v4, v4, v5
	ds_read2_b32 v[6:7], v96 offset0:206 offset1:239
	s_waitcnt lgkmcnt(0)
	v_cvt_pk_bf16_f32 v5, v6, v7
	global_store_dwordx4 v[10:11], v[2:5], off
	ds_read2_b32 v[2:3], v96 offset0:16 offset1:49
	v_or_b32_e32 v0, s0, v93
	s_waitcnt lgkmcnt(0)
	v_cvt_pk_bf16_f32 v2, v2, v3
	ds_read2_b32 v[4:5], v96 offset0:82 offset1:115
	v_lshlrev_b32_e32 v0, 9, v0
	s_waitcnt lgkmcnt(0)
	v_cvt_pk_bf16_f32 v3, v4, v5
	ds_read2_b32 v[4:5], v96 offset0:148 offset1:181
	v_lshl_add_u64 v[10:11], v[8:9], 0, v[0:1]
	s_waitcnt lgkmcnt(0)
	v_cvt_pk_bf16_f32 v4, v4, v5
	ds_read2_b32 v[6:7], v96 offset0:214 offset1:247
	s_waitcnt lgkmcnt(0)
	v_cvt_pk_bf16_f32 v5, v6, v7
	global_store_dwordx4 v[10:11], v[2:5], off
	ds_read2_b32 v[2:3], v96 offset0:24 offset1:57
	v_or_b32_e32 v0, s0, v95
	s_waitcnt lgkmcnt(0)
	v_cvt_pk_bf16_f32 v2, v2, v3
	ds_read2_b32 v[4:5], v96 offset0:90 offset1:123
	s_waitcnt lgkmcnt(0)
	v_cvt_pk_bf16_f32 v3, v4, v5
	ds_read2_b32 v[4:5], v96 offset0:156 offset1:189
	s_waitcnt lgkmcnt(0)
	v_cvt_pk_bf16_f32 v4, v4, v5
	ds_read2_b32 v[6:7], v96 offset0:222 offset1:255
	v_lshlrev_b32_e32 v0, 9, v0
	s_waitcnt lgkmcnt(0)
	v_cvt_pk_bf16_f32 v5, v6, v7
	v_lshl_add_u64 v[6:7], v[8:9], 0, v[0:1]
	global_store_dwordx4 v[6:7], v[2:5], off
	s_waitcnt lgkmcnt(0)

; #define LAS __attribute__((address_space(3)))
; #define LDS_WAIT() asm volatile("s_waitcnt lgkmcnt(0)" ::: "memory")
; __device__ __forceinline__ unsigned pk2(float lo, float hi) { return pg8::cvt_pk_bf16(lo, hi); }
; #define INP(i) ((const float*)ldp(T, (i)))
; #define TRJ(cnt, W, ldn, N, WT, ldk, gain, rbase, rstride) if (r >= 0) { if (r < (cnt)) { tr_item((W), (ldn), (N), (WT), (ldk), (gain), (rbase), (rstride), scr, r, lane); r = -1; } else r -= (cnt); }
; __device__ __forceinline__ void tr_item(const float* W, int ldn, int N, bf16_t* WT, int ldk, const float* gain, int rbase, int rstride, LAS float* scr, int item, int lane) {
;     const int nblk = N / 32, kb = item / nblk, nb = item % nblk, k0 = 64 * kb, n0 = 32 * nb;
;     f32x4 v[8]; float gk[8];
; #pragma unroll
;     for (int i = 0; i < 8; ++i) { const int kk = 8 * i + (lane >> 3); v[i] = *(const f32x4*)(W + (size_t)(k0 + kk) * ldn + n0 + 4 * (lane & 7)); gk[i] = gain ? gain[k0 + kk] : 1.0f; }
; #pragma unroll
;     for (int i = 0; i < 8; ++i) { LAS float* d = scr + (8 * i + (lane >> 3)) * 33 + 4 * (lane & 7); d[0] = v[i].x * gk[i]; d[1] = v[i].y * gk[i]; d[2] = v[i].z * gk[i]; d[3] = v[i].w * gk[i]; }
;     LDS_WAIT(); asm volatile("" ::: "memory");
;     const int c = lane & 7;
; #pragma unroll
;     for (int j = 0; j < 4; ++j) { const int n = (lane >> 3) + 8 * j; const LAS float* s = scr + (8 * c) * 33 + n;
;         u32x4 o; o.x = pk2(s[0 * 33], s[1 * 33]); o.y = pk2(s[2 * 33], s[3 * 33]); o.z = pk2(s[4 * 33], s[5 * 33]); o.w = pk2(s[6 * 33], s[7 * 33]);
;         const int nn = n0 + n, dest = rbase + (nn >> 7) * rstride + (nn & 127);
;         *(u32x4*)(WT + (size_t)dest * ldk + k0 + 8 * c) = o; }
;     LDS_WAIT(); asm volatile("" ::: "memory");
; __device__ __forceinline__ void prep_phase(const PT& T, LAS unsigned char* lds) {
;     ...
;         TRJ(I_GRP, INP(13) + 2 * 65536, 256, 256, Wb + WO_C_GRP + 2 * 65536, 256, nullptr, 0, 128)
.LBB0_495:
	s_andn2_b64 vcc, exec, s[0:1]
	s_cbranch_vccnz .LBB0_497
	v_mov_b32_e32 v0, s63
	ds_read_b64 v[2:3], v0
	s_lshl_b32 s0, s4, 3
	s_lshl_b32 s1, s4, 5
	s_and_b32 s8, s0, 0xc0
	s_and_b32 s0, s1, 0xe0
	s_waitcnt lgkmcnt(0)
	v_readfirstlane_b32 s4, v2
	s_lshl_b32 s1, s0, 2
	v_readfirstlane_b32 s5, v3
	s_add_u32 s4, s4, s1
	v_or_b32_e32 v4, s8, v81
	s_addc_u32 s5, s5, 0
	v_lshlrev_b32_e32 v0, 2, v34
	v_lshl_add_u64 v[2:3], s[4:5], 0, v[0:1]
	v_lshlrev_b32_e32 v0, 10, v4
	v_lshl_add_u64 v[30:31], v[2:3], 0, v[0:1]
	s_mov_b32 s1, 0x80000
	v_add_co_u32_e32 v2, vcc, s1, v30
	s_mov_b32 s1, 0x82000
	s_nop 0
	v_addc_co_u32_e32 v3, vcc, 0, v31, vcc
	v_add_co_u32_e32 v6, vcc, s1, v30
	s_mov_b32 s1, 0x84000
	s_nop 0
	v_addc_co_u32_e32 v7, vcc, 0, v31, vcc
	v_add_co_u32_e32 v10, vcc, s1, v30
	s_mov_b32 s1, 0x86000
	s_nop 0
	v_addc_co_u32_e32 v11, vcc, 0, v31, vcc
	v_add_co_u32_e32 v14, vcc, s1, v30
	s_mov_b32 s1, 0x88000
	s_nop 0
	v_addc_co_u32_e32 v15, vcc, 0, v31, vcc
	v_add_co_u32_e32 v18, vcc, s1, v30
	s_mov_b32 s1, 0x8a000
	s_nop 0
	v_addc_co_u32_e32 v19, vcc, 0, v31, vcc
	v_add_co_u32_e32 v22, vcc, s1, v30
	global_load_dwordx4 v[2:5], v[2:3], off
	s_nop 0
	global_load_dwordx4 v[6:9], v[6:7], off
	v_addc_co_u32_e32 v23, vcc, 0, v31, vcc
	global_load_dwordx4 v[10:13], v[10:11], off
	s_nop 0
	global_load_dwordx4 v[14:17], v[14:15], off
	s_nop 0
	global_load_dwordx4 v[18:21], v[18:19], off
	s_nop 0
	global_load_dwordx4 v[22:25], v[22:23], off
	s_mov_b32 s1, 0x8c000
	v_add_co_u32_e32 v26, vcc, s1, v30
	s_mov_b32 s1, 0x8e000
	s_nop 0
	v_addc_co_u32_e32 v27, vcc, 0, v31, vcc
	global_load_dwordx4 v[26:29], v[26:27], off
	v_add_co_u32_e32 v30, vcc, s1, v30
	v_add_u32_e32 v0, v85, v91
	s_nop 0
	v_addc_co_u32_e32 v31, vcc, 0, v31, vcc
	global_load_dwordx4 v[30:33], v[30:31], off
	v_add_u32_e32 v78, 0x1080, v87
	v_add_u32_e32 v80, 0x1088, v87
	v_add_u32_e32 v82, 0x14a0, v87
	v_add_u32_e32 v83, 0x14a8, v87
	v_add_u32_e32 v84, 0x18c0, v87
	v_add_u32_e32 v86, 0x18c8, v87
	v_add_u32_e32 v88, 0x1ce0, v87
	v_add_u32_e32 v90, 0x1ce8, v87
	v_add_u32_e32 v92, 0x420, v0
	v_add_u32_e32 v94, 0x428, v0
	v_add_u32_e32 v97, 0x840, v0
	v_add_u32_e32 v98, 0x848, v0
	s_lshl_b32 s46, s8, 1
	s_mov_b32 s5, -1
	s_waitcnt vmcnt(0) lgkmcnt(0)
	ds_write2_b32 v87, v2, v3 offset1:1
	ds_write2_b32 v87, v4, v5 offset0:2 offset1:3
	ds_write2_b32 v0, v6, v7 offset1:1
	ds_write2_b32 v0, v8, v9 offset0:2 offset1:3
	ds_write2_b32 v92, v10, v11 offset1:1
	ds_write2_b32 v94, v12, v13 offset1:1
	ds_write2_b32 v97, v14, v15 offset1:1
	ds_write2_b32 v98, v16, v17 offset1:1
	ds_write2_b32 v78, v18, v19 offset1:1
	ds_write2_b32 v80, v20, v21 offset1:1
	ds_write2_b32 v82, v22, v23 offset1:1
	ds_write2_b32 v83, v24, v25 offset1:1
	ds_write2_b32 v84, v26, v27 offset1:1
	ds_write2_b32 v86, v28, v29 offset1:1
	ds_write2_b32 v88, v30, v31 offset1:1
	ds_write2_b32 v90, v32, v33 offset1:1
	s_waitcnt lgkmcnt(0)
	ds_read2_b32 v[2:3], v96 offset1:33
	v_or_b32_e32 v0, s0, v81
	s_waitcnt lgkmcnt(0)
	v_cvt_pk_bf16_f32 v2, v2, v3
	ds_read2_b32 v[4:5], v96 offset0:66 offset1:99
	v_lshl_add_u64 v[8:9], v[58:59], 0, s[46:47]
	v_lshlrev_b32_e32 v0, 9, v0
	s_waitcnt lgkmcnt(0)
	v_cvt_pk_bf16_f32 v3, v4, v5
	ds_read2_b32 v[4:5], v96 offset0:132 offset1:165
	v_lshl_add_u64 v[10:11], v[8:9], 0, v[0:1]
	s_waitcnt lgkmcnt(0)
	v_cvt_pk_bf16_f32 v4, v4, v5
	ds_read2_b32 v[6:7], v96 offset0:198 offset1:231
	s_waitcnt lgkmcnt(0)
	v_cvt_pk_bf16_f32 v5, v6, v7
	global_store_dwordx4 v[10:11], v[2:5], off
	ds_read2_b32 v[2:3], v96 offset0:8 offset1:41
	v_or_b32_e32 v0, s0, v89
	s_waitcnt lgkmcnt(0)
	v_cvt_pk_bf16_f32 v2, v2, v3
	ds_read2_b32 v[4:5], v96 offset0:74 offset1:107
	v_lshlrev_b32_e32 v0, 9, v0
	s_waitcnt lgkmcnt(0)
	v_cvt_pk_bf16_f32 v3, v4, v5
	ds_read2_b32 v[4:5], v96 offset0:140 offset1:173
	v_lshl_add_u64 v[10:11], v[8:9], 0, v[0:1]
	s_waitcnt lgkmcnt(0)
	v_cvt_pk_bf16_f32 v4, v4, v5
	ds_read2_b32 v[6:7], v96 offset0:206 offset1:239
	s_waitcnt lgkmcnt(0)
	v_cvt_pk_bf16_f32 v5, v6, v7
	global_store_dwordx4 v[10:11], v[2:5], off
	ds_read2_b32 v[2:3], v96 offset0:16 offset1:49
	v_or_b32_e32 v0, s0, v93
	s_waitcnt lgkmcnt(0)
	v_cvt_pk_bf16_f32 v2, v2, v3
	ds_read2_b32 v[4:5], v96 offset0:82 offset1:115
	v_lshlrev_b32_e32 v0, 9, v0
	s_waitcnt lgkmcnt(0)
	v_cvt_pk_bf16_f32 v3, v4, v5
	ds_read2_b32 v[4:5], v96 offset0:148 offset1:181
	v_lshl_add_u64 v[10:11], v[8:9], 0, v[0:1]
	s_waitcnt lgkmcnt(0)
	v_cvt_pk_bf16_f32 v4, v4, v5
	ds_read2_b32 v[6:7], v96 offset0:214 offset1:247
	s_waitcnt lgkmcnt(0)
	v_cvt_pk_bf16_f32 v5, v6, v7
	global_store_dwordx4 v[10:11], v[2:5], off
	ds_read2_b32 v[2:3], v96 offset0:24 offset1:57
	v_or_b32_e32 v0, s0, v95
	s_waitcnt lgkmcnt(0)
	v_cvt_pk_bf16_f32 v2, v2, v3
	ds_read2_b32 v[4:5], v96 offset0:90 offset1:123
	s_waitcnt lgkmcnt(0)
	v_cvt_pk_bf16_f32 v3, v4, v5
	ds_read2_b32 v[4:5], v96 offset0:156 offset1:189
	s_waitcnt lgkmcnt(0)
	v_cvt_pk_bf16_f32 v4, v4, v5
	ds_read2_b32 v[6:7], v96 offset0:222 offset1:255
	v_lshlrev_b32_e32 v0, 9, v0
	s_waitcnt lgkmcnt(0)
	v_cvt_pk_bf16_f32 v5, v6, v7
	v_lshl_add_u64 v[6:7], v[8:9], 0, v[0:1]
	global_store_dwordx4 v[6:7], v[2:5], off
	s_waitcnt lgkmcnt(0)

; #define LAS __attribute__((address_space(3)))
; #define LDS_WAIT() asm volatile("s_waitcnt lgkmcnt(0)" ::: "memory")
; __device__ __forceinline__ unsigned pk2(float lo, float hi) { return pg8::cvt_pk_bf16(lo, hi); }
; #define INP(i) ((const float*)ldp(T, (i)))
; #define TRJ(cnt, W, ldn, N, WT, ldk, gain, rbase, rstride) if (r >= 0) { if (r < (cnt)) { tr_item((W), (ldn), (N), (WT), (ldk), (gain), (rbase), (rstride), scr, r, lane); r = -1; } else r -= (cnt); }
; __device__ __forceinline__ void tr_item(const float* W, int ldn, int N, bf16_t* WT, int ldk, const float* gain, int rbase, int rstride, LAS float* scr, int item, int lane) {
;     const int nblk = N / 32, kb = item / nblk, nb = item % nblk, k0 = 64 * kb, n0 = 32 * nb;
;     f32x4 v[8]; float gk[8];
; #pragma unroll
;     for (int i = 0; i < 8; ++i) { const int kk = 8 * i + (lane >> 3); v[i] = *(const f32x4*)(W + (size_t)(k0 + kk) * ldn + n0 + 4 * (lane & 7)); gk[i] = gain ? gain[k0 + kk] : 1.0f; }
; #pragma unroll
;     for (int i = 0; i < 8; ++i) { LAS float* d = scr + (8 * i + (lane >> 3)) * 33 + 4 * (lane & 7); d[0] = v[i].x * gk[i]; d[1] = v[i].y * gk[i]; d[2] = v[i].z * gk[i]; d[3] = v[i].w * gk[i]; }
;     LDS_WAIT(); asm volatile("" ::: "memory");
;     const int c = lane & 7;
; #pragma unroll
;     for (int j = 0; j < 4; ++j) { const int n = (lane >> 3) + 8 * j; const LAS float* s = scr + (8 * c) * 33 + n;
;         u32x4 o; o.x = pk2(s[0 * 33], s[1 * 33]); o.y = pk2(s[2 * 33], s[3 * 33]); o.z = pk2(s[4 * 33], s[5 * 33]); o.w = pk2(s[6 * 33], s[7 * 33]);
;         const int nn = n0 + n, dest = rbase + (nn >> 7) * rstride + (nn & 127);
;         *(u32x4*)(WT + (size_t)dest * ldk + k0 + 8 * c) = o; }
;     LDS_WAIT(); asm volatile("" ::: "memory");
; __device__ __forceinline__ void prep_phase(const PT& T, LAS unsigned char* lds) {
;     ...
;         TRJ(I_GRP, INP(13) + 3 * 65536, 256, 256, Wb + WO_C_GRP + 3 * 65536, 256, nullptr, 0, 128)
.LBB0_501:
	s_andn2_b64 vcc, exec, s[0:1]
	s_cbranch_vccnz .LBB0_503
	v_mov_b32_e32 v0, s63
	ds_read_b64 v[2:3], v0
	s_lshl_b32 s0, s4, 3
	s_lshl_b32 s1, s4, 5
	s_and_b32 s8, s0, 0xc0
	s_and_b32 s0, s1, 0xe0
	s_waitcnt lgkmcnt(0)
	v_readfirstlane_b32 s4, v2
	s_lshl_b32 s1, s0, 2
	v_readfirstlane_b32 s5, v3
	s_add_u32 s4, s4, s1
	v_or_b32_e32 v4, s8, v81
	s_addc_u32 s5, s5, 0
	v_lshlrev_b32_e32 v0, 2, v34
	v_lshl_add_u64 v[2:3], s[4:5], 0, v[0:1]
	v_lshlrev_b32_e32 v0, 10, v4
	v_lshl_add_u64 v[30:31], v[2:3], 0, v[0:1]
	s_mov_b32 s1, 0xc0000
	v_add_co_u32_e32 v2, vcc, s1, v30
	s_mov_b32 s1, 0xc2000
	s_nop 0
	v_addc_co_u32_e32 v3, vcc, 0, v31, vcc
	v_add_co_u32_e32 v6, vcc, s1, v30
	s_mov_b32 s1, 0xc4000
	s_nop 0
	v_addc_co_u32_e32 v7, vcc, 0, v31, vcc
	v_add_co_u32_e32 v10, vcc, s1, v30
	s_mov_b32 s1, 0xc6000
	s_nop 0
	v_addc_co_u32_e32 v11, vcc, 0, v31, vcc
	v_add_co_u32_e32 v14, vcc, s1, v30
	s_mov_b32 s1, 0xc8000
	s_nop 0
	v_addc_co_u32_e32 v15, vcc, 0, v31, vcc
	v_add_co_u32_e32 v18, vcc, s1, v30
	s_mov_b32 s1, 0xca000
	s_nop 0
	v_addc_co_u32_e32 v19, vcc, 0, v31, vcc
	v_add_co_u32_e32 v22, vcc, s1, v30
	global_load_dwordx4 v[2:5], v[2:3], off
	s_nop 0
	global_load_dwordx4 v[6:9], v[6:7], off
	v_addc_co_u32_e32 v23, vcc, 0, v31, vcc
	global_load_dwordx4 v[10:13], v[10:11], off
	s_nop 0
	global_load_dwordx4 v[14:17], v[14:15], off
	s_nop 0
	global_load_dwordx4 v[18:21], v[18:19], off
	s_nop 0
	global_load_dwordx4 v[22:25], v[22:23], off
	s_mov_b32 s1, 0xcc000
	v_add_co_u32_e32 v26, vcc, s1, v30
	s_mov_b32 s1, 0xce000
	s_nop 0
	v_addc_co_u32_e32 v27, vcc, 0, v31, vcc
	global_load_dwordx4 v[26:29], v[26:27], off
	v_add_co_u32_e32 v30, vcc, s1, v30
	v_add_u32_e32 v0, v85, v91
	s_nop 0
	v_addc_co_u32_e32 v31, vcc, 0, v31, vcc
	global_load_dwordx4 v[30:33], v[30:31], off
	v_add_u32_e32 v78, 0x1080, v87
	v_add_u32_e32 v80, 0x1088, v87
	v_add_u32_e32 v82, 0x14a0, v87
	v_add_u32_e32 v83, 0x14a8, v87
	v_add_u32_e32 v84, 0x18c0, v87
	v_add_u32_e32 v86, 0x18c8, v87
	v_add_u32_e32 v88, 0x1ce0, v87
	v_add_u32_e32 v90, 0x1ce8, v87
	v_add_u32_e32 v92, 0x420, v0
	v_add_u32_e32 v94, 0x428, v0
	v_add_u32_e32 v97, 0x840, v0
	v_add_u32_e32 v98, 0x848, v0
	s_lshl_b32 s46, s8, 1
	s_mov_b32 s5, -1
	s_waitcnt vmcnt(0) lgkmcnt(0)
	ds_write2_b32 v87, v2, v3 offset1:1
	ds_write2_b32 v87, v4, v5 offset0:2 offset1:3
	ds_write2_b32 v0, v6, v7 offset1:1
	ds_write2_b32 v0, v8, v9 offset0:2 offset1:3
	ds_write2_b32 v92, v10, v11 offset1:1
	ds_write2_b32 v94, v12, v13 offset1:1
	ds_write2_b32 v97, v14, v15 offset1:1
	ds_write2_b32 v98, v16, v17 offset1:1
	ds_write2_b32 v78, v18, v19 offset1:1
	ds_write2_b32 v80, v20, v21 offset1:1
	ds_write2_b32 v82, v22, v23 offset1:1
	ds_write2_b32 v83, v24, v25 offset1:1
	ds_write2_b32 v84, v26, v27 offset1:1
	ds_write2_b32 v86, v28, v29 offset1:1
	ds_write2_b32 v88, v30, v31 offset1:1
	ds_write2_b32 v90, v32, v33 offset1:1
	s_waitcnt lgkmcnt(0)
	ds_read2_b32 v[2:3], v96 offset1:33
	v_or_b32_e32 v0, s0, v81
	s_waitcnt lgkmcnt(0)
	v_cvt_pk_bf16_f32 v2, v2, v3
	ds_read2_b32 v[4:5], v96 offset0:66 offset1:99
	v_lshl_add_u64 v[8:9], v[60:61], 0, s[46:47]
	v_lshlrev_b32_e32 v0, 9, v0
	s_waitcnt lgkmcnt(0)
	v_cvt_pk_bf16_f32 v3, v4, v5
	ds_read2_b32 v[4:5], v96 offset0:132 offset1:165
	v_lshl_add_u64 v[10:11], v[8:9], 0, v[0:1]
	s_waitcnt lgkmcnt(0)
	v_cvt_pk_bf16_f32 v4, v4, v5
	ds_read2_b32 v[6:7], v96 offset0:198 offset1:231
	s_waitcnt lgkmcnt(0)
	v_cvt_pk_bf16_f32 v5, v6, v7
	global_store_dwordx4 v[10:11], v[2:5], off
	ds_read2_b32 v[2:3], v96 offset0:8 offset1:41
	v_or_b32_e32 v0, s0, v89
	s_waitcnt lgkmcnt(0)
	v_cvt_pk_bf16_f32 v2, v2, v3
	ds_read2_b32 v[4:5], v96 offset0:74 offset1:107
	v_lshlrev_b32_e32 v0, 9, v0
	s_waitcnt lgkmcnt(0)
	v_cvt_pk_bf16_f32 v3, v4, v5
	ds_read2_b32 v[4:5], v96 offset0:140 offset1:173
	v_lshl_add_u64 v[10:11], v[8:9], 0, v[0:1]
	s_waitcnt lgkmcnt(0)
	v_cvt_pk_bf16_f32 v4, v4, v5
	ds_read2_b32 v[6:7], v96 offset0:206 offset1:239
	s_waitcnt lgkmcnt(0)
	v_cvt_pk_bf16_f32 v5, v6, v7
	global_store_dwordx4 v[10:11], v[2:5], off
	ds_read2_b32 v[2:3], v96 offset0:16 offset1:49
	v_or_b32_e32 v0, s0, v93
	s_waitcnt lgkmcnt(0)
	v_cvt_pk_bf16_f32 v2, v2, v3
	ds_read2_b32 v[4:5], v96 offset0:82 offset1:115
	v_lshlrev_b32_e32 v0, 9, v0
	s_waitcnt lgkmcnt(0)
	v_cvt_pk_bf16_f32 v3, v4, v5
	ds_read2_b32 v[4:5], v96 offset0:148 offset1:181
	v_lshl_add_u64 v[10:11], v[8:9], 0, v[0:1]
	s_waitcnt lgkmcnt(0)
	v_cvt_pk_bf16_f32 v4, v4, v5
	ds_read2_b32 v[6:7], v96 offset0:214 offset1:247
	s_waitcnt lgkmcnt(0)
	v_cvt_pk_bf16_f32 v5, v6, v7
	global_store_dwordx4 v[10:11], v[2:5], off
	ds_read2_b32 v[2:3], v96 offset0:24 offset1:57
	v_or_b32_e32 v0, s0, v95
	s_waitcnt lgkmcnt(0)
	v_cvt_pk_bf16_f32 v2, v2, v3
	ds_read2_b32 v[4:5], v96 offset0:90 offset1:123
	s_waitcnt lgkmcnt(0)
	v_cvt_pk_bf16_f32 v3, v4, v5
	ds_read2_b32 v[4:5], v96 offset0:156 offset1:189
	s_waitcnt lgkmcnt(0)
	v_cvt_pk_bf16_f32 v4, v4, v5
	ds_read2_b32 v[6:7], v96 offset0:222 offset1:255
	v_lshlrev_b32_e32 v0, 9, v0
	s_waitcnt lgkmcnt(0)
	v_cvt_pk_bf16_f32 v5, v6, v7
	v_lshl_add_u64 v[6:7], v[8:9], 0, v[0:1]
	global_store_dwordx4 v[6:7], v[2:5], off
	s_waitcnt lgkmcnt(0)

; #define LAS __attribute__((address_space(3)))
; #define INP(i) ((const float*)ldp(T, (i)))
; #define TRJ(cnt, W, ldn, N, WT, ldk, gain, rbase, rstride) if (r >= 0) { if (r < (cnt)) { tr_item((W), (ldn), (N), (WT), (ldk), (gain), (rbase), (rstride), scr, r, lane); r = -1; } else r -= (cnt); }
; __device__ __forceinline__ void tr_item(const float* W, int ldn, int N, bf16_t* WT, int ldk, const float* gain, int rbase, int rstride, LAS float* scr, int item, int lane) {
;     const int nblk = N / 32, kb = item / nblk, nb = item % nblk, k0 = 64 * kb, n0 = 32 * nb;
;     f32x4 v[8]; float gk[8];
; #pragma unroll
;     for (int i = 0; i < 8; ++i) { const int kk = 8 * i + (lane >> 3); v[i] = *(const f32x4*)(W + (size_t)(k0 + kk) * ldn + n0 + 4 * (lane & 7)); gk[i] = gain ? gain[k0 + kk] : 1.0f; }
; #pragma unroll
;     for (int i = 0; i < 8; ++i) { LAS float* d = scr + (8 * i + (lane >> 3)) * 33 + 4 * (lane & 7); d[0] = v[i].x * gk[i]; d[1] = v[i].y * gk[i]; d[2] = v[i].z * gk[i]; d[3] = v[i].w * gk[i]; }
; __device__ __forceinline__ void prep_phase(const PT& T, LAS unsigned char* lds) {
;     ...
;             TRJ(I_UP, INP(16) + (size_t)l * D * FH, FH, FH, Wb + WO_F_GU0 + l * WO_F_STRIDE, D, INP(2) + l * D, 0, 256)
.LBB0_507:
	s_andn2_b64 vcc, exec, s[0:1]
	s_cbranch_vccnz .LBB0_525
	v_mov_b32_e32 v0, s62
	s_and_b32 s0, s4, 0xffff
	ds_read_b64 v[2:3], v0
	s_mul_i32 s0, s0, 0xba2f
	s_lshr_b32 s8, s0, 16
	s_lshr_b32 s0, s0, 22
	s_mulk_i32 s0, 0x58
	s_sub_i32 s0, s4, s0
	s_and_b32 s20, s0, 0xffff
	s_waitcnt lgkmcnt(0)
	v_readfirstlane_b32 s5, v2
	s_and_b32 s19, s8, 0xffc0
	s_lshl_b32 s0, s20, 7
	v_mov_b32_e32 v0, s12
	v_readfirstlane_b32 s1, v3
	v_or_b32_e32 v8, s19, v81
	s_add_u32 s0, s5, s0
	ds_read_b64 v[6:7], v0
	s_addc_u32 s1, s1, 0
	v_lshlrev_b32_e32 v0, 2, v34
	v_mul_u32_u24_e32 v14, 0xb00, v8
	v_lshl_add_u64 v[30:31], s[0:1], 0, v[0:1]
	v_lshlrev_b32_e32 v0, 2, v14
	v_lshl_add_u64 v[10:11], v[30:31], 0, v[0:1]
	global_load_dwordx4 v[2:5], v[10:11], off
	s_waitcnt lgkmcnt(0)
	v_readfirstlane_b32 s9, v7
	v_readfirstlane_b32 s8, v6
	s_cmp_lg_u64 s[8:9], 0
	s_cselect_b64 s[4:5], -1, 0
	s_cmp_eq_u64 s[8:9], 0
	v_mov_b32_e32 v78, 1.0
	v_lshlrev_b32_e32 v82, 2, v8
	v_mov_b32_e32 v80, 1.0
	s_cbranch_scc1 .LBB0_510
	v_mov_b32_e32 v83, v1
	v_lshl_add_u64 v[6:7], s[8:9], 0, v[82:83]
	global_load_dword v80, v[6:7], off
.LBB0_510:
	v_add_co_u32_e32 v6, vcc, 0x16000, v10
	v_cndmask_b32_e64 v0, 0, 1, s[4:5]
	s_nop 0
	v_addc_co_u32_e32 v7, vcc, 0, v11, vcc
	global_load_dwordx4 v[6:9], v[6:7], off
	v_cmp_ne_u32_e64 s[0:1], 1, v0
	s_andn2_b64 vcc, exec, s[4:5]
	s_cbranch_vccnz .LBB0_512
	v_mov_b32_e32 v83, v1
	v_lshl_add_u64 v[12:13], s[8:9], 0, v[82:83]
	global_load_dword v78, v[12:13], off offset:32
.LBB0_512:
	v_lshl_add_u64 v[10:11], v[10:11], 0, s[82:83]
	v_add_co_u32_e32 v10, vcc, 0x16000, v10
	v_mov_b32_e32 v84, 1.0
	s_nop 0
	v_addc_co_u32_e32 v11, vcc, 0, v11, vcc
	global_load_dwordx4 v[10:13], v[10:11], off
	s_and_b64 vcc, exec, s[0:1]
	v_mov_b32_e32 v86, 1.0
	s_cbranch_vccnz .LBB0_514
	v_mov_b32_e32 v83, v1
	v_lshl_add_u64 v[16:17], s[8:9], 0, v[82:83]
	global_load_dword v86, v[16:17], off offset:64
.LBB0_514:
	v_add_u32_e32 v18, 0x10800, v14
	v_lshlrev_b32_e32 v0, 2, v18
	v_lshl_add_u64 v[14:15], v[30:31], 0, v[0:1]
	global_load_dwordx4 v[14:17], v[14:15], off
	s_and_b64 vcc, exec, s[0:1]
	s_cbranch_vccnz .LBB0_516
	v_mov_b32_e32 v83, v1
	v_lshl_add_u64 v[20:21], s[8:9], 0, v[82:83]
	global_load_dword v84, v[20:21], off offset:96
.LBB0_516:
	v_add_u32_e32 v22, 0x5800, v18
	v_lshlrev_b32_e32 v0, 2, v22
	v_lshl_add_u64 v[18:19], v[30:31], 0, v[0:1]
	global_load_dwordx4 v[18:21], v[18:19], off
	v_mov_b32_e32 v88, 1.0
	s_and_b64 vcc, exec, s[0:1]
	v_mov_b32_e32 v90, 1.0
	s_cbranch_vccnz .LBB0_518
	v_mov_b32_e32 v83, v1
	v_lshl_add_u64 v[24:25], s[8:9], 0, v[82:83]
	global_load_dword v90, v[24:25], off offset:128
.LBB0_518:
	v_add_u32_e32 v0, 0x5800, v22
	v_lshl_add_u64 v[22:23], v[0:1], 2, v[30:31]
	global_load_dwordx4 v[22:25], v[22:23], off
	s_and_b64 vcc, exec, s[0:1]
	s_cbranch_vccnz .LBB0_520
	v_mov_b32_e32 v83, v1
	v_lshl_add_u64 v[26:27], s[8:9], 0, v[82:83]
	global_load_dword v88, v[26:27], off offset:160
.LBB0_520:
	v_add_u32_e32 v0, 0x5800, v0
	v_lshl_add_u64 v[26:27], v[0:1], 2, v[30:31]
	global_load_dwordx4 v[26:29], v[26:27], off
	v_mov_b32_e32 v92, 1.0
	s_and_b64 vcc, exec, s[0:1]
	v_mov_b32_e32 v94, 1.0
	s_cbranch_vccnz .LBB0_522
	v_mov_b32_e32 v83, v1
	v_lshl_add_u64 v[32:33], s[8:9], 0, v[82:83]
	global_load_dword v94, v[32:33], off offset:192
.LBB0_522:
	v_add_u32_e32 v0, 0x5800, v0
	v_lshl_add_u64 v[30:31], v[0:1], 2, v[30:31]
	global_load_dwordx4 v[30:33], v[30:31], off
	s_and_b64 vcc, exec, s[0:1]
	s_cbranch_vccnz .LBB0_524
	v_mov_b32_e32 v83, v1
	v_lshl_add_u64 v[82:83], s[8:9], 0, v[82:83]
	global_load_dword v92, v[82:83], off offset:224
; #define LAS __attribute__((address_space(3)))
; #define LDS_WAIT() asm volatile("s_waitcnt lgkmcnt(0)" ::: "memory")
; __device__ __forceinline__ unsigned pk2(float lo, float hi) { return pg8::cvt_pk_bf16(lo, hi); }
; __device__ __forceinline__ void tr_item(const float* W, int ldn, int N, bf16_t* WT, int ldk, const float* gain, int rbase, int rstride, LAS float* scr, int item, int lane) {
;     ...
;     for (int i = 0; i < 8; ++i) { LAS float* d = scr + (8 * i + (lane >> 3)) * 33 + 4 * (lane & 7); d[0] = v[i].x * gk[i]; d[1] = v[i].y * gk[i]; d[2] = v[i].z * gk[i]; d[3] = v[i].w * gk[i]; }
;     LDS_WAIT(); asm volatile("" ::: "memory");
;     const int c = lane & 7;
; #pragma unroll
;     for (int j = 0; j < 4; ++j) { const int n = (lane >> 3) + 8 * j; const LAS float* s = scr + (8 * c) * 33 + n;
;         u32x4 o; o.x = pk2(s[0 * 33], s[1 * 33]); o.y = pk2(s[2 * 33], s[3 * 33]); o.z = pk2(s[4 * 33], s[5 * 33]); o.w = pk2(s[6 * 33], s[7 * 33]);
;         const int nn = n0 + n, dest = rbase + (nn >> 7) * rstride + (nn & 127);
;         *(u32x4*)(WT + (size_t)dest * ldk + k0 + 8 * c) = o; }
;     LDS_WAIT(); asm volatile("" ::: "memory");
.LBB0_524:
	s_waitcnt vmcnt(0) lgkmcnt(0)
	v_pk_mul_f32 v[2:3], v[2:3], v[80:81] op_sel_hi:[1,0]
	ds_write2_b32 v87, v2, v3 offset1:1
	v_pk_mul_f32 v[2:3], v[4:5], v[80:81] op_sel_hi:[1,0]
	ds_write2_b32 v87, v2, v3 offset0:2 offset1:3
	v_pk_mul_f32 v[2:3], v[6:7], v[78:79] op_sel_hi:[1,0]
	v_add_u32_e32 v0, v85, v91
	ds_write2_b32 v0, v2, v3 offset1:1
	v_pk_mul_f32 v[2:3], v[8:9], v[78:79] op_sel_hi:[1,0]
	ds_write2_b32 v0, v2, v3 offset0:2 offset1:3
	v_pk_mul_f32 v[2:3], v[10:11], v[86:87] op_sel_hi:[1,0]
	v_add_u32_e32 v4, 0x420, v0
	ds_write2_b32 v4, v2, v3 offset1:1
	v_pk_mul_f32 v[2:3], v[12:13], v[86:87] op_sel_hi:[1,0]
	v_add_u32_e32 v4, 0x428, v0
	ds_write2_b32 v4, v2, v3 offset1:1
	v_pk_mul_f32 v[2:3], v[14:15], v[84:85] op_sel_hi:[1,0]
	v_add_u32_e32 v4, 0x840, v0
	ds_write2_b32 v4, v2, v3 offset1:1
	v_pk_mul_f32 v[2:3], v[16:17], v[84:85] op_sel_hi:[1,0]
	v_add_u32_e32 v0, 0x848, v0
	ds_write2_b32 v0, v2, v3 offset1:1
	v_pk_mul_f32 v[2:3], v[18:19], v[90:91] op_sel_hi:[1,0]
	v_add_u32_e32 v0, 0x1080, v87
	ds_write2_b32 v0, v2, v3 offset1:1
	v_pk_mul_f32 v[2:3], v[20:21], v[90:91] op_sel_hi:[1,0]
	v_add_u32_e32 v0, 0x1088, v87
	ds_write2_b32 v0, v2, v3 offset1:1
	v_pk_mul_f32 v[2:3], v[22:23], v[88:89] op_sel_hi:[1,0]
	v_add_u32_e32 v0, 0x14a0, v87
	ds_write2_b32 v0, v2, v3 offset1:1
	v_pk_mul_f32 v[2:3], v[24:25], v[88:89] op_sel_hi:[1,0]
	v_add_u32_e32 v0, 0x14a8, v87
	ds_write2_b32 v0, v2, v3 offset1:1
	v_pk_mul_f32 v[2:3], v[26:27], v[94:95] op_sel_hi:[1,0]
	v_add_u32_e32 v0, 0x18c0, v87
	ds_write2_b32 v0, v2, v3 offset1:1
	v_pk_mul_f32 v[2:3], v[28:29], v[94:95] op_sel_hi:[1,0]
	v_add_u32_e32 v0, 0x18c8, v87
	ds_write2_b32 v0, v2, v3 offset1:1
	v_pk_mul_f32 v[2:3], v[30:31], v[92:93] op_sel_hi:[1,0]
	v_add_u32_e32 v0, 0x1ce0, v87
	ds_write2_b32 v0, v2, v3 offset1:1
	v_pk_mul_f32 v[2:3], v[32:33], v[92:93] op_sel_hi:[1,0]
	v_add_u32_e32 v0, 0x1ce8, v87
	ds_write2_b32 v0, v2, v3 offset1:1
	s_waitcnt lgkmcnt(0)
	s_lshl_b32 s0, s20, 5
	s_lshl_b32 s1, s20, 6
	ds_read2_b32 v[2:3], v96 offset1:33
	s_and_b32 s1, s1, 0x1f00
	s_and_b32 s0, s0, 0x60
	s_waitcnt lgkmcnt(0)
	v_cvt_pk_bf16_f32 v2, v2, v3
	ds_read2_b32 v[4:5], v96 offset0:66 offset1:99
	s_or_b32 s0, s1, s0
	s_and_b32 s1, 0xffff, s19
	s_waitcnt lgkmcnt(0)
	v_cvt_pk_bf16_f32 v3, v4, v5
	ds_read2_b32 v[4:5], v96 offset0:132 offset1:165
	s_lshl_b32 s46, s1, 1
	v_or_b32_e32 v0, s0, v81
	s_waitcnt lgkmcnt(0)
	v_cvt_pk_bf16_f32 v4, v4, v5
	ds_read2_b32 v[6:7], v96 offset0:198 offset1:231
	v_lshl_add_u64 v[8:9], v[62:63], 0, s[46:47]
	v_lshlrev_b32_e32 v0, 11, v0
	s_waitcnt lgkmcnt(0)
	v_cvt_pk_bf16_f32 v5, v6, v7
	v_lshl_add_u64 v[6:7], v[8:9], 0, v[0:1]
	global_store_dwordx4 v[6:7], v[2:5], off
	ds_read2_b32 v[2:3], v96 offset0:8 offset1:41
	v_or_b32_e32 v0, s0, v89
	s_waitcnt lgkmcnt(0)
	v_cvt_pk_bf16_f32 v2, v2, v3
	ds_read2_b32 v[4:5], v96 offset0:74 offset1:107
	s_waitcnt lgkmcnt(0)
	v_cvt_pk_bf16_f32 v3, v4, v5
	ds_read2_b32 v[4:5], v96 offset0:140 offset1:173
	s_waitcnt lgkmcnt(0)
	v_cvt_pk_bf16_f32 v4, v4, v5
	ds_read2_b32 v[6:7], v96 offset0:206 offset1:239
	v_lshlrev_b32_e32 v0, 11, v0
	s_waitcnt lgkmcnt(0)
	v_cvt_pk_bf16_f32 v5, v6, v7
	v_lshl_add_u64 v[6:7], v[8:9], 0, v[0:1]
	global_store_dwordx4 v[6:7], v[2:5], off
	ds_read2_b32 v[2:3], v96 offset0:16 offset1:49
	v_or_b32_e32 v0, s0, v93
	s_waitcnt lgkmcnt(0)
	v_cvt_pk_bf16_f32 v2, v2, v3
	ds_read2_b32 v[4:5], v96 offset0:82 offset1:115
	s_waitcnt lgkmcnt(0)
	v_cvt_pk_bf16_f32 v3, v4, v5
	ds_read2_b32 v[4:5], v96 offset0:148 offset1:181
	s_waitcnt lgkmcnt(0)
	v_cvt_pk_bf16_f32 v4, v4, v5
	ds_read2_b32 v[6:7], v96 offset0:214 offset1:247
	v_lshlrev_b32_e32 v0, 11, v0
	s_waitcnt lgkmcnt(0)
	v_cvt_pk_bf16_f32 v5, v6, v7
	v_lshl_add_u64 v[6:7], v[8:9], 0, v[0:1]
	global_store_dwordx4 v[6:7], v[2:5], off
	ds_read2_b32 v[2:3], v96 offset0:24 offset1:57
	v_or_b32_e32 v0, s0, v95
	s_waitcnt lgkmcnt(0)
	v_cvt_pk_bf16_f32 v2, v2, v3
	ds_read2_b32 v[4:5], v96 offset0:90 offset1:123
	s_waitcnt lgkmcnt(0)
	v_cvt_pk_bf16_f32 v3, v4, v5
	ds_read2_b32 v[4:5], v96 offset0:156 offset1:189
	s_waitcnt lgkmcnt(0)
	v_cvt_pk_bf16_f32 v4, v4, v5
	ds_read2_b32 v[6:7], v96 offset0:222 offset1:255
	v_lshlrev_b32_e32 v0, 11, v0
	s_waitcnt lgkmcnt(0)
	v_cvt_pk_bf16_f32 v5, v6, v7
	v_lshl_add_u64 v[6:7], v[8:9], 0, v[0:1]
	global_store_dwordx4 v[6:7], v[2:5], off
	s_waitcnt lgkmcnt(0)
	s_mov_b32 s5, -1

; #define INP(i) ((const float*)ldp(T, (i)))
; #define TRJ(cnt, W, ldn, N, WT, ldk, gain, rbase, rstride) if (r >= 0) { if (r < (cnt)) { tr_item((W), (ldn), (N), (WT), (ldk), (gain), (rbase), (rstride), scr, r, lane); r = -1; } else r -= (cnt); }
; __device__ __forceinline__ void tr_item(const float* W, int ldn, int N, bf16_t* WT, int ldk, const float* gain, int rbase, int rstride, LAS float* scr, int item, int lane) {
;     const int nblk = N / 32, kb = item / nblk, nb = item % nblk, k0 = 64 * kb, n0 = 32 * nb;
;     f32x4 v[8]; float gk[8];
; #pragma unroll
;     for (int i = 0; i < 8; ++i) { const int kk = 8 * i + (lane >> 3); v[i] = *(const f32x4*)(W + (size_t)(k0 + kk) * ldn + n0 + 4 * (lane & 7)); gk[i] = gain ? gain[k0 + kk] : 1.0f; }
; __device__ __forceinline__ void prep_phase(const PT& T, LAS unsigned char* lds) {
;     ...
;             TRJ(I_UP, INP(17) + (size_t)l * D * FH, FH, FH, Wb + WO_F_GU0 + l * WO_F_STRIDE, D, INP(2) + l * D, 128, 256)
.LBB0_529:
	s_andn2_b64 vcc, exec, s[0:1]
	s_cbranch_vccnz .LBB0_547
	v_mov_b32_e32 v0, s13
	s_and_b32 s0, s4, 0xffff
	ds_read_b64 v[2:3], v0
	s_mul_i32 s0, s0, 0xba2f
	s_lshr_b32 s8, s0, 16
	s_lshr_b32 s0, s0, 22
	s_mulk_i32 s0, 0x58
	s_sub_i32 s0, s4, s0
	s_and_b32 s20, s0, 0xffff
	s_waitcnt lgkmcnt(0)
	v_readfirstlane_b32 s5, v2
	s_and_b32 s19, s8, 0xffc0
	s_lshl_b32 s0, s20, 7
	v_mov_b32_e32 v0, s12
	v_readfirstlane_b32 s1, v3
	v_or_b32_e32 v8, s19, v81
	s_add_u32 s0, s5, s0
	ds_read_b64 v[6:7], v0
	s_addc_u32 s1, s1, 0
	v_lshlrev_b32_e32 v0, 2, v34
	v_mul_u32_u24_e32 v14, 0xb00, v8
	v_lshl_add_u64 v[30:31], s[0:1], 0, v[0:1]
	v_lshlrev_b32_e32 v0, 2, v14
	v_lshl_add_u64 v[10:11], v[30:31], 0, v[0:1]
	global_load_dwordx4 v[2:5], v[10:11], off
	s_waitcnt lgkmcnt(0)
	v_readfirstlane_b32 s9, v7
	v_readfirstlane_b32 s8, v6
	s_cmp_lg_u64 s[8:9], 0
	s_cselect_b64 s[4:5], -1, 0
	s_cmp_eq_u64 s[8:9], 0
	v_mov_b32_e32 v78, 1.0
	v_lshlrev_b32_e32 v82, 2, v8
	v_mov_b32_e32 v80, 1.0
	s_cbranch_scc1 .LBB0_532
	v_mov_b32_e32 v83, v1
	v_lshl_add_u64 v[6:7], s[8:9], 0, v[82:83]
	global_load_dword v80, v[6:7], off

; #define LAS __attribute__((address_space(3)))
; #define LDS_WAIT() asm volatile("s_waitcnt lgkmcnt(0)" ::: "memory")
; __device__ __forceinline__ unsigned pk2(float lo, float hi) { return pg8::cvt_pk_bf16(lo, hi); }
; __device__ __forceinline__ void tr_item(const float* W, int ldn, int N, bf16_t* WT, int ldk, const float* gain, int rbase, int rstride, LAS float* scr, int item, int lane) {
;     ...
;     for (int i = 0; i < 8; ++i) { LAS float* d = scr + (8 * i + (lane >> 3)) * 33 + 4 * (lane & 7); d[0] = v[i].x * gk[i]; d[1] = v[i].y * gk[i]; d[2] = v[i].z * gk[i]; d[3] = v[i].w * gk[i]; }
;     LDS_WAIT(); asm volatile("" ::: "memory");
;     const int c = lane & 7;
; #pragma unroll
;     for (int j = 0; j < 4; ++j) { const int n = (lane >> 3) + 8 * j; const LAS float* s = scr + (8 * c) * 33 + n;
;         u32x4 o; o.x = pk2(s[0 * 33], s[1 * 33]); o.y = pk2(s[2 * 33], s[3 * 33]); o.z = pk2(s[4 * 33], s[5 * 33]); o.w = pk2(s[6 * 33], s[7 * 33]);
;         const int nn = n0 + n, dest = rbase + (nn >> 7) * rstride + (nn & 127);
;         *(u32x4*)(WT + (size_t)dest * ldk + k0 + 8 * c) = o; }
;     LDS_WAIT(); asm volatile("" ::: "memory");
.LBB0_546:
	s_waitcnt vmcnt(0) lgkmcnt(0)
	v_pk_mul_f32 v[2:3], v[2:3], v[80:81] op_sel_hi:[1,0]
	ds_write2_b32 v87, v2, v3 offset1:1
	v_pk_mul_f32 v[2:3], v[4:5], v[80:81] op_sel_hi:[1,0]
	ds_write2_b32 v87, v2, v3 offset0:2 offset1:3
	v_pk_mul_f32 v[2:3], v[6:7], v[78:79] op_sel_hi:[1,0]
	v_add_u32_e32 v0, v85, v91
	ds_write2_b32 v0, v2, v3 offset1:1
	v_pk_mul_f32 v[2:3], v[8:9], v[78:79] op_sel_hi:[1,0]
	ds_write2_b32 v0, v2, v3 offset0:2 offset1:3
	v_pk_mul_f32 v[2:3], v[10:11], v[86:87] op_sel_hi:[1,0]
	v_add_u32_e32 v4, 0x420, v0
	ds_write2_b32 v4, v2, v3 offset1:1
	v_pk_mul_f32 v[2:3], v[12:13], v[86:87] op_sel_hi:[1,0]
	v_add_u32_e32 v4, 0x428, v0
	ds_write2_b32 v4, v2, v3 offset1:1
	v_pk_mul_f32 v[2:3], v[14:15], v[84:85] op_sel_hi:[1,0]
	v_add_u32_e32 v4, 0x840, v0
	ds_write2_b32 v4, v2, v3 offset1:1
	v_pk_mul_f32 v[2:3], v[16:17], v[84:85] op_sel_hi:[1,0]
	v_add_u32_e32 v0, 0x848, v0
	ds_write2_b32 v0, v2, v3 offset1:1
	v_pk_mul_f32 v[2:3], v[18:19], v[90:91] op_sel_hi:[1,0]
	v_add_u32_e32 v0, 0x1080, v87
	ds_write2_b32 v0, v2, v3 offset1:1
	v_pk_mul_f32 v[2:3], v[20:21], v[90:91] op_sel_hi:[1,0]
	v_add_u32_e32 v0, 0x1088, v87
	ds_write2_b32 v0, v2, v3 offset1:1
	v_pk_mul_f32 v[2:3], v[22:23], v[88:89] op_sel_hi:[1,0]
	v_add_u32_e32 v0, 0x14a0, v87
	ds_write2_b32 v0, v2, v3 offset1:1
	v_pk_mul_f32 v[2:3], v[24:25], v[88:89] op_sel_hi:[1,0]
	v_add_u32_e32 v0, 0x14a8, v87
	ds_write2_b32 v0, v2, v3 offset1:1
	v_pk_mul_f32 v[2:3], v[26:27], v[94:95] op_sel_hi:[1,0]
	v_add_u32_e32 v0, 0x18c0, v87
	ds_write2_b32 v0, v2, v3 offset1:1
	v_pk_mul_f32 v[2:3], v[28:29], v[94:95] op_sel_hi:[1,0]
	v_add_u32_e32 v0, 0x18c8, v87
	ds_write2_b32 v0, v2, v3 offset1:1
	v_pk_mul_f32 v[2:3], v[30:31], v[92:93] op_sel_hi:[1,0]
	v_add_u32_e32 v0, 0x1ce0, v87
	ds_write2_b32 v0, v2, v3 offset1:1
	v_pk_mul_f32 v[2:3], v[32:33], v[92:93] op_sel_hi:[1,0]
	v_add_u32_e32 v0, 0x1ce8, v87
	ds_write2_b32 v0, v2, v3 offset1:1
	s_waitcnt lgkmcnt(0)
	s_lshl_b32 s0, s20, 5
	s_lshl_b32 s1, s20, 6
	s_and_b32 s1, s1, 0x1f00
	s_and_b32 s0, s0, 0x60
	ds_read2_b32 v[2:3], v96 offset1:33
	s_or_b32 s0, s1, s0
	s_waitcnt lgkmcnt(0)
	v_cvt_pk_bf16_f32 v2, v2, v3
	ds_read2_b32 v[4:5], v96 offset0:66 offset1:99
	s_bitset1_b32 s0, 7
	s_and_b32 s1, 0xffff, s19
	s_waitcnt lgkmcnt(0)
	v_cvt_pk_bf16_f32 v3, v4, v5
	ds_read2_b32 v[4:5], v96 offset0:132 offset1:165
	s_lshl_b32 s46, s1, 1
	v_or_b32_e32 v0, s0, v81
	s_waitcnt lgkmcnt(0)
	v_cvt_pk_bf16_f32 v4, v4, v5
	ds_read2_b32 v[6:7], v96 offset0:198 offset1:231
	v_lshl_add_u64 v[8:9], v[62:63], 0, s[46:47]
	v_lshlrev_b32_e32 v0, 11, v0
	s_waitcnt lgkmcnt(0)
	v_cvt_pk_bf16_f32 v5, v6, v7
	v_lshl_add_u64 v[6:7], v[8:9], 0, v[0:1]
	global_store_dwordx4 v[6:7], v[2:5], off
	ds_read2_b32 v[2:3], v96 offset0:8 offset1:41
	v_or_b32_e32 v0, s0, v89
	s_waitcnt lgkmcnt(0)
	v_cvt_pk_bf16_f32 v2, v2, v3
	ds_read2_b32 v[4:5], v96 offset0:74 offset1:107
	s_waitcnt lgkmcnt(0)
	v_cvt_pk_bf16_f32 v3, v4, v5
	ds_read2_b32 v[4:5], v96 offset0:140 offset1:173
	s_waitcnt lgkmcnt(0)
	v_cvt_pk_bf16_f32 v4, v4, v5
	ds_read2_b32 v[6:7], v96 offset0:206 offset1:239
	v_lshlrev_b32_e32 v0, 11, v0
	s_waitcnt lgkmcnt(0)
	v_cvt_pk_bf16_f32 v5, v6, v7
	v_lshl_add_u64 v[6:7], v[8:9], 0, v[0:1]
	global_store_dwordx4 v[6:7], v[2:5], off
	ds_read2_b32 v[2:3], v96 offset0:16 offset1:49
	v_or_b32_e32 v0, s0, v93
	s_waitcnt lgkmcnt(0)
	v_cvt_pk_bf16_f32 v2, v2, v3
	ds_read2_b32 v[4:5], v96 offset0:82 offset1:115
	s_waitcnt lgkmcnt(0)
	v_cvt_pk_bf16_f32 v3, v4, v5
	ds_read2_b32 v[4:5], v96 offset0:148 offset1:181
	s_waitcnt lgkmcnt(0)
	v_cvt_pk_bf16_f32 v4, v4, v5
	ds_read2_b32 v[6:7], v96 offset0:214 offset1:247
	v_lshlrev_b32_e32 v0, 11, v0
	s_waitcnt lgkmcnt(0)
	v_cvt_pk_bf16_f32 v5, v6, v7
	v_lshl_add_u64 v[6:7], v[8:9], 0, v[0:1]
	global_store_dwordx4 v[6:7], v[2:5], off
	ds_read2_b32 v[2:3], v96 offset0:24 offset1:57
	v_or_b32_e32 v0, s0, v95
	s_waitcnt lgkmcnt(0)
	v_cvt_pk_bf16_f32 v2, v2, v3
	ds_read2_b32 v[4:5], v96 offset0:90 offset1:123
	s_waitcnt lgkmcnt(0)
	v_cvt_pk_bf16_f32 v3, v4, v5
	ds_read2_b32 v[4:5], v96 offset0:156 offset1:189
	s_waitcnt lgkmcnt(0)
	v_cvt_pk_bf16_f32 v4, v4, v5
	ds_read2_b32 v[6:7], v96 offset0:222 offset1:255
	v_lshlrev_b32_e32 v0, 11, v0
	s_waitcnt lgkmcnt(0)
	v_cvt_pk_bf16_f32 v5, v6, v7
	v_lshl_add_u64 v[6:7], v[8:9], 0, v[0:1]
	global_store_dwordx4 v[6:7], v[2:5], off
	s_waitcnt lgkmcnt(0)
	s_mov_b32 s5, -1

; #define LAS __attribute__((address_space(3)))
; #define LDS_WAIT() asm volatile("s_waitcnt lgkmcnt(0)" ::: "memory")
; __device__ __forceinline__ unsigned pk2(float lo, float hi) { return pg8::cvt_pk_bf16(lo, hi); }
; #define INP(i) ((const float*)ldp(T, (i)))
; #define TRJ(cnt, W, ldn, N, WT, ldk, gain, rbase, rstride) if (r >= 0) { if (r < (cnt)) { tr_item((W), (ldn), (N), (WT), (ldk), (gain), (rbase), (rstride), scr, r, lane); r = -1; } else r -= (cnt); }
; __device__ __forceinline__ void tr_item(const float* W, int ldn, int N, bf16_t* WT, int ldk, const float* gain, int rbase, int rstride, LAS float* scr, int item, int lane) {
;     const int nblk = N / 32, kb = item / nblk, nb = item % nblk, k0 = 64 * kb, n0 = 32 * nb;
;     f32x4 v[8]; float gk[8];
; #pragma unroll
;     for (int i = 0; i < 8; ++i) { const int kk = 8 * i + (lane >> 3); v[i] = *(const f32x4*)(W + (size_t)(k0 + kk) * ldn + n0 + 4 * (lane & 7)); gk[i] = gain ? gain[k0 + kk] : 1.0f; }
; #pragma unroll
;     for (int i = 0; i < 8; ++i) { LAS float* d = scr + (8 * i + (lane >> 3)) * 33 + 4 * (lane & 7); d[0] = v[i].x * gk[i]; d[1] = v[i].y * gk[i]; d[2] = v[i].z * gk[i]; d[3] = v[i].w * gk[i]; }
;     LDS_WAIT(); asm volatile("" ::: "memory");
;     const int c = lane & 7;
; #pragma unroll
;     for (int j = 0; j < 4; ++j) { const int n = (lane >> 3) + 8 * j; const LAS float* s = scr + (8 * c) * 33 + n;
;         u32x4 o; o.x = pk2(s[0 * 33], s[1 * 33]); o.y = pk2(s[2 * 33], s[3 * 33]); o.z = pk2(s[4 * 33], s[5 * 33]); o.w = pk2(s[6 * 33], s[7 * 33]);
;         const int nn = n0 + n, dest = rbase + (nn >> 7) * rstride + (nn & 127);
;         *(u32x4*)(WT + (size_t)dest * ldk + k0 + 8 * c) = o; }
;     LDS_WAIT(); asm volatile("" ::: "memory");
; __device__ __forceinline__ void prep_phase(const PT& T, LAS unsigned char* lds) {
;     ...
;             TRJ(I_DN, INP(18) + (size_t)l * D * FH, D, D, Wb + WO_F_D0 + l * WO_F_STRIDE, FH, nullptr, 0, 128)
.LBB0_551:
	s_andn2_b64 vcc, exec, s[0:1]
	s_cbranch_vccnz .LBB0_553
	v_mov_b32_e32 v0, s40
	ds_read_b64 v[2:3], v0
	s_lshl_b32 s0, s4, 1
	s_lshl_b32 s1, s4, 5
	s_and_b32 s8, s0, 0xfc0
	s_and_b32 s0, s1, 0x3e0
	s_waitcnt lgkmcnt(0)
	v_readfirstlane_b32 s4, v2
	s_lshl_b32 s1, s0, 2
	v_readfirstlane_b32 s5, v3
	s_add_u32 s4, s4, s1
	v_or_b32_e32 v4, s8, v81
	s_addc_u32 s5, s5, 0
	v_lshlrev_b32_e32 v0, 2, v34
	v_lshl_add_u64 v[2:3], s[4:5], 0, v[0:1]
	v_lshlrev_b32_e32 v0, 12, v4
	v_lshl_add_u64 v[30:31], v[2:3], 0, v[0:1]
	v_add_co_u32_e32 v6, vcc, s77, v30
	v_add_u32_e32 v0, v85, v91
	s_nop 0
	v_addc_co_u32_e32 v7, vcc, 0, v31, vcc
	v_add_co_u32_e32 v10, vcc, s24, v30
	global_load_dwordx4 v[2:5], v[30:31], off
	s_nop 0
	global_load_dwordx4 v[6:9], v[6:7], off
	v_addc_co_u32_e32 v11, vcc, 0, v31, vcc
	v_add_co_u32_e32 v14, vcc, s71, v30
	v_add_u32_e32 v78, 0x1080, v87
	s_nop 0
	v_addc_co_u32_e32 v15, vcc, 0, v31, vcc
	v_add_co_u32_e32 v18, vcc, s27, v30
	global_load_dwordx4 v[10:13], v[10:11], off
	s_nop 0
	global_load_dwordx4 v[14:17], v[14:15], off
	v_addc_co_u32_e32 v19, vcc, 0, v31, vcc
	v_add_co_u32_e32 v22, vcc, s28, v30
	v_add_u32_e32 v80, 0x1088, v87
	s_nop 0
	v_addc_co_u32_e32 v23, vcc, 0, v31, vcc
	global_load_dwordx4 v[18:21], v[18:19], off
	s_nop 0
	global_load_dwordx4 v[22:25], v[22:23], off
	v_add_co_u32_e32 v26, vcc, s81, v30
	v_add_u32_e32 v82, 0x14a0, v87
	s_nop 0
	v_addc_co_u32_e32 v27, vcc, 0, v31, vcc
	global_load_dwordx4 v[26:29], v[26:27], off
	v_add_co_u32_e32 v30, vcc, s29, v30
	v_add_u32_e32 v83, 0x14a8, v87
	s_nop 0
	v_addc_co_u32_e32 v31, vcc, 0, v31, vcc
	global_load_dwordx4 v[30:33], v[30:31], off
	v_add_u32_e32 v84, 0x18c0, v87
	v_add_u32_e32 v86, 0x18c8, v87
	v_add_u32_e32 v88, 0x1ce0, v87
	v_add_u32_e32 v90, 0x1ce8, v87
	v_add_u32_e32 v92, 0x420, v0
	v_add_u32_e32 v94, 0x428, v0
	v_add_u32_e32 v97, 0x840, v0
	v_add_u32_e32 v98, 0x848, v0
	s_lshl_b32 s46, s8, 1
	s_mov_b32 s5, -1
	s_waitcnt vmcnt(0) lgkmcnt(0)
	ds_write2_b32 v87, v2, v3 offset1:1
	ds_write2_b32 v87, v4, v5 offset0:2 offset1:3
	ds_write2_b32 v0, v6, v7 offset1:1
	ds_write2_b32 v0, v8, v9 offset0:2 offset1:3
	ds_write2_b32 v92, v10, v11 offset1:1
	ds_write2_b32 v94, v12, v13 offset1:1
	ds_write2_b32 v97, v14, v15 offset1:1
	ds_write2_b32 v98, v16, v17 offset1:1
	ds_write2_b32 v78, v18, v19 offset1:1
	ds_write2_b32 v80, v20, v21 offset1:1
	ds_write2_b32 v82, v22, v23 offset1:1
	ds_write2_b32 v83, v24, v25 offset1:1
	ds_write2_b32 v84, v26, v27 offset1:1
	ds_write2_b32 v86, v28, v29 offset1:1
	ds_write2_b32 v88, v30, v31 offset1:1
	ds_write2_b32 v90, v32, v33 offset1:1
	s_waitcnt lgkmcnt(0)
	v_or_b32_e32 v0, s0, v81
	ds_read2_b32 v[2:3], v96 offset1:33
	v_mul_u32_u24_e32 v0, 0xb00, v0
	s_waitcnt lgkmcnt(0)
	v_cvt_pk_bf16_f32 v2, v2, v3
	ds_read2_b32 v[4:5], v96 offset0:66 offset1:99
	v_lshl_add_u64 v[8:9], v[64:65], 0, s[46:47]
	v_lshlrev_b32_e32 v0, 1, v0
	s_waitcnt lgkmcnt(0)
	v_cvt_pk_bf16_f32 v3, v4, v5
	ds_read2_b32 v[4:5], v96 offset0:132 offset1:165
	v_lshl_add_u64 v[10:11], v[8:9], 0, v[0:1]
	s_waitcnt lgkmcnt(0)
	v_cvt_pk_bf16_f32 v4, v4, v5
	ds_read2_b32 v[6:7], v96 offset0:198 offset1:231
	s_waitcnt lgkmcnt(0)
	v_cvt_pk_bf16_f32 v5, v6, v7
	global_store_dwordx4 v[10:11], v[2:5], off
	v_or_b32_e32 v0, s0, v89
	ds_read2_b32 v[2:3], v96 offset0:8 offset1:41
	v_mul_u32_u24_e32 v0, 0xb00, v0
	s_waitcnt lgkmcnt(0)
	v_cvt_pk_bf16_f32 v2, v2, v3
	ds_read2_b32 v[4:5], v96 offset0:74 offset1:107
	v_lshlrev_b32_e32 v0, 1, v0
	s_waitcnt lgkmcnt(0)
	v_cvt_pk_bf16_f32 v3, v4, v5
	ds_read2_b32 v[4:5], v96 offset0:140 offset1:173
	v_lshl_add_u64 v[10:11], v[8:9], 0, v[0:1]
	s_waitcnt lgkmcnt(0)
	v_cvt_pk_bf16_f32 v4, v4, v5
	ds_read2_b32 v[6:7], v96 offset0:206 offset1:239
	s_waitcnt lgkmcnt(0)
	v_cvt_pk_bf16_f32 v5, v6, v7
	global_store_dwordx4 v[10:11], v[2:5], off
	v_or_b32_e32 v0, s0, v93
	ds_read2_b32 v[2:3], v96 offset0:16 offset1:49
	v_mul_u32_u24_e32 v0, 0xb00, v0
	s_waitcnt lgkmcnt(0)
	v_cvt_pk_bf16_f32 v2, v2, v3
	ds_read2_b32 v[4:5], v96 offset0:82 offset1:115
	v_lshlrev_b32_e32 v0, 1, v0
	s_waitcnt lgkmcnt(0)
	v_cvt_pk_bf16_f32 v3, v4, v5
	ds_read2_b32 v[4:5], v96 offset0:148 offset1:181
	v_lshl_add_u64 v[10:11], v[8:9], 0, v[0:1]
	s_waitcnt lgkmcnt(0)
	v_cvt_pk_bf16_f32 v4, v4, v5
	ds_read2_b32 v[6:7], v96 offset0:214 offset1:247
	s_waitcnt lgkmcnt(0)
	v_cvt_pk_bf16_f32 v5, v6, v7
	global_store_dwordx4 v[10:11], v[2:5], off
	ds_read2_b32 v[2:3], v96 offset0:24 offset1:57
	v_or_b32_e32 v0, s0, v95
	s_waitcnt lgkmcnt(0)
	v_cvt_pk_bf16_f32 v2, v2, v3
	ds_read2_b32 v[4:5], v96 offset0:90 offset1:123
	s_waitcnt lgkmcnt(0)
	v_cvt_pk_bf16_f32 v3, v4, v5
	ds_read2_b32 v[4:5], v96 offset0:156 offset1:189
	v_mul_u32_u24_e32 v0, 0xb00, v0
	s_waitcnt lgkmcnt(0)
	v_cvt_pk_bf16_f32 v4, v4, v5
	ds_read2_b32 v[6:7], v96 offset0:222 offset1:255
	v_lshlrev_b32_e32 v0, 1, v0
	s_waitcnt lgkmcnt(0)
	v_cvt_pk_bf16_f32 v5, v6, v7
	v_lshl_add_u64 v[6:7], v[8:9], 0, v[0:1]
	global_store_dwordx4 v[6:7], v[2:5], off
	s_waitcnt lgkmcnt(0)

; #define INP(i) ((const float*)ldp(T, (i)))
; #define TRJ(cnt, W, ldn, N, WT, ldk, gain, rbase, rstride) if (r >= 0) { if (r < (cnt)) { tr_item((W), (ldn), (N), (WT), (ldk), (gain), (rbase), (rstride), scr, r, lane); r = -1; } else r -= (cnt); }
; __device__ __forceinline__ void tr_item(const float* W, int ldn, int N, bf16_t* WT, int ldk, const float* gain, int rbase, int rstride, LAS float* scr, int item, int lane) {
;     const int nblk = N / 32, kb = item / nblk, nb = item % nblk, k0 = 64 * kb, n0 = 32 * nb;
;     f32x4 v[8]; float gk[8];
; #pragma unroll
;     for (int i = 0; i < 8; ++i) { const int kk = 8 * i + (lane >> 3); v[i] = *(const f32x4*)(W + (size_t)(k0 + kk) * ldn + n0 + 4 * (lane & 7)); gk[i] = gain ? gain[k0 + kk] : 1.0f; }
; __device__ __forceinline__ void prep_phase(const PT& T, LAS unsigned char* lds) {
;     ...
;             TRJ(I_UP, INP(16) + (size_t)l * D * FH, FH, FH, Wb + WO_F_GU0 + l * WO_F_STRIDE, D, INP(2) + l * D, 0, 256)
.LBB0_557:
	s_andn2_b64 vcc, exec, s[0:1]
	s_cbranch_vccnz .LBB0_575
	v_mov_b32_e32 v0, s62
	ds_read_b64 v[2:3], v0
	v_mov_b32_e32 v0, s12
	ds_read_b64 v[4:5], v0
	v_lshlrev_b32_e32 v0, 2, v34
	v_mov_b32_e32 v78, 1.0
	s_waitcnt lgkmcnt(0)
	v_readfirstlane_b32 s21, v2
	v_readfirstlane_b32 s5, v3
	v_readfirstlane_b32 s0, v4
	v_readfirstlane_b32 s1, v5
	s_add_u32 s8, s0, 0x1000
	s_addc_u32 s9, s1, 0
	s_and_b32 s19, s4, 0xffff
	s_mul_i32 s19, s19, 0xba2f
	s_lshr_b32 s22, s19, 16
	s_lshr_b32 s19, s19, 22
	s_mulk_i32 s19, 0x58
	s_sub_i32 s4, s4, s19
	s_and_b32 s20, s4, 0xffff
	s_and_b32 s19, s22, 0xffc0
	s_lshl_b32 s4, s20, 7
	s_add_u32 s4, s21, s4
	v_or_b32_e32 v83, s19, v81
	s_addc_u32 s5, s5, 0
	v_lshl_add_u64 v[2:3], s[4:5], 0, v[0:1]
	s_mov_b64 s[4:5], 0xb00000
	v_mul_u32_u24_e32 v14, 0xb00, v83
	v_lshl_add_u64 v[30:31], v[2:3], 0, s[4:5]
	v_lshlrev_b32_e32 v0, 2, v14
	v_lshl_add_u64 v[10:11], v[30:31], 0, v[0:1]
	global_load_dwordx4 v[2:5], v[10:11], off
	s_cmp_lg_u64 s[0:1], 0
	s_cselect_b64 s[4:5], -1, 0
	s_cmp_eq_u64 s[0:1], 0
	v_mov_b32_e32 v80, 1.0
	s_cbranch_scc1 .LBB0_560
	v_lshlrev_b32_e32 v0, 2, v83
	v_lshl_add_u64 v[6:7], s[8:9], 0, v[0:1]
	global_load_dword v80, v[6:7], off
.LBB0_560:
	v_add_co_u32_e32 v6, vcc, 0x16000, v10
	v_cndmask_b32_e64 v0, 0, 1, s[4:5]
	s_nop 0
	v_addc_co_u32_e32 v7, vcc, 0, v11, vcc
	global_load_dwordx4 v[6:9], v[6:7], off
	v_cmp_ne_u32_e64 s[0:1], 1, v0
	s_andn2_b64 vcc, exec, s[4:5]
	s_cbranch_vccnz .LBB0_562
	v_lshl_or_b32 v0, v83, 2, 32
	v_lshl_add_u64 v[12:13], s[8:9], 0, v[0:1]
	global_load_dword v78, v[12:13], off
.LBB0_562:
	v_lshl_add_u64 v[10:11], v[10:11], 0, s[82:83]
	v_add_co_u32_e32 v10, vcc, 0x16000, v10
	v_mov_b32_e32 v82, 1.0
	s_nop 0
	v_addc_co_u32_e32 v11, vcc, 0, v11, vcc
	global_load_dwordx4 v[10:13], v[10:11], off
	s_and_b64 vcc, exec, s[0:1]
	v_mov_b32_e32 v84, 1.0
	s_cbranch_vccnz .LBB0_564
	v_lshl_or_b32 v0, v83, 2, 64
	v_lshl_add_u64 v[16:17], s[8:9], 0, v[0:1]
	global_load_dword v84, v[16:17], off
.LBB0_564:
	v_add_u32_e32 v18, 0x10800, v14
	v_lshlrev_b32_e32 v0, 2, v18
	v_lshl_add_u64 v[14:15], v[30:31], 0, v[0:1]
	global_load_dwordx4 v[14:17], v[14:15], off
	s_and_b64 vcc, exec, s[0:1]
	s_cbranch_vccnz .LBB0_566
	v_lshl_or_b32 v0, v83, 2, v235
	v_lshl_add_u64 v[20:21], s[8:9], 0, v[0:1]
	global_load_dword v82, v[20:21], off
.LBB0_566:
	v_add_u32_e32 v22, 0x5800, v18
	v_lshlrev_b32_e32 v0, 2, v22
	v_lshl_add_u64 v[18:19], v[30:31], 0, v[0:1]
	global_load_dwordx4 v[18:21], v[18:19], off
	v_mov_b32_e32 v86, 1.0
	s_and_b64 vcc, exec, s[0:1]
	v_mov_b32_e32 v88, 1.0
	s_cbranch_vccnz .LBB0_568
	v_lshl_or_b32 v0, v83, 2, v236
	v_lshl_add_u64 v[24:25], s[8:9], 0, v[0:1]
	global_load_dword v88, v[24:25], off
.LBB0_568:
	v_add_u32_e32 v0, 0x5800, v22
	v_lshl_add_u64 v[22:23], v[0:1], 2, v[30:31]
	global_load_dwordx4 v[22:25], v[22:23], off
	s_and_b64 vcc, exec, s[0:1]
	s_cbranch_vccnz .LBB0_570
	v_lshl_or_b32 v26, v83, 2, v237
	v_mov_b32_e32 v27, v1
	v_lshl_add_u64 v[26:27], s[8:9], 0, v[26:27]
	global_load_dword v86, v[26:27], off
.LBB0_570:
	v_add_u32_e32 v0, 0x5800, v0
	v_lshl_add_u64 v[26:27], v[0:1], 2, v[30:31]
	global_load_dwordx4 v[26:29], v[26:27], off
	v_mov_b32_e32 v90, 1.0
	s_and_b64 vcc, exec, s[0:1]
	v_mov_b32_e32 v92, 1.0
	s_cbranch_vccnz .LBB0_572
	v_lshl_or_b32 v32, v83, 2, v238
	v_mov_b32_e32 v33, v1
	v_lshl_add_u64 v[32:33], s[8:9], 0, v[32:33]
	global_load_dword v92, v[32:33], off
.LBB0_572:
	v_add_u32_e32 v0, 0x5800, v0
	v_lshl_add_u64 v[30:31], v[0:1], 2, v[30:31]
	global_load_dwordx4 v[30:33], v[30:31], off
	s_and_b64 vcc, exec, s[0:1]
	s_cbranch_vccnz .LBB0_574
	v_lshl_or_b32 v0, v83, 2, v239
	v_lshl_add_u64 v[98:99], s[8:9], 0, v[0:1]
	global_load_dword v90, v[98:99], off
; #define LAS __attribute__((address_space(3)))
; #define LDS_WAIT() asm volatile("s_waitcnt lgkmcnt(0)" ::: "memory")
; __device__ __forceinline__ unsigned pk2(float lo, float hi) { return pg8::cvt_pk_bf16(lo, hi); }
; __device__ __forceinline__ void tr_item(const float* W, int ldn, int N, bf16_t* WT, int ldk, const float* gain, int rbase, int rstride, LAS float* scr, int item, int lane) {
;     ...
;     for (int i = 0; i < 8; ++i) { LAS float* d = scr + (8 * i + (lane >> 3)) * 33 + 4 * (lane & 7); d[0] = v[i].x * gk[i]; d[1] = v[i].y * gk[i]; d[2] = v[i].z * gk[i]; d[3] = v[i].w * gk[i]; }
;     LDS_WAIT(); asm volatile("" ::: "memory");
;     const int c = lane & 7;
; #pragma unroll
;     for (int j = 0; j < 4; ++j) { const int n = (lane >> 3) + 8 * j; const LAS float* s = scr + (8 * c) * 33 + n;
;         u32x4 o; o.x = pk2(s[0 * 33], s[1 * 33]); o.y = pk2(s[2 * 33], s[3 * 33]); o.z = pk2(s[4 * 33], s[5 * 33]); o.w = pk2(s[6 * 33], s[7 * 33]);
;         const int nn = n0 + n, dest = rbase + (nn >> 7) * rstride + (nn & 127);
;         *(u32x4*)(WT + (size_t)dest * ldk + k0 + 8 * c) = o; }
;     LDS_WAIT(); asm volatile("" ::: "memory");
.LBB0_574:
	s_waitcnt vmcnt(0) lgkmcnt(0)
	v_pk_mul_f32 v[2:3], v[2:3], v[80:81] op_sel_hi:[1,0]
	ds_write2_b32 v87, v2, v3 offset1:1
	v_pk_mul_f32 v[2:3], v[4:5], v[80:81] op_sel_hi:[1,0]
	ds_write2_b32 v87, v2, v3 offset0:2 offset1:3
	v_pk_mul_f32 v[2:3], v[6:7], v[78:79] op_sel_hi:[1,0]
	v_add_u32_e32 v0, v85, v91
	ds_write2_b32 v0, v2, v3 offset1:1
	v_pk_mul_f32 v[2:3], v[8:9], v[78:79] op_sel_hi:[1,0]
	ds_write2_b32 v0, v2, v3 offset0:2 offset1:3
	v_pk_mul_f32 v[2:3], v[10:11], v[84:85] op_sel_hi:[1,0]
	v_add_u32_e32 v4, 0x420, v0
	ds_write2_b32 v4, v2, v3 offset1:1
	v_pk_mul_f32 v[2:3], v[12:13], v[84:85] op_sel_hi:[1,0]
	v_add_u32_e32 v4, 0x428, v0
	ds_write2_b32 v4, v2, v3 offset1:1
	v_pk_mul_f32 v[2:3], v[14:15], v[82:83] op_sel_hi:[1,0]
	v_add_u32_e32 v4, 0x840, v0
	ds_write2_b32 v4, v2, v3 offset1:1
	v_pk_mul_f32 v[2:3], v[16:17], v[82:83] op_sel_hi:[1,0]
	v_add_u32_e32 v0, 0x848, v0
	ds_write2_b32 v0, v2, v3 offset1:1
	v_pk_mul_f32 v[2:3], v[18:19], v[88:89] op_sel_hi:[1,0]
	v_add_u32_e32 v0, 0x1080, v87
	ds_write2_b32 v0, v2, v3 offset1:1
	v_pk_mul_f32 v[2:3], v[20:21], v[88:89] op_sel_hi:[1,0]
	v_add_u32_e32 v0, 0x1088, v87
	ds_write2_b32 v0, v2, v3 offset1:1
	v_pk_mul_f32 v[2:3], v[22:23], v[86:87] op_sel_hi:[1,0]
	v_add_u32_e32 v0, 0x14a0, v87
	ds_write2_b32 v0, v2, v3 offset1:1
	v_pk_mul_f32 v[2:3], v[24:25], v[86:87] op_sel_hi:[1,0]
	v_add_u32_e32 v0, 0x14a8, v87
	ds_write2_b32 v0, v2, v3 offset1:1
	v_pk_mul_f32 v[2:3], v[26:27], v[92:93] op_sel_hi:[1,0]
	v_add_u32_e32 v0, 0x18c0, v87
	ds_write2_b32 v0, v2, v3 offset1:1
	v_pk_mul_f32 v[2:3], v[28:29], v[92:93] op_sel_hi:[1,0]
	v_add_u32_e32 v0, 0x18c8, v87
	ds_write2_b32 v0, v2, v3 offset1:1
	v_pk_mul_f32 v[2:3], v[30:31], v[90:91] op_sel_hi:[1,0]
	v_add_u32_e32 v0, 0x1ce0, v87
	ds_write2_b32 v0, v2, v3 offset1:1
	v_pk_mul_f32 v[2:3], v[32:33], v[90:91] op_sel_hi:[1,0]
	v_add_u32_e32 v0, 0x1ce8, v87
	ds_write2_b32 v0, v2, v3 offset1:1
	s_waitcnt lgkmcnt(0)
	s_lshl_b32 s0, s20, 5
	s_lshl_b32 s1, s20, 6
	ds_read2_b32 v[2:3], v96 offset1:33
	s_and_b32 s1, s1, 0x1f00
	s_and_b32 s0, s0, 0x60
	s_waitcnt lgkmcnt(0)
	v_cvt_pk_bf16_f32 v2, v2, v3
	ds_read2_b32 v[4:5], v96 offset0:66 offset1:99
	s_or_b32 s0, s1, s0
	s_and_b32 s1, 0xffff, s19
	s_waitcnt lgkmcnt(0)
	v_cvt_pk_bf16_f32 v3, v4, v5
	ds_read2_b32 v[4:5], v96 offset0:132 offset1:165
	s_lshl_b32 s46, s1, 1
	v_or_b32_e32 v0, s0, v81
	s_waitcnt lgkmcnt(0)
	v_cvt_pk_bf16_f32 v4, v4, v5
	ds_read2_b32 v[6:7], v96 offset0:198 offset1:231
	v_lshl_add_u64 v[8:9], v[66:67], 0, s[46:47]
	v_lshlrev_b32_e32 v0, 11, v0
	s_waitcnt lgkmcnt(0)
	v_cvt_pk_bf16_f32 v5, v6, v7
	v_lshl_add_u64 v[6:7], v[8:9], 0, v[0:1]
	global_store_dwordx4 v[6:7], v[2:5], off
	ds_read2_b32 v[2:3], v96 offset0:8 offset1:41
	v_or_b32_e32 v0, s0, v89
	s_waitcnt lgkmcnt(0)
	v_cvt_pk_bf16_f32 v2, v2, v3
	ds_read2_b32 v[4:5], v96 offset0:74 offset1:107
	s_waitcnt lgkmcnt(0)
	v_cvt_pk_bf16_f32 v3, v4, v5
	ds_read2_b32 v[4:5], v96 offset0:140 offset1:173
	s_waitcnt lgkmcnt(0)
	v_cvt_pk_bf16_f32 v4, v4, v5
	ds_read2_b32 v[6:7], v96 offset0:206 offset1:239
	v_lshlrev_b32_e32 v0, 11, v0
	s_waitcnt lgkmcnt(0)
	v_cvt_pk_bf16_f32 v5, v6, v7
	v_lshl_add_u64 v[6:7], v[8:9], 0, v[0:1]
	global_store_dwordx4 v[6:7], v[2:5], off
	ds_read2_b32 v[2:3], v96 offset0:16 offset1:49
	v_or_b32_e32 v0, s0, v93
	s_waitcnt lgkmcnt(0)
	v_cvt_pk_bf16_f32 v2, v2, v3
	ds_read2_b32 v[4:5], v96 offset0:82 offset1:115
	s_waitcnt lgkmcnt(0)
	v_cvt_pk_bf16_f32 v3, v4, v5
	ds_read2_b32 v[4:5], v96 offset0:148 offset1:181
	s_waitcnt lgkmcnt(0)
	v_cvt_pk_bf16_f32 v4, v4, v5
	ds_read2_b32 v[6:7], v96 offset0:214 offset1:247
	v_lshlrev_b32_e32 v0, 11, v0
	s_waitcnt lgkmcnt(0)
	v_cvt_pk_bf16_f32 v5, v6, v7
	v_lshl_add_u64 v[6:7], v[8:9], 0, v[0:1]
	global_store_dwordx4 v[6:7], v[2:5], off
	ds_read2_b32 v[2:3], v96 offset0:24 offset1:57
	v_or_b32_e32 v0, s0, v95
	s_waitcnt lgkmcnt(0)
	v_cvt_pk_bf16_f32 v2, v2, v3
	ds_read2_b32 v[4:5], v96 offset0:90 offset1:123
	s_waitcnt lgkmcnt(0)
	v_cvt_pk_bf16_f32 v3, v4, v5
	ds_read2_b32 v[4:5], v96 offset0:156 offset1:189
	s_waitcnt lgkmcnt(0)
	v_cvt_pk_bf16_f32 v4, v4, v5
	ds_read2_b32 v[6:7], v96 offset0:222 offset1:255
	v_lshlrev_b32_e32 v0, 11, v0
	s_waitcnt lgkmcnt(0)
	v_cvt_pk_bf16_f32 v5, v6, v7
	v_lshl_add_u64 v[6:7], v[8:9], 0, v[0:1]
	global_store_dwordx4 v[6:7], v[2:5], off
	s_waitcnt lgkmcnt(0)
	s_mov_b32 s5, -1

; #define INP(i) ((const float*)ldp(T, (i)))
; #define TRJ(cnt, W, ldn, N, WT, ldk, gain, rbase, rstride) if (r >= 0) { if (r < (cnt)) { tr_item((W), (ldn), (N), (WT), (ldk), (gain), (rbase), (rstride), scr, r, lane); r = -1; } else r -= (cnt); }
; __device__ __forceinline__ void tr_item(const float* W, int ldn, int N, bf16_t* WT, int ldk, const float* gain, int rbase, int rstride, LAS float* scr, int item, int lane) {
;     const int nblk = N / 32, kb = item / nblk, nb = item % nblk, k0 = 64 * kb, n0 = 32 * nb;
;     f32x4 v[8]; float gk[8];
; #pragma unroll
;     for (int i = 0; i < 8; ++i) { const int kk = 8 * i + (lane >> 3); v[i] = *(const f32x4*)(W + (size_t)(k0 + kk) * ldn + n0 + 4 * (lane & 7)); gk[i] = gain ? gain[k0 + kk] : 1.0f; }
; __device__ __forceinline__ void prep_phase(const PT& T, LAS unsigned char* lds) {
;     ...
;             TRJ(I_UP, INP(17) + (size_t)l * D * FH, FH, FH, Wb + WO_F_GU0 + l * WO_F_STRIDE, D, INP(2) + l * D, 128, 256)
.LBB0_579:
	s_andn2_b64 vcc, exec, s[0:1]
	s_cbranch_vccnz .LBB0_597
	v_mov_b32_e32 v0, s13
	ds_read_b64 v[2:3], v0
	v_mov_b32_e32 v0, s12
	ds_read_b64 v[4:5], v0
	v_lshlrev_b32_e32 v0, 2, v34
	v_mov_b32_e32 v78, 1.0
	s_waitcnt lgkmcnt(0)
	v_readfirstlane_b32 s21, v2
	v_readfirstlane_b32 s5, v3
	v_readfirstlane_b32 s0, v4
	v_readfirstlane_b32 s1, v5
	s_add_u32 s8, s0, 0x1000
	s_addc_u32 s9, s1, 0
	s_and_b32 s19, s4, 0xffff
	s_mul_i32 s19, s19, 0xba2f
	s_lshr_b32 s22, s19, 16
	s_lshr_b32 s19, s19, 22
	s_mulk_i32 s19, 0x58
	s_sub_i32 s4, s4, s19
	s_and_b32 s20, s4, 0xffff
	s_and_b32 s19, s22, 0xffc0
	s_lshl_b32 s4, s20, 7
	s_add_u32 s4, s21, s4
	v_or_b32_e32 v83, s19, v81
	s_addc_u32 s5, s5, 0
	v_lshl_add_u64 v[2:3], s[4:5], 0, v[0:1]
	s_mov_b64 s[4:5], 0xb00000
	v_mul_u32_u24_e32 v14, 0xb00, v83
	v_lshl_add_u64 v[30:31], v[2:3], 0, s[4:5]
	v_lshlrev_b32_e32 v0, 2, v14
	v_lshl_add_u64 v[10:11], v[30:31], 0, v[0:1]
	global_load_dwordx4 v[2:5], v[10:11], off
	s_cmp_lg_u64 s[0:1], 0
	s_cselect_b64 s[4:5], -1, 0
	s_cmp_eq_u64 s[0:1], 0
	v_mov_b32_e32 v80, 1.0
	s_cbranch_scc1 .LBB0_582
	v_lshlrev_b32_e32 v0, 2, v83
	v_lshl_add_u64 v[6:7], s[8:9], 0, v[0:1]
	global_load_dword v80, v[6:7], off

; #define LAS __attribute__((address_space(3)))
; #define LDS_WAIT() asm volatile("s_waitcnt lgkmcnt(0)" ::: "memory")
; __device__ __forceinline__ unsigned pk2(float lo, float hi) { return pg8::cvt_pk_bf16(lo, hi); }
; __device__ __forceinline__ void tr_item(const float* W, int ldn, int N, bf16_t* WT, int ldk, const float* gain, int rbase, int rstride, LAS float* scr, int item, int lane) {
;     ...
;     for (int i = 0; i < 8; ++i) { LAS float* d = scr + (8 * i + (lane >> 3)) * 33 + 4 * (lane & 7); d[0] = v[i].x * gk[i]; d[1] = v[i].y * gk[i]; d[2] = v[i].z * gk[i]; d[3] = v[i].w * gk[i]; }
;     LDS_WAIT(); asm volatile("" ::: "memory");
;     const int c = lane & 7;
; #pragma unroll
;     for (int j = 0; j < 4; ++j) { const int n = (lane >> 3) + 8 * j; const LAS float* s = scr + (8 * c) * 33 + n;
;         u32x4 o; o.x = pk2(s[0 * 33], s[1 * 33]); o.y = pk2(s[2 * 33], s[3 * 33]); o.z = pk2(s[4 * 33], s[5 * 33]); o.w = pk2(s[6 * 33], s[7 * 33]);
;         const int nn = n0 + n, dest = rbase + (nn >> 7) * rstride + (nn & 127);
;         *(u32x4*)(WT + (size_t)dest * ldk + k0 + 8 * c) = o; }
;     LDS_WAIT(); asm volatile("" ::: "memory");
.LBB0_596:
	s_waitcnt vmcnt(0) lgkmcnt(0)
	v_pk_mul_f32 v[2:3], v[2:3], v[80:81] op_sel_hi:[1,0]
	ds_write2_b32 v87, v2, v3 offset1:1
	v_pk_mul_f32 v[2:3], v[4:5], v[80:81] op_sel_hi:[1,0]
	ds_write2_b32 v87, v2, v3 offset0:2 offset1:3
	v_pk_mul_f32 v[2:3], v[6:7], v[78:79] op_sel_hi:[1,0]
	v_add_u32_e32 v0, v85, v91
	ds_write2_b32 v0, v2, v3 offset1:1
	v_pk_mul_f32 v[2:3], v[8:9], v[78:79] op_sel_hi:[1,0]
	ds_write2_b32 v0, v2, v3 offset0:2 offset1:3
	v_pk_mul_f32 v[2:3], v[10:11], v[84:85] op_sel_hi:[1,0]
	v_add_u32_e32 v4, 0x420, v0
	ds_write2_b32 v4, v2, v3 offset1:1
	v_pk_mul_f32 v[2:3], v[12:13], v[84:85] op_sel_hi:[1,0]
	v_add_u32_e32 v4, 0x428, v0
	ds_write2_b32 v4, v2, v3 offset1:1
	v_pk_mul_f32 v[2:3], v[14:15], v[82:83] op_sel_hi:[1,0]
	v_add_u32_e32 v4, 0x840, v0
	ds_write2_b32 v4, v2, v3 offset1:1
	v_pk_mul_f32 v[2:3], v[16:17], v[82:83] op_sel_hi:[1,0]
	v_add_u32_e32 v0, 0x848, v0
	ds_write2_b32 v0, v2, v3 offset1:1
	v_pk_mul_f32 v[2:3], v[18:19], v[88:89] op_sel_hi:[1,0]
	v_add_u32_e32 v0, 0x1080, v87
	ds_write2_b32 v0, v2, v3 offset1:1
	v_pk_mul_f32 v[2:3], v[20:21], v[88:89] op_sel_hi:[1,0]
	v_add_u32_e32 v0, 0x1088, v87
	ds_write2_b32 v0, v2, v3 offset1:1
	v_pk_mul_f32 v[2:3], v[22:23], v[86:87] op_sel_hi:[1,0]
	v_add_u32_e32 v0, 0x14a0, v87
	ds_write2_b32 v0, v2, v3 offset1:1
	v_pk_mul_f32 v[2:3], v[24:25], v[86:87] op_sel_hi:[1,0]
	v_add_u32_e32 v0, 0x14a8, v87
	ds_write2_b32 v0, v2, v3 offset1:1
	v_pk_mul_f32 v[2:3], v[26:27], v[92:93] op_sel_hi:[1,0]
	v_add_u32_e32 v0, 0x18c0, v87
	ds_write2_b32 v0, v2, v3 offset1:1
	v_pk_mul_f32 v[2:3], v[28:29], v[92:93] op_sel_hi:[1,0]
	v_add_u32_e32 v0, 0x18c8, v87
	ds_write2_b32 v0, v2, v3 offset1:1
	v_pk_mul_f32 v[2:3], v[30:31], v[90:91] op_sel_hi:[1,0]
	v_add_u32_e32 v0, 0x1ce0, v87
	ds_write2_b32 v0, v2, v3 offset1:1
	v_pk_mul_f32 v[2:3], v[32:33], v[90:91] op_sel_hi:[1,0]
	v_add_u32_e32 v0, 0x1ce8, v87
	ds_write2_b32 v0, v2, v3 offset1:1
	s_waitcnt lgkmcnt(0)
	s_lshl_b32 s0, s20, 5
	s_lshl_b32 s1, s20, 6
	s_and_b32 s1, s1, 0x1f00
	s_and_b32 s0, s0, 0x60
	ds_read2_b32 v[2:3], v96 offset1:33
	s_or_b32 s0, s1, s0
	s_waitcnt lgkmcnt(0)
	v_cvt_pk_bf16_f32 v2, v2, v3
	ds_read2_b32 v[4:5], v96 offset0:66 offset1:99
	s_bitset1_b32 s0, 7
	s_and_b32 s1, 0xffff, s19
	s_waitcnt lgkmcnt(0)
	v_cvt_pk_bf16_f32 v3, v4, v5
	ds_read2_b32 v[4:5], v96 offset0:132 offset1:165
	s_lshl_b32 s46, s1, 1
	v_or_b32_e32 v0, s0, v81
	s_waitcnt lgkmcnt(0)
	v_cvt_pk_bf16_f32 v4, v4, v5
	ds_read2_b32 v[6:7], v96 offset0:198 offset1:231
	v_lshl_add_u64 v[8:9], v[66:67], 0, s[46:47]
	v_lshlrev_b32_e32 v0, 11, v0
	s_waitcnt lgkmcnt(0)
	v_cvt_pk_bf16_f32 v5, v6, v7
	v_lshl_add_u64 v[6:7], v[8:9], 0, v[0:1]
	global_store_dwordx4 v[6:7], v[2:5], off
	ds_read2_b32 v[2:3], v96 offset0:8 offset1:41
	v_or_b32_e32 v0, s0, v89
	s_waitcnt lgkmcnt(0)
	v_cvt_pk_bf16_f32 v2, v2, v3
	ds_read2_b32 v[4:5], v96 offset0:74 offset1:107
	s_waitcnt lgkmcnt(0)
	v_cvt_pk_bf16_f32 v3, v4, v5
	ds_read2_b32 v[4:5], v96 offset0:140 offset1:173
	s_waitcnt lgkmcnt(0)
	v_cvt_pk_bf16_f32 v4, v4, v5
	ds_read2_b32 v[6:7], v96 offset0:206 offset1:239
	v_lshlrev_b32_e32 v0, 11, v0
	s_waitcnt lgkmcnt(0)
	v_cvt_pk_bf16_f32 v5, v6, v7
	v_lshl_add_u64 v[6:7], v[8:9], 0, v[0:1]
	global_store_dwordx4 v[6:7], v[2:5], off
	ds_read2_b32 v[2:3], v96 offset0:16 offset1:49
	v_or_b32_e32 v0, s0, v93
	s_waitcnt lgkmcnt(0)
	v_cvt_pk_bf16_f32 v2, v2, v3
	ds_read2_b32 v[4:5], v96 offset0:82 offset1:115
	s_waitcnt lgkmcnt(0)
	v_cvt_pk_bf16_f32 v3, v4, v5
	ds_read2_b32 v[4:5], v96 offset0:148 offset1:181
	s_waitcnt lgkmcnt(0)
	v_cvt_pk_bf16_f32 v4, v4, v5
	ds_read2_b32 v[6:7], v96 offset0:214 offset1:247
	v_lshlrev_b32_e32 v0, 11, v0
	s_waitcnt lgkmcnt(0)
	v_cvt_pk_bf16_f32 v5, v6, v7
	v_lshl_add_u64 v[6:7], v[8:9], 0, v[0:1]
	global_store_dwordx4 v[6:7], v[2:5], off
	ds_read2_b32 v[2:3], v96 offset0:24 offset1:57
	v_or_b32_e32 v0, s0, v95
	s_waitcnt lgkmcnt(0)
	v_cvt_pk_bf16_f32 v2, v2, v3
	ds_read2_b32 v[4:5], v96 offset0:90 offset1:123
	s_waitcnt lgkmcnt(0)
	v_cvt_pk_bf16_f32 v3, v4, v5
	ds_read2_b32 v[4:5], v96 offset0:156 offset1:189
	s_waitcnt lgkmcnt(0)
	v_cvt_pk_bf16_f32 v4, v4, v5
	ds_read2_b32 v[6:7], v96 offset0:222 offset1:255
	v_lshlrev_b32_e32 v0, 11, v0
	s_waitcnt lgkmcnt(0)
	v_cvt_pk_bf16_f32 v5, v6, v7
	v_lshl_add_u64 v[6:7], v[8:9], 0, v[0:1]
	global_store_dwordx4 v[6:7], v[2:5], off
	s_waitcnt lgkmcnt(0)
	s_mov_b32 s5, -1

; #define LAS __attribute__((address_space(3)))
; #define LDS_WAIT() asm volatile("s_waitcnt lgkmcnt(0)" ::: "memory")
; __device__ __forceinline__ unsigned pk2(float lo, float hi) { return pg8::cvt_pk_bf16(lo, hi); }
; #define INP(i) ((const float*)ldp(T, (i)))
; #define TRJ(cnt, W, ldn, N, WT, ldk, gain, rbase, rstride) if (r >= 0) { if (r < (cnt)) { tr_item((W), (ldn), (N), (WT), (ldk), (gain), (rbase), (rstride), scr, r, lane); r = -1; } else r -= (cnt); }
; __device__ __forceinline__ void tr_item(const float* W, int ldn, int N, bf16_t* WT, int ldk, const float* gain, int rbase, int rstride, LAS float* scr, int item, int lane) {
;     const int nblk = N / 32, kb = item / nblk, nb = item % nblk, k0 = 64 * kb, n0 = 32 * nb;
;     f32x4 v[8]; float gk[8];
; #pragma unroll
;     for (int i = 0; i < 8; ++i) { const int kk = 8 * i + (lane >> 3); v[i] = *(const f32x4*)(W + (size_t)(k0 + kk) * ldn + n0 + 4 * (lane & 7)); gk[i] = gain ? gain[k0 + kk] : 1.0f; }
; #pragma unroll
;     for (int i = 0; i < 8; ++i) { LAS float* d = scr + (8 * i + (lane >> 3)) * 33 + 4 * (lane & 7); d[0] = v[i].x * gk[i]; d[1] = v[i].y * gk[i]; d[2] = v[i].z * gk[i]; d[3] = v[i].w * gk[i]; }
;     LDS_WAIT(); asm volatile("" ::: "memory");
;     const int c = lane & 7;
; #pragma unroll
;     for (int j = 0; j < 4; ++j) { const int n = (lane >> 3) + 8 * j; const LAS float* s = scr + (8 * c) * 33 + n;
;         u32x4 o; o.x = pk2(s[0 * 33], s[1 * 33]); o.y = pk2(s[2 * 33], s[3 * 33]); o.z = pk2(s[4 * 33], s[5 * 33]); o.w = pk2(s[6 * 33], s[7 * 33]);
;         const int nn = n0 + n, dest = rbase + (nn >> 7) * rstride + (nn & 127);
;         *(u32x4*)(WT + (size_t)dest * ldk + k0 + 8 * c) = o; }
;     LDS_WAIT(); asm volatile("" ::: "memory");
; __device__ __forceinline__ void prep_phase(const PT& T, LAS unsigned char* lds) {
;     ...
;             TRJ(I_DN, INP(18) + (size_t)l * D * FH, D, D, Wb + WO_F_D0 + l * WO_F_STRIDE, FH, nullptr, 0, 128)
.LBB0_601:
	s_andn2_b64 vcc, exec, s[0:1]
	s_cbranch_vccnz .LBB0_603
	v_mov_b32_e32 v0, s40
	ds_read_b64 v[2:3], v0
	s_lshl_b32 s0, s4, 1
	s_lshl_b32 s1, s4, 5
	s_and_b32 s8, s0, 0xfc0
	s_and_b32 s0, s1, 0x3e0
	s_waitcnt lgkmcnt(0)
	v_readfirstlane_b32 s4, v2
	s_lshl_b32 s1, s0, 2
	v_readfirstlane_b32 s5, v3
	s_add_u32 s4, s4, s1
	v_or_b32_e32 v4, s8, v81
	s_addc_u32 s5, s5, 0
	v_lshlrev_b32_e32 v0, 2, v34
	v_lshl_add_u64 v[2:3], s[4:5], 0, v[0:1]
	v_lshlrev_b32_e32 v0, 12, v4
	v_lshl_add_u64 v[30:31], v[2:3], 0, v[0:1]
	s_mov_b32 s1, 0xb00000
	v_add_co_u32_e32 v2, vcc, s1, v30
	s_mov_b32 s1, 0xb08000
	s_nop 0
	v_addc_co_u32_e32 v3, vcc, 0, v31, vcc
	v_add_co_u32_e32 v6, vcc, s1, v30
	s_mov_b32 s1, 0xb10000
	s_nop 0
	v_addc_co_u32_e32 v7, vcc, 0, v31, vcc
	v_add_co_u32_e32 v10, vcc, s1, v30
	s_mov_b32 s1, 0xb18000
	s_nop 0
	v_addc_co_u32_e32 v11, vcc, 0, v31, vcc
	v_add_co_u32_e32 v14, vcc, s1, v30
	s_mov_b32 s1, 0xb20000
	s_nop 0
	v_addc_co_u32_e32 v15, vcc, 0, v31, vcc
	v_add_co_u32_e32 v18, vcc, s1, v30
	s_mov_b32 s1, 0xb28000
	s_nop 0
	v_addc_co_u32_e32 v19, vcc, 0, v31, vcc
	v_add_co_u32_e32 v22, vcc, s1, v30
	global_load_dwordx4 v[2:5], v[2:3], off
	s_nop 0
	global_load_dwordx4 v[6:9], v[6:7], off
	v_addc_co_u32_e32 v23, vcc, 0, v31, vcc
	global_load_dwordx4 v[10:13], v[10:11], off
	s_nop 0
	global_load_dwordx4 v[14:17], v[14:15], off
	s_nop 0
	global_load_dwordx4 v[18:21], v[18:19], off
	s_nop 0
	global_load_dwordx4 v[22:25], v[22:23], off
	s_mov_b32 s1, 0xb30000
	v_add_co_u32_e32 v26, vcc, s1, v30
	s_mov_b32 s1, 0xb38000
	s_nop 0
	v_addc_co_u32_e32 v27, vcc, 0, v31, vcc
	global_load_dwordx4 v[26:29], v[26:27], off
	v_add_co_u32_e32 v30, vcc, s1, v30
	v_add_u32_e32 v0, v85, v91
	s_nop 0
	v_addc_co_u32_e32 v31, vcc, 0, v31, vcc
	global_load_dwordx4 v[30:33], v[30:31], off
	v_add_u32_e32 v78, 0x1080, v87
	v_add_u32_e32 v80, 0x1088, v87
	v_add_u32_e32 v82, 0x14a0, v87
	v_add_u32_e32 v83, 0x14a8, v87
	v_add_u32_e32 v84, 0x18c0, v87
	v_add_u32_e32 v86, 0x18c8, v87
	v_add_u32_e32 v88, 0x1ce0, v87
	v_add_u32_e32 v90, 0x1ce8, v87
	v_add_u32_e32 v92, 0x420, v0
	v_add_u32_e32 v94, 0x428, v0
	v_add_u32_e32 v97, 0x840, v0
	v_add_u32_e32 v98, 0x848, v0
	s_lshl_b32 s46, s8, 1
	s_mov_b32 s5, -1
	s_waitcnt vmcnt(0) lgkmcnt(0)
	ds_write2_b32 v87, v2, v3 offset1:1
	ds_write2_b32 v87, v4, v5 offset0:2 offset1:3
	ds_write2_b32 v0, v6, v7 offset1:1
	ds_write2_b32 v0, v8, v9 offset0:2 offset1:3
	ds_write2_b32 v92, v10, v11 offset1:1
	ds_write2_b32 v94, v12, v13 offset1:1
	ds_write2_b32 v97, v14, v15 offset1:1
	ds_write2_b32 v98, v16, v17 offset1:1
	ds_write2_b32 v78, v18, v19 offset1:1
	ds_write2_b32 v80, v20, v21 offset1:1
	ds_write2_b32 v82, v22, v23 offset1:1
	ds_write2_b32 v83, v24, v25 offset1:1
	ds_write2_b32 v84, v26, v27 offset1:1
	ds_write2_b32 v86, v28, v29 offset1:1
	ds_write2_b32 v88, v30, v31 offset1:1
	ds_write2_b32 v90, v32, v33 offset1:1
	s_waitcnt lgkmcnt(0)
	v_or_b32_e32 v0, s0, v81
	ds_read2_b32 v[2:3], v96 offset1:33
	v_mul_u32_u24_e32 v0, 0xb00, v0
	s_waitcnt lgkmcnt(0)
	v_cvt_pk_bf16_f32 v2, v2, v3
	ds_read2_b32 v[4:5], v96 offset0:66 offset1:99
	v_lshl_add_u64 v[8:9], v[68:69], 0, s[46:47]
	v_lshlrev_b32_e32 v0, 1, v0
	s_waitcnt lgkmcnt(0)
	v_cvt_pk_bf16_f32 v3, v4, v5
	ds_read2_b32 v[4:5], v96 offset0:132 offset1:165
	v_lshl_add_u64 v[10:11], v[8:9], 0, v[0:1]
	s_waitcnt lgkmcnt(0)
	v_cvt_pk_bf16_f32 v4, v4, v5
	ds_read2_b32 v[6:7], v96 offset0:198 offset1:231
	s_waitcnt lgkmcnt(0)
	v_cvt_pk_bf16_f32 v5, v6, v7
	global_store_dwordx4 v[10:11], v[2:5], off
	v_or_b32_e32 v0, s0, v89
	ds_read2_b32 v[2:3], v96 offset0:8 offset1:41
	v_mul_u32_u24_e32 v0, 0xb00, v0
	s_waitcnt lgkmcnt(0)
	v_cvt_pk_bf16_f32 v2, v2, v3
	ds_read2_b32 v[4:5], v96 offset0:74 offset1:107
	v_lshlrev_b32_e32 v0, 1, v0
	s_waitcnt lgkmcnt(0)
	v_cvt_pk_bf16_f32 v3, v4, v5
	ds_read2_b32 v[4:5], v96 offset0:140 offset1:173
	v_lshl_add_u64 v[10:11], v[8:9], 0, v[0:1]
	s_waitcnt lgkmcnt(0)
	v_cvt_pk_bf16_f32 v4, v4, v5
	ds_read2_b32 v[6:7], v96 offset0:206 offset1:239
	s_waitcnt lgkmcnt(0)
	v_cvt_pk_bf16_f32 v5, v6, v7
	global_store_dwordx4 v[10:11], v[2:5], off
	v_or_b32_e32 v0, s0, v93
	ds_read2_b32 v[2:3], v96 offset0:16 offset1:49
	v_mul_u32_u24_e32 v0, 0xb00, v0
	s_waitcnt lgkmcnt(0)
	v_cvt_pk_bf16_f32 v2, v2, v3
	ds_read2_b32 v[4:5], v96 offset0:82 offset1:115
	v_lshlrev_b32_e32 v0, 1, v0
	s_waitcnt lgkmcnt(0)
	v_cvt_pk_bf16_f32 v3, v4, v5
	ds_read2_b32 v[4:5], v96 offset0:148 offset1:181
	v_lshl_add_u64 v[10:11], v[8:9], 0, v[0:1]
	s_waitcnt lgkmcnt(0)
	v_cvt_pk_bf16_f32 v4, v4, v5
	ds_read2_b32 v[6:7], v96 offset0:214 offset1:247
	s_waitcnt lgkmcnt(0)
	v_cvt_pk_bf16_f32 v5, v6, v7
	global_store_dwordx4 v[10:11], v[2:5], off
	ds_read2_b32 v[2:3], v96 offset0:24 offset1:57
	v_or_b32_e32 v0, s0, v95
	s_waitcnt lgkmcnt(0)
	v_cvt_pk_bf16_f32 v2, v2, v3
	ds_read2_b32 v[4:5], v96 offset0:90 offset1:123
	s_waitcnt lgkmcnt(0)
	v_cvt_pk_bf16_f32 v3, v4, v5
	ds_read2_b32 v[4:5], v96 offset0:156 offset1:189
	v_mul_u32_u24_e32 v0, 0xb00, v0
	s_waitcnt lgkmcnt(0)
	v_cvt_pk_bf16_f32 v4, v4, v5
	ds_read2_b32 v[6:7], v96 offset0:222 offset1:255
	v_lshlrev_b32_e32 v0, 1, v0
	s_waitcnt lgkmcnt(0)
	v_cvt_pk_bf16_f32 v5, v6, v7
	v_lshl_add_u64 v[6:7], v[8:9], 0, v[0:1]
	global_store_dwordx4 v[6:7], v[2:5], off
	s_waitcnt lgkmcnt(0)

; #define INP(i) ((const float*)ldp(T, (i)))
; #define TRJ(cnt, W, ldn, N, WT, ldk, gain, rbase, rstride) if (r >= 0) { if (r < (cnt)) { tr_item((W), (ldn), (N), (WT), (ldk), (gain), (rbase), (rstride), scr, r, lane); r = -1; } else r -= (cnt); }
; __device__ __forceinline__ void tr_item(const float* W, int ldn, int N, bf16_t* WT, int ldk, const float* gain, int rbase, int rstride, LAS float* scr, int item, int lane) {
;     const int nblk = N / 32, kb = item / nblk, nb = item % nblk, k0 = 64 * kb, n0 = 32 * nb;
;     f32x4 v[8]; float gk[8];
; #pragma unroll
;     for (int i = 0; i < 8; ++i) { const int kk = 8 * i + (lane >> 3); v[i] = *(const f32x4*)(W + (size_t)(k0 + kk) * ldn + n0 + 4 * (lane & 7)); gk[i] = gain ? gain[k0 + kk] : 1.0f; }
; __device__ __forceinline__ void prep_phase(const PT& T, LAS unsigned char* lds) {
;     ...
;             TRJ(I_UP, INP(16) + (size_t)l * D * FH, FH, FH, Wb + WO_F_GU0 + l * WO_F_STRIDE, D, INP(2) + l * D, 0, 256)
.LBB0_607:
	s_andn2_b64 vcc, exec, s[0:1]
	s_cbranch_vccnz .LBB0_625
	v_mov_b32_e32 v0, s62
	ds_read_b64 v[2:3], v0
	v_mov_b32_e32 v0, s12
	ds_read_b64 v[4:5], v0
	v_lshlrev_b32_e32 v0, 2, v34
	v_mov_b32_e32 v78, 1.0
	s_waitcnt lgkmcnt(0)
	v_readfirstlane_b32 s21, v2
	v_readfirstlane_b32 s5, v3
	v_readfirstlane_b32 s0, v4
	v_readfirstlane_b32 s1, v5
	s_add_u32 s8, s0, 0x2000
	s_addc_u32 s9, s1, 0
	s_and_b32 s19, s4, 0xffff
	s_mul_i32 s19, s19, 0xba2f
	s_lshr_b32 s22, s19, 16
	s_lshr_b32 s19, s19, 22
	s_mulk_i32 s19, 0x58
	s_sub_i32 s4, s4, s19
	s_and_b32 s20, s4, 0xffff
	s_and_b32 s19, s22, 0xffc0
	s_lshl_b32 s4, s20, 7
	s_add_u32 s4, s21, s4
	v_or_b32_e32 v83, s19, v81
	s_addc_u32 s5, s5, 0
	v_lshl_add_u64 v[2:3], s[4:5], 0, v[0:1]
	s_mov_b64 s[4:5], 0x1600000
	v_mul_u32_u24_e32 v14, 0xb00, v83
	v_lshl_add_u64 v[30:31], v[2:3], 0, s[4:5]
	v_lshlrev_b32_e32 v0, 2, v14
	v_lshl_add_u64 v[10:11], v[30:31], 0, v[0:1]
	global_load_dwordx4 v[2:5], v[10:11], off
	s_cmp_lg_u64 s[0:1], 0
	s_cselect_b64 s[4:5], -1, 0
	s_cmp_eq_u64 s[0:1], 0
	v_mov_b32_e32 v80, 1.0
	s_cbranch_scc1 .LBB0_610
	v_lshlrev_b32_e32 v0, 2, v83
	v_lshl_add_u64 v[6:7], s[8:9], 0, v[0:1]
	global_load_dword v80, v[6:7], off

; #define LAS __attribute__((address_space(3)))
; #define LDS_WAIT() asm volatile("s_waitcnt lgkmcnt(0)" ::: "memory")
; __device__ __forceinline__ unsigned pk2(float lo, float hi) { return pg8::cvt_pk_bf16(lo, hi); }
; __device__ __forceinline__ void tr_item(const float* W, int ldn, int N, bf16_t* WT, int ldk, const float* gain, int rbase, int rstride, LAS float* scr, int item, int lane) {
;     ...
;     for (int i = 0; i < 8; ++i) { LAS float* d = scr + (8 * i + (lane >> 3)) * 33 + 4 * (lane & 7); d[0] = v[i].x * gk[i]; d[1] = v[i].y * gk[i]; d[2] = v[i].z * gk[i]; d[3] = v[i].w * gk[i]; }
;     LDS_WAIT(); asm volatile("" ::: "memory");
;     const int c = lane & 7;
; #pragma unroll
;     for (int j = 0; j < 4; ++j) { const int n = (lane >> 3) + 8 * j; const LAS float* s = scr + (8 * c) * 33 + n;
;         u32x4 o; o.x = pk2(s[0 * 33], s[1 * 33]); o.y = pk2(s[2 * 33], s[3 * 33]); o.z = pk2(s[4 * 33], s[5 * 33]); o.w = pk2(s[6 * 33], s[7 * 33]);
;         const int nn = n0 + n, dest = rbase + (nn >> 7) * rstride + (nn & 127);
;         *(u32x4*)(WT + (size_t)dest * ldk + k0 + 8 * c) = o; }
;     LDS_WAIT(); asm volatile("" ::: "memory");
.LBB0_624:
	s_waitcnt vmcnt(0) lgkmcnt(0)
	v_pk_mul_f32 v[2:3], v[2:3], v[80:81] op_sel_hi:[1,0]
	ds_write2_b32 v87, v2, v3 offset1:1
	v_pk_mul_f32 v[2:3], v[4:5], v[80:81] op_sel_hi:[1,0]
	ds_write2_b32 v87, v2, v3 offset0:2 offset1:3
	v_pk_mul_f32 v[2:3], v[6:7], v[78:79] op_sel_hi:[1,0]
	v_add_u32_e32 v0, v85, v91
	ds_write2_b32 v0, v2, v3 offset1:1
	v_pk_mul_f32 v[2:3], v[8:9], v[78:79] op_sel_hi:[1,0]
	ds_write2_b32 v0, v2, v3 offset0:2 offset1:3
	v_pk_mul_f32 v[2:3], v[10:11], v[84:85] op_sel_hi:[1,0]
	v_add_u32_e32 v4, 0x420, v0
	ds_write2_b32 v4, v2, v3 offset1:1
	v_pk_mul_f32 v[2:3], v[12:13], v[84:85] op_sel_hi:[1,0]
	v_add_u32_e32 v4, 0x428, v0
	ds_write2_b32 v4, v2, v3 offset1:1
	v_pk_mul_f32 v[2:3], v[14:15], v[82:83] op_sel_hi:[1,0]
	v_add_u32_e32 v4, 0x840, v0
	ds_write2_b32 v4, v2, v3 offset1:1
	v_pk_mul_f32 v[2:3], v[16:17], v[82:83] op_sel_hi:[1,0]
	v_add_u32_e32 v0, 0x848, v0
	ds_write2_b32 v0, v2, v3 offset1:1
	v_pk_mul_f32 v[2:3], v[18:19], v[88:89] op_sel_hi:[1,0]
	v_add_u32_e32 v0, 0x1080, v87
	ds_write2_b32 v0, v2, v3 offset1:1
	v_pk_mul_f32 v[2:3], v[20:21], v[88:89] op_sel_hi:[1,0]
	v_add_u32_e32 v0, 0x1088, v87
	ds_write2_b32 v0, v2, v3 offset1:1
	v_pk_mul_f32 v[2:3], v[22:23], v[86:87] op_sel_hi:[1,0]
	v_add_u32_e32 v0, 0x14a0, v87
	ds_write2_b32 v0, v2, v3 offset1:1
	v_pk_mul_f32 v[2:3], v[24:25], v[86:87] op_sel_hi:[1,0]
	v_add_u32_e32 v0, 0x14a8, v87
	ds_write2_b32 v0, v2, v3 offset1:1
	v_pk_mul_f32 v[2:3], v[26:27], v[92:93] op_sel_hi:[1,0]
	v_add_u32_e32 v0, 0x18c0, v87
	ds_write2_b32 v0, v2, v3 offset1:1
	v_pk_mul_f32 v[2:3], v[28:29], v[92:93] op_sel_hi:[1,0]
	v_add_u32_e32 v0, 0x18c8, v87
	ds_write2_b32 v0, v2, v3 offset1:1
	v_pk_mul_f32 v[2:3], v[30:31], v[90:91] op_sel_hi:[1,0]
	v_add_u32_e32 v0, 0x1ce0, v87
	ds_write2_b32 v0, v2, v3 offset1:1
	v_pk_mul_f32 v[2:3], v[32:33], v[90:91] op_sel_hi:[1,0]
	v_add_u32_e32 v0, 0x1ce8, v87
	ds_write2_b32 v0, v2, v3 offset1:1
	s_waitcnt lgkmcnt(0)
	s_lshl_b32 s0, s20, 5
	s_lshl_b32 s1, s20, 6
	ds_read2_b32 v[2:3], v96 offset1:33
	s_and_b32 s1, s1, 0x1f00
	s_and_b32 s0, s0, 0x60
	s_waitcnt lgkmcnt(0)
	v_cvt_pk_bf16_f32 v2, v2, v3
	ds_read2_b32 v[4:5], v96 offset0:66 offset1:99
	s_or_b32 s0, s1, s0
	s_and_b32 s1, 0xffff, s19
	s_waitcnt lgkmcnt(0)
	v_cvt_pk_bf16_f32 v3, v4, v5
	ds_read2_b32 v[4:5], v96 offset0:132 offset1:165
	s_lshl_b32 s46, s1, 1
	v_or_b32_e32 v0, s0, v81
	s_waitcnt lgkmcnt(0)
	v_cvt_pk_bf16_f32 v4, v4, v5
	ds_read2_b32 v[6:7], v96 offset0:198 offset1:231
	v_lshl_add_u64 v[8:9], v[70:71], 0, s[46:47]
	v_lshlrev_b32_e32 v0, 11, v0
	s_waitcnt lgkmcnt(0)
	v_cvt_pk_bf16_f32 v5, v6, v7
	v_lshl_add_u64 v[6:7], v[8:9], 0, v[0:1]
	global_store_dwordx4 v[6:7], v[2:5], off
	ds_read2_b32 v[2:3], v96 offset0:8 offset1:41
	v_or_b32_e32 v0, s0, v89
	s_waitcnt lgkmcnt(0)
	v_cvt_pk_bf16_f32 v2, v2, v3
	ds_read2_b32 v[4:5], v96 offset0:74 offset1:107
	s_waitcnt lgkmcnt(0)
	v_cvt_pk_bf16_f32 v3, v4, v5
	ds_read2_b32 v[4:5], v96 offset0:140 offset1:173
	s_waitcnt lgkmcnt(0)
	v_cvt_pk_bf16_f32 v4, v4, v5
	ds_read2_b32 v[6:7], v96 offset0:206 offset1:239
	v_lshlrev_b32_e32 v0, 11, v0
	s_waitcnt lgkmcnt(0)
	v_cvt_pk_bf16_f32 v5, v6, v7
	v_lshl_add_u64 v[6:7], v[8:9], 0, v[0:1]
	global_store_dwordx4 v[6:7], v[2:5], off
	ds_read2_b32 v[2:3], v96 offset0:16 offset1:49
	v_or_b32_e32 v0, s0, v93
	s_waitcnt lgkmcnt(0)
	v_cvt_pk_bf16_f32 v2, v2, v3
	ds_read2_b32 v[4:5], v96 offset0:82 offset1:115
	s_waitcnt lgkmcnt(0)
	v_cvt_pk_bf16_f32 v3, v4, v5
	ds_read2_b32 v[4:5], v96 offset0:148 offset1:181
	s_waitcnt lgkmcnt(0)
	v_cvt_pk_bf16_f32 v4, v4, v5
	ds_read2_b32 v[6:7], v96 offset0:214 offset1:247
	v_lshlrev_b32_e32 v0, 11, v0
	s_waitcnt lgkmcnt(0)
	v_cvt_pk_bf16_f32 v5, v6, v7
	v_lshl_add_u64 v[6:7], v[8:9], 0, v[0:1]
	global_store_dwordx4 v[6:7], v[2:5], off
	ds_read2_b32 v[2:3], v96 offset0:24 offset1:57
	v_or_b32_e32 v0, s0, v95
	s_waitcnt lgkmcnt(0)
	v_cvt_pk_bf16_f32 v2, v2, v3
	ds_read2_b32 v[4:5], v96 offset0:90 offset1:123
	s_waitcnt lgkmcnt(0)
	v_cvt_pk_bf16_f32 v3, v4, v5
	ds_read2_b32 v[4:5], v96 offset0:156 offset1:189
	s_waitcnt lgkmcnt(0)
	v_cvt_pk_bf16_f32 v4, v4, v5
	ds_read2_b32 v[6:7], v96 offset0:222 offset1:255
	v_lshlrev_b32_e32 v0, 11, v0
	s_waitcnt lgkmcnt(0)
	v_cvt_pk_bf16_f32 v5, v6, v7
	v_lshl_add_u64 v[6:7], v[8:9], 0, v[0:1]
	global_store_dwordx4 v[6:7], v[2:5], off
	s_waitcnt lgkmcnt(0)
	s_mov_b32 s5, -1

; #define INP(i) ((const float*)ldp(T, (i)))
; #define TRJ(cnt, W, ldn, N, WT, ldk, gain, rbase, rstride) if (r >= 0) { if (r < (cnt)) { tr_item((W), (ldn), (N), (WT), (ldk), (gain), (rbase), (rstride), scr, r, lane); r = -1; } else r -= (cnt); }
; __device__ __forceinline__ void tr_item(const float* W, int ldn, int N, bf16_t* WT, int ldk, const float* gain, int rbase, int rstride, LAS float* scr, int item, int lane) {
;     const int nblk = N / 32, kb = item / nblk, nb = item % nblk, k0 = 64 * kb, n0 = 32 * nb;
;     f32x4 v[8]; float gk[8];
; #pragma unroll
;     for (int i = 0; i < 8; ++i) { const int kk = 8 * i + (lane >> 3); v[i] = *(const f32x4*)(W + (size_t)(k0 + kk) * ldn + n0 + 4 * (lane & 7)); gk[i] = gain ? gain[k0 + kk] : 1.0f; }
; __device__ __forceinline__ void prep_phase(const PT& T, LAS unsigned char* lds) {
;     ...
;             TRJ(I_UP, INP(17) + (size_t)l * D * FH, FH, FH, Wb + WO_F_GU0 + l * WO_F_STRIDE, D, INP(2) + l * D, 128, 256)
.LBB0_629:
	s_andn2_b64 vcc, exec, s[0:1]
	s_cbranch_vccnz .LBB0_647
	v_mov_b32_e32 v0, s13
	ds_read_b64 v[2:3], v0
	v_mov_b32_e32 v0, s12
	ds_read_b64 v[4:5], v0
	v_lshlrev_b32_e32 v0, 2, v34
	v_mov_b32_e32 v78, 1.0
	s_waitcnt lgkmcnt(0)
	v_readfirstlane_b32 s21, v2
	v_readfirstlane_b32 s5, v3
	v_readfirstlane_b32 s0, v4
	v_readfirstlane_b32 s1, v5
	s_add_u32 s8, s0, 0x2000
	s_addc_u32 s9, s1, 0
	s_and_b32 s19, s4, 0xffff
	s_mul_i32 s19, s19, 0xba2f
	s_lshr_b32 s22, s19, 16
	s_lshr_b32 s19, s19, 22
	s_mulk_i32 s19, 0x58
	s_sub_i32 s4, s4, s19
	s_and_b32 s20, s4, 0xffff
	s_and_b32 s19, s22, 0xffc0
	s_lshl_b32 s4, s20, 7
	s_add_u32 s4, s21, s4
	v_or_b32_e32 v83, s19, v81
	s_addc_u32 s5, s5, 0
	v_lshl_add_u64 v[2:3], s[4:5], 0, v[0:1]
	s_mov_b64 s[4:5], 0x1600000
	v_mul_u32_u24_e32 v14, 0xb00, v83
	v_lshl_add_u64 v[30:31], v[2:3], 0, s[4:5]
	v_lshlrev_b32_e32 v0, 2, v14
	v_lshl_add_u64 v[10:11], v[30:31], 0, v[0:1]
	global_load_dwordx4 v[2:5], v[10:11], off
	s_cmp_lg_u64 s[0:1], 0
	s_cselect_b64 s[4:5], -1, 0
	s_cmp_eq_u64 s[0:1], 0
	v_mov_b32_e32 v80, 1.0
	s_cbranch_scc1 .LBB0_632
	v_lshlrev_b32_e32 v0, 2, v83
	v_lshl_add_u64 v[6:7], s[8:9], 0, v[0:1]
	global_load_dword v80, v[6:7], off

; #define LAS __attribute__((address_space(3)))
; #define LDS_WAIT() asm volatile("s_waitcnt lgkmcnt(0)" ::: "memory")
; __device__ __forceinline__ unsigned pk2(float lo, float hi) { return pg8::cvt_pk_bf16(lo, hi); }
; __device__ __forceinline__ void tr_item(const float* W, int ldn, int N, bf16_t* WT, int ldk, const float* gain, int rbase, int rstride, LAS float* scr, int item, int lane) {
;     ...
;     for (int i = 0; i < 8; ++i) { LAS float* d = scr + (8 * i + (lane >> 3)) * 33 + 4 * (lane & 7); d[0] = v[i].x * gk[i]; d[1] = v[i].y * gk[i]; d[2] = v[i].z * gk[i]; d[3] = v[i].w * gk[i]; }
;     LDS_WAIT(); asm volatile("" ::: "memory");
;     const int c = lane & 7;
; #pragma unroll
;     for (int j = 0; j < 4; ++j) { const int n = (lane >> 3) + 8 * j; const LAS float* s = scr + (8 * c) * 33 + n;
;         u32x4 o; o.x = pk2(s[0 * 33], s[1 * 33]); o.y = pk2(s[2 * 33], s[3 * 33]); o.z = pk2(s[4 * 33], s[5 * 33]); o.w = pk2(s[6 * 33], s[7 * 33]);
;         const int nn = n0 + n, dest = rbase + (nn >> 7) * rstride + (nn & 127);
;         *(u32x4*)(WT + (size_t)dest * ldk + k0 + 8 * c) = o; }
;     LDS_WAIT(); asm volatile("" ::: "memory");
.LBB0_646:
	s_waitcnt vmcnt(0) lgkmcnt(0)
	v_pk_mul_f32 v[2:3], v[2:3], v[80:81] op_sel_hi:[1,0]
	ds_write2_b32 v87, v2, v3 offset1:1
	v_pk_mul_f32 v[2:3], v[4:5], v[80:81] op_sel_hi:[1,0]
	ds_write2_b32 v87, v2, v3 offset0:2 offset1:3
	v_pk_mul_f32 v[2:3], v[6:7], v[78:79] op_sel_hi:[1,0]
	v_add_u32_e32 v0, v85, v91
	ds_write2_b32 v0, v2, v3 offset1:1
	v_pk_mul_f32 v[2:3], v[8:9], v[78:79] op_sel_hi:[1,0]
	ds_write2_b32 v0, v2, v3 offset0:2 offset1:3
	v_pk_mul_f32 v[2:3], v[10:11], v[84:85] op_sel_hi:[1,0]
	v_add_u32_e32 v4, 0x420, v0
	ds_write2_b32 v4, v2, v3 offset1:1
	v_pk_mul_f32 v[2:3], v[12:13], v[84:85] op_sel_hi:[1,0]
	v_add_u32_e32 v4, 0x428, v0
	ds_write2_b32 v4, v2, v3 offset1:1
	v_pk_mul_f32 v[2:3], v[14:15], v[82:83] op_sel_hi:[1,0]
	v_add_u32_e32 v4, 0x840, v0
	ds_write2_b32 v4, v2, v3 offset1:1
	v_pk_mul_f32 v[2:3], v[16:17], v[82:83] op_sel_hi:[1,0]
	v_add_u32_e32 v0, 0x848, v0
	ds_write2_b32 v0, v2, v3 offset1:1
	v_pk_mul_f32 v[2:3], v[18:19], v[88:89] op_sel_hi:[1,0]
	v_add_u32_e32 v0, 0x1080, v87
	ds_write2_b32 v0, v2, v3 offset1:1
	v_pk_mul_f32 v[2:3], v[20:21], v[88:89] op_sel_hi:[1,0]
	v_add_u32_e32 v0, 0x1088, v87
	ds_write2_b32 v0, v2, v3 offset1:1
	v_pk_mul_f32 v[2:3], v[22:23], v[86:87] op_sel_hi:[1,0]
	v_add_u32_e32 v0, 0x14a0, v87
	ds_write2_b32 v0, v2, v3 offset1:1
	v_pk_mul_f32 v[2:3], v[24:25], v[86:87] op_sel_hi:[1,0]
	v_add_u32_e32 v0, 0x14a8, v87
	ds_write2_b32 v0, v2, v3 offset1:1
	v_pk_mul_f32 v[2:3], v[26:27], v[92:93] op_sel_hi:[1,0]
	v_add_u32_e32 v0, 0x18c0, v87
	ds_write2_b32 v0, v2, v3 offset1:1
	v_pk_mul_f32 v[2:3], v[28:29], v[92:93] op_sel_hi:[1,0]
	v_add_u32_e32 v0, 0x18c8, v87
	ds_write2_b32 v0, v2, v3 offset1:1
	v_pk_mul_f32 v[2:3], v[30:31], v[90:91] op_sel_hi:[1,0]
	v_add_u32_e32 v0, 0x1ce0, v87
	ds_write2_b32 v0, v2, v3 offset1:1
	v_pk_mul_f32 v[2:3], v[32:33], v[90:91] op_sel_hi:[1,0]
	v_add_u32_e32 v0, 0x1ce8, v87
	ds_write2_b32 v0, v2, v3 offset1:1
	s_waitcnt lgkmcnt(0)
	s_lshl_b32 s0, s20, 5
	s_lshl_b32 s1, s20, 6
	s_and_b32 s1, s1, 0x1f00
	s_and_b32 s0, s0, 0x60
	ds_read2_b32 v[2:3], v96 offset1:33
	s_or_b32 s0, s1, s0
	s_waitcnt lgkmcnt(0)
	v_cvt_pk_bf16_f32 v2, v2, v3
	ds_read2_b32 v[4:5], v96 offset0:66 offset1:99
	s_bitset1_b32 s0, 7
	s_and_b32 s1, 0xffff, s19
	s_waitcnt lgkmcnt(0)
	v_cvt_pk_bf16_f32 v3, v4, v5
	ds_read2_b32 v[4:5], v96 offset0:132 offset1:165
	s_lshl_b32 s46, s1, 1
	v_or_b32_e32 v0, s0, v81
	s_waitcnt lgkmcnt(0)
	v_cvt_pk_bf16_f32 v4, v4, v5
	ds_read2_b32 v[6:7], v96 offset0:198 offset1:231
	v_lshl_add_u64 v[8:9], v[70:71], 0, s[46:47]
	v_lshlrev_b32_e32 v0, 11, v0
	s_waitcnt lgkmcnt(0)
	v_cvt_pk_bf16_f32 v5, v6, v7
	v_lshl_add_u64 v[6:7], v[8:9], 0, v[0:1]
	global_store_dwordx4 v[6:7], v[2:5], off
	ds_read2_b32 v[2:3], v96 offset0:8 offset1:41
	v_or_b32_e32 v0, s0, v89
	s_waitcnt lgkmcnt(0)
	v_cvt_pk_bf16_f32 v2, v2, v3
	ds_read2_b32 v[4:5], v96 offset0:74 offset1:107
	s_waitcnt lgkmcnt(0)
	v_cvt_pk_bf16_f32 v3, v4, v5
	ds_read2_b32 v[4:5], v96 offset0:140 offset1:173
	s_waitcnt lgkmcnt(0)
	v_cvt_pk_bf16_f32 v4, v4, v5
	ds_read2_b32 v[6:7], v96 offset0:206 offset1:239
	v_lshlrev_b32_e32 v0, 11, v0
	s_waitcnt lgkmcnt(0)
	v_cvt_pk_bf16_f32 v5, v6, v7
	v_lshl_add_u64 v[6:7], v[8:9], 0, v[0:1]
	global_store_dwordx4 v[6:7], v[2:5], off
	ds_read2_b32 v[2:3], v96 offset0:16 offset1:49
	v_or_b32_e32 v0, s0, v93
	s_waitcnt lgkmcnt(0)
	v_cvt_pk_bf16_f32 v2, v2, v3
	ds_read2_b32 v[4:5], v96 offset0:82 offset1:115
	s_waitcnt lgkmcnt(0)
	v_cvt_pk_bf16_f32 v3, v4, v5
	ds_read2_b32 v[4:5], v96 offset0:148 offset1:181
	s_waitcnt lgkmcnt(0)
	v_cvt_pk_bf16_f32 v4, v4, v5
	ds_read2_b32 v[6:7], v96 offset0:214 offset1:247
	v_lshlrev_b32_e32 v0, 11, v0
	s_waitcnt lgkmcnt(0)
	v_cvt_pk_bf16_f32 v5, v6, v7
	v_lshl_add_u64 v[6:7], v[8:9], 0, v[0:1]
	global_store_dwordx4 v[6:7], v[2:5], off
	ds_read2_b32 v[2:3], v96 offset0:24 offset1:57
	v_or_b32_e32 v0, s0, v95
	s_waitcnt lgkmcnt(0)
	v_cvt_pk_bf16_f32 v2, v2, v3
	ds_read2_b32 v[4:5], v96 offset0:90 offset1:123
	s_waitcnt lgkmcnt(0)
	v_cvt_pk_bf16_f32 v3, v4, v5
	ds_read2_b32 v[4:5], v96 offset0:156 offset1:189
	s_waitcnt lgkmcnt(0)
	v_cvt_pk_bf16_f32 v4, v4, v5
	ds_read2_b32 v[6:7], v96 offset0:222 offset1:255
	v_lshlrev_b32_e32 v0, 11, v0
	s_waitcnt lgkmcnt(0)
	v_cvt_pk_bf16_f32 v5, v6, v7
	v_lshl_add_u64 v[6:7], v[8:9], 0, v[0:1]
	global_store_dwordx4 v[6:7], v[2:5], off
	s_waitcnt lgkmcnt(0)
	s_mov_b32 s5, -1

; #define LAS __attribute__((address_space(3)))
; #define LDS_WAIT() asm volatile("s_waitcnt lgkmcnt(0)" ::: "memory")
; __device__ __forceinline__ unsigned pk2(float lo, float hi) { return pg8::cvt_pk_bf16(lo, hi); }
; #define INP(i) ((const float*)ldp(T, (i)))
; #define TRJ(cnt, W, ldn, N, WT, ldk, gain, rbase, rstride) if (r >= 0) { if (r < (cnt)) { tr_item((W), (ldn), (N), (WT), (ldk), (gain), (rbase), (rstride), scr, r, lane); r = -1; } else r -= (cnt); }
; __device__ __forceinline__ void tr_item(const float* W, int ldn, int N, bf16_t* WT, int ldk, const float* gain, int rbase, int rstride, LAS float* scr, int item, int lane) {
;     const int nblk = N / 32, kb = item / nblk, nb = item % nblk, k0 = 64 * kb, n0 = 32 * nb;
;     f32x4 v[8]; float gk[8];
; #pragma unroll
;     for (int i = 0; i < 8; ++i) { const int kk = 8 * i + (lane >> 3); v[i] = *(const f32x4*)(W + (size_t)(k0 + kk) * ldn + n0 + 4 * (lane & 7)); gk[i] = gain ? gain[k0 + kk] : 1.0f; }
; #pragma unroll
;     for (int i = 0; i < 8; ++i) { LAS float* d = scr + (8 * i + (lane >> 3)) * 33 + 4 * (lane & 7); d[0] = v[i].x * gk[i]; d[1] = v[i].y * gk[i]; d[2] = v[i].z * gk[i]; d[3] = v[i].w * gk[i]; }
;     LDS_WAIT(); asm volatile("" ::: "memory");
;     const int c = lane & 7;
; #pragma unroll
;     for (int j = 0; j < 4; ++j) { const int n = (lane >> 3) + 8 * j; const LAS float* s = scr + (8 * c) * 33 + n;
;         u32x4 o; o.x = pk2(s[0 * 33], s[1 * 33]); o.y = pk2(s[2 * 33], s[3 * 33]); o.z = pk2(s[4 * 33], s[5 * 33]); o.w = pk2(s[6 * 33], s[7 * 33]);
;         const int nn = n0 + n, dest = rbase + (nn >> 7) * rstride + (nn & 127);
;         *(u32x4*)(WT + (size_t)dest * ldk + k0 + 8 * c) = o; }
;     LDS_WAIT(); asm volatile("" ::: "memory");
; __device__ __forceinline__ void prep_phase(const PT& T, LAS unsigned char* lds) {
;     ...
;             TRJ(I_DN, INP(18) + (size_t)l * D * FH, D, D, Wb + WO_F_D0 + l * WO_F_STRIDE, FH, nullptr, 0, 128)
.LBB0_651:
	s_andn2_b64 vcc, exec, s[0:1]
	s_cbranch_vccnz .LBB0_653
	v_mov_b32_e32 v0, s40
	ds_read_b64 v[2:3], v0
	s_lshl_b32 s0, s4, 1
	s_lshl_b32 s1, s4, 5
	s_and_b32 s8, s0, 0xfc0
	s_and_b32 s0, s1, 0x3e0
	s_waitcnt lgkmcnt(0)
	v_readfirstlane_b32 s4, v2
	s_lshl_b32 s1, s0, 2
	v_readfirstlane_b32 s5, v3
	s_add_u32 s4, s4, s1
	v_or_b32_e32 v4, s8, v81
	s_addc_u32 s5, s5, 0
	v_lshlrev_b32_e32 v0, 2, v34
	v_lshl_add_u64 v[2:3], s[4:5], 0, v[0:1]
	v_lshlrev_b32_e32 v0, 12, v4
	v_lshl_add_u64 v[30:31], v[2:3], 0, v[0:1]
	s_mov_b32 s1, 0x1600000
	v_add_co_u32_e32 v2, vcc, s1, v30
	s_mov_b32 s1, 0x1608000
	s_nop 0
	v_addc_co_u32_e32 v3, vcc, 0, v31, vcc
	v_add_co_u32_e32 v6, vcc, s1, v30
	s_mov_b32 s1, 0x1610000
	s_nop 0
	v_addc_co_u32_e32 v7, vcc, 0, v31, vcc
	v_add_co_u32_e32 v10, vcc, s1, v30
	s_mov_b32 s1, 0x1618000
	s_nop 0
	v_addc_co_u32_e32 v11, vcc, 0, v31, vcc
	v_add_co_u32_e32 v14, vcc, s1, v30
	s_mov_b32 s1, 0x1620000
	s_nop 0
	v_addc_co_u32_e32 v15, vcc, 0, v31, vcc
	v_add_co_u32_e32 v18, vcc, s1, v30
	s_mov_b32 s1, 0x1628000
	s_nop 0
	v_addc_co_u32_e32 v19, vcc, 0, v31, vcc
	v_add_co_u32_e32 v22, vcc, s1, v30
	global_load_dwordx4 v[2:5], v[2:3], off
	s_nop 0
	global_load_dwordx4 v[6:9], v[6:7], off
	v_addc_co_u32_e32 v23, vcc, 0, v31, vcc
	global_load_dwordx4 v[10:13], v[10:11], off
	s_nop 0
	global_load_dwordx4 v[14:17], v[14:15], off
	s_nop 0
	global_load_dwordx4 v[18:21], v[18:19], off
	s_nop 0
	global_load_dwordx4 v[22:25], v[22:23], off
	s_mov_b32 s1, 0x1630000
	v_add_co_u32_e32 v26, vcc, s1, v30
	s_mov_b32 s1, 0x1638000
	s_nop 0
	v_addc_co_u32_e32 v27, vcc, 0, v31, vcc
	global_load_dwordx4 v[26:29], v[26:27], off
	v_add_co_u32_e32 v30, vcc, s1, v30
	v_add_u32_e32 v0, v85, v91
	s_nop 0
	v_addc_co_u32_e32 v31, vcc, 0, v31, vcc
	global_load_dwordx4 v[30:33], v[30:31], off
	v_add_u32_e32 v78, 0x1080, v87
	v_add_u32_e32 v80, 0x1088, v87
	v_add_u32_e32 v82, 0x14a0, v87
	v_add_u32_e32 v83, 0x14a8, v87
	v_add_u32_e32 v84, 0x18c0, v87
	v_add_u32_e32 v86, 0x18c8, v87
	v_add_u32_e32 v88, 0x1ce0, v87
	v_add_u32_e32 v90, 0x1ce8, v87
	v_add_u32_e32 v92, 0x420, v0
	v_add_u32_e32 v94, 0x428, v0
	v_add_u32_e32 v97, 0x840, v0
	v_add_u32_e32 v98, 0x848, v0
	s_lshl_b32 s46, s8, 1
	s_mov_b32 s5, -1
	s_waitcnt vmcnt(0) lgkmcnt(0)
	ds_write2_b32 v87, v2, v3 offset1:1
	ds_write2_b32 v87, v4, v5 offset0:2 offset1:3
	ds_write2_b32 v0, v6, v7 offset1:1
	ds_write2_b32 v0, v8, v9 offset0:2 offset1:3
	ds_write2_b32 v92, v10, v11 offset1:1
	ds_write2_b32 v94, v12, v13 offset1:1
	ds_write2_b32 v97, v14, v15 offset1:1
	ds_write2_b32 v98, v16, v17 offset1:1
	ds_write2_b32 v78, v18, v19 offset1:1
	ds_write2_b32 v80, v20, v21 offset1:1
	ds_write2_b32 v82, v22, v23 offset1:1
	ds_write2_b32 v83, v24, v25 offset1:1
	ds_write2_b32 v84, v26, v27 offset1:1
	ds_write2_b32 v86, v28, v29 offset1:1
	ds_write2_b32 v88, v30, v31 offset1:1
	ds_write2_b32 v90, v32, v33 offset1:1
	s_waitcnt lgkmcnt(0)
	v_or_b32_e32 v0, s0, v81
	ds_read2_b32 v[2:3], v96 offset1:33
	v_mul_u32_u24_e32 v0, 0xb00, v0
	s_waitcnt lgkmcnt(0)
	v_cvt_pk_bf16_f32 v2, v2, v3
	ds_read2_b32 v[4:5], v96 offset0:66 offset1:99
	v_lshl_add_u64 v[8:9], v[72:73], 0, s[46:47]
	v_lshlrev_b32_e32 v0, 1, v0
	s_waitcnt lgkmcnt(0)
	v_cvt_pk_bf16_f32 v3, v4, v5
	ds_read2_b32 v[4:5], v96 offset0:132 offset1:165
	v_lshl_add_u64 v[10:11], v[8:9], 0, v[0:1]
	s_waitcnt lgkmcnt(0)
	v_cvt_pk_bf16_f32 v4, v4, v5
	ds_read2_b32 v[6:7], v96 offset0:198 offset1:231
	s_waitcnt lgkmcnt(0)
	v_cvt_pk_bf16_f32 v5, v6, v7
	global_store_dwordx4 v[10:11], v[2:5], off
	v_or_b32_e32 v0, s0, v89
	ds_read2_b32 v[2:3], v96 offset0:8 offset1:41
	v_mul_u32_u24_e32 v0, 0xb00, v0
	s_waitcnt lgkmcnt(0)
	v_cvt_pk_bf16_f32 v2, v2, v3
	ds_read2_b32 v[4:5], v96 offset0:74 offset1:107
	v_lshlrev_b32_e32 v0, 1, v0
	s_waitcnt lgkmcnt(0)
	v_cvt_pk_bf16_f32 v3, v4, v5
	ds_read2_b32 v[4:5], v96 offset0:140 offset1:173
	v_lshl_add_u64 v[10:11], v[8:9], 0, v[0:1]
	s_waitcnt lgkmcnt(0)
	v_cvt_pk_bf16_f32 v4, v4, v5
	ds_read2_b32 v[6:7], v96 offset0:206 offset1:239
	s_waitcnt lgkmcnt(0)
	v_cvt_pk_bf16_f32 v5, v6, v7
	global_store_dwordx4 v[10:11], v[2:5], off
	v_or_b32_e32 v0, s0, v93
	ds_read2_b32 v[2:3], v96 offset0:16 offset1:49
	v_mul_u32_u24_e32 v0, 0xb00, v0
	s_waitcnt lgkmcnt(0)
	v_cvt_pk_bf16_f32 v2, v2, v3
	ds_read2_b32 v[4:5], v96 offset0:82 offset1:115
	v_lshlrev_b32_e32 v0, 1, v0
	s_waitcnt lgkmcnt(0)
	v_cvt_pk_bf16_f32 v3, v4, v5
	ds_read2_b32 v[4:5], v96 offset0:148 offset1:181
	v_lshl_add_u64 v[10:11], v[8:9], 0, v[0:1]
	s_waitcnt lgkmcnt(0)
	v_cvt_pk_bf16_f32 v4, v4, v5
	ds_read2_b32 v[6:7], v96 offset0:214 offset1:247
	s_waitcnt lgkmcnt(0)
	v_cvt_pk_bf16_f32 v5, v6, v7
	global_store_dwordx4 v[10:11], v[2:5], off
	ds_read2_b32 v[2:3], v96 offset0:24 offset1:57
	v_or_b32_e32 v0, s0, v95
	s_waitcnt lgkmcnt(0)
	v_cvt_pk_bf16_f32 v2, v2, v3
	ds_read2_b32 v[4:5], v96 offset0:90 offset1:123
	s_waitcnt lgkmcnt(0)
	v_cvt_pk_bf16_f32 v3, v4, v5
	ds_read2_b32 v[4:5], v96 offset0:156 offset1:189
	v_mul_u32_u24_e32 v0, 0xb00, v0
	s_waitcnt lgkmcnt(0)
	v_cvt_pk_bf16_f32 v4, v4, v5
	ds_read2_b32 v[6:7], v96 offset0:222 offset1:255
	v_lshlrev_b32_e32 v0, 1, v0
	s_waitcnt lgkmcnt(0)
	v_cvt_pk_bf16_f32 v5, v6, v7
	v_lshl_add_u64 v[6:7], v[8:9], 0, v[0:1]
	global_store_dwordx4 v[6:7], v[2:5], off
	s_waitcnt lgkmcnt(0)

; #define LAS __attribute__((address_space(3)))
; #define INP(i) ((const float*)ldp(T, (i)))
; #define TRJ(cnt, W, ldn, N, WT, ldk, gain, rbase, rstride) if (r >= 0) { if (r < (cnt)) { tr_item((W), (ldn), (N), (WT), (ldk), (gain), (rbase), (rstride), scr, r, lane); r = -1; } else r -= (cnt); }
; __device__ __forceinline__ void tr_item(const float* W, int ldn, int N, bf16_t* WT, int ldk, const float* gain, int rbase, int rstride, LAS float* scr, int item, int lane) {
;     const int nblk = N / 32, kb = item / nblk, nb = item % nblk, k0 = 64 * kb, n0 = 32 * nb;
;     f32x4 v[8]; float gk[8];
; #pragma unroll
;     for (int i = 0; i < 8; ++i) { const int kk = 8 * i + (lane >> 3); v[i] = *(const f32x4*)(W + (size_t)(k0 + kk) * ldn + n0 + 4 * (lane & 7)); gk[i] = gain ? gain[k0 + kk] : 1.0f; }
; __device__ __forceinline__ void prep_phase(const PT& T, LAS unsigned char* lds) {
;     ...
;             TRJ(I_UP, INP(16) + (size_t)l * D * FH, FH, FH, Wb + WO_F_GU0 + l * WO_F_STRIDE, D, INP(2) + l * D, 0, 256)
.LBB0_657:
	s_andn2_b64 vcc, exec, s[0:1]
	s_cbranch_vccnz .LBB0_675
	v_mov_b32_e32 v0, s62
	ds_read_b64 v[2:3], v0
	v_mov_b32_e32 v0, s12
	ds_read_b64 v[4:5], v0
	v_lshlrev_b32_e32 v0, 2, v34
	v_mov_b32_e32 v78, 1.0
	s_waitcnt lgkmcnt(0)
	v_readfirstlane_b32 s21, v2
	v_readfirstlane_b32 s5, v3
	v_readfirstlane_b32 s0, v4
	v_readfirstlane_b32 s1, v5
	s_add_u32 s8, s0, 0x3000
	s_addc_u32 s9, s1, 0
	s_and_b32 s19, s4, 0xffff
	s_mul_i32 s19, s19, 0xba2f
	s_lshr_b32 s22, s19, 16
	s_lshr_b32 s19, s19, 22
	s_mulk_i32 s19, 0x58
	s_sub_i32 s4, s4, s19
	s_and_b32 s20, s4, 0xffff
	s_and_b32 s19, s22, 0xffc0
	s_lshl_b32 s4, s20, 7
	s_add_u32 s4, s21, s4
	v_or_b32_e32 v83, s19, v81
	s_addc_u32 s5, s5, 0
	v_lshl_add_u64 v[2:3], s[4:5], 0, v[0:1]
	s_mov_b64 s[4:5], 0x2100000
	v_mul_u32_u24_e32 v14, 0xb00, v83
	v_lshl_add_u64 v[30:31], v[2:3], 0, s[4:5]
	v_lshlrev_b32_e32 v0, 2, v14
	v_lshl_add_u64 v[10:11], v[30:31], 0, v[0:1]
	global_load_dwordx4 v[2:5], v[10:11], off
	s_cmp_lg_u64 s[0:1], 0
	s_cselect_b64 s[4:5], -1, 0
	s_cmp_eq_u64 s[0:1], 0
	v_mov_b32_e32 v80, 1.0
	s_cbranch_scc1 .LBB0_660
	v_lshlrev_b32_e32 v0, 2, v83
	v_lshl_add_u64 v[6:7], s[8:9], 0, v[0:1]
	global_load_dword v80, v[6:7], off

; #define LAS __attribute__((address_space(3)))
; #define LDS_WAIT() asm volatile("s_waitcnt lgkmcnt(0)" ::: "memory")
; __device__ __forceinline__ unsigned pk2(float lo, float hi) { return pg8::cvt_pk_bf16(lo, hi); }
; #define INP(i) ((const float*)ldp(T, (i)))
; #define TRJ(cnt, W, ldn, N, WT, ldk, gain, rbase, rstride) if (r >= 0) { if (r < (cnt)) { tr_item((W), (ldn), (N), (WT), (ldk), (gain), (rbase), (rstride), scr, r, lane); r = -1; } else r -= (cnt); }
; __device__ __forceinline__ void tr_item(const float* W, int ldn, int N, bf16_t* WT, int ldk, const float* gain, int rbase, int rstride, LAS float* scr, int item, int lane) {
;     ...
; #pragma unroll
;     for (int i = 0; i < 8; ++i) { LAS float* d = scr + (8 * i + (lane >> 3)) * 33 + 4 * (lane & 7); d[0] = v[i].x * gk[i]; d[1] = v[i].y * gk[i]; d[2] = v[i].z * gk[i]; d[3] = v[i].w * gk[i]; }
;     LDS_WAIT(); asm volatile("" ::: "memory");
;     const int c = lane & 7;
; #pragma unroll
;     for (int j = 0; j < 4; ++j) { const int n = (lane >> 3) + 8 * j; const LAS float* s = scr + (8 * c) * 33 + n;
;         u32x4 o; o.x = pk2(s[0 * 33], s[1 * 33]); o.y = pk2(s[2 * 33], s[3 * 33]); o.z = pk2(s[4 * 33], s[5 * 33]); o.w = pk2(s[6 * 33], s[7 * 33]);
;         const int nn = n0 + n, dest = rbase + (nn >> 7) * rstride + (nn & 127);
;         *(u32x4*)(WT + (size_t)dest * ldk + k0 + 8 * c) = o; }
;     LDS_WAIT(); asm volatile("" ::: "memory");
; __device__ __forceinline__ void prep_phase(const PT& T, LAS unsigned char* lds) {
;     ...
;             TRJ(I_UP, INP(16) + (size_t)l * D * FH, FH, FH, Wb + WO_F_GU0 + l * WO_F_STRIDE, D, INP(2) + l * D, 0, 256)
.LBB0_674:
	s_waitcnt vmcnt(0) lgkmcnt(0)
	v_pk_mul_f32 v[2:3], v[2:3], v[80:81] op_sel_hi:[1,0]
	ds_write2_b32 v87, v2, v3 offset1:1
	v_pk_mul_f32 v[2:3], v[4:5], v[80:81] op_sel_hi:[1,0]
	ds_write2_b32 v87, v2, v3 offset0:2 offset1:3
	v_pk_mul_f32 v[2:3], v[6:7], v[78:79] op_sel_hi:[1,0]
	v_add_u32_e32 v0, v85, v91
	ds_write2_b32 v0, v2, v3 offset1:1
	v_pk_mul_f32 v[2:3], v[8:9], v[78:79] op_sel_hi:[1,0]
	ds_write2_b32 v0, v2, v3 offset0:2 offset1:3
	v_pk_mul_f32 v[2:3], v[10:11], v[84:85] op_sel_hi:[1,0]
	v_add_u32_e32 v4, 0x420, v0
	ds_write2_b32 v4, v2, v3 offset1:1
	v_pk_mul_f32 v[2:3], v[12:13], v[84:85] op_sel_hi:[1,0]
	v_add_u32_e32 v4, 0x428, v0
	ds_write2_b32 v4, v2, v3 offset1:1
	v_pk_mul_f32 v[2:3], v[14:15], v[82:83] op_sel_hi:[1,0]
	v_add_u32_e32 v4, 0x840, v0
	ds_write2_b32 v4, v2, v3 offset1:1
	v_pk_mul_f32 v[2:3], v[16:17], v[82:83] op_sel_hi:[1,0]
	v_add_u32_e32 v0, 0x848, v0
	ds_write2_b32 v0, v2, v3 offset1:1
	v_pk_mul_f32 v[2:3], v[18:19], v[88:89] op_sel_hi:[1,0]
	v_add_u32_e32 v0, 0x1080, v87
	ds_write2_b32 v0, v2, v3 offset1:1
	v_pk_mul_f32 v[2:3], v[20:21], v[88:89] op_sel_hi:[1,0]
	v_add_u32_e32 v0, 0x1088, v87
	ds_write2_b32 v0, v2, v3 offset1:1
	v_pk_mul_f32 v[2:3], v[22:23], v[86:87] op_sel_hi:[1,0]
	v_add_u32_e32 v0, 0x14a0, v87
	ds_write2_b32 v0, v2, v3 offset1:1
	v_pk_mul_f32 v[2:3], v[24:25], v[86:87] op_sel_hi:[1,0]
	v_add_u32_e32 v0, 0x14a8, v87
	ds_write2_b32 v0, v2, v3 offset1:1
	v_pk_mul_f32 v[2:3], v[26:27], v[92:93] op_sel_hi:[1,0]
	v_add_u32_e32 v0, 0x18c0, v87
	ds_write2_b32 v0, v2, v3 offset1:1
	v_pk_mul_f32 v[2:3], v[28:29], v[92:93] op_sel_hi:[1,0]
	v_add_u32_e32 v0, 0x18c8, v87
	ds_write2_b32 v0, v2, v3 offset1:1
	v_pk_mul_f32 v[2:3], v[30:31], v[90:91] op_sel_hi:[1,0]
	v_add_u32_e32 v0, 0x1ce0, v87
	ds_write2_b32 v0, v2, v3 offset1:1
	v_pk_mul_f32 v[2:3], v[32:33], v[90:91] op_sel_hi:[1,0]
	v_add_u32_e32 v0, 0x1ce8, v87
	ds_write2_b32 v0, v2, v3 offset1:1
	s_waitcnt lgkmcnt(0)
	s_lshl_b32 s0, s20, 5
	s_lshl_b32 s1, s20, 6
	ds_read2_b32 v[2:3], v96 offset1:33
	s_and_b32 s1, s1, 0x1f00
	s_and_b32 s0, s0, 0x60
	s_waitcnt lgkmcnt(0)
	v_cvt_pk_bf16_f32 v2, v2, v3
	ds_read2_b32 v[4:5], v96 offset0:66 offset1:99
	s_or_b32 s0, s1, s0
	s_and_b32 s1, 0xffff, s19
	s_waitcnt lgkmcnt(0)
	v_cvt_pk_bf16_f32 v3, v4, v5
	ds_read2_b32 v[4:5], v96 offset0:132 offset1:165
	s_lshl_b32 s46, s1, 1
	v_or_b32_e32 v0, s0, v81
	s_waitcnt lgkmcnt(0)
	v_cvt_pk_bf16_f32 v4, v4, v5
	ds_read2_b32 v[6:7], v96 offset0:198 offset1:231
	v_lshl_add_u64 v[8:9], v[74:75], 0, s[46:47]
	v_lshlrev_b32_e32 v0, 11, v0
	s_waitcnt lgkmcnt(0)
	v_cvt_pk_bf16_f32 v5, v6, v7
	v_lshl_add_u64 v[6:7], v[8:9], 0, v[0:1]
	global_store_dwordx4 v[6:7], v[2:5], off
	ds_read2_b32 v[2:3], v96 offset0:8 offset1:41
	v_or_b32_e32 v0, s0, v89
	s_waitcnt lgkmcnt(0)
	v_cvt_pk_bf16_f32 v2, v2, v3
	ds_read2_b32 v[4:5], v96 offset0:74 offset1:107
	s_waitcnt lgkmcnt(0)
	v_cvt_pk_bf16_f32 v3, v4, v5
	ds_read2_b32 v[4:5], v96 offset0:140 offset1:173
	s_waitcnt lgkmcnt(0)
	v_cvt_pk_bf16_f32 v4, v4, v5
	ds_read2_b32 v[6:7], v96 offset0:206 offset1:239
	v_lshlrev_b32_e32 v0, 11, v0
	s_waitcnt lgkmcnt(0)
	v_cvt_pk_bf16_f32 v5, v6, v7
	v_lshl_add_u64 v[6:7], v[8:9], 0, v[0:1]
	global_store_dwordx4 v[6:7], v[2:5], off
	ds_read2_b32 v[2:3], v96 offset0:16 offset1:49
	v_or_b32_e32 v0, s0, v93
	s_waitcnt lgkmcnt(0)
	v_cvt_pk_bf16_f32 v2, v2, v3
	ds_read2_b32 v[4:5], v96 offset0:82 offset1:115
	s_waitcnt lgkmcnt(0)
	v_cvt_pk_bf16_f32 v3, v4, v5
	ds_read2_b32 v[4:5], v96 offset0:148 offset1:181
	s_waitcnt lgkmcnt(0)
	v_cvt_pk_bf16_f32 v4, v4, v5
	ds_read2_b32 v[6:7], v96 offset0:214 offset1:247
	v_lshlrev_b32_e32 v0, 11, v0
	s_waitcnt lgkmcnt(0)
	v_cvt_pk_bf16_f32 v5, v6, v7
	v_lshl_add_u64 v[6:7], v[8:9], 0, v[0:1]
	global_store_dwordx4 v[6:7], v[2:5], off
	ds_read2_b32 v[2:3], v96 offset0:24 offset1:57
	v_or_b32_e32 v0, s0, v95
	s_waitcnt lgkmcnt(0)
	v_cvt_pk_bf16_f32 v2, v2, v3
	ds_read2_b32 v[4:5], v96 offset0:90 offset1:123
	s_waitcnt lgkmcnt(0)
	v_cvt_pk_bf16_f32 v3, v4, v5
	ds_read2_b32 v[4:5], v96 offset0:156 offset1:189
	s_waitcnt lgkmcnt(0)
	v_cvt_pk_bf16_f32 v4, v4, v5
	ds_read2_b32 v[6:7], v96 offset0:222 offset1:255
	v_lshlrev_b32_e32 v0, 11, v0
	s_waitcnt lgkmcnt(0)
	v_cvt_pk_bf16_f32 v5, v6, v7
	v_lshl_add_u64 v[6:7], v[8:9], 0, v[0:1]
	global_store_dwordx4 v[6:7], v[2:5], off
	s_waitcnt lgkmcnt(0)
	s_mov_b32 s5, -1

; #define LAS __attribute__((address_space(3)))
; #define INP(i) ((const float*)ldp(T, (i)))
; #define TRJ(cnt, W, ldn, N, WT, ldk, gain, rbase, rstride) if (r >= 0) { if (r < (cnt)) { tr_item((W), (ldn), (N), (WT), (ldk), (gain), (rbase), (rstride), scr, r, lane); r = -1; } else r -= (cnt); }
; __device__ __forceinline__ void tr_item(const float* W, int ldn, int N, bf16_t* WT, int ldk, const float* gain, int rbase, int rstride, LAS float* scr, int item, int lane) {
;     const int nblk = N / 32, kb = item / nblk, nb = item % nblk, k0 = 64 * kb, n0 = 32 * nb;
;     f32x4 v[8]; float gk[8];
; #pragma unroll
;     for (int i = 0; i < 8; ++i) { const int kk = 8 * i + (lane >> 3); v[i] = *(const f32x4*)(W + (size_t)(k0 + kk) * ldn + n0 + 4 * (lane & 7)); gk[i] = gain ? gain[k0 + kk] : 1.0f; }
; __device__ __forceinline__ void prep_phase(const PT& T, LAS unsigned char* lds) {
;     ...
;             TRJ(I_UP, INP(17) + (size_t)l * D * FH, FH, FH, Wb + WO_F_GU0 + l * WO_F_STRIDE, D, INP(2) + l * D, 128, 256)
.LBB0_679:
	s_andn2_b64 vcc, exec, s[0:1]
	s_cbranch_vccnz .LBB0_697
	v_mov_b32_e32 v0, s13
	ds_read_b64 v[2:3], v0
	v_mov_b32_e32 v0, s12
	ds_read_b64 v[4:5], v0
	v_lshlrev_b32_e32 v0, 2, v34
	v_mov_b32_e32 v78, 1.0
	s_waitcnt lgkmcnt(0)
	v_readfirstlane_b32 s21, v2
	v_readfirstlane_b32 s5, v3
	v_readfirstlane_b32 s0, v4
	v_readfirstlane_b32 s1, v5
	s_add_u32 s8, s0, 0x3000
	s_addc_u32 s9, s1, 0
	s_and_b32 s19, s4, 0xffff
	s_mul_i32 s19, s19, 0xba2f
	s_lshr_b32 s22, s19, 16
	s_lshr_b32 s19, s19, 22
	s_mulk_i32 s19, 0x58
	s_sub_i32 s4, s4, s19
	s_and_b32 s20, s4, 0xffff
	s_and_b32 s19, s22, 0xffc0
	s_lshl_b32 s4, s20, 7
	s_add_u32 s4, s21, s4
	v_or_b32_e32 v83, s19, v81
	s_addc_u32 s5, s5, 0
	v_lshl_add_u64 v[2:3], s[4:5], 0, v[0:1]
	s_mov_b64 s[4:5], 0x2100000
	v_mul_u32_u24_e32 v14, 0xb00, v83
	v_lshl_add_u64 v[30:31], v[2:3], 0, s[4:5]
	v_lshlrev_b32_e32 v0, 2, v14
	v_lshl_add_u64 v[10:11], v[30:31], 0, v[0:1]
	global_load_dwordx4 v[2:5], v[10:11], off
	s_cmp_lg_u64 s[0:1], 0
	s_cselect_b64 s[4:5], -1, 0
	s_cmp_eq_u64 s[0:1], 0
	v_mov_b32_e32 v80, 1.0
	s_cbranch_scc1 .LBB0_682
	v_lshlrev_b32_e32 v0, 2, v83
	v_lshl_add_u64 v[6:7], s[8:9], 0, v[0:1]
	global_load_dword v80, v[6:7], off

; #define LAS __attribute__((address_space(3)))
; #define LDS_WAIT() asm volatile("s_waitcnt lgkmcnt(0)" ::: "memory")
; __device__ __forceinline__ unsigned pk2(float lo, float hi) { return pg8::cvt_pk_bf16(lo, hi); }
; #define INP(i) ((const float*)ldp(T, (i)))
; #define TRJ(cnt, W, ldn, N, WT, ldk, gain, rbase, rstride) if (r >= 0) { if (r < (cnt)) { tr_item((W), (ldn), (N), (WT), (ldk), (gain), (rbase), (rstride), scr, r, lane); r = -1; } else r -= (cnt); }
; __device__ __forceinline__ void tr_item(const float* W, int ldn, int N, bf16_t* WT, int ldk, const float* gain, int rbase, int rstride, LAS float* scr, int item, int lane) {
;     ...
; #pragma unroll
;     for (int i = 0; i < 8; ++i) { LAS float* d = scr + (8 * i + (lane >> 3)) * 33 + 4 * (lane & 7); d[0] = v[i].x * gk[i]; d[1] = v[i].y * gk[i]; d[2] = v[i].z * gk[i]; d[3] = v[i].w * gk[i]; }
;     LDS_WAIT(); asm volatile("" ::: "memory");
;     const int c = lane & 7;
; #pragma unroll
;     for (int j = 0; j < 4; ++j) { const int n = (lane >> 3) + 8 * j; const LAS float* s = scr + (8 * c) * 33 + n;
;         u32x4 o; o.x = pk2(s[0 * 33], s[1 * 33]); o.y = pk2(s[2 * 33], s[3 * 33]); o.z = pk2(s[4 * 33], s[5 * 33]); o.w = pk2(s[6 * 33], s[7 * 33]);
;         const int nn = n0 + n, dest = rbase + (nn >> 7) * rstride + (nn & 127);
;         *(u32x4*)(WT + (size_t)dest * ldk + k0 + 8 * c) = o; }
;     LDS_WAIT(); asm volatile("" ::: "memory");
; __device__ __forceinline__ void prep_phase(const PT& T, LAS unsigned char* lds) {
;     ...
;             TRJ(I_UP, INP(17) + (size_t)l * D * FH, FH, FH, Wb + WO_F_GU0 + l * WO_F_STRIDE, D, INP(2) + l * D, 128, 256)
.LBB0_696:
	s_waitcnt vmcnt(0) lgkmcnt(0)
	v_pk_mul_f32 v[2:3], v[2:3], v[80:81] op_sel_hi:[1,0]
	ds_write2_b32 v87, v2, v3 offset1:1
	v_pk_mul_f32 v[2:3], v[4:5], v[80:81] op_sel_hi:[1,0]
	ds_write2_b32 v87, v2, v3 offset0:2 offset1:3
	v_pk_mul_f32 v[2:3], v[6:7], v[78:79] op_sel_hi:[1,0]
	v_add_u32_e32 v0, v85, v91
	ds_write2_b32 v0, v2, v3 offset1:1
	v_pk_mul_f32 v[2:3], v[8:9], v[78:79] op_sel_hi:[1,0]
	ds_write2_b32 v0, v2, v3 offset0:2 offset1:3
	v_pk_mul_f32 v[2:3], v[10:11], v[84:85] op_sel_hi:[1,0]
	v_add_u32_e32 v4, 0x420, v0
	ds_write2_b32 v4, v2, v3 offset1:1
	v_pk_mul_f32 v[2:3], v[12:13], v[84:85] op_sel_hi:[1,0]
	v_add_u32_e32 v4, 0x428, v0
	ds_write2_b32 v4, v2, v3 offset1:1
	v_pk_mul_f32 v[2:3], v[14:15], v[82:83] op_sel_hi:[1,0]
	v_add_u32_e32 v4, 0x840, v0
	ds_write2_b32 v4, v2, v3 offset1:1
	v_pk_mul_f32 v[2:3], v[16:17], v[82:83] op_sel_hi:[1,0]
	v_add_u32_e32 v0, 0x848, v0
	ds_write2_b32 v0, v2, v3 offset1:1
	v_pk_mul_f32 v[2:3], v[18:19], v[88:89] op_sel_hi:[1,0]
	v_add_u32_e32 v0, 0x1080, v87
	ds_write2_b32 v0, v2, v3 offset1:1
	v_pk_mul_f32 v[2:3], v[20:21], v[88:89] op_sel_hi:[1,0]
	v_add_u32_e32 v0, 0x1088, v87
	ds_write2_b32 v0, v2, v3 offset1:1
	v_pk_mul_f32 v[2:3], v[22:23], v[86:87] op_sel_hi:[1,0]
	v_add_u32_e32 v0, 0x14a0, v87
	ds_write2_b32 v0, v2, v3 offset1:1
	v_pk_mul_f32 v[2:3], v[24:25], v[86:87] op_sel_hi:[1,0]
	v_add_u32_e32 v0, 0x14a8, v87
	ds_write2_b32 v0, v2, v3 offset1:1
	v_pk_mul_f32 v[2:3], v[26:27], v[92:93] op_sel_hi:[1,0]
	v_add_u32_e32 v0, 0x18c0, v87
	ds_write2_b32 v0, v2, v3 offset1:1
	v_pk_mul_f32 v[2:3], v[28:29], v[92:93] op_sel_hi:[1,0]
	v_add_u32_e32 v0, 0x18c8, v87
	ds_write2_b32 v0, v2, v3 offset1:1
	v_pk_mul_f32 v[2:3], v[30:31], v[90:91] op_sel_hi:[1,0]
	v_add_u32_e32 v0, 0x1ce0, v87
	ds_write2_b32 v0, v2, v3 offset1:1
	v_pk_mul_f32 v[2:3], v[32:33], v[90:91] op_sel_hi:[1,0]
	v_add_u32_e32 v0, 0x1ce8, v87
	ds_write2_b32 v0, v2, v3 offset1:1
	s_waitcnt lgkmcnt(0)
	s_lshl_b32 s0, s20, 5
	s_lshl_b32 s1, s20, 6
	s_and_b32 s1, s1, 0x1f00
	s_and_b32 s0, s0, 0x60
	ds_read2_b32 v[2:3], v96 offset1:33
	s_or_b32 s0, s1, s0
	s_waitcnt lgkmcnt(0)
	v_cvt_pk_bf16_f32 v2, v2, v3
	ds_read2_b32 v[4:5], v96 offset0:66 offset1:99
	s_bitset1_b32 s0, 7
	s_and_b32 s1, 0xffff, s19
	s_waitcnt lgkmcnt(0)
	v_cvt_pk_bf16_f32 v3, v4, v5
	ds_read2_b32 v[4:5], v96 offset0:132 offset1:165
	s_lshl_b32 s46, s1, 1
	v_or_b32_e32 v0, s0, v81
	s_waitcnt lgkmcnt(0)
	v_cvt_pk_bf16_f32 v4, v4, v5
	ds_read2_b32 v[6:7], v96 offset0:198 offset1:231
	v_lshl_add_u64 v[8:9], v[74:75], 0, s[46:47]
	v_lshlrev_b32_e32 v0, 11, v0
	s_waitcnt lgkmcnt(0)
	v_cvt_pk_bf16_f32 v5, v6, v7
	v_lshl_add_u64 v[6:7], v[8:9], 0, v[0:1]
	global_store_dwordx4 v[6:7], v[2:5], off
	ds_read2_b32 v[2:3], v96 offset0:8 offset1:41
	v_or_b32_e32 v0, s0, v89
	s_waitcnt lgkmcnt(0)
	v_cvt_pk_bf16_f32 v2, v2, v3
	ds_read2_b32 v[4:5], v96 offset0:74 offset1:107
	s_waitcnt lgkmcnt(0)
	v_cvt_pk_bf16_f32 v3, v4, v5
	ds_read2_b32 v[4:5], v96 offset0:140 offset1:173
	s_waitcnt lgkmcnt(0)
	v_cvt_pk_bf16_f32 v4, v4, v5
	ds_read2_b32 v[6:7], v96 offset0:206 offset1:239
	v_lshlrev_b32_e32 v0, 11, v0
	s_waitcnt lgkmcnt(0)
	v_cvt_pk_bf16_f32 v5, v6, v7
	v_lshl_add_u64 v[6:7], v[8:9], 0, v[0:1]
	global_store_dwordx4 v[6:7], v[2:5], off
	ds_read2_b32 v[2:3], v96 offset0:16 offset1:49
	v_or_b32_e32 v0, s0, v93
	s_waitcnt lgkmcnt(0)
	v_cvt_pk_bf16_f32 v2, v2, v3
	ds_read2_b32 v[4:5], v96 offset0:82 offset1:115
	s_waitcnt lgkmcnt(0)
	v_cvt_pk_bf16_f32 v3, v4, v5
	ds_read2_b32 v[4:5], v96 offset0:148 offset1:181
	s_waitcnt lgkmcnt(0)
	v_cvt_pk_bf16_f32 v4, v4, v5
	ds_read2_b32 v[6:7], v96 offset0:214 offset1:247
	v_lshlrev_b32_e32 v0, 11, v0
	s_waitcnt lgkmcnt(0)
	v_cvt_pk_bf16_f32 v5, v6, v7
	v_lshl_add_u64 v[6:7], v[8:9], 0, v[0:1]
	global_store_dwordx4 v[6:7], v[2:5], off
	ds_read2_b32 v[2:3], v96 offset0:24 offset1:57
	v_or_b32_e32 v0, s0, v95
	s_waitcnt lgkmcnt(0)
	v_cvt_pk_bf16_f32 v2, v2, v3
	ds_read2_b32 v[4:5], v96 offset0:90 offset1:123
	s_waitcnt lgkmcnt(0)
	v_cvt_pk_bf16_f32 v3, v4, v5
	ds_read2_b32 v[4:5], v96 offset0:156 offset1:189
	s_waitcnt lgkmcnt(0)
	v_cvt_pk_bf16_f32 v4, v4, v5
	ds_read2_b32 v[6:7], v96 offset0:222 offset1:255
	v_lshlrev_b32_e32 v0, 11, v0
	s_waitcnt lgkmcnt(0)
	v_cvt_pk_bf16_f32 v5, v6, v7
	v_lshl_add_u64 v[6:7], v[8:9], 0, v[0:1]
	global_store_dwordx4 v[6:7], v[2:5], off
	s_waitcnt lgkmcnt(0)
	s_mov_b32 s5, -1

; #define LAS __attribute__((address_space(3)))
; #define LDS_WAIT() asm volatile("s_waitcnt lgkmcnt(0)" ::: "memory")
; __device__ __forceinline__ unsigned pk2(float lo, float hi) { return pg8::cvt_pk_bf16(lo, hi); }
; #define INP(i) ((const float*)ldp(T, (i)))
; #define TRJ(cnt, W, ldn, N, WT, ldk, gain, rbase, rstride) if (r >= 0) { if (r < (cnt)) { tr_item((W), (ldn), (N), (WT), (ldk), (gain), (rbase), (rstride), scr, r, lane); r = -1; } else r -= (cnt); }
; __device__ __forceinline__ void tr_item(const float* W, int ldn, int N, bf16_t* WT, int ldk, const float* gain, int rbase, int rstride, LAS float* scr, int item, int lane) {
;     const int nblk = N / 32, kb = item / nblk, nb = item % nblk, k0 = 64 * kb, n0 = 32 * nb;
;     f32x4 v[8]; float gk[8];
; #pragma unroll
;     for (int i = 0; i < 8; ++i) { const int kk = 8 * i + (lane >> 3); v[i] = *(const f32x4*)(W + (size_t)(k0 + kk) * ldn + n0 + 4 * (lane & 7)); gk[i] = gain ? gain[k0 + kk] : 1.0f; }
; #pragma unroll
;     for (int i = 0; i < 8; ++i) { LAS float* d = scr + (8 * i + (lane >> 3)) * 33 + 4 * (lane & 7); d[0] = v[i].x * gk[i]; d[1] = v[i].y * gk[i]; d[2] = v[i].z * gk[i]; d[3] = v[i].w * gk[i]; }
;     LDS_WAIT(); asm volatile("" ::: "memory");
;     const int c = lane & 7;
; #pragma unroll
;     for (int j = 0; j < 4; ++j) { const int n = (lane >> 3) + 8 * j; const LAS float* s = scr + (8 * c) * 33 + n;
;         u32x4 o; o.x = pk2(s[0 * 33], s[1 * 33]); o.y = pk2(s[2 * 33], s[3 * 33]); o.z = pk2(s[4 * 33], s[5 * 33]); o.w = pk2(s[6 * 33], s[7 * 33]);
;         const int nn = n0 + n, dest = rbase + (nn >> 7) * rstride + (nn & 127);
;         *(u32x4*)(WT + (size_t)dest * ldk + k0 + 8 * c) = o; }
;     LDS_WAIT(); asm volatile("" ::: "memory");
; __device__ __forceinline__ void prep_phase(const PT& T, LAS unsigned char* lds) {
;     ...
;             TRJ(I_DN, INP(18) + (size_t)l * D * FH, D, D, Wb + WO_F_D0 + l * WO_F_STRIDE, FH, nullptr, 0, 128)
.LBB0_698:
	s_cmp_lt_i32 s4, 0
	s_cbranch_scc1 .LBB0_404
	v_mov_b32_e32 v0, s40
	ds_read_b64 v[2:3], v0
	s_lshl_b32 s0, s4, 1
	s_lshl_b32 s1, s4, 5
	s_and_b32 s8, s0, 0xfc0
	s_and_b32 s0, s1, 0x3e0
	s_waitcnt lgkmcnt(0)
	v_readfirstlane_b32 s4, v2
	s_lshl_b32 s1, s0, 2
	v_readfirstlane_b32 s5, v3
	s_add_u32 s4, s4, s1
	v_or_b32_e32 v4, s8, v81
	s_addc_u32 s5, s5, 0
	v_lshlrev_b32_e32 v0, 2, v34
	v_lshl_add_u64 v[2:3], s[4:5], 0, v[0:1]
	v_lshlrev_b32_e32 v0, 12, v4
	v_lshl_add_u64 v[30:31], v[2:3], 0, v[0:1]
	s_mov_b32 s1, 0x2100000
	v_add_co_u32_e32 v2, vcc, s1, v30
	s_mov_b32 s1, 0x2108000
	s_nop 0
	v_addc_co_u32_e32 v3, vcc, 0, v31, vcc
	v_add_co_u32_e32 v6, vcc, s1, v30
	s_mov_b32 s1, 0x2110000
	s_nop 0
	v_addc_co_u32_e32 v7, vcc, 0, v31, vcc
	v_add_co_u32_e32 v10, vcc, s1, v30
	s_mov_b32 s1, 0x2118000
	s_nop 0
	v_addc_co_u32_e32 v11, vcc, 0, v31, vcc
	v_add_co_u32_e32 v14, vcc, s1, v30
	s_mov_b32 s1, 0x2120000
	s_nop 0
	v_addc_co_u32_e32 v15, vcc, 0, v31, vcc
	v_add_co_u32_e32 v18, vcc, s1, v30
	s_mov_b32 s1, 0x2128000
	s_nop 0
	v_addc_co_u32_e32 v19, vcc, 0, v31, vcc
	v_add_co_u32_e32 v22, vcc, s1, v30
	global_load_dwordx4 v[2:5], v[2:3], off
	s_nop 0
	global_load_dwordx4 v[6:9], v[6:7], off
	v_addc_co_u32_e32 v23, vcc, 0, v31, vcc
	global_load_dwordx4 v[10:13], v[10:11], off
	s_nop 0
	global_load_dwordx4 v[14:17], v[14:15], off
	s_nop 0
	global_load_dwordx4 v[18:21], v[18:19], off
	s_nop 0
	global_load_dwordx4 v[22:25], v[22:23], off
	s_mov_b32 s1, 0x2130000
	v_add_co_u32_e32 v26, vcc, s1, v30
	s_mov_b32 s1, 0x2138000
	s_nop 0
	v_addc_co_u32_e32 v27, vcc, 0, v31, vcc
	global_load_dwordx4 v[26:29], v[26:27], off
	v_add_co_u32_e32 v30, vcc, s1, v30
	v_add_u32_e32 v0, v85, v91
	s_nop 0
	v_addc_co_u32_e32 v31, vcc, 0, v31, vcc
	global_load_dwordx4 v[30:33], v[30:31], off
	v_add_u32_e32 v78, 0x1080, v87
	v_add_u32_e32 v80, 0x1088, v87
	v_add_u32_e32 v82, 0x14a0, v87
	v_add_u32_e32 v83, 0x14a8, v87
	v_add_u32_e32 v84, 0x18c0, v87
	v_add_u32_e32 v86, 0x18c8, v87
	v_add_u32_e32 v88, 0x1ce0, v87
	v_add_u32_e32 v90, 0x1ce8, v87
	v_add_u32_e32 v92, 0x420, v0
	v_add_u32_e32 v94, 0x428, v0
	v_add_u32_e32 v97, 0x840, v0
	v_add_u32_e32 v98, 0x848, v0
	s_lshl_b32 s46, s8, 1
	s_waitcnt vmcnt(0) lgkmcnt(0)
	ds_write2_b32 v87, v2, v3 offset1:1
	ds_write2_b32 v87, v4, v5 offset0:2 offset1:3
	ds_write2_b32 v0, v6, v7 offset1:1
	ds_write2_b32 v0, v8, v9 offset0:2 offset1:3
	ds_write2_b32 v92, v10, v11 offset1:1
	ds_write2_b32 v94, v12, v13 offset1:1
	ds_write2_b32 v97, v14, v15 offset1:1
	ds_write2_b32 v98, v16, v17 offset1:1
	ds_write2_b32 v78, v18, v19 offset1:1
	ds_write2_b32 v80, v20, v21 offset1:1
	ds_write2_b32 v82, v22, v23 offset1:1
	ds_write2_b32 v83, v24, v25 offset1:1
	ds_write2_b32 v84, v26, v27 offset1:1
	ds_write2_b32 v86, v28, v29 offset1:1
	ds_write2_b32 v88, v30, v31 offset1:1
	ds_write2_b32 v90, v32, v33 offset1:1
	s_waitcnt lgkmcnt(0)
	v_or_b32_e32 v0, s0, v81
	ds_read2_b32 v[2:3], v96 offset1:33
	v_mul_u32_u24_e32 v0, 0xb00, v0
	s_waitcnt lgkmcnt(0)
	v_cvt_pk_bf16_f32 v2, v2, v3
	ds_read2_b32 v[4:5], v96 offset0:66 offset1:99
	v_lshl_add_u64 v[8:9], v[76:77], 0, s[46:47]
	v_lshlrev_b32_e32 v0, 1, v0
	s_waitcnt lgkmcnt(0)
	v_cvt_pk_bf16_f32 v3, v4, v5
	ds_read2_b32 v[4:5], v96 offset0:132 offset1:165
	v_lshl_add_u64 v[10:11], v[8:9], 0, v[0:1]
	s_waitcnt lgkmcnt(0)
	v_cvt_pk_bf16_f32 v4, v4, v5
	ds_read2_b32 v[6:7], v96 offset0:198 offset1:231
	s_waitcnt lgkmcnt(0)
	v_cvt_pk_bf16_f32 v5, v6, v7
	global_store_dwordx4 v[10:11], v[2:5], off
	v_or_b32_e32 v0, s0, v89
	ds_read2_b32 v[2:3], v96 offset0:8 offset1:41
	v_mul_u32_u24_e32 v0, 0xb00, v0
	s_waitcnt lgkmcnt(0)
	v_cvt_pk_bf16_f32 v2, v2, v3
	ds_read2_b32 v[4:5], v96 offset0:74 offset1:107
	v_lshlrev_b32_e32 v0, 1, v0
	s_waitcnt lgkmcnt(0)
	v_cvt_pk_bf16_f32 v3, v4, v5
	ds_read2_b32 v[4:5], v96 offset0:140 offset1:173
	v_lshl_add_u64 v[10:11], v[8:9], 0, v[0:1]
	s_waitcnt lgkmcnt(0)
	v_cvt_pk_bf16_f32 v4, v4, v5
	ds_read2_b32 v[6:7], v96 offset0:206 offset1:239
	s_waitcnt lgkmcnt(0)
	v_cvt_pk_bf16_f32 v5, v6, v7
	global_store_dwordx4 v[10:11], v[2:5], off
	v_or_b32_e32 v0, s0, v93
	ds_read2_b32 v[2:3], v96 offset0:16 offset1:49
	v_mul_u32_u24_e32 v0, 0xb00, v0
	s_waitcnt lgkmcnt(0)
	v_cvt_pk_bf16_f32 v2, v2, v3
	ds_read2_b32 v[4:5], v96 offset0:82 offset1:115
	v_lshlrev_b32_e32 v0, 1, v0
	s_waitcnt lgkmcnt(0)
	v_cvt_pk_bf16_f32 v3, v4, v5
	ds_read2_b32 v[4:5], v96 offset0:148 offset1:181
	v_lshl_add_u64 v[10:11], v[8:9], 0, v[0:1]
	s_waitcnt lgkmcnt(0)
	v_cvt_pk_bf16_f32 v4, v4, v5
	ds_read2_b32 v[6:7], v96 offset0:214 offset1:247
	s_waitcnt lgkmcnt(0)
	v_cvt_pk_bf16_f32 v5, v6, v7
	global_store_dwordx4 v[10:11], v[2:5], off
	ds_read2_b32 v[2:3], v96 offset0:24 offset1:57
	v_or_b32_e32 v0, s0, v95
	s_waitcnt lgkmcnt(0)
	v_cvt_pk_bf16_f32 v2, v2, v3
	ds_read2_b32 v[4:5], v96 offset0:90 offset1:123
	s_waitcnt lgkmcnt(0)
	v_cvt_pk_bf16_f32 v3, v4, v5
	ds_read2_b32 v[4:5], v96 offset0:156 offset1:189
	v_mul_u32_u24_e32 v0, 0xb00, v0
	s_waitcnt lgkmcnt(0)
	v_cvt_pk_bf16_f32 v4, v4, v5
	ds_read2_b32 v[6:7], v96 offset0:222 offset1:255
	v_lshlrev_b32_e32 v0, 1, v0
	s_waitcnt lgkmcnt(0)
	v_cvt_pk_bf16_f32 v5, v6, v7
	v_lshl_add_u64 v[6:7], v[8:9], 0, v[0:1]
	global_store_dwordx4 v[6:7], v[2:5], off
	s_waitcnt lgkmcnt(0)
	s_branch .LBB0_404

; __device__ __forceinline__ unsigned f2bf(float f) { unsigned u = __builtin_bit_cast(unsigned, f); return (u + 0x7fffu + ((u >> 16) & 1u)) >> 16; }
; #define INP(i) ((const float*)ldp(T, (i)))
; __device__ __forceinline__ void prep_phase(const PT& T, LAS unsigned char* lds) {
;     ...
;     const float* wsp6 = INP(6);
;     for (int idx = bid * NTHR + tid; idx < 2 * 8 * 128 * 128; idx += G * NTHR) {
;         const int i = (idx >> 7) & 127, j = idx & 127; const float w = wsp6[idx];
;         (Wb + WO_A_S0 + (size_t)(idx >> 17) * WO_A_STRIDE)[idx & 131071] = (bf16_t)f2bf((i < 64 && j >= 64) ? 0.f : w);
;     }
.LBB0_703:
	v_ashrrev_i32_e32 v13, 31, v4
	v_mov_b32_e32 v12, v4
	v_ashrrev_i32_e32 v11, 31, v5
	v_mov_b32_e32 v10, v5
	v_lshl_add_u64 v[12:13], v[12:13], 2, s[18:19]
	v_lshl_add_u64 v[10:11], v[10:11], 2, s[18:19]
	global_load_dword v3, v[12:13], off
	global_load_dword v9, v[10:11], off
	v_ashrrev_i32_e32 v10, 17, v4
	v_ashrrev_i32_e32 v0, 17, v5
	v_and_b32_e32 v17, 0x1ffff, v4
	v_mul_hi_i32_i24_e32 v11, 0x640000, v10
	v_mul_i32_i24_e32 v10, 0x640000, v10
	v_and_b32_e32 v15, 0x2040, v4
	v_and_b32_e32 v16, 0x1ffff, v5
	v_mul_hi_i32_i24_e32 v13, 0x640000, v0
	v_mul_i32_i24_e32 v12, 0x640000, v0
	v_lshlrev_b32_e32 v0, 1, v17
	v_lshl_add_u64 v[10:11], s[10:11], 0, v[10:11]
	v_and_b32_e32 v14, 0x2040, v5
	v_cmp_ne_u32_e64 s[0:1], 64, v15
	v_lshl_add_u64 v[12:13], s[10:11], 0, v[12:13]
	v_lshl_add_u64 v[10:11], v[10:11], 0, v[0:1]
	v_lshlrev_b32_e32 v0, 1, v16
	v_add_u32_e32 v8, -2, v8
	v_cmp_ne_u32_e64 s[6:7], 64, v14
	v_lshl_add_u64 v[12:13], v[12:13], 0, v[0:1]
	v_cmp_eq_u32_e32 vcc, 0, v8
	v_add_u32_e32 v5, s5, v5
	v_add_u32_e32 v4, s4, v4
	s_or_b64 s[22:23], vcc, s[22:23]
	s_waitcnt vmcnt(0) lgkmcnt(0)
	v_cndmask_b32_e64 v0, 0, v3, s[0:1]
	v_cndmask_b32_e64 v3, 0, v9, s[6:7]
	v_and_b32_sdwa v14, v0, v223 dst_sel:DWORD dst_unused:UNUSED_PAD src0_sel:WORD_1 src1_sel:DWORD
	v_and_b32_sdwa v9, v3, v223 dst_sel:DWORD dst_unused:UNUSED_PAD src0_sel:WORD_1 src1_sel:DWORD
	v_add3_u32 v0, v0, v14, s84
	v_add3_u32 v3, v3, v9, s84
	global_store_short_d16_hi v[10:11], v0, off
	global_store_short_d16_hi v[12:13], v3, off
	s_andn2_b64 exec, exec, s[22:23]
	s_cbranch_execnz .LBB0_703
	s_or_b64 exec, exec, s[22:23]
	v_mad_u64_u32 v[2:3], s[0:1], v7, s16, v[2:3]
	v_cmp_ne_u32_e32 vcc, v6, v7
	s_orn2_b64 s[0:1], vcc, exec

; __device__ __forceinline__ unsigned f2bf(float f) { unsigned u = __builtin_bit_cast(unsigned, f); return (u + 0x7fffu + ((u >> 16) & 1u)) >> 16; }
; __device__ __forceinline__ void prep_phase(const PT& T, LAS unsigned char* lds) {
;     ...
;     for (int idx = bid * NTHR + tid; idx < 2 * 8 * 128 * 128; idx += G * NTHR) {
;         const int i = (idx >> 7) & 127, j = idx & 127; const float w = wsp6[idx];
;         (Wb + WO_A_S0 + (size_t)(idx >> 17) * WO_A_STRIDE)[idx & 131071] = (bf16_t)f2bf((i < 64 && j >= 64) ? 0.f : w);
;     }
.LBB0_707:
	global_load_dword v3, v[4:5], off
	v_ashrrev_i32_e32 v6, 17, v2
	v_and_b32_e32 v0, 0x2040, v2
	v_and_b32_e32 v8, 0x1ffff, v2
	v_mul_hi_i32_i24_e32 v7, 0x640000, v6
	v_mul_i32_i24_e32 v6, 0x640000, v6
	v_cmp_ne_u32_e32 vcc, 64, v0
	v_lshlrev_b32_e32 v0, 1, v8
	v_lshl_add_u64 v[6:7], s[10:11], 0, v[6:7]
	v_add_u32_e32 v2, s16, v2
	s_mov_b32 s0, 0x3ffff
	v_lshl_add_u64 v[6:7], v[6:7], 0, v[0:1]
	v_cmp_lt_i32_e64 s[0:1], s0, v2
	v_lshl_add_u64 v[4:5], v[4:5], 0, s[6:7]
	s_or_b64 s[18:19], s[0:1], s[18:19]
	s_waitcnt vmcnt(0) lgkmcnt(0)
	v_cndmask_b32_e32 v0, 0, v3, vcc
	v_bfe_u32 v3, v0, 16, 1
	v_add3_u32 v0, v0, v3, s84
	global_store_short_d16_hi v[6:7], v0, off
	s_andn2_b64 exec, exec, s[18:19]
	s_cbranch_execnz .LBB0_707

; __device__ __forceinline__ unsigned pk2(float lo, float hi) { return pg8::cvt_pk_bf16(lo, hi); }
; #define INP(i) ((const float*)ldp(T, (i)))
; __device__ __forceinline__ float wave_sum(float v) {
; #pragma unroll
;     for (int o = 1; o < 64; o <<= 1) v += __shfl_xor(v, o);
;     return v;
; }
; __device__ __forceinline__ void prep_phase(const PT& T, LAS unsigned char* lds) {
;     ...
;     bf16_t* XB = (bf16_t*)(WSP + WS_XB); float* ss0 = (float*)(WSP + WS_CTL);
;     const float* xin = INP(0);
;     for (int m = 4 * gw; m < M; m += 4 * NGW) {
;         f32x4 v[4][4];
; #pragma unroll
;         for (int r = 0; r < 4; ++r)
; #pragma unroll
;             for (int j = 0; j < 4; ++j) v[r][j] = ((const f32x4*)(xin + (size_t)(m + r) * D) + lane)[64 * j];
; #pragma unroll
;         for (int r = 0; r < 4; ++r) { u32x2* o8 = (u32x2*)(XB + (size_t)(m + r) * D) + lane; float sq = 0.f;
; #pragma unroll
;             for (int j = 0; j < 4; ++j) { u32x2 w; w.x = pk2(v[r][j].x, v[r][j].y); w.y = pk2(v[r][j].z, v[r][j].w); o8[64 * j] = w;
;                 const float r0 = bflo(w.x), r1 = bfhi(w.x), r2 = bflo(w.y), r3 = bfhi(w.y); sq += (r0 * r0 + r1 * r1) + (r2 * r2 + r3 * r3); }
;             sq = wave_sum(sq); if (lane == 0) *(f32x4*)(ss0 + 4 * (size_t)(m + r)) = (f32x4){sq, 0.f, 0.f, 0.f}; }
.LBB0_711:
	s_waitcnt lgkmcnt(0)
	v_add_co_u32_e32 v2, vcc, 0xffffc400, v54
	s_movk_i32 s4, 0xfc00
	s_nop 0
	v_addc_co_u32_e32 v3, vcc, -1, v55, vcc
	v_add_co_u32_e32 v4, vcc, 0xffffc800, v54
	v_lshl_add_u64 v[56:57], s[0:1], 0, v[52:53]
	s_nop 0
	v_addc_co_u32_e32 v5, vcc, -1, v55, vcc
	global_load_dwordx4 v[58:61], v[2:3], off
	global_load_dwordx4 v[62:65], v[4:5], off
	v_add_co_u32_e32 v2, vcc, 0xffffcc00, v54
	s_nop 1
	v_addc_co_u32_e32 v3, vcc, -1, v55, vcc
	v_add_co_u32_e32 v4, vcc, 0xffffd000, v54
	s_nop 1
	v_addc_co_u32_e32 v5, vcc, -1, v55, vcc
	global_load_dwordx4 v[66:69], v[2:3], off
	global_load_dwordx4 v[70:73], v[4:5], off
	v_add_co_u32_e32 v2, vcc, 0xffffd400, v54
	s_nop 1
	v_addc_co_u32_e32 v3, vcc, -1, v55, vcc
	v_add_co_u32_e32 v4, vcc, 0xffffd800, v54
	s_nop 1
	v_addc_co_u32_e32 v5, vcc, -1, v55, vcc
	global_load_dwordx4 v[48:51], v[2:3], off
	global_load_dwordx4 v[44:47], v[4:5], off
	v_add_co_u32_e32 v2, vcc, 0xffffdc00, v54
	s_nop 1
	v_addc_co_u32_e32 v3, vcc, -1, v55, vcc
	v_add_co_u32_e32 v4, vcc, 0xffffe000, v54
	s_nop 1
	v_addc_co_u32_e32 v5, vcc, -1, v55, vcc
	global_load_dwordx4 v[40:43], v[2:3], off
	global_load_dwordx4 v[36:39], v[4:5], off
	v_add_co_u32_e32 v2, vcc, 0xffffe400, v54
	s_nop 1
	v_addc_co_u32_e32 v3, vcc, -1, v55, vcc
	v_add_co_u32_e32 v4, vcc, 0xffffe800, v54
	s_nop 1
	v_addc_co_u32_e32 v5, vcc, -1, v55, vcc
	global_load_dwordx4 v[32:35], v[2:3], off
	global_load_dwordx4 v[28:31], v[4:5], off
	v_add_co_u32_e32 v2, vcc, 0xffffec00, v54
	s_nop 1
	v_addc_co_u32_e32 v3, vcc, -1, v55, vcc
	v_add_co_u32_e32 v4, vcc, 0xfffff000, v54
	s_nop 1
	v_addc_co_u32_e32 v5, vcc, -1, v55, vcc
	global_load_dwordx4 v[24:27], v[2:3], off
	global_load_dwordx4 v[20:23], v[4:5], off
	v_add_co_u32_e32 v2, vcc, 0xfffff400, v54
	s_nop 1
	v_addc_co_u32_e32 v3, vcc, -1, v55, vcc
	v_add_co_u32_e32 v4, vcc, 0xfffff800, v54
	s_nop 1
	v_addc_co_u32_e32 v5, vcc, -1, v55, vcc
	global_load_dwordx4 v[16:19], v[2:3], off
	global_load_dwordx4 v[12:15], v[4:5], off
	v_add_co_u32_e32 v2, vcc, s4, v54
	s_nop 1
	v_addc_co_u32_e32 v3, vcc, -1, v55, vcc
	global_load_dwordx4 v[8:11], v[2:3], off
	global_load_dwordx4 v[4:7], v[54:55], off
	v_add_co_u32_e32 v74, vcc, s2, v56
	s_waitcnt vmcnt(0) lgkmcnt(0)
	v_cvt_pk_bf16_f32 v2, v58, v59
	s_nop 0
	v_addc_co_u32_e32 v75, vcc, 0, v57, vcc
	v_cvt_pk_bf16_f32 v3, v60, v61
	global_store_dwordx2 v[74:75], v[2:3], off
	v_lshlrev_b32_e32 v0, 16, v2
	v_and_b32_e32 v2, 0xffff0000, v2
	v_lshlrev_b32_e32 v58, 16, v3
	v_and_b32_e32 v3, 0xffff0000, v3
	v_mul_f32_e32 v2, v2, v2
	v_fmac_f32_e32 v2, v0, v0
	v_mul_f32_e32 v0, v3, v3
	v_fmac_f32_e32 v0, v58, v58
	v_add_f32_e32 v0, v2, v0
	v_cvt_pk_bf16_f32 v2, v62, v63
	v_cvt_pk_bf16_f32 v3, v64, v65
	global_store_dwordx2 v[74:75], v[2:3], off offset:512
	v_lshlrev_b32_e32 v58, 16, v2
	v_and_b32_e32 v2, 0xffff0000, v2
	v_lshlrev_b32_e32 v59, 16, v3
	v_and_b32_e32 v3, 0xffff0000, v3
	v_mul_f32_e32 v2, v2, v2
	v_mul_f32_e32 v3, v3, v3
	v_fmac_f32_e32 v2, v58, v58
	v_fmac_f32_e32 v3, v59, v59
	v_add_f32_e32 v2, v2, v3
	v_add_f32_e32 v0, v0, v2
	v_cvt_pk_bf16_f32 v2, v66, v67
	v_cvt_pk_bf16_f32 v3, v68, v69
	global_store_dwordx2 v[74:75], v[2:3], off offset:1024
	v_lshlrev_b32_e32 v58, 16, v2
	v_and_b32_e32 v2, 0xffff0000, v2
	v_lshlrev_b32_e32 v59, 16, v3
	v_and_b32_e32 v3, 0xffff0000, v3
	v_mul_f32_e32 v2, v2, v2
	v_mul_f32_e32 v3, v3, v3
	v_fmac_f32_e32 v2, v58, v58
	v_fmac_f32_e32 v3, v59, v59
	v_add_f32_e32 v2, v2, v3
	v_cvt_pk_bf16_f32 v64, v70, v71
	v_add_f32_e32 v0, v0, v2
	v_and_b32_e32 v3, 0xffff0000, v64
	v_cvt_pk_bf16_f32 v65, v72, v73
	v_lshlrev_b32_e32 v2, 16, v64
	v_and_b32_e32 v59, 0xffff0000, v65
	v_mul_f32_e32 v3, v3, v3
	v_lshlrev_b32_e32 v58, 16, v65
	v_fmac_f32_e32 v3, v2, v2
	v_mul_f32_e32 v2, v59, v59
	v_fmac_f32_e32 v2, v58, v58
	v_add_f32_e32 v2, v3, v2
	v_add_f32_e32 v0, v0, v2
	v_and_b32_e32 v2, 64, v226
	v_add_u32_e32 v2, 64, v2
	v_xor_b32_e32 v3, 1, v226
	v_cmp_lt_i32_e32 vcc, v3, v2
	global_store_dwordx2 v[74:75], v[64:65], off offset:1536
	s_nop 0
	v_cndmask_b32_e32 v3, v226, v3, vcc
	v_lshlrev_b32_e32 v58, 2, v3
	ds_bpermute_b32 v3, v58, v0
	s_waitcnt lgkmcnt(0)
	v_add_f32_e32 v0, v0, v3
	v_xor_b32_e32 v3, 2, v226
	v_cmp_lt_i32_e32 vcc, v3, v2
	s_nop 1
	v_cndmask_b32_e32 v3, v226, v3, vcc
	v_lshlrev_b32_e32 v59, 2, v3
	ds_bpermute_b32 v3, v59, v0
	s_waitcnt lgkmcnt(0)
	v_add_f32_e32 v0, v0, v3
	v_xor_b32_e32 v3, 4, v226
	v_cmp_lt_i32_e32 vcc, v3, v2
	s_nop 1
	v_cndmask_b32_e32 v3, v226, v3, vcc
	v_lshlrev_b32_e32 v60, 2, v3
	ds_bpermute_b32 v3, v60, v0
	s_waitcnt lgkmcnt(0)
	v_add_f32_e32 v0, v0, v3
	v_xor_b32_e32 v3, 8, v226
	v_cmp_lt_i32_e32 vcc, v3, v2
	s_nop 1
	v_cndmask_b32_e32 v3, v226, v3, vcc
	v_lshlrev_b32_e32 v61, 2, v3
	ds_bpermute_b32 v3, v61, v0
	s_waitcnt lgkmcnt(0)
	v_add_f32_e32 v0, v0, v3
	v_xor_b32_e32 v3, 16, v226
	v_cmp_lt_i32_e32 vcc, v3, v2
	s_nop 1
	v_cndmask_b32_e32 v3, v226, v3, vcc
	v_lshlrev_b32_e32 v62, 2, v3
	ds_bpermute_b32 v3, v62, v0
	s_waitcnt lgkmcnt(0)
	v_add_f32_e32 v0, v0, v3
	v_xor_b32_e32 v3, 32, v226
	v_cmp_lt_i32_e32 vcc, v3, v2
	s_nop 1
	v_cndmask_b32_e32 v2, v226, v3, vcc
	v_lshlrev_b32_e32 v63, 2, v2
	ds_bpermute_b32 v2, v63, v0
	s_and_saveexec_b64 s[4:5], s[6:7]
	s_cbranch_execz .LBB0_713
	s_add_u32 s9, s0, s16
	s_waitcnt lgkmcnt(0)
	v_add_f32_e32 v0, v0, v2
	s_addc_u32 s11, s1, s17
	v_mov_b32_e32 v2, s9
	v_add_co_u32_e32 v64, vcc, 0x19000000, v2
	v_mov_b32_e32 v2, s11
	s_nop 0
	v_addc_co_u32_e32 v65, vcc, 0, v2, vcc
	v_mov_b32_e32 v2, v1
	v_mov_b32_e32 v3, v1
	global_store_dwordx4 v[64:65], v[0:3], off
; __device__ __forceinline__ unsigned pk2(float lo, float hi) { return pg8::cvt_pk_bf16(lo, hi); }
; __device__ __forceinline__ float wave_sum(float v) {
; #pragma unroll
;     for (int o = 1; o < 64; o <<= 1) v += __shfl_xor(v, o);
;     return v;
; }
; __device__ __forceinline__ void prep_phase(const PT& T, LAS unsigned char* lds) {
;     ...
;         for (int r = 0; r < 4; ++r) { u32x2* o8 = (u32x2*)(XB + (size_t)(m + r) * D) + lane; float sq = 0.f;
; #pragma unroll
;             for (int j = 0; j < 4; ++j) { u32x2 w; w.x = pk2(v[r][j].x, v[r][j].y); w.y = pk2(v[r][j].z, v[r][j].w); o8[64 * j] = w;
;                 const float r0 = bflo(w.x), r1 = bfhi(w.x), r2 = bflo(w.y), r3 = bfhi(w.y); sq += (r0 * r0 + r1 * r1) + (r2 * r2 + r3 * r3); }
;             sq = wave_sum(sq); if (lane == 0) *(f32x4*)(ss0 + 4 * (size_t)(m + r)) = (f32x4){sq, 0.f, 0.f, 0.f}; }
.LBB0_713:
	s_or_b64 exec, exec, s[4:5]
	s_waitcnt lgkmcnt(0)
	v_cvt_pk_bf16_f32 v2, v48, v49
	v_add_co_u32_e32 v48, vcc, 0x6000000, v56
	v_cvt_pk_bf16_f32 v3, v50, v51
	v_lshlrev_b32_e32 v0, 16, v2
	s_nop 0
	v_addc_co_u32_e32 v49, vcc, 0, v57, vcc
	global_store_dwordx2 v[48:49], v[2:3], off offset:2048
	v_and_b32_e32 v2, 0xffff0000, v2
	v_lshlrev_b32_e32 v50, 16, v3
	v_and_b32_e32 v3, 0xffff0000, v3
	v_mul_f32_e32 v2, v2, v2
	v_fmac_f32_e32 v2, v0, v0
	v_mul_f32_e32 v0, v3, v3
	v_fmac_f32_e32 v0, v50, v50
	v_add_f32_e32 v0, v2, v0
	v_cvt_pk_bf16_f32 v2, v44, v45
	v_cvt_pk_bf16_f32 v3, v46, v47
	global_store_dwordx2 v[48:49], v[2:3], off offset:2560
	v_lshlrev_b32_e32 v44, 16, v2
	v_and_b32_e32 v2, 0xffff0000, v2
	v_lshlrev_b32_e32 v45, 16, v3
	v_and_b32_e32 v3, 0xffff0000, v3
	v_mul_f32_e32 v2, v2, v2
	v_mul_f32_e32 v3, v3, v3
	v_fmac_f32_e32 v2, v44, v44
	v_fmac_f32_e32 v3, v45, v45
	v_add_f32_e32 v2, v2, v3
	v_add_f32_e32 v0, v0, v2
	v_cvt_pk_bf16_f32 v2, v40, v41
	v_cvt_pk_bf16_f32 v3, v42, v43
	global_store_dwordx2 v[48:49], v[2:3], off offset:3072
	v_lshlrev_b32_e32 v40, 16, v2
	v_and_b32_e32 v2, 0xffff0000, v2
	v_lshlrev_b32_e32 v41, 16, v3
	v_and_b32_e32 v3, 0xffff0000, v3
	v_mul_f32_e32 v2, v2, v2
	v_mul_f32_e32 v3, v3, v3
	v_fmac_f32_e32 v2, v40, v40
	v_fmac_f32_e32 v3, v41, v41
	v_add_f32_e32 v2, v2, v3
	v_cvt_pk_bf16_f32 v36, v36, v37
	v_add_f32_e32 v0, v0, v2
	v_and_b32_e32 v3, 0xffff0000, v36
	v_cvt_pk_bf16_f32 v37, v38, v39
	v_lshlrev_b32_e32 v2, 16, v36
	v_and_b32_e32 v39, 0xffff0000, v37
	v_mul_f32_e32 v3, v3, v3
	v_lshlrev_b32_e32 v38, 16, v37
	v_fmac_f32_e32 v3, v2, v2
	v_mul_f32_e32 v2, v39, v39
	v_fmac_f32_e32 v2, v38, v38
	v_add_f32_e32 v2, v3, v2
	v_add_f32_e32 v0, v0, v2
	ds_bpermute_b32 v2, v58, v0
	global_store_dwordx2 v[48:49], v[36:37], off offset:3584
	s_waitcnt lgkmcnt(0)
	v_add_f32_e32 v0, v0, v2
	ds_bpermute_b32 v2, v59, v0
	s_waitcnt lgkmcnt(0)
	v_add_f32_e32 v0, v0, v2
	ds_bpermute_b32 v2, v60, v0
	s_waitcnt lgkmcnt(0)
	v_add_f32_e32 v0, v0, v2
	ds_bpermute_b32 v2, v61, v0
	s_waitcnt lgkmcnt(0)
	v_add_f32_e32 v0, v0, v2
	ds_bpermute_b32 v2, v62, v0
	s_waitcnt lgkmcnt(0)
	v_add_f32_e32 v0, v0, v2
	ds_bpermute_b32 v2, v63, v0
	s_and_saveexec_b64 s[4:5], s[6:7]
	s_cbranch_execz .LBB0_715
	s_add_u32 s9, s0, s16
	s_waitcnt lgkmcnt(0)
	v_add_f32_e32 v0, v0, v2
	s_addc_u32 s11, s1, s17
	v_mov_b32_e32 v2, s9
	v_add_co_u32_e32 v36, vcc, 0x19000000, v2
	v_mov_b32_e32 v2, s11
	s_nop 0
	v_addc_co_u32_e32 v37, vcc, 0, v2, vcc
	v_mov_b32_e32 v2, v1
	v_mov_b32_e32 v3, v1
	global_store_dwordx4 v[36:37], v[0:3], off offset:16
.LBB0_715:
	s_or_b64 exec, exec, s[4:5]
	s_waitcnt lgkmcnt(0)
	v_cvt_pk_bf16_f32 v2, v32, v33
	v_add_co_u32_e32 v32, vcc, 0x6001000, v56
	v_cvt_pk_bf16_f32 v3, v34, v35
	v_lshlrev_b32_e32 v0, 16, v2
	s_nop 0
	v_addc_co_u32_e32 v33, vcc, 0, v57, vcc
	global_store_dwordx2 v[32:33], v[2:3], off
	v_and_b32_e32 v2, 0xffff0000, v2
	v_lshlrev_b32_e32 v34, 16, v3
	v_and_b32_e32 v3, 0xffff0000, v3
	v_mul_f32_e32 v2, v2, v2
	v_fmac_f32_e32 v2, v0, v0
	v_mul_f32_e32 v0, v3, v3
	v_fmac_f32_e32 v0, v34, v34
	v_add_f32_e32 v0, v2, v0
	v_cvt_pk_bf16_f32 v2, v28, v29
	v_cvt_pk_bf16_f32 v3, v30, v31
	global_store_dwordx2 v[32:33], v[2:3], off offset:512
	v_lshlrev_b32_e32 v28, 16, v2
	v_and_b32_e32 v2, 0xffff0000, v2
	v_lshlrev_b32_e32 v29, 16, v3
	v_and_b32_e32 v3, 0xffff0000, v3
	v_mul_f32_e32 v2, v2, v2
	v_mul_f32_e32 v3, v3, v3
	v_fmac_f32_e32 v2, v28, v28
	v_fmac_f32_e32 v3, v29, v29
	v_add_f32_e32 v2, v2, v3
	v_add_f32_e32 v0, v0, v2
	v_cvt_pk_bf16_f32 v2, v24, v25
	v_cvt_pk_bf16_f32 v3, v26, v27
	global_store_dwordx2 v[32:33], v[2:3], off offset:1024
	v_lshlrev_b32_e32 v24, 16, v2
	v_and_b32_e32 v2, 0xffff0000, v2
	v_lshlrev_b32_e32 v25, 16, v3
	v_and_b32_e32 v3, 0xffff0000, v3
	v_mul_f32_e32 v2, v2, v2
	v_mul_f32_e32 v3, v3, v3
	v_fmac_f32_e32 v2, v24, v24
	v_fmac_f32_e32 v3, v25, v25
	v_add_f32_e32 v2, v2, v3
	v_cvt_pk_bf16_f32 v20, v20, v21
	v_add_f32_e32 v0, v0, v2
	v_and_b32_e32 v3, 0xffff0000, v20
	v_cvt_pk_bf16_f32 v21, v22, v23
	v_lshlrev_b32_e32 v2, 16, v20
	v_and_b32_e32 v23, 0xffff0000, v21
	v_mul_f32_e32 v3, v3, v3
	v_lshlrev_b32_e32 v22, 16, v21
	v_fmac_f32_e32 v3, v2, v2
	v_mul_f32_e32 v2, v23, v23
	v_fmac_f32_e32 v2, v22, v22
	v_add_f32_e32 v2, v3, v2
	v_add_f32_e32 v0, v0, v2
	ds_bpermute_b32 v2, v58, v0
	global_store_dwordx2 v[32:33], v[20:21], off offset:1536
	s_waitcnt lgkmcnt(0)
	v_add_f32_e32 v0, v0, v2
	ds_bpermute_b32 v2, v59, v0
	s_waitcnt lgkmcnt(0)
	v_add_f32_e32 v0, v0, v2
	ds_bpermute_b32 v2, v60, v0
	s_waitcnt lgkmcnt(0)
	v_add_f32_e32 v0, v0, v2
	ds_bpermute_b32 v2, v61, v0
	s_waitcnt lgkmcnt(0)
	v_add_f32_e32 v0, v0, v2
	ds_bpermute_b32 v2, v62, v0
	s_waitcnt lgkmcnt(0)
	v_add_f32_e32 v0, v0, v2
	ds_bpermute_b32 v2, v63, v0
	s_and_saveexec_b64 s[4:5], s[6:7]
	s_cbranch_execz .LBB0_717
	s_add_u32 s9, s0, s16
	s_waitcnt lgkmcnt(0)
	v_add_f32_e32 v0, v0, v2
	s_addc_u32 s11, s1, s17
	v_mov_b32_e32 v2, s9
	v_add_co_u32_e32 v20, vcc, 0x19000000, v2
	v_mov_b32_e32 v2, s11
	s_nop 0
	v_addc_co_u32_e32 v21, vcc, 0, v2, vcc
	v_mov_b32_e32 v2, v1
	v_mov_b32_e32 v3, v1
	global_store_dwordx4 v[20:21], v[0:3], off offset:32
; __device__ __forceinline__ unsigned pk2(float lo, float hi) { return pg8::cvt_pk_bf16(lo, hi); }
; __device__ __forceinline__ int tid_opaque() { int t = threadIdx.x; asm volatile("" : "+v"(t)); return t; }
; __device__ __forceinline__ int sgpr_opaque(int x) { asm volatile("" : "+s"(x)); return x; }
; #define INP(i) ((const float*)ldp(T, (i)))
; __device__ __forceinline__ void prep_phase(const PT& T, LAS unsigned char* lds) {
;     ...
;         for (int r = 0; r < 4; ++r) { u32x2* o8 = (u32x2*)(XB + (size_t)(m + r) * D) + lane; float sq = 0.f;
; #pragma unroll
;             for (int j = 0; j < 4; ++j) { u32x2 w; w.x = pk2(v[r][j].x, v[r][j].y); w.y = pk2(v[r][j].z, v[r][j].w); o8[64 * j] = w;
;                 const float r0 = bflo(w.x), r1 = bfhi(w.x), r2 = bflo(w.y), r3 = bfhi(w.y); sq += (r0 * r0 + r1 * r1) + (r2 * r2 + r3 * r3); }
;             sq = wave_sum(sq); if (lane == 0) *(f32x4*)(ss0 + 4 * (size_t)(m + r)) = (f32x4){sq, 0.f, 0.f, 0.f}; }
; __device__ __forceinline__ void conv_phase(const PT& T, int vc) {
;     const int tid = tid_opaque(), chunk = tid & 127, c8 = chunk * 8, rsub = tid >> 7, R8 = sgpr_opaque(gridDim.x) >> 3, vx = sgpr_opaque(vc) & 7, vr = sgpr_opaque(vc) >> 3;
;     const bf16_t* __restrict__ Q = (const bf16_t*)((unsigned char*)OUTP) + (size_t)vx * CHUNK_ADJ; const bf16_t* __restrict__ Bg = Q + CHUNK_ADJ; bf16_t* __restrict__ YB = (bf16_t*)(WSP + WS_T2);
;     float w[3][8];
; #pragma unroll
;     for (int k = 0; k < 3; ++k) { const f32x4 a = *(const f32x4*)(INP(10) + k * D + c8), b = *(const f32x4*)(INP(10) + k * D + c8 + 4);
;         w[k][0] = a.x; w[k][1] = a.y; w[k][2] = a.z; w[k][3] = a.w; w[k][4] = b.x; w[k][5] = b.y; w[k][6] = b.z; w[k][7] = b.w; }
;     for (int ri = vr * 4 + rsub; ri < 512; ri += R8 * 4) {
;         const int run = 512 * vx + ri, r0 = run * 8, tt0 = r0 & (SEQ - 1);
;         u32x4 q[10], b[8];
;         q[0] = (u32x4){0u, 0u, 0u, 0u}; q[1] = q[0];
;         if (tt0 >= 2) { q[0] = *(const u32x4*)(Q + (size_t)(r0 - 2) * D + c8); q[1] = *(const u32x4*)(Q + (size_t)(r0 - 1) * D + c8); }
; #pragma unroll
;         for (int i = 0; i < 8; ++i) { const size_t off = (size_t)(r0 + i) * D + c8; q[2 + i] = *(const u32x4*)(Q + off); b[i] = *(const u32x4*)(Bg + off); }
.LBB0_717:
	s_or_b64 exec, exec, s[4:5]
	s_waitcnt lgkmcnt(0)
	v_cvt_pk_bf16_f32 v2, v16, v17
	v_add_co_u32_e32 v16, vcc, 0x6001000, v56
	v_cvt_pk_bf16_f32 v3, v18, v19
	v_lshlrev_b32_e32 v0, 16, v2
	s_nop 0
	v_addc_co_u32_e32 v17, vcc, 0, v57, vcc
	global_store_dwordx2 v[16:17], v[2:3], off offset:2048
	v_and_b32_e32 v2, 0xffff0000, v2
	v_lshlrev_b32_e32 v18, 16, v3
	v_and_b32_e32 v3, 0xffff0000, v3
	v_mul_f32_e32 v2, v2, v2
	v_fmac_f32_e32 v2, v0, v0
	v_mul_f32_e32 v0, v3, v3
	v_fmac_f32_e32 v0, v18, v18
	v_add_f32_e32 v0, v2, v0
	v_cvt_pk_bf16_f32 v2, v12, v13
	v_cvt_pk_bf16_f32 v3, v14, v15
	global_store_dwordx2 v[16:17], v[2:3], off offset:2560
	v_lshlrev_b32_e32 v12, 16, v2
	v_and_b32_e32 v2, 0xffff0000, v2
	v_lshlrev_b32_e32 v13, 16, v3
	v_and_b32_e32 v3, 0xffff0000, v3
	v_mul_f32_e32 v2, v2, v2
	v_mul_f32_e32 v3, v3, v3
	v_fmac_f32_e32 v2, v12, v12
	v_fmac_f32_e32 v3, v13, v13
	v_add_f32_e32 v2, v2, v3
	v_add_f32_e32 v0, v0, v2
	v_cvt_pk_bf16_f32 v2, v8, v9
	v_cvt_pk_bf16_f32 v3, v10, v11
	global_store_dwordx2 v[16:17], v[2:3], off offset:3072
	v_lshlrev_b32_e32 v8, 16, v2
	v_and_b32_e32 v2, 0xffff0000, v2
	v_lshlrev_b32_e32 v9, 16, v3
	v_and_b32_e32 v3, 0xffff0000, v3
	v_mul_f32_e32 v2, v2, v2
	v_mul_f32_e32 v3, v3, v3
	v_fmac_f32_e32 v2, v8, v8
	v_fmac_f32_e32 v3, v9, v9
	v_add_f32_e32 v2, v2, v3
	v_cvt_pk_bf16_f32 v4, v4, v5
	v_add_f32_e32 v0, v0, v2
	v_and_b32_e32 v3, 0xffff0000, v4
	v_cvt_pk_bf16_f32 v5, v6, v7
	v_lshlrev_b32_e32 v2, 16, v4
	v_and_b32_e32 v7, 0xffff0000, v5
	v_mul_f32_e32 v3, v3, v3
	v_lshlrev_b32_e32 v6, 16, v5
	v_fmac_f32_e32 v3, v2, v2
	v_mul_f32_e32 v2, v7, v7
	v_fmac_f32_e32 v2, v6, v6
	v_add_f32_e32 v2, v3, v2
	v_add_f32_e32 v0, v0, v2
	ds_bpermute_b32 v2, v58, v0
	global_store_dwordx2 v[16:17], v[4:5], off offset:3584
	s_waitcnt lgkmcnt(0)
	v_add_f32_e32 v0, v0, v2
	ds_bpermute_b32 v2, v59, v0
	s_waitcnt lgkmcnt(0)
	v_add_f32_e32 v0, v0, v2
	ds_bpermute_b32 v2, v60, v0
	s_waitcnt lgkmcnt(0)
	v_add_f32_e32 v0, v0, v2
	ds_bpermute_b32 v2, v61, v0
	s_waitcnt lgkmcnt(0)
	v_add_f32_e32 v0, v0, v2
	ds_bpermute_b32 v2, v62, v0
	s_waitcnt lgkmcnt(0)
	v_add_f32_e32 v0, v0, v2
	ds_bpermute_b32 v2, v63, v0
	s_and_saveexec_b64 s[4:5], s[6:7]
	s_cbranch_execz .LBB0_710
	s_add_u32 s9, s0, s16
	s_waitcnt lgkmcnt(0)
	v_add_f32_e32 v0, v0, v2
	s_addc_u32 s11, s1, s17
	v_mov_b32_e32 v2, s9
	v_add_co_u32_e32 v4, vcc, 0x19000000, v2
	v_mov_b32_e32 v2, s11
	s_nop 0
	v_addc_co_u32_e32 v5, vcc, 0, v2, vcc
	v_mov_b32_e32 v2, v1
	v_mov_b32_e32 v3, v1
	global_store_dwordx4 v[4:5], v[0:3], off offset:48
	s_branch .LBB0_710
.LBB0_719:
	s_cmp_eq_u32 s86, 1
	s_mov_b64 s[6:7], -1
	s_cbranch_scc0 .LBB0_726
	v_readlane_b32 s4, v254, 8
	v_readlane_b32 s6, v254, 22
	v_mov_b32_e32 v0, v220
	v_mov_b32_e32 v2, s4
	v_readlane_b32 s4, v254, 11
	s_mov_b32 s14, s68
	s_mov_b32 s8, s6
	v_mov_b32_e32 v6, s4
	s_waitcnt lgkmcnt(0)
	ds_read2_b64 v[2:5], v2 offset1:1
	ds_read_b64 v[6:7], v6
	s_ashr_i32 s15, s6, 1
	v_ashrrev_i32_e32 v26, 7, v0
	s_and_b32 s6, s15, -4
	v_add_u32_e32 v132, s6, v26
	s_movk_i32 s6, 0x200
	s_waitcnt lgkmcnt(0)
	v_readfirstlane_b32 s11, v3
	v_readfirstlane_b32 s10, v2
	v_readfirstlane_b32 s21, v5
	v_readfirstlane_b32 s20, v4
	v_readfirstlane_b32 s5, v7
	v_readfirstlane_b32 s4, v6
	v_cmp_gt_i32_e32 vcc, s6, v132
	s_and_saveexec_b64 s[6:7], vcc
	s_cbranch_execz .LBB0_725
	v_lshlrev_b32_e32 v0, 3, v0
	v_and_b32_e32 v28, 0x3f8, v0
	v_lshlrev_b32_e32 v0, 2, v28
	v_lshl_add_u64 v[22:23], s[4:5], 0, v[0:1]
	s_mov_b64 s[4:5], 0x2000
	v_lshl_add_u64 v[10:11], v[22:23], 0, s[4:5]
	v_add_co_u32_e32 v14, vcc, s9, v22
	s_mov_b64 s[4:5], 0x1000
	s_nop 0
	v_addc_co_u32_e32 v15, vcc, 0, v23, vcc
	v_lshl_add_u64 v[18:19], v[22:23], 0, s[4:5]
	s_movk_i32 s4, 0x1000
	global_load_dwordx4 v[2:5], v[22:23], off offset:16
	global_load_dwordx4 v[6:9], v[22:23], off
	v_add_co_u32_e32 v22, vcc, s4, v22
	global_load_dwordx4 v[10:13], v[10:11], off offset:16
	s_nop 0
	v_addc_co_u32_e32 v23, vcc, 0, v23, vcc
	global_load_dwordx4 v[14:17], v[14:15], off
	s_and_b32 s4, s8, 7
	global_load_dwordx4 v[18:21], v[18:19], off offset:16
	s_lshl_b32 s5, s4, 23
	global_load_dwordx4 v[22:25], v[22:23], off
	s_add_u32 s10, s10, s5
	s_addc_u32 s11, s11, 0
	s_add_u32 s18, s10, 0x800000
	s_addc_u32 s19, s11, 0
	s_lshl_b32 s15, s15, 3
	s_lshl_b32 s5, s4, 12
	s_andn2_b32 s15, s15, 31
	v_lshlrev_b32_e32 v0, 1, v28
	s_ashr_i32 s14, s14, 1
	s_add_i32 s15, s5, s15
	v_lshl_add_u64 v[70:71], s[10:11], 0, v[0:1]
	v_lshl_add_u64 v[30:31], s[20:21], 0, v[0:1]
	s_mov_b64 s[16:17], 0x15000000
	s_and_b32 s4, s14, -4
	s_lshl_b32 s14, s14, 3
	v_lshl_add_u32 v0, v26, 3, s15
	s_mov_b64 s[8:9], 0
	v_lshl_add_u64 v[72:73], v[30:31], 0, s[16:17]
	s_and_b32 s5, s14, 0xffffffe0
	v_or_b32_e32 v74, 7, v0
	v_lshlrev_b32_e32 v0, 1, v28
	s_waitcnt vmcnt(0) lgkmcnt(0)
	v_mov_b32_e32 v76, v4
	v_mov_b32_e32 v78, v5
	v_mov_b32_e32 v80, v2
	v_mov_b32_e32 v82, v3
	v_mov_b32_e32 v84, v8
	v_mov_b32_e32 v86, v9
	v_mov_b32_e32 v88, v6
	v_mov_b32_e32 v90, v7
	v_mov_b32_e32 v77, v12
	v_mov_b32_e32 v79, v13
	v_mov_b32_e32 v81, v10
	v_mov_b32_e32 v83, v11
	v_mov_b32_e32 v85, v16
	v_mov_b32_e32 v87, v17
	v_mov_b32_e32 v89, v14
	v_mov_b32_e32 v91, v15
	v_mov_b32_e32 v93, v12
	v_mov_b32_e32 v95, v10
	v_mov_b32_e32 v97, v16
	v_mov_b32_e32 v99, v14
	v_mov_b32_e32 v92, v20
	v_mov_b32_e32 v12, v21
	v_mov_b32_e32 v94, v18
	v_mov_b32_e32 v10, v19
	v_mov_b32_e32 v96, v24
	v_mov_b32_e32 v16, v25
	v_mov_b32_e32 v98, v22
	v_mov_b32_e32 v14, v23
	s_branch .LBB0_723
; __device__ __forceinline__ unsigned pk2(float lo, float hi) { return pg8::cvt_pk_bf16(lo, hi); }
; #define CV(e, qa, qb, qc, bv, LOHI) (LOHI(bv) * (w[0][e] * LOHI(qa) + w[1][e] * LOHI(qb) + w[2][e] * LOHI(qc)))
; __device__ __forceinline__ void conv_phase(const PT& T, int vc) {
;     ...
;     for (int ri = vr * 4 + rsub; ri < 512; ri += R8 * 4) {
;         const int run = 512 * vx + ri, r0 = run * 8, tt0 = r0 & (SEQ - 1);
;         u32x4 q[10], b[8];
;         q[0] = (u32x4){0u, 0u, 0u, 0u}; q[1] = q[0];
;         if (tt0 >= 2) { q[0] = *(const u32x4*)(Q + (size_t)(r0 - 2) * D + c8); q[1] = *(const u32x4*)(Q + (size_t)(r0 - 1) * D + c8); }
; #pragma unroll
;         for (int i = 0; i < 8; ++i) { const size_t off = (size_t)(r0 + i) * D + c8; q[2 + i] = *(const u32x4*)(Q + off); b[i] = *(const u32x4*)(Bg + off); }
; #pragma unroll
;         for (int i = 0; i < 8; ++i) { const u32x4 q0 = q[i], q1 = q[i + 1], q2 = q[i + 2], bb = b[i]; u32x4 o;
;     ...
;             o.x = pk2(CV(0, q0.x, q1.x, q2.x, bb.x, bflo), CV(1, q0.x, q1.x, q2.x, bb.x, bfhi)); o.y = pk2(CV(2, q0.y, q1.y, q2.y, bb.y, bflo), CV(3, q0.y, q1.y, q2.y, bb.y, bfhi));
;             o.z = pk2(CV(4, q0.z, q1.z, q2.z, bb.z, bflo), CV(5, q0.z, q1.z, q2.z, bb.z, bfhi)); o.w = pk2(CV(6, q0.w, q1.w, q2.w, bb.w, bflo), CV(7, q0.w, q1.w, q2.w, bb.w, bfhi));
;     ...
;             *(u32x4*)(YB + (size_t)(r0 + i) * D + c8) = o; }
.LBB0_722:
	s_or_b64 exec, exec, s[20:21]
	v_add_u32_e32 v26, -7, v74
	v_ashrrev_i32_e32 v27, 31, v26
	v_lshlrev_b64 v[112:113], 11, v[26:27]
	v_or_b32_e32 v26, v112, v0
	v_mov_b32_e32 v27, v113
	v_lshl_add_u64 v[28:29], s[10:11], 0, v[26:27]
	v_lshl_add_u64 v[26:27], s[18:19], 0, v[26:27]
	global_load_dwordx4 v[54:57], v[26:27], off
	global_load_dwordx4 v[134:137], v[28:29], off
	v_add_u32_e32 v26, -6, v74
	v_ashrrev_i32_e32 v27, 31, v26
	v_lshlrev_b64 v[110:111], 11, v[26:27]
	v_or_b32_e32 v26, v110, v0
	v_mov_b32_e32 v27, v111
	v_lshl_add_u64 v[28:29], s[10:11], 0, v[26:27]
	global_load_dwordx4 v[42:45], v[28:29], off
	v_lshl_add_u64 v[26:27], s[18:19], 0, v[26:27]
	global_load_dwordx4 v[138:141], v[26:27], off
	v_add_u32_e32 v28, -5, v74
	v_add_u32_e32 v30, -4, v74
	v_add_u32_e32 v32, -3, v74
	v_add_u32_e32 v34, -2, v74
	v_add_u32_e32 v36, -1, v74
	v_ashrrev_i32_e32 v75, 31, v74
	v_ashrrev_i32_e32 v29, 31, v28
	v_ashrrev_i32_e32 v31, 31, v30
	v_ashrrev_i32_e32 v33, 31, v32
	v_ashrrev_i32_e32 v35, 31, v34
	v_ashrrev_i32_e32 v37, 31, v36
	v_lshlrev_b64 v[100:101], 11, v[74:75]
	v_lshlrev_b64 v[130:131], 11, v[28:29]
	v_lshlrev_b64 v[108:109], 11, v[30:31]
	v_lshlrev_b64 v[106:107], 11, v[32:33]
	v_lshlrev_b64 v[104:105], 11, v[34:35]
	v_lshlrev_b64 v[102:103], 11, v[36:37]
	v_or_b32_e32 v26, v100, v0
	v_mov_b32_e32 v27, v101
	v_or_b32_e32 v28, v130, v0
	v_mov_b32_e32 v29, v131
	v_or_b32_e32 v30, v108, v0
	v_mov_b32_e32 v31, v109
	v_or_b32_e32 v32, v106, v0
	v_mov_b32_e32 v33, v107
	v_or_b32_e32 v34, v104, v0
	v_mov_b32_e32 v35, v105
	s_waitcnt vmcnt(0) lgkmcnt(0)
	v_lshlrev_b32_e32 v124, 16, v46
	v_and_b32_e32 v122, 0xffff0000, v46
	v_lshlrev_b32_e32 v120, 16, v47
	v_and_b32_e32 v118, 0xffff0000, v47
	v_or_b32_e32 v36, v102, v0
	v_mov_b32_e32 v37, v103
	v_lshl_add_u64 v[46:47], s[10:11], 0, v[26:27]
	v_lshl_add_u64 v[146:147], s[18:19], 0, v[26:27]
	v_lshl_add_u64 v[26:27], s[10:11], 0, v[28:29]
	v_lshl_add_u64 v[28:29], s[18:19], 0, v[28:29]
	v_lshl_add_u64 v[50:51], s[10:11], 0, v[30:31]
	v_lshl_add_u64 v[30:31], s[18:19], 0, v[30:31]
	v_lshl_add_u64 v[52:53], s[10:11], 0, v[32:33]
	v_lshl_add_u64 v[32:33], s[18:19], 0, v[32:33]
	v_lshl_add_u64 v[126:127], s[10:11], 0, v[34:35]
	v_lshl_add_u64 v[34:35], s[18:19], 0, v[34:35]
	v_lshl_add_u64 v[148:149], s[10:11], 0, v[36:37]
	v_lshl_add_u64 v[150:151], s[18:19], 0, v[36:37]
	global_load_dwordx4 v[58:61], v[26:27], off
	global_load_dwordx4 v[142:145], v[28:29], off
	global_load_dwordx4 v[62:65], v[50:51], off
	global_load_dwordx4 v[66:69], v[30:31], off
	s_nop 0
	global_load_dwordx4 v[26:29], v[52:53], off
	s_nop 0
	global_load_dwordx4 v[50:53], v[32:33], off
	s_nop 0
	global_load_dwordx4 v[30:33], v[126:127], off
	s_nop 0
	global_load_dwordx4 v[34:37], v[34:35], off
	v_lshlrev_b32_e32 v116, 16, v48
	v_and_b32_e32 v114, 0xffff0000, v48
	v_lshlrev_b32_e32 v152, 16, v38
	v_lshlrev_b32_e32 v160, 16, v40
	v_and_b32_e32 v162, 0xffff0000, v40
	v_lshlrev_b32_e32 v164, 16, v41
	v_and_b32_e32 v166, 0xffff0000, v41
	v_and_b32_e32 v154, 0xffff0000, v38
	v_lshlrev_b32_e32 v156, 16, v39
	v_and_b32_e32 v158, 0xffff0000, v39
	v_lshlrev_b32_e32 v128, 16, v49
	v_and_b32_e32 v126, 0xffff0000, v49
	v_lshl_add_u64 v[112:113], v[72:73], 0, v[112:113]
	v_lshl_add_u64 v[110:111], v[72:73], 0, v[110:111]
	v_add_u32_e32 v132, s4, v132
	s_movk_i32 s14, 0x1ff
	v_cmp_lt_i32_e32 vcc, s14, v132
	s_or_b64 s[8:9], vcc, s[8:9]
	v_add_u32_e32 v74, s5, v74
	v_lshlrev_b32_e32 v48, 16, v54
	v_lshlrev_b32_e32 v125, 16, v134
	v_and_b32_e32 v75, 0xffff0000, v54
	v_lshlrev_b32_e32 v133, 16, v55
	v_and_b32_e32 v168, 0xffff0000, v55
	v_pk_mul_f32 v[54:55], v[88:89], v[124:125]
	v_and_b32_e32 v123, 0xffff0000, v134
	v_fma_f32 v40, v22, v152, v54
	v_lshlrev_b32_e32 v153, 16, v42
	v_add_f32_e32 v40, v40, v55
	v_lshlrev_b32_e32 v117, 16, v136
	v_and_b32_e32 v115, 0xffff0000, v136
	v_mul_f32_e32 v136, v40, v48
	v_pk_mul_f32 v[40:41], v[88:89], v[152:153]
	v_lshlrev_b32_e32 v121, 16, v135
	v_and_b32_e32 v119, 0xffff0000, v135
	v_pk_mul_f32 v[134:135], v[90:91], v[122:123]
	v_fma_f32 v40, v22, v125, v40
	v_add_f32_e32 v152, v40, v41
	v_fma_f32 v40, v23, v154, v134
	v_and_b32_e32 v155, 0xffff0000, v42
	v_add_f32_e32 v40, v40, v135
	v_mul_f32_e32 v75, v40, v75
	v_pk_mul_f32 v[40:41], v[90:91], v[154:155]
	v_lshlrev_b32_e32 v157, 16, v43
	v_and_b32_e32 v159, 0xffff0000, v43
	v_pk_mul_f32 v[42:43], v[84:85], v[120:121]
	v_fma_f32 v40, v23, v123, v40
	v_add_f32_e32 v154, v40, v41
	v_fma_f32 v40, v24, v156, v42
	v_pk_mul_f32 v[38:39], v[86:87], v[118:119]
	v_add_f32_e32 v40, v40, v43
	v_mul_f32_e32 v133, v40, v133
	v_pk_mul_f32 v[40:41], v[84:85], v[156:157]
	v_fma_f32 v38, v25, v158, v38
	v_fma_f32 v40, v24, v121, v40
	v_add_f32_e32 v38, v38, v39
	v_lshlrev_b32_e32 v169, 16, v56
	v_and_b32_e32 v170, 0xffff0000, v56
	v_lshlrev_b32_e32 v124, 16, v57
	v_lshlrev_b32_e32 v129, 16, v137
	v_and_b32_e32 v171, 0xffff0000, v57
	v_and_b32_e32 v127, 0xffff0000, v137
	v_lshlrev_b32_e32 v161, 16, v44
	v_and_b32_e32 v163, 0xffff0000, v44
	v_lshlrev_b32_e32 v165, 16, v45
	v_and_b32_e32 v167, 0xffff0000, v45
	v_add_f32_e32 v156, v40, v41
	v_mul_f32_e32 v135, v38, v168
	global_load_dwordx4 v[38:41], v[148:149], off
	global_load_dwordx4 v[54:57], v[150:151], off
	global_load_dwordx4 v[42:45], v[46:47], off
	s_nop 0
	global_load_dwordx4 v[46:49], v[146:147], off
	v_cvt_pk_bf16_f32 v134, v136, v75
	v_pk_mul_f32 v[136:137], v[86:87], v[158:159]
	v_cvt_pk_bf16_f32 v135, v133, v135
	v_lshlrev_b32_e32 v120, 16, v138
	v_fma_f32 v75, v25, v119, v136
	v_add_f32_e32 v75, v75, v137
	v_pk_mul_f32 v[136:137], v[80:81], v[116:117]
	v_and_b32_e32 v172, 0xffff0000, v138
; __device__ __forceinline__ unsigned pk2(float lo, float hi) { return pg8::cvt_pk_bf16(lo, hi); }
; #define CV(e, qa, qb, qc, bv, LOHI) (LOHI(bv) * (w[0][e] * LOHI(qa) + w[1][e] * LOHI(qb) + w[2][e] * LOHI(qc)))
; __device__ __forceinline__ void conv_phase(const PT& T, int vc) {
;     ...
;         for (int i = 0; i < 8; ++i) { const u32x4 q0 = q[i], q1 = q[i + 1], q2 = q[i + 2], bb = b[i]; u32x4 o;
;     ...
;             o.x = pk2(CV(0, q0.x, q1.x, q2.x, bb.x, bflo), CV(1, q0.x, q1.x, q2.x, bb.x, bfhi)); o.y = pk2(CV(2, q0.y, q1.y, q2.y, bb.y, bflo), CV(3, q0.y, q1.y, q2.y, bb.y, bfhi));
;             o.z = pk2(CV(4, q0.z, q1.z, q2.z, bb.z, bflo), CV(5, q0.z, q1.z, q2.z, bb.z, bfhi)); o.w = pk2(CV(6, q0.w, q1.w, q2.w, bb.w, bflo), CV(7, q0.w, q1.w, q2.w, bb.w, bfhi));
;     ...
;             *(u32x4*)(YB + (size_t)(r0 + i) * D + c8) = o; }
	v_fma_f32 v116, v18, v160, v136
	v_add_f32_e32 v116, v116, v137
	v_pk_mul_f32 v[136:137], v[80:81], v[160:161]
	v_lshlrev_b32_e32 v173, 16, v139
	v_fma_f32 v133, v18, v117, v136
	v_add_f32_e32 v133, v133, v137
	v_pk_mul_f32 v[136:137], v[82:83], v[114:115]
	v_and_b32_e32 v174, 0xffff0000, v139
	v_fma_f32 v136, v19, v162, v136
	v_add_f32_e32 v136, v136, v137
	v_mul_f32_e32 v116, v116, v169
	v_mul_f32_e32 v136, v136, v170
	v_pk_mul_f32 v[138:139], v[82:83], v[162:163]
	v_cvt_pk_bf16_f32 v136, v116, v136
	v_lshlrev_b32_e32 v175, 16, v141
	v_fma_f32 v116, v19, v115, v138
	v_add_f32_e32 v116, v116, v139
	v_pk_mul_f32 v[138:139], v[76:77], v[128:129]
	v_mul_f32_e32 v75, v75, v174
	v_fma_f32 v128, v20, v164, v138
	v_add_f32_e32 v128, v128, v139
	v_pk_mul_f32 v[138:139], v[76:77], v[164:165]
	v_mul_f32_e32 v124, v128, v124
	v_fma_f32 v137, v20, v129, v138
	v_add_f32_e32 v137, v137, v139
	v_pk_mul_f32 v[138:139], v[78:79], v[126:127]
	v_mul_f32_e32 v128, v137, v175
	v_fma_f32 v138, v21, v166, v138
	v_add_f32_e32 v138, v138, v139
	v_mul_f32_e32 v137, v138, v171
	v_cvt_pk_bf16_f32 v137, v124, v137
	global_store_dwordx4 v[112:113], v[134:137], off
	v_pk_mul_f32 v[112:113], v[78:79], v[166:167]
	v_mul_f32_e32 v120, v152, v120
	v_mul_f32_e32 v139, v154, v172
	v_mul_f32_e32 v146, v156, v173
	v_cvt_pk_bf16_f32 v134, v120, v139
	v_cvt_pk_bf16_f32 v135, v146, v75
	v_fma_f32 v75, v21, v127, v112
	v_add_f32_e32 v75, v75, v113
	s_waitcnt vmcnt(0) lgkmcnt(0)
	v_lshlrev_b32_e32 v113, 16, v62
	v_lshlrev_b32_e32 v112, 16, v58
	v_pk_mov_b32 v[124:125], v[124:125], v[112:113] op_sel:[1,0]
	v_and_b32_e32 v141, 0xffff0000, v141
	v_pk_mul_f32 v[124:125], v[88:89], v[124:125]
	v_lshlrev_b32_e32 v168, 16, v140
	v_and_b32_e32 v140, 0xffff0000, v140
	v_mul_f32_e32 v75, v75, v141
	v_fma_f32 v124, v22, v153, v124
	v_mul_f32_e32 v133, v133, v168
	v_mul_f32_e32 v116, v116, v140
	v_cvt_pk_bf16_f32 v136, v133, v116
	v_cvt_pk_bf16_f32 v137, v128, v75
	v_lshlrev_b32_e32 v75, 16, v142
	v_add_f32_e32 v124, v124, v125
	v_mul_f32_e32 v75, v124, v75
	v_pk_mul_f32 v[124:125], v[98:99], v[112:113]
	v_lshlrev_b32_e32 v120, 16, v66
	v_fma_f32 v124, v6, v153, v124
	v_add_f32_e32 v124, v124, v125
	global_store_dwordx4 v[110:111], v[134:137], off
	v_lshl_add_u64 v[110:111], v[72:73], 0, v[130:131]
	v_mul_f32_e32 v130, v124, v120
	v_and_b32_e32 v125, 0xffff0000, v62
	v_and_b32_e32 v124, 0xffff0000, v58
	v_pk_mov_b32 v[122:123], v[122:123], v[124:125] op_sel:[1,0]
	v_and_b32_e32 v116, 0xffff0000, v142
	v_pk_mul_f32 v[122:123], v[90:91], v[122:123]
	v_and_b32_e32 v66, 0xffff0000, v66
	v_fma_f32 v58, v23, v155, v122
	v_add_f32_e32 v58, v58, v123
	v_pk_mul_f32 v[122:123], v[14:15], v[124:125]
	v_mul_f32_e32 v58, v58, v116
	v_fma_f32 v62, v7, v155, v122
	v_add_f32_e32 v62, v62, v123
	v_lshlrev_b32_e32 v123, 16, v63
	v_lshlrev_b32_e32 v122, 16, v59
	v_pk_mov_b32 v[120:121], v[120:121], v[122:123] op_sel:[1,0]
	v_cvt_pk_bf16_f32 v58, v75, v58
	v_mul_f32_e32 v75, v62, v66
	v_pk_mul_f32 v[120:121], v[84:85], v[120:121]
	v_lshlrev_b32_e32 v128, 16, v143
	v_fma_f32 v66, v24, v157, v120
	v_add_f32_e32 v66, v66, v121
	v_pk_mul_f32 v[120:121], v[96:97], v[122:123]
	v_mul_f32_e32 v116, v66, v128
	v_fma_f32 v66, v8, v157, v120
	v_lshlrev_b32_e32 v62, 16, v67
	v_add_f32_e32 v66, v66, v121
	v_mul_f32_e32 v120, v66, v62
	v_and_b32_e32 v63, 0xffff0000, v63
	v_and_b32_e32 v62, 0xffff0000, v59
	v_and_b32_e32 v121, 0xffff0000, v67
	v_pk_mov_b32 v[66:67], v[118:119], v[62:63] op_sel:[1,0]
	v_and_b32_e32 v133, 0xffff0000, v143
	v_pk_mul_f32 v[66:67], v[86:87], v[66:67]
	v_lshlrev_b32_e32 v134, 16, v144
	v_fma_f32 v59, v25, v159, v66
	v_add_f32_e32 v59, v59, v67
	v_pk_mul_f32 v[66:67], v[16:17], v[62:63]
	v_mul_f32_e32 v59, v59, v133
	v_fma_f32 v66, v9, v159, v66
	v_add_f32_e32 v66, v66, v67
	v_mul_f32_e32 v121, v66, v121
	v_lshlrev_b32_e32 v67, 16, v64
	v_lshlrev_b32_e32 v66, 16, v60
	v_cvt_pk_bf16_f32 v59, v116, v59
	v_pk_mov_b32 v[116:117], v[116:117], v[66:67] op_sel:[1,0]
	v_lshlrev_b32_e32 v118, 16, v68
	v_pk_mul_f32 v[116:117], v[80:81], v[116:117]
	v_and_b32_e32 v135, 0xffff0000, v144
	v_fma_f32 v116, v18, v161, v116
	v_add_f32_e32 v116, v116, v117
	v_mul_f32_e32 v119, v116, v134
	v_pk_mul_f32 v[116:117], v[94:95], v[66:67]
	v_and_b32_e32 v68, 0xffff0000, v68
	v_fma_f32 v116, v2, v161, v116
	v_add_f32_e32 v116, v116, v117
	v_mul_f32_e32 v128, v116, v118
	v_and_b32_e32 v117, 0xffff0000, v64
	v_and_b32_e32 v116, 0xffff0000, v60
	v_pk_mov_b32 v[114:115], v[114:115], v[116:117] op_sel:[1,0]
	v_lshlrev_b32_e32 v136, 16, v145
	v_pk_mul_f32 v[114:115], v[82:83], v[114:115]
	v_and_b32_e32 v137, 0xffff0000, v145
	v_fma_f32 v60, v19, v163, v114
	v_add_f32_e32 v60, v60, v115
	v_pk_mul_f32 v[114:115], v[10:11], v[116:117]
	v_mul_f32_e32 v60, v60, v135
	v_fma_f32 v64, v3, v163, v114
	v_add_f32_e32 v64, v64, v115
	v_lshlrev_b32_e32 v115, 16, v65
	v_lshlrev_b32_e32 v114, 16, v61
	v_cvt_pk_bf16_f32 v60, v119, v60
	v_pk_mov_b32 v[118:119], v[128:129], v[114:115] op_sel:[1,0]
	v_mul_f32_e32 v131, v64, v68
	v_pk_mul_f32 v[118:119], v[76:77], v[118:119]
	v_lshlrev_b32_e32 v64, 16, v69
	v_fma_f32 v68, v20, v165, v118
	v_add_f32_e32 v68, v68, v119
	v_pk_mul_f32 v[118:119], v[92:93], v[114:115]
	v_mul_f32_e32 v129, v68, v136
	v_fma_f32 v68, v4, v165, v118
	v_add_f32_e32 v68, v68, v119
	v_mul_f32_e32 v118, v68, v64
	v_and_b32_e32 v65, 0xffff0000, v65
	v_and_b32_e32 v64, 0xffff0000, v61
	v_and_b32_e32 v119, 0xffff0000, v69
	v_pk_mov_b32 v[68:69], v[126:127], v[64:65] op_sel:[1,0]
	s_nop 0
	v_pk_mul_f32 v[68:69], v[78:79], v[68:69]
	s_nop 0
	v_fma_f32 v61, v21, v167, v68
	v_add_f32_e32 v61, v61, v69
	v_mul_f32_e32 v61, v61, v137
; __device__ __forceinline__ unsigned pk2(float lo, float hi) { return pg8::cvt_pk_bf16(lo, hi); }
; #define CV(e, qa, qb, qc, bv, LOHI) (LOHI(bv) * (w[0][e] * LOHI(qa) + w[1][e] * LOHI(qb) + w[2][e] * LOHI(qc)))
; __device__ __forceinline__ void conv_phase(const PT& T, int vc) {
;     ...
;         for (int i = 0; i < 8; ++i) { const u32x4 q0 = q[i], q1 = q[i + 1], q2 = q[i + 2], bb = b[i]; u32x4 o;
;     ...
;             o.x = pk2(CV(0, q0.x, q1.x, q2.x, bb.x, bflo), CV(1, q0.x, q1.x, q2.x, bb.x, bfhi)); o.y = pk2(CV(2, q0.y, q1.y, q2.y, bb.y, bflo), CV(3, q0.y, q1.y, q2.y, bb.y, bfhi));
;             o.z = pk2(CV(4, q0.z, q1.z, q2.z, bb.z, bflo), CV(5, q0.z, q1.z, q2.z, bb.z, bfhi)); o.w = pk2(CV(6, q0.w, q1.w, q2.w, bb.w, bflo), CV(7, q0.w, q1.w, q2.w, bb.w, bfhi));
;     ...
;             *(u32x4*)(YB + (size_t)(r0 + i) * D + c8) = o; }
	v_cvt_pk_bf16_f32 v61, v129, v61
	v_pk_mul_f32 v[68:69], v[12:13], v[64:65]
	global_store_dwordx4 v[110:111], v[58:61], off
	v_and_b32_e32 v110, 0xffff0000, v52
	v_lshlrev_b32_e32 v111, 16, v53
	v_fma_f32 v61, v5, v167, v68
	v_add_f32_e32 v61, v61, v69
	v_cvt_pk_bf16_f32 v58, v130, v75
	v_cvt_pk_bf16_f32 v59, v120, v121
	v_mul_f32_e32 v61, v61, v119
	v_lshl_add_u64 v[68:69], v[72:73], 0, v[108:109]
	v_lshlrev_b32_e32 v109, 16, v52
	v_lshlrev_b32_e32 v52, 16, v26
	v_cvt_pk_bf16_f32 v60, v128, v131
	v_cvt_pk_bf16_f32 v61, v118, v61
	global_store_dwordx4 v[68:69], v[58:61], off
	v_and_b32_e32 v118, 0xffff0000, v53
	v_lshlrev_b32_e32 v53, 16, v30
	v_mov_b32_e32 v58, v112
	v_mov_b32_e32 v59, v52
	v_pk_mul_f32 v[58:59], v[88:89], v[58:59]
	v_lshlrev_b32_e32 v60, 16, v50
	v_fma_f32 v58, v22, v113, v58
	v_add_f32_e32 v58, v58, v59
	v_mul_f32_e32 v69, v58, v60
	v_pk_mul_f32 v[58:59], v[98:99], v[52:53]
	v_lshlrev_b32_e32 v61, 16, v34
	v_fma_f32 v58, v6, v113, v58
	v_add_f32_e32 v58, v58, v59
	v_and_b32_e32 v68, 0xffff0000, v50
	v_lshlrev_b32_e32 v75, 16, v51
	v_and_b32_e32 v108, 0xffff0000, v51
	v_lshl_add_u64 v[50:51], v[72:73], 0, v[106:107]
	v_mul_f32_e32 v106, v58, v61
	v_and_b32_e32 v58, 0xffff0000, v26
	v_mov_b32_e32 v60, v124
	v_mov_b32_e32 v61, v58
	v_pk_mul_f32 v[60:61], v[90:91], v[60:61]
	v_and_b32_e32 v59, 0xffff0000, v30
	v_fma_f32 v26, v23, v125, v60
	v_add_f32_e32 v26, v26, v61
	v_pk_mul_f32 v[60:61], v[14:15], v[58:59]
	v_mul_f32_e32 v26, v26, v68
	v_fma_f32 v30, v7, v125, v60
	v_lshlrev_b32_e32 v60, 16, v27
	v_cvt_pk_bf16_f32 v26, v69, v26
	v_mov_b32_e32 v68, v122
	v_mov_b32_e32 v69, v60
	v_and_b32_e32 v34, 0xffff0000, v34
	v_add_f32_e32 v30, v30, v61
	v_pk_mul_f32 v[68:69], v[84:85], v[68:69]
	v_mul_f32_e32 v107, v30, v34
	v_lshlrev_b32_e32 v61, 16, v31
	v_fma_f32 v34, v24, v123, v68
	v_add_f32_e32 v34, v34, v69
	v_pk_mul_f32 v[68:69], v[96:97], v[60:61]
	v_mul_f32_e32 v75, v34, v75
	v_fma_f32 v34, v8, v123, v68
	v_lshlrev_b32_e32 v30, 16, v35
	v_add_f32_e32 v34, v34, v69
	v_mul_f32_e32 v112, v34, v30
	v_and_b32_e32 v30, 0xffff0000, v27
	v_and_b32_e32 v68, 0xffff0000, v35
	v_mov_b32_e32 v34, v62
	v_mov_b32_e32 v35, v30
	v_pk_mul_f32 v[34:35], v[86:87], v[34:35]
	v_and_b32_e32 v31, 0xffff0000, v31
	v_fma_f32 v27, v25, v63, v34
	v_add_f32_e32 v27, v27, v35
	v_pk_mul_f32 v[34:35], v[16:17], v[30:31]
	v_mul_f32_e32 v27, v27, v108
	v_fma_f32 v34, v9, v63, v34
	v_add_f32_e32 v34, v34, v35
	v_cvt_pk_bf16_f32 v27, v75, v27
	v_mul_f32_e32 v75, v34, v68
	v_lshlrev_b32_e32 v34, 16, v28
	v_mov_b32_e32 v62, v66
	v_mov_b32_e32 v63, v34
	v_pk_mul_f32 v[62:63], v[80:81], v[62:63]
	v_lshlrev_b32_e32 v35, 16, v32
	v_fma_f32 v62, v18, v67, v62
	v_add_f32_e32 v62, v62, v63
	v_mul_f32_e32 v69, v62, v109
	v_pk_mul_f32 v[62:63], v[94:95], v[34:35]
	v_lshlrev_b32_e32 v68, 16, v36
	v_fma_f32 v62, v2, v67, v62
	v_add_f32_e32 v62, v62, v63
	v_mul_f32_e32 v108, v62, v68
	v_and_b32_e32 v62, 0xffff0000, v28
	v_mov_b32_e32 v66, v116
	v_mov_b32_e32 v67, v62
	v_pk_mul_f32 v[66:67], v[82:83], v[66:67]
	v_and_b32_e32 v63, 0xffff0000, v32
	v_fma_f32 v28, v19, v117, v66
	v_add_f32_e32 v28, v28, v67
	v_pk_mul_f32 v[66:67], v[10:11], v[62:63]
	v_mul_f32_e32 v28, v28, v110
	v_fma_f32 v32, v3, v117, v66
	v_lshlrev_b32_e32 v66, 16, v29
	v_cvt_pk_bf16_f32 v28, v69, v28
	v_mov_b32_e32 v68, v114
	v_mov_b32_e32 v69, v66
	v_and_b32_e32 v36, 0xffff0000, v36
	v_add_f32_e32 v32, v32, v67
	v_pk_mul_f32 v[68:69], v[76:77], v[68:69]
	v_mul_f32_e32 v109, v32, v36
	v_lshlrev_b32_e32 v67, 16, v33
	v_fma_f32 v36, v20, v115, v68
	v_add_f32_e32 v36, v36, v69
	v_pk_mul_f32 v[68:69], v[92:93], v[66:67]
	v_mul_f32_e32 v110, v36, v111
	v_fma_f32 v36, v4, v115, v68
	v_lshlrev_b32_e32 v32, 16, v37
	v_add_f32_e32 v36, v36, v69
	v_mul_f32_e32 v68, v36, v32
	v_and_b32_e32 v32, 0xffff0000, v29
	v_and_b32_e32 v69, 0xffff0000, v37
	v_mov_b32_e32 v36, v64
	v_mov_b32_e32 v37, v32
	v_pk_mul_f32 v[36:37], v[78:79], v[36:37]
	v_and_b32_e32 v33, 0xffff0000, v33
	v_fma_f32 v29, v21, v65, v36
	v_add_f32_e32 v29, v29, v37
	v_mul_f32_e32 v29, v29, v118
	v_cvt_pk_bf16_f32 v29, v110, v29
	v_pk_mul_f32 v[36:37], v[12:13], v[32:33]
	global_store_dwordx4 v[50:51], v[26:29], off
	v_lshlrev_b32_e32 v50, 16, v54
	v_and_b32_e32 v51, 0xffff0000, v54
	v_fma_f32 v29, v5, v65, v36
	v_add_f32_e32 v29, v29, v37
	v_cvt_pk_bf16_f32 v26, v106, v107
	v_mul_f32_e32 v29, v29, v69
	v_lshl_add_u64 v[36:37], v[72:73], 0, v[104:105]
	v_cvt_pk_bf16_f32 v27, v112, v75
	v_cvt_pk_bf16_f32 v28, v108, v109
	v_cvt_pk_bf16_f32 v29, v68, v29
	global_store_dwordx4 v[36:37], v[26:29], off
	v_lshlrev_b32_e32 v68, 16, v46
	v_and_b32_e32 v46, 0xffff0000, v46
	v_lshlrev_b32_e32 v26, 16, v38
; __device__ __forceinline__ unsigned pk2(float lo, float hi) { return pg8::cvt_pk_bf16(lo, hi); }
; #define CV(e, qa, qb, qc, bv, LOHI) (LOHI(bv) * (w[0][e] * LOHI(qa) + w[1][e] * LOHI(qb) + w[2][e] * LOHI(qc)))
; __device__ __forceinline__ void conv_phase(const PT& T, int vc) {
;     ...
;         q[0] = (u32x4){0u, 0u, 0u, 0u}; q[1] = q[0];
;         if (tt0 >= 2) { q[0] = *(const u32x4*)(Q + (size_t)(r0 - 2) * D + c8); q[1] = *(const u32x4*)(Q + (size_t)(r0 - 1) * D + c8); }
; #pragma unroll
;         for (int i = 0; i < 8; ++i) { const size_t off = (size_t)(r0 + i) * D + c8; q[2 + i] = *(const u32x4*)(Q + off); b[i] = *(const u32x4*)(Bg + off); }
; #pragma unroll
;         for (int i = 0; i < 8; ++i) { const u32x4 q0 = q[i], q1 = q[i + 1], q2 = q[i + 2], bb = b[i]; u32x4 o;
;     ...
;             o.x = pk2(CV(0, q0.x, q1.x, q2.x, bb.x, bflo), CV(1, q0.x, q1.x, q2.x, bb.x, bfhi)); o.y = pk2(CV(2, q0.y, q1.y, q2.y, bb.y, bflo), CV(3, q0.y, q1.y, q2.y, bb.y, bfhi));
;             o.z = pk2(CV(4, q0.z, q1.z, q2.z, bb.z, bflo), CV(5, q0.z, q1.z, q2.z, bb.z, bfhi)); o.w = pk2(CV(6, q0.w, q1.w, q2.w, bb.w, bflo), CV(7, q0.w, q1.w, q2.w, bb.w, bfhi));
;     ...
;             *(u32x4*)(YB + (size_t)(r0 + i) * D + c8) = o; }
	v_mov_b32_e32 v28, v52
	v_mov_b32_e32 v29, v26
	v_lshlrev_b32_e32 v27, 16, v42
	v_pk_mul_f32 v[28:29], v[88:89], v[28:29]
	v_pk_mul_f32 v[26:27], v[98:99], v[26:27]
	v_fma_f32 v28, v22, v53, v28
	v_add_f32_e32 v28, v28, v29
	v_fma_f32 v26, v6, v53, v26
	v_mul_f32_e32 v50, v28, v50
	v_add_f32_e32 v26, v26, v27
	v_and_b32_e32 v28, 0xffff0000, v38
	v_mul_f32_e32 v52, v26, v68
	v_mov_b32_e32 v26, v58
	v_mov_b32_e32 v27, v28
	v_and_b32_e32 v29, 0xffff0000, v42
	v_pk_mul_f32 v[26:27], v[90:91], v[26:27]
	v_pk_mul_f32 v[28:29], v[14:15], v[28:29]
	v_fma_f32 v26, v23, v59, v26
	v_add_f32_e32 v26, v26, v27
	v_fma_f32 v27, v7, v59, v28
	v_add_f32_e32 v27, v27, v29
	v_lshlrev_b32_e32 v28, 16, v39
	v_lshlrev_b32_e32 v29, 16, v43
	v_mul_f32_e32 v26, v26, v51
	v_mov_b32_e32 v51, v28
	v_pk_mul_f32 v[28:29], v[96:97], v[28:29]
	v_cvt_pk_bf16_f32 v26, v50, v26
	v_mov_b32_e32 v50, v60
	v_fma_f32 v28, v8, v61, v28
	v_mul_f32_e32 v42, v27, v46
	v_lshlrev_b32_e32 v27, 16, v47
	v_pk_mul_f32 v[50:51], v[84:85], v[50:51]
	v_add_f32_e32 v28, v28, v29
	v_fma_f32 v38, v24, v61, v50
	v_mul_f32_e32 v50, v28, v27
	v_and_b32_e32 v29, 0xffff0000, v43
	v_and_b32_e32 v28, 0xffff0000, v39
	v_lshlrev_b32_e32 v54, 16, v55
	v_add_f32_e32 v38, v38, v51
	v_mov_b32_e32 v39, v28
	v_pk_mul_f32 v[28:29], v[16:17], v[28:29]
	v_mul_f32_e32 v46, v38, v54
	v_mov_b32_e32 v38, v30
	v_fma_f32 v28, v9, v31, v28
	v_and_b32_e32 v47, 0xffff0000, v47
	v_pk_mul_f32 v[38:39], v[86:87], v[38:39]
	v_add_f32_e32 v28, v28, v29
	v_fma_f32 v27, v25, v31, v38
	v_mul_f32_e32 v38, v28, v47
	v_lshlrev_b32_e32 v28, 16, v40
	v_mov_b32_e32 v30, v34
	v_mov_b32_e32 v31, v28
	v_lshlrev_b32_e32 v29, 16, v44
	v_pk_mul_f32 v[30:31], v[80:81], v[30:31]
	v_pk_mul_f32 v[28:29], v[94:95], v[28:29]
	v_fma_f32 v30, v18, v35, v30
	v_lshlrev_b32_e32 v64, 16, v56
	v_add_f32_e32 v30, v30, v31
	v_fma_f32 v28, v2, v35, v28
	v_add_f32_e32 v27, v27, v39
	v_lshlrev_b32_e32 v39, 16, v48
	v_mul_f32_e32 v34, v30, v64
	v_add_f32_e32 v28, v28, v29
	v_and_b32_e32 v30, 0xffff0000, v40
	v_mul_f32_e32 v39, v28, v39
	v_mov_b32_e32 v28, v62
	v_mov_b32_e32 v29, v30
	v_and_b32_e32 v31, 0xffff0000, v44
	v_pk_mul_f32 v[28:29], v[82:83], v[28:29]
	v_pk_mul_f32 v[30:31], v[10:11], v[30:31]
	v_fma_f32 v28, v19, v63, v28
	v_and_b32_e32 v55, 0xffff0000, v55
	v_and_b32_e32 v56, 0xffff0000, v56
	v_add_f32_e32 v28, v28, v29
	v_fma_f32 v29, v3, v63, v30
	v_mul_f32_e32 v27, v27, v55
	v_and_b32_e32 v35, 0xffff0000, v48
	v_mul_f32_e32 v28, v28, v56
	v_add_f32_e32 v29, v29, v31
	v_lshlrev_b32_e32 v30, 16, v41
	v_lshlrev_b32_e32 v31, 16, v45
	v_cvt_pk_bf16_f32 v27, v46, v27
	v_cvt_pk_bf16_f32 v28, v34, v28
	v_mul_f32_e32 v40, v29, v35
	v_mov_b32_e32 v34, v66
	v_mov_b32_e32 v35, v30
	v_pk_mul_f32 v[30:31], v[92:93], v[30:31]
	v_pk_mul_f32 v[34:35], v[76:77], v[34:35]
	v_fma_f32 v30, v4, v67, v30
	v_lshlrev_b32_e32 v29, 16, v49
	v_fma_f32 v34, v20, v67, v34
	v_add_f32_e32 v30, v30, v31
	v_lshlrev_b32_e32 v65, 16, v57
	v_add_f32_e32 v34, v34, v35
	v_mul_f32_e32 v44, v30, v29
	v_and_b32_e32 v30, 0xffff0000, v41
	v_mul_f32_e32 v43, v34, v65
	v_mov_b32_e32 v34, v32
	v_mov_b32_e32 v35, v30
	v_pk_mul_f32 v[34:35], v[78:79], v[34:35]
	v_and_b32_e32 v57, 0xffff0000, v57
	v_fma_f32 v29, v21, v33, v34
	v_add_f32_e32 v29, v29, v35
	v_and_b32_e32 v31, 0xffff0000, v45
	v_mul_f32_e32 v29, v29, v57
	v_lshl_add_u64 v[36:37], v[72:73], 0, v[102:103]
	v_cvt_pk_bf16_f32 v29, v43, v29
	v_pk_mul_f32 v[30:31], v[12:13], v[30:31]
	global_store_dwordx4 v[36:37], v[26:29], off
	v_and_b32_e32 v46, 0xffff0000, v49
	s_nop 0
	v_fma_f32 v29, v5, v33, v30
	v_add_f32_e32 v29, v29, v31
	v_mul_f32_e32 v29, v29, v46
	v_lshl_add_u64 v[30:31], v[72:73], 0, v[100:101]
	v_cvt_pk_bf16_f32 v26, v52, v42
	v_cvt_pk_bf16_f32 v27, v50, v38
	v_cvt_pk_bf16_f32 v28, v39, v40
	v_cvt_pk_bf16_f32 v29, v44, v29
	global_store_dwordx4 v[30:31], v[26:29], off
	s_andn2_b64 exec, exec, s[8:9]
	s_cbranch_execz .LBB0_725
.LBB0_723:
	v_mov_b32_e32 v46, 0
	v_cmp_ne_u32_sdwa s[14:15], v132, v1 src0_sel:BYTE_0 src1_sel:DWORD
	v_mov_b32_e32 v47, 0
	v_mov_b32_e32 v48, 0
	v_mov_b32_e32 v49, 0
	v_mov_b32_e32 v38, 0
	v_mov_b32_e32 v39, 0
	v_mov_b32_e32 v40, 0
	v_mov_b32_e32 v41, 0
	s_and_saveexec_b64 s[20:21], s[14:15]
	s_cbranch_execz .LBB0_722
	v_add_u32_e32 v26, -9, v74
	v_ashrrev_i32_e32 v27, 31, v26
	v_add_u32_e32 v28, -8, v74
	v_lshlrev_b64 v[26:27], 11, v[26:27]
	v_ashrrev_i32_e32 v29, 31, v28
	v_lshl_add_u64 v[26:27], v[70:71], 0, v[26:27]
	v_lshlrev_b64 v[28:29], 11, v[28:29]
	v_lshl_add_u64 v[28:29], v[70:71], 0, v[28:29]
	global_load_dwordx4 v[46:49], v[26:27], off
	global_load_dwordx4 v[38:41], v[28:29], off
	s_branch .LBB0_722

; __device__ __forceinline__ unsigned pk2(float lo, float hi) { return pg8::cvt_pk_bf16(lo, hi); }
; template <int W>
; __device__ __forceinline__ void pool_run(const bf16_t* __restrict__ Pp, bf16_t* __restrict__ Dp, int r0, int tt0, int c8) {
;     u32x4 v[W - 1 + 8];
; #pragma unroll
;     for (int k = 0; k < W - 1; ++k) v[k] = (tt0 - (W - 1) + k >= 0) ? *(const u32x4*)(Pp + (size_t)(r0 - (W - 1) + k) * D + c8) : (u32x4){0u, 0u, 0u, 0u};
; #pragma unroll
;     for (int i = 0; i < 8; ++i) v[W - 1 + i] = *(const u32x4*)(Pp + (size_t)(r0 + i) * D + c8);
;     float s[8];
; #pragma unroll
;     for (int e = 0; e < 8; ++e) s[e] = 0.f;
; #pragma unroll
;     for (int k = 0; k < W - 1; ++k) { s[0] += bflo(v[k].x); s[1] += bfhi(v[k].x); s[2] += bflo(v[k].y); s[3] += bfhi(v[k].y); s[4] += bflo(v[k].z); s[5] += bfhi(v[k].z); s[6] += bflo(v[k].w); s[7] += bfhi(v[k].w); }
; #pragma unroll
;     for (int i = 0; i < 8; ++i) { const int tt = tt0 + i; const u32x4 x = v[W - 1 + i];
;         const float p[8] = {bflo(x.x), bfhi(x.x), bflo(x.y), bfhi(x.y), bflo(x.z), bfhi(x.z), bflo(x.w), bfhi(x.w)};
; #pragma unroll
;         for (int e = 0; e < 8; ++e) s[e] += p[e];
;         const int cnt = (tt + 1) < W ? (tt + 1) : W; const float inv = 1.0f / (float)cnt;
;         u32x4 o; o.x = pk2(s[0] * inv - p[0], s[1] * inv - p[1]); o.y = pk2(s[2] * inv - p[2], s[3] * inv - p[3]); o.z = pk2(s[4] * inv - p[4], s[5] * inv - p[5]); o.w = pk2(s[6] * inv - p[6], s[7] * inv - p[7]);
;         *(u32x4*)(Dp + (size_t)(r0 + i) * D + c8) = o;
;         const u32x4 y = v[i];
;         s[0] -= bflo(y.x); s[1] -= bfhi(y.x); s[2] -= bflo(y.y); s[3] -= bfhi(y.y); s[4] -= bflo(y.z); s[5] -= bfhi(y.z); s[6] -= bflo(y.w); s[7] -= bfhi(y.w); }
; }
.LBB0_730:
	s_or_b64 exec, exec, s[4:5]
	v_ashrrev_i32_e32 v99, 31, v98
	v_add_u32_e32 v4, 1, v98
	v_lshlrev_b64 v[58:59], 11, v[98:99]
	v_ashrrev_i32_e32 v5, 31, v4
	v_lshl_add_u64 v[2:3], v[94:95], 0, v[58:59]
	v_lshlrev_b64 v[60:61], 11, v[4:5]
	v_lshl_add_u64 v[4:5], v[94:95], 0, v[60:61]
	global_load_dwordx4 v[46:49], v[2:3], off
	global_load_dwordx4 v[50:53], v[4:5], off
	v_add_u32_e32 v2, 2, v98
	v_ashrrev_i32_e32 v3, 31, v2
	v_add_u32_e32 v4, 3, v98
	v_lshlrev_b64 v[42:43], 11, v[2:3]
	v_ashrrev_i32_e32 v5, 31, v4
	v_lshl_add_u64 v[2:3], v[94:95], 0, v[42:43]
	v_lshlrev_b64 v[40:41], 11, v[4:5]
	v_lshl_add_u64 v[4:5], v[94:95], 0, v[40:41]
	global_load_dwordx4 v[54:57], v[2:3], off
	global_load_dwordx4 v[18:21], v[4:5], off
	v_add_u32_e32 v2, 4, v98
	v_ashrrev_i32_e32 v3, 31, v2
	v_add_u32_e32 v4, 5, v98
	v_lshlrev_b64 v[38:39], 11, v[2:3]
	v_ashrrev_i32_e32 v5, 31, v4
	v_lshl_add_u64 v[2:3], v[94:95], 0, v[38:39]
	v_lshlrev_b64 v[36:37], 11, v[4:5]
	v_lshl_add_u64 v[4:5], v[94:95], 0, v[36:37]
	global_load_dwordx4 v[14:17], v[2:3], off
	global_load_dwordx4 v[10:13], v[4:5], off
	s_waitcnt vmcnt(0) lgkmcnt(0)
	v_and_b32_e32 v63, 0xffff0000, v26
	v_lshlrev_b32_e32 v64, 16, v27
	v_lshlrev_b32_e32 v45, 16, v26
	v_add_f32_e32 v26, 0, v63
	v_add_f32_e32 v65, 0, v64
	v_and_b32_e32 v66, 0xffff0000, v27
	v_lshlrev_b32_e32 v67, 16, v28
	v_and_b32_e32 v74, 0xffff0000, v22
	v_lshlrev_b32_e32 v75, 16, v23
	v_add_f32_e32 v27, 0, v66
	v_add_f32_e32 v68, 0, v67
	v_and_b32_e32 v28, 0xffff0000, v28
	v_lshlrev_b32_e32 v70, 16, v29
	v_and_b32_e32 v29, 0xffff0000, v29
	v_lshlrev_b32_e32 v73, 16, v22
	v_add_f32_e32 v22, v26, v74
	v_add_f32_e32 v26, v65, v75
	v_and_b32_e32 v65, 0xffff0000, v23
	v_lshlrev_b32_e32 v76, 16, v24
	v_add_f32_e32 v69, 0, v28
	v_add_f32_e32 v72, 0, v29
	v_add_f32_e32 v23, v27, v65
	v_add_f32_e32 v27, v68, v76
	v_and_b32_e32 v68, 0xffff0000, v24
	v_and_b32_e32 v77, 0xffff0000, v25
	v_add_f32_e32 v24, v69, v68
	v_lshlrev_b32_e32 v69, 16, v25
	v_add_f32_e32 v25, v72, v77
	v_lshlrev_b32_e32 v72, 16, v30
	v_and_b32_e32 v30, 0xffff0000, v30
	v_add_f32_e32 v22, v22, v30
	v_add_u32_e32 v2, 6, v98
	v_add_u32_e32 v4, 7, v98
	v_ashrrev_i32_e32 v3, 31, v2
	v_ashrrev_i32_e32 v5, 31, v4
	v_lshlrev_b32_e32 v78, 16, v31
	v_and_b32_e32 v31, 0xffff0000, v31
	v_lshlrev_b64 v[34:35], 11, v[2:3]
	v_lshlrev_b64 v[100:101], 11, v[4:5]
	v_add_f32_e32 v23, v23, v31
	v_lshl_add_u64 v[2:3], v[94:95], 0, v[34:35]
	v_lshl_add_u64 v[4:5], v[94:95], 0, v[100:101]
	v_add_f32_e32 v26, v26, v78
	global_load_dwordx4 v[6:9], v[2:3], off
	s_nop 0
	global_load_dwordx4 v[2:5], v[4:5], off
	v_lshlrev_b32_e32 v79, 16, v32
	v_and_b32_e32 v32, 0xffff0000, v32
	v_add_f32_e32 v24, v24, v32
	v_lshlrev_b32_e32 v80, 16, v33
	v_and_b32_e32 v33, 0xffff0000, v33
	v_add_f32_e32 v25, v25, v33
	v_add_f32_e32 v27, v27, v79
	v_add_f32_e32 v62, 0, v45
	v_add_f32_e32 v62, v62, v73
	v_add_f32_e32 v62, v62, v72
	v_add_f32_e32 v71, 0, v70
	v_add_f32_e32 v71, v71, v69
	v_add_f32_e32 v71, v71, v80
	v_lshlrev_b32_e32 v81, 16, v46
	v_and_b32_e32 v46, 0xffff0000, v46
	v_add_f32_e32 v85, v22, v46
	v_min_u32_e32 v22, 3, v117
	v_add_u32_e32 v22, 1, v22
	v_lshlrev_b32_e32 v82, 16, v47
	v_and_b32_e32 v47, 0xffff0000, v47
	v_cvt_f32_ubyte0_e32 v22, v22
	v_add_f32_e32 v87, v23, v47
	v_div_scale_f32 v23, s[4:5], v22, v22, 1.0
	v_add_f32_e32 v86, v26, v82
	v_rcp_f32_e32 v26, v23
	v_lshlrev_b32_e32 v83, 16, v48
	v_and_b32_e32 v48, 0xffff0000, v48
	v_add_f32_e32 v89, v24, v48
	v_fma_f32 v24, -v23, v26, 1.0
	v_lshlrev_b32_e32 v84, 16, v49
	v_and_b32_e32 v49, 0xffff0000, v49
	v_fmac_f32_e32 v26, v24, v26
	v_div_scale_f32 v24, vcc, 1.0, v22, 1.0
	v_add_f32_e32 v90, v25, v49
	v_mul_f32_e32 v25, v24, v26
	v_add_f32_e32 v88, v27, v83
	v_fma_f32 v27, -v23, v25, v24
	v_fmac_f32_e32 v25, v27, v26
	v_fma_f32 v23, -v23, v25, v24
	v_div_fmas_f32 v23, v23, v26, v25
	v_add_f32_e32 v62, v62, v81
	v_div_fixup_f32 v25, v23, v22, 1.0
	v_fma_f32 v22, v25, v62, -v81
	v_fma_f32 v23, v25, v85, -v46
	v_cvt_pk_bf16_f32 v22, v22, v23
	v_fma_f32 v23, v25, v86, -v82
	v_fma_f32 v24, v25, v87, -v47
	v_add_f32_e32 v71, v71, v84
	v_cvt_pk_bf16_f32 v23, v23, v24
	v_fma_f32 v24, v25, v88, -v83
	v_fma_f32 v26, v25, v89, -v48
	v_cvt_pk_bf16_f32 v24, v24, v26
	v_fma_f32 v26, v25, v71, -v84
	v_fma_f32 v25, v25, v90, -v49
	v_cvt_pk_bf16_f32 v25, v26, v25
	v_lshl_add_u64 v[26:27], v[96:97], 0, v[58:59]
	global_store_dwordx4 v[26:27], v[22:25], off
	v_lshlrev_b32_e32 v58, 16, v51
	v_and_b32_e32 v51, 0xffff0000, v51
	v_sub_f32_e32 v22, v62, v45
	v_lshlrev_b32_e32 v45, 16, v50
	v_sub_f32_e32 v23, v85, v63
	v_add_f32_e32 v63, v22, v45
	v_min_u32_e32 v22, 2, v117
	v_add_u32_e32 v22, 2, v22
	v_and_b32_e32 v50, 0xffff0000, v50
	v_cvt_f32_ubyte0_e32 v22, v22
	v_sub_f32_e32 v24, v86, v64
	v_add_f32_e32 v64, v23, v50
	v_div_scale_f32 v23, s[4:5], v22, v22, 1.0
	v_sub_f32_e32 v25, v87, v66
	v_add_f32_e32 v66, v24, v58
	v_rcp_f32_e32 v24, v23
	v_sub_f32_e32 v26, v88, v67
	v_add_f32_e32 v67, v25, v51
	v_lshlrev_b32_e32 v59, 16, v52
	v_fma_f32 v25, -v23, v24, 1.0
	v_fmac_f32_e32 v24, v25, v24
	v_div_scale_f32 v25, vcc, 1.0, v22, 1.0
	v_sub_f32_e32 v27, v89, v28
	v_sub_f32_e32 v28, v71, v70
	v_and_b32_e32 v52, 0xffff0000, v52
	v_add_f32_e32 v70, v26, v59
	v_mul_f32_e32 v26, v25, v24
	v_add_f32_e32 v71, v27, v52
	v_fma_f32 v27, -v23, v26, v25
	v_fmac_f32_e32 v26, v27, v24
	v_fma_f32 v23, -v23, v26, v25
	v_div_fmas_f32 v23, v23, v24, v26
	v_div_fixup_f32 v25, v23, v22, 1.0
	v_fma_f32 v22, v25, v63, -v45
	v_fma_f32 v23, v25, v64, -v50
	v_sub_f32_e32 v29, v90, v29
	v_lshlrev_b32_e32 v62, 16, v53
	v_and_b32_e32 v53, 0xffff0000, v53
	v_cvt_pk_bf16_f32 v22, v22, v23
; __device__ __forceinline__ unsigned pk2(float lo, float hi) { return pg8::cvt_pk_bf16(lo, hi); }
; template <int W>
; __device__ __forceinline__ void pool_run(const bf16_t* __restrict__ Pp, bf16_t* __restrict__ Dp, int r0, int tt0, int c8) {
;     ...
;     for (int i = 0; i < 8; ++i) { const int tt = tt0 + i; const u32x4 x = v[W - 1 + i];
;         const float p[8] = {bflo(x.x), bfhi(x.x), bflo(x.y), bfhi(x.y), bflo(x.z), bfhi(x.z), bflo(x.w), bfhi(x.w)};
; #pragma unroll
;         for (int e = 0; e < 8; ++e) s[e] += p[e];
;         const int cnt = (tt + 1) < W ? (tt + 1) : W; const float inv = 1.0f / (float)cnt;
;         u32x4 o; o.x = pk2(s[0] * inv - p[0], s[1] * inv - p[1]); o.y = pk2(s[2] * inv - p[2], s[3] * inv - p[3]); o.z = pk2(s[4] * inv - p[4], s[5] * inv - p[5]); o.w = pk2(s[6] * inv - p[6], s[7] * inv - p[7]);
;         *(u32x4*)(Dp + (size_t)(r0 + i) * D + c8) = o;
;         const u32x4 y = v[i];
;         s[0] -= bflo(y.x); s[1] -= bfhi(y.x); s[2] -= bflo(y.y); s[3] -= bfhi(y.y); s[4] -= bflo(y.z); s[5] -= bfhi(y.z); s[6] -= bflo(y.w); s[7] -= bfhi(y.w); }
; }
	v_fma_f32 v23, v25, v66, -v58
	v_fma_f32 v24, v25, v67, -v51
	v_add_f32_e32 v28, v28, v62
	v_add_f32_e32 v29, v29, v53
	v_cvt_pk_bf16_f32 v23, v23, v24
	v_fma_f32 v24, v25, v70, -v59
	v_fma_f32 v26, v25, v71, -v52
	v_cvt_pk_bf16_f32 v24, v24, v26
	v_fma_f32 v26, v25, v28, -v62
	v_fma_f32 v25, v25, v29, -v53
	v_cvt_pk_bf16_f32 v25, v26, v25
	v_lshl_add_u64 v[26:27], v[96:97], 0, v[60:61]
	global_store_dwordx4 v[26:27], v[22:25], off
	v_lshlrev_b32_e32 v60, 16, v54
	v_and_b32_e32 v54, 0xffff0000, v54
	v_sub_f32_e32 v22, v63, v73
	v_sub_f32_e32 v23, v64, v74
	v_sub_f32_e32 v25, v67, v65
	v_add_f32_e32 v65, v22, v60
	v_div_scale_f32 v22, s[4:5], v44, v44, 1.0
	v_sub_f32_e32 v24, v66, v75
	v_add_f32_e32 v66, v23, v54
	v_rcp_f32_e32 v23, v22
	v_lshlrev_b32_e32 v61, 16, v55
	v_add_f32_e32 v67, v24, v61
	v_and_b32_e32 v55, 0xffff0000, v55
	v_fma_f32 v24, -v22, v23, 1.0
	v_fmac_f32_e32 v23, v24, v23
	v_div_scale_f32 v24, vcc, 1.0, v44, 1.0
	v_sub_f32_e32 v26, v70, v76
	v_sub_f32_e32 v27, v71, v68
	v_lshlrev_b32_e32 v63, 16, v56
	v_add_f32_e32 v68, v25, v55
	v_mul_f32_e32 v25, v24, v23
	v_sub_f32_e32 v28, v28, v69
	v_add_f32_e32 v69, v26, v63
	v_fma_f32 v26, -v22, v25, v24
	v_fmac_f32_e32 v25, v26, v23
	v_fma_f32 v22, -v22, v25, v24
	v_div_fmas_f32 v22, v22, v23, v25
	v_div_fixup_f32 v25, v22, v44, 1.0
	v_and_b32_e32 v56, 0xffff0000, v56
	v_fma_f32 v22, v25, v65, -v60
	v_fma_f32 v23, v25, v66, -v54
	v_sub_f32_e32 v29, v29, v77
	v_lshlrev_b32_e32 v64, 16, v57
	v_and_b32_e32 v57, 0xffff0000, v57
	v_add_f32_e32 v70, v27, v56
	v_cvt_pk_bf16_f32 v22, v22, v23
	v_fma_f32 v23, v25, v67, -v61
	v_fma_f32 v24, v25, v68, -v55
	v_add_f32_e32 v28, v28, v64
	v_add_f32_e32 v29, v29, v57
	v_cvt_pk_bf16_f32 v23, v23, v24
	v_fma_f32 v24, v25, v69, -v63
	v_fma_f32 v26, v25, v70, -v56
	v_cvt_pk_bf16_f32 v24, v24, v26
	v_fma_f32 v26, v25, v28, -v64
	v_fma_f32 v25, v25, v29, -v57
	v_cvt_pk_bf16_f32 v25, v26, v25
	v_lshl_add_u64 v[26:27], v[96:97], 0, v[42:43]
	global_store_dwordx4 v[26:27], v[22:25], off
	v_sub_f32_e32 v27, v70, v32
	v_sub_f32_e32 v29, v29, v33
	v_sub_f32_e32 v22, v65, v72
	v_sub_f32_e32 v23, v66, v30
	v_sub_f32_e32 v25, v68, v31
	v_lshlrev_b32_e32 v30, 16, v18
	v_and_b32_e32 v31, 0xffff0000, v18
	v_sub_f32_e32 v24, v67, v78
	v_lshlrev_b32_e32 v32, 16, v19
	v_and_b32_e32 v33, 0xffff0000, v19
	v_add_f32_e32 v66, v22, v30
	v_add_f32_e32 v67, v23, v31
	s_mov_b32 s4, 0x3e800000
	v_sub_f32_e32 v26, v69, v79
	v_lshlrev_b32_e32 v42, 16, v20
	v_and_b32_e32 v43, 0xffff0000, v20
	v_add_f32_e32 v24, v24, v32
	v_add_f32_e32 v25, v25, v33
	v_fma_f32 v18, v66, s4, -v30
	v_fma_f32 v19, v67, s4, -v31
	v_sub_f32_e32 v28, v28, v80
	v_lshlrev_b32_e32 v44, 16, v21
	v_and_b32_e32 v65, 0xffff0000, v21
	v_add_f32_e32 v26, v26, v42
	v_add_f32_e32 v27, v27, v43
	v_cvt_pk_bf16_f32 v18, v18, v19
	v_fma_f32 v19, v24, s4, -v32
	v_fma_f32 v20, v25, s4, -v33
	v_add_f32_e32 v28, v28, v44
	v_add_f32_e32 v29, v29, v65
	v_cvt_pk_bf16_f32 v19, v19, v20
	v_fma_f32 v20, v26, s4, -v42
	v_fma_f32 v21, v27, s4, -v43
	v_cvt_pk_bf16_f32 v20, v20, v21
	v_fma_f32 v21, v28, s4, -v44
	v_fma_f32 v22, v29, s4, -v65
	v_cvt_pk_bf16_f32 v21, v21, v22
	v_lshl_add_u64 v[22:23], v[96:97], 0, v[40:41]
	global_store_dwordx4 v[22:23], v[18:21], off
	v_sub_f32_e32 v22, v26, v83
	v_lshlrev_b32_e32 v26, 16, v14
	v_sub_f32_e32 v18, v66, v81
	v_sub_f32_e32 v19, v67, v46
	v_and_b32_e32 v14, 0xffff0000, v14
	v_sub_f32_e32 v20, v24, v82
	v_sub_f32_e32 v21, v25, v47
	v_sub_f32_e32 v23, v27, v48
	v_lshlrev_b32_e32 v27, 16, v15
	v_and_b32_e32 v15, 0xffff0000, v15
	v_add_f32_e32 v40, v18, v26
	v_add_f32_e32 v41, v19, v14
	v_sub_f32_e32 v24, v28, v84
	v_lshlrev_b32_e32 v28, 16, v16
	v_and_b32_e32 v16, 0xffff0000, v16
	v_add_f32_e32 v20, v20, v27
	v_add_f32_e32 v21, v21, v15
	v_fma_f32 v18, v40, s4, -v26
	v_fma_f32 v14, v41, s4, -v14
	v_sub_f32_e32 v25, v29, v49
	v_lshlrev_b32_e32 v29, 16, v17
	v_and_b32_e32 v17, 0xffff0000, v17
	v_add_f32_e32 v22, v22, v28
	v_add_f32_e32 v23, v23, v16
	v_cvt_pk_bf16_f32 v14, v18, v14
	v_fma_f32 v18, v20, s4, -v27
	v_fma_f32 v15, v21, s4, -v15
	v_add_f32_e32 v24, v24, v29
	v_add_f32_e32 v25, v25, v17
	v_cvt_pk_bf16_f32 v15, v18, v15
	v_fma_f32 v18, v22, s4, -v28
	v_fma_f32 v16, v23, s4, -v16
	v_cvt_pk_bf16_f32 v16, v18, v16
	v_fma_f32 v18, v24, s4, -v29
	v_fma_f32 v17, v25, s4, -v17
	v_cvt_pk_bf16_f32 v17, v18, v17
	v_lshl_add_u64 v[18:19], v[96:97], 0, v[38:39]
	global_store_dwordx4 v[18:19], v[14:17], off
	v_sub_f32_e32 v18, v22, v59
	v_lshlrev_b32_e32 v22, 16, v10
	v_sub_f32_e32 v14, v40, v45
	v_sub_f32_e32 v15, v41, v50
	v_and_b32_e32 v10, 0xffff0000, v10
	v_sub_f32_e32 v16, v20, v58
	v_sub_f32_e32 v17, v21, v51
	v_sub_f32_e32 v19, v23, v52
	v_lshlrev_b32_e32 v23, 16, v11
	v_and_b32_e32 v11, 0xffff0000, v11
	v_add_f32_e32 v26, v14, v22
	v_add_f32_e32 v27, v15, v10
	v_sub_f32_e32 v20, v24, v62
	v_lshlrev_b32_e32 v24, 16, v12
	v_and_b32_e32 v12, 0xffff0000, v12
	v_add_f32_e32 v16, v16, v23
	v_add_f32_e32 v17, v17, v11
	v_fma_f32 v14, v26, s4, -v22
	v_fma_f32 v10, v27, s4, -v10
	v_sub_f32_e32 v21, v25, v53
	v_lshlrev_b32_e32 v25, 16, v13
	v_and_b32_e32 v13, 0xffff0000, v13
	v_add_f32_e32 v18, v18, v24
	v_add_f32_e32 v19, v19, v12
	v_cvt_pk_bf16_f32 v10, v14, v10
	v_fma_f32 v14, v16, s4, -v23
	v_fma_f32 v11, v17, s4, -v11
	v_add_f32_e32 v20, v20, v25
	v_add_f32_e32 v21, v21, v13
	v_cvt_pk_bf16_f32 v11, v14, v11
	v_fma_f32 v14, v18, s4, -v24
	v_fma_f32 v12, v19, s4, -v12
	v_cvt_pk_bf16_f32 v12, v14, v12
	v_fma_f32 v14, v20, s4, -v25
	v_fma_f32 v13, v21, s4, -v13
	v_cvt_pk_bf16_f32 v13, v14, v13
	v_lshl_add_u64 v[14:15], v[96:97], 0, v[36:37]
	global_store_dwordx4 v[14:15], v[10:13], off
	v_sub_f32_e32 v14, v18, v63
	s_waitcnt vmcnt(0) lgkmcnt(0)
; __device__ __forceinline__ unsigned pk2(float lo, float hi) { return pg8::cvt_pk_bf16(lo, hi); }
; template <int W>
; __device__ __forceinline__ void pool_run(const bf16_t* __restrict__ Pp, bf16_t* __restrict__ Dp, int r0, int tt0, int c8) {
;     u32x4 v[W - 1 + 8];
; #pragma unroll
;     for (int k = 0; k < W - 1; ++k) v[k] = (tt0 - (W - 1) + k >= 0) ? *(const u32x4*)(Pp + (size_t)(r0 - (W - 1) + k) * D + c8) : (u32x4){0u, 0u, 0u, 0u};
; #pragma unroll
;     for (int i = 0; i < 8; ++i) v[W - 1 + i] = *(const u32x4*)(Pp + (size_t)(r0 + i) * D + c8);
;     float s[8];
; #pragma unroll
;     for (int e = 0; e < 8; ++e) s[e] = 0.f;
; #pragma unroll
;     for (int k = 0; k < W - 1; ++k) { s[0] += bflo(v[k].x); s[1] += bfhi(v[k].x); s[2] += bflo(v[k].y); s[3] += bfhi(v[k].y); s[4] += bflo(v[k].z); s[5] += bfhi(v[k].z); s[6] += bflo(v[k].w); s[7] += bfhi(v[k].w); }
; #pragma unroll
;     for (int i = 0; i < 8; ++i) { const int tt = tt0 + i; const u32x4 x = v[W - 1 + i];
;         const float p[8] = {bflo(x.x), bfhi(x.x), bflo(x.y), bfhi(x.y), bflo(x.z), bfhi(x.z), bflo(x.w), bfhi(x.w)};
; #pragma unroll
;         for (int e = 0; e < 8; ++e) s[e] += p[e];
;         const int cnt = (tt + 1) < W ? (tt + 1) : W; const float inv = 1.0f / (float)cnt;
;         u32x4 o; o.x = pk2(s[0] * inv - p[0], s[1] * inv - p[1]); o.y = pk2(s[2] * inv - p[2], s[3] * inv - p[3]); o.z = pk2(s[4] * inv - p[4], s[5] * inv - p[5]); o.w = pk2(s[6] * inv - p[6], s[7] * inv - p[7]);
;         *(u32x4*)(Dp + (size_t)(r0 + i) * D + c8) = o;
;         const u32x4 y = v[i];
;         s[0] -= bflo(y.x); s[1] -= bfhi(y.x); s[2] -= bflo(y.y); s[3] -= bfhi(y.y); s[4] -= bflo(y.z); s[5] -= bfhi(y.z); s[6] -= bflo(y.w); s[7] -= bfhi(y.w); }
; }
; __device__ __forceinline__ void pool_phase(const PT& T, int vc) {
;     ...
;     for (int ri = vr * 4 + rsel; ri < 512; ri += R8 * 4) {
;         const int run = 512 * vx + ri, r0 = run * 8, tt0 = r0 & (SEQ - 1);
;         if (g == 0) pool_run<2>(Pp, Dp, r0, tt0, c8); else if (g == 1) pool_run<4>(Pp, Dp, r0, tt0, c8); else if (g == 2) pool_run<8>(Pp, Dp, r0, tt0, c8); else pool_run<16>(Pp, Dp, r0, tt0, c8);
	v_lshlrev_b32_e32 v18, 16, v6
	v_sub_f32_e32 v10, v26, v60
	v_sub_f32_e32 v11, v27, v54
	v_and_b32_e32 v6, 0xffff0000, v6
	v_sub_f32_e32 v12, v16, v61
	v_sub_f32_e32 v13, v17, v55
	v_sub_f32_e32 v15, v19, v56
	v_lshlrev_b32_e32 v19, 16, v7
	v_and_b32_e32 v7, 0xffff0000, v7
	v_add_f32_e32 v22, v10, v18
	v_add_f32_e32 v23, v11, v6
	v_sub_f32_e32 v16, v20, v64
	v_lshlrev_b32_e32 v20, 16, v8
	v_and_b32_e32 v8, 0xffff0000, v8
	v_add_f32_e32 v12, v12, v19
	v_add_f32_e32 v13, v13, v7
	v_fma_f32 v10, v22, s4, -v18
	v_fma_f32 v6, v23, s4, -v6
	v_sub_f32_e32 v17, v21, v57
	v_lshlrev_b32_e32 v21, 16, v9
	v_and_b32_e32 v9, 0xffff0000, v9
	v_add_f32_e32 v14, v14, v20
	v_add_f32_e32 v15, v15, v8
	v_cvt_pk_bf16_f32 v6, v10, v6
	v_fma_f32 v10, v12, s4, -v19
	v_fma_f32 v7, v13, s4, -v7
	v_add_f32_e32 v16, v16, v21
	v_add_f32_e32 v17, v17, v9
	v_cvt_pk_bf16_f32 v7, v10, v7
	v_fma_f32 v10, v14, s4, -v20
	v_fma_f32 v8, v15, s4, -v8
	v_cvt_pk_bf16_f32 v8, v10, v8
	v_fma_f32 v10, v16, s4, -v21
	v_fma_f32 v9, v17, s4, -v9
	v_cvt_pk_bf16_f32 v9, v10, v9
	v_lshl_add_u64 v[10:11], v[96:97], 0, v[34:35]
	global_store_dwordx4 v[10:11], v[6:9], off
	v_sub_f32_e32 v10, v14, v42
	v_lshlrev_b32_e32 v14, 16, v2
	v_sub_f32_e32 v6, v22, v30
	v_sub_f32_e32 v7, v23, v31
	v_and_b32_e32 v2, 0xffff0000, v2
	v_sub_f32_e32 v8, v12, v32
	v_sub_f32_e32 v9, v13, v33
	v_sub_f32_e32 v11, v15, v43
	v_lshlrev_b32_e32 v15, 16, v3
	v_and_b32_e32 v3, 0xffff0000, v3
	v_add_f32_e32 v6, v6, v14
	v_add_f32_e32 v7, v7, v2
	v_sub_f32_e32 v12, v16, v44
	v_sub_f32_e32 v13, v17, v65
	v_lshlrev_b32_e32 v16, 16, v4
	v_and_b32_e32 v4, 0xffff0000, v4
	v_lshlrev_b32_e32 v17, 16, v5
	v_and_b32_e32 v5, 0xffff0000, v5
	v_add_f32_e32 v8, v8, v15
	v_add_f32_e32 v9, v9, v3
	v_fma_f32 v6, v6, s4, -v14
	v_fma_f32 v2, v7, s4, -v2
	v_add_f32_e32 v10, v10, v16
	v_add_f32_e32 v11, v11, v4
	v_add_f32_e32 v13, v13, v5
	v_cvt_pk_bf16_f32 v2, v6, v2
	v_fma_f32 v6, v8, s4, -v15
	v_fma_f32 v3, v9, s4, -v3
	v_add_f32_e32 v12, v12, v17
	v_cvt_pk_bf16_f32 v3, v6, v3
	v_fma_f32 v6, v10, s4, -v16
	v_fma_f32 v4, v11, s4, -v4
	v_fma_f32 v5, v13, s4, -v5
	v_cvt_pk_bf16_f32 v4, v6, v4
	v_fma_f32 v6, v12, s4, -v17
	v_cvt_pk_bf16_f32 v5, v6, v5
.LBB0_731:
	v_add_u32_e32 v116, s10, v116
	s_movk_i32 s4, 0x1ff
	v_cmp_lt_i32_e32 vcc, s4, v116
	v_lshl_add_u64 v[6:7], v[96:97], 0, v[100:101]
	s_or_b64 s[6:7], vcc, s[6:7]
	v_add_u32_e32 v0, s11, v0
	global_store_dwordx4 v[6:7], v[2:5], off
	s_andn2_b64 exec, exec, s[6:7]
	s_cbranch_execz .LBB0_794
.LBB0_732:
	v_add_u32_e32 v98, s9, v0
	v_and_b32_e32 v117, 0x7f8, v0
	s_cmp_lt_i32 s8, 2
	s_mov_b64 s[4:5], -1
	s_cbranch_scc1 .LBB0_782
	s_cmp_gt_i32 s8, 2
	s_cbranch_scc0 .LBB0_765
	v_cmp_lt_u32_e32 vcc, 14, v117
	v_mov_b32_e32 v14, 0
	v_mov_b32_e32 v18, 0
	v_mov_b32_e32 v19, 0
	v_mov_b32_e32 v20, 0
	v_mov_b32_e32 v21, 0
	s_and_saveexec_b64 s[4:5], vcc
	s_cbranch_execz .LBB0_736
	v_add_u32_e32 v2, -15, v98
	v_ashrrev_i32_e32 v3, 31, v2
	v_lshlrev_b64 v[2:3], 11, v[2:3]
	v_lshl_add_u64 v[2:3], v[94:95], 0, v[2:3]
	global_load_dwordx4 v[18:21], v[2:3], off
.LBB0_736:
	s_or_b64 exec, exec, s[4:5]
	v_cmp_lt_u32_e32 vcc, 13, v117
	v_mov_b32_e32 v15, 0
	v_mov_b32_e32 v16, 0
	v_mov_b32_e32 v17, 0
	s_and_saveexec_b64 s[4:5], vcc
	s_cbranch_execz .LBB0_738
	v_add_u32_e32 v2, -14, v98
	v_ashrrev_i32_e32 v3, 31, v2
	v_lshlrev_b64 v[2:3], 11, v[2:3]
	v_lshl_add_u64 v[2:3], v[94:95], 0, v[2:3]
	global_load_dwordx4 v[14:17], v[2:3], off
.LBB0_738:
	s_or_b64 exec, exec, s[4:5]
	v_cmp_lt_u32_e32 vcc, 12, v117
	v_mov_b32_e32 v22, 0
	v_mov_b32_e32 v30, 0
	v_mov_b32_e32 v31, 0
	v_mov_b32_e32 v32, 0
	v_mov_b32_e32 v33, 0
	s_and_saveexec_b64 s[4:5], vcc
	s_cbranch_execz .LBB0_740
	v_add_u32_e32 v2, -13, v98
	v_ashrrev_i32_e32 v3, 31, v2
	v_lshlrev_b64 v[2:3], 11, v[2:3]
	v_lshl_add_u64 v[2:3], v[94:95], 0, v[2:3]
	global_load_dwordx4 v[30:33], v[2:3], off
.LBB0_740:
	s_or_b64 exec, exec, s[4:5]
	v_cmp_lt_u32_e32 vcc, 11, v117
	v_mov_b32_e32 v23, 0
	v_mov_b32_e32 v24, 0
	v_mov_b32_e32 v25, 0
	s_and_saveexec_b64 s[4:5], vcc
	s_cbranch_execz .LBB0_742
	v_add_u32_e32 v2, -12, v98
	v_ashrrev_i32_e32 v3, 31, v2
	v_lshlrev_b64 v[2:3], 11, v[2:3]
	v_lshl_add_u64 v[2:3], v[94:95], 0, v[2:3]
	global_load_dwordx4 v[22:25], v[2:3], off
.LBB0_742:
	s_or_b64 exec, exec, s[4:5]
	v_cmp_lt_u32_e32 vcc, 10, v117
	v_mov_b32_e32 v34, 0
	v_mov_b32_e32 v38, 0
	v_mov_b32_e32 v39, 0
	v_mov_b32_e32 v40, 0
	v_mov_b32_e32 v41, 0
	s_and_saveexec_b64 s[4:5], vcc
	s_cbranch_execz .LBB0_744
	v_add_u32_e32 v2, -11, v98
	v_ashrrev_i32_e32 v3, 31, v2
	v_lshlrev_b64 v[2:3], 11, v[2:3]
	v_lshl_add_u64 v[2:3], v[94:95], 0, v[2:3]
	global_load_dwordx4 v[38:41], v[2:3], off
.LBB0_744:
	s_or_b64 exec, exec, s[4:5]
	v_cmp_lt_u32_e32 vcc, 9, v117
	v_mov_b32_e32 v35, 0
	v_mov_b32_e32 v36, 0
	v_mov_b32_e32 v37, 0
	s_and_saveexec_b64 s[4:5], vcc
	s_cbranch_execz .LBB0_746
	v_add_u32_e32 v2, -10, v98
	v_ashrrev_i32_e32 v3, 31, v2
	v_lshlrev_b64 v[2:3], 11, v[2:3]
	v_lshl_add_u64 v[2:3], v[94:95], 0, v[2:3]
	global_load_dwordx4 v[34:37], v[2:3], off
.LBB0_746:
	s_or_b64 exec, exec, s[4:5]
	v_cmp_lt_u32_e32 vcc, 8, v117
	v_mov_b32_e32 v46, 0
	v_mov_b32_e32 v50, 0
	v_mov_b32_e32 v51, 0
	v_mov_b32_e32 v52, 0
	v_mov_b32_e32 v53, 0
	s_and_saveexec_b64 s[4:5], vcc
	s_cbranch_execz .LBB0_748
	v_add_u32_e32 v2, -9, v98
	v_ashrrev_i32_e32 v3, 31, v2
	v_lshlrev_b64 v[2:3], 11, v[2:3]
	v_lshl_add_u64 v[2:3], v[94:95], 0, v[2:3]
	global_load_dwordx4 v[50:53], v[2:3], off
.LBB0_748:
	s_or_b64 exec, exec, s[4:5]
	v_cmp_ne_u32_e32 vcc, 0, v117
	v_mov_b32_e32 v47, 0
	v_mov_b32_e32 v48, 0
	v_mov_b32_e32 v49, 0
	s_and_saveexec_b64 s[4:5], vcc
	s_cbranch_execz .LBB0_750
	v_add_u32_e32 v2, -8, v98
	v_ashrrev_i32_e32 v3, 31, v2
	v_lshlrev_b64 v[2:3], 11, v[2:3]
	v_lshl_add_u64 v[2:3], v[94:95], 0, v[2:3]
	global_load_dwordx4 v[46:49], v[2:3], off
; template <int W>
; __device__ __forceinline__ void pool_run(const bf16_t* __restrict__ Pp, bf16_t* __restrict__ Dp, int r0, int tt0, int c8) {
;     ...
;     for (int k = 0; k < W - 1; ++k) v[k] = (tt0 - (W - 1) + k >= 0) ? *(const u32x4*)(Pp + (size_t)(r0 - (W - 1) + k) * D + c8) : (u32x4){0u, 0u, 0u, 0u};
; #pragma unroll
;     for (int i = 0; i < 8; ++i) v[W - 1 + i] = *(const u32x4*)(Pp + (size_t)(r0 + i) * D + c8);
;     float s[8];
; #pragma unroll
;     for (int e = 0; e < 8; ++e) s[e] = 0.f;
; #pragma unroll
;     for (int k = 0; k < W - 1; ++k) { s[0] += bflo(v[k].x); s[1] += bfhi(v[k].x); s[2] += bflo(v[k].y); s[3] += bfhi(v[k].y); s[4] += bflo(v[k].z); s[5] += bfhi(v[k].z); s[6] += bflo(v[k].w); s[7] += bfhi(v[k].w); }
; #pragma unroll
;     for (int i = 0; i < 8; ++i) { const int tt = tt0 + i; const u32x4 x = v[W - 1 + i];
;         const float p[8] = {bflo(x.x), bfhi(x.x), bflo(x.y), bfhi(x.y), bflo(x.z), bfhi(x.z), bflo(x.w), bfhi(x.w)};
; #pragma unroll
;         for (int e = 0; e < 8; ++e) s[e] += p[e];
.LBB0_750:
	s_or_b64 exec, exec, s[4:5]
	v_mov_b32_e32 v54, 0
	v_mov_b32_e32 v58, 0
	v_mov_b32_e32 v59, 0
	v_mov_b32_e32 v60, 0
	v_mov_b32_e32 v61, 0
	s_and_saveexec_b64 s[4:5], vcc
	s_cbranch_execz .LBB0_752
	v_add_u32_e32 v2, -7, v98
	v_ashrrev_i32_e32 v3, 31, v2
	v_lshlrev_b64 v[2:3], 11, v[2:3]
	v_lshl_add_u64 v[2:3], v[94:95], 0, v[2:3]
	global_load_dwordx4 v[58:61], v[2:3], off
.LBB0_752:
	s_or_b64 exec, exec, s[4:5]
	v_mov_b32_e32 v55, 0
	v_mov_b32_e32 v56, 0
	v_mov_b32_e32 v57, 0
	s_and_saveexec_b64 s[4:5], vcc
	s_cbranch_execz .LBB0_754
	v_add_u32_e32 v2, -6, v98
	v_ashrrev_i32_e32 v3, 31, v2
	v_lshlrev_b64 v[2:3], 11, v[2:3]
	v_lshl_add_u64 v[2:3], v[94:95], 0, v[2:3]
	global_load_dwordx4 v[54:57], v[2:3], off
.LBB0_754:
	s_or_b64 exec, exec, s[4:5]
	v_mov_b32_e32 v66, 0
	v_mov_b32_e32 v70, 0
	v_mov_b32_e32 v71, 0
	v_mov_b32_e32 v72, 0
	v_mov_b32_e32 v73, 0
	s_and_saveexec_b64 s[4:5], vcc
	s_cbranch_execz .LBB0_756
	v_add_u32_e32 v2, -5, v98
	v_ashrrev_i32_e32 v3, 31, v2
	v_lshlrev_b64 v[2:3], 11, v[2:3]
	v_lshl_add_u64 v[2:3], v[94:95], 0, v[2:3]
	global_load_dwordx4 v[70:73], v[2:3], off
.LBB0_756:
	s_or_b64 exec, exec, s[4:5]
	v_mov_b32_e32 v67, 0
	v_mov_b32_e32 v68, 0
	v_mov_b32_e32 v69, 0
	s_and_saveexec_b64 s[4:5], vcc
	s_cbranch_execz .LBB0_758
	v_add_u32_e32 v2, -4, v98
	v_ashrrev_i32_e32 v3, 31, v2
	v_lshlrev_b64 v[2:3], 11, v[2:3]
	v_lshl_add_u64 v[2:3], v[94:95], 0, v[2:3]
	global_load_dwordx4 v[66:69], v[2:3], off
.LBB0_758:
	s_or_b64 exec, exec, s[4:5]
	v_mov_b32_e32 v74, 0
	v_mov_b32_e32 v82, 0
	v_mov_b32_e32 v83, 0
	v_mov_b32_e32 v84, 0
	v_mov_b32_e32 v85, 0
	s_and_saveexec_b64 s[4:5], vcc
	s_cbranch_execz .LBB0_760
	v_add_u32_e32 v2, -3, v98
	v_ashrrev_i32_e32 v3, 31, v2
	v_lshlrev_b64 v[2:3], 11, v[2:3]
	v_lshl_add_u64 v[2:3], v[94:95], 0, v[2:3]
	global_load_dwordx4 v[82:85], v[2:3], off
.LBB0_760:
	s_or_b64 exec, exec, s[4:5]
	v_mov_b32_e32 v75, 0
	v_mov_b32_e32 v76, 0
	v_mov_b32_e32 v77, 0
	s_and_saveexec_b64 s[4:5], vcc
	s_cbranch_execz .LBB0_762
	v_add_u32_e32 v2, -2, v98
	v_ashrrev_i32_e32 v3, 31, v2
	v_lshlrev_b64 v[2:3], 11, v[2:3]
	v_lshl_add_u64 v[2:3], v[94:95], 0, v[2:3]
	global_load_dwordx4 v[74:77], v[2:3], off
.LBB0_762:
	s_or_b64 exec, exec, s[4:5]
	v_mov_b32_e32 v86, 0
	v_mov_b32_e32 v87, 0
	v_mov_b32_e32 v88, 0
	v_mov_b32_e32 v89, 0
	s_and_saveexec_b64 s[4:5], vcc
	s_cbranch_execz .LBB0_764
	v_add_u32_e32 v2, -1, v98
	v_ashrrev_i32_e32 v3, 31, v2
	v_lshlrev_b64 v[2:3], 11, v[2:3]
	v_lshl_add_u64 v[2:3], v[94:95], 0, v[2:3]
	global_load_dwordx4 v[86:89], v[2:3], off
.LBB0_764:
	s_or_b64 exec, exec, s[4:5]
	v_ashrrev_i32_e32 v99, 31, v98
	v_add_u32_e32 v4, 1, v98
	v_lshlrev_b64 v[114:115], 11, v[98:99]
	v_ashrrev_i32_e32 v5, 31, v4
	v_lshl_add_u64 v[2:3], v[94:95], 0, v[114:115]
	v_lshlrev_b64 v[112:113], 11, v[4:5]
	v_lshl_add_u64 v[4:5], v[94:95], 0, v[112:113]
	global_load_dwordx4 v[90:93], v[2:3], off
	global_load_dwordx4 v[78:81], v[4:5], off
	s_waitcnt vmcnt(0) lgkmcnt(0)
	v_and_b32_e32 v119, 0xffff0000, v18
	v_lshlrev_b32_e32 v120, 16, v19
	v_lshlrev_b32_e32 v99, 16, v18
	v_add_f32_e32 v18, 0, v119
	v_add_f32_e32 v121, 0, v120
	v_and_b32_e32 v122, 0xffff0000, v19
	v_lshlrev_b32_e32 v123, 16, v20
	v_and_b32_e32 v130, 0xffff0000, v14
	v_lshlrev_b32_e32 v131, 16, v15
	v_add_f32_e32 v19, 0, v122
	v_add_f32_e32 v124, 0, v123
	v_and_b32_e32 v125, 0xffff0000, v20
	v_lshlrev_b32_e32 v126, 16, v21
	v_lshlrev_b32_e32 v129, 16, v14
	v_add_f32_e32 v14, v18, v130
	v_add_f32_e32 v18, v121, v131
	v_and_b32_e32 v121, 0xffff0000, v15
	v_lshlrev_b32_e32 v132, 16, v16
	v_add_f32_e32 v118, 0, v99
	v_add_f32_e32 v20, 0, v125
	v_add_f32_e32 v127, 0, v126
	v_and_b32_e32 v128, 0xffff0000, v21
	v_add_f32_e32 v15, v19, v121
	v_add_f32_e32 v19, v124, v132
	v_and_b32_e32 v124, 0xffff0000, v16
	v_lshlrev_b32_e32 v133, 16, v17
	v_add_f32_e32 v21, 0, v128
	v_add_f32_e32 v118, v118, v129
	v_add_f32_e32 v16, v20, v124
	v_add_f32_e32 v20, v127, v133
	v_and_b32_e32 v127, 0xffff0000, v17
	v_lshlrev_b32_e32 v134, 16, v30
	v_lshlrev_b32_e32 v135, 16, v31
	v_and_b32_e32 v138, 0xffff0000, v32
	v_add_f32_e32 v17, v21, v127
	v_add_f32_e32 v21, v118, v134
	v_and_b32_e32 v118, 0xffff0000, v30
	v_add_f32_e32 v18, v18, v135
	v_and_b32_e32 v136, 0xffff0000, v31
	v_lshlrev_b32_e32 v137, 16, v32
	v_add_f32_e32 v16, v16, v138
	v_lshlrev_b32_e32 v143, 16, v23
	v_and_b32_e32 v146, 0xffff0000, v24
	v_add_f32_e32 v14, v14, v118
	v_add_f32_e32 v15, v15, v136
	v_add_f32_e32 v19, v19, v137
	v_and_b32_e32 v140, 0xffff0000, v33
	v_and_b32_e32 v142, 0xffff0000, v22
	v_add_f32_e32 v18, v18, v143
	v_and_b32_e32 v144, 0xffff0000, v23
	v_lshlrev_b32_e32 v145, 16, v24
	v_add_f32_e32 v16, v16, v146
	v_lshlrev_b32_e32 v151, 16, v39
	v_lshlrev_b32_e32 v153, 16, v40
	v_and_b32_e32 v40, 0xffff0000, v40
	v_add_f32_e32 v17, v17, v140
	v_add_f32_e32 v14, v14, v142
	v_add_f32_e32 v15, v15, v144
	v_add_f32_e32 v19, v19, v145
	v_and_b32_e32 v148, 0xffff0000, v25
	v_and_b32_e32 v150, 0xffff0000, v38
	v_add_f32_e32 v18, v18, v151
	v_and_b32_e32 v152, 0xffff0000, v39
	v_add_f32_e32 v16, v16, v40
	v_lshlrev_b32_e32 v24, 16, v35
	v_and_b32_e32 v31, 0xffff0000, v36
	v_lshlrev_b32_e32 v139, 16, v33
	v_lshlrev_b32_e32 v147, 16, v25
	v_add_f32_e32 v17, v17, v148
	v_add_f32_e32 v14, v14, v150
	v_add_f32_e32 v15, v15, v152
	v_add_f32_e32 v19, v19, v153
	v_lshlrev_b32_e32 v154, 16, v41
	v_and_b32_e32 v41, 0xffff0000, v41
	v_and_b32_e32 v23, 0xffff0000, v34
	v_add_f32_e32 v18, v18, v24
	v_and_b32_e32 v25, 0xffff0000, v35
	v_lshlrev_b32_e32 v30, 16, v36
	v_add_f32_e32 v36, v16, v31
	v_lshlrev_b32_e32 v16, 16, v51
	v_add_f32_e32 v20, v20, v139
	v_lshlrev_b32_e32 v141, 16, v22
; __device__ __forceinline__ unsigned pk2(float lo, float hi) { return pg8::cvt_pk_bf16(lo, hi); }
; template <int W>
; __device__ __forceinline__ void pool_run(const bf16_t* __restrict__ Pp, bf16_t* __restrict__ Dp, int r0, int tt0, int c8) {
;     ...
;     for (int i = 0; i < 8; ++i) v[W - 1 + i] = *(const u32x4*)(Pp + (size_t)(r0 + i) * D + c8);
;     float s[8];
; #pragma unroll
;     for (int e = 0; e < 8; ++e) s[e] = 0.f;
; #pragma unroll
;     for (int k = 0; k < W - 1; ++k) { s[0] += bflo(v[k].x); s[1] += bfhi(v[k].x); s[2] += bflo(v[k].y); s[3] += bfhi(v[k].y); s[4] += bflo(v[k].z); s[5] += bfhi(v[k].z); s[6] += bflo(v[k].w); s[7] += bfhi(v[k].w); }
; #pragma unroll
;     for (int i = 0; i < 8; ++i) { const int tt = tt0 + i; const u32x4 x = v[W - 1 + i];
;         const float p[8] = {bflo(x.x), bfhi(x.x), bflo(x.y), bfhi(x.y), bflo(x.z), bfhi(x.z), bflo(x.w), bfhi(x.w)};
; #pragma unroll
;         for (int e = 0; e < 8; ++e) s[e] += p[e];
;         const int cnt = (tt + 1) < W ? (tt + 1) : W; const float inv = 1.0f / (float)cnt;
;         u32x4 o; o.x = pk2(s[0] * inv - p[0], s[1] * inv - p[1]); o.y = pk2(s[2] * inv - p[2], s[3] * inv - p[3]); o.z = pk2(s[4] * inv - p[4], s[5] * inv - p[5]); o.w = pk2(s[6] * inv - p[6], s[7] * inv - p[7]);
	v_add_f32_e32 v17, v17, v41
	v_lshlrev_b32_e32 v22, 16, v34
	v_add_f32_e32 v34, v14, v23
	v_add_f32_e32 v35, v15, v25
	v_add_f32_e32 v19, v19, v30
	v_and_b32_e32 v33, 0xffff0000, v37
	v_lshlrev_b32_e32 v14, 16, v50
	v_and_b32_e32 v15, 0xffff0000, v50
	v_add_f32_e32 v50, v18, v16
	v_lshlrev_b32_e32 v18, 16, v52
	v_add_f32_e32 v21, v21, v141
	v_add_f32_e32 v20, v20, v147
	v_lshlrev_b32_e32 v149, 16, v38
	v_lshlrev_b32_e32 v32, 16, v37
	v_add_f32_e32 v37, v17, v33
	v_add_f32_e32 v34, v34, v15
	v_and_b32_e32 v17, 0xffff0000, v51
	v_add_f32_e32 v51, v19, v18
	v_and_b32_e32 v19, 0xffff0000, v52
	v_lshlrev_b32_e32 v52, 16, v46
	v_and_b32_e32 v46, 0xffff0000, v46
	v_add_f32_e32 v21, v21, v149
	v_add_f32_e32 v20, v20, v154
	v_add_f32_e32 v35, v35, v17
	v_add_f32_e32 v34, v34, v46
	v_lshlrev_b32_e32 v46, 16, v47
	v_and_b32_e32 v47, 0xffff0000, v47
	v_add_f32_e32 v21, v21, v22
	v_add_f32_e32 v38, v20, v32
	v_add_f32_e32 v36, v36, v19
	v_lshlrev_b32_e32 v20, 16, v53
	v_add_f32_e32 v35, v35, v47
	v_lshlrev_b32_e32 v47, 16, v48
	v_and_b32_e32 v48, 0xffff0000, v48
	v_add_f32_e32 v39, v21, v14
	v_add_f32_e32 v38, v38, v20
	v_and_b32_e32 v21, 0xffff0000, v53
	v_add_f32_e32 v36, v36, v48
	v_lshlrev_b32_e32 v48, 16, v49
	v_add_f32_e32 v37, v37, v21
	v_add_f32_e32 v38, v38, v48
	v_and_b32_e32 v48, 0xffff0000, v49
	v_add_f32_e32 v39, v39, v52
	v_add_f32_e32 v37, v37, v48
	v_lshlrev_b32_e32 v48, 16, v58
	v_add_f32_e32 v39, v39, v48
	v_and_b32_e32 v48, 0xffff0000, v58
	v_add_f32_e32 v46, v50, v46
	v_add_f32_e32 v34, v34, v48
	v_lshlrev_b32_e32 v48, 16, v59
	v_add_f32_e32 v46, v46, v48
	v_and_b32_e32 v48, 0xffff0000, v59
	v_add_f32_e32 v47, v51, v47
	v_add_f32_e32 v35, v35, v48
	v_lshlrev_b32_e32 v48, 16, v60
	v_add_f32_e32 v47, v47, v48
	v_and_b32_e32 v48, 0xffff0000, v60
	v_add_f32_e32 v36, v36, v48
	v_lshlrev_b32_e32 v48, 16, v61
	v_add_f32_e32 v38, v38, v48
	v_and_b32_e32 v48, 0xffff0000, v61
	v_add_f32_e32 v37, v37, v48
	v_lshlrev_b32_e32 v48, 16, v54
	v_add_f32_e32 v39, v39, v48
	v_and_b32_e32 v48, 0xffff0000, v54
	v_add_f32_e32 v34, v34, v48
	v_lshlrev_b32_e32 v48, 16, v55
	v_add_f32_e32 v46, v46, v48
	v_and_b32_e32 v48, 0xffff0000, v55
	v_add_f32_e32 v35, v35, v48
	v_lshlrev_b32_e32 v48, 16, v56
	v_add_u32_e32 v2, 2, v98
	v_add_f32_e32 v47, v47, v48
	v_and_b32_e32 v48, 0xffff0000, v56
	v_ashrrev_i32_e32 v3, 31, v2
	v_add_u32_e32 v4, 3, v98
	v_add_f32_e32 v36, v36, v48
	v_lshlrev_b32_e32 v48, 16, v57
	v_lshlrev_b64 v[110:111], 11, v[2:3]
	v_ashrrev_i32_e32 v5, 31, v4
	v_add_f32_e32 v38, v38, v48
	v_and_b32_e32 v48, 0xffff0000, v57
	v_lshl_add_u64 v[2:3], v[94:95], 0, v[110:111]
	v_lshlrev_b64 v[108:109], 11, v[4:5]
	v_add_f32_e32 v37, v37, v48
	v_lshlrev_b32_e32 v48, 16, v70
	v_lshl_add_u64 v[4:5], v[94:95], 0, v[108:109]
	global_load_dwordx4 v[62:65], v[2:3], off
	global_load_dwordx4 v[42:45], v[4:5], off
	v_add_f32_e32 v39, v39, v48
	v_and_b32_e32 v48, 0xffff0000, v70
	v_add_f32_e32 v34, v34, v48
	v_lshlrev_b32_e32 v48, 16, v71
	v_add_f32_e32 v46, v46, v48
	v_and_b32_e32 v48, 0xffff0000, v71
	v_add_f32_e32 v35, v35, v48
	v_lshlrev_b32_e32 v48, 16, v72
	v_add_f32_e32 v47, v47, v48
	v_and_b32_e32 v48, 0xffff0000, v72
	v_add_f32_e32 v36, v36, v48
	v_lshlrev_b32_e32 v48, 16, v73
	v_add_f32_e32 v38, v38, v48
	v_and_b32_e32 v48, 0xffff0000, v73
	v_add_f32_e32 v37, v37, v48
	v_lshlrev_b32_e32 v48, 16, v66
	v_add_f32_e32 v39, v39, v48
	v_and_b32_e32 v48, 0xffff0000, v66
	v_add_f32_e32 v34, v34, v48
	v_lshlrev_b32_e32 v48, 16, v67
	v_add_f32_e32 v46, v46, v48
	v_and_b32_e32 v48, 0xffff0000, v67
	v_add_f32_e32 v35, v35, v48
	v_lshlrev_b32_e32 v48, 16, v68
	v_add_f32_e32 v47, v47, v48
	v_and_b32_e32 v48, 0xffff0000, v68
	v_add_f32_e32 v36, v36, v48
	v_lshlrev_b32_e32 v48, 16, v69
	v_add_f32_e32 v38, v38, v48
	v_and_b32_e32 v48, 0xffff0000, v69
	v_add_f32_e32 v37, v37, v48
	v_lshlrev_b32_e32 v48, 16, v82
	v_add_f32_e32 v39, v39, v48
	v_and_b32_e32 v48, 0xffff0000, v82
	v_add_f32_e32 v34, v34, v48
	v_lshlrev_b32_e32 v48, 16, v83
	v_add_f32_e32 v46, v46, v48
	v_and_b32_e32 v48, 0xffff0000, v83
	v_add_f32_e32 v35, v35, v48
	v_lshlrev_b32_e32 v48, 16, v84
	v_add_f32_e32 v47, v47, v48
	v_and_b32_e32 v48, 0xffff0000, v84
	v_add_f32_e32 v36, v36, v48
	v_lshlrev_b32_e32 v48, 16, v85
	v_add_f32_e32 v38, v38, v48
	v_and_b32_e32 v48, 0xffff0000, v85
	v_add_f32_e32 v37, v37, v48
	v_lshlrev_b32_e32 v48, 16, v74
	v_add_f32_e32 v39, v39, v48
	v_and_b32_e32 v48, 0xffff0000, v74
	v_add_f32_e32 v34, v34, v48
	v_lshlrev_b32_e32 v48, 16, v75
	v_add_f32_e32 v46, v46, v48
	v_and_b32_e32 v48, 0xffff0000, v75
	v_add_f32_e32 v35, v35, v48
	v_lshlrev_b32_e32 v48, 16, v76
	v_add_f32_e32 v47, v47, v48
	v_and_b32_e32 v48, 0xffff0000, v76
	v_add_f32_e32 v36, v36, v48
	v_lshlrev_b32_e32 v48, 16, v77
	v_add_f32_e32 v38, v38, v48
	v_and_b32_e32 v48, 0xffff0000, v77
	v_add_f32_e32 v37, v37, v48
	v_lshlrev_b32_e32 v48, 16, v86
	v_add_f32_e32 v39, v39, v48
	v_and_b32_e32 v48, 0xffff0000, v86
	v_add_f32_e32 v34, v34, v48
	v_lshlrev_b32_e32 v48, 16, v87
	v_add_f32_e32 v46, v46, v48
	v_and_b32_e32 v48, 0xffff0000, v87
	v_add_f32_e32 v35, v35, v48
	v_lshlrev_b32_e32 v48, 16, v88
	v_and_b32_e32 v49, 0xffff0000, v90
	v_add_f32_e32 v47, v47, v48
	v_and_b32_e32 v48, 0xffff0000, v88
	v_add_f32_e32 v57, v34, v49
	v_min_u32_e32 v34, 15, v117
	v_add_f32_e32 v36, v36, v48
	v_lshlrev_b32_e32 v48, 16, v89
	v_add_u32_e32 v34, 1, v34
	v_add_f32_e32 v38, v38, v48
	v_and_b32_e32 v48, 0xffff0000, v89
	v_and_b32_e32 v51, 0xffff0000, v91
	v_cvt_f32_ubyte0_e32 v34, v34
	v_add_f32_e32 v37, v37, v48
	v_lshlrev_b32_e32 v48, 16, v90
	v_add_f32_e32 v58, v35, v51
	v_div_scale_f32 v35, s[4:5], v34, v34, 1.0
	v_add_u32_e32 v2, 4, v98
; __device__ __forceinline__ unsigned pk2(float lo, float hi) { return pg8::cvt_pk_bf16(lo, hi); }
; template <int W>
; __device__ __forceinline__ void pool_run(const bf16_t* __restrict__ Pp, bf16_t* __restrict__ Dp, int r0, int tt0, int c8) {
;     ...
;     for (int i = 0; i < 8; ++i) v[W - 1 + i] = *(const u32x4*)(Pp + (size_t)(r0 + i) * D + c8);
;     float s[8];
; #pragma unroll
;     for (int e = 0; e < 8; ++e) s[e] = 0.f;
; #pragma unroll
;     for (int k = 0; k < W - 1; ++k) { s[0] += bflo(v[k].x); s[1] += bfhi(v[k].x); s[2] += bflo(v[k].y); s[3] += bfhi(v[k].y); s[4] += bflo(v[k].z); s[5] += bfhi(v[k].z); s[6] += bflo(v[k].w); s[7] += bfhi(v[k].w); }
; #pragma unroll
;     for (int i = 0; i < 8; ++i) { const int tt = tt0 + i; const u32x4 x = v[W - 1 + i];
;         const float p[8] = {bflo(x.x), bfhi(x.x), bflo(x.y), bfhi(x.y), bflo(x.z), bfhi(x.z), bflo(x.w), bfhi(x.w)};
; #pragma unroll
;         for (int e = 0; e < 8; ++e) s[e] += p[e];
;         const int cnt = (tt + 1) < W ? (tt + 1) : W; const float inv = 1.0f / (float)cnt;
;         u32x4 o; o.x = pk2(s[0] * inv - p[0], s[1] * inv - p[1]); o.y = pk2(s[2] * inv - p[2], s[3] * inv - p[3]); o.z = pk2(s[4] * inv - p[4], s[5] * inv - p[5]); o.w = pk2(s[6] * inv - p[6], s[7] * inv - p[7]);
;         *(u32x4*)(Dp + (size_t)(r0 + i) * D + c8) = o;
;         const u32x4 y = v[i];
;         s[0] -= bflo(y.x); s[1] -= bfhi(y.x); s[2] -= bflo(y.y); s[3] -= bfhi(y.y); s[4] -= bflo(y.z); s[5] -= bfhi(y.z); s[6] -= bflo(y.w); s[7] -= bfhi(y.w); }
	v_add_f32_e32 v56, v39, v48
	v_rcp_f32_e32 v39, v35
	v_ashrrev_i32_e32 v3, 31, v2
	v_add_u32_e32 v4, 5, v98
	v_lshlrev_b64 v[106:107], 11, v[2:3]
	v_ashrrev_i32_e32 v5, 31, v4
	v_lshl_add_u64 v[2:3], v[94:95], 0, v[106:107]
	v_lshlrev_b64 v[104:105], 11, v[4:5]
	v_and_b32_e32 v53, 0xffff0000, v92
	v_lshl_add_u64 v[4:5], v[94:95], 0, v[104:105]
	global_load_dwordx4 v[26:29], v[2:3], off
	global_load_dwordx4 v[10:13], v[4:5], off
	v_add_f32_e32 v59, v36, v53
	v_fma_f32 v36, -v35, v39, 1.0
	v_and_b32_e32 v55, 0xffff0000, v93
	v_fmac_f32_e32 v39, v36, v39
	v_div_scale_f32 v36, vcc, 1.0, v34, 1.0
	v_lshlrev_b32_e32 v54, 16, v93
	v_add_f32_e32 v61, v37, v55
	v_mul_f32_e32 v37, v36, v39
	v_add_f32_e32 v60, v38, v54
	v_fma_f32 v38, -v35, v37, v36
	v_fmac_f32_e32 v37, v38, v39
	v_add_u32_e32 v2, 6, v98
	v_add_u32_e32 v4, 7, v98
	v_fma_f32 v35, -v35, v37, v36
	v_ashrrev_i32_e32 v3, 31, v2
	v_ashrrev_i32_e32 v5, 31, v4
	v_div_fmas_f32 v35, v35, v39, v37
	v_lshlrev_b64 v[102:103], 11, v[2:3]
	v_lshlrev_b64 v[100:101], 11, v[4:5]
	v_lshlrev_b32_e32 v50, 16, v91
	v_div_fixup_f32 v37, v35, v34, 1.0
	v_lshl_add_u64 v[2:3], v[94:95], 0, v[102:103]
	v_lshl_add_u64 v[4:5], v[94:95], 0, v[100:101]
	v_lshlrev_b32_e32 v52, 16, v92
	v_add_f32_e32 v46, v46, v50
	v_fma_f32 v34, v37, v56, -v48
	v_fma_f32 v35, v37, v57, -v49
	global_load_dwordx4 v[6:9], v[2:3], off
	s_nop 0
	global_load_dwordx4 v[2:5], v[4:5], off
	v_add_f32_e32 v47, v47, v52
	v_cvt_pk_bf16_f32 v34, v34, v35
	v_fma_f32 v35, v37, v46, -v50
	v_fma_f32 v36, v37, v58, -v51
	v_cvt_pk_bf16_f32 v35, v35, v36
	v_fma_f32 v36, v37, v47, -v52
	v_fma_f32 v38, v37, v59, -v53
	v_cvt_pk_bf16_f32 v36, v36, v38
	v_fma_f32 v38, v37, v60, -v54
	v_fma_f32 v37, v37, v61, -v55
	v_cvt_pk_bf16_f32 v37, v38, v37
	v_lshl_add_u64 v[38:39], v[96:97], 0, v[114:115]
	global_store_dwordx4 v[38:39], v[34:37], off
	v_lshlrev_b32_e32 v48, 16, v78
	v_and_b32_e32 v49, 0xffff0000, v78
	v_sub_f32_e32 v34, v56, v99
	v_add_f32_e32 v56, v34, v48
	v_min_u32_e32 v34, 14, v117
	v_add_u32_e32 v34, 2, v34
	v_sub_f32_e32 v35, v57, v119
	v_cvt_f32_ubyte0_e32 v34, v34
	v_sub_f32_e32 v36, v46, v120
	v_lshlrev_b32_e32 v50, 16, v79
	v_add_f32_e32 v57, v35, v49
	v_div_scale_f32 v35, s[4:5], v34, v34, 1.0
	v_sub_f32_e32 v37, v58, v122
	v_add_f32_e32 v58, v36, v50
	v_rcp_f32_e32 v36, v35
	v_and_b32_e32 v51, 0xffff0000, v79
	v_sub_f32_e32 v39, v59, v125
	v_add_f32_e32 v59, v37, v51
	v_fma_f32 v37, -v35, v36, 1.0
	v_sub_f32_e32 v38, v47, v123
	v_lshlrev_b32_e32 v52, 16, v80
	v_fmac_f32_e32 v36, v37, v36
	v_div_scale_f32 v37, vcc, 1.0, v34, 1.0
	v_sub_f32_e32 v46, v60, v126
	v_and_b32_e32 v53, 0xffff0000, v80
	v_add_f32_e32 v60, v38, v52
	v_mul_f32_e32 v38, v37, v36
	v_sub_f32_e32 v47, v61, v128
	v_add_f32_e32 v61, v39, v53
	v_fma_f32 v39, -v35, v38, v37
	v_fmac_f32_e32 v38, v39, v36
	v_fma_f32 v35, -v35, v38, v37
	v_div_fmas_f32 v35, v35, v36, v38
	v_div_fixup_f32 v37, v35, v34, 1.0
	v_fma_f32 v34, v37, v56, -v48
	v_fma_f32 v35, v37, v57, -v49
	v_lshlrev_b32_e32 v54, 16, v81
	v_and_b32_e32 v55, 0xffff0000, v81
	v_cvt_pk_bf16_f32 v34, v34, v35
	v_fma_f32 v35, v37, v58, -v50
	v_fma_f32 v36, v37, v59, -v51
	v_add_f32_e32 v46, v46, v54
	v_add_f32_e32 v47, v47, v55
	v_cvt_pk_bf16_f32 v35, v35, v36
	v_fma_f32 v36, v37, v60, -v52
	v_fma_f32 v38, v37, v61, -v53
	v_cvt_pk_bf16_f32 v36, v36, v38
	v_fma_f32 v38, v37, v46, -v54
	v_fma_f32 v37, v37, v47, -v55
	v_cvt_pk_bf16_f32 v37, v38, v37
	v_lshl_add_u64 v[38:39], v[96:97], 0, v[112:113]
	global_store_dwordx4 v[38:39], v[34:37], off
	s_waitcnt vmcnt(0) lgkmcnt(0)
	v_lshlrev_b32_e32 v48, 16, v62
	v_and_b32_e32 v49, 0xffff0000, v62
	v_sub_f32_e32 v34, v56, v129
	v_add_f32_e32 v56, v34, v48
	v_min_u32_e32 v34, 13, v117
	v_add_u32_e32 v34, 3, v34
	v_sub_f32_e32 v35, v57, v130
	v_cvt_f32_ubyte0_e32 v34, v34
	v_sub_f32_e32 v36, v58, v131
	v_lshlrev_b32_e32 v50, 16, v63
	v_add_f32_e32 v57, v35, v49
	v_div_scale_f32 v35, s[4:5], v34, v34, 1.0
	v_add_f32_e32 v58, v36, v50
	v_rcp_f32_e32 v36, v35
	v_sub_f32_e32 v37, v59, v121
	v_and_b32_e32 v51, 0xffff0000, v63
	v_add_f32_e32 v59, v37, v51
	v_fma_f32 v37, -v35, v36, 1.0
	v_sub_f32_e32 v38, v60, v132
	v_lshlrev_b32_e32 v52, 16, v64
	v_fmac_f32_e32 v36, v37, v36
	v_div_scale_f32 v37, vcc, 1.0, v34, 1.0
	v_sub_f32_e32 v39, v61, v124
	v_and_b32_e32 v53, 0xffff0000, v64
	v_add_f32_e32 v60, v38, v52
	v_mul_f32_e32 v38, v37, v36
	v_add_f32_e32 v61, v39, v53
	v_fma_f32 v39, -v35, v38, v37
	v_fmac_f32_e32 v38, v39, v36
	v_fma_f32 v35, -v35, v38, v37
	v_div_fmas_f32 v35, v35, v36, v38
	v_div_fixup_f32 v37, v35, v34, 1.0
	v_fma_f32 v34, v37, v56, -v48
	v_fma_f32 v35, v37, v57, -v49
	v_sub_f32_e32 v46, v46, v133
	v_sub_f32_e32 v47, v47, v127
	v_lshlrev_b32_e32 v54, 16, v65
	v_and_b32_e32 v55, 0xffff0000, v65
	v_cvt_pk_bf16_f32 v34, v34, v35
	v_fma_f32 v35, v37, v58, -v50
	v_fma_f32 v36, v37, v59, -v51
	v_add_f32_e32 v46, v46, v54
	v_add_f32_e32 v47, v47, v55
	v_cvt_pk_bf16_f32 v35, v35, v36
	v_fma_f32 v36, v37, v60, -v52
	v_fma_f32 v38, v37, v61, -v53
	v_cvt_pk_bf16_f32 v36, v36, v38
	v_fma_f32 v38, v37, v46, -v54
	v_fma_f32 v37, v37, v47, -v55
	v_cvt_pk_bf16_f32 v37, v38, v37
	v_lshl_add_u64 v[38:39], v[96:97], 0, v[110:111]
	global_store_dwordx4 v[38:39], v[34:37], off
	v_lshlrev_b32_e32 v48, 16, v42
	v_and_b32_e32 v42, 0xffff0000, v42
	v_sub_f32_e32 v34, v56, v134
	v_add_f32_e32 v52, v34, v48
	v_min_u32_e32 v34, 12, v117
	v_add_u32_e32 v34, 4, v34
	v_sub_f32_e32 v35, v57, v118
	v_cvt_f32_ubyte0_e32 v34, v34
	v_sub_f32_e32 v36, v58, v135
	v_lshlrev_b32_e32 v49, 16, v43
	v_add_f32_e32 v53, v35, v42
	v_div_scale_f32 v35, s[4:5], v34, v34, 1.0
	v_add_f32_e32 v54, v36, v49
; __device__ __forceinline__ unsigned pk2(float lo, float hi) { return pg8::cvt_pk_bf16(lo, hi); }
; template <int W>
; __device__ __forceinline__ void pool_run(const bf16_t* __restrict__ Pp, bf16_t* __restrict__ Dp, int r0, int tt0, int c8) {
;     ...
;     for (int i = 0; i < 8; ++i) { const int tt = tt0 + i; const u32x4 x = v[W - 1 + i];
;         const float p[8] = {bflo(x.x), bfhi(x.x), bflo(x.y), bfhi(x.y), bflo(x.z), bfhi(x.z), bflo(x.w), bfhi(x.w)};
; #pragma unroll
;         for (int e = 0; e < 8; ++e) s[e] += p[e];
;         const int cnt = (tt + 1) < W ? (tt + 1) : W; const float inv = 1.0f / (float)cnt;
;         u32x4 o; o.x = pk2(s[0] * inv - p[0], s[1] * inv - p[1]); o.y = pk2(s[2] * inv - p[2], s[3] * inv - p[3]); o.z = pk2(s[4] * inv - p[4], s[5] * inv - p[5]); o.w = pk2(s[6] * inv - p[6], s[7] * inv - p[7]);
;         *(u32x4*)(Dp + (size_t)(r0 + i) * D + c8) = o;
;         const u32x4 y = v[i];
;         s[0] -= bflo(y.x); s[1] -= bfhi(y.x); s[2] -= bflo(y.y); s[3] -= bfhi(y.y); s[4] -= bflo(y.z); s[5] -= bfhi(y.z); s[6] -= bflo(y.w); s[7] -= bfhi(y.w); }
	v_rcp_f32_e32 v36, v35
	v_sub_f32_e32 v37, v59, v136
	v_and_b32_e32 v43, 0xffff0000, v43
	v_add_f32_e32 v55, v37, v43
	v_fma_f32 v37, -v35, v36, 1.0
	v_sub_f32_e32 v38, v60, v137
	v_lshlrev_b32_e32 v50, 16, v44
	v_fmac_f32_e32 v36, v37, v36
	v_div_scale_f32 v37, vcc, 1.0, v34, 1.0
	v_sub_f32_e32 v39, v61, v138
	v_and_b32_e32 v44, 0xffff0000, v44
	v_add_f32_e32 v56, v38, v50
	v_mul_f32_e32 v38, v37, v36
	v_add_f32_e32 v57, v39, v44
	v_fma_f32 v39, -v35, v38, v37
	v_fmac_f32_e32 v38, v39, v36
	v_fma_f32 v35, -v35, v38, v37
	v_div_fmas_f32 v35, v35, v36, v38
	v_div_fixup_f32 v37, v35, v34, 1.0
	v_fma_f32 v34, v37, v52, -v48
	v_fma_f32 v35, v37, v53, -v42
	v_sub_f32_e32 v46, v46, v139
	v_sub_f32_e32 v47, v47, v140
	v_lshlrev_b32_e32 v51, 16, v45
	v_and_b32_e32 v45, 0xffff0000, v45
	v_cvt_pk_bf16_f32 v34, v34, v35
	v_fma_f32 v35, v37, v54, -v49
	v_fma_f32 v36, v37, v55, -v43
	v_add_f32_e32 v46, v46, v51
	v_add_f32_e32 v47, v47, v45
	v_cvt_pk_bf16_f32 v35, v35, v36
	v_fma_f32 v36, v37, v56, -v50
	v_fma_f32 v38, v37, v57, -v44
	v_cvt_pk_bf16_f32 v36, v36, v38
	v_fma_f32 v38, v37, v46, -v51
	v_fma_f32 v37, v37, v47, -v45
	v_cvt_pk_bf16_f32 v37, v38, v37
	v_lshl_add_u64 v[38:39], v[96:97], 0, v[108:109]
	global_store_dwordx4 v[38:39], v[34:37], off
	v_lshlrev_b32_e32 v44, 16, v26
	v_and_b32_e32 v26, 0xffff0000, v26
	v_sub_f32_e32 v34, v52, v141
	v_add_f32_e32 v48, v34, v44
	v_min_u32_e32 v34, 11, v117
	v_add_u32_e32 v34, 5, v34
	v_sub_f32_e32 v35, v53, v142
	v_cvt_f32_ubyte0_e32 v34, v34
	v_add_f32_e32 v49, v35, v26
	v_div_scale_f32 v35, s[4:5], v34, v34, 1.0
	v_rcp_f32_e32 v50, v35
	v_sub_f32_e32 v36, v54, v143
	v_sub_f32_e32 v37, v55, v144
	v_lshlrev_b32_e32 v45, 16, v27
	v_fma_f32 v51, -v35, v50, 1.0
	v_fmac_f32_e32 v50, v51, v50
	v_div_scale_f32 v51, vcc, 1.0, v34, 1.0
	v_mul_f32_e32 v52, v51, v50
	v_fma_f32 v53, -v35, v52, v51
	v_fmac_f32_e32 v52, v53, v50
	v_fma_f32 v35, -v35, v52, v51
	v_div_fmas_f32 v35, v35, v50, v52
	v_and_b32_e32 v27, 0xffff0000, v27
	v_div_fixup_f32 v34, v35, v34, 1.0
	v_sub_f32_e32 v38, v56, v145
	v_sub_f32_e32 v39, v57, v146
	v_sub_f32_e32 v42, v46, v147
	v_lshlrev_b32_e32 v46, 16, v28
	v_and_b32_e32 v28, 0xffff0000, v28
	v_add_f32_e32 v36, v36, v45
	v_add_f32_e32 v37, v37, v27
	v_fma_f32 v35, v34, v48, -v44
	v_fma_f32 v26, v34, v49, -v26
	v_sub_f32_e32 v43, v47, v148
	v_lshlrev_b32_e32 v47, 16, v29
	v_and_b32_e32 v29, 0xffff0000, v29
	v_add_f32_e32 v38, v38, v46
	v_add_f32_e32 v39, v39, v28
	v_cvt_pk_bf16_f32 v26, v35, v26
	v_fma_f32 v35, v34, v36, -v45
	v_fma_f32 v27, v34, v37, -v27
	v_add_f32_e32 v42, v42, v47
	v_add_f32_e32 v43, v43, v29
	v_cvt_pk_bf16_f32 v27, v35, v27
	v_fma_f32 v35, v34, v38, -v46
	v_fma_f32 v28, v34, v39, -v28
	v_cvt_pk_bf16_f32 v28, v35, v28
	v_fma_f32 v35, v34, v42, -v47
	v_fma_f32 v29, v34, v43, -v29
	v_cvt_pk_bf16_f32 v29, v35, v29
	v_lshl_add_u64 v[34:35], v[96:97], 0, v[106:107]
	global_store_dwordx4 v[34:35], v[26:29], off
	v_sub_f32_e32 v34, v38, v153
	v_lshlrev_b32_e32 v38, 16, v10
	v_sub_f32_e32 v26, v48, v149
	v_sub_f32_e32 v28, v36, v151
	v_sub_f32_e32 v36, v42, v154
	v_add_f32_e32 v42, v26, v38
	v_min_u32_e32 v26, 10, v117
	v_add_u32_e32 v26, 6, v26
	v_sub_f32_e32 v27, v49, v150
	v_and_b32_e32 v10, 0xffff0000, v10
	v_cvt_f32_ubyte0_e32 v26, v26
	v_sub_f32_e32 v29, v37, v152
	v_sub_f32_e32 v37, v43, v41
	v_add_f32_e32 v43, v27, v10
	v_div_scale_f32 v27, s[4:5], v26, v26, 1.0
	v_rcp_f32_e32 v44, v27
	v_sub_f32_e32 v35, v39, v40
	v_lshlrev_b32_e32 v39, 16, v11
	v_and_b32_e32 v11, 0xffff0000, v11
	v_fma_f32 v45, -v27, v44, 1.0
	v_fmac_f32_e32 v44, v45, v44
	v_div_scale_f32 v45, vcc, 1.0, v26, 1.0
	v_mul_f32_e32 v46, v45, v44
	v_fma_f32 v47, -v27, v46, v45
	v_fmac_f32_e32 v46, v47, v44
	v_fma_f32 v27, -v27, v46, v45
	v_div_fmas_f32 v27, v27, v44, v46
	v_div_fixup_f32 v26, v27, v26, 1.0
	v_lshlrev_b32_e32 v40, 16, v12
	v_and_b32_e32 v12, 0xffff0000, v12
	v_add_f32_e32 v28, v28, v39
	v_add_f32_e32 v29, v29, v11
	v_fma_f32 v27, v26, v42, -v38
	v_fma_f32 v10, v26, v43, -v10
	v_lshlrev_b32_e32 v41, 16, v13
	v_and_b32_e32 v13, 0xffff0000, v13
	v_add_f32_e32 v34, v34, v40
	v_add_f32_e32 v35, v35, v12
	v_cvt_pk_bf16_f32 v10, v27, v10
	v_fma_f32 v27, v26, v28, -v39
	v_fma_f32 v11, v26, v29, -v11
	v_add_f32_e32 v36, v36, v41
	v_add_f32_e32 v37, v37, v13
	v_cvt_pk_bf16_f32 v11, v27, v11
	v_fma_f32 v27, v26, v34, -v40
	v_fma_f32 v12, v26, v35, -v12
	v_cvt_pk_bf16_f32 v12, v27, v12
	v_fma_f32 v27, v26, v36, -v41
	v_fma_f32 v13, v26, v37, -v13
	v_cvt_pk_bf16_f32 v13, v27, v13
	v_lshl_add_u64 v[26:27], v[96:97], 0, v[104:105]
	global_store_dwordx4 v[26:27], v[10:13], off
	v_lshlrev_b32_e32 v26, 16, v6
	v_and_b32_e32 v6, 0xffff0000, v6
	v_sub_f32_e32 v10, v42, v22
	v_sub_f32_e32 v22, v34, v30
	v_add_f32_e32 v30, v10, v26
	v_min_u32_e32 v10, 9, v117
	v_add_u32_e32 v10, 7, v10
	v_sub_f32_e32 v11, v43, v23
	v_cvt_f32_ubyte0_e32 v10, v10
	v_sub_f32_e32 v23, v35, v31
	v_add_f32_e32 v31, v11, v6
	v_div_scale_f32 v11, s[4:5], v10, v10, 1.0
	v_sub_f32_e32 v12, v28, v24
	v_sub_f32_e32 v24, v36, v32
	v_rcp_f32_e32 v32, v11
	v_sub_f32_e32 v13, v29, v25
	v_sub_f32_e32 v25, v37, v33
	v_lshlrev_b32_e32 v27, 16, v7
	v_fma_f32 v33, -v11, v32, 1.0
	v_fmac_f32_e32 v32, v33, v32
	v_div_scale_f32 v33, vcc, 1.0, v10, 1.0
	v_mul_f32_e32 v34, v33, v32
	v_fma_f32 v35, -v11, v34, v33
	v_fmac_f32_e32 v34, v35, v32
	v_fma_f32 v11, -v11, v34, v33
	v_div_fmas_f32 v11, v11, v32, v34
	v_and_b32_e32 v7, 0xffff0000, v7
	v_div_fixup_f32 v10, v11, v10, 1.0
	v_lshlrev_b32_e32 v28, 16, v8
	v_and_b32_e32 v8, 0xffff0000, v8
	v_add_f32_e32 v12, v12, v27
	v_add_f32_e32 v13, v13, v7
	v_fma_f32 v11, v10, v30, -v26
	v_fma_f32 v6, v10, v31, -v6
; __device__ __forceinline__ unsigned pk2(float lo, float hi) { return pg8::cvt_pk_bf16(lo, hi); }
; template <int W>
; __device__ __forceinline__ void pool_run(const bf16_t* __restrict__ Pp, bf16_t* __restrict__ Dp, int r0, int tt0, int c8) {
;     u32x4 v[W - 1 + 8];
; #pragma unroll
;     for (int k = 0; k < W - 1; ++k) v[k] = (tt0 - (W - 1) + k >= 0) ? *(const u32x4*)(Pp + (size_t)(r0 - (W - 1) + k) * D + c8) : (u32x4){0u, 0u, 0u, 0u};
; #pragma unroll
;     for (int i = 0; i < 8; ++i) v[W - 1 + i] = *(const u32x4*)(Pp + (size_t)(r0 + i) * D + c8);
;     float s[8];
; #pragma unroll
;     for (int e = 0; e < 8; ++e) s[e] = 0.f;
; #pragma unroll
;     for (int k = 0; k < W - 1; ++k) { s[0] += bflo(v[k].x); s[1] += bfhi(v[k].x); s[2] += bflo(v[k].y); s[3] += bfhi(v[k].y); s[4] += bflo(v[k].z); s[5] += bfhi(v[k].z); s[6] += bflo(v[k].w); s[7] += bfhi(v[k].w); }
; #pragma unroll
;     for (int i = 0; i < 8; ++i) { const int tt = tt0 + i; const u32x4 x = v[W - 1 + i];
;         const float p[8] = {bflo(x.x), bfhi(x.x), bflo(x.y), bfhi(x.y), bflo(x.z), bfhi(x.z), bflo(x.w), bfhi(x.w)};
; #pragma unroll
;         for (int e = 0; e < 8; ++e) s[e] += p[e];
;         const int cnt = (tt + 1) < W ? (tt + 1) : W; const float inv = 1.0f / (float)cnt;
;         u32x4 o; o.x = pk2(s[0] * inv - p[0], s[1] * inv - p[1]); o.y = pk2(s[2] * inv - p[2], s[3] * inv - p[3]); o.z = pk2(s[4] * inv - p[4], s[5] * inv - p[5]); o.w = pk2(s[6] * inv - p[6], s[7] * inv - p[7]);
;         *(u32x4*)(Dp + (size_t)(r0 + i) * D + c8) = o;
;         const u32x4 y = v[i];
;         s[0] -= bflo(y.x); s[1] -= bfhi(y.x); s[2] -= bflo(y.y); s[3] -= bfhi(y.y); s[4] -= bflo(y.z); s[5] -= bfhi(y.z); s[6] -= bflo(y.w); s[7] -= bfhi(y.w); }
; }
	v_lshlrev_b32_e32 v29, 16, v9
	v_and_b32_e32 v9, 0xffff0000, v9
	v_add_f32_e32 v22, v22, v28
	v_add_f32_e32 v23, v23, v8
	v_cvt_pk_bf16_f32 v6, v11, v6
	v_fma_f32 v11, v10, v12, -v27
	v_fma_f32 v7, v10, v13, -v7
	v_add_f32_e32 v24, v24, v29
	v_add_f32_e32 v25, v25, v9
	v_cvt_pk_bf16_f32 v7, v11, v7
	v_fma_f32 v11, v10, v22, -v28
	v_fma_f32 v8, v10, v23, -v8
	v_cvt_pk_bf16_f32 v8, v11, v8
	v_fma_f32 v11, v10, v24, -v29
	v_fma_f32 v9, v10, v25, -v9
	v_cvt_pk_bf16_f32 v9, v11, v9
	v_lshl_add_u64 v[10:11], v[96:97], 0, v[102:103]
	global_store_dwordx4 v[10:11], v[6:9], off
	v_sub_f32_e32 v10, v22, v18
	v_min_u32_e32 v18, 8, v117
	v_add_u32_e32 v18, 8, v18
	v_cvt_f32_ubyte0_e32 v18, v18
	v_sub_f32_e32 v11, v23, v19
	v_div_scale_f32 v19, s[4:5], v18, v18, 1.0
	v_sub_f32_e32 v8, v12, v16
	v_sub_f32_e32 v12, v24, v20
	v_rcp_f32_e32 v20, v19
	v_sub_f32_e32 v9, v13, v17
	v_sub_f32_e32 v13, v25, v21
	v_sub_f32_e32 v6, v30, v14
	v_fma_f32 v21, -v19, v20, 1.0
	v_fmac_f32_e32 v20, v21, v20
	v_div_scale_f32 v21, vcc, 1.0, v18, 1.0
	v_mul_f32_e32 v22, v21, v20
	v_fma_f32 v23, -v19, v22, v21
	v_fmac_f32_e32 v22, v23, v20
	v_fma_f32 v19, -v19, v22, v21
	v_sub_f32_e32 v7, v31, v15
	v_lshlrev_b32_e32 v14, 16, v2
	v_and_b32_e32 v2, 0xffff0000, v2
	v_div_fmas_f32 v19, v19, v20, v22
	v_lshlrev_b32_e32 v15, 16, v3
	v_and_b32_e32 v3, 0xffff0000, v3
	v_add_f32_e32 v6, v6, v14
	v_add_f32_e32 v7, v7, v2
	v_div_fixup_f32 v18, v19, v18, 1.0
	v_lshlrev_b32_e32 v16, 16, v4
	v_and_b32_e32 v4, 0xffff0000, v4
	v_lshlrev_b32_e32 v17, 16, v5
	v_and_b32_e32 v5, 0xffff0000, v5
	v_add_f32_e32 v8, v8, v15
	v_add_f32_e32 v9, v9, v3
	v_fma_f32 v6, v18, v6, -v14
	v_fma_f32 v2, v18, v7, -v2
	v_add_f32_e32 v10, v10, v16
	v_add_f32_e32 v11, v11, v4
	v_add_f32_e32 v13, v13, v5
	v_cvt_pk_bf16_f32 v2, v6, v2
	v_fma_f32 v6, v18, v8, -v15
	v_fma_f32 v3, v18, v9, -v3
	v_add_f32_e32 v12, v12, v17
	v_cvt_pk_bf16_f32 v3, v6, v3
	v_fma_f32 v6, v18, v10, -v16
	v_fma_f32 v4, v18, v11, -v4
	v_fma_f32 v5, v18, v13, -v5
	s_mov_b64 s[4:5], 0
	v_cvt_pk_bf16_f32 v4, v6, v4
	v_fma_f32 v6, v18, v12, -v17
	v_cvt_pk_bf16_f32 v5, v6, v5
.LBB0_765:
	s_and_b64 vcc, exec, s[4:5]
	s_cbranch_vccz .LBB0_781
	v_mov_b32_e32 v22, 0
	v_cmp_ne_u32_e32 vcc, 0, v117
	v_mov_b32_e32 v26, 0
	v_mov_b32_e32 v27, 0
	v_mov_b32_e32 v28, 0
	v_mov_b32_e32 v29, 0
	s_and_saveexec_b64 s[4:5], vcc
	s_cbranch_execz .LBB0_768
	v_add_u32_e32 v2, -7, v98
	v_ashrrev_i32_e32 v3, 31, v2
	v_lshlrev_b64 v[2:3], 11, v[2:3]
	v_lshl_add_u64 v[2:3], v[94:95], 0, v[2:3]
	global_load_dwordx4 v[26:29], v[2:3], off
.LBB0_768:
	s_or_b64 exec, exec, s[4:5]
	v_mov_b32_e32 v23, 0
	v_mov_b32_e32 v24, 0
	v_mov_b32_e32 v25, 0
	s_and_saveexec_b64 s[4:5], vcc
	s_cbranch_execz .LBB0_770
	v_add_u32_e32 v2, -6, v98
	v_ashrrev_i32_e32 v3, 31, v2
	v_lshlrev_b64 v[2:3], 11, v[2:3]
	v_lshl_add_u64 v[2:3], v[94:95], 0, v[2:3]
	global_load_dwordx4 v[22:25], v[2:3], off
.LBB0_770:
	s_or_b64 exec, exec, s[4:5]
	v_mov_b32_e32 v30, 0
	v_mov_b32_e32 v38, 0
	v_mov_b32_e32 v39, 0
	v_mov_b32_e32 v40, 0
	v_mov_b32_e32 v41, 0
	s_and_saveexec_b64 s[4:5], vcc
	s_cbranch_execz .LBB0_772
	v_add_u32_e32 v2, -5, v98
	v_ashrrev_i32_e32 v3, 31, v2
	v_lshlrev_b64 v[2:3], 11, v[2:3]
	v_lshl_add_u64 v[2:3], v[94:95], 0, v[2:3]
	global_load_dwordx4 v[38:41], v[2:3], off
.LBB0_772:
	s_or_b64 exec, exec, s[4:5]
	v_mov_b32_e32 v31, 0
	v_mov_b32_e32 v32, 0
	v_mov_b32_e32 v33, 0
	s_and_saveexec_b64 s[4:5], vcc
	s_cbranch_execz .LBB0_774
	v_add_u32_e32 v2, -4, v98
	v_ashrrev_i32_e32 v3, 31, v2
	v_lshlrev_b64 v[2:3], 11, v[2:3]
	v_lshl_add_u64 v[2:3], v[94:95], 0, v[2:3]
	global_load_dwordx4 v[30:33], v[2:3], off
.LBB0_774:
	s_or_b64 exec, exec, s[4:5]
	v_mov_b32_e32 v42, 0
	v_mov_b32_e32 v46, 0
	v_mov_b32_e32 v47, 0
	v_mov_b32_e32 v48, 0
	v_mov_b32_e32 v49, 0
	s_and_saveexec_b64 s[4:5], vcc
	s_cbranch_execz .LBB0_776
	v_add_u32_e32 v2, -3, v98
	v_ashrrev_i32_e32 v3, 31, v2
	v_lshlrev_b64 v[2:3], 11, v[2:3]
	v_lshl_add_u64 v[2:3], v[94:95], 0, v[2:3]
	global_load_dwordx4 v[46:49], v[2:3], off
.LBB0_776:
	s_or_b64 exec, exec, s[4:5]
	v_mov_b32_e32 v43, 0
	v_mov_b32_e32 v44, 0
	v_mov_b32_e32 v45, 0
	s_and_saveexec_b64 s[4:5], vcc
	s_cbranch_execz .LBB0_778
	v_add_u32_e32 v2, -2, v98
	v_ashrrev_i32_e32 v3, 31, v2
	v_lshlrev_b64 v[2:3], 11, v[2:3]
	v_lshl_add_u64 v[2:3], v[94:95], 0, v[2:3]
	global_load_dwordx4 v[42:45], v[2:3], off
.LBB0_778:
	s_or_b64 exec, exec, s[4:5]
	v_mov_b32_e32 v50, 0
	v_mov_b32_e32 v66, 0x40e00000
	v_mov_b32_e32 v51, 0
	v_mov_b32_e32 v52, 0
	v_mov_b32_e32 v53, 0
	s_and_saveexec_b64 s[4:5], vcc
	s_cbranch_execz .LBB0_780
	v_add_u32_e32 v2, -1, v98
	v_ashrrev_i32_e32 v3, 31, v2
	v_lshlrev_b64 v[2:3], 11, v[2:3]
	v_lshl_add_u64 v[2:3], v[94:95], 0, v[2:3]
	global_load_dwordx4 v[50:53], v[2:3], off
	v_mov_b32_e32 v66, 0x41000000
; template <int W>
; __device__ __forceinline__ void pool_run(const bf16_t* __restrict__ Pp, bf16_t* __restrict__ Dp, int r0, int tt0, int c8) {
;     ...
;     for (int k = 0; k < W - 1; ++k) v[k] = (tt0 - (W - 1) + k >= 0) ? *(const u32x4*)(Pp + (size_t)(r0 - (W - 1) + k) * D + c8) : (u32x4){0u, 0u, 0u, 0u};
; #pragma unroll
;     for (int i = 0; i < 8; ++i) v[W - 1 + i] = *(const u32x4*)(Pp + (size_t)(r0 + i) * D + c8);
;     float s[8];
; #pragma unroll
;     for (int e = 0; e < 8; ++e) s[e] = 0.f;
; #pragma unroll
;     for (int k = 0; k < W - 1; ++k) { s[0] += bflo(v[k].x); s[1] += bfhi(v[k].x); s[2] += bflo(v[k].y); s[3] += bfhi(v[k].y); s[4] += bflo(v[k].z); s[5] += bfhi(v[k].z); s[6] += bflo(v[k].w); s[7] += bfhi(v[k].w); }
; #pragma unroll
;     for (int i = 0; i < 8; ++i) { const int tt = tt0 + i; const u32x4 x = v[W - 1 + i];
;         const float p[8] = {bflo(x.x), bfhi(x.x), bflo(x.y), bfhi(x.y), bflo(x.z), bfhi(x.z), bflo(x.w), bfhi(x.w)};
; #pragma unroll
;         for (int e = 0; e < 8; ++e) s[e] += p[e];
.LBB0_780:
	s_or_b64 exec, exec, s[4:5]
	v_ashrrev_i32_e32 v99, 31, v98
	v_add_u32_e32 v4, 1, v98
	v_lshlrev_b64 v[76:77], 11, v[98:99]
	v_ashrrev_i32_e32 v5, 31, v4
	v_lshl_add_u64 v[2:3], v[94:95], 0, v[76:77]
	v_lshlrev_b64 v[64:65], 11, v[4:5]
	v_lshl_add_u64 v[4:5], v[94:95], 0, v[64:65]
	global_load_dwordx4 v[68:71], v[2:3], off
	global_load_dwordx4 v[72:75], v[4:5], off
	v_add_u32_e32 v2, 2, v98
	v_ashrrev_i32_e32 v3, 31, v2
	v_add_u32_e32 v4, 3, v98
	v_lshlrev_b64 v[62:63], 11, v[2:3]
	v_ashrrev_i32_e32 v5, 31, v4
	v_lshl_add_u64 v[2:3], v[94:95], 0, v[62:63]
	v_lshlrev_b64 v[60:61], 11, v[4:5]
	v_lshl_add_u64 v[4:5], v[94:95], 0, v[60:61]
	global_load_dwordx4 v[34:37], v[2:3], off
	global_load_dwordx4 v[18:21], v[4:5], off
	s_waitcnt vmcnt(0) lgkmcnt(0)
	v_and_b32_e32 v79, 0xffff0000, v26
	v_lshlrev_b32_e32 v80, 16, v27
	v_lshlrev_b32_e32 v67, 16, v26
	v_add_f32_e32 v26, 0, v79
	v_add_f32_e32 v81, 0, v80
	v_and_b32_e32 v82, 0xffff0000, v27
	v_lshlrev_b32_e32 v83, 16, v28
	v_and_b32_e32 v90, 0xffff0000, v22
	v_lshlrev_b32_e32 v91, 16, v23
	v_add_f32_e32 v27, 0, v82
	v_add_f32_e32 v84, 0, v83
	v_and_b32_e32 v28, 0xffff0000, v28
	v_lshlrev_b32_e32 v86, 16, v29
	v_and_b32_e32 v29, 0xffff0000, v29
	v_lshlrev_b32_e32 v89, 16, v22
	v_add_f32_e32 v22, v26, v90
	v_add_f32_e32 v26, v81, v91
	v_and_b32_e32 v81, 0xffff0000, v23
	v_lshlrev_b32_e32 v92, 16, v24
	v_add_f32_e32 v85, 0, v28
	v_add_f32_e32 v88, 0, v29
	v_add_f32_e32 v23, v27, v81
	v_add_f32_e32 v27, v84, v92
	v_and_b32_e32 v84, 0xffff0000, v24
	v_and_b32_e32 v93, 0xffff0000, v25
	v_add_f32_e32 v24, v85, v84
	v_lshlrev_b32_e32 v85, 16, v25
	v_add_f32_e32 v25, v88, v93
	v_lshlrev_b32_e32 v88, 16, v38
	v_and_b32_e32 v38, 0xffff0000, v38
	v_add_f32_e32 v22, v22, v38
	v_lshlrev_b32_e32 v104, 16, v30
	v_and_b32_e32 v30, 0xffff0000, v30
	v_add_f32_e32 v22, v22, v30
	v_lshlrev_b32_e32 v108, 16, v46
	v_and_b32_e32 v46, 0xffff0000, v46
	v_lshlrev_b32_e32 v99, 16, v39
	v_and_b32_e32 v39, 0xffff0000, v39
	v_add_f32_e32 v22, v22, v46
	v_lshlrev_b32_e32 v112, 16, v42
	v_and_b32_e32 v42, 0xffff0000, v42
	v_add_f32_e32 v23, v23, v39
	v_lshlrev_b32_e32 v105, 16, v31
	v_and_b32_e32 v31, 0xffff0000, v31
	v_add_f32_e32 v22, v22, v42
	v_lshlrev_b32_e32 v118, 16, v50
	v_and_b32_e32 v50, 0xffff0000, v50
	v_add_f32_e32 v26, v26, v99
	v_add_f32_e32 v23, v23, v31
	v_lshlrev_b32_e32 v109, 16, v47
	v_and_b32_e32 v47, 0xffff0000, v47
	v_add_f32_e32 v22, v22, v50
	v_add_f32_e32 v26, v26, v105
	v_add_f32_e32 v23, v23, v47
	v_lshlrev_b32_e32 v113, 16, v43
	v_and_b32_e32 v43, 0xffff0000, v43
	v_add_f32_e32 v26, v26, v109
	v_add_f32_e32 v23, v23, v43
	v_lshlrev_b32_e32 v119, 16, v51
	v_and_b32_e32 v51, 0xffff0000, v51
	v_lshlrev_b32_e32 v102, 16, v40
	v_and_b32_e32 v40, 0xffff0000, v40
	v_add_f32_e32 v26, v26, v113
	v_add_f32_e32 v23, v23, v51
	v_add_f32_e32 v24, v24, v40
	v_lshlrev_b32_e32 v106, 16, v32
	v_and_b32_e32 v32, 0xffff0000, v32
	v_add_f32_e32 v26, v26, v119
	v_add_u32_e32 v2, 4, v98
	v_lshlrev_b32_e32 v122, 16, v68
	v_and_b32_e32 v68, 0xffff0000, v68
	v_add_f32_e32 v126, v22, v68
	v_min_u32_e32 v22, 7, v117
	v_add_u32_e32 v22, 1, v22
	v_lshlrev_b32_e32 v123, 16, v69
	v_and_b32_e32 v69, 0xffff0000, v69
	v_cvt_f32_ubyte0_e32 v22, v22
	v_add_f32_e32 v128, v23, v69
	v_div_scale_f32 v23, s[4:5], v22, v22, 1.0
	v_lshlrev_b32_e32 v103, 16, v41
	v_and_b32_e32 v41, 0xffff0000, v41
	v_add_f32_e32 v24, v24, v32
	v_lshlrev_b32_e32 v110, 16, v48
	v_and_b32_e32 v48, 0xffff0000, v48
	v_add_f32_e32 v127, v26, v123
	v_rcp_f32_e32 v26, v23
	v_ashrrev_i32_e32 v3, 31, v2
	v_add_u32_e32 v4, 5, v98
	v_add_f32_e32 v25, v25, v41
	v_lshlrev_b32_e32 v107, 16, v33
	v_and_b32_e32 v33, 0xffff0000, v33
	v_add_f32_e32 v24, v24, v48
	v_lshlrev_b32_e32 v114, 16, v44
	v_and_b32_e32 v44, 0xffff0000, v44
	v_lshlrev_b64 v[58:59], 11, v[2:3]
	v_ashrrev_i32_e32 v5, 31, v4
	v_add_f32_e32 v27, v27, v102
	v_add_f32_e32 v25, v25, v33
	v_lshlrev_b32_e32 v111, 16, v49
	v_and_b32_e32 v49, 0xffff0000, v49
	v_add_f32_e32 v24, v24, v44
	v_lshlrev_b32_e32 v120, 16, v52
	v_and_b32_e32 v52, 0xffff0000, v52
	v_lshl_add_u64 v[2:3], v[94:95], 0, v[58:59]
	v_lshlrev_b64 v[56:57], 11, v[4:5]
	v_add_f32_e32 v27, v27, v106
	v_add_f32_e32 v25, v25, v49
	v_lshlrev_b32_e32 v115, 16, v45
	v_and_b32_e32 v45, 0xffff0000, v45
	v_add_f32_e32 v24, v24, v52
	v_lshlrev_b32_e32 v124, 16, v70
	v_and_b32_e32 v70, 0xffff0000, v70
	v_lshl_add_u64 v[4:5], v[94:95], 0, v[56:57]
	global_load_dwordx4 v[14:17], v[2:3], off
	global_load_dwordx4 v[10:13], v[4:5], off
	v_add_f32_e32 v78, 0, v67
	v_add_f32_e32 v27, v27, v110
	v_add_f32_e32 v25, v25, v45
	v_lshlrev_b32_e32 v121, 16, v53
	v_and_b32_e32 v53, 0xffff0000, v53
	v_add_f32_e32 v130, v24, v70
	v_fma_f32 v24, -v23, v26, 1.0
	v_add_f32_e32 v78, v78, v89
	v_add_f32_e32 v27, v27, v114
	v_add_f32_e32 v25, v25, v53
	v_lshlrev_b32_e32 v125, 16, v71
	v_and_b32_e32 v71, 0xffff0000, v71
	v_fmac_f32_e32 v26, v24, v26
	v_div_scale_f32 v24, vcc, 1.0, v22, 1.0
	v_add_f32_e32 v78, v78, v88
	v_add_f32_e32 v27, v27, v120
	v_add_f32_e32 v131, v25, v71
	v_mul_f32_e32 v25, v24, v26
	v_add_f32_e32 v87, 0, v86
	v_add_f32_e32 v78, v78, v104
	v_add_f32_e32 v129, v27, v124
	v_fma_f32 v27, -v23, v25, v24
	v_add_f32_e32 v87, v87, v85
	v_add_f32_e32 v78, v78, v108
	v_fmac_f32_e32 v25, v27, v26
	v_add_u32_e32 v2, 6, v98
	v_add_u32_e32 v4, 7, v98
	v_add_f32_e32 v87, v87, v103
	v_add_f32_e32 v78, v78, v112
	v_fma_f32 v23, -v23, v25, v24
	v_ashrrev_i32_e32 v3, 31, v2
	v_ashrrev_i32_e32 v5, 31, v4
	v_add_f32_e32 v87, v87, v107
	v_add_f32_e32 v78, v78, v118
	v_div_fmas_f32 v23, v23, v26, v25
	v_lshlrev_b64 v[54:55], 11, v[2:3]
	v_lshlrev_b64 v[100:101], 11, v[4:5]
; __device__ __forceinline__ unsigned pk2(float lo, float hi) { return pg8::cvt_pk_bf16(lo, hi); }
; template <int W>
; __device__ __forceinline__ void pool_run(const bf16_t* __restrict__ Pp, bf16_t* __restrict__ Dp, int r0, int tt0, int c8) {
;     u32x4 v[W - 1 + 8];
; #pragma unroll
;     for (int k = 0; k < W - 1; ++k) v[k] = (tt0 - (W - 1) + k >= 0) ? *(const u32x4*)(Pp + (size_t)(r0 - (W - 1) + k) * D + c8) : (u32x4){0u, 0u, 0u, 0u};
; #pragma unroll
;     for (int i = 0; i < 8; ++i) v[W - 1 + i] = *(const u32x4*)(Pp + (size_t)(r0 + i) * D + c8);
;     float s[8];
; #pragma unroll
;     for (int e = 0; e < 8; ++e) s[e] = 0.f;
; #pragma unroll
;     for (int k = 0; k < W - 1; ++k) { s[0] += bflo(v[k].x); s[1] += bfhi(v[k].x); s[2] += bflo(v[k].y); s[3] += bfhi(v[k].y); s[4] += bflo(v[k].z); s[5] += bfhi(v[k].z); s[6] += bflo(v[k].w); s[7] += bfhi(v[k].w); }
; #pragma unroll
;     for (int i = 0; i < 8; ++i) { const int tt = tt0 + i; const u32x4 x = v[W - 1 + i];
;         const float p[8] = {bflo(x.x), bfhi(x.x), bflo(x.y), bfhi(x.y), bflo(x.z), bfhi(x.z), bflo(x.w), bfhi(x.w)};
; #pragma unroll
;         for (int e = 0; e < 8; ++e) s[e] += p[e];
;         const int cnt = (tt + 1) < W ? (tt + 1) : W; const float inv = 1.0f / (float)cnt;
;         u32x4 o; o.x = pk2(s[0] * inv - p[0], s[1] * inv - p[1]); o.y = pk2(s[2] * inv - p[2], s[3] * inv - p[3]); o.z = pk2(s[4] * inv - p[4], s[5] * inv - p[5]); o.w = pk2(s[6] * inv - p[6], s[7] * inv - p[7]);
;         *(u32x4*)(Dp + (size_t)(r0 + i) * D + c8) = o;
;         const u32x4 y = v[i];
;         s[0] -= bflo(y.x); s[1] -= bfhi(y.x); s[2] -= bflo(y.y); s[3] -= bfhi(y.y); s[4] -= bflo(y.z); s[5] -= bfhi(y.z); s[6] -= bflo(y.w); s[7] -= bfhi(y.w); }
; }
	v_add_f32_e32 v87, v87, v111
	v_add_f32_e32 v78, v78, v122
	v_div_fixup_f32 v25, v23, v22, 1.0
	v_lshl_add_u64 v[2:3], v[94:95], 0, v[54:55]
	v_lshl_add_u64 v[4:5], v[94:95], 0, v[100:101]
	v_add_f32_e32 v87, v87, v115
	v_fma_f32 v22, v25, v78, -v122
	v_fma_f32 v23, v25, v126, -v68
	global_load_dwordx4 v[6:9], v[2:3], off
	s_nop 0
	global_load_dwordx4 v[2:5], v[4:5], off
	v_add_f32_e32 v87, v87, v121
	v_cvt_pk_bf16_f32 v22, v22, v23
	v_fma_f32 v23, v25, v127, -v123
	v_fma_f32 v24, v25, v128, -v69
	v_add_f32_e32 v87, v87, v125
	v_cvt_pk_bf16_f32 v23, v23, v24
	v_fma_f32 v24, v25, v129, -v124
	v_fma_f32 v26, v25, v130, -v70
	v_cvt_pk_bf16_f32 v24, v24, v26
	v_fma_f32 v26, v25, v87, -v125
	v_fma_f32 v25, v25, v131, -v71
	v_cvt_pk_bf16_f32 v25, v26, v25
	v_lshl_add_u64 v[26:27], v[96:97], 0, v[76:77]
	global_store_dwordx4 v[26:27], v[22:25], off
	v_and_b32_e32 v68, 0xffff0000, v72
	v_lshlrev_b32_e32 v69, 16, v73
	v_sub_f32_e32 v22, v78, v67
	v_lshlrev_b32_e32 v67, 16, v72
	v_and_b32_e32 v70, 0xffff0000, v73
	v_lshlrev_b32_e32 v71, 16, v74
	v_and_b32_e32 v72, 0xffff0000, v74
	v_lshlrev_b32_e32 v73, 16, v75
	v_and_b32_e32 v74, 0xffff0000, v75
	v_add_f32_e32 v75, v22, v67
	v_min_u32_e32 v22, 6, v117
	v_add_u32_e32 v22, 2, v22
	v_sub_f32_e32 v23, v126, v79
	v_cvt_f32_ubyte0_e32 v22, v22
	v_sub_f32_e32 v24, v127, v80
	v_add_f32_e32 v76, v23, v68
	v_div_scale_f32 v23, s[4:5], v22, v22, 1.0
	v_add_f32_e32 v77, v24, v69
	v_rcp_f32_e32 v24, v23
	v_sub_f32_e32 v25, v128, v82
	v_add_f32_e32 v78, v25, v70
	v_sub_f32_e32 v26, v129, v83
	v_fma_f32 v25, -v23, v24, 1.0
	v_fmac_f32_e32 v24, v25, v24
	v_div_scale_f32 v25, vcc, 1.0, v22, 1.0
	v_sub_f32_e32 v27, v130, v28
	v_add_f32_e32 v79, v26, v71
	v_mul_f32_e32 v26, v25, v24
	v_add_f32_e32 v80, v27, v72
	v_fma_f32 v27, -v23, v26, v25
	v_fmac_f32_e32 v26, v27, v24
	v_fma_f32 v23, -v23, v26, v25
	v_div_fmas_f32 v23, v23, v24, v26
	v_div_fixup_f32 v25, v23, v22, 1.0
	v_fma_f32 v22, v25, v75, -v67
	v_fma_f32 v23, v25, v76, -v68
	v_sub_f32_e32 v28, v87, v86
	v_sub_f32_e32 v29, v131, v29
	v_cvt_pk_bf16_f32 v22, v22, v23
	v_fma_f32 v23, v25, v77, -v69
	v_fma_f32 v24, v25, v78, -v70
	v_add_f32_e32 v28, v28, v73
	v_add_f32_e32 v29, v29, v74
	v_cvt_pk_bf16_f32 v23, v23, v24
	v_fma_f32 v24, v25, v79, -v71
	v_fma_f32 v26, v25, v80, -v72
	v_cvt_pk_bf16_f32 v24, v24, v26
	v_fma_f32 v26, v25, v28, -v73
	v_fma_f32 v25, v25, v29, -v74
	v_cvt_pk_bf16_f32 v25, v26, v25
	v_lshl_add_u64 v[26:27], v[96:97], 0, v[64:65]
	global_store_dwordx4 v[26:27], v[22:25], off
	v_lshlrev_b32_e32 v64, 16, v34
	v_and_b32_e32 v34, 0xffff0000, v34
	v_sub_f32_e32 v22, v75, v89
	v_add_f32_e32 v69, v22, v64
	v_min_u32_e32 v22, 5, v117
	v_add_u32_e32 v22, 3, v22
	v_sub_f32_e32 v23, v76, v90
	v_cvt_f32_ubyte0_e32 v22, v22
	v_sub_f32_e32 v24, v77, v91
	v_lshlrev_b32_e32 v65, 16, v35
	v_add_f32_e32 v70, v23, v34
	v_div_scale_f32 v23, s[4:5], v22, v22, 1.0
	v_add_f32_e32 v71, v24, v65
	v_rcp_f32_e32 v24, v23
	v_sub_f32_e32 v25, v78, v81
	v_and_b32_e32 v35, 0xffff0000, v35
	v_add_f32_e32 v72, v25, v35
	v_fma_f32 v25, -v23, v24, 1.0
	v_sub_f32_e32 v26, v79, v92
	v_lshlrev_b32_e32 v67, 16, v36
	v_fmac_f32_e32 v24, v25, v24
	v_div_scale_f32 v25, vcc, 1.0, v22, 1.0
	v_sub_f32_e32 v27, v80, v84
	v_and_b32_e32 v36, 0xffff0000, v36
	v_add_f32_e32 v73, v26, v67
	v_mul_f32_e32 v26, v25, v24
	v_add_f32_e32 v74, v27, v36
	v_fma_f32 v27, -v23, v26, v25
	v_fmac_f32_e32 v26, v27, v24
	v_fma_f32 v23, -v23, v26, v25
	v_div_fmas_f32 v23, v23, v24, v26
	v_div_fixup_f32 v25, v23, v22, 1.0
	v_fma_f32 v22, v25, v69, -v64
	v_fma_f32 v23, v25, v70, -v34
	v_sub_f32_e32 v28, v28, v85
	v_sub_f32_e32 v29, v29, v93
	v_lshlrev_b32_e32 v68, 16, v37
	v_and_b32_e32 v37, 0xffff0000, v37
	v_cvt_pk_bf16_f32 v22, v22, v23
	v_fma_f32 v23, v25, v71, -v65
	v_fma_f32 v24, v25, v72, -v35
	v_add_f32_e32 v28, v28, v68
	v_add_f32_e32 v29, v29, v37
	v_cvt_pk_bf16_f32 v23, v23, v24
	v_fma_f32 v24, v25, v73, -v67
	v_fma_f32 v26, v25, v74, -v36
	v_cvt_pk_bf16_f32 v24, v24, v26
	v_fma_f32 v26, v25, v28, -v68
	v_fma_f32 v25, v25, v29, -v37
	v_cvt_pk_bf16_f32 v25, v26, v25
	v_lshl_add_u64 v[26:27], v[96:97], 0, v[62:63]
	global_store_dwordx4 v[26:27], v[22:25], off
	v_lshlrev_b32_e32 v34, 16, v18
	v_and_b32_e32 v18, 0xffff0000, v18
	v_sub_f32_e32 v22, v69, v88
	v_sub_f32_e32 v23, v70, v38
	v_add_f32_e32 v38, v22, v34
	v_min_u32_e32 v22, 4, v117
	v_add_u32_e32 v22, 4, v22
	v_cvt_f32_ubyte0_e32 v22, v22
	v_sub_f32_e32 v25, v72, v39
	v_add_f32_e32 v39, v23, v18
	v_div_scale_f32 v23, s[4:5], v22, v22, 1.0
	v_sub_f32_e32 v27, v74, v40
	v_rcp_f32_e32 v40, v23
	v_sub_f32_e32 v29, v29, v41
	v_sub_f32_e32 v24, v71, v99
	v_lshlrev_b32_e32 v35, 16, v19
	v_fma_f32 v41, -v23, v40, 1.0
	v_fmac_f32_e32 v40, v41, v40
	v_div_scale_f32 v41, vcc, 1.0, v22, 1.0
	v_mul_f32_e32 v62, v41, v40
	v_fma_f32 v63, -v23, v62, v41
	v_fmac_f32_e32 v62, v63, v40
	v_fma_f32 v23, -v23, v62, v41
	v_div_fmas_f32 v23, v23, v40, v62
	v_and_b32_e32 v19, 0xffff0000, v19
	v_div_fixup_f32 v22, v23, v22, 1.0
	v_sub_f32_e32 v26, v73, v102
	v_lshlrev_b32_e32 v36, 16, v20
	v_and_b32_e32 v20, 0xffff0000, v20
	v_add_f32_e32 v24, v24, v35
	v_add_f32_e32 v25, v25, v19
	v_fma_f32 v23, v22, v38, -v34
	v_fma_f32 v18, v22, v39, -v18
	v_sub_f32_e32 v28, v28, v103
	v_lshlrev_b32_e32 v37, 16, v21
	v_and_b32_e32 v21, 0xffff0000, v21
	v_add_f32_e32 v26, v26, v36
	v_add_f32_e32 v27, v27, v20
	v_cvt_pk_bf16_f32 v18, v23, v18
	v_fma_f32 v23, v22, v24, -v35
	v_fma_f32 v19, v22, v25, -v19
	v_add_f32_e32 v28, v28, v37
	v_add_f32_e32 v29, v29, v21
	v_cvt_pk_bf16_f32 v19, v23, v19
	v_fma_f32 v23, v22, v26, -v36
	v_fma_f32 v20, v22, v27, -v20
	v_cvt_pk_bf16_f32 v20, v23, v20
	v_fma_f32 v23, v22, v28, -v37
	v_fma_f32 v21, v22, v29, -v21
	v_cvt_pk_bf16_f32 v21, v23, v21
	v_lshl_add_u64 v[22:23], v[96:97], 0, v[60:61]
	global_store_dwordx4 v[22:23], v[18:21], off
	v_sub_f32_e32 v22, v26, v106
	s_waitcnt vmcnt(0) lgkmcnt(0)
; __device__ __forceinline__ unsigned pk2(float lo, float hi) { return pg8::cvt_pk_bf16(lo, hi); }
; template <int W>
; __device__ __forceinline__ void pool_run(const bf16_t* __restrict__ Pp, bf16_t* __restrict__ Dp, int r0, int tt0, int c8) {
;     ...
;     for (int i = 0; i < 8; ++i) { const int tt = tt0 + i; const u32x4 x = v[W - 1 + i];
;         const float p[8] = {bflo(x.x), bfhi(x.x), bflo(x.y), bfhi(x.y), bflo(x.z), bfhi(x.z), bflo(x.w), bfhi(x.w)};
; #pragma unroll
;         for (int e = 0; e < 8; ++e) s[e] += p[e];
;         const int cnt = (tt + 1) < W ? (tt + 1) : W; const float inv = 1.0f / (float)cnt;
;         u32x4 o; o.x = pk2(s[0] * inv - p[0], s[1] * inv - p[1]); o.y = pk2(s[2] * inv - p[2], s[3] * inv - p[3]); o.z = pk2(s[4] * inv - p[4], s[5] * inv - p[5]); o.w = pk2(s[6] * inv - p[6], s[7] * inv - p[7]);
;         *(u32x4*)(Dp + (size_t)(r0 + i) * D + c8) = o;
;         const u32x4 y = v[i];
;         s[0] -= bflo(y.x); s[1] -= bfhi(y.x); s[2] -= bflo(y.y); s[3] -= bfhi(y.y); s[4] -= bflo(y.z); s[5] -= bfhi(y.z); s[6] -= bflo(y.w); s[7] -= bfhi(y.w); }
	v_lshlrev_b32_e32 v26, 16, v14
	v_sub_f32_e32 v18, v38, v104
	v_sub_f32_e32 v19, v39, v30
	v_add_f32_e32 v30, v18, v26
	v_min_u32_e32 v18, 3, v117
	v_add_u32_e32 v18, 5, v18
	v_and_b32_e32 v14, 0xffff0000, v14
	v_cvt_f32_ubyte0_e32 v18, v18
	v_sub_f32_e32 v21, v25, v31
	v_add_f32_e32 v31, v19, v14
	v_div_scale_f32 v19, s[4:5], v18, v18, 1.0
	v_sub_f32_e32 v23, v27, v32
	v_rcp_f32_e32 v32, v19
	v_sub_f32_e32 v25, v29, v33
	v_sub_f32_e32 v20, v24, v105
	v_lshlrev_b32_e32 v27, 16, v15
	v_fma_f32 v33, -v19, v32, 1.0
	v_fmac_f32_e32 v32, v33, v32
	v_div_scale_f32 v33, vcc, 1.0, v18, 1.0
	v_mul_f32_e32 v34, v33, v32
	v_fma_f32 v35, -v19, v34, v33
	v_fmac_f32_e32 v34, v35, v32
	v_fma_f32 v19, -v19, v34, v33
	v_div_fmas_f32 v19, v19, v32, v34
	v_and_b32_e32 v15, 0xffff0000, v15
	v_div_fixup_f32 v18, v19, v18, 1.0
	v_sub_f32_e32 v24, v28, v107
	v_lshlrev_b32_e32 v28, 16, v16
	v_and_b32_e32 v16, 0xffff0000, v16
	v_add_f32_e32 v20, v20, v27
	v_add_f32_e32 v21, v21, v15
	v_fma_f32 v19, v18, v30, -v26
	v_fma_f32 v14, v18, v31, -v14
	v_lshlrev_b32_e32 v29, 16, v17
	v_and_b32_e32 v17, 0xffff0000, v17
	v_add_f32_e32 v22, v22, v28
	v_add_f32_e32 v23, v23, v16
	v_cvt_pk_bf16_f32 v14, v19, v14
	v_fma_f32 v19, v18, v20, -v27
	v_fma_f32 v15, v18, v21, -v15
	v_add_f32_e32 v24, v24, v29
	v_add_f32_e32 v25, v25, v17
	v_cvt_pk_bf16_f32 v15, v19, v15
	v_fma_f32 v19, v18, v22, -v28
	v_fma_f32 v16, v18, v23, -v16
	v_cvt_pk_bf16_f32 v16, v19, v16
	v_fma_f32 v19, v18, v24, -v29
	v_fma_f32 v17, v18, v25, -v17
	v_cvt_pk_bf16_f32 v17, v19, v17
	v_lshl_add_u64 v[18:19], v[96:97], 0, v[58:59]
	global_store_dwordx4 v[18:19], v[14:17], off
	v_sub_f32_e32 v18, v22, v110
	v_lshlrev_b32_e32 v22, 16, v10
	v_sub_f32_e32 v14, v30, v108
	v_add_f32_e32 v26, v14, v22
	v_min_u32_e32 v14, 2, v117
	v_add_u32_e32 v14, 6, v14
	v_sub_f32_e32 v15, v31, v46
	v_and_b32_e32 v10, 0xffff0000, v10
	v_cvt_f32_ubyte0_e32 v14, v14
	v_add_f32_e32 v27, v15, v10
	v_div_scale_f32 v15, s[4:5], v14, v14, 1.0
	v_rcp_f32_e32 v28, v15
	v_sub_f32_e32 v16, v20, v109
	v_sub_f32_e32 v17, v21, v47
	v_sub_f32_e32 v19, v23, v48
	v_fma_f32 v29, -v15, v28, 1.0
	v_fmac_f32_e32 v28, v29, v28
	v_div_scale_f32 v29, vcc, 1.0, v14, 1.0
	v_mul_f32_e32 v30, v29, v28
	v_fma_f32 v31, -v15, v30, v29
	v_fmac_f32_e32 v30, v31, v28
	v_fma_f32 v15, -v15, v30, v29
	v_div_fmas_f32 v15, v15, v28, v30
	v_lshlrev_b32_e32 v23, 16, v11
	v_and_b32_e32 v11, 0xffff0000, v11
	v_div_fixup_f32 v14, v15, v14, 1.0
	v_sub_f32_e32 v20, v24, v111
	v_lshlrev_b32_e32 v24, 16, v12
	v_and_b32_e32 v12, 0xffff0000, v12
	v_add_f32_e32 v16, v16, v23
	v_add_f32_e32 v17, v17, v11
	v_fma_f32 v15, v14, v26, -v22
	v_fma_f32 v10, v14, v27, -v10
	v_sub_f32_e32 v21, v25, v49
	v_lshlrev_b32_e32 v25, 16, v13
	v_and_b32_e32 v13, 0xffff0000, v13
	v_add_f32_e32 v18, v18, v24
	v_add_f32_e32 v19, v19, v12
	v_cvt_pk_bf16_f32 v10, v15, v10
	v_fma_f32 v15, v14, v16, -v23
	v_fma_f32 v11, v14, v17, -v11
	v_add_f32_e32 v20, v20, v25
	v_add_f32_e32 v21, v21, v13
	v_cvt_pk_bf16_f32 v11, v15, v11
	v_fma_f32 v15, v14, v18, -v24
	v_fma_f32 v12, v14, v19, -v12
	v_cvt_pk_bf16_f32 v12, v15, v12
	v_fma_f32 v15, v14, v20, -v25
	v_fma_f32 v13, v14, v21, -v13
	v_cvt_pk_bf16_f32 v13, v15, v13
	v_lshl_add_u64 v[14:15], v[96:97], 0, v[56:57]
	global_store_dwordx4 v[14:15], v[10:13], off
	v_sub_f32_e32 v14, v18, v114
	v_lshlrev_b32_e32 v18, 16, v6
	v_sub_f32_e32 v10, v26, v112
	v_sub_f32_e32 v11, v27, v42
	v_and_b32_e32 v6, 0xffff0000, v6
	v_add_f32_e32 v22, v10, v18
	v_div_scale_f32 v10, s[4:5], v66, v66, 1.0
	v_add_f32_e32 v23, v11, v6
	v_rcp_f32_e32 v11, v10
	v_sub_f32_e32 v12, v16, v113
	v_sub_f32_e32 v13, v17, v43
	v_sub_f32_e32 v15, v19, v44
	v_fma_f32 v24, -v10, v11, 1.0
	v_fmac_f32_e32 v11, v24, v11
	v_div_scale_f32 v24, vcc, 1.0, v66, 1.0
	v_mul_f32_e32 v25, v24, v11
	v_fma_f32 v26, -v10, v25, v24
	v_fmac_f32_e32 v25, v26, v11
	v_fma_f32 v10, -v10, v25, v24
	v_div_fmas_f32 v10, v10, v11, v25
	v_lshlrev_b32_e32 v19, 16, v7
	v_and_b32_e32 v7, 0xffff0000, v7
	v_div_fixup_f32 v10, v10, v66, 1.0
	v_sub_f32_e32 v16, v20, v115
	v_lshlrev_b32_e32 v20, 16, v8
	v_and_b32_e32 v8, 0xffff0000, v8
	v_add_f32_e32 v12, v12, v19
	v_add_f32_e32 v13, v13, v7
	v_fma_f32 v11, v10, v22, -v18
	v_fma_f32 v6, v10, v23, -v6
	v_sub_f32_e32 v17, v21, v45
	v_lshlrev_b32_e32 v21, 16, v9
	v_and_b32_e32 v9, 0xffff0000, v9
	v_add_f32_e32 v14, v14, v20
	v_add_f32_e32 v15, v15, v8
	v_cvt_pk_bf16_f32 v6, v11, v6
	v_fma_f32 v11, v10, v12, -v19
	v_fma_f32 v7, v10, v13, -v7
	v_add_f32_e32 v16, v16, v21
	v_add_f32_e32 v17, v17, v9
	v_cvt_pk_bf16_f32 v7, v11, v7
	v_fma_f32 v11, v10, v14, -v20
	v_fma_f32 v8, v10, v15, -v8
	v_cvt_pk_bf16_f32 v8, v11, v8
	v_fma_f32 v11, v10, v16, -v21
	v_fma_f32 v9, v10, v17, -v9
	v_cvt_pk_bf16_f32 v9, v11, v9
	v_lshl_add_u64 v[10:11], v[96:97], 0, v[54:55]
	global_store_dwordx4 v[10:11], v[6:9], off
	v_sub_f32_e32 v10, v14, v120
	v_lshlrev_b32_e32 v14, 16, v2
	v_sub_f32_e32 v6, v22, v118
	v_sub_f32_e32 v7, v23, v50
	v_and_b32_e32 v2, 0xffff0000, v2
	v_sub_f32_e32 v8, v12, v119
	v_sub_f32_e32 v9, v13, v51
	v_sub_f32_e32 v11, v15, v52
	v_lshlrev_b32_e32 v15, 16, v3
	v_and_b32_e32 v3, 0xffff0000, v3
	v_add_f32_e32 v6, v6, v14
	v_add_f32_e32 v7, v7, v2
	s_mov_b32 s4, 0x3e000000
	v_sub_f32_e32 v12, v16, v121
	v_sub_f32_e32 v13, v17, v53
	v_lshlrev_b32_e32 v16, 16, v4
	v_and_b32_e32 v4, 0xffff0000, v4
	v_lshlrev_b32_e32 v17, 16, v5
	v_and_b32_e32 v5, 0xffff0000, v5
	v_add_f32_e32 v8, v8, v15
	v_add_f32_e32 v9, v9, v3
	v_fma_f32 v6, v6, s4, -v14
	v_fma_f32 v2, v7, s4, -v2
	v_add_f32_e32 v10, v10, v16
	v_add_f32_e32 v11, v11, v4
	v_add_f32_e32 v13, v13, v5
	v_cvt_pk_bf16_f32 v2, v6, v2
	v_fma_f32 v6, v8, s4, -v15
	v_fma_f32 v3, v9, s4, -v3
	v_add_f32_e32 v12, v12, v17
	v_cvt_pk_bf16_f32 v3, v6, v3
	v_fma_f32 v6, v10, s4, -v16
	v_fma_f32 v4, v11, s4, -v4
	v_fma_f32 v5, v13, s4, -v5
	v_cvt_pk_bf16_f32 v4, v6, v4
	v_fma_f32 v6, v12, s4, -v17
	v_cvt_pk_bf16_f32 v5, v6, v5

; __device__ __forceinline__ unsigned pk2(float lo, float hi) { return pg8::cvt_pk_bf16(lo, hi); }
; template <int W>
; __device__ __forceinline__ void pool_run(const bf16_t* __restrict__ Pp, bf16_t* __restrict__ Dp, int r0, int tt0, int c8) {
;     u32x4 v[W - 1 + 8];
; #pragma unroll
;     for (int k = 0; k < W - 1; ++k) v[k] = (tt0 - (W - 1) + k >= 0) ? *(const u32x4*)(Pp + (size_t)(r0 - (W - 1) + k) * D + c8) : (u32x4){0u, 0u, 0u, 0u};
; #pragma unroll
;     for (int i = 0; i < 8; ++i) v[W - 1 + i] = *(const u32x4*)(Pp + (size_t)(r0 + i) * D + c8);
;     float s[8];
; #pragma unroll
;     for (int e = 0; e < 8; ++e) s[e] = 0.f;
; #pragma unroll
;     for (int k = 0; k < W - 1; ++k) { s[0] += bflo(v[k].x); s[1] += bfhi(v[k].x); s[2] += bflo(v[k].y); s[3] += bfhi(v[k].y); s[4] += bflo(v[k].z); s[5] += bfhi(v[k].z); s[6] += bflo(v[k].w); s[7] += bfhi(v[k].w); }
; #pragma unroll
;     for (int i = 0; i < 8; ++i) { const int tt = tt0 + i; const u32x4 x = v[W - 1 + i];
;         const float p[8] = {bflo(x.x), bfhi(x.x), bflo(x.y), bfhi(x.y), bflo(x.z), bfhi(x.z), bflo(x.w), bfhi(x.w)};
; #pragma unroll
;         for (int e = 0; e < 8; ++e) s[e] += p[e];
;         const int cnt = (tt + 1) < W ? (tt + 1) : W; const float inv = 1.0f / (float)cnt;
;         u32x4 o; o.x = pk2(s[0] * inv - p[0], s[1] * inv - p[1]); o.y = pk2(s[2] * inv - p[2], s[3] * inv - p[3]); o.z = pk2(s[4] * inv - p[4], s[5] * inv - p[5]); o.w = pk2(s[6] * inv - p[6], s[7] * inv - p[7]);
;         *(u32x4*)(Dp + (size_t)(r0 + i) * D + c8) = o;
;         const u32x4 y = v[i];
;         s[0] -= bflo(y.x); s[1] -= bfhi(y.x); s[2] -= bflo(y.y); s[3] -= bfhi(y.y); s[4] -= bflo(y.z); s[5] -= bfhi(y.z); s[6] -= bflo(y.w); s[7] -= bfhi(y.w); }
; __device__ __forceinline__ void pool_phase(const PT& T, int vc) {
;     ...
;         if (g == 0) pool_run<2>(Pp, Dp, r0, tt0, c8); else if (g == 1) pool_run<4>(Pp, Dp, r0, tt0, c8); else if (g == 2) pool_run<8>(Pp, Dp, r0, tt0, c8); else pool_run<16>(Pp, Dp, r0, tt0, c8);
.LBB0_782:
	s_andn2_b64 vcc, exec, s[4:5]
	s_cbranch_vccnz .LBB0_731
	s_mov_b64 s[4:5], -1
	s_cmp_eq_u32 s8, 1
	v_cmp_ne_u32_e32 vcc, 0, v117
	s_cbranch_scc1 .LBB0_787
	v_mov_b32_e32 v2, 0
	v_mov_b32_e32 v14, 1.0
	v_mov_b32_e32 v3, 0
	v_mov_b32_e32 v4, 0
	v_mov_b32_e32 v5, 0
	s_and_saveexec_b64 s[4:5], vcc
	s_cbranch_execz .LBB0_786
	v_add_u32_e32 v2, -1, v98
	v_ashrrev_i32_e32 v3, 31, v2
	v_lshlrev_b64 v[2:3], 11, v[2:3]
	v_lshl_add_u64 v[2:3], v[94:95], 0, v[2:3]
	global_load_dwordx4 v[2:5], v[2:3], off
	v_mov_b32_e32 v14, 2.0
.LBB0_786:
	s_or_b64 exec, exec, s[4:5]
	v_ashrrev_i32_e32 v99, 31, v98
	v_lshlrev_b64 v[40:41], 11, v[98:99]
	v_lshl_add_u64 v[6:7], v[94:95], 0, v[40:41]
	global_load_dwordx4 v[16:19], v[6:7], off
	v_add_u32_e32 v6, 1, v98
	v_ashrrev_i32_e32 v7, 31, v6
	v_lshlrev_b64 v[42:43], 11, v[6:7]
	s_waitcnt vmcnt(0) lgkmcnt(0)
	v_lshlrev_b32_e32 v54, 16, v2
	v_and_b32_e32 v55, 0xffff0000, v2
	v_lshlrev_b32_e32 v56, 16, v3
	v_and_b32_e32 v57, 0xffff0000, v3
	v_lshl_add_u64 v[2:3], v[94:95], 0, v[42:43]
	global_load_dwordx4 v[20:23], v[2:3], off
	v_add_u32_e32 v8, 2, v98
	v_add_u32_e32 v10, 3, v98
	v_add_u32_e32 v12, 4, v98
	v_add_u32_e32 v24, 5, v98
	v_add_u32_e32 v26, 6, v98
	v_add_u32_e32 v28, 7, v98
	v_ashrrev_i32_e32 v9, 31, v8
	v_ashrrev_i32_e32 v11, 31, v10
	v_ashrrev_i32_e32 v13, 31, v12
	v_ashrrev_i32_e32 v25, 31, v24
	v_ashrrev_i32_e32 v27, 31, v26
	v_ashrrev_i32_e32 v29, 31, v28
	v_lshlrev_b64 v[44:45], 11, v[8:9]
	v_lshlrev_b64 v[46:47], 11, v[10:11]
	v_lshlrev_b64 v[48:49], 11, v[12:13]
	v_lshlrev_b64 v[12:13], 11, v[24:25]
	v_lshlrev_b32_e32 v58, 16, v4
	v_and_b32_e32 v59, 0xffff0000, v4
	v_lshlrev_b32_e32 v60, 16, v5
	v_and_b32_e32 v61, 0xffff0000, v5
	v_lshlrev_b64 v[10:11], 11, v[26:27]
	v_lshlrev_b64 v[100:101], 11, v[28:29]
	v_lshl_add_u64 v[2:3], v[94:95], 0, v[44:45]
	v_lshl_add_u64 v[4:5], v[94:95], 0, v[46:47]
	v_lshl_add_u64 v[6:7], v[94:95], 0, v[48:49]
	v_lshl_add_u64 v[8:9], v[94:95], 0, v[12:13]
	v_lshl_add_u64 v[50:51], v[94:95], 0, v[10:11]
	v_lshl_add_u64 v[52:53], v[94:95], 0, v[100:101]
	global_load_dwordx4 v[24:27], v[2:3], off
	global_load_dwordx4 v[28:31], v[4:5], off
	global_load_dwordx4 v[32:35], v[6:7], off
	global_load_dwordx4 v[36:39], v[8:9], off
	s_nop 0
	global_load_dwordx4 v[6:9], v[50:51], off
	global_load_dwordx4 v[2:5], v[52:53], off
	v_div_scale_f32 v15, s[4:5], v14, v14, 1.0
	v_rcp_f32_e32 v71, v15
	v_div_scale_f32 v62, vcc, 1.0, v14, 1.0
	v_add_f32_e32 v63, 0, v54
	v_fma_f32 v50, -v15, v71, 1.0
	v_fmac_f32_e32 v71, v50, v71
	v_mul_f32_e32 v50, v62, v71
	v_fma_f32 v51, -v15, v50, v62
	v_fmac_f32_e32 v50, v51, v71
	v_fma_f32 v15, -v15, v50, v62
	v_add_f32_e32 v64, 0, v55
	v_div_fmas_f32 v15, v15, v71, v50
	v_add_f32_e32 v65, 0, v56
	v_add_f32_e32 v66, 0, v57
	v_div_fixup_f32 v50, v15, v14, 1.0
	v_add_f32_e32 v67, 0, v58
	v_add_f32_e32 v68, 0, v59
	v_add_f32_e32 v69, 0, v60
	v_add_f32_e32 v70, 0, v61
	v_lshl_add_u64 v[12:13], v[96:97], 0, v[12:13]
	v_lshl_add_u64 v[10:11], v[96:97], 0, v[10:11]
	s_mov_b64 s[4:5], 0
	v_lshlrev_b32_e32 v51, 16, v16
	v_and_b32_e32 v52, 0xffff0000, v16
	v_lshlrev_b32_e32 v53, 16, v17
	v_and_b32_e32 v62, 0xffff0000, v17
	v_add_f32_e32 v63, v63, v51
	v_add_f32_e32 v64, v64, v52
	v_lshlrev_b32_e32 v71, 16, v18
	v_and_b32_e32 v72, 0xffff0000, v18
	v_add_f32_e32 v65, v65, v53
	v_add_f32_e32 v66, v66, v62
	v_fma_f32 v14, v50, v63, -v51
	v_fma_f32 v15, v50, v64, -v52
	v_lshlrev_b32_e32 v73, 16, v19
	v_and_b32_e32 v74, 0xffff0000, v19
	v_add_f32_e32 v67, v67, v71
	v_add_f32_e32 v68, v68, v72
	v_cvt_pk_bf16_f32 v14, v14, v15
	v_fma_f32 v15, v50, v65, -v53
	v_fma_f32 v16, v50, v66, -v62
	v_add_f32_e32 v69, v69, v73
	v_add_f32_e32 v70, v70, v74
	v_cvt_pk_bf16_f32 v15, v15, v16
	v_fma_f32 v16, v50, v67, -v71
	v_fma_f32 v17, v50, v68, -v72
	v_cvt_pk_bf16_f32 v16, v16, v17
	v_fma_f32 v17, v50, v69, -v73
	v_fma_f32 v18, v50, v70, -v74
	v_cvt_pk_bf16_f32 v17, v17, v18
	v_lshl_add_u64 v[18:19], v[96:97], 0, v[40:41]
	global_store_dwordx4 v[18:19], v[14:17], off
	s_waitcnt vmcnt(0) lgkmcnt(0)
	v_lshlrev_b32_e32 v50, 16, v20
	v_and_b32_e32 v20, 0xffff0000, v20
	v_sub_f32_e32 v14, v63, v54
	v_sub_f32_e32 v15, v64, v55
	v_sub_f32_e32 v16, v65, v56
	v_sub_f32_e32 v17, v66, v57
	v_sub_f32_e32 v18, v67, v58
	v_lshlrev_b32_e32 v54, 16, v21
	v_and_b32_e32 v21, 0xffff0000, v21
	v_add_f32_e32 v57, v14, v50
	v_add_f32_e32 v58, v15, v20
	v_sub_f32_e32 v19, v68, v59
	v_sub_f32_e32 v40, v69, v60
	v_lshlrev_b32_e32 v55, 16, v22
	v_and_b32_e32 v22, 0xffff0000, v22
	v_add_f32_e32 v59, v16, v54
	v_add_f32_e32 v60, v17, v21
	v_fma_f32 v14, v57, 0.5, -v50
	v_fma_f32 v15, v58, 0.5, -v20
	v_sub_f32_e32 v41, v70, v61
	v_lshlrev_b32_e32 v56, 16, v23
	v_and_b32_e32 v23, 0xffff0000, v23
	v_add_f32_e32 v61, v18, v55
	v_add_f32_e32 v63, v19, v22
	v_cvt_pk_bf16_f32 v14, v14, v15
	v_fma_f32 v15, v59, 0.5, -v54
	v_fma_f32 v16, v60, 0.5, -v21
	v_add_f32_e32 v40, v40, v56
	v_add_f32_e32 v41, v41, v23
	v_cvt_pk_bf16_f32 v15, v15, v16
	v_fma_f32 v16, v61, 0.5, -v55
	v_fma_f32 v17, v63, 0.5, -v22
	v_cvt_pk_bf16_f32 v16, v16, v17
	v_fma_f32 v17, v40, 0.5, -v56
	v_fma_f32 v18, v41, 0.5, -v23
	v_cvt_pk_bf16_f32 v17, v17, v18
	v_lshl_add_u64 v[18:19], v[96:97], 0, v[42:43]
	global_store_dwordx4 v[18:19], v[14:17], off
	v_lshlrev_b32_e32 v42, 16, v24
	v_and_b32_e32 v24, 0xffff0000, v24
	v_sub_f32_e32 v14, v57, v51
	v_sub_f32_e32 v15, v58, v52
	v_sub_f32_e32 v16, v59, v53
	v_sub_f32_e32 v17, v60, v62
	v_lshlrev_b32_e32 v43, 16, v25
	v_and_b32_e32 v25, 0xffff0000, v25
	v_add_f32_e32 v53, v14, v42
	v_add_f32_e32 v57, v15, v24
	v_sub_f32_e32 v18, v61, v71
	v_sub_f32_e32 v19, v63, v72
	v_lshlrev_b32_e32 v51, 16, v26
; __device__ __forceinline__ unsigned pk2(float lo, float hi) { return pg8::cvt_pk_bf16(lo, hi); }
; template <int W>
; __device__ __forceinline__ void pool_run(const bf16_t* __restrict__ Pp, bf16_t* __restrict__ Dp, int r0, int tt0, int c8) {
;     ...
;     for (int i = 0; i < 8; ++i) { const int tt = tt0 + i; const u32x4 x = v[W - 1 + i];
;         const float p[8] = {bflo(x.x), bfhi(x.x), bflo(x.y), bfhi(x.y), bflo(x.z), bfhi(x.z), bflo(x.w), bfhi(x.w)};
; #pragma unroll
;         for (int e = 0; e < 8; ++e) s[e] += p[e];
;         const int cnt = (tt + 1) < W ? (tt + 1) : W; const float inv = 1.0f / (float)cnt;
;         u32x4 o; o.x = pk2(s[0] * inv - p[0], s[1] * inv - p[1]); o.y = pk2(s[2] * inv - p[2], s[3] * inv - p[3]); o.z = pk2(s[4] * inv - p[4], s[5] * inv - p[5]); o.w = pk2(s[6] * inv - p[6], s[7] * inv - p[7]);
;         *(u32x4*)(Dp + (size_t)(r0 + i) * D + c8) = o;
;         const u32x4 y = v[i];
;         s[0] -= bflo(y.x); s[1] -= bfhi(y.x); s[2] -= bflo(y.y); s[3] -= bfhi(y.y); s[4] -= bflo(y.z); s[5] -= bfhi(y.z); s[6] -= bflo(y.w); s[7] -= bfhi(y.w); }
	v_and_b32_e32 v26, 0xffff0000, v26
	v_add_f32_e32 v58, v16, v43
	v_add_f32_e32 v59, v17, v25
	v_fma_f32 v14, v53, 0.5, -v42
	v_fma_f32 v15, v57, 0.5, -v24
	v_sub_f32_e32 v40, v40, v73
	v_sub_f32_e32 v41, v41, v74
	v_lshlrev_b32_e32 v52, 16, v27
	v_and_b32_e32 v27, 0xffff0000, v27
	v_add_f32_e32 v60, v18, v51
	v_add_f32_e32 v61, v19, v26
	v_cvt_pk_bf16_f32 v14, v14, v15
	v_fma_f32 v15, v58, 0.5, -v43
	v_fma_f32 v16, v59, 0.5, -v25
	v_add_f32_e32 v40, v40, v52
	v_add_f32_e32 v41, v41, v27
	v_cvt_pk_bf16_f32 v15, v15, v16
	v_fma_f32 v16, v60, 0.5, -v51
	v_fma_f32 v17, v61, 0.5, -v26
	v_cvt_pk_bf16_f32 v16, v16, v17
	v_fma_f32 v17, v40, 0.5, -v52
	v_fma_f32 v18, v41, 0.5, -v27
	v_cvt_pk_bf16_f32 v17, v17, v18
	v_lshl_add_u64 v[18:19], v[96:97], 0, v[44:45]
	global_store_dwordx4 v[18:19], v[14:17], off
	v_sub_f32_e32 v19, v61, v22
	v_lshlrev_b32_e32 v22, 16, v28
	v_sub_f32_e32 v14, v53, v50
	v_sub_f32_e32 v15, v57, v20
	v_sub_f32_e32 v17, v59, v21
	v_sub_f32_e32 v21, v41, v23
	v_and_b32_e32 v23, 0xffff0000, v28
	v_sub_f32_e32 v16, v58, v54
	v_lshlrev_b32_e32 v28, 16, v29
	v_and_b32_e32 v29, 0xffff0000, v29
	v_add_f32_e32 v44, v14, v22
	v_add_f32_e32 v45, v15, v23
	v_sub_f32_e32 v18, v60, v55
	v_sub_f32_e32 v20, v40, v56
	v_lshlrev_b32_e32 v40, 16, v30
	v_and_b32_e32 v30, 0xffff0000, v30
	v_add_f32_e32 v50, v16, v28
	v_add_f32_e32 v53, v17, v29
	v_fma_f32 v14, v44, 0.5, -v22
	v_fma_f32 v15, v45, 0.5, -v23
	v_lshlrev_b32_e32 v41, 16, v31
	v_and_b32_e32 v31, 0xffff0000, v31
	v_add_f32_e32 v54, v18, v40
	v_add_f32_e32 v55, v19, v30
	v_cvt_pk_bf16_f32 v14, v14, v15
	v_fma_f32 v15, v50, 0.5, -v28
	v_fma_f32 v16, v53, 0.5, -v29
	v_add_f32_e32 v20, v20, v41
	v_add_f32_e32 v21, v21, v31
	v_cvt_pk_bf16_f32 v15, v15, v16
	v_fma_f32 v16, v54, 0.5, -v40
	v_fma_f32 v17, v55, 0.5, -v30
	v_cvt_pk_bf16_f32 v16, v16, v17
	v_fma_f32 v17, v20, 0.5, -v41
	v_fma_f32 v18, v21, 0.5, -v31
	v_cvt_pk_bf16_f32 v17, v17, v18
	v_lshl_add_u64 v[18:19], v[96:97], 0, v[46:47]
	global_store_dwordx4 v[18:19], v[14:17], off
	v_sub_f32_e32 v19, v55, v26
	v_sub_f32_e32 v21, v21, v27
	v_sub_f32_e32 v14, v44, v42
	v_sub_f32_e32 v15, v45, v24
	v_sub_f32_e32 v17, v53, v25
	v_lshlrev_b32_e32 v24, 16, v32
	v_and_b32_e32 v25, 0xffff0000, v32
	v_sub_f32_e32 v16, v50, v43
	v_lshlrev_b32_e32 v26, 16, v33
	v_and_b32_e32 v27, 0xffff0000, v33
	v_add_f32_e32 v42, v14, v24
	v_add_f32_e32 v43, v15, v25
	v_sub_f32_e32 v18, v54, v51
	v_lshlrev_b32_e32 v32, 16, v34
	v_and_b32_e32 v33, 0xffff0000, v34
	v_add_f32_e32 v44, v16, v26
	v_add_f32_e32 v45, v17, v27
	v_fma_f32 v14, v42, 0.5, -v24
	v_fma_f32 v15, v43, 0.5, -v25
	v_sub_f32_e32 v20, v20, v52
	v_lshlrev_b32_e32 v34, 16, v35
	v_and_b32_e32 v35, 0xffff0000, v35
	v_add_f32_e32 v46, v18, v32
	v_add_f32_e32 v47, v19, v33
	v_cvt_pk_bf16_f32 v14, v14, v15
	v_fma_f32 v15, v44, 0.5, -v26
	v_fma_f32 v16, v45, 0.5, -v27
	v_add_f32_e32 v20, v20, v34
	v_add_f32_e32 v21, v21, v35
	v_cvt_pk_bf16_f32 v15, v15, v16
	v_fma_f32 v16, v46, 0.5, -v32
	v_fma_f32 v17, v47, 0.5, -v33
	v_cvt_pk_bf16_f32 v16, v16, v17
	v_fma_f32 v17, v20, 0.5, -v34
	v_fma_f32 v18, v21, 0.5, -v35
	v_cvt_pk_bf16_f32 v17, v17, v18
	v_lshl_add_u64 v[18:19], v[96:97], 0, v[48:49]
	global_store_dwordx4 v[18:19], v[14:17], off
	v_sub_f32_e32 v19, v47, v30
	v_sub_f32_e32 v21, v21, v31
	v_sub_f32_e32 v14, v42, v22
	v_sub_f32_e32 v15, v43, v23
	v_lshlrev_b32_e32 v22, 16, v36
	v_and_b32_e32 v23, 0xffff0000, v36
	v_sub_f32_e32 v16, v44, v28
	v_sub_f32_e32 v17, v45, v29
	v_lshlrev_b32_e32 v28, 16, v37
	v_and_b32_e32 v29, 0xffff0000, v37
	v_lshlrev_b32_e32 v30, 16, v38
	v_and_b32_e32 v31, 0xffff0000, v38
	v_lshlrev_b32_e32 v36, 16, v39
	v_and_b32_e32 v37, 0xffff0000, v39
	v_add_f32_e32 v38, v14, v22
	v_add_f32_e32 v39, v15, v23
	v_sub_f32_e32 v18, v46, v40
	v_sub_f32_e32 v20, v20, v41
	v_add_f32_e32 v40, v16, v28
	v_add_f32_e32 v41, v17, v29
	v_fma_f32 v14, v38, 0.5, -v22
	v_fma_f32 v15, v39, 0.5, -v23
	v_add_f32_e32 v18, v18, v30
	v_add_f32_e32 v19, v19, v31
	v_cvt_pk_bf16_f32 v14, v14, v15
	v_fma_f32 v15, v40, 0.5, -v28
	v_fma_f32 v16, v41, 0.5, -v29
	v_add_f32_e32 v20, v20, v36
	v_cvt_pk_bf16_f32 v15, v15, v16
	v_fma_f32 v16, v18, 0.5, -v30
	v_fma_f32 v17, v19, 0.5, -v31
	v_add_f32_e32 v21, v21, v37
	v_cvt_pk_bf16_f32 v16, v16, v17
	v_fma_f32 v17, v20, 0.5, -v36
	v_fma_f32 v42, v21, 0.5, -v37
	v_cvt_pk_bf16_f32 v17, v17, v42
	global_store_dwordx4 v[12:13], v[14:17], off
	v_sub_f32_e32 v12, v38, v24
	v_sub_f32_e32 v13, v39, v25
	v_sub_f32_e32 v16, v18, v32
	v_sub_f32_e32 v18, v20, v34
	v_lshlrev_b32_e32 v20, 16, v6
	v_and_b32_e32 v6, 0xffff0000, v6
	v_sub_f32_e32 v14, v40, v26
	v_sub_f32_e32 v15, v41, v27
	v_sub_f32_e32 v17, v19, v33
	v_sub_f32_e32 v19, v21, v35
	v_lshlrev_b32_e32 v21, 16, v7
	v_and_b32_e32 v7, 0xffff0000, v7
	v_lshlrev_b32_e32 v24, 16, v8
	v_and_b32_e32 v8, 0xffff0000, v8
	v_add_f32_e32 v12, v12, v20
	v_add_f32_e32 v13, v13, v6
	v_lshlrev_b32_e32 v25, 16, v9
	v_and_b32_e32 v9, 0xffff0000, v9
	v_add_f32_e32 v14, v14, v21
	v_add_f32_e32 v15, v15, v7
	v_add_f32_e32 v17, v17, v8
	v_fma_f32 v20, v12, 0.5, -v20
	v_fma_f32 v6, v13, 0.5, -v6
	v_add_f32_e32 v16, v16, v24
	v_add_f32_e32 v19, v19, v9
	v_cvt_pk_bf16_f32 v6, v20, v6
	v_fma_f32 v20, v14, 0.5, -v21
	v_fma_f32 v7, v15, 0.5, -v7
	v_fma_f32 v8, v17, 0.5, -v8
	v_add_f32_e32 v18, v18, v25
	v_cvt_pk_bf16_f32 v7, v20, v7
	v_fma_f32 v20, v16, 0.5, -v24
	v_cvt_pk_bf16_f32 v8, v20, v8
	v_fma_f32 v9, v19, 0.5, -v9
	v_fma_f32 v20, v18, 0.5, -v25
	v_cvt_pk_bf16_f32 v9, v20, v9
	global_store_dwordx4 v[10:11], v[6:9], off
	v_sub_f32_e32 v10, v16, v30
	v_sub_f32_e32 v11, v17, v31
	v_sub_f32_e32 v6, v12, v22
	v_sub_f32_e32 v7, v13, v23
	v_sub_f32_e32 v8, v14, v28
	v_lshlrev_b32_e32 v14, 16, v2
	v_and_b32_e32 v2, 0xffff0000, v2
	v_sub_f32_e32 v9, v15, v29
	v_lshlrev_b32_e32 v15, 16, v3
	v_and_b32_e32 v3, 0xffff0000, v3
	v_add_f32_e32 v6, v6, v14
	v_add_f32_e32 v7, v7, v2
	v_sub_f32_e32 v13, v19, v37
	v_lshlrev_b32_e32 v16, 16, v4
	v_and_b32_e32 v4, 0xffff0000, v4
	v_lshlrev_b32_e32 v17, 16, v5
	v_and_b32_e32 v5, 0xffff0000, v5
	v_add_f32_e32 v8, v8, v15
	v_add_f32_e32 v9, v9, v3
	v_fma_f32 v6, v6, 0.5, -v14
	v_fma_f32 v2, v7, 0.5, -v2
	v_sub_f32_e32 v12, v18, v36
	v_add_f32_e32 v10, v10, v16
	v_add_f32_e32 v11, v11, v4
	v_add_f32_e32 v13, v13, v5
	v_cvt_pk_bf16_f32 v2, v6, v2
	v_fma_f32 v6, v8, 0.5, -v15
	v_fma_f32 v3, v9, 0.5, -v3
	v_add_f32_e32 v12, v12, v17
	v_cvt_pk_bf16_f32 v3, v6, v3
	v_fma_f32 v6, v10, 0.5, -v16
	v_fma_f32 v4, v11, 0.5, -v4
	v_fma_f32 v5, v13, 0.5, -v5
	v_cvt_pk_bf16_f32 v4, v6, v4
	v_fma_f32 v6, v12, 0.5, -v17
	v_cvt_pk_bf16_f32 v5, v6, v5
; template <int W>
; __device__ __forceinline__ void pool_run(const bf16_t* __restrict__ Pp, bf16_t* __restrict__ Dp, int r0, int tt0, int c8) {
;     u32x4 v[W - 1 + 8];
; #pragma unroll
;     for (int k = 0; k < W - 1; ++k) v[k] = (tt0 - (W - 1) + k >= 0) ? *(const u32x4*)(Pp + (size_t)(r0 - (W - 1) + k) * D + c8) : (u32x4){0u, 0u, 0u, 0u};
; #pragma unroll
;     for (int i = 0; i < 8; ++i) v[W - 1 + i] = *(const u32x4*)(Pp + (size_t)(r0 + i) * D + c8);
.LBB0_787:
	s_and_b64 vcc, exec, s[4:5]
	s_cbranch_vccz .LBB0_731
	v_mov_b32_e32 v22, 0
	v_cmp_ne_u32_e32 vcc, 0, v117
	v_mov_b32_e32 v26, 0
	v_mov_b32_e32 v27, 0
	v_mov_b32_e32 v28, 0
	v_mov_b32_e32 v29, 0
	s_and_saveexec_b64 s[4:5], vcc
	s_cbranch_execz .LBB0_790
	v_add_u32_e32 v2, -3, v98
	v_ashrrev_i32_e32 v3, 31, v2
	v_lshlrev_b64 v[2:3], 11, v[2:3]
	v_lshl_add_u64 v[2:3], v[94:95], 0, v[2:3]
	global_load_dwordx4 v[26:29], v[2:3], off
.LBB0_790:
	s_or_b64 exec, exec, s[4:5]
	v_mov_b32_e32 v23, 0
	v_mov_b32_e32 v24, 0
	v_mov_b32_e32 v25, 0
	s_and_saveexec_b64 s[4:5], vcc
	s_cbranch_execz .LBB0_792
	v_add_u32_e32 v2, -2, v98
	v_ashrrev_i32_e32 v3, 31, v2
	v_lshlrev_b64 v[2:3], 11, v[2:3]
	v_lshl_add_u64 v[2:3], v[94:95], 0, v[2:3]
	global_load_dwordx4 v[22:25], v[2:3], off
.LBB0_792:
	s_or_b64 exec, exec, s[4:5]
	v_mov_b32_e32 v30, 0
	v_mov_b32_e32 v44, 0x40400000
	v_mov_b32_e32 v31, 0
	v_mov_b32_e32 v32, 0
	v_mov_b32_e32 v33, 0
	s_and_saveexec_b64 s[4:5], vcc
	s_cbranch_execz .LBB0_730
	v_add_u32_e32 v2, -1, v98
	v_ashrrev_i32_e32 v3, 31, v2
	v_lshlrev_b64 v[2:3], 11, v[2:3]
	v_lshl_add_u64 v[2:3], v[94:95], 0, v[2:3]
	global_load_dwordx4 v[30:33], v[2:3], off
	v_mov_b32_e32 v44, 4.0
	s_branch .LBB0_730
